# GEMM MMA segments: redundant post-barrier s_waitcnt lgkmcnt(0) removed
# speedup vs baseline: 1.0080x; 1.0016x over previous
; #define G_STAGE(bufoff, gbase, voff) do { _Pragma("unroll") for (int _i = 0; _i < 2; ++_i) \
;         __builtin_amdgcn_global_load_lds((const unsigned*)((const char*)(gbase) + voff[_i]), (LAS unsigned*)(lds + (bufoff) + ldsw + _i * 8192), 16, 0, 0); } while (0)
; #define G_LDA(dst, b, h) do { _Pragma("unroll") for (int m = 0; m < 4; ++m) _Pragma("unroll") for (int k = 0; k < 2; ++k) dst[m][k] = *(const LAS bf16x8*)(lds + G_SA(b, h) + aoff + m * 2048 + k * 1024); } while (0)
; #define G_LDB(dst, b, h) do { _Pragma("unroll") for (int n = 0; n < 2; ++n) _Pragma("unroll") for (int k = 0; k < 2; ++k) dst[n][k] = *(const LAS bf16x8*)(lds + G_SB(b, h) + boff + n * 2048 + k * 1024); } while (0)
; #define G_MMA(ai, bj, At_, Bt_) do { __builtin_amdgcn_s_setprio(1); _Pragma("unroll") for (int m = 0; m < 4; ++m) _Pragma("unroll") for (int n = 0; n < 2; ++n) _Pragma("unroll") for (int k = 0; k < 2; ++k) \
;         acc[ai][bj][m][n] = __builtin_amdgcn_mfma_f32_16x16x32_bf16(Bt_[n][k], At_[m][k], acc[ai][bj][m][n], 0, 0, 0); __builtin_amdgcn_s_setprio(0); } while (0)
; #define WAIT_V(n) asm volatile("s_waitcnt vmcnt(" #n ")" ::: "memory")
; template <class Get, class Epi>
; DI void gemm_loop(int ntiles, int ld, char* shm, const Get& get, const Epi& epi) {
;     ...
;         const int Ln = L + gridDim.x; const bool has_next = Ln < ntiles; if (has_next) nxt = get(Ln);
;         const char* nA = has_next ? (const char*)nxt.A + (size_t)nxt.brow * ld * 2 : cA; const char* nB = has_next ? (const char*)nxt.Bt + (size_t)nxt.bcol * ld * 2 : cB;
;         const int nt = cur.K / BK;
;         for (int t = 0; t < nt; t += 2) {
;             const bool last = (t == nt - 2);
;             const char* a1 = cA + (size_t)(t + 1) * kstep;
;             const char* a2 = last ? nA : cA + (size_t)(t + 2) * kstep; const char* b2 = last ? nB : cB + (size_t)(t + 2) * kstep;
;             const char* a3 = a2 + kstep; const char* b3 = b2 + kstep;
;             G_LDB(B0, 0, 0); G_LDB(B1, 0, 1); SCHED; G_LDA(At, 0, 0); G_STAGE(G_SA(1, 1), a1 + hstep, voffA);
;             WAIT_V(8); WAIT_L(0); BAR; G_MMA(0, 0, At, B0); G_MMA(0, 1, At, B1); BAR; SCHED;
;             G_LDA(At, 0, 1); G_STAGE(G_SB(0, 0), b2, voffB); G_STAGE(G_SB(0, 1), b2 + hstep, voffB); G_STAGE(G_SA(0, 0), a2, voffA);
;             WAIT_V(8); WAIT_L(0); BAR; G_MMA(1, 0, At, B0); G_MMA(1, 1, At, B1); BAR; SCHED;
.LBB0_332:
	ds_read_b128 v[0:3], v142
	ds_read_b128 v[4:7], v142 offset:1024
	ds_read_b128 v[8:11], v142 offset:2048
	ds_read_b128 v[12:15], v142 offset:3072
	ds_read_b128 v[16:19], v143
	ds_read_b128 v[20:23], v143 offset:1024
	ds_read_b128 v[24:27], v143 offset:2048
	ds_read_b128 v[28:31], v143 offset:3072
	s_ashr_i32 s37, s36, 31
	s_lshl_b64 s[42:43], s[36:37], 11
	s_add_u32 s42, s73, s42
	s_addc_u32 s43, s74, s43
	s_and_b64 s[44:45], s[38:39], exec
	s_cselect_b32 s55, s43, s15
	s_cselect_b32 s54, s42, s14
	s_ashr_i32 s41, s40, 31
	s_lshl_b64 s[44:45], s[40:41], 11
	s_add_u32 s44, s59, s44
	s_addc_u32 s45, s72, s45
	s_and_b64 s[46:47], s[38:39], exec
	s_cselect_b32 s47, s45, s51
	s_cselect_b32 s46, s44, s50
	s_add_u32 s94, s14, 0x40080
	s_addc_u32 s95, s15, 0
	s_mov_b32 m0, s81
	v_lshl_add_u64 v[64:65], s[94:95], 0, v[134:135]
	ds_read_b128 v[32:35], v144
	ds_read_b128 v[36:39], v144 offset:1024
	ds_read_b128 v[40:43], v144 offset:2048
	ds_read_b128 v[44:47], v144 offset:3072
	ds_read_b128 v[48:51], v144 offset:4096
	ds_read_b128 v[52:55], v144 offset:5120
	ds_read_b128 v[56:59], v144 offset:6144
	ds_read_b128 v[60:63], v144 offset:7168
	global_load_lds_dwordx4 v[64:65], off
	v_lshl_add_u64 v[64:65], s[94:95], 0, v[130:131]
	s_mov_b32 m0, s82
	s_nop 0
	global_load_lds_dwordx4 v[64:65], off
	s_waitcnt vmcnt(8)
	s_waitcnt lgkmcnt(0)
	s_barrier
	s_setprio 1
	v_mfma_f32_16x16x32_bf16 v[64:67], v[0:3], v[32:35], 0
	v_mfma_f32_16x16x32_bf16 v[68:71], v[8:11], v[32:35], 0
	v_mfma_f32_16x16x32_bf16 v[72:75], v[0:3], v[40:43], 0
	v_mfma_f32_16x16x32_bf16 v[76:79], v[8:11], v[40:43], 0
	v_mfma_f32_16x16x32_bf16 v[80:83], v[0:3], v[48:51], 0
	v_mfma_f32_16x16x32_bf16 v[84:87], v[8:11], v[48:51], 0
	v_mfma_f32_16x16x32_bf16 v[88:91], v[0:3], v[56:59], 0
	v_mfma_f32_16x16x32_bf16 v[92:95], v[8:11], v[56:59], 0
	v_mfma_f32_16x16x32_bf16 v[64:67], v[4:7], v[36:39], v[64:67]
	v_mfma_f32_16x16x32_bf16 v[68:71], v[12:15], v[36:39], v[68:71]
	v_mfma_f32_16x16x32_bf16 v[72:75], v[4:7], v[44:47], v[72:75]
	v_mfma_f32_16x16x32_bf16 v[76:79], v[12:15], v[44:47], v[76:79]
	v_mfma_f32_16x16x32_bf16 v[80:83], v[4:7], v[52:55], v[80:83]
	v_mfma_f32_16x16x32_bf16 v[84:87], v[12:15], v[52:55], v[84:87]
	v_mfma_f32_16x16x32_bf16 v[88:91], v[4:7], v[60:63], v[88:91]
	v_mfma_f32_16x16x32_bf16 v[92:95], v[12:15], v[60:63], v[92:95]
	s_setprio 0
	s_setprio 1
	v_mfma_f32_16x16x32_bf16 v[96:99], v[16:19], v[32:35], 0
	v_mfma_f32_16x16x32_bf16 v[32:35], v[24:27], v[32:35], 0
	v_mfma_f32_16x16x32_bf16 v[96:99], v[20:23], v[36:39], v[96:99]
	v_mfma_f32_16x16x32_bf16 v[32:35], v[28:31], v[36:39], v[32:35]
	v_mfma_f32_16x16x32_bf16 v[36:39], v[16:19], v[40:43], 0
	v_mfma_f32_16x16x32_bf16 v[40:43], v[24:27], v[40:43], 0
	v_mfma_f32_16x16x32_bf16 v[36:39], v[20:23], v[44:47], v[36:39]
	v_mfma_f32_16x16x32_bf16 v[40:43], v[28:31], v[44:47], v[40:43]
	v_mfma_f32_16x16x32_bf16 v[44:47], v[16:19], v[48:51], 0
	v_mfma_f32_16x16x32_bf16 v[48:51], v[24:27], v[48:51], 0
	v_mfma_f32_16x16x32_bf16 v[44:47], v[20:23], v[52:55], v[44:47]
	v_mfma_f32_16x16x32_bf16 v[48:51], v[28:31], v[52:55], v[48:51]
	v_mfma_f32_16x16x32_bf16 v[52:55], v[16:19], v[56:59], 0
	v_mfma_f32_16x16x32_bf16 v[56:59], v[24:27], v[56:59], 0
	v_mfma_f32_16x16x32_bf16 v[52:55], v[20:23], v[60:63], v[52:55]
	v_mfma_f32_16x16x32_bf16 v[56:59], v[28:31], v[60:63], v[56:59]
	s_setprio 0
	s_barrier
	v_lshl_add_u64 v[140:141], s[50:51], 0, v[132:133]
	s_mov_b32 m0, s83
	v_lshl_add_u64 v[136:137], v[140:141], 0, s[28:29]
	v_lshl_add_u64 v[184:185], s[50:51], 0, v[128:129]
	s_add_u32 s94, s50, 0x40100
	ds_read_b128 v[60:63], v144 offset:16384
	ds_read_b128 v[100:103], v144 offset:17408
	ds_read_b128 v[104:107], v144 offset:18432
	ds_read_b128 v[108:111], v144 offset:19456
	ds_read_b128 v[112:115], v144 offset:20480
	ds_read_b128 v[116:119], v144 offset:21504
	ds_read_b128 v[120:123], v144 offset:22528
	ds_read_b128 v[124:127], v144 offset:23552
	global_load_lds_dwordx4 v[136:137], off
	v_lshl_add_u64 v[136:137], v[184:185], 0, s[28:29]
	s_mov_b32 m0, s84
	s_addc_u32 s95, s51, 0
	global_load_lds_dwordx4 v[136:137], off
	v_lshl_add_u64 v[136:137], s[94:95], 0, v[132:133]
	s_mov_b32 m0, s85
	v_lshl_add_u64 v[186:187], s[14:15], 0, v[134:135]
	global_load_lds_dwordx4 v[136:137], off
	v_lshl_add_u64 v[136:137], s[94:95], 0, v[128:129]
	s_mov_b32 m0, s86
	v_lshl_add_u64 v[212:213], s[14:15], 0, v[130:131]
	global_load_lds_dwordx4 v[136:137], off
	v_lshl_add_u64 v[136:137], v[186:187], 0, s[28:29]
	s_mov_b32 m0, s58
	s_nop 0
	global_load_lds_dwordx4 v[136:137], off
	v_lshl_add_u64 v[136:137], v[212:213], 0, s[28:29]
	s_mov_b32 m0, s75
	s_nop 0
	global_load_lds_dwordx4 v[136:137], off
	s_waitcnt vmcnt(8)
	s_waitcnt lgkmcnt(0)
	s_barrier
; #define G_STAGE(bufoff, gbase, voff) do { _Pragma("unroll") for (int _i = 0; _i < 2; ++_i) \
;         __builtin_amdgcn_global_load_lds((const unsigned*)((const char*)(gbase) + voff[_i]), (LAS unsigned*)(lds + (bufoff) + ldsw + _i * 8192), 16, 0, 0); } while (0)
; #define G_LDA(dst, b, h) do { _Pragma("unroll") for (int m = 0; m < 4; ++m) _Pragma("unroll") for (int k = 0; k < 2; ++k) dst[m][k] = *(const LAS bf16x8*)(lds + G_SA(b, h) + aoff + m * 2048 + k * 1024); } while (0)
; #define G_LDB(dst, b, h) do { _Pragma("unroll") for (int n = 0; n < 2; ++n) _Pragma("unroll") for (int k = 0; k < 2; ++k) dst[n][k] = *(const LAS bf16x8*)(lds + G_SB(b, h) + boff + n * 2048 + k * 1024); } while (0)
; #define G_MMA(ai, bj, At_, Bt_) do { __builtin_amdgcn_s_setprio(1); _Pragma("unroll") for (int m = 0; m < 4; ++m) _Pragma("unroll") for (int n = 0; n < 2; ++n) _Pragma("unroll") for (int k = 0; k < 2; ++k) \
;         acc[ai][bj][m][n] = __builtin_amdgcn_mfma_f32_16x16x32_bf16(Bt_[n][k], At_[m][k], acc[ai][bj][m][n], 0, 0, 0); __builtin_amdgcn_s_setprio(0); } while (0)
; #define WAIT_V(n) asm volatile("s_waitcnt vmcnt(" #n ")" ::: "memory")
; #define WAIT_L(n) asm volatile("s_waitcnt lgkmcnt(" #n ")" ::: "memory")
; #define BAR __builtin_amdgcn_s_barrier()
; #define SCHED __builtin_amdgcn_sched_barrier(0)
; template <class Get, class Epi>
; DI void gemm_loop(int ntiles, int ld, char* shm, const Get& get, const Epi& epi) {
;     ...
;             G_LDA(At, 0, 1); G_STAGE(G_SB(0, 0), b2, voffB); G_STAGE(G_SB(0, 1), b2 + hstep, voffB); G_STAGE(G_SA(0, 0), a2, voffA);
;             WAIT_V(8); WAIT_L(0); BAR; G_MMA(1, 0, At, B0); G_MMA(1, 1, At, B1); BAR; SCHED;
;             G_LDB(B0, 1, 0); G_LDB(B1, 1, 1); SCHED; G_LDA(At, 1, 0); G_STAGE(G_SA(0, 1), a2 + hstep, voffA);
;             WAIT_V(8); WAIT_L(0); BAR; G_MMA(0, 0, At, B0); G_MMA(0, 1, At, B1); BAR; SCHED;
;             G_LDA(At, 1, 1); G_STAGE(G_SB(1, 0), b3, voffB); G_STAGE(G_SB(1, 1), b3 + hstep, voffB); G_STAGE(G_SA(1, 0), a3, voffA);
	s_setprio 1
	v_mfma_f32_16x16x32_bf16 v[136:139], v[0:3], v[60:63], 0
	v_mfma_f32_16x16x32_bf16 v[152:155], v[0:3], v[104:107], 0
	v_mfma_f32_16x16x32_bf16 v[160:163], v[0:3], v[112:115], 0
	v_mfma_f32_16x16x32_bf16 v[0:3], v[0:3], v[120:123], 0
	v_mfma_f32_16x16x32_bf16 v[136:139], v[4:7], v[100:103], v[136:139]
	v_mfma_f32_16x16x32_bf16 v[152:155], v[4:7], v[108:111], v[152:155]
	v_mfma_f32_16x16x32_bf16 v[160:163], v[4:7], v[116:119], v[160:163]
	v_mfma_f32_16x16x32_bf16 v[0:3], v[4:7], v[124:127], v[0:3]
	v_mfma_f32_16x16x32_bf16 v[4:7], v[8:11], v[120:123], 0
	v_mfma_f32_16x16x32_bf16 v[148:151], v[8:11], v[60:63], 0
	v_mfma_f32_16x16x32_bf16 v[156:159], v[8:11], v[104:107], 0
	v_mfma_f32_16x16x32_bf16 v[164:167], v[8:11], v[112:115], 0
	v_mfma_f32_16x16x32_bf16 v[4:7], v[12:15], v[124:127], v[4:7]
	v_mfma_f32_16x16x32_bf16 v[148:151], v[12:15], v[100:103], v[148:151]
	v_mfma_f32_16x16x32_bf16 v[156:159], v[12:15], v[108:111], v[156:159]
	v_mfma_f32_16x16x32_bf16 v[164:167], v[12:15], v[116:119], v[164:167]
	s_setprio 0
	s_setprio 1
	v_mfma_f32_16x16x32_bf16 v[8:11], v[16:19], v[60:63], 0
	v_mfma_f32_16x16x32_bf16 v[12:15], v[24:27], v[60:63], 0
	v_mfma_f32_16x16x32_bf16 v[8:11], v[20:23], v[100:103], v[8:11]
	v_mfma_f32_16x16x32_bf16 v[12:15], v[28:31], v[100:103], v[12:15]
	v_mfma_f32_16x16x32_bf16 v[60:63], v[16:19], v[104:107], 0
	v_mfma_f32_16x16x32_bf16 v[100:103], v[24:27], v[104:107], 0
	v_mfma_f32_16x16x32_bf16 v[104:107], v[16:19], v[112:115], 0
	v_mfma_f32_16x16x32_bf16 v[16:19], v[16:19], v[120:123], 0
	v_mfma_f32_16x16x32_bf16 v[60:63], v[20:23], v[108:111], v[60:63]
	v_mfma_f32_16x16x32_bf16 v[100:103], v[28:31], v[108:111], v[100:103]
	v_mfma_f32_16x16x32_bf16 v[104:107], v[20:23], v[116:119], v[104:107]
	v_mfma_f32_16x16x32_bf16 v[108:111], v[24:27], v[112:115], 0
	v_mfma_f32_16x16x32_bf16 v[16:19], v[20:23], v[124:127], v[16:19]
	v_mfma_f32_16x16x32_bf16 v[20:23], v[24:27], v[120:123], 0
	v_mfma_f32_16x16x32_bf16 v[108:111], v[28:31], v[116:119], v[108:111]
	v_mfma_f32_16x16x32_bf16 v[20:23], v[28:31], v[124:127], v[20:23]
	s_setprio 0
	s_barrier
	ds_read_b128 v[24:27], v145
	ds_read_b128 v[28:31], v145 offset:1024
	ds_read_b128 v[112:115], v145 offset:2048
	ds_read_b128 v[116:119], v145 offset:3072
	ds_read_b128 v[120:123], v146
	ds_read_b128 v[124:127], v146 offset:1024
	ds_read_b128 v[168:171], v146 offset:2048
	ds_read_b128 v[172:175], v146 offset:3072
	s_add_u32 s94, s14, 0x40100
	s_addc_u32 s95, s15, 0
	s_mov_b32 m0, s76
	v_lshl_add_u64 v[214:215], s[94:95], 0, v[134:135]
	ds_read_b128 v[176:179], v144 offset:32768
	ds_read_b128 v[180:183], v144 offset:33792
	ds_read_b128 v[188:191], v144 offset:34816
	ds_read_b128 v[192:195], v144 offset:35840
	ds_read_b128 v[196:199], v144 offset:36864
	ds_read_b128 v[200:203], v144 offset:37888
	ds_read_b128 v[204:207], v144 offset:38912
	ds_read_b128 v[208:211], v144 offset:39936
	global_load_lds_dwordx4 v[214:215], off
	v_lshl_add_u64 v[214:215], s[94:95], 0, v[130:131]
	s_mov_b32 m0, s78
	s_nop 0
	global_load_lds_dwordx4 v[214:215], off
	s_waitcnt vmcnt(8)
	s_waitcnt lgkmcnt(0)
	s_barrier
	s_setprio 1
	v_mfma_f32_16x16x32_bf16 v[64:67], v[24:27], v[176:179], v[64:67]
	v_mfma_f32_16x16x32_bf16 v[68:71], v[112:115], v[176:179], v[68:71]
	v_mfma_f32_16x16x32_bf16 v[72:75], v[24:27], v[188:191], v[72:75]
	v_mfma_f32_16x16x32_bf16 v[76:79], v[112:115], v[188:191], v[76:79]
	v_mfma_f32_16x16x32_bf16 v[80:83], v[24:27], v[196:199], v[80:83]
	v_mfma_f32_16x16x32_bf16 v[84:87], v[112:115], v[196:199], v[84:87]
	v_mfma_f32_16x16x32_bf16 v[88:91], v[24:27], v[204:207], v[88:91]
	v_mfma_f32_16x16x32_bf16 v[92:95], v[112:115], v[204:207], v[92:95]
	v_mfma_f32_16x16x32_bf16 v[64:67], v[28:31], v[180:183], v[64:67]
	v_mfma_f32_16x16x32_bf16 v[68:71], v[116:119], v[180:183], v[68:71]
	v_mfma_f32_16x16x32_bf16 v[72:75], v[28:31], v[192:195], v[72:75]
	v_mfma_f32_16x16x32_bf16 v[76:79], v[116:119], v[192:195], v[76:79]
	v_mfma_f32_16x16x32_bf16 v[80:83], v[28:31], v[200:203], v[80:83]
	v_mfma_f32_16x16x32_bf16 v[84:87], v[116:119], v[200:203], v[84:87]
	v_mfma_f32_16x16x32_bf16 v[88:91], v[28:31], v[208:211], v[88:91]
	v_mfma_f32_16x16x32_bf16 v[92:95], v[116:119], v[208:211], v[92:95]
	s_setprio 0
	s_setprio 1
	v_mfma_f32_16x16x32_bf16 v[96:99], v[120:123], v[176:179], v[96:99]
	v_mfma_f32_16x16x32_bf16 v[32:35], v[168:171], v[176:179], v[32:35]
	v_mfma_f32_16x16x32_bf16 v[36:39], v[120:123], v[188:191], v[36:39]
	v_mfma_f32_16x16x32_bf16 v[40:43], v[168:171], v[188:191], v[40:43]
	v_mfma_f32_16x16x32_bf16 v[44:47], v[120:123], v[196:199], v[44:47]
	v_mfma_f32_16x16x32_bf16 v[48:51], v[168:171], v[196:199], v[48:51]
	v_mfma_f32_16x16x32_bf16 v[52:55], v[120:123], v[204:207], v[52:55]
	v_mfma_f32_16x16x32_bf16 v[56:59], v[168:171], v[204:207], v[56:59]
	v_mfma_f32_16x16x32_bf16 v[96:99], v[124:127], v[180:183], v[96:99]
	v_mfma_f32_16x16x32_bf16 v[32:35], v[172:175], v[180:183], v[32:35]
	v_mfma_f32_16x16x32_bf16 v[36:39], v[124:127], v[192:195], v[36:39]
	v_mfma_f32_16x16x32_bf16 v[40:43], v[172:175], v[192:195], v[40:43]
	v_mfma_f32_16x16x32_bf16 v[44:47], v[124:127], v[200:203], v[44:47]
	v_mfma_f32_16x16x32_bf16 v[48:51], v[172:175], v[200:203], v[48:51]
	v_mfma_f32_16x16x32_bf16 v[52:55], v[124:127], v[208:211], v[52:55]
	v_mfma_f32_16x16x32_bf16 v[56:59], v[172:175], v[208:211], v[56:59]
	s_setprio 0
	s_barrier
; #define G_STAGE(bufoff, gbase, voff) do { _Pragma("unroll") for (int _i = 0; _i < 2; ++_i) \
;         __builtin_amdgcn_global_load_lds((const unsigned*)((const char*)(gbase) + voff[_i]), (LAS unsigned*)(lds + (bufoff) + ldsw + _i * 8192), 16, 0, 0); } while (0)
; #define G_LDA(dst, b, h) do { _Pragma("unroll") for (int m = 0; m < 4; ++m) _Pragma("unroll") for (int k = 0; k < 2; ++k) dst[m][k] = *(const LAS bf16x8*)(lds + G_SA(b, h) + aoff + m * 2048 + k * 1024); } while (0)
; #define G_LDB(dst, b, h) do { _Pragma("unroll") for (int n = 0; n < 2; ++n) _Pragma("unroll") for (int k = 0; k < 2; ++k) dst[n][k] = *(const LAS bf16x8*)(lds + G_SB(b, h) + boff + n * 2048 + k * 1024); } while (0)
; #define G_MMA(ai, bj, At_, Bt_) do { __builtin_amdgcn_s_setprio(1); _Pragma("unroll") for (int m = 0; m < 4; ++m) _Pragma("unroll") for (int n = 0; n < 2; ++n) _Pragma("unroll") for (int k = 0; k < 2; ++k) \
;         acc[ai][bj][m][n] = __builtin_amdgcn_mfma_f32_16x16x32_bf16(Bt_[n][k], At_[m][k], acc[ai][bj][m][n], 0, 0, 0); __builtin_amdgcn_s_setprio(0); } while (0)
; #define WAIT_V(n) asm volatile("s_waitcnt vmcnt(" #n ")" ::: "memory")
; #define WAIT_L(n) asm volatile("s_waitcnt lgkmcnt(" #n ")" ::: "memory")
; #define BAR __builtin_amdgcn_s_barrier()
; #define SCHED __builtin_amdgcn_sched_barrier(0)
; template <class Get, class Epi>
; DI void gemm_loop(int ntiles, int ld, char* shm, const Get& get, const Epi& epi) {
;     ...
;             G_LDB(B0, 0, 0); G_LDB(B1, 0, 1); SCHED; G_LDA(At, 0, 0); G_STAGE(G_SA(1, 1), a1 + hstep, voffA);
;             WAIT_V(8); WAIT_L(0); BAR; G_MMA(0, 0, At, B0); G_MMA(0, 1, At, B1); BAR; SCHED;
;     ...
;             G_LDB(B0, 1, 0); G_LDB(B1, 1, 1); SCHED; G_LDA(At, 1, 0); G_STAGE(G_SA(0, 1), a2 + hstep, voffA);
;             WAIT_V(8); WAIT_L(0); BAR; G_MMA(0, 0, At, B0); G_MMA(0, 1, At, B1); BAR; SCHED;
;             G_LDA(At, 1, 1); G_STAGE(G_SB(1, 0), b3, voffB); G_STAGE(G_SB(1, 1), b3 + hstep, voffB); G_STAGE(G_SA(1, 0), a3, voffA);
;             WAIT_V(8); WAIT_L(0); BAR; G_MMA(1, 0, At, B0); G_MMA(1, 1, At, B1); BAR; SCHED;
	s_mov_b32 m0, s87
	v_lshl_add_u64 v[140:141], v[140:141], 0, s[30:31]
	s_add_u32 s50, s50, 0x40180
	ds_read_b128 v[176:179], v144 offset:49152
	ds_read_b128 v[180:183], v144 offset:50176
	ds_read_b128 v[188:191], v144 offset:51200
	ds_read_b128 v[192:195], v144 offset:52224
	ds_read_b128 v[196:199], v144 offset:53248
	ds_read_b128 v[200:203], v144 offset:54272
	ds_read_b128 v[204:207], v144 offset:55296
	ds_read_b128 v[208:211], v144 offset:56320
	global_load_lds_dwordx4 v[140:141], off
	v_lshl_add_u64 v[140:141], v[184:185], 0, s[30:31]
	s_mov_b32 m0, s88
	s_addc_u32 s51, s51, 0
	global_load_lds_dwordx4 v[140:141], off
	v_lshl_add_u64 v[140:141], s[50:51], 0, v[132:133]
	s_mov_b32 m0, s89
	s_nop 0
	global_load_lds_dwordx4 v[140:141], off
	v_lshl_add_u64 v[140:141], s[50:51], 0, v[128:129]
	s_mov_b32 m0, s90
	s_nop 0
	global_load_lds_dwordx4 v[140:141], off
	v_lshl_add_u64 v[140:141], v[186:187], 0, s[30:31]
	s_mov_b32 m0, s79
	s_nop 0
	global_load_lds_dwordx4 v[140:141], off
	v_lshl_add_u64 v[140:141], v[212:213], 0, s[30:31]
	s_mov_b32 m0, s80
	s_nop 0
	global_load_lds_dwordx4 v[140:141], off
	s_waitcnt vmcnt(8)
	s_waitcnt lgkmcnt(0)
	s_barrier
	s_setprio 1
	v_mfma_f32_16x16x32_bf16 v[0:3], v[24:27], v[204:207], v[0:3]
	v_mfma_f32_16x16x32_bf16 v[4:7], v[112:115], v[204:207], v[4:7]
	v_mfma_f32_16x16x32_bf16 v[136:139], v[24:27], v[176:179], v[136:139]
	v_mfma_f32_16x16x32_bf16 v[148:151], v[112:115], v[176:179], v[148:151]
	v_mfma_f32_16x16x32_bf16 v[152:155], v[24:27], v[188:191], v[152:155]
	v_mfma_f32_16x16x32_bf16 v[156:159], v[112:115], v[188:191], v[156:159]
	v_mfma_f32_16x16x32_bf16 v[160:163], v[24:27], v[196:199], v[160:163]
	v_mfma_f32_16x16x32_bf16 v[164:167], v[112:115], v[196:199], v[164:167]
	v_mfma_f32_16x16x32_bf16 v[0:3], v[28:31], v[208:211], v[0:3]
	v_mfma_f32_16x16x32_bf16 v[4:7], v[116:119], v[208:211], v[4:7]
	v_mfma_f32_16x16x32_bf16 v[136:139], v[28:31], v[180:183], v[136:139]
	v_mfma_f32_16x16x32_bf16 v[148:151], v[116:119], v[180:183], v[148:151]
	v_mfma_f32_16x16x32_bf16 v[152:155], v[28:31], v[192:195], v[152:155]
	v_mfma_f32_16x16x32_bf16 v[156:159], v[116:119], v[192:195], v[156:159]
	v_mfma_f32_16x16x32_bf16 v[160:163], v[28:31], v[200:203], v[160:163]
	v_mfma_f32_16x16x32_bf16 v[164:167], v[116:119], v[200:203], v[164:167]
	s_setprio 0
	s_setprio 1
	v_mfma_f32_16x16x32_bf16 v[8:11], v[120:123], v[176:179], v[8:11]
	v_mfma_f32_16x16x32_bf16 v[12:15], v[168:171], v[176:179], v[12:15]
	v_mfma_f32_16x16x32_bf16 v[24:27], v[120:123], v[188:191], v[60:63]
	v_mfma_f32_16x16x32_bf16 v[28:31], v[168:171], v[188:191], v[100:103]
	v_mfma_f32_16x16x32_bf16 v[60:63], v[120:123], v[196:199], v[104:107]
	v_mfma_f32_16x16x32_bf16 v[100:103], v[168:171], v[196:199], v[108:111]
	v_mfma_f32_16x16x32_bf16 v[16:19], v[120:123], v[204:207], v[16:19]
	v_mfma_f32_16x16x32_bf16 v[20:23], v[168:171], v[204:207], v[20:23]
	v_mfma_f32_16x16x32_bf16 v[8:11], v[124:127], v[180:183], v[8:11]
	v_mfma_f32_16x16x32_bf16 v[12:15], v[172:175], v[180:183], v[12:15]
	v_mfma_f32_16x16x32_bf16 v[24:27], v[124:127], v[192:195], v[24:27]
	v_mfma_f32_16x16x32_bf16 v[28:31], v[172:175], v[192:195], v[28:31]
	v_mfma_f32_16x16x32_bf16 v[60:63], v[124:127], v[200:203], v[60:63]
	v_mfma_f32_16x16x32_bf16 v[100:103], v[172:175], v[200:203], v[100:103]
	v_mfma_f32_16x16x32_bf16 v[16:19], v[124:127], v[208:211], v[16:19]
	v_mfma_f32_16x16x32_bf16 v[20:23], v[172:175], v[208:211], v[20:23]
	s_setprio 0
	s_barrier
	ds_read_b128 v[104:107], v142
	ds_read_b128 v[108:111], v142 offset:1024
	ds_read_b128 v[112:115], v142 offset:2048
	ds_read_b128 v[116:119], v142 offset:3072
	ds_read_b128 v[120:123], v143
	ds_read_b128 v[124:127], v143 offset:1024
	ds_read_b128 v[168:171], v143 offset:2048
	ds_read_b128 v[172:175], v143 offset:3072
	s_add_u32 s14, s14, 0x40180
	s_addc_u32 s15, s15, 0
	s_mov_b32 m0, s81
	v_lshl_add_u64 v[140:141], s[14:15], 0, v[134:135]
	ds_read_b128 v[176:179], v144
	ds_read_b128 v[180:183], v144 offset:1024
	ds_read_b128 v[188:191], v144 offset:2048
	ds_read_b128 v[192:195], v144 offset:3072
	ds_read_b128 v[196:199], v144 offset:4096
	ds_read_b128 v[200:203], v144 offset:5120
	ds_read_b128 v[204:207], v144 offset:6144
	ds_read_b128 v[208:211], v144 offset:7168
	global_load_lds_dwordx4 v[140:141], off
	v_lshl_add_u64 v[140:141], s[14:15], 0, v[130:131]
	s_mov_b32 m0, s82
	s_nop 0
	global_load_lds_dwordx4 v[140:141], off
	s_waitcnt vmcnt(8)
	s_waitcnt lgkmcnt(0)
	s_barrier
	s_setprio 1
	v_mfma_f32_16x16x32_bf16 v[64:67], v[104:107], v[176:179], v[64:67]
	v_mfma_f32_16x16x32_bf16 v[68:71], v[112:115], v[176:179], v[68:71]
	v_mfma_f32_16x16x32_bf16 v[72:75], v[104:107], v[188:191], v[72:75]
	v_mfma_f32_16x16x32_bf16 v[76:79], v[112:115], v[188:191], v[76:79]
	v_mfma_f32_16x16x32_bf16 v[80:83], v[104:107], v[196:199], v[80:83]
	v_mfma_f32_16x16x32_bf16 v[84:87], v[112:115], v[196:199], v[84:87]
	v_mfma_f32_16x16x32_bf16 v[88:91], v[104:107], v[204:207], v[88:91]
	v_mfma_f32_16x16x32_bf16 v[92:95], v[112:115], v[204:207], v[92:95]
	v_mfma_f32_16x16x32_bf16 v[64:67], v[108:111], v[180:183], v[64:67]
	v_mfma_f32_16x16x32_bf16 v[68:71], v[116:119], v[180:183], v[68:71]
	v_mfma_f32_16x16x32_bf16 v[72:75], v[108:111], v[192:195], v[72:75]
	v_mfma_f32_16x16x32_bf16 v[76:79], v[116:119], v[192:195], v[76:79]
	v_mfma_f32_16x16x32_bf16 v[80:83], v[108:111], v[200:203], v[80:83]
	v_mfma_f32_16x16x32_bf16 v[84:87], v[116:119], v[200:203], v[84:87]
	v_mfma_f32_16x16x32_bf16 v[88:91], v[108:111], v[208:211], v[88:91]
	v_mfma_f32_16x16x32_bf16 v[92:95], v[116:119], v[208:211], v[92:95]
	s_setprio 0
	s_setprio 1
	v_mfma_f32_16x16x32_bf16 v[48:51], v[168:171], v[196:199], v[48:51]
	v_mfma_f32_16x16x32_bf16 v[96:99], v[120:123], v[176:179], v[96:99]
	v_mfma_f32_16x16x32_bf16 v[32:35], v[168:171], v[176:179], v[32:35]
	v_mfma_f32_16x16x32_bf16 v[176:179], v[172:175], v[200:203], v[48:51]
	v_mfma_f32_16x16x32_bf16 v[48:51], v[120:123], v[204:207], v[52:55]
	v_mfma_f32_16x16x32_bf16 v[212:215], v[124:127], v[180:183], v[96:99]
	v_mfma_f32_16x16x32_bf16 v[32:35], v[172:175], v[180:183], v[32:35]
	v_mfma_f32_16x16x32_bf16 v[36:39], v[120:123], v[188:191], v[36:39]
	v_mfma_f32_16x16x32_bf16 v[40:43], v[168:171], v[188:191], v[40:43]
	v_mfma_f32_16x16x32_bf16 v[44:47], v[120:123], v[196:199], v[44:47]
	v_mfma_f32_16x16x32_bf16 v[180:183], v[124:127], v[208:211], v[48:51]
	v_mfma_f32_16x16x32_bf16 v[48:51], v[168:171], v[204:207], v[56:59]
	v_mfma_f32_16x16x32_bf16 v[36:39], v[124:127], v[192:195], v[36:39]
	v_mfma_f32_16x16x32_bf16 v[40:43], v[172:175], v[192:195], v[40:43]
	v_mfma_f32_16x16x32_bf16 v[44:47], v[124:127], v[200:203], v[44:47]
	v_mfma_f32_16x16x32_bf16 v[56:59], v[172:175], v[208:211], v[48:51]
	s_setprio 0
	s_barrier
; #define G_STAGE(bufoff, gbase, voff) do { _Pragma("unroll") for (int _i = 0; _i < 2; ++_i) \
;         __builtin_amdgcn_global_load_lds((const unsigned*)((const char*)(gbase) + voff[_i]), (LAS unsigned*)(lds + (bufoff) + ldsw + _i * 8192), 16, 0, 0); } while (0)
; #define G_LDA(dst, b, h) do { _Pragma("unroll") for (int m = 0; m < 4; ++m) _Pragma("unroll") for (int k = 0; k < 2; ++k) dst[m][k] = *(const LAS bf16x8*)(lds + G_SA(b, h) + aoff + m * 2048 + k * 1024); } while (0)
; #define G_LDB(dst, b, h) do { _Pragma("unroll") for (int n = 0; n < 2; ++n) _Pragma("unroll") for (int k = 0; k < 2; ++k) dst[n][k] = *(const LAS bf16x8*)(lds + G_SB(b, h) + boff + n * 2048 + k * 1024); } while (0)
; #define G_MMA(ai, bj, At_, Bt_) do { __builtin_amdgcn_s_setprio(1); _Pragma("unroll") for (int m = 0; m < 4; ++m) _Pragma("unroll") for (int n = 0; n < 2; ++n) _Pragma("unroll") for (int k = 0; k < 2; ++k) \
;         acc[ai][bj][m][n] = __builtin_amdgcn_mfma_f32_16x16x32_bf16(Bt_[n][k], At_[m][k], acc[ai][bj][m][n], 0, 0, 0); __builtin_amdgcn_s_setprio(0); } while (0)
; #define WAIT_V(n) asm volatile("s_waitcnt vmcnt(" #n ")" ::: "memory")
; #define WAIT_L(n) asm volatile("s_waitcnt lgkmcnt(" #n ")" ::: "memory")
; #define BAR __builtin_amdgcn_s_barrier()
; #define SCHED __builtin_amdgcn_sched_barrier(0)
; template <class Get, class Epi>
; DI void gemm_loop(int ntiles, int ld, char* shm, const Get& get, const Epi& epi) {
;     ...
;             G_LDA(At, 0, 1); G_STAGE(G_SB(0, 0), b2, voffB); G_STAGE(G_SB(0, 1), b2 + hstep, voffB); G_STAGE(G_SA(0, 0), a2, voffA);
;             WAIT_V(8); WAIT_L(0); BAR; G_MMA(1, 0, At, B0); G_MMA(1, 1, At, B1); BAR; SCHED;
;             G_LDB(B0, 1, 0); G_LDB(B1, 1, 1); SCHED; G_LDA(At, 1, 0); G_STAGE(G_SA(0, 1), a2 + hstep, voffA);
;             WAIT_V(8); WAIT_L(0); BAR; G_MMA(0, 0, At, B0); G_MMA(0, 1, At, B1); BAR; SCHED;
;             G_LDA(At, 1, 1); G_STAGE(G_SB(1, 0), b3, voffB); G_STAGE(G_SB(1, 1), b3 + hstep, voffB); G_STAGE(G_SA(1, 0), a3, voffA);
	s_mov_b32 m0, s83
	v_lshl_add_u64 v[140:141], s[46:47], 0, v[132:133]
	s_add_u32 s14, s46, 0x40000
	ds_read_b128 v[48:51], v144 offset:16384
	ds_read_b128 v[52:55], v144 offset:17408
	ds_read_b128 v[96:99], v144 offset:18432
	ds_read_b128 v[188:191], v144 offset:19456
	ds_read_b128 v[192:195], v144 offset:20480
	ds_read_b128 v[196:199], v144 offset:21504
	ds_read_b128 v[200:203], v144 offset:22528
	ds_read_b128 v[204:207], v144 offset:23552
	global_load_lds_dwordx4 v[140:141], off
	v_lshl_add_u64 v[184:185], s[46:47], 0, v[128:129]
	s_mov_b32 m0, s84
	s_addc_u32 s15, s47, 0
	global_load_lds_dwordx4 v[184:185], off
	v_lshl_add_u64 v[186:187], s[14:15], 0, v[132:133]
	s_mov_b32 m0, s85
	v_lshl_add_u64 v[248:249], s[54:55], 0, v[130:131]
	global_load_lds_dwordx4 v[186:187], off
	v_lshl_add_u64 v[186:187], s[14:15], 0, v[128:129]
	s_mov_b32 m0, s86
	s_nop 0
	global_load_lds_dwordx4 v[186:187], off
	v_lshl_add_u64 v[186:187], s[54:55], 0, v[134:135]
	s_mov_b32 m0, s58
	s_nop 0
	global_load_lds_dwordx4 v[186:187], off
	s_mov_b32 m0, s75
	s_nop 0
	global_load_lds_dwordx4 v[248:249], off
	s_waitcnt vmcnt(8)
	s_waitcnt lgkmcnt(0)
	s_barrier
	s_setprio 1
	v_mfma_f32_16x16x32_bf16 v[0:3], v[104:107], v[200:203], v[0:3]
	v_mfma_f32_16x16x32_bf16 v[4:7], v[112:115], v[200:203], v[4:7]
	v_mfma_f32_16x16x32_bf16 v[136:139], v[104:107], v[48:51], v[136:139]
	v_mfma_f32_16x16x32_bf16 v[148:151], v[112:115], v[48:51], v[148:151]
	v_mfma_f32_16x16x32_bf16 v[152:155], v[104:107], v[96:99], v[152:155]
	v_mfma_f32_16x16x32_bf16 v[156:159], v[112:115], v[96:99], v[156:159]
	v_mfma_f32_16x16x32_bf16 v[160:163], v[104:107], v[192:195], v[160:163]
	v_mfma_f32_16x16x32_bf16 v[164:167], v[112:115], v[192:195], v[164:167]
	v_mfma_f32_16x16x32_bf16 v[0:3], v[108:111], v[204:207], v[0:3]
	v_mfma_f32_16x16x32_bf16 v[4:7], v[116:119], v[204:207], v[4:7]
	v_mfma_f32_16x16x32_bf16 v[136:139], v[108:111], v[52:55], v[136:139]
	v_mfma_f32_16x16x32_bf16 v[148:151], v[116:119], v[52:55], v[148:151]
	v_mfma_f32_16x16x32_bf16 v[152:155], v[108:111], v[188:191], v[152:155]
	v_mfma_f32_16x16x32_bf16 v[156:159], v[116:119], v[188:191], v[156:159]
	v_mfma_f32_16x16x32_bf16 v[160:163], v[108:111], v[196:199], v[160:163]
	v_mfma_f32_16x16x32_bf16 v[164:167], v[116:119], v[196:199], v[164:167]
	s_setprio 0
	s_setprio 1
	v_mfma_f32_16x16x32_bf16 v[8:11], v[120:123], v[48:51], v[8:11]
	v_mfma_f32_16x16x32_bf16 v[12:15], v[168:171], v[48:51], v[12:15]
	v_mfma_f32_16x16x32_bf16 v[24:27], v[120:123], v[96:99], v[24:27]
	v_mfma_f32_16x16x32_bf16 v[28:31], v[168:171], v[96:99], v[28:31]
	v_mfma_f32_16x16x32_bf16 v[48:51], v[120:123], v[192:195], v[60:63]
	v_mfma_f32_16x16x32_bf16 v[24:27], v[124:127], v[188:191], v[24:27]
	v_mfma_f32_16x16x32_bf16 v[28:31], v[172:175], v[188:191], v[28:31]
	v_mfma_f32_16x16x32_bf16 v[188:191], v[124:127], v[196:199], v[48:51]
	v_mfma_f32_16x16x32_bf16 v[48:51], v[168:171], v[192:195], v[100:103]
	v_mfma_f32_16x16x32_bf16 v[16:19], v[120:123], v[200:203], v[16:19]
	v_mfma_f32_16x16x32_bf16 v[8:11], v[124:127], v[52:55], v[8:11]
	v_mfma_f32_16x16x32_bf16 v[12:15], v[172:175], v[52:55], v[12:15]
	v_mfma_f32_16x16x32_bf16 v[192:195], v[172:175], v[196:199], v[48:51]
	v_mfma_f32_16x16x32_bf16 v[196:199], v[124:127], v[204:207], v[16:19]
	v_mfma_f32_16x16x32_bf16 v[16:19], v[168:171], v[200:203], v[20:23]
	v_mfma_f32_16x16x32_bf16 v[168:171], v[172:175], v[204:207], v[16:19]
	s_setprio 0
	s_barrier
	ds_read_b128 v[172:175], v145
	ds_read_b128 v[200:203], v145 offset:1024
	ds_read_b128 v[204:207], v145 offset:2048
	ds_read_b128 v[208:211], v145 offset:3072
	ds_read_b128 v[216:219], v146
	ds_read_b128 v[220:223], v146 offset:1024
	ds_read_b128 v[224:227], v146 offset:2048
	ds_read_b128 v[228:231], v146 offset:3072
	s_add_u32 s14, s54, 0x40000
	s_addc_u32 s15, s55, 0
	s_mov_b32 m0, s76
	v_lshl_add_u64 v[48:49], s[14:15], 0, v[134:135]
	ds_read_b128 v[16:19], v144 offset:32768
	ds_read_b128 v[20:23], v144 offset:33792
	ds_read_b128 v[60:63], v144 offset:34816
	ds_read_b128 v[108:111], v144 offset:35840
	ds_read_b128 v[232:235], v144 offset:36864
	ds_read_b128 v[236:239], v144 offset:37888
	ds_read_b128 v[240:243], v144 offset:38912
	ds_read_b128 v[244:247], v144 offset:39936
	global_load_lds_dwordx4 v[48:49], off
	v_lshl_add_u64 v[48:49], s[14:15], 0, v[130:131]
	s_mov_b32 m0, s78
	s_nop 0
	global_load_lds_dwordx4 v[48:49], off
	s_waitcnt vmcnt(8)
	s_waitcnt lgkmcnt(0)
	s_barrier
; #define G_STAGE(bufoff, gbase, voff) do { _Pragma("unroll") for (int _i = 0; _i < 2; ++_i) \
;         __builtin_amdgcn_global_load_lds((const unsigned*)((const char*)(gbase) + voff[_i]), (LAS unsigned*)(lds + (bufoff) + ldsw + _i * 8192), 16, 0, 0); } while (0)
; #define G_LDA(dst, b, h) do { _Pragma("unroll") for (int m = 0; m < 4; ++m) _Pragma("unroll") for (int k = 0; k < 2; ++k) dst[m][k] = *(const LAS bf16x8*)(lds + G_SA(b, h) + aoff + m * 2048 + k * 1024); } while (0)
; #define G_MMA(ai, bj, At_, Bt_) do { __builtin_amdgcn_s_setprio(1); _Pragma("unroll") for (int m = 0; m < 4; ++m) _Pragma("unroll") for (int n = 0; n < 2; ++n) _Pragma("unroll") for (int k = 0; k < 2; ++k) \
;         acc[ai][bj][m][n] = __builtin_amdgcn_mfma_f32_16x16x32_bf16(Bt_[n][k], At_[m][k], acc[ai][bj][m][n], 0, 0, 0); __builtin_amdgcn_s_setprio(0); } while (0)
; #define WAIT_V(n) asm volatile("s_waitcnt vmcnt(" #n ")" ::: "memory")
; #define WAIT_L(n) asm volatile("s_waitcnt lgkmcnt(" #n ")" ::: "memory")
; #define BAR __builtin_amdgcn_s_barrier()
; #define SCHED __builtin_amdgcn_sched_barrier(0)
; template <class Get, class Epi>
; DI void gemm_loop(int ntiles, int ld, char* shm, const Get& get, const Epi& epi) {
;     ...
;             WAIT_V(8); WAIT_L(0); BAR; G_MMA(0, 0, At, B0); G_MMA(0, 1, At, B1); BAR; SCHED;
;             G_LDA(At, 1, 1); G_STAGE(G_SB(1, 0), b3, voffB); G_STAGE(G_SB(1, 1), b3 + hstep, voffB); G_STAGE(G_SA(1, 0), a3, voffA);
;             WAIT_V(8); WAIT_L(0); BAR; G_MMA(1, 0, At, B0); G_MMA(1, 1, At, B1); BAR; SCHED;
;         }
;         if (wr == 0) BAR;
;         { int tx2 = threadIdx.x, brow2 = cur.brow, bcol2 = cur.bcol, Lo = L; asm volatile("" : "+v"(tx2), "+s"(brow2), "+s"(bcol2), "+s"(Lo));
;           const int wid2 = tx2 >> 6, lane2 = tx2 & 63; epi(Lo, acc, brow2, bcol2, wid2 >> 2, wid2 & 3, lane2 & 15, lane2 >> 4); }
;         if (!has_next) break;
	s_setprio 1
	v_mfma_f32_16x16x32_bf16 v[48:51], v[172:175], v[16:19], v[64:67]
	v_mfma_f32_16x16x32_bf16 v[112:115], v[200:203], v[20:23], v[48:51]
	v_mfma_f32_16x16x32_bf16 v[48:51], v[204:207], v[16:19], v[68:71]
	v_mfma_f32_16x16x32_bf16 v[116:119], v[208:211], v[20:23], v[48:51]
	v_mfma_f32_16x16x32_bf16 v[48:51], v[172:175], v[60:63], v[72:75]
	v_mfma_f32_16x16x32_bf16 v[96:99], v[200:203], v[108:111], v[48:51]
	v_mfma_f32_16x16x32_bf16 v[48:51], v[204:207], v[60:63], v[76:79]
	v_mfma_f32_16x16x32_bf16 v[100:103], v[208:211], v[108:111], v[48:51]
	v_mfma_f32_16x16x32_bf16 v[48:51], v[172:175], v[232:235], v[80:83]
	v_mfma_f32_16x16x32_bf16 v[80:83], v[200:203], v[236:239], v[48:51]
	v_mfma_f32_16x16x32_bf16 v[48:51], v[204:207], v[232:235], v[84:87]
	v_mfma_f32_16x16x32_bf16 v[84:87], v[208:211], v[236:239], v[48:51]
	v_mfma_f32_16x16x32_bf16 v[48:51], v[172:175], v[240:243], v[88:91]
	v_mfma_f32_16x16x32_bf16 v[52:55], v[204:207], v[240:243], v[92:95]
	v_mfma_f32_16x16x32_bf16 v[48:51], v[200:203], v[244:247], v[48:51]
	v_mfma_f32_16x16x32_bf16 v[52:55], v[208:211], v[244:247], v[52:55]
	s_setprio 0
	s_setprio 1
	v_mfma_f32_16x16x32_bf16 v[64:67], v[216:219], v[16:19], v[212:215]
	v_mfma_f32_16x16x32_bf16 v[16:19], v[224:227], v[16:19], v[32:35]
	v_mfma_f32_16x16x32_bf16 v[124:127], v[228:231], v[20:23], v[16:19]
	v_mfma_f32_16x16x32_bf16 v[16:19], v[216:219], v[60:63], v[36:39]
	v_mfma_f32_16x16x32_bf16 v[104:107], v[220:223], v[108:111], v[16:19]
	v_mfma_f32_16x16x32_bf16 v[16:19], v[224:227], v[60:63], v[40:43]
	v_mfma_f32_16x16x32_bf16 v[108:111], v[228:231], v[108:111], v[16:19]
	v_mfma_f32_16x16x32_bf16 v[16:19], v[216:219], v[232:235], v[44:47]
	v_mfma_f32_16x16x32_bf16 v[88:91], v[220:223], v[236:239], v[16:19]
	v_mfma_f32_16x16x32_bf16 v[16:19], v[224:227], v[232:235], v[176:179]
	v_mfma_f32_16x16x32_bf16 v[92:95], v[228:231], v[236:239], v[16:19]
	v_mfma_f32_16x16x32_bf16 v[16:19], v[216:219], v[240:243], v[180:183]
	v_mfma_f32_16x16x32_bf16 v[120:123], v[220:223], v[20:23], v[64:67]
	v_mfma_f32_16x16x32_bf16 v[64:67], v[220:223], v[244:247], v[16:19]
	v_mfma_f32_16x16x32_bf16 v[16:19], v[224:227], v[240:243], v[56:59]
	v_mfma_f32_16x16x32_bf16 v[68:71], v[228:231], v[244:247], v[16:19]
	s_setprio 0
	s_barrier
	s_mov_b32 m0, s87
	s_nop 3
	v_lshl_add_u64 v[16:17], v[140:141], 0, s[12:13]
	s_add_u32 s14, s46, 0x40080
	ds_read_b128 v[40:43], v144 offset:49152
	ds_read_b128 v[44:47], v144 offset:50176
	ds_read_b128 v[176:179], v144 offset:51200
	ds_read_b128 v[180:183], v144 offset:52224
	ds_read_b128 v[212:215], v144 offset:53248
	ds_read_b128 v[232:235], v144 offset:54272
	ds_read_b128 v[236:239], v144 offset:55296
	ds_read_b128 v[240:243], v144 offset:56320
	global_load_lds_dwordx4 v[16:17], off
	v_lshl_add_u64 v[16:17], v[184:185], 0, s[12:13]
	s_mov_b32 m0, s88
	s_addc_u32 s15, s47, 0
	global_load_lds_dwordx4 v[16:17], off
	v_lshl_add_u64 v[16:17], s[14:15], 0, v[132:133]
	s_mov_b32 m0, s89
	s_nop 0
	global_load_lds_dwordx4 v[16:17], off
	v_lshl_add_u64 v[16:17], s[14:15], 0, v[128:129]
	s_mov_b32 m0, s90
	s_nop 0
	global_load_lds_dwordx4 v[16:17], off
	v_lshl_add_u64 v[16:17], v[186:187], 0, s[12:13]
	s_mov_b32 m0, s79
	s_nop 0
	global_load_lds_dwordx4 v[16:17], off
	v_lshl_add_u64 v[16:17], v[248:249], 0, s[12:13]
	s_mov_b32 m0, s80
	s_nop 0
	global_load_lds_dwordx4 v[16:17], off
	s_waitcnt vmcnt(8)
	s_waitcnt lgkmcnt(0)
	s_barrier
	s_setprio 1
	v_mfma_f32_16x16x32_bf16 v[16:19], v[172:175], v[40:43], v[136:139]
	v_mfma_f32_16x16x32_bf16 v[56:59], v[200:203], v[44:47], v[16:19]
	v_mfma_f32_16x16x32_bf16 v[16:19], v[204:207], v[40:43], v[148:151]
	v_mfma_f32_16x16x32_bf16 v[60:63], v[208:211], v[44:47], v[16:19]
	v_mfma_f32_16x16x32_bf16 v[16:19], v[172:175], v[176:179], v[152:155]
	v_mfma_f32_16x16x32_bf16 v[32:35], v[200:203], v[180:183], v[16:19]
	v_mfma_f32_16x16x32_bf16 v[16:19], v[204:207], v[176:179], v[156:159]
	v_mfma_f32_16x16x32_bf16 v[36:39], v[208:211], v[180:183], v[16:19]
	v_mfma_f32_16x16x32_bf16 v[16:19], v[172:175], v[212:215], v[160:163]
	v_mfma_f32_16x16x32_bf16 v[20:23], v[204:207], v[212:215], v[164:167]
	v_mfma_f32_16x16x32_bf16 v[0:3], v[172:175], v[236:239], v[0:3]
	v_mfma_f32_16x16x32_bf16 v[4:7], v[204:207], v[236:239], v[4:7]
	v_mfma_f32_16x16x32_bf16 v[16:19], v[200:203], v[232:235], v[16:19]
	v_mfma_f32_16x16x32_bf16 v[20:23], v[208:211], v[232:235], v[20:23]
	v_mfma_f32_16x16x32_bf16 v[0:3], v[200:203], v[240:243], v[0:3]
	v_mfma_f32_16x16x32_bf16 v[4:7], v[208:211], v[240:243], v[4:7]
	s_setprio 0
	s_setprio 1
	v_mfma_f32_16x16x32_bf16 v[8:11], v[216:219], v[40:43], v[8:11]
	v_mfma_f32_16x16x32_bf16 v[72:75], v[220:223], v[44:47], v[8:11]
	v_mfma_f32_16x16x32_bf16 v[8:11], v[224:227], v[40:43], v[12:15]
	v_mfma_f32_16x16x32_bf16 v[76:79], v[228:231], v[44:47], v[8:11]
	v_mfma_f32_16x16x32_bf16 v[8:11], v[216:219], v[176:179], v[24:27]
	v_mfma_f32_16x16x32_bf16 v[40:43], v[220:223], v[180:183], v[8:11]
	v_mfma_f32_16x16x32_bf16 v[8:11], v[224:227], v[176:179], v[28:31]
	v_mfma_f32_16x16x32_bf16 v[44:47], v[228:231], v[180:183], v[8:11]
	v_mfma_f32_16x16x32_bf16 v[8:11], v[216:219], v[212:215], v[188:191]
	v_mfma_f32_16x16x32_bf16 v[24:27], v[220:223], v[232:235], v[8:11]
	v_mfma_f32_16x16x32_bf16 v[8:11], v[224:227], v[212:215], v[192:195]
	v_mfma_f32_16x16x32_bf16 v[28:31], v[228:231], v[232:235], v[8:11]
	v_mfma_f32_16x16x32_bf16 v[8:11], v[216:219], v[236:239], v[196:199]
	v_mfma_f32_16x16x32_bf16 v[12:15], v[224:227], v[236:239], v[168:171]
	v_mfma_f32_16x16x32_bf16 v[8:11], v[220:223], v[240:243], v[8:11]
	v_mfma_f32_16x16x32_bf16 v[12:15], v[228:231], v[240:243], v[12:15]
	s_setprio 0
	s_barrier
	s_and_b64 vcc, exec, s[2:3]
	s_cbranch_vccnz .LBB0_334
	s_barrier

; #define G_STAGE(bufoff, gbase, voff) do { _Pragma("unroll") for (int _i = 0; _i < 2; ++_i) \
;         __builtin_amdgcn_global_load_lds((const unsigned*)((const char*)(gbase) + voff[_i]), (LAS unsigned*)(lds + (bufoff) + ldsw + _i * 8192), 16, 0, 0); } while (0)
; #define G_LDA(dst, b, h) do { _Pragma("unroll") for (int m = 0; m < 4; ++m) _Pragma("unroll") for (int k = 0; k < 2; ++k) dst[m][k] = *(const LAS bf16x8*)(lds + G_SA(b, h) + aoff + m * 2048 + k * 1024); } while (0)
; #define G_MMA(ai, bj, At_, Bt_) do { __builtin_amdgcn_s_setprio(1); _Pragma("unroll") for (int m = 0; m < 4; ++m) _Pragma("unroll") for (int n = 0; n < 2; ++n) _Pragma("unroll") for (int k = 0; k < 2; ++k) \
;         acc[ai][bj][m][n] = __builtin_amdgcn_mfma_f32_16x16x32_bf16(Bt_[n][k], At_[m][k], acc[ai][bj][m][n], 0, 0, 0); __builtin_amdgcn_s_setprio(0); } while (0)
; #define WAIT_V(n) asm volatile("s_waitcnt vmcnt(" #n ")" ::: "memory")
; #define WAIT_L(n) asm volatile("s_waitcnt lgkmcnt(" #n ")" ::: "memory")
; #define BAR __builtin_amdgcn_s_barrier()
; #define SCHED __builtin_amdgcn_sched_barrier(0)
; template <class Get, class Epi>
; DI void gemm_loop(int ntiles, int ld, char* shm, const Get& get, const Epi& epi) {
;     ...
;             WAIT_V(8); WAIT_L(0); BAR; G_MMA(0, 0, At, B0); G_MMA(0, 1, At, B1); BAR; SCHED;
;             G_LDA(At, 0, 1); G_STAGE(G_SB(0, 0), b2, voffB); G_STAGE(G_SB(0, 1), b2 + hstep, voffB); G_STAGE(G_SA(0, 0), a2, voffA);
.Lrj_431_0:
	s_waitcnt lgkmcnt(0)
	s_barrier
	s_setprio 1
	v_mfma_f32_16x16x32_bf16 v[124:127], v[146:149], v[178:181], 0
	v_mfma_f32_16x16x32_bf16 v[120:123], v[154:157], v[178:181], 0
	v_mfma_f32_16x16x32_bf16 v[116:119], v[146:149], v[192:195], 0
	v_mfma_f32_16x16x32_bf16 v[112:115], v[154:157], v[192:195], 0
	v_mfma_f32_16x16x32_bf16 v[100:103], v[146:149], v[200:203], 0
	v_mfma_f32_16x16x32_bf16 v[96:99], v[154:157], v[200:203], 0
	v_mfma_f32_16x16x32_bf16 v[84:87], v[146:149], v[208:211], 0
	v_mfma_f32_16x16x32_bf16 v[80:83], v[154:157], v[208:211], 0
	v_mfma_f32_16x16x32_bf16 v[124:127], v[150:153], v[188:191], v[124:127]
	v_mfma_f32_16x16x32_bf16 v[120:123], v[158:161], v[188:191], v[120:123]
	v_mfma_f32_16x16x32_bf16 v[116:119], v[150:153], v[196:199], v[116:119]
	v_mfma_f32_16x16x32_bf16 v[112:115], v[158:161], v[196:199], v[112:115]
	v_mfma_f32_16x16x32_bf16 v[100:103], v[150:153], v[204:207], v[100:103]
	v_mfma_f32_16x16x32_bf16 v[96:99], v[158:161], v[204:207], v[96:99]
	v_mfma_f32_16x16x32_bf16 v[84:87], v[150:153], v[212:215], v[84:87]
	v_mfma_f32_16x16x32_bf16 v[80:83], v[158:161], v[212:215], v[80:83]
	s_setprio 0
	s_setprio 1
	v_mfma_f32_16x16x32_bf16 v[108:111], v[162:165], v[178:181], 0
	v_mfma_f32_16x16x32_bf16 v[104:107], v[170:173], v[178:181], 0
	v_mfma_f32_16x16x32_bf16 v[92:95], v[162:165], v[192:195], 0
	v_mfma_f32_16x16x32_bf16 v[88:91], v[170:173], v[192:195], 0
	v_mfma_f32_16x16x32_bf16 v[76:79], v[162:165], v[200:203], 0
	v_mfma_f32_16x16x32_bf16 v[72:75], v[170:173], v[200:203], 0
	v_mfma_f32_16x16x32_bf16 v[68:71], v[162:165], v[208:211], 0
	v_mfma_f32_16x16x32_bf16 v[64:67], v[170:173], v[208:211], 0
	v_mfma_f32_16x16x32_bf16 v[108:111], v[166:169], v[188:191], v[108:111]
	v_mfma_f32_16x16x32_bf16 v[104:107], v[174:177], v[188:191], v[104:107]
	v_mfma_f32_16x16x32_bf16 v[92:95], v[166:169], v[196:199], v[92:95]
	v_mfma_f32_16x16x32_bf16 v[88:91], v[174:177], v[196:199], v[88:91]
	v_mfma_f32_16x16x32_bf16 v[76:79], v[166:169], v[204:207], v[76:79]
	v_mfma_f32_16x16x32_bf16 v[72:75], v[174:177], v[204:207], v[72:75]
	v_mfma_f32_16x16x32_bf16 v[68:71], v[166:169], v[212:215], v[68:71]
	v_mfma_f32_16x16x32_bf16 v[64:67], v[174:177], v[212:215], v[64:67]
	s_setprio 0
	s_barrier
	s_add_i32 s82, s54, s38
	v_lshl_add_u64 v[182:183], s[14:15], 0, v[132:133]
	s_mov_b32 m0, s82
	ds_read_b128 v[178:181], v143 offset:16384
	ds_read_b128 v[188:191], v143 offset:17408
	ds_read_b128 v[192:195], v143 offset:18432
	ds_read_b128 v[196:199], v143 offset:19456
	ds_read_b128 v[200:203], v143 offset:20480
	ds_read_b128 v[204:207], v143 offset:21504
	ds_read_b128 v[208:211], v143 offset:22528
	ds_read_b128 v[212:215], v143 offset:23552
	global_load_lds_dwordx4 v[182:183], off
	s_add_i32 m0, s82, 0x2000
	s_add_u32 s82, s14, 0x100000
	v_lshl_add_u64 v[184:185], s[14:15], 0, v[128:129]
	s_addc_u32 s83, s15, 0
	s_add_i32 s84, s55, s38
	global_load_lds_dwordx4 v[184:185], off
	v_lshl_add_u64 v[186:187], s[82:83], 0, v[132:133]
	s_mov_b32 m0, s84
	v_lshl_add_u64 v[216:217], s[36:37], 0, v[130:131]
	global_load_lds_dwordx4 v[186:187], off
	v_lshl_add_u64 v[186:187], s[82:83], 0, v[128:129]
	s_add_i32 m0, s84, 0x2000
	s_nop 0
	global_load_lds_dwordx4 v[186:187], off
	v_lshl_add_u64 v[186:187], s[36:37], 0, v[134:135]
	s_mov_b32 m0, s43
	s_nop 0
	global_load_lds_dwordx4 v[186:187], off
	s_mov_b32 m0, s44
	s_nop 0
	global_load_lds_dwordx4 v[216:217], off
	s_cmp_lg_u32 s100, 0
	s_cbranch_scc0 .Lrf_431_1
	s_waitcnt vmcnt(16)
	s_branch .Lrj_431_1

; #define G_STAGE(bufoff, gbase, voff) do { _Pragma("unroll") for (int _i = 0; _i < 2; ++_i) \
;         __builtin_amdgcn_global_load_lds((const unsigned*)((const char*)(gbase) + voff[_i]), (LAS unsigned*)(lds + (bufoff) + ldsw + _i * 8192), 16, 0, 0); } while (0)
; #define G_LDA(dst, b, h) do { _Pragma("unroll") for (int m = 0; m < 4; ++m) _Pragma("unroll") for (int k = 0; k < 2; ++k) dst[m][k] = *(const LAS bf16x8*)(lds + G_SA(b, h) + aoff + m * 2048 + k * 1024); } while (0)
; #define G_LDB(dst, b, h) do { _Pragma("unroll") for (int n = 0; n < 2; ++n) _Pragma("unroll") for (int k = 0; k < 2; ++k) dst[n][k] = *(const LAS bf16x8*)(lds + G_SB(b, h) + boff + n * 2048 + k * 1024); } while (0)
; #define G_MMA(ai, bj, At_, Bt_) do { __builtin_amdgcn_s_setprio(1); _Pragma("unroll") for (int m = 0; m < 4; ++m) _Pragma("unroll") for (int n = 0; n < 2; ++n) _Pragma("unroll") for (int k = 0; k < 2; ++k) \
;         acc[ai][bj][m][n] = __builtin_amdgcn_mfma_f32_16x16x32_bf16(Bt_[n][k], At_[m][k], acc[ai][bj][m][n], 0, 0, 0); __builtin_amdgcn_s_setprio(0); } while (0)
; #define WAIT_V(n) asm volatile("s_waitcnt vmcnt(" #n ")" ::: "memory")
; #define WAIT_L(n) asm volatile("s_waitcnt lgkmcnt(" #n ")" ::: "memory")
; #define BAR __builtin_amdgcn_s_barrier()
; #define SCHED __builtin_amdgcn_sched_barrier(0)
; template <class Get, class Epi>
; DI void gemm_loop(int ntiles, int ld, char* shm, const Get& get, const Epi& epi) {
;     ...
;             WAIT_V(8); WAIT_L(0); BAR; G_MMA(1, 0, At, B0); G_MMA(1, 1, At, B1); BAR; SCHED;
;             G_LDB(B0, 1, 0); G_LDB(B1, 1, 1); SCHED; G_LDA(At, 1, 0); G_STAGE(G_SA(0, 1), a2 + hstep, voffA);
;             WAIT_V(8); WAIT_L(0); BAR; G_MMA(0, 0, At, B0); G_MMA(0, 1, At, B1); BAR; SCHED;
.Lrj_431_1:
	s_waitcnt lgkmcnt(0)
	s_barrier
	s_setprio 1
	v_mfma_f32_16x16x32_bf16 v[60:63], v[146:149], v[178:181], 0
	v_mfma_f32_16x16x32_bf16 v[56:59], v[154:157], v[178:181], 0
	v_mfma_f32_16x16x32_bf16 v[52:55], v[146:149], v[192:195], 0
	v_mfma_f32_16x16x32_bf16 v[48:51], v[154:157], v[192:195], 0
	v_mfma_f32_16x16x32_bf16 v[36:39], v[146:149], v[200:203], 0
	v_mfma_f32_16x16x32_bf16 v[32:35], v[154:157], v[200:203], 0
	v_mfma_f32_16x16x32_bf16 v[20:23], v[146:149], v[208:211], 0
	v_mfma_f32_16x16x32_bf16 v[16:19], v[154:157], v[208:211], 0
	v_mfma_f32_16x16x32_bf16 v[60:63], v[150:153], v[188:191], v[60:63]
	v_mfma_f32_16x16x32_bf16 v[56:59], v[158:161], v[188:191], v[56:59]
	v_mfma_f32_16x16x32_bf16 v[52:55], v[150:153], v[196:199], v[52:55]
	v_mfma_f32_16x16x32_bf16 v[48:51], v[158:161], v[196:199], v[48:51]
	v_mfma_f32_16x16x32_bf16 v[36:39], v[150:153], v[204:207], v[36:39]
	v_mfma_f32_16x16x32_bf16 v[32:35], v[158:161], v[204:207], v[32:35]
	v_mfma_f32_16x16x32_bf16 v[20:23], v[150:153], v[212:215], v[20:23]
	v_mfma_f32_16x16x32_bf16 v[16:19], v[158:161], v[212:215], v[16:19]
	s_setprio 0
	s_setprio 1
	v_mfma_f32_16x16x32_bf16 v[44:47], v[162:165], v[178:181], 0
	v_mfma_f32_16x16x32_bf16 v[40:43], v[170:173], v[178:181], 0
	v_mfma_f32_16x16x32_bf16 v[28:31], v[162:165], v[192:195], 0
	v_mfma_f32_16x16x32_bf16 v[24:27], v[170:173], v[192:195], 0
	v_mfma_f32_16x16x32_bf16 v[12:15], v[162:165], v[200:203], 0
	v_mfma_f32_16x16x32_bf16 v[8:11], v[170:173], v[200:203], 0
	v_mfma_f32_16x16x32_bf16 v[4:7], v[162:165], v[208:211], 0
	v_mfma_f32_16x16x32_bf16 v[0:3], v[170:173], v[208:211], 0
	v_mfma_f32_16x16x32_bf16 v[44:47], v[166:169], v[188:191], v[44:47]
	v_mfma_f32_16x16x32_bf16 v[40:43], v[174:177], v[188:191], v[40:43]
	v_mfma_f32_16x16x32_bf16 v[28:31], v[166:169], v[196:199], v[28:31]
	v_mfma_f32_16x16x32_bf16 v[24:27], v[174:177], v[196:199], v[24:27]
	v_mfma_f32_16x16x32_bf16 v[12:15], v[166:169], v[204:207], v[12:15]
	v_mfma_f32_16x16x32_bf16 v[8:11], v[174:177], v[204:207], v[8:11]
	v_mfma_f32_16x16x32_bf16 v[4:7], v[166:169], v[212:215], v[4:7]
	v_mfma_f32_16x16x32_bf16 v[0:3], v[174:177], v[212:215], v[0:3]
	s_setprio 0
	s_barrier
	s_add_i32 s82, 0, 0x18000
	v_add_u32_e32 v145, s82, v140
	s_add_i32 s83, 0, 0x1c000
	ds_read_b128 v[146:149], v145
	ds_read_b128 v[150:153], v145 offset:1024
	ds_read_b128 v[154:157], v145 offset:2048
	ds_read_b128 v[158:161], v145 offset:3072
	v_add_u32_e32 v145, s83, v140
	ds_read_b128 v[162:165], v145
	ds_read_b128 v[166:169], v145 offset:1024
	ds_read_b128 v[170:173], v145 offset:2048
	ds_read_b128 v[174:177], v145 offset:3072
	s_add_u32 s36, s36, 0x100000
	s_addc_u32 s37, s37, 0
	s_mov_b32 m0, s45
	v_lshl_add_u64 v[218:219], s[36:37], 0, v[134:135]
	ds_read_b128 v[178:181], v143 offset:32768
	ds_read_b128 v[188:191], v143 offset:33792
	ds_read_b128 v[192:195], v143 offset:34816
	ds_read_b128 v[196:199], v143 offset:35840
	ds_read_b128 v[200:203], v143 offset:36864
	ds_read_b128 v[204:207], v143 offset:37888
	ds_read_b128 v[208:211], v143 offset:38912
	ds_read_b128 v[212:215], v143 offset:39936
	global_load_lds_dwordx4 v[218:219], off
	v_lshl_add_u64 v[218:219], s[36:37], 0, v[130:131]
	s_mov_b32 m0, s46
	s_nop 0
	global_load_lds_dwordx4 v[218:219], off
	s_waitcnt vmcnt(8)
	s_waitcnt lgkmcnt(0)
	s_barrier
	s_setprio 1
	v_mfma_f32_16x16x32_bf16 v[124:127], v[146:149], v[178:181], v[124:127]
	v_mfma_f32_16x16x32_bf16 v[120:123], v[154:157], v[178:181], v[120:123]
	v_mfma_f32_16x16x32_bf16 v[116:119], v[146:149], v[192:195], v[116:119]
	v_mfma_f32_16x16x32_bf16 v[112:115], v[154:157], v[192:195], v[112:115]
	v_mfma_f32_16x16x32_bf16 v[100:103], v[146:149], v[200:203], v[100:103]
	v_mfma_f32_16x16x32_bf16 v[96:99], v[154:157], v[200:203], v[96:99]
	v_mfma_f32_16x16x32_bf16 v[84:87], v[146:149], v[208:211], v[84:87]
	v_mfma_f32_16x16x32_bf16 v[80:83], v[154:157], v[208:211], v[80:83]
	v_mfma_f32_16x16x32_bf16 v[124:127], v[150:153], v[188:191], v[124:127]
	v_mfma_f32_16x16x32_bf16 v[120:123], v[158:161], v[188:191], v[120:123]
	v_mfma_f32_16x16x32_bf16 v[116:119], v[150:153], v[196:199], v[116:119]
	v_mfma_f32_16x16x32_bf16 v[112:115], v[158:161], v[196:199], v[112:115]
	v_mfma_f32_16x16x32_bf16 v[100:103], v[150:153], v[204:207], v[100:103]
	v_mfma_f32_16x16x32_bf16 v[96:99], v[158:161], v[204:207], v[96:99]
	v_mfma_f32_16x16x32_bf16 v[84:87], v[150:153], v[212:215], v[84:87]
	v_mfma_f32_16x16x32_bf16 v[80:83], v[158:161], v[212:215], v[80:83]
	s_setprio 0
	s_setprio 1
	v_mfma_f32_16x16x32_bf16 v[108:111], v[162:165], v[178:181], v[108:111]
	v_mfma_f32_16x16x32_bf16 v[104:107], v[170:173], v[178:181], v[104:107]
	v_mfma_f32_16x16x32_bf16 v[92:95], v[162:165], v[192:195], v[92:95]
	v_mfma_f32_16x16x32_bf16 v[88:91], v[170:173], v[192:195], v[88:91]
	v_mfma_f32_16x16x32_bf16 v[76:79], v[162:165], v[200:203], v[76:79]
	v_mfma_f32_16x16x32_bf16 v[72:75], v[170:173], v[200:203], v[72:75]
	v_mfma_f32_16x16x32_bf16 v[68:71], v[162:165], v[208:211], v[68:71]
	v_mfma_f32_16x16x32_bf16 v[64:67], v[170:173], v[208:211], v[64:67]
	v_mfma_f32_16x16x32_bf16 v[108:111], v[166:169], v[188:191], v[108:111]
	v_mfma_f32_16x16x32_bf16 v[104:107], v[174:177], v[188:191], v[104:107]
	v_mfma_f32_16x16x32_bf16 v[92:95], v[166:169], v[196:199], v[92:95]
	v_mfma_f32_16x16x32_bf16 v[88:91], v[174:177], v[196:199], v[88:91]
	v_mfma_f32_16x16x32_bf16 v[76:79], v[166:169], v[204:207], v[76:79]
	v_mfma_f32_16x16x32_bf16 v[72:75], v[174:177], v[204:207], v[72:75]
	v_mfma_f32_16x16x32_bf16 v[68:71], v[166:169], v[212:215], v[68:71]
	v_mfma_f32_16x16x32_bf16 v[64:67], v[174:177], v[212:215], v[64:67]
	s_setprio 0
	s_barrier
; #define G_STAGE(bufoff, gbase, voff) do { _Pragma("unroll") for (int _i = 0; _i < 2; ++_i) \
;         __builtin_amdgcn_global_load_lds((const unsigned*)((const char*)(gbase) + voff[_i]), (LAS unsigned*)(lds + (bufoff) + ldsw + _i * 8192), 16, 0, 0); } while (0)
; #define G_LDA(dst, b, h) do { _Pragma("unroll") for (int m = 0; m < 4; ++m) _Pragma("unroll") for (int k = 0; k < 2; ++k) dst[m][k] = *(const LAS bf16x8*)(lds + G_SA(b, h) + aoff + m * 2048 + k * 1024); } while (0)
; #define G_LDB(dst, b, h) do { _Pragma("unroll") for (int n = 0; n < 2; ++n) _Pragma("unroll") for (int k = 0; k < 2; ++k) dst[n][k] = *(const LAS bf16x8*)(lds + G_SB(b, h) + boff + n * 2048 + k * 1024); } while (0)
; #define G_MMA(ai, bj, At_, Bt_) do { __builtin_amdgcn_s_setprio(1); _Pragma("unroll") for (int m = 0; m < 4; ++m) _Pragma("unroll") for (int n = 0; n < 2; ++n) _Pragma("unroll") for (int k = 0; k < 2; ++k) \
;         acc[ai][bj][m][n] = __builtin_amdgcn_mfma_f32_16x16x32_bf16(Bt_[n][k], At_[m][k], acc[ai][bj][m][n], 0, 0, 0); __builtin_amdgcn_s_setprio(0); } while (0)
; #define WAIT_V(n) asm volatile("s_waitcnt vmcnt(" #n ")" ::: "memory")
; #define WAIT_L(n) asm volatile("s_waitcnt lgkmcnt(" #n ")" ::: "memory")
; #define BAR __builtin_amdgcn_s_barrier()
; #define SCHED __builtin_amdgcn_sched_barrier(0)
; template <class Get, class Epi>
; DI void gemm_loop(int ntiles, int ld, char* shm, const Get& get, const Epi& epi) {
;     ...
;         for (int t = 0; t < nt; t += 2) {
;             const bool last = (t == nt - 2);
;             const char* a1 = cA + (size_t)(t + 1) * kstep;
;             const char* a2 = last ? nA : cA + (size_t)(t + 2) * kstep; const char* b2 = last ? nB : cB + (size_t)(t + 2) * kstep;
;             const char* a3 = a2 + kstep; const char* b3 = b2 + kstep;
;             G_LDB(B0, 0, 0); G_LDB(B1, 0, 1); SCHED; G_LDA(At, 0, 0); G_STAGE(G_SA(1, 1), a1 + hstep, voffA);
;     ...
;             G_LDA(At, 1, 1); G_STAGE(G_SB(1, 0), b3, voffB); G_STAGE(G_SB(1, 1), b3 + hstep, voffB); G_STAGE(G_SA(1, 0), a3, voffA);
;             WAIT_V(8); WAIT_L(0); BAR; G_MMA(1, 0, At, B0); G_MMA(1, 1, At, B1); BAR; SCHED;
	s_add_i32 s36, s82, s38
	v_lshl_add_u64 v[182:183], v[182:183], 0, s[8:9]
	s_mov_b32 m0, s36
	ds_read_b128 v[178:181], v143 offset:49152
	ds_read_b128 v[188:191], v143 offset:50176
	ds_read_b128 v[192:195], v143 offset:51200
	ds_read_b128 v[196:199], v143 offset:52224
	ds_read_b128 v[200:203], v143 offset:53248
	ds_read_b128 v[204:207], v143 offset:54272
	ds_read_b128 v[208:211], v143 offset:55296
	ds_read_b128 v[212:215], v143 offset:56320
	global_load_lds_dwordx4 v[182:183], off
	s_add_i32 m0, s36, 0x2000
	s_add_u32 s14, s14, 0x100080
	v_lshl_add_u64 v[182:183], v[184:185], 0, s[8:9]
	s_addc_u32 s15, s15, 0
	s_add_i32 s36, s83, s38
	global_load_lds_dwordx4 v[182:183], off
	v_lshl_add_u64 v[182:183], s[14:15], 0, v[132:133]
	s_mov_b32 m0, s36
	s_nop 0
	global_load_lds_dwordx4 v[182:183], off
	v_lshl_add_u64 v[182:183], s[14:15], 0, v[128:129]
	s_add_i32 m0, s36, 0x2000
	s_nop 0
	global_load_lds_dwordx4 v[182:183], off
	v_lshl_add_u64 v[182:183], v[186:187], 0, s[8:9]
	s_mov_b32 m0, s47
	s_nop 0
	global_load_lds_dwordx4 v[182:183], off
	v_lshl_add_u64 v[182:183], v[216:217], 0, s[8:9]
	s_mov_b32 m0, s50
	s_nop 0
	global_load_lds_dwordx4 v[182:183], off
	s_waitcnt vmcnt(8)
	s_waitcnt lgkmcnt(0)
	s_barrier
	s_setprio 1
	v_mfma_f32_16x16x32_bf16 v[60:63], v[146:149], v[178:181], v[60:63]
	v_mfma_f32_16x16x32_bf16 v[56:59], v[154:157], v[178:181], v[56:59]
	v_mfma_f32_16x16x32_bf16 v[52:55], v[146:149], v[192:195], v[52:55]
	v_mfma_f32_16x16x32_bf16 v[48:51], v[154:157], v[192:195], v[48:51]
	v_mfma_f32_16x16x32_bf16 v[36:39], v[146:149], v[200:203], v[36:39]
	v_mfma_f32_16x16x32_bf16 v[32:35], v[154:157], v[200:203], v[32:35]
	v_mfma_f32_16x16x32_bf16 v[20:23], v[146:149], v[208:211], v[20:23]
	v_mfma_f32_16x16x32_bf16 v[16:19], v[154:157], v[208:211], v[16:19]
	v_mfma_f32_16x16x32_bf16 v[60:63], v[150:153], v[188:191], v[60:63]
	v_mfma_f32_16x16x32_bf16 v[56:59], v[158:161], v[188:191], v[56:59]
	v_mfma_f32_16x16x32_bf16 v[52:55], v[150:153], v[196:199], v[52:55]
	v_mfma_f32_16x16x32_bf16 v[48:51], v[158:161], v[196:199], v[48:51]
	v_mfma_f32_16x16x32_bf16 v[36:39], v[150:153], v[204:207], v[36:39]
	v_mfma_f32_16x16x32_bf16 v[32:35], v[158:161], v[204:207], v[32:35]
	v_mfma_f32_16x16x32_bf16 v[20:23], v[150:153], v[212:215], v[20:23]
	v_mfma_f32_16x16x32_bf16 v[16:19], v[158:161], v[212:215], v[16:19]
	s_setprio 0
	s_setprio 1
	v_mfma_f32_16x16x32_bf16 v[44:47], v[162:165], v[178:181], v[44:47]
	v_mfma_f32_16x16x32_bf16 v[40:43], v[170:173], v[178:181], v[40:43]
	v_mfma_f32_16x16x32_bf16 v[28:31], v[162:165], v[192:195], v[28:31]
	v_mfma_f32_16x16x32_bf16 v[24:27], v[170:173], v[192:195], v[24:27]
	v_mfma_f32_16x16x32_bf16 v[12:15], v[162:165], v[200:203], v[12:15]
	v_mfma_f32_16x16x32_bf16 v[8:11], v[170:173], v[200:203], v[8:11]
	v_mfma_f32_16x16x32_bf16 v[4:7], v[162:165], v[208:211], v[4:7]
	v_mfma_f32_16x16x32_bf16 v[0:3], v[170:173], v[208:211], v[0:3]
	v_mfma_f32_16x16x32_bf16 v[44:47], v[166:169], v[188:191], v[44:47]
	v_mfma_f32_16x16x32_bf16 v[40:43], v[174:177], v[188:191], v[40:43]
	v_mfma_f32_16x16x32_bf16 v[28:31], v[166:169], v[196:199], v[28:31]
	v_mfma_f32_16x16x32_bf16 v[24:27], v[174:177], v[196:199], v[24:27]
	v_mfma_f32_16x16x32_bf16 v[12:15], v[166:169], v[204:207], v[12:15]
	v_mfma_f32_16x16x32_bf16 v[8:11], v[174:177], v[204:207], v[8:11]
	v_mfma_f32_16x16x32_bf16 v[4:7], v[166:169], v[212:215], v[4:7]
	v_mfma_f32_16x16x32_bf16 v[0:3], v[174:177], v[212:215], v[0:3]
	s_setprio 0
	s_barrier
	s_add_i32 s81, s81, 2
	s_add_u32 s34, s34, 0x100
	s_addc_u32 s35, s35, 0
	s_add_u32 s79, s79, 0x100
	s_addc_u32 s80, s80, 0
	s_cmp_gt_u32 s81, 61
	s_cbranch_scc0 .LBB0_431
	s_branch .Lpost_431
.LBB0_431:
	ds_read_b128 v[146:149], v141
	ds_read_b128 v[150:153], v141 offset:1024
	ds_read_b128 v[154:157], v141 offset:2048
	ds_read_b128 v[158:161], v141 offset:3072
	ds_read_b128 v[162:165], v142
	ds_read_b128 v[166:169], v142 offset:1024
	ds_read_b128 v[170:173], v142 offset:2048
	ds_read_b128 v[174:177], v142 offset:3072
	s_add_u32 s14, s34, 0xfff00080
	s_addc_u32 s15, s35, -1
	s_cmp_eq_u32 s81, 60
	s_cselect_b32 s37, s74, s15
	s_cselect_b32 s36, s75, s14
	s_cselect_b32 s15, s76, s80
	s_cselect_b32 s14, s78, s79
	s_mov_b32 m0, s56
	v_lshl_add_u64 v[182:183], s[34:35], 0, v[136:137]
	ds_read_b128 v[178:181], v143
	ds_read_b128 v[188:191], v143 offset:1024
	ds_read_b128 v[192:195], v143 offset:2048
	ds_read_b128 v[196:199], v143 offset:3072
	ds_read_b128 v[200:203], v143 offset:4096
	ds_read_b128 v[204:207], v143 offset:5120
	ds_read_b128 v[208:211], v143 offset:6144
	ds_read_b128 v[212:215], v143 offset:7168
	global_load_lds_dwordx4 v[182:183], off
	v_lshl_add_u64 v[182:183], s[34:35], 0, v[138:139]
	s_add_i32 m0, s43, 0xe000
	s_nop 0
	global_load_lds_dwordx4 v[182:183], off
	s_waitcnt vmcnt(8)
	s_waitcnt lgkmcnt(0)
	s_barrier
; #define G_STAGE(bufoff, gbase, voff) do { _Pragma("unroll") for (int _i = 0; _i < 2; ++_i) \
;         __builtin_amdgcn_global_load_lds((const unsigned*)((const char*)(gbase) + voff[_i]), (LAS unsigned*)(lds + (bufoff) + ldsw + _i * 8192), 16, 0, 0); } while (0)
; #define G_LDA(dst, b, h) do { _Pragma("unroll") for (int m = 0; m < 4; ++m) _Pragma("unroll") for (int k = 0; k < 2; ++k) dst[m][k] = *(const LAS bf16x8*)(lds + G_SA(b, h) + aoff + m * 2048 + k * 1024); } while (0)
; #define G_MMA(ai, bj, At_, Bt_) do { __builtin_amdgcn_s_setprio(1); _Pragma("unroll") for (int m = 0; m < 4; ++m) _Pragma("unroll") for (int n = 0; n < 2; ++n) _Pragma("unroll") for (int k = 0; k < 2; ++k) \
;         acc[ai][bj][m][n] = __builtin_amdgcn_mfma_f32_16x16x32_bf16(Bt_[n][k], At_[m][k], acc[ai][bj][m][n], 0, 0, 0); __builtin_amdgcn_s_setprio(0); } while (0)
; #define WAIT_V(n) asm volatile("s_waitcnt vmcnt(" #n ")" ::: "memory")
; #define WAIT_L(n) asm volatile("s_waitcnt lgkmcnt(" #n ")" ::: "memory")
; #define BAR __builtin_amdgcn_s_barrier()
; #define SCHED __builtin_amdgcn_sched_barrier(0)
; template <class Get, class Epi>
; DI void gemm_loop(int ntiles, int ld, char* shm, const Get& get, const Epi& epi) {
;     ...
;             WAIT_V(8); WAIT_L(0); BAR; G_MMA(0, 0, At, B0); G_MMA(0, 1, At, B1); BAR; SCHED;
;             G_LDA(At, 0, 1); G_STAGE(G_SB(0, 0), b2, voffB); G_STAGE(G_SB(0, 1), b2 + hstep, voffB); G_STAGE(G_SA(0, 0), a2, voffA);
;             WAIT_V(8); WAIT_L(0); BAR; G_MMA(1, 0, At, B0); G_MMA(1, 1, At, B1); BAR; SCHED;
	s_setprio 1
	v_mfma_f32_16x16x32_bf16 v[124:127], v[146:149], v[178:181], v[124:127]
	v_mfma_f32_16x16x32_bf16 v[120:123], v[154:157], v[178:181], v[120:123]
	v_mfma_f32_16x16x32_bf16 v[116:119], v[146:149], v[192:195], v[116:119]
	v_mfma_f32_16x16x32_bf16 v[112:115], v[154:157], v[192:195], v[112:115]
	v_mfma_f32_16x16x32_bf16 v[100:103], v[146:149], v[200:203], v[100:103]
	v_mfma_f32_16x16x32_bf16 v[96:99], v[154:157], v[200:203], v[96:99]
	v_mfma_f32_16x16x32_bf16 v[84:87], v[146:149], v[208:211], v[84:87]
	v_mfma_f32_16x16x32_bf16 v[80:83], v[154:157], v[208:211], v[80:83]
	v_mfma_f32_16x16x32_bf16 v[124:127], v[150:153], v[188:191], v[124:127]
	v_mfma_f32_16x16x32_bf16 v[120:123], v[158:161], v[188:191], v[120:123]
	v_mfma_f32_16x16x32_bf16 v[116:119], v[150:153], v[196:199], v[116:119]
	v_mfma_f32_16x16x32_bf16 v[112:115], v[158:161], v[196:199], v[112:115]
	v_mfma_f32_16x16x32_bf16 v[100:103], v[150:153], v[204:207], v[100:103]
	v_mfma_f32_16x16x32_bf16 v[96:99], v[158:161], v[204:207], v[96:99]
	v_mfma_f32_16x16x32_bf16 v[84:87], v[150:153], v[212:215], v[84:87]
	v_mfma_f32_16x16x32_bf16 v[80:83], v[158:161], v[212:215], v[80:83]
	s_setprio 0
	s_setprio 1
	v_mfma_f32_16x16x32_bf16 v[108:111], v[162:165], v[178:181], v[108:111]
	v_mfma_f32_16x16x32_bf16 v[104:107], v[170:173], v[178:181], v[104:107]
	v_mfma_f32_16x16x32_bf16 v[92:95], v[162:165], v[192:195], v[92:95]
	v_mfma_f32_16x16x32_bf16 v[88:91], v[170:173], v[192:195], v[88:91]
	v_mfma_f32_16x16x32_bf16 v[76:79], v[162:165], v[200:203], v[76:79]
	v_mfma_f32_16x16x32_bf16 v[72:75], v[170:173], v[200:203], v[72:75]
	v_mfma_f32_16x16x32_bf16 v[68:71], v[162:165], v[208:211], v[68:71]
	v_mfma_f32_16x16x32_bf16 v[64:67], v[170:173], v[208:211], v[64:67]
	v_mfma_f32_16x16x32_bf16 v[108:111], v[166:169], v[188:191], v[108:111]
	v_mfma_f32_16x16x32_bf16 v[104:107], v[174:177], v[188:191], v[104:107]
	v_mfma_f32_16x16x32_bf16 v[92:95], v[166:169], v[196:199], v[92:95]
	v_mfma_f32_16x16x32_bf16 v[88:91], v[174:177], v[196:199], v[88:91]
	v_mfma_f32_16x16x32_bf16 v[76:79], v[166:169], v[204:207], v[76:79]
	v_mfma_f32_16x16x32_bf16 v[72:75], v[174:177], v[204:207], v[72:75]
	v_mfma_f32_16x16x32_bf16 v[68:71], v[166:169], v[212:215], v[68:71]
	v_mfma_f32_16x16x32_bf16 v[64:67], v[174:177], v[212:215], v[64:67]
	s_setprio 0
	s_barrier
	s_add_i32 s82, s54, s38
	v_lshl_add_u64 v[182:183], s[14:15], 0, v[132:133]
	s_mov_b32 m0, s82
	ds_read_b128 v[178:181], v143 offset:16384
	ds_read_b128 v[188:191], v143 offset:17408
	ds_read_b128 v[192:195], v143 offset:18432
	ds_read_b128 v[196:199], v143 offset:19456
	ds_read_b128 v[200:203], v143 offset:20480
	ds_read_b128 v[204:207], v143 offset:21504
	ds_read_b128 v[208:211], v143 offset:22528
	ds_read_b128 v[212:215], v143 offset:23552
	global_load_lds_dwordx4 v[182:183], off
	s_add_i32 m0, s82, 0x2000
	s_add_u32 s82, s14, 0x100000
	v_lshl_add_u64 v[184:185], s[14:15], 0, v[128:129]
	s_addc_u32 s83, s15, 0
	s_add_i32 s84, s55, s38
	global_load_lds_dwordx4 v[184:185], off
	v_lshl_add_u64 v[186:187], s[82:83], 0, v[132:133]
	s_mov_b32 m0, s84
	v_lshl_add_u64 v[216:217], s[36:37], 0, v[130:131]
	global_load_lds_dwordx4 v[186:187], off
	v_lshl_add_u64 v[186:187], s[82:83], 0, v[128:129]
	s_add_i32 m0, s84, 0x2000
	s_nop 0
	global_load_lds_dwordx4 v[186:187], off
	v_lshl_add_u64 v[186:187], s[36:37], 0, v[134:135]
	s_mov_b32 m0, s43
	s_nop 0
	global_load_lds_dwordx4 v[186:187], off
	s_mov_b32 m0, s44
	s_nop 0
	global_load_lds_dwordx4 v[216:217], off
	s_waitcnt vmcnt(8)
	s_waitcnt lgkmcnt(0)
	s_barrier
	s_setprio 1
	v_mfma_f32_16x16x32_bf16 v[60:63], v[146:149], v[178:181], v[60:63]
	v_mfma_f32_16x16x32_bf16 v[56:59], v[154:157], v[178:181], v[56:59]
	v_mfma_f32_16x16x32_bf16 v[52:55], v[146:149], v[192:195], v[52:55]
	v_mfma_f32_16x16x32_bf16 v[48:51], v[154:157], v[192:195], v[48:51]
	v_mfma_f32_16x16x32_bf16 v[36:39], v[146:149], v[200:203], v[36:39]
	v_mfma_f32_16x16x32_bf16 v[32:35], v[154:157], v[200:203], v[32:35]
	v_mfma_f32_16x16x32_bf16 v[20:23], v[146:149], v[208:211], v[20:23]
	v_mfma_f32_16x16x32_bf16 v[16:19], v[154:157], v[208:211], v[16:19]
	v_mfma_f32_16x16x32_bf16 v[60:63], v[150:153], v[188:191], v[60:63]
	v_mfma_f32_16x16x32_bf16 v[56:59], v[158:161], v[188:191], v[56:59]
	v_mfma_f32_16x16x32_bf16 v[52:55], v[150:153], v[196:199], v[52:55]
	v_mfma_f32_16x16x32_bf16 v[48:51], v[158:161], v[196:199], v[48:51]
	v_mfma_f32_16x16x32_bf16 v[36:39], v[150:153], v[204:207], v[36:39]
	v_mfma_f32_16x16x32_bf16 v[32:35], v[158:161], v[204:207], v[32:35]
	v_mfma_f32_16x16x32_bf16 v[20:23], v[150:153], v[212:215], v[20:23]
	v_mfma_f32_16x16x32_bf16 v[16:19], v[158:161], v[212:215], v[16:19]
	s_setprio 0
	s_setprio 1
	v_mfma_f32_16x16x32_bf16 v[44:47], v[162:165], v[178:181], v[44:47]
	v_mfma_f32_16x16x32_bf16 v[40:43], v[170:173], v[178:181], v[40:43]
	v_mfma_f32_16x16x32_bf16 v[28:31], v[162:165], v[192:195], v[28:31]
	v_mfma_f32_16x16x32_bf16 v[24:27], v[170:173], v[192:195], v[24:27]
	v_mfma_f32_16x16x32_bf16 v[12:15], v[162:165], v[200:203], v[12:15]
	v_mfma_f32_16x16x32_bf16 v[8:11], v[170:173], v[200:203], v[8:11]
	v_mfma_f32_16x16x32_bf16 v[4:7], v[162:165], v[208:211], v[4:7]
	v_mfma_f32_16x16x32_bf16 v[0:3], v[170:173], v[208:211], v[0:3]
	v_mfma_f32_16x16x32_bf16 v[44:47], v[166:169], v[188:191], v[44:47]
	v_mfma_f32_16x16x32_bf16 v[40:43], v[174:177], v[188:191], v[40:43]
	v_mfma_f32_16x16x32_bf16 v[28:31], v[166:169], v[196:199], v[28:31]
	v_mfma_f32_16x16x32_bf16 v[24:27], v[174:177], v[196:199], v[24:27]
	v_mfma_f32_16x16x32_bf16 v[12:15], v[166:169], v[204:207], v[12:15]
	v_mfma_f32_16x16x32_bf16 v[8:11], v[174:177], v[204:207], v[8:11]
	v_mfma_f32_16x16x32_bf16 v[4:7], v[166:169], v[212:215], v[4:7]
	v_mfma_f32_16x16x32_bf16 v[0:3], v[174:177], v[212:215], v[0:3]
	s_setprio 0
	s_barrier
; #define G_STAGE(bufoff, gbase, voff) do { _Pragma("unroll") for (int _i = 0; _i < 2; ++_i) \
;         __builtin_amdgcn_global_load_lds((const unsigned*)((const char*)(gbase) + voff[_i]), (LAS unsigned*)(lds + (bufoff) + ldsw + _i * 8192), 16, 0, 0); } while (0)
; #define G_LDA(dst, b, h) do { _Pragma("unroll") for (int m = 0; m < 4; ++m) _Pragma("unroll") for (int k = 0; k < 2; ++k) dst[m][k] = *(const LAS bf16x8*)(lds + G_SA(b, h) + aoff + m * 2048 + k * 1024); } while (0)
; #define G_LDB(dst, b, h) do { _Pragma("unroll") for (int n = 0; n < 2; ++n) _Pragma("unroll") for (int k = 0; k < 2; ++k) dst[n][k] = *(const LAS bf16x8*)(lds + G_SB(b, h) + boff + n * 2048 + k * 1024); } while (0)
; #define G_MMA(ai, bj, At_, Bt_) do { __builtin_amdgcn_s_setprio(1); _Pragma("unroll") for (int m = 0; m < 4; ++m) _Pragma("unroll") for (int n = 0; n < 2; ++n) _Pragma("unroll") for (int k = 0; k < 2; ++k) \
;         acc[ai][bj][m][n] = __builtin_amdgcn_mfma_f32_16x16x32_bf16(Bt_[n][k], At_[m][k], acc[ai][bj][m][n], 0, 0, 0); __builtin_amdgcn_s_setprio(0); } while (0)
; #define WAIT_V(n) asm volatile("s_waitcnt vmcnt(" #n ")" ::: "memory")
; #define WAIT_L(n) asm volatile("s_waitcnt lgkmcnt(" #n ")" ::: "memory")
; #define BAR __builtin_amdgcn_s_barrier()
; #define SCHED __builtin_amdgcn_sched_barrier(0)
; template <class Get, class Epi>
; DI void gemm_loop(int ntiles, int ld, char* shm, const Get& get, const Epi& epi) {
;     ...
;             G_LDB(B0, 1, 0); G_LDB(B1, 1, 1); SCHED; G_LDA(At, 1, 0); G_STAGE(G_SA(0, 1), a2 + hstep, voffA);
;             WAIT_V(8); WAIT_L(0); BAR; G_MMA(0, 0, At, B0); G_MMA(0, 1, At, B1); BAR; SCHED;
	s_add_i32 s82, 0, 0x18000
	v_add_u32_e32 v145, s82, v140
	s_add_i32 s83, 0, 0x1c000
	ds_read_b128 v[146:149], v145
	ds_read_b128 v[150:153], v145 offset:1024
	ds_read_b128 v[154:157], v145 offset:2048
	ds_read_b128 v[158:161], v145 offset:3072
	v_add_u32_e32 v145, s83, v140
	ds_read_b128 v[162:165], v145
	ds_read_b128 v[166:169], v145 offset:1024
	ds_read_b128 v[170:173], v145 offset:2048
	ds_read_b128 v[174:177], v145 offset:3072
	s_add_u32 s36, s36, 0x100000
	s_addc_u32 s37, s37, 0
	s_mov_b32 m0, s45
	v_lshl_add_u64 v[218:219], s[36:37], 0, v[134:135]
	ds_read_b128 v[178:181], v143 offset:32768
	ds_read_b128 v[188:191], v143 offset:33792
	ds_read_b128 v[192:195], v143 offset:34816
	ds_read_b128 v[196:199], v143 offset:35840
	ds_read_b128 v[200:203], v143 offset:36864
	ds_read_b128 v[204:207], v143 offset:37888
	ds_read_b128 v[208:211], v143 offset:38912
	ds_read_b128 v[212:215], v143 offset:39936
	global_load_lds_dwordx4 v[218:219], off
	v_lshl_add_u64 v[218:219], s[36:37], 0, v[130:131]
	s_mov_b32 m0, s46
	s_nop 0
	global_load_lds_dwordx4 v[218:219], off
	s_waitcnt vmcnt(8)
	s_waitcnt lgkmcnt(0)
	s_barrier
	s_setprio 1
	v_mfma_f32_16x16x32_bf16 v[124:127], v[146:149], v[178:181], v[124:127]
	v_mfma_f32_16x16x32_bf16 v[120:123], v[154:157], v[178:181], v[120:123]
	v_mfma_f32_16x16x32_bf16 v[116:119], v[146:149], v[192:195], v[116:119]
	v_mfma_f32_16x16x32_bf16 v[112:115], v[154:157], v[192:195], v[112:115]
	v_mfma_f32_16x16x32_bf16 v[100:103], v[146:149], v[200:203], v[100:103]
	v_mfma_f32_16x16x32_bf16 v[96:99], v[154:157], v[200:203], v[96:99]
	v_mfma_f32_16x16x32_bf16 v[84:87], v[146:149], v[208:211], v[84:87]
	v_mfma_f32_16x16x32_bf16 v[80:83], v[154:157], v[208:211], v[80:83]
	v_mfma_f32_16x16x32_bf16 v[124:127], v[150:153], v[188:191], v[124:127]
	v_mfma_f32_16x16x32_bf16 v[120:123], v[158:161], v[188:191], v[120:123]
	v_mfma_f32_16x16x32_bf16 v[116:119], v[150:153], v[196:199], v[116:119]
	v_mfma_f32_16x16x32_bf16 v[112:115], v[158:161], v[196:199], v[112:115]
	v_mfma_f32_16x16x32_bf16 v[100:103], v[150:153], v[204:207], v[100:103]
	v_mfma_f32_16x16x32_bf16 v[96:99], v[158:161], v[204:207], v[96:99]
	v_mfma_f32_16x16x32_bf16 v[84:87], v[150:153], v[212:215], v[84:87]
	v_mfma_f32_16x16x32_bf16 v[80:83], v[158:161], v[212:215], v[80:83]
	s_setprio 0
	s_setprio 1
	v_mfma_f32_16x16x32_bf16 v[108:111], v[162:165], v[178:181], v[108:111]
	v_mfma_f32_16x16x32_bf16 v[104:107], v[170:173], v[178:181], v[104:107]
	v_mfma_f32_16x16x32_bf16 v[92:95], v[162:165], v[192:195], v[92:95]
	v_mfma_f32_16x16x32_bf16 v[88:91], v[170:173], v[192:195], v[88:91]
	v_mfma_f32_16x16x32_bf16 v[76:79], v[162:165], v[200:203], v[76:79]
	v_mfma_f32_16x16x32_bf16 v[72:75], v[170:173], v[200:203], v[72:75]
	v_mfma_f32_16x16x32_bf16 v[68:71], v[162:165], v[208:211], v[68:71]
	v_mfma_f32_16x16x32_bf16 v[64:67], v[170:173], v[208:211], v[64:67]
	v_mfma_f32_16x16x32_bf16 v[108:111], v[166:169], v[188:191], v[108:111]
	v_mfma_f32_16x16x32_bf16 v[104:107], v[174:177], v[188:191], v[104:107]
	v_mfma_f32_16x16x32_bf16 v[92:95], v[166:169], v[196:199], v[92:95]
	v_mfma_f32_16x16x32_bf16 v[88:91], v[174:177], v[196:199], v[88:91]
	v_mfma_f32_16x16x32_bf16 v[76:79], v[166:169], v[204:207], v[76:79]
	v_mfma_f32_16x16x32_bf16 v[72:75], v[174:177], v[204:207], v[72:75]
	v_mfma_f32_16x16x32_bf16 v[68:71], v[166:169], v[212:215], v[68:71]
	v_mfma_f32_16x16x32_bf16 v[64:67], v[174:177], v[212:215], v[64:67]
	s_setprio 0
	s_barrier
; #define G_STAGE(bufoff, gbase, voff) do { _Pragma("unroll") for (int _i = 0; _i < 2; ++_i) \
;         __builtin_amdgcn_global_load_lds((const unsigned*)((const char*)(gbase) + voff[_i]), (LAS unsigned*)(lds + (bufoff) + ldsw + _i * 8192), 16, 0, 0); } while (0)
; #define G_LDA(dst, b, h) do { _Pragma("unroll") for (int m = 0; m < 4; ++m) _Pragma("unroll") for (int k = 0; k < 2; ++k) dst[m][k] = *(const LAS bf16x8*)(lds + G_SA(b, h) + aoff + m * 2048 + k * 1024); } while (0)
; #define G_MMA(ai, bj, At_, Bt_) do { __builtin_amdgcn_s_setprio(1); _Pragma("unroll") for (int m = 0; m < 4; ++m) _Pragma("unroll") for (int n = 0; n < 2; ++n) _Pragma("unroll") for (int k = 0; k < 2; ++k) \
;         acc[ai][bj][m][n] = __builtin_amdgcn_mfma_f32_16x16x32_bf16(Bt_[n][k], At_[m][k], acc[ai][bj][m][n], 0, 0, 0); __builtin_amdgcn_s_setprio(0); } while (0)
; #define WAIT_V(n) asm volatile("s_waitcnt vmcnt(" #n ")" ::: "memory")
; #define WAIT_L(n) asm volatile("s_waitcnt lgkmcnt(" #n ")" ::: "memory")
; #define BAR __builtin_amdgcn_s_barrier()
; #define SCHED __builtin_amdgcn_sched_barrier(0)
; template <class Get, class Epi>
; DI void gemm_loop(int ntiles, int ld, char* shm, const Get& get, const Epi& epi) {
;     ...
;         for (int t = 0; t < nt; t += 2) {
;             const bool last = (t == nt - 2);
;     ...
;             G_LDA(At, 1, 1); G_STAGE(G_SB(1, 0), b3, voffB); G_STAGE(G_SB(1, 1), b3 + hstep, voffB); G_STAGE(G_SA(1, 0), a3, voffA);
;             WAIT_V(8); WAIT_L(0); BAR; G_MMA(1, 0, At, B0); G_MMA(1, 1, At, B1); BAR; SCHED;
	s_add_i32 s36, s82, s38
	v_lshl_add_u64 v[182:183], v[182:183], 0, s[8:9]
	s_mov_b32 m0, s36
	ds_read_b128 v[178:181], v143 offset:49152
	ds_read_b128 v[188:191], v143 offset:50176
	ds_read_b128 v[192:195], v143 offset:51200
	ds_read_b128 v[196:199], v143 offset:52224
	ds_read_b128 v[200:203], v143 offset:53248
	ds_read_b128 v[204:207], v143 offset:54272
	ds_read_b128 v[208:211], v143 offset:55296
	ds_read_b128 v[212:215], v143 offset:56320
	global_load_lds_dwordx4 v[182:183], off
	s_add_i32 m0, s36, 0x2000
	s_add_u32 s14, s14, 0x100080
	v_lshl_add_u64 v[182:183], v[184:185], 0, s[8:9]
	s_addc_u32 s15, s15, 0
	s_add_i32 s36, s83, s38
	global_load_lds_dwordx4 v[182:183], off
	v_lshl_add_u64 v[182:183], s[14:15], 0, v[132:133]
	s_mov_b32 m0, s36
	s_nop 0
	global_load_lds_dwordx4 v[182:183], off
	v_lshl_add_u64 v[182:183], s[14:15], 0, v[128:129]
	s_add_i32 m0, s36, 0x2000
	s_nop 0
	global_load_lds_dwordx4 v[182:183], off
	v_lshl_add_u64 v[182:183], v[186:187], 0, s[8:9]
	s_mov_b32 m0, s47
	s_nop 0
	global_load_lds_dwordx4 v[182:183], off
	v_lshl_add_u64 v[182:183], v[216:217], 0, s[8:9]
	s_mov_b32 m0, s50
	s_nop 0
	global_load_lds_dwordx4 v[182:183], off
	s_waitcnt vmcnt(8)
	s_waitcnt lgkmcnt(0)
	s_barrier
	s_setprio 1
	v_mfma_f32_16x16x32_bf16 v[60:63], v[146:149], v[178:181], v[60:63]
	v_mfma_f32_16x16x32_bf16 v[56:59], v[154:157], v[178:181], v[56:59]
	v_mfma_f32_16x16x32_bf16 v[52:55], v[146:149], v[192:195], v[52:55]
	v_mfma_f32_16x16x32_bf16 v[48:51], v[154:157], v[192:195], v[48:51]
	v_mfma_f32_16x16x32_bf16 v[36:39], v[146:149], v[200:203], v[36:39]
	v_mfma_f32_16x16x32_bf16 v[32:35], v[154:157], v[200:203], v[32:35]
	v_mfma_f32_16x16x32_bf16 v[20:23], v[146:149], v[208:211], v[20:23]
	v_mfma_f32_16x16x32_bf16 v[16:19], v[154:157], v[208:211], v[16:19]
	v_mfma_f32_16x16x32_bf16 v[60:63], v[150:153], v[188:191], v[60:63]
	v_mfma_f32_16x16x32_bf16 v[56:59], v[158:161], v[188:191], v[56:59]
	v_mfma_f32_16x16x32_bf16 v[52:55], v[150:153], v[196:199], v[52:55]
	v_mfma_f32_16x16x32_bf16 v[48:51], v[158:161], v[196:199], v[48:51]
	v_mfma_f32_16x16x32_bf16 v[36:39], v[150:153], v[204:207], v[36:39]
	v_mfma_f32_16x16x32_bf16 v[32:35], v[158:161], v[204:207], v[32:35]
	v_mfma_f32_16x16x32_bf16 v[20:23], v[150:153], v[212:215], v[20:23]
	v_mfma_f32_16x16x32_bf16 v[16:19], v[158:161], v[212:215], v[16:19]
	s_setprio 0
	s_setprio 1
	v_mfma_f32_16x16x32_bf16 v[44:47], v[162:165], v[178:181], v[44:47]
	v_mfma_f32_16x16x32_bf16 v[40:43], v[170:173], v[178:181], v[40:43]
	v_mfma_f32_16x16x32_bf16 v[28:31], v[162:165], v[192:195], v[28:31]
	v_mfma_f32_16x16x32_bf16 v[24:27], v[170:173], v[192:195], v[24:27]
	v_mfma_f32_16x16x32_bf16 v[12:15], v[162:165], v[200:203], v[12:15]
	v_mfma_f32_16x16x32_bf16 v[8:11], v[170:173], v[200:203], v[8:11]
	v_mfma_f32_16x16x32_bf16 v[4:7], v[162:165], v[208:211], v[4:7]
	v_mfma_f32_16x16x32_bf16 v[0:3], v[170:173], v[208:211], v[0:3]
	v_mfma_f32_16x16x32_bf16 v[44:47], v[166:169], v[188:191], v[44:47]
	v_mfma_f32_16x16x32_bf16 v[40:43], v[174:177], v[188:191], v[40:43]
	v_mfma_f32_16x16x32_bf16 v[28:31], v[166:169], v[196:199], v[28:31]
	v_mfma_f32_16x16x32_bf16 v[24:27], v[174:177], v[196:199], v[24:27]
	v_mfma_f32_16x16x32_bf16 v[12:15], v[166:169], v[204:207], v[12:15]
	v_mfma_f32_16x16x32_bf16 v[8:11], v[174:177], v[204:207], v[8:11]
	v_mfma_f32_16x16x32_bf16 v[4:7], v[166:169], v[212:215], v[4:7]
	v_mfma_f32_16x16x32_bf16 v[0:3], v[174:177], v[212:215], v[0:3]
	s_setprio 0
	s_barrier
	s_add_i32 s81, s81, 2
	s_add_u32 s34, s34, 0x100
	s_addc_u32 s35, s35, 0
	s_add_u32 s79, s79, 0x100
	s_addc_u32 s80, s80, 0
	s_cmp_gt_u32 s81, 61
	s_cbranch_scc0 .LBB0_431

; #define G_STAGE(bufoff, gbase, voff) do { _Pragma("unroll") for (int _i = 0; _i < 2; ++_i) \
;         __builtin_amdgcn_global_load_lds((const unsigned*)((const char*)(gbase) + voff[_i]), (LAS unsigned*)(lds + (bufoff) + ldsw + _i * 8192), 16, 0, 0); } while (0)
; #define G_LDA(dst, b, h) do { _Pragma("unroll") for (int m = 0; m < 4; ++m) _Pragma("unroll") for (int k = 0; k < 2; ++k) dst[m][k] = *(const LAS bf16x8*)(lds + G_SA(b, h) + aoff + m * 2048 + k * 1024); } while (0)
; #define G_MMA(ai, bj, At_, Bt_) do { __builtin_amdgcn_s_setprio(1); _Pragma("unroll") for (int m = 0; m < 4; ++m) _Pragma("unroll") for (int n = 0; n < 2; ++n) _Pragma("unroll") for (int k = 0; k < 2; ++k) \
;         acc[ai][bj][m][n] = __builtin_amdgcn_mfma_f32_16x16x32_bf16(Bt_[n][k], At_[m][k], acc[ai][bj][m][n], 0, 0, 0); __builtin_amdgcn_s_setprio(0); } while (0)
; #define WAIT_V(n) asm volatile("s_waitcnt vmcnt(" #n ")" ::: "memory")
; #define WAIT_L(n) asm volatile("s_waitcnt lgkmcnt(" #n ")" ::: "memory")
; #define BAR __builtin_amdgcn_s_barrier()
; #define SCHED __builtin_amdgcn_sched_barrier(0)
; template <class Get, class Epi>
; DI void gemm_loop(int ntiles, int ld, char* shm, const Get& get, const Epi& epi) {
;     ...
;             WAIT_V(8); WAIT_L(0); BAR; G_MMA(0, 0, At, B0); G_MMA(0, 1, At, B1); BAR; SCHED;
;             G_LDA(At, 0, 1); G_STAGE(G_SB(0, 0), b2, voffB); G_STAGE(G_SB(0, 1), b2 + hstep, voffB); G_STAGE(G_SA(0, 0), a2, voffA);
.Lrj_445_0:
	s_waitcnt lgkmcnt(0)
	s_barrier
	s_setprio 1
	v_mfma_f32_16x16x32_bf16 v[124:127], v[146:149], v[178:181], 0
	v_mfma_f32_16x16x32_bf16 v[120:123], v[154:157], v[178:181], 0
	v_mfma_f32_16x16x32_bf16 v[116:119], v[146:149], v[192:195], 0
	v_mfma_f32_16x16x32_bf16 v[112:115], v[154:157], v[192:195], 0
	v_mfma_f32_16x16x32_bf16 v[100:103], v[146:149], v[200:203], 0
	v_mfma_f32_16x16x32_bf16 v[96:99], v[154:157], v[200:203], 0
	v_mfma_f32_16x16x32_bf16 v[84:87], v[146:149], v[208:211], 0
	v_mfma_f32_16x16x32_bf16 v[80:83], v[154:157], v[208:211], 0
	v_mfma_f32_16x16x32_bf16 v[124:127], v[150:153], v[188:191], v[124:127]
	v_mfma_f32_16x16x32_bf16 v[120:123], v[158:161], v[188:191], v[120:123]
	v_mfma_f32_16x16x32_bf16 v[116:119], v[150:153], v[196:199], v[116:119]
	v_mfma_f32_16x16x32_bf16 v[112:115], v[158:161], v[196:199], v[112:115]
	v_mfma_f32_16x16x32_bf16 v[100:103], v[150:153], v[204:207], v[100:103]
	v_mfma_f32_16x16x32_bf16 v[96:99], v[158:161], v[204:207], v[96:99]
	v_mfma_f32_16x16x32_bf16 v[84:87], v[150:153], v[212:215], v[84:87]
	v_mfma_f32_16x16x32_bf16 v[80:83], v[158:161], v[212:215], v[80:83]
	s_setprio 0
	s_setprio 1
	v_mfma_f32_16x16x32_bf16 v[108:111], v[162:165], v[178:181], 0
	v_mfma_f32_16x16x32_bf16 v[104:107], v[170:173], v[178:181], 0
	v_mfma_f32_16x16x32_bf16 v[92:95], v[162:165], v[192:195], 0
	v_mfma_f32_16x16x32_bf16 v[88:91], v[170:173], v[192:195], 0
	v_mfma_f32_16x16x32_bf16 v[76:79], v[162:165], v[200:203], 0
	v_mfma_f32_16x16x32_bf16 v[72:75], v[170:173], v[200:203], 0
	v_mfma_f32_16x16x32_bf16 v[68:71], v[162:165], v[208:211], 0
	v_mfma_f32_16x16x32_bf16 v[64:67], v[170:173], v[208:211], 0
	v_mfma_f32_16x16x32_bf16 v[108:111], v[166:169], v[188:191], v[108:111]
	v_mfma_f32_16x16x32_bf16 v[104:107], v[174:177], v[188:191], v[104:107]
	v_mfma_f32_16x16x32_bf16 v[92:95], v[166:169], v[196:199], v[92:95]
	v_mfma_f32_16x16x32_bf16 v[88:91], v[174:177], v[196:199], v[88:91]
	v_mfma_f32_16x16x32_bf16 v[76:79], v[166:169], v[204:207], v[76:79]
	v_mfma_f32_16x16x32_bf16 v[72:75], v[174:177], v[204:207], v[72:75]
	v_mfma_f32_16x16x32_bf16 v[68:71], v[166:169], v[212:215], v[68:71]
	v_mfma_f32_16x16x32_bf16 v[64:67], v[174:177], v[212:215], v[64:67]
	s_setprio 0
	s_barrier
	s_mov_b32 m0, s54
	v_lshl_add_u64 v[182:183], s[14:15], 0, v[132:133]
	s_add_u32 s82, s14, 0x20000
	ds_read_b128 v[178:181], v142 offset:16384
	ds_read_b128 v[188:191], v142 offset:17408
	ds_read_b128 v[192:195], v142 offset:18432
	ds_read_b128 v[196:199], v142 offset:19456
	ds_read_b128 v[200:203], v142 offset:20480
	ds_read_b128 v[204:207], v142 offset:21504
	ds_read_b128 v[208:211], v142 offset:22528
	ds_read_b128 v[212:215], v142 offset:23552
	global_load_lds_dwordx4 v[182:183], off
	v_lshl_add_u64 v[184:185], s[14:15], 0, v[128:129]
	s_mov_b32 m0, s55
	s_addc_u32 s83, s15, 0
	global_load_lds_dwordx4 v[184:185], off
	v_lshl_add_u64 v[186:187], s[82:83], 0, v[132:133]
	s_mov_b32 m0, s56
	v_lshl_add_u64 v[216:217], s[38:39], 0, v[130:131]
	global_load_lds_dwordx4 v[186:187], off
	v_lshl_add_u64 v[186:187], s[82:83], 0, v[128:129]
	s_mov_b32 m0, s57
	s_nop 0
	global_load_lds_dwordx4 v[186:187], off
	v_lshl_add_u64 v[186:187], s[38:39], 0, v[134:135]
	s_mov_b32 m0, s41
	s_nop 0
	global_load_lds_dwordx4 v[186:187], off
	s_mov_b32 m0, s43
	s_nop 0
	global_load_lds_dwordx4 v[216:217], off
	s_cmp_lg_u32 s100, 0
	s_cbranch_scc0 .Lrf_445_1
	s_waitcnt vmcnt(16)
	s_branch .Lrj_445_1

; #define G_STAGE(bufoff, gbase, voff) do { _Pragma("unroll") for (int _i = 0; _i < 2; ++_i) \
;         __builtin_amdgcn_global_load_lds((const unsigned*)((const char*)(gbase) + voff[_i]), (LAS unsigned*)(lds + (bufoff) + ldsw + _i * 8192), 16, 0, 0); } while (0)
; #define G_LDA(dst, b, h) do { _Pragma("unroll") for (int m = 0; m < 4; ++m) _Pragma("unroll") for (int k = 0; k < 2; ++k) dst[m][k] = *(const LAS bf16x8*)(lds + G_SA(b, h) + aoff + m * 2048 + k * 1024); } while (0)
; #define G_LDB(dst, b, h) do { _Pragma("unroll") for (int n = 0; n < 2; ++n) _Pragma("unroll") for (int k = 0; k < 2; ++k) dst[n][k] = *(const LAS bf16x8*)(lds + G_SB(b, h) + boff + n * 2048 + k * 1024); } while (0)
; #define G_MMA(ai, bj, At_, Bt_) do { __builtin_amdgcn_s_setprio(1); _Pragma("unroll") for (int m = 0; m < 4; ++m) _Pragma("unroll") for (int n = 0; n < 2; ++n) _Pragma("unroll") for (int k = 0; k < 2; ++k) \
;         acc[ai][bj][m][n] = __builtin_amdgcn_mfma_f32_16x16x32_bf16(Bt_[n][k], At_[m][k], acc[ai][bj][m][n], 0, 0, 0); __builtin_amdgcn_s_setprio(0); } while (0)
; #define WAIT_V(n) asm volatile("s_waitcnt vmcnt(" #n ")" ::: "memory")
; #define WAIT_L(n) asm volatile("s_waitcnt lgkmcnt(" #n ")" ::: "memory")
; #define BAR __builtin_amdgcn_s_barrier()
; #define SCHED __builtin_amdgcn_sched_barrier(0)
; template <class Get, class Epi>
; DI void gemm_loop(int ntiles, int ld, char* shm, const Get& get, const Epi& epi) {
;     ...
;             WAIT_V(8); WAIT_L(0); BAR; G_MMA(1, 0, At, B0); G_MMA(1, 1, At, B1); BAR; SCHED;
;             G_LDB(B0, 1, 0); G_LDB(B1, 1, 1); SCHED; G_LDA(At, 1, 0); G_STAGE(G_SA(0, 1), a2 + hstep, voffA);
;             WAIT_V(8); WAIT_L(0); BAR; G_MMA(0, 0, At, B0); G_MMA(0, 1, At, B1); BAR; SCHED;
.Lrj_445_1:
	s_waitcnt lgkmcnt(0)
	s_barrier
	s_setprio 1
	v_mfma_f32_16x16x32_bf16 v[60:63], v[146:149], v[178:181], 0
	v_mfma_f32_16x16x32_bf16 v[56:59], v[154:157], v[178:181], 0
	v_mfma_f32_16x16x32_bf16 v[52:55], v[146:149], v[192:195], 0
	v_mfma_f32_16x16x32_bf16 v[48:51], v[154:157], v[192:195], 0
	v_mfma_f32_16x16x32_bf16 v[36:39], v[146:149], v[200:203], 0
	v_mfma_f32_16x16x32_bf16 v[32:35], v[154:157], v[200:203], 0
	v_mfma_f32_16x16x32_bf16 v[20:23], v[146:149], v[208:211], 0
	v_mfma_f32_16x16x32_bf16 v[16:19], v[154:157], v[208:211], 0
	v_mfma_f32_16x16x32_bf16 v[60:63], v[150:153], v[188:191], v[60:63]
	v_mfma_f32_16x16x32_bf16 v[56:59], v[158:161], v[188:191], v[56:59]
	v_mfma_f32_16x16x32_bf16 v[52:55], v[150:153], v[196:199], v[52:55]
	v_mfma_f32_16x16x32_bf16 v[48:51], v[158:161], v[196:199], v[48:51]
	v_mfma_f32_16x16x32_bf16 v[36:39], v[150:153], v[204:207], v[36:39]
	v_mfma_f32_16x16x32_bf16 v[32:35], v[158:161], v[204:207], v[32:35]
	v_mfma_f32_16x16x32_bf16 v[20:23], v[150:153], v[212:215], v[20:23]
	v_mfma_f32_16x16x32_bf16 v[16:19], v[158:161], v[212:215], v[16:19]
	s_setprio 0
	s_setprio 1
	v_mfma_f32_16x16x32_bf16 v[44:47], v[162:165], v[178:181], 0
	v_mfma_f32_16x16x32_bf16 v[40:43], v[170:173], v[178:181], 0
	v_mfma_f32_16x16x32_bf16 v[28:31], v[162:165], v[192:195], 0
	v_mfma_f32_16x16x32_bf16 v[24:27], v[170:173], v[192:195], 0
	v_mfma_f32_16x16x32_bf16 v[12:15], v[162:165], v[200:203], 0
	v_mfma_f32_16x16x32_bf16 v[8:11], v[170:173], v[200:203], 0
	v_mfma_f32_16x16x32_bf16 v[4:7], v[162:165], v[208:211], 0
	v_mfma_f32_16x16x32_bf16 v[0:3], v[170:173], v[208:211], 0
	v_mfma_f32_16x16x32_bf16 v[44:47], v[166:169], v[188:191], v[44:47]
	v_mfma_f32_16x16x32_bf16 v[40:43], v[174:177], v[188:191], v[40:43]
	v_mfma_f32_16x16x32_bf16 v[28:31], v[166:169], v[196:199], v[28:31]
	v_mfma_f32_16x16x32_bf16 v[24:27], v[174:177], v[196:199], v[24:27]
	v_mfma_f32_16x16x32_bf16 v[12:15], v[166:169], v[204:207], v[12:15]
	v_mfma_f32_16x16x32_bf16 v[8:11], v[174:177], v[204:207], v[8:11]
	v_mfma_f32_16x16x32_bf16 v[4:7], v[166:169], v[212:215], v[4:7]
	v_mfma_f32_16x16x32_bf16 v[0:3], v[174:177], v[212:215], v[0:3]
	s_setprio 0
	s_barrier
	ds_read_b128 v[146:149], v143
	ds_read_b128 v[150:153], v143 offset:1024
	ds_read_b128 v[154:157], v143 offset:2048
	ds_read_b128 v[158:161], v143 offset:3072
	ds_read_b128 v[162:165], v144
	ds_read_b128 v[166:169], v144 offset:1024
	ds_read_b128 v[170:173], v144 offset:2048
	ds_read_b128 v[174:177], v144 offset:3072
	s_add_u32 s38, s38, 0x20000
	s_addc_u32 s39, s39, 0
	s_mov_b32 m0, s44
	v_lshl_add_u64 v[218:219], s[38:39], 0, v[134:135]
	ds_read_b128 v[178:181], v142 offset:32768
	ds_read_b128 v[188:191], v142 offset:33792
	ds_read_b128 v[192:195], v142 offset:34816
	ds_read_b128 v[196:199], v142 offset:35840
	ds_read_b128 v[200:203], v142 offset:36864
	ds_read_b128 v[204:207], v142 offset:37888
	ds_read_b128 v[208:211], v142 offset:38912
	ds_read_b128 v[212:215], v142 offset:39936
	global_load_lds_dwordx4 v[218:219], off
	v_lshl_add_u64 v[218:219], s[38:39], 0, v[130:131]
	s_mov_b32 m0, s45
	s_nop 0
	global_load_lds_dwordx4 v[218:219], off
	s_waitcnt vmcnt(8)
	s_waitcnt lgkmcnt(0)
	s_barrier
	s_setprio 1
	v_mfma_f32_16x16x32_bf16 v[124:127], v[146:149], v[178:181], v[124:127]
	v_mfma_f32_16x16x32_bf16 v[120:123], v[154:157], v[178:181], v[120:123]
	v_mfma_f32_16x16x32_bf16 v[116:119], v[146:149], v[192:195], v[116:119]
	v_mfma_f32_16x16x32_bf16 v[112:115], v[154:157], v[192:195], v[112:115]
	v_mfma_f32_16x16x32_bf16 v[100:103], v[146:149], v[200:203], v[100:103]
	v_mfma_f32_16x16x32_bf16 v[96:99], v[154:157], v[200:203], v[96:99]
	v_mfma_f32_16x16x32_bf16 v[84:87], v[146:149], v[208:211], v[84:87]
	v_mfma_f32_16x16x32_bf16 v[80:83], v[154:157], v[208:211], v[80:83]
	v_mfma_f32_16x16x32_bf16 v[124:127], v[150:153], v[188:191], v[124:127]
	v_mfma_f32_16x16x32_bf16 v[120:123], v[158:161], v[188:191], v[120:123]
	v_mfma_f32_16x16x32_bf16 v[116:119], v[150:153], v[196:199], v[116:119]
	v_mfma_f32_16x16x32_bf16 v[112:115], v[158:161], v[196:199], v[112:115]
	v_mfma_f32_16x16x32_bf16 v[100:103], v[150:153], v[204:207], v[100:103]
	v_mfma_f32_16x16x32_bf16 v[96:99], v[158:161], v[204:207], v[96:99]
	v_mfma_f32_16x16x32_bf16 v[84:87], v[150:153], v[212:215], v[84:87]
	v_mfma_f32_16x16x32_bf16 v[80:83], v[158:161], v[212:215], v[80:83]
	s_setprio 0
	s_setprio 1
	v_mfma_f32_16x16x32_bf16 v[108:111], v[162:165], v[178:181], v[108:111]
	v_mfma_f32_16x16x32_bf16 v[104:107], v[170:173], v[178:181], v[104:107]
	v_mfma_f32_16x16x32_bf16 v[92:95], v[162:165], v[192:195], v[92:95]
	v_mfma_f32_16x16x32_bf16 v[88:91], v[170:173], v[192:195], v[88:91]
	v_mfma_f32_16x16x32_bf16 v[76:79], v[162:165], v[200:203], v[76:79]
	v_mfma_f32_16x16x32_bf16 v[72:75], v[170:173], v[200:203], v[72:75]
	v_mfma_f32_16x16x32_bf16 v[68:71], v[162:165], v[208:211], v[68:71]
	v_mfma_f32_16x16x32_bf16 v[64:67], v[170:173], v[208:211], v[64:67]
	v_mfma_f32_16x16x32_bf16 v[108:111], v[166:169], v[188:191], v[108:111]
	v_mfma_f32_16x16x32_bf16 v[104:107], v[174:177], v[188:191], v[104:107]
	v_mfma_f32_16x16x32_bf16 v[92:95], v[166:169], v[196:199], v[92:95]
	v_mfma_f32_16x16x32_bf16 v[88:91], v[174:177], v[196:199], v[88:91]
	v_mfma_f32_16x16x32_bf16 v[76:79], v[166:169], v[204:207], v[76:79]
	v_mfma_f32_16x16x32_bf16 v[72:75], v[174:177], v[204:207], v[72:75]
	v_mfma_f32_16x16x32_bf16 v[68:71], v[166:169], v[212:215], v[68:71]
	v_mfma_f32_16x16x32_bf16 v[64:67], v[174:177], v[212:215], v[64:67]
	s_setprio 0
	s_barrier
; #define G_STAGE(bufoff, gbase, voff) do { _Pragma("unroll") for (int _i = 0; _i < 2; ++_i) \
;         __builtin_amdgcn_global_load_lds((const unsigned*)((const char*)(gbase) + voff[_i]), (LAS unsigned*)(lds + (bufoff) + ldsw + _i * 8192), 16, 0, 0); } while (0)
; #define G_LDA(dst, b, h) do { _Pragma("unroll") for (int m = 0; m < 4; ++m) _Pragma("unroll") for (int k = 0; k < 2; ++k) dst[m][k] = *(const LAS bf16x8*)(lds + G_SA(b, h) + aoff + m * 2048 + k * 1024); } while (0)
; #define G_LDB(dst, b, h) do { _Pragma("unroll") for (int n = 0; n < 2; ++n) _Pragma("unroll") for (int k = 0; k < 2; ++k) dst[n][k] = *(const LAS bf16x8*)(lds + G_SB(b, h) + boff + n * 2048 + k * 1024); } while (0)
; #define G_MMA(ai, bj, At_, Bt_) do { __builtin_amdgcn_s_setprio(1); _Pragma("unroll") for (int m = 0; m < 4; ++m) _Pragma("unroll") for (int n = 0; n < 2; ++n) _Pragma("unroll") for (int k = 0; k < 2; ++k) \
;         acc[ai][bj][m][n] = __builtin_amdgcn_mfma_f32_16x16x32_bf16(Bt_[n][k], At_[m][k], acc[ai][bj][m][n], 0, 0, 0); __builtin_amdgcn_s_setprio(0); } while (0)
; #define WAIT_V(n) asm volatile("s_waitcnt vmcnt(" #n ")" ::: "memory")
; #define WAIT_L(n) asm volatile("s_waitcnt lgkmcnt(" #n ")" ::: "memory")
; #define BAR __builtin_amdgcn_s_barrier()
; #define SCHED __builtin_amdgcn_sched_barrier(0)
; template <class Get, class Epi>
; DI void gemm_loop(int ntiles, int ld, char* shm, const Get& get, const Epi& epi) {
;     ...
;         for (int t = 0; t < nt; t += 2) {
;             const bool last = (t == nt - 2);
;             const char* a1 = cA + (size_t)(t + 1) * kstep;
;             const char* a2 = last ? nA : cA + (size_t)(t + 2) * kstep; const char* b2 = last ? nB : cB + (size_t)(t + 2) * kstep;
;             const char* a3 = a2 + kstep; const char* b3 = b2 + kstep;
;             G_LDB(B0, 0, 0); G_LDB(B1, 0, 1); SCHED; G_LDA(At, 0, 0); G_STAGE(G_SA(1, 1), a1 + hstep, voffA);
;     ...
;             G_LDA(At, 1, 1); G_STAGE(G_SB(1, 0), b3, voffB); G_STAGE(G_SB(1, 1), b3 + hstep, voffB); G_STAGE(G_SA(1, 0), a3, voffA);
;             WAIT_V(8); WAIT_L(0); BAR; G_MMA(1, 0, At, B0); G_MMA(1, 1, At, B1); BAR; SCHED;
	s_mov_b32 m0, s58
	v_lshl_add_u64 v[182:183], v[182:183], 0, s[12:13]
	s_add_u32 s14, s14, 0x20080
	ds_read_b128 v[178:181], v142 offset:49152
	ds_read_b128 v[188:191], v142 offset:50176
	ds_read_b128 v[192:195], v142 offset:51200
	ds_read_b128 v[196:199], v142 offset:52224
	ds_read_b128 v[200:203], v142 offset:53248
	ds_read_b128 v[204:207], v142 offset:54272
	ds_read_b128 v[208:211], v142 offset:55296
	ds_read_b128 v[212:215], v142 offset:56320
	global_load_lds_dwordx4 v[182:183], off
	v_lshl_add_u64 v[182:183], v[184:185], 0, s[12:13]
	s_mov_b32 m0, s59
	s_addc_u32 s15, s15, 0
	global_load_lds_dwordx4 v[182:183], off
	v_lshl_add_u64 v[182:183], s[14:15], 0, v[132:133]
	s_mov_b32 m0, s72
	s_nop 0
	global_load_lds_dwordx4 v[182:183], off
	v_lshl_add_u64 v[182:183], s[14:15], 0, v[128:129]
	s_mov_b32 m0, s73
	s_nop 0
	global_load_lds_dwordx4 v[182:183], off
	v_lshl_add_u64 v[182:183], v[186:187], 0, s[12:13]
	s_mov_b32 m0, s46
	s_nop 0
	global_load_lds_dwordx4 v[182:183], off
	v_lshl_add_u64 v[182:183], v[216:217], 0, s[12:13]
	s_mov_b32 m0, s47
	s_nop 0
	global_load_lds_dwordx4 v[182:183], off
	s_waitcnt vmcnt(8)
	s_waitcnt lgkmcnt(0)
	s_barrier
	s_setprio 1
	v_mfma_f32_16x16x32_bf16 v[60:63], v[146:149], v[178:181], v[60:63]
	v_mfma_f32_16x16x32_bf16 v[56:59], v[154:157], v[178:181], v[56:59]
	v_mfma_f32_16x16x32_bf16 v[52:55], v[146:149], v[192:195], v[52:55]
	v_mfma_f32_16x16x32_bf16 v[48:51], v[154:157], v[192:195], v[48:51]
	v_mfma_f32_16x16x32_bf16 v[36:39], v[146:149], v[200:203], v[36:39]
	v_mfma_f32_16x16x32_bf16 v[32:35], v[154:157], v[200:203], v[32:35]
	v_mfma_f32_16x16x32_bf16 v[20:23], v[146:149], v[208:211], v[20:23]
	v_mfma_f32_16x16x32_bf16 v[16:19], v[154:157], v[208:211], v[16:19]
	v_mfma_f32_16x16x32_bf16 v[60:63], v[150:153], v[188:191], v[60:63]
	v_mfma_f32_16x16x32_bf16 v[56:59], v[158:161], v[188:191], v[56:59]
	v_mfma_f32_16x16x32_bf16 v[52:55], v[150:153], v[196:199], v[52:55]
	v_mfma_f32_16x16x32_bf16 v[48:51], v[158:161], v[196:199], v[48:51]
	v_mfma_f32_16x16x32_bf16 v[36:39], v[150:153], v[204:207], v[36:39]
	v_mfma_f32_16x16x32_bf16 v[32:35], v[158:161], v[204:207], v[32:35]
	v_mfma_f32_16x16x32_bf16 v[20:23], v[150:153], v[212:215], v[20:23]
	v_mfma_f32_16x16x32_bf16 v[16:19], v[158:161], v[212:215], v[16:19]
	s_setprio 0
	s_setprio 1
	v_mfma_f32_16x16x32_bf16 v[44:47], v[162:165], v[178:181], v[44:47]
	v_mfma_f32_16x16x32_bf16 v[40:43], v[170:173], v[178:181], v[40:43]
	v_mfma_f32_16x16x32_bf16 v[28:31], v[162:165], v[192:195], v[28:31]
	v_mfma_f32_16x16x32_bf16 v[24:27], v[170:173], v[192:195], v[24:27]
	v_mfma_f32_16x16x32_bf16 v[12:15], v[162:165], v[200:203], v[12:15]
	v_mfma_f32_16x16x32_bf16 v[8:11], v[170:173], v[200:203], v[8:11]
	v_mfma_f32_16x16x32_bf16 v[4:7], v[162:165], v[208:211], v[4:7]
	v_mfma_f32_16x16x32_bf16 v[0:3], v[170:173], v[208:211], v[0:3]
	v_mfma_f32_16x16x32_bf16 v[44:47], v[166:169], v[188:191], v[44:47]
	v_mfma_f32_16x16x32_bf16 v[40:43], v[174:177], v[188:191], v[40:43]
	v_mfma_f32_16x16x32_bf16 v[28:31], v[166:169], v[196:199], v[28:31]
	v_mfma_f32_16x16x32_bf16 v[24:27], v[174:177], v[196:199], v[24:27]
	v_mfma_f32_16x16x32_bf16 v[12:15], v[166:169], v[204:207], v[12:15]
	v_mfma_f32_16x16x32_bf16 v[8:11], v[174:177], v[204:207], v[8:11]
	v_mfma_f32_16x16x32_bf16 v[4:7], v[166:169], v[212:215], v[4:7]
	v_mfma_f32_16x16x32_bf16 v[0:3], v[174:177], v[212:215], v[0:3]
	s_setprio 0
	s_barrier
	s_add_i32 s81, s81, 2
	s_add_u32 s36, s36, 0x100
	s_addc_u32 s37, s37, 0
	s_add_u32 s79, s79, 0x100
	s_addc_u32 s80, s80, 0
	s_cmp_gt_u32 s81, 5
	s_cbranch_scc0 .LBB0_445
	s_branch .Lpost_445
.LBB0_445:
	ds_read_b128 v[146:149], v140
	ds_read_b128 v[150:153], v140 offset:1024
	ds_read_b128 v[154:157], v140 offset:2048
	ds_read_b128 v[158:161], v140 offset:3072
	ds_read_b128 v[162:165], v141
	ds_read_b128 v[166:169], v141 offset:1024
	ds_read_b128 v[170:173], v141 offset:2048
	ds_read_b128 v[174:177], v141 offset:3072
	s_add_u32 s14, s36, 0xfffe0080
	s_addc_u32 s15, s37, -1
	s_cmp_eq_u32 s81, 4
	s_cselect_b32 s39, s3, s15
	s_cselect_b32 s38, s2, s14
	s_cselect_b32 s15, s76, s80
	s_cselect_b32 s14, s78, s79
	s_mov_b32 m0, s50
	v_lshl_add_u64 v[182:183], s[36:37], 0, v[136:137]
	ds_read_b128 v[178:181], v142
	ds_read_b128 v[188:191], v142 offset:1024
	ds_read_b128 v[192:195], v142 offset:2048
	ds_read_b128 v[196:199], v142 offset:3072
	ds_read_b128 v[200:203], v142 offset:4096
	ds_read_b128 v[204:207], v142 offset:5120
	ds_read_b128 v[208:211], v142 offset:6144
	ds_read_b128 v[212:215], v142 offset:7168
	global_load_lds_dwordx4 v[182:183], off
	v_lshl_add_u64 v[182:183], s[36:37], 0, v[138:139]
	s_mov_b32 m0, s51
	s_nop 0
	global_load_lds_dwordx4 v[182:183], off
	s_waitcnt vmcnt(8)
	s_waitcnt lgkmcnt(0)
	s_barrier
; #define G_STAGE(bufoff, gbase, voff) do { _Pragma("unroll") for (int _i = 0; _i < 2; ++_i) \
;         __builtin_amdgcn_global_load_lds((const unsigned*)((const char*)(gbase) + voff[_i]), (LAS unsigned*)(lds + (bufoff) + ldsw + _i * 8192), 16, 0, 0); } while (0)
; #define G_LDA(dst, b, h) do { _Pragma("unroll") for (int m = 0; m < 4; ++m) _Pragma("unroll") for (int k = 0; k < 2; ++k) dst[m][k] = *(const LAS bf16x8*)(lds + G_SA(b, h) + aoff + m * 2048 + k * 1024); } while (0)
; #define G_MMA(ai, bj, At_, Bt_) do { __builtin_amdgcn_s_setprio(1); _Pragma("unroll") for (int m = 0; m < 4; ++m) _Pragma("unroll") for (int n = 0; n < 2; ++n) _Pragma("unroll") for (int k = 0; k < 2; ++k) \
;         acc[ai][bj][m][n] = __builtin_amdgcn_mfma_f32_16x16x32_bf16(Bt_[n][k], At_[m][k], acc[ai][bj][m][n], 0, 0, 0); __builtin_amdgcn_s_setprio(0); } while (0)
; #define WAIT_V(n) asm volatile("s_waitcnt vmcnt(" #n ")" ::: "memory")
; #define WAIT_L(n) asm volatile("s_waitcnt lgkmcnt(" #n ")" ::: "memory")
; #define BAR __builtin_amdgcn_s_barrier()
; #define SCHED __builtin_amdgcn_sched_barrier(0)
; template <class Get, class Epi>
; DI void gemm_loop(int ntiles, int ld, char* shm, const Get& get, const Epi& epi) {
;     ...
;             WAIT_V(8); WAIT_L(0); BAR; G_MMA(0, 0, At, B0); G_MMA(0, 1, At, B1); BAR; SCHED;
;             G_LDA(At, 0, 1); G_STAGE(G_SB(0, 0), b2, voffB); G_STAGE(G_SB(0, 1), b2 + hstep, voffB); G_STAGE(G_SA(0, 0), a2, voffA);
;             WAIT_V(8); WAIT_L(0); BAR; G_MMA(1, 0, At, B0); G_MMA(1, 1, At, B1); BAR; SCHED;
	s_setprio 1
	v_mfma_f32_16x16x32_bf16 v[124:127], v[146:149], v[178:181], v[124:127]
	v_mfma_f32_16x16x32_bf16 v[120:123], v[154:157], v[178:181], v[120:123]
	v_mfma_f32_16x16x32_bf16 v[116:119], v[146:149], v[192:195], v[116:119]
	v_mfma_f32_16x16x32_bf16 v[112:115], v[154:157], v[192:195], v[112:115]
	v_mfma_f32_16x16x32_bf16 v[100:103], v[146:149], v[200:203], v[100:103]
	v_mfma_f32_16x16x32_bf16 v[96:99], v[154:157], v[200:203], v[96:99]
	v_mfma_f32_16x16x32_bf16 v[84:87], v[146:149], v[208:211], v[84:87]
	v_mfma_f32_16x16x32_bf16 v[80:83], v[154:157], v[208:211], v[80:83]
	v_mfma_f32_16x16x32_bf16 v[124:127], v[150:153], v[188:191], v[124:127]
	v_mfma_f32_16x16x32_bf16 v[120:123], v[158:161], v[188:191], v[120:123]
	v_mfma_f32_16x16x32_bf16 v[116:119], v[150:153], v[196:199], v[116:119]
	v_mfma_f32_16x16x32_bf16 v[112:115], v[158:161], v[196:199], v[112:115]
	v_mfma_f32_16x16x32_bf16 v[100:103], v[150:153], v[204:207], v[100:103]
	v_mfma_f32_16x16x32_bf16 v[96:99], v[158:161], v[204:207], v[96:99]
	v_mfma_f32_16x16x32_bf16 v[84:87], v[150:153], v[212:215], v[84:87]
	v_mfma_f32_16x16x32_bf16 v[80:83], v[158:161], v[212:215], v[80:83]
	s_setprio 0
	s_setprio 1
	v_mfma_f32_16x16x32_bf16 v[108:111], v[162:165], v[178:181], v[108:111]
	v_mfma_f32_16x16x32_bf16 v[104:107], v[170:173], v[178:181], v[104:107]
	v_mfma_f32_16x16x32_bf16 v[92:95], v[162:165], v[192:195], v[92:95]
	v_mfma_f32_16x16x32_bf16 v[88:91], v[170:173], v[192:195], v[88:91]
	v_mfma_f32_16x16x32_bf16 v[76:79], v[162:165], v[200:203], v[76:79]
	v_mfma_f32_16x16x32_bf16 v[72:75], v[170:173], v[200:203], v[72:75]
	v_mfma_f32_16x16x32_bf16 v[68:71], v[162:165], v[208:211], v[68:71]
	v_mfma_f32_16x16x32_bf16 v[64:67], v[170:173], v[208:211], v[64:67]
	v_mfma_f32_16x16x32_bf16 v[108:111], v[166:169], v[188:191], v[108:111]
	v_mfma_f32_16x16x32_bf16 v[104:107], v[174:177], v[188:191], v[104:107]
	v_mfma_f32_16x16x32_bf16 v[92:95], v[166:169], v[196:199], v[92:95]
	v_mfma_f32_16x16x32_bf16 v[88:91], v[174:177], v[196:199], v[88:91]
	v_mfma_f32_16x16x32_bf16 v[76:79], v[166:169], v[204:207], v[76:79]
	v_mfma_f32_16x16x32_bf16 v[72:75], v[174:177], v[204:207], v[72:75]
	v_mfma_f32_16x16x32_bf16 v[68:71], v[166:169], v[212:215], v[68:71]
	v_mfma_f32_16x16x32_bf16 v[64:67], v[174:177], v[212:215], v[64:67]
	s_setprio 0
	s_barrier
	s_mov_b32 m0, s54
	v_lshl_add_u64 v[182:183], s[14:15], 0, v[132:133]
	s_add_u32 s82, s14, 0x20000
	ds_read_b128 v[178:181], v142 offset:16384
	ds_read_b128 v[188:191], v142 offset:17408
	ds_read_b128 v[192:195], v142 offset:18432
	ds_read_b128 v[196:199], v142 offset:19456
	ds_read_b128 v[200:203], v142 offset:20480
	ds_read_b128 v[204:207], v142 offset:21504
	ds_read_b128 v[208:211], v142 offset:22528
	ds_read_b128 v[212:215], v142 offset:23552
	global_load_lds_dwordx4 v[182:183], off
	v_lshl_add_u64 v[184:185], s[14:15], 0, v[128:129]
	s_mov_b32 m0, s55
	s_addc_u32 s83, s15, 0
	global_load_lds_dwordx4 v[184:185], off
	v_lshl_add_u64 v[186:187], s[82:83], 0, v[132:133]
	s_mov_b32 m0, s56
	v_lshl_add_u64 v[216:217], s[38:39], 0, v[130:131]
	global_load_lds_dwordx4 v[186:187], off
	v_lshl_add_u64 v[186:187], s[82:83], 0, v[128:129]
	s_mov_b32 m0, s57
	s_nop 0
	global_load_lds_dwordx4 v[186:187], off
	v_lshl_add_u64 v[186:187], s[38:39], 0, v[134:135]
	s_mov_b32 m0, s41
	s_nop 0
	global_load_lds_dwordx4 v[186:187], off
	s_mov_b32 m0, s43
	s_nop 0
	global_load_lds_dwordx4 v[216:217], off
	s_waitcnt vmcnt(8)
	s_waitcnt lgkmcnt(0)
	s_barrier
	s_setprio 1
	v_mfma_f32_16x16x32_bf16 v[60:63], v[146:149], v[178:181], v[60:63]
	v_mfma_f32_16x16x32_bf16 v[56:59], v[154:157], v[178:181], v[56:59]
	v_mfma_f32_16x16x32_bf16 v[52:55], v[146:149], v[192:195], v[52:55]
	v_mfma_f32_16x16x32_bf16 v[48:51], v[154:157], v[192:195], v[48:51]
	v_mfma_f32_16x16x32_bf16 v[36:39], v[146:149], v[200:203], v[36:39]
	v_mfma_f32_16x16x32_bf16 v[32:35], v[154:157], v[200:203], v[32:35]
	v_mfma_f32_16x16x32_bf16 v[20:23], v[146:149], v[208:211], v[20:23]
	v_mfma_f32_16x16x32_bf16 v[16:19], v[154:157], v[208:211], v[16:19]
	v_mfma_f32_16x16x32_bf16 v[60:63], v[150:153], v[188:191], v[60:63]
	v_mfma_f32_16x16x32_bf16 v[56:59], v[158:161], v[188:191], v[56:59]
	v_mfma_f32_16x16x32_bf16 v[52:55], v[150:153], v[196:199], v[52:55]
	v_mfma_f32_16x16x32_bf16 v[48:51], v[158:161], v[196:199], v[48:51]
	v_mfma_f32_16x16x32_bf16 v[36:39], v[150:153], v[204:207], v[36:39]
	v_mfma_f32_16x16x32_bf16 v[32:35], v[158:161], v[204:207], v[32:35]
	v_mfma_f32_16x16x32_bf16 v[20:23], v[150:153], v[212:215], v[20:23]
	v_mfma_f32_16x16x32_bf16 v[16:19], v[158:161], v[212:215], v[16:19]
	s_setprio 0
	s_setprio 1
	v_mfma_f32_16x16x32_bf16 v[44:47], v[162:165], v[178:181], v[44:47]
	v_mfma_f32_16x16x32_bf16 v[40:43], v[170:173], v[178:181], v[40:43]
	v_mfma_f32_16x16x32_bf16 v[28:31], v[162:165], v[192:195], v[28:31]
	v_mfma_f32_16x16x32_bf16 v[24:27], v[170:173], v[192:195], v[24:27]
	v_mfma_f32_16x16x32_bf16 v[12:15], v[162:165], v[200:203], v[12:15]
	v_mfma_f32_16x16x32_bf16 v[8:11], v[170:173], v[200:203], v[8:11]
	v_mfma_f32_16x16x32_bf16 v[4:7], v[162:165], v[208:211], v[4:7]
	v_mfma_f32_16x16x32_bf16 v[0:3], v[170:173], v[208:211], v[0:3]
	v_mfma_f32_16x16x32_bf16 v[44:47], v[166:169], v[188:191], v[44:47]
	v_mfma_f32_16x16x32_bf16 v[40:43], v[174:177], v[188:191], v[40:43]
	v_mfma_f32_16x16x32_bf16 v[28:31], v[166:169], v[196:199], v[28:31]
	v_mfma_f32_16x16x32_bf16 v[24:27], v[174:177], v[196:199], v[24:27]
	v_mfma_f32_16x16x32_bf16 v[12:15], v[166:169], v[204:207], v[12:15]
	v_mfma_f32_16x16x32_bf16 v[8:11], v[174:177], v[204:207], v[8:11]
	v_mfma_f32_16x16x32_bf16 v[4:7], v[166:169], v[212:215], v[4:7]
	v_mfma_f32_16x16x32_bf16 v[0:3], v[174:177], v[212:215], v[0:3]
	s_setprio 0
	s_barrier
; #define G_STAGE(bufoff, gbase, voff) do { _Pragma("unroll") for (int _i = 0; _i < 2; ++_i) \
;         __builtin_amdgcn_global_load_lds((const unsigned*)((const char*)(gbase) + voff[_i]), (LAS unsigned*)(lds + (bufoff) + ldsw + _i * 8192), 16, 0, 0); } while (0)
; #define G_LDA(dst, b, h) do { _Pragma("unroll") for (int m = 0; m < 4; ++m) _Pragma("unroll") for (int k = 0; k < 2; ++k) dst[m][k] = *(const LAS bf16x8*)(lds + G_SA(b, h) + aoff + m * 2048 + k * 1024); } while (0)
; #define G_LDB(dst, b, h) do { _Pragma("unroll") for (int n = 0; n < 2; ++n) _Pragma("unroll") for (int k = 0; k < 2; ++k) dst[n][k] = *(const LAS bf16x8*)(lds + G_SB(b, h) + boff + n * 2048 + k * 1024); } while (0)
; #define G_MMA(ai, bj, At_, Bt_) do { __builtin_amdgcn_s_setprio(1); _Pragma("unroll") for (int m = 0; m < 4; ++m) _Pragma("unroll") for (int n = 0; n < 2; ++n) _Pragma("unroll") for (int k = 0; k < 2; ++k) \
;         acc[ai][bj][m][n] = __builtin_amdgcn_mfma_f32_16x16x32_bf16(Bt_[n][k], At_[m][k], acc[ai][bj][m][n], 0, 0, 0); __builtin_amdgcn_s_setprio(0); } while (0)
; #define WAIT_V(n) asm volatile("s_waitcnt vmcnt(" #n ")" ::: "memory")
; #define WAIT_L(n) asm volatile("s_waitcnt lgkmcnt(" #n ")" ::: "memory")
; #define BAR __builtin_amdgcn_s_barrier()
; #define SCHED __builtin_amdgcn_sched_barrier(0)
; template <class Get, class Epi>
; DI void gemm_loop(int ntiles, int ld, char* shm, const Get& get, const Epi& epi) {
;     ...
;         for (int t = 0; t < nt; t += 2) {
;             const bool last = (t == nt - 2);
;     ...
;             G_LDB(B0, 1, 0); G_LDB(B1, 1, 1); SCHED; G_LDA(At, 1, 0); G_STAGE(G_SA(0, 1), a2 + hstep, voffA);
;             WAIT_V(8); WAIT_L(0); BAR; G_MMA(0, 0, At, B0); G_MMA(0, 1, At, B1); BAR; SCHED;
;             G_LDA(At, 1, 1); G_STAGE(G_SB(1, 0), b3, voffB); G_STAGE(G_SB(1, 1), b3 + hstep, voffB); G_STAGE(G_SA(1, 0), a3, voffA);
;             WAIT_V(8); WAIT_L(0); BAR; G_MMA(1, 0, At, B0); G_MMA(1, 1, At, B1); BAR; SCHED;
	ds_read_b128 v[146:149], v143
	ds_read_b128 v[150:153], v143 offset:1024
	ds_read_b128 v[154:157], v143 offset:2048
	ds_read_b128 v[158:161], v143 offset:3072
	ds_read_b128 v[162:165], v144
	ds_read_b128 v[166:169], v144 offset:1024
	ds_read_b128 v[170:173], v144 offset:2048
	ds_read_b128 v[174:177], v144 offset:3072
	s_add_u32 s38, s38, 0x20000
	s_addc_u32 s39, s39, 0
	s_mov_b32 m0, s44
	v_lshl_add_u64 v[218:219], s[38:39], 0, v[134:135]
	ds_read_b128 v[178:181], v142 offset:32768
	ds_read_b128 v[188:191], v142 offset:33792
	ds_read_b128 v[192:195], v142 offset:34816
	ds_read_b128 v[196:199], v142 offset:35840
	ds_read_b128 v[200:203], v142 offset:36864
	ds_read_b128 v[204:207], v142 offset:37888
	ds_read_b128 v[208:211], v142 offset:38912
	ds_read_b128 v[212:215], v142 offset:39936
	global_load_lds_dwordx4 v[218:219], off
	v_lshl_add_u64 v[218:219], s[38:39], 0, v[130:131]
	s_mov_b32 m0, s45
	s_nop 0
	global_load_lds_dwordx4 v[218:219], off
	s_waitcnt vmcnt(8)
	s_waitcnt lgkmcnt(0)
	s_barrier
	s_setprio 1
	v_mfma_f32_16x16x32_bf16 v[124:127], v[146:149], v[178:181], v[124:127]
	v_mfma_f32_16x16x32_bf16 v[120:123], v[154:157], v[178:181], v[120:123]
	v_mfma_f32_16x16x32_bf16 v[116:119], v[146:149], v[192:195], v[116:119]
	v_mfma_f32_16x16x32_bf16 v[112:115], v[154:157], v[192:195], v[112:115]
	v_mfma_f32_16x16x32_bf16 v[100:103], v[146:149], v[200:203], v[100:103]
	v_mfma_f32_16x16x32_bf16 v[96:99], v[154:157], v[200:203], v[96:99]
	v_mfma_f32_16x16x32_bf16 v[84:87], v[146:149], v[208:211], v[84:87]
	v_mfma_f32_16x16x32_bf16 v[80:83], v[154:157], v[208:211], v[80:83]
	v_mfma_f32_16x16x32_bf16 v[124:127], v[150:153], v[188:191], v[124:127]
	v_mfma_f32_16x16x32_bf16 v[120:123], v[158:161], v[188:191], v[120:123]
	v_mfma_f32_16x16x32_bf16 v[116:119], v[150:153], v[196:199], v[116:119]
	v_mfma_f32_16x16x32_bf16 v[112:115], v[158:161], v[196:199], v[112:115]
	v_mfma_f32_16x16x32_bf16 v[100:103], v[150:153], v[204:207], v[100:103]
	v_mfma_f32_16x16x32_bf16 v[96:99], v[158:161], v[204:207], v[96:99]
	v_mfma_f32_16x16x32_bf16 v[84:87], v[150:153], v[212:215], v[84:87]
	v_mfma_f32_16x16x32_bf16 v[80:83], v[158:161], v[212:215], v[80:83]
	s_setprio 0
	s_setprio 1
	v_mfma_f32_16x16x32_bf16 v[108:111], v[162:165], v[178:181], v[108:111]
	v_mfma_f32_16x16x32_bf16 v[104:107], v[170:173], v[178:181], v[104:107]
	v_mfma_f32_16x16x32_bf16 v[92:95], v[162:165], v[192:195], v[92:95]
	v_mfma_f32_16x16x32_bf16 v[88:91], v[170:173], v[192:195], v[88:91]
	v_mfma_f32_16x16x32_bf16 v[76:79], v[162:165], v[200:203], v[76:79]
	v_mfma_f32_16x16x32_bf16 v[72:75], v[170:173], v[200:203], v[72:75]
	v_mfma_f32_16x16x32_bf16 v[68:71], v[162:165], v[208:211], v[68:71]
	v_mfma_f32_16x16x32_bf16 v[64:67], v[170:173], v[208:211], v[64:67]
	v_mfma_f32_16x16x32_bf16 v[108:111], v[166:169], v[188:191], v[108:111]
	v_mfma_f32_16x16x32_bf16 v[104:107], v[174:177], v[188:191], v[104:107]
	v_mfma_f32_16x16x32_bf16 v[92:95], v[166:169], v[196:199], v[92:95]
	v_mfma_f32_16x16x32_bf16 v[88:91], v[174:177], v[196:199], v[88:91]
	v_mfma_f32_16x16x32_bf16 v[76:79], v[166:169], v[204:207], v[76:79]
	v_mfma_f32_16x16x32_bf16 v[72:75], v[174:177], v[204:207], v[72:75]
	v_mfma_f32_16x16x32_bf16 v[68:71], v[166:169], v[212:215], v[68:71]
	v_mfma_f32_16x16x32_bf16 v[64:67], v[174:177], v[212:215], v[64:67]
	s_setprio 0
	s_barrier
	s_mov_b32 m0, s58
	v_lshl_add_u64 v[182:183], v[182:183], 0, s[12:13]
	s_add_u32 s14, s14, 0x20080
	ds_read_b128 v[178:181], v142 offset:49152
	ds_read_b128 v[188:191], v142 offset:50176
	ds_read_b128 v[192:195], v142 offset:51200
	ds_read_b128 v[196:199], v142 offset:52224
	ds_read_b128 v[200:203], v142 offset:53248
	ds_read_b128 v[204:207], v142 offset:54272
	ds_read_b128 v[208:211], v142 offset:55296
	ds_read_b128 v[212:215], v142 offset:56320
	global_load_lds_dwordx4 v[182:183], off
	v_lshl_add_u64 v[182:183], v[184:185], 0, s[12:13]
	s_mov_b32 m0, s59
	s_addc_u32 s15, s15, 0
	global_load_lds_dwordx4 v[182:183], off
	v_lshl_add_u64 v[182:183], s[14:15], 0, v[132:133]
	s_mov_b32 m0, s72
	s_nop 0
	global_load_lds_dwordx4 v[182:183], off
	v_lshl_add_u64 v[182:183], s[14:15], 0, v[128:129]
	s_mov_b32 m0, s73
	s_nop 0
	global_load_lds_dwordx4 v[182:183], off
	v_lshl_add_u64 v[182:183], v[186:187], 0, s[12:13]
	s_mov_b32 m0, s46
	s_nop 0
	global_load_lds_dwordx4 v[182:183], off
	v_lshl_add_u64 v[182:183], v[216:217], 0, s[12:13]
	s_mov_b32 m0, s47
	s_nop 0
	global_load_lds_dwordx4 v[182:183], off
	s_waitcnt vmcnt(8)
	s_waitcnt lgkmcnt(0)
	s_barrier
	s_setprio 1
	v_mfma_f32_16x16x32_bf16 v[60:63], v[146:149], v[178:181], v[60:63]
	v_mfma_f32_16x16x32_bf16 v[56:59], v[154:157], v[178:181], v[56:59]
	v_mfma_f32_16x16x32_bf16 v[52:55], v[146:149], v[192:195], v[52:55]
	v_mfma_f32_16x16x32_bf16 v[48:51], v[154:157], v[192:195], v[48:51]
	v_mfma_f32_16x16x32_bf16 v[36:39], v[146:149], v[200:203], v[36:39]
	v_mfma_f32_16x16x32_bf16 v[32:35], v[154:157], v[200:203], v[32:35]
	v_mfma_f32_16x16x32_bf16 v[20:23], v[146:149], v[208:211], v[20:23]
	v_mfma_f32_16x16x32_bf16 v[16:19], v[154:157], v[208:211], v[16:19]
	v_mfma_f32_16x16x32_bf16 v[60:63], v[150:153], v[188:191], v[60:63]
	v_mfma_f32_16x16x32_bf16 v[56:59], v[158:161], v[188:191], v[56:59]
	v_mfma_f32_16x16x32_bf16 v[52:55], v[150:153], v[196:199], v[52:55]
	v_mfma_f32_16x16x32_bf16 v[48:51], v[158:161], v[196:199], v[48:51]
	v_mfma_f32_16x16x32_bf16 v[36:39], v[150:153], v[204:207], v[36:39]
	v_mfma_f32_16x16x32_bf16 v[32:35], v[158:161], v[204:207], v[32:35]
	v_mfma_f32_16x16x32_bf16 v[20:23], v[150:153], v[212:215], v[20:23]
	v_mfma_f32_16x16x32_bf16 v[16:19], v[158:161], v[212:215], v[16:19]
	s_setprio 0
	s_setprio 1
	v_mfma_f32_16x16x32_bf16 v[44:47], v[162:165], v[178:181], v[44:47]
	v_mfma_f32_16x16x32_bf16 v[40:43], v[170:173], v[178:181], v[40:43]
	v_mfma_f32_16x16x32_bf16 v[28:31], v[162:165], v[192:195], v[28:31]
	v_mfma_f32_16x16x32_bf16 v[24:27], v[170:173], v[192:195], v[24:27]
	v_mfma_f32_16x16x32_bf16 v[12:15], v[162:165], v[200:203], v[12:15]
	v_mfma_f32_16x16x32_bf16 v[8:11], v[170:173], v[200:203], v[8:11]
	v_mfma_f32_16x16x32_bf16 v[4:7], v[162:165], v[208:211], v[4:7]
	v_mfma_f32_16x16x32_bf16 v[0:3], v[170:173], v[208:211], v[0:3]
	v_mfma_f32_16x16x32_bf16 v[44:47], v[166:169], v[188:191], v[44:47]
	v_mfma_f32_16x16x32_bf16 v[40:43], v[174:177], v[188:191], v[40:43]
	v_mfma_f32_16x16x32_bf16 v[28:31], v[166:169], v[196:199], v[28:31]
	v_mfma_f32_16x16x32_bf16 v[24:27], v[174:177], v[196:199], v[24:27]
	v_mfma_f32_16x16x32_bf16 v[12:15], v[166:169], v[204:207], v[12:15]
	v_mfma_f32_16x16x32_bf16 v[8:11], v[174:177], v[204:207], v[8:11]
	v_mfma_f32_16x16x32_bf16 v[4:7], v[166:169], v[212:215], v[4:7]
	v_mfma_f32_16x16x32_bf16 v[0:3], v[174:177], v[212:215], v[0:3]
	s_setprio 0
	s_barrier
	s_add_i32 s81, s81, 2
	s_add_u32 s36, s36, 0x100
	s_addc_u32 s37, s37, 0
	s_add_u32 s79, s79, 0x100
	s_addc_u32 s80, s80, 0
	s_cmp_gt_u32 s81, 5
	s_cbranch_scc0 .LBB0_445

; #define G_STAGE(bufoff, gbase, voff) do { _Pragma("unroll") for (int _i = 0; _i < 2; ++_i) \
;         __builtin_amdgcn_global_load_lds((const unsigned*)((const char*)(gbase) + voff[_i]), (LAS unsigned*)(lds + (bufoff) + ldsw + _i * 8192), 16, 0, 0); } while (0)
; #define G_LDA(dst, b, h) do { _Pragma("unroll") for (int m = 0; m < 4; ++m) _Pragma("unroll") for (int k = 0; k < 2; ++k) dst[m][k] = *(const LAS bf16x8*)(lds + G_SA(b, h) + aoff + m * 2048 + k * 1024); } while (0)
; #define G_MMA(ai, bj, At_, Bt_) do { __builtin_amdgcn_s_setprio(1); _Pragma("unroll") for (int m = 0; m < 4; ++m) _Pragma("unroll") for (int n = 0; n < 2; ++n) _Pragma("unroll") for (int k = 0; k < 2; ++k) \
;         acc[ai][bj][m][n] = __builtin_amdgcn_mfma_f32_16x16x32_bf16(Bt_[n][k], At_[m][k], acc[ai][bj][m][n], 0, 0, 0); __builtin_amdgcn_s_setprio(0); } while (0)
; #define WAIT_V(n) asm volatile("s_waitcnt vmcnt(" #n ")" ::: "memory")
; #define WAIT_L(n) asm volatile("s_waitcnt lgkmcnt(" #n ")" ::: "memory")
; #define BAR __builtin_amdgcn_s_barrier()
; #define SCHED __builtin_amdgcn_sched_barrier(0)
; template <class Get, class Epi>
; DI void gemm_loop(int ntiles, int ld, char* shm, const Get& get, const Epi& epi) {
;     ...
;             WAIT_V(8); WAIT_L(0); BAR; G_MMA(0, 0, At, B0); G_MMA(0, 1, At, B1); BAR; SCHED;
;             G_LDA(At, 0, 1); G_STAGE(G_SB(0, 0), b2, voffB); G_STAGE(G_SB(0, 1), b2 + hstep, voffB); G_STAGE(G_SA(0, 0), a2, voffA);
.Lrj_528_0:
	s_waitcnt lgkmcnt(0)
	s_barrier
	s_setprio 1
	v_mfma_f32_16x16x32_bf16 v[124:127], v[128:131], v[172:175], 0
	v_mfma_f32_16x16x32_bf16 v[120:123], v[136:139], v[172:175], 0
	v_mfma_f32_16x16x32_bf16 v[116:119], v[128:131], v[188:191], 0
	v_mfma_f32_16x16x32_bf16 v[112:115], v[136:139], v[188:191], 0
	v_mfma_f32_16x16x32_bf16 v[108:111], v[128:131], v[196:199], 0
	v_mfma_f32_16x16x32_bf16 v[104:107], v[136:139], v[196:199], 0
	v_mfma_f32_16x16x32_bf16 v[100:103], v[128:131], v[204:207], 0
	v_mfma_f32_16x16x32_bf16 v[96:99], v[136:139], v[204:207], 0
	v_mfma_f32_16x16x32_bf16 v[124:127], v[132:135], v[180:183], v[124:127]
	v_mfma_f32_16x16x32_bf16 v[120:123], v[140:143], v[180:183], v[120:123]
	v_mfma_f32_16x16x32_bf16 v[116:119], v[132:135], v[192:195], v[116:119]
	v_mfma_f32_16x16x32_bf16 v[112:115], v[140:143], v[192:195], v[112:115]
	v_mfma_f32_16x16x32_bf16 v[108:111], v[132:135], v[200:203], v[108:111]
	v_mfma_f32_16x16x32_bf16 v[104:107], v[140:143], v[200:203], v[104:107]
	v_mfma_f32_16x16x32_bf16 v[100:103], v[132:135], v[208:211], v[100:103]
	v_mfma_f32_16x16x32_bf16 v[96:99], v[140:143], v[208:211], v[96:99]
	s_setprio 0
	s_setprio 1
	v_mfma_f32_16x16x32_bf16 v[60:63], v[144:147], v[172:175], 0
	v_mfma_f32_16x16x32_bf16 v[56:59], v[164:167], v[172:175], 0
	v_mfma_f32_16x16x32_bf16 v[52:55], v[144:147], v[188:191], 0
	v_mfma_f32_16x16x32_bf16 v[48:51], v[164:167], v[188:191], 0
	v_mfma_f32_16x16x32_bf16 v[44:47], v[144:147], v[196:199], 0
	v_mfma_f32_16x16x32_bf16 v[40:43], v[164:167], v[196:199], 0
	v_mfma_f32_16x16x32_bf16 v[36:39], v[144:147], v[204:207], 0
	v_mfma_f32_16x16x32_bf16 v[32:35], v[164:167], v[204:207], 0
	v_mfma_f32_16x16x32_bf16 v[60:63], v[148:151], v[180:183], v[60:63]
	v_mfma_f32_16x16x32_bf16 v[56:59], v[168:171], v[180:183], v[56:59]
	v_mfma_f32_16x16x32_bf16 v[52:55], v[148:151], v[192:195], v[52:55]
	v_mfma_f32_16x16x32_bf16 v[48:51], v[168:171], v[192:195], v[48:51]
	v_mfma_f32_16x16x32_bf16 v[44:47], v[148:151], v[200:203], v[44:47]
	v_mfma_f32_16x16x32_bf16 v[40:43], v[168:171], v[200:203], v[40:43]
	v_mfma_f32_16x16x32_bf16 v[36:39], v[148:151], v[208:211], v[36:39]
	v_mfma_f32_16x16x32_bf16 v[32:35], v[168:171], v[208:211], v[32:35]
	s_setprio 0
	s_barrier
	s_add_i32 s84, s78, s56
	v_lshl_add_u64 v[184:185], s[14:15], 0, v[154:155]
	s_mov_b32 m0, s84
	ds_read_b128 v[172:175], v179 offset:16384
	ds_read_b128 v[180:183], v179 offset:17408
	ds_read_b128 v[188:191], v179 offset:18432
	ds_read_b128 v[192:195], v179 offset:19456
	ds_read_b128 v[196:199], v179 offset:20480
	ds_read_b128 v[200:203], v179 offset:21504
	ds_read_b128 v[204:207], v179 offset:22528
	ds_read_b128 v[208:211], v179 offset:23552
	global_load_lds_dwordx4 v[184:185], off
	s_add_i32 m0, s84, 0x2000
	s_add_u32 s84, s14, 0x40000
	v_lshl_add_u64 v[186:187], s[14:15], 0, v[158:159]
	s_addc_u32 s85, s15, 0
	s_add_i32 s86, s79, s56
	global_load_lds_dwordx4 v[186:187], off
	v_lshl_add_u64 v[212:213], s[84:85], 0, v[154:155]
	s_mov_b32 m0, s86
	v_lshl_add_u64 v[214:215], s[46:47], 0, v[156:157]
	global_load_lds_dwordx4 v[212:213], off
	v_lshl_add_u64 v[212:213], s[84:85], 0, v[158:159]
	s_add_i32 m0, s86, 0x2000
	s_nop 0
	global_load_lds_dwordx4 v[212:213], off
	v_lshl_add_u64 v[212:213], s[46:47], 0, v[152:153]
	s_mov_b32 m0, s57
	s_nop 0
	global_load_lds_dwordx4 v[212:213], off
	s_mov_b32 m0, s58
	s_nop 0
	global_load_lds_dwordx4 v[214:215], off
	s_cmp_lg_u32 s100, 0
	s_cbranch_scc0 .Lrf_528_1
	s_waitcnt vmcnt(16)
	s_branch .Lrj_528_1

; #define G_STAGE(bufoff, gbase, voff) do { _Pragma("unroll") for (int _i = 0; _i < 2; ++_i) \
;         __builtin_amdgcn_global_load_lds((const unsigned*)((const char*)(gbase) + voff[_i]), (LAS unsigned*)(lds + (bufoff) + ldsw + _i * 8192), 16, 0, 0); } while (0)
; #define G_LDA(dst, b, h) do { _Pragma("unroll") for (int m = 0; m < 4; ++m) _Pragma("unroll") for (int k = 0; k < 2; ++k) dst[m][k] = *(const LAS bf16x8*)(lds + G_SA(b, h) + aoff + m * 2048 + k * 1024); } while (0)
; #define G_LDB(dst, b, h) do { _Pragma("unroll") for (int n = 0; n < 2; ++n) _Pragma("unroll") for (int k = 0; k < 2; ++k) dst[n][k] = *(const LAS bf16x8*)(lds + G_SB(b, h) + boff + n * 2048 + k * 1024); } while (0)
; #define G_MMA(ai, bj, At_, Bt_) do { __builtin_amdgcn_s_setprio(1); _Pragma("unroll") for (int m = 0; m < 4; ++m) _Pragma("unroll") for (int n = 0; n < 2; ++n) _Pragma("unroll") for (int k = 0; k < 2; ++k) \
;         acc[ai][bj][m][n] = __builtin_amdgcn_mfma_f32_16x16x32_bf16(Bt_[n][k], At_[m][k], acc[ai][bj][m][n], 0, 0, 0); __builtin_amdgcn_s_setprio(0); } while (0)
; #define WAIT_V(n) asm volatile("s_waitcnt vmcnt(" #n ")" ::: "memory")
; #define WAIT_L(n) asm volatile("s_waitcnt lgkmcnt(" #n ")" ::: "memory")
; #define BAR __builtin_amdgcn_s_barrier()
; #define SCHED __builtin_amdgcn_sched_barrier(0)
; template <class Get, class Epi>
; DI void gemm_loop(int ntiles, int ld, char* shm, const Get& get, const Epi& epi) {
;     ...
;             WAIT_V(8); WAIT_L(0); BAR; G_MMA(1, 0, At, B0); G_MMA(1, 1, At, B1); BAR; SCHED;
;             G_LDB(B0, 1, 0); G_LDB(B1, 1, 1); SCHED; G_LDA(At, 1, 0); G_STAGE(G_SA(0, 1), a2 + hstep, voffA);
;             WAIT_V(8); WAIT_L(0); BAR; G_MMA(0, 0, At, B0); G_MMA(0, 1, At, B1); BAR; SCHED;
.Lrj_528_1:
	s_waitcnt lgkmcnt(0)
	s_barrier
	s_setprio 1
	v_mfma_f32_16x16x32_bf16 v[92:95], v[128:131], v[172:175], 0
	v_mfma_f32_16x16x32_bf16 v[88:91], v[136:139], v[172:175], 0
	v_mfma_f32_16x16x32_bf16 v[84:87], v[128:131], v[188:191], 0
	v_mfma_f32_16x16x32_bf16 v[80:83], v[136:139], v[188:191], 0
	v_mfma_f32_16x16x32_bf16 v[76:79], v[128:131], v[196:199], 0
	v_mfma_f32_16x16x32_bf16 v[72:75], v[136:139], v[196:199], 0
	v_mfma_f32_16x16x32_bf16 v[68:71], v[128:131], v[204:207], 0
	v_mfma_f32_16x16x32_bf16 v[64:67], v[136:139], v[204:207], 0
	v_mfma_f32_16x16x32_bf16 v[92:95], v[132:135], v[180:183], v[92:95]
	v_mfma_f32_16x16x32_bf16 v[88:91], v[140:143], v[180:183], v[88:91]
	v_mfma_f32_16x16x32_bf16 v[84:87], v[132:135], v[192:195], v[84:87]
	v_mfma_f32_16x16x32_bf16 v[80:83], v[140:143], v[192:195], v[80:83]
	v_mfma_f32_16x16x32_bf16 v[76:79], v[132:135], v[200:203], v[76:79]
	v_mfma_f32_16x16x32_bf16 v[72:75], v[140:143], v[200:203], v[72:75]
	v_mfma_f32_16x16x32_bf16 v[68:71], v[132:135], v[208:211], v[68:71]
	v_mfma_f32_16x16x32_bf16 v[64:67], v[140:143], v[208:211], v[64:67]
	s_setprio 0
	s_setprio 1
	v_mfma_f32_16x16x32_bf16 v[28:31], v[144:147], v[172:175], 0
	v_mfma_f32_16x16x32_bf16 v[24:27], v[164:167], v[172:175], 0
	v_mfma_f32_16x16x32_bf16 v[20:23], v[144:147], v[188:191], 0
	v_mfma_f32_16x16x32_bf16 v[16:19], v[164:167], v[188:191], 0
	v_mfma_f32_16x16x32_bf16 v[12:15], v[144:147], v[196:199], 0
	v_mfma_f32_16x16x32_bf16 v[8:11], v[164:167], v[196:199], 0
	v_mfma_f32_16x16x32_bf16 v[4:7], v[144:147], v[204:207], 0
	v_mfma_f32_16x16x32_bf16 v[0:3], v[164:167], v[204:207], 0
	v_mfma_f32_16x16x32_bf16 v[28:31], v[148:151], v[180:183], v[28:31]
	v_mfma_f32_16x16x32_bf16 v[24:27], v[168:171], v[180:183], v[24:27]
	v_mfma_f32_16x16x32_bf16 v[20:23], v[148:151], v[192:195], v[20:23]
	v_mfma_f32_16x16x32_bf16 v[16:19], v[168:171], v[192:195], v[16:19]
	v_mfma_f32_16x16x32_bf16 v[12:15], v[148:151], v[200:203], v[12:15]
	v_mfma_f32_16x16x32_bf16 v[8:11], v[168:171], v[200:203], v[8:11]
	v_mfma_f32_16x16x32_bf16 v[4:7], v[148:151], v[208:211], v[4:7]
	v_mfma_f32_16x16x32_bf16 v[0:3], v[168:171], v[208:211], v[0:3]
	s_setprio 0
	s_barrier
	s_add_i32 s84, 0, 0x18000
	s_add_i32 s85, 0, 0x1c000
	v_add_u32_e32 v140, s84, v176
	v_add_u32_e32 v168, s85, v176
	ds_read_b128 v[128:131], v140
	ds_read_b128 v[132:135], v140 offset:1024
	ds_read_b128 v[136:139], v140 offset:2048
	ds_read_b128 v[140:143], v140 offset:3072
	ds_read_b128 v[144:147], v168
	ds_read_b128 v[148:151], v168 offset:1024
	ds_read_b128 v[164:167], v168 offset:2048
	ds_read_b128 v[168:171], v168 offset:3072
	s_add_u32 s46, s46, 0x40000
	s_addc_u32 s47, s47, 0
	s_mov_b32 m0, s59
	v_lshl_add_u64 v[216:217], s[46:47], 0, v[152:153]
	ds_read_b128 v[172:175], v179 offset:32768
	ds_read_b128 v[180:183], v179 offset:33792
	ds_read_b128 v[188:191], v179 offset:34816
	ds_read_b128 v[192:195], v179 offset:35840
	ds_read_b128 v[196:199], v179 offset:36864
	ds_read_b128 v[200:203], v179 offset:37888
	ds_read_b128 v[204:207], v179 offset:38912
	ds_read_b128 v[208:211], v179 offset:39936
	global_load_lds_dwordx4 v[216:217], off
	v_lshl_add_u64 v[216:217], s[46:47], 0, v[156:157]
	s_mov_b32 m0, s72
	s_nop 0
	global_load_lds_dwordx4 v[216:217], off
	s_waitcnt vmcnt(8)
	s_waitcnt lgkmcnt(0)
	s_barrier
	s_setprio 1
	v_mfma_f32_16x16x32_bf16 v[124:127], v[128:131], v[172:175], v[124:127]
	v_mfma_f32_16x16x32_bf16 v[120:123], v[136:139], v[172:175], v[120:123]
	v_mfma_f32_16x16x32_bf16 v[116:119], v[128:131], v[188:191], v[116:119]
	v_mfma_f32_16x16x32_bf16 v[112:115], v[136:139], v[188:191], v[112:115]
	v_mfma_f32_16x16x32_bf16 v[108:111], v[128:131], v[196:199], v[108:111]
	v_mfma_f32_16x16x32_bf16 v[104:107], v[136:139], v[196:199], v[104:107]
	v_mfma_f32_16x16x32_bf16 v[100:103], v[128:131], v[204:207], v[100:103]
	v_mfma_f32_16x16x32_bf16 v[96:99], v[136:139], v[204:207], v[96:99]
	v_mfma_f32_16x16x32_bf16 v[124:127], v[132:135], v[180:183], v[124:127]
	v_mfma_f32_16x16x32_bf16 v[120:123], v[140:143], v[180:183], v[120:123]
	v_mfma_f32_16x16x32_bf16 v[116:119], v[132:135], v[192:195], v[116:119]
	v_mfma_f32_16x16x32_bf16 v[112:115], v[140:143], v[192:195], v[112:115]
	v_mfma_f32_16x16x32_bf16 v[108:111], v[132:135], v[200:203], v[108:111]
	v_mfma_f32_16x16x32_bf16 v[104:107], v[140:143], v[200:203], v[104:107]
	v_mfma_f32_16x16x32_bf16 v[100:103], v[132:135], v[208:211], v[100:103]
	v_mfma_f32_16x16x32_bf16 v[96:99], v[140:143], v[208:211], v[96:99]
	s_setprio 0
	s_setprio 1
	v_mfma_f32_16x16x32_bf16 v[60:63], v[144:147], v[172:175], v[60:63]
	v_mfma_f32_16x16x32_bf16 v[56:59], v[164:167], v[172:175], v[56:59]
	v_mfma_f32_16x16x32_bf16 v[52:55], v[144:147], v[188:191], v[52:55]
	v_mfma_f32_16x16x32_bf16 v[48:51], v[164:167], v[188:191], v[48:51]
	v_mfma_f32_16x16x32_bf16 v[44:47], v[144:147], v[196:199], v[44:47]
	v_mfma_f32_16x16x32_bf16 v[40:43], v[164:167], v[196:199], v[40:43]
	v_mfma_f32_16x16x32_bf16 v[36:39], v[144:147], v[204:207], v[36:39]
	v_mfma_f32_16x16x32_bf16 v[32:35], v[164:167], v[204:207], v[32:35]
	v_mfma_f32_16x16x32_bf16 v[60:63], v[148:151], v[180:183], v[60:63]
	v_mfma_f32_16x16x32_bf16 v[56:59], v[168:171], v[180:183], v[56:59]
	v_mfma_f32_16x16x32_bf16 v[52:55], v[148:151], v[192:195], v[52:55]
	v_mfma_f32_16x16x32_bf16 v[48:51], v[168:171], v[192:195], v[48:51]
	v_mfma_f32_16x16x32_bf16 v[44:47], v[148:151], v[200:203], v[44:47]
	v_mfma_f32_16x16x32_bf16 v[40:43], v[168:171], v[200:203], v[40:43]
	v_mfma_f32_16x16x32_bf16 v[36:39], v[148:151], v[208:211], v[36:39]
	v_mfma_f32_16x16x32_bf16 v[32:35], v[168:171], v[208:211], v[32:35]
	s_setprio 0
	s_barrier
; #define G_STAGE(bufoff, gbase, voff) do { _Pragma("unroll") for (int _i = 0; _i < 2; ++_i) \
;         __builtin_amdgcn_global_load_lds((const unsigned*)((const char*)(gbase) + voff[_i]), (LAS unsigned*)(lds + (bufoff) + ldsw + _i * 8192), 16, 0, 0); } while (0)
; #define G_LDA(dst, b, h) do { _Pragma("unroll") for (int m = 0; m < 4; ++m) _Pragma("unroll") for (int k = 0; k < 2; ++k) dst[m][k] = *(const LAS bf16x8*)(lds + G_SA(b, h) + aoff + m * 2048 + k * 1024); } while (0)
; #define G_LDB(dst, b, h) do { _Pragma("unroll") for (int n = 0; n < 2; ++n) _Pragma("unroll") for (int k = 0; k < 2; ++k) dst[n][k] = *(const LAS bf16x8*)(lds + G_SB(b, h) + boff + n * 2048 + k * 1024); } while (0)
; #define G_MMA(ai, bj, At_, Bt_) do { __builtin_amdgcn_s_setprio(1); _Pragma("unroll") for (int m = 0; m < 4; ++m) _Pragma("unroll") for (int n = 0; n < 2; ++n) _Pragma("unroll") for (int k = 0; k < 2; ++k) \
;         acc[ai][bj][m][n] = __builtin_amdgcn_mfma_f32_16x16x32_bf16(Bt_[n][k], At_[m][k], acc[ai][bj][m][n], 0, 0, 0); __builtin_amdgcn_s_setprio(0); } while (0)
; #define WAIT_V(n) asm volatile("s_waitcnt vmcnt(" #n ")" ::: "memory")
; #define WAIT_L(n) asm volatile("s_waitcnt lgkmcnt(" #n ")" ::: "memory")
; #define BAR __builtin_amdgcn_s_barrier()
; #define SCHED __builtin_amdgcn_sched_barrier(0)
; template <class Get, class Epi>
; DI void gemm_loop(int ntiles, int ld, char* shm, const Get& get, const Epi& epi) {
;     ...
;         for (int t = 0; t < nt; t += 2) {
;             const bool last = (t == nt - 2);
;             const char* a1 = cA + (size_t)(t + 1) * kstep;
;             const char* a2 = last ? nA : cA + (size_t)(t + 2) * kstep; const char* b2 = last ? nB : cB + (size_t)(t + 2) * kstep;
;             const char* a3 = a2 + kstep; const char* b3 = b2 + kstep;
;             G_LDB(B0, 0, 0); G_LDB(B1, 0, 1); SCHED; G_LDA(At, 0, 0); G_STAGE(G_SA(1, 1), a1 + hstep, voffA);
;     ...
;             G_LDA(At, 1, 1); G_STAGE(G_SB(1, 0), b3, voffB); G_STAGE(G_SB(1, 1), b3 + hstep, voffB); G_STAGE(G_SA(1, 0), a3, voffA);
;             WAIT_V(8); WAIT_L(0); BAR; G_MMA(1, 0, At, B0); G_MMA(1, 1, At, B1); BAR; SCHED;
	s_add_i32 s46, s84, s56
	v_lshl_add_u64 v[184:185], v[184:185], 0, s[10:11]
	s_mov_b32 m0, s46
	ds_read_b128 v[172:175], v179 offset:49152
	ds_read_b128 v[180:183], v179 offset:50176
	ds_read_b128 v[188:191], v179 offset:51200
	ds_read_b128 v[192:195], v179 offset:52224
	ds_read_b128 v[196:199], v179 offset:53248
	ds_read_b128 v[200:203], v179 offset:54272
	ds_read_b128 v[204:207], v179 offset:55296
	ds_read_b128 v[208:211], v179 offset:56320
	global_load_lds_dwordx4 v[184:185], off
	s_add_i32 m0, s46, 0x2000
	s_add_u32 s14, s14, 0x40080
	v_lshl_add_u64 v[184:185], v[186:187], 0, s[10:11]
	s_addc_u32 s15, s15, 0
	s_add_i32 s46, s85, s56
	global_load_lds_dwordx4 v[184:185], off
	v_lshl_add_u64 v[184:185], s[14:15], 0, v[154:155]
	s_mov_b32 m0, s46
	s_nop 0
	global_load_lds_dwordx4 v[184:185], off
	v_lshl_add_u64 v[184:185], s[14:15], 0, v[158:159]
	s_add_i32 m0, s46, 0x2000
	s_nop 0
	global_load_lds_dwordx4 v[184:185], off
	v_lshl_add_u64 v[184:185], v[212:213], 0, s[10:11]
	s_mov_b32 m0, s75
	s_nop 0
	global_load_lds_dwordx4 v[184:185], off
	v_lshl_add_u64 v[184:185], v[214:215], 0, s[10:11]
	s_mov_b32 m0, s76
	s_nop 0
	global_load_lds_dwordx4 v[184:185], off
	s_waitcnt vmcnt(8)
	s_waitcnt lgkmcnt(0)
	s_barrier
	s_setprio 1
	v_mfma_f32_16x16x32_bf16 v[92:95], v[128:131], v[172:175], v[92:95]
	v_mfma_f32_16x16x32_bf16 v[88:91], v[136:139], v[172:175], v[88:91]
	v_mfma_f32_16x16x32_bf16 v[84:87], v[128:131], v[188:191], v[84:87]
	v_mfma_f32_16x16x32_bf16 v[80:83], v[136:139], v[188:191], v[80:83]
	v_mfma_f32_16x16x32_bf16 v[76:79], v[128:131], v[196:199], v[76:79]
	v_mfma_f32_16x16x32_bf16 v[72:75], v[136:139], v[196:199], v[72:75]
	v_mfma_f32_16x16x32_bf16 v[68:71], v[128:131], v[204:207], v[68:71]
	v_mfma_f32_16x16x32_bf16 v[64:67], v[136:139], v[204:207], v[64:67]
	v_mfma_f32_16x16x32_bf16 v[92:95], v[132:135], v[180:183], v[92:95]
	v_mfma_f32_16x16x32_bf16 v[88:91], v[140:143], v[180:183], v[88:91]
	v_mfma_f32_16x16x32_bf16 v[84:87], v[132:135], v[192:195], v[84:87]
	v_mfma_f32_16x16x32_bf16 v[80:83], v[140:143], v[192:195], v[80:83]
	v_mfma_f32_16x16x32_bf16 v[76:79], v[132:135], v[200:203], v[76:79]
	v_mfma_f32_16x16x32_bf16 v[72:75], v[140:143], v[200:203], v[72:75]
	v_mfma_f32_16x16x32_bf16 v[68:71], v[132:135], v[208:211], v[68:71]
	v_mfma_f32_16x16x32_bf16 v[64:67], v[140:143], v[208:211], v[64:67]
	s_setprio 0
	s_setprio 1
	v_mfma_f32_16x16x32_bf16 v[28:31], v[144:147], v[172:175], v[28:31]
	v_mfma_f32_16x16x32_bf16 v[24:27], v[164:167], v[172:175], v[24:27]
	v_mfma_f32_16x16x32_bf16 v[20:23], v[144:147], v[188:191], v[20:23]
	v_mfma_f32_16x16x32_bf16 v[16:19], v[164:167], v[188:191], v[16:19]
	v_mfma_f32_16x16x32_bf16 v[12:15], v[144:147], v[196:199], v[12:15]
	v_mfma_f32_16x16x32_bf16 v[8:11], v[164:167], v[196:199], v[8:11]
	v_mfma_f32_16x16x32_bf16 v[4:7], v[144:147], v[204:207], v[4:7]
	v_mfma_f32_16x16x32_bf16 v[0:3], v[164:167], v[204:207], v[0:3]
	v_mfma_f32_16x16x32_bf16 v[28:31], v[148:151], v[180:183], v[28:31]
	v_mfma_f32_16x16x32_bf16 v[24:27], v[168:171], v[180:183], v[24:27]
	v_mfma_f32_16x16x32_bf16 v[20:23], v[148:151], v[192:195], v[20:23]
	v_mfma_f32_16x16x32_bf16 v[16:19], v[168:171], v[192:195], v[16:19]
	v_mfma_f32_16x16x32_bf16 v[12:15], v[148:151], v[200:203], v[12:15]
	v_mfma_f32_16x16x32_bf16 v[8:11], v[168:171], v[200:203], v[8:11]
	v_mfma_f32_16x16x32_bf16 v[4:7], v[148:151], v[208:211], v[4:7]
	v_mfma_f32_16x16x32_bf16 v[0:3], v[168:171], v[208:211], v[0:3]
	s_setprio 0
	s_barrier
	s_add_u32 s44, s44, 0x100
	s_addc_u32 s45, s45, 0
	s_add_u32 s55, s55, 0x100
	s_addc_u32 s82, s82, 0
	s_cmp_ge_u32 s83, s51
	s_mov_b32 s14, s83
	s_cbranch_scc0 .LBB0_528
	s_branch .Lpost_528
.LBB0_528:
	ds_read_b128 v[128:131], v177
	ds_read_b128 v[132:135], v177 offset:1024
	ds_read_b128 v[136:139], v177 offset:2048
	ds_read_b128 v[140:143], v177 offset:3072
	ds_read_b128 v[144:147], v178
	ds_read_b128 v[148:151], v178 offset:1024
	ds_read_b128 v[164:167], v178 offset:2048
	ds_read_b128 v[168:171], v178 offset:3072
	s_add_i32 s83, s14, 2
	s_add_u32 s15, s44, 0xfffc0080
	s_addc_u32 s46, s45, -1
	s_cmp_eq_u32 s54, s14
	s_cselect_b32 s14, s43, s55
	s_cselect_b32 s47, s3, s46
	s_cselect_b32 s46, s35, s15
	s_cselect_b32 s15, s37, s82
	v_lshl_add_u64 v[184:185], s[44:45], 0, v[160:161]
	s_add_i32 m0, s57, 0xc000
	ds_read_b128 v[172:175], v179
	ds_read_b128 v[180:183], v179 offset:1024
	ds_read_b128 v[188:191], v179 offset:2048
	ds_read_b128 v[192:195], v179 offset:3072
	ds_read_b128 v[196:199], v179 offset:4096
	ds_read_b128 v[200:203], v179 offset:5120
	ds_read_b128 v[204:207], v179 offset:6144
	ds_read_b128 v[208:211], v179 offset:7168
	global_load_lds_dwordx4 v[184:185], off
	v_lshl_add_u64 v[184:185], s[44:45], 0, v[162:163]
	s_add_i32 m0, s57, 0xe000
	s_nop 0
	global_load_lds_dwordx4 v[184:185], off
	s_waitcnt vmcnt(8)
	s_waitcnt lgkmcnt(0)
	s_barrier
; #define G_STAGE(bufoff, gbase, voff) do { _Pragma("unroll") for (int _i = 0; _i < 2; ++_i) \
;         __builtin_amdgcn_global_load_lds((const unsigned*)((const char*)(gbase) + voff[_i]), (LAS unsigned*)(lds + (bufoff) + ldsw + _i * 8192), 16, 0, 0); } while (0)
; #define G_LDA(dst, b, h) do { _Pragma("unroll") for (int m = 0; m < 4; ++m) _Pragma("unroll") for (int k = 0; k < 2; ++k) dst[m][k] = *(const LAS bf16x8*)(lds + G_SA(b, h) + aoff + m * 2048 + k * 1024); } while (0)
; #define G_MMA(ai, bj, At_, Bt_) do { __builtin_amdgcn_s_setprio(1); _Pragma("unroll") for (int m = 0; m < 4; ++m) _Pragma("unroll") for (int n = 0; n < 2; ++n) _Pragma("unroll") for (int k = 0; k < 2; ++k) \
;         acc[ai][bj][m][n] = __builtin_amdgcn_mfma_f32_16x16x32_bf16(Bt_[n][k], At_[m][k], acc[ai][bj][m][n], 0, 0, 0); __builtin_amdgcn_s_setprio(0); } while (0)
; #define WAIT_V(n) asm volatile("s_waitcnt vmcnt(" #n ")" ::: "memory")
; #define WAIT_L(n) asm volatile("s_waitcnt lgkmcnt(" #n ")" ::: "memory")
; #define BAR __builtin_amdgcn_s_barrier()
; #define SCHED __builtin_amdgcn_sched_barrier(0)
; template <class Get, class Epi>
; DI void gemm_loop(int ntiles, int ld, char* shm, const Get& get, const Epi& epi) {
;     ...
;             WAIT_V(8); WAIT_L(0); BAR; G_MMA(0, 0, At, B0); G_MMA(0, 1, At, B1); BAR; SCHED;
;             G_LDA(At, 0, 1); G_STAGE(G_SB(0, 0), b2, voffB); G_STAGE(G_SB(0, 1), b2 + hstep, voffB); G_STAGE(G_SA(0, 0), a2, voffA);
;             WAIT_V(8); WAIT_L(0); BAR; G_MMA(1, 0, At, B0); G_MMA(1, 1, At, B1); BAR; SCHED;
	s_setprio 1
	v_mfma_f32_16x16x32_bf16 v[124:127], v[128:131], v[172:175], v[124:127]
	v_mfma_f32_16x16x32_bf16 v[120:123], v[136:139], v[172:175], v[120:123]
	v_mfma_f32_16x16x32_bf16 v[116:119], v[128:131], v[188:191], v[116:119]
	v_mfma_f32_16x16x32_bf16 v[112:115], v[136:139], v[188:191], v[112:115]
	v_mfma_f32_16x16x32_bf16 v[108:111], v[128:131], v[196:199], v[108:111]
	v_mfma_f32_16x16x32_bf16 v[104:107], v[136:139], v[196:199], v[104:107]
	v_mfma_f32_16x16x32_bf16 v[100:103], v[128:131], v[204:207], v[100:103]
	v_mfma_f32_16x16x32_bf16 v[96:99], v[136:139], v[204:207], v[96:99]
	v_mfma_f32_16x16x32_bf16 v[124:127], v[132:135], v[180:183], v[124:127]
	v_mfma_f32_16x16x32_bf16 v[120:123], v[140:143], v[180:183], v[120:123]
	v_mfma_f32_16x16x32_bf16 v[116:119], v[132:135], v[192:195], v[116:119]
	v_mfma_f32_16x16x32_bf16 v[112:115], v[140:143], v[192:195], v[112:115]
	v_mfma_f32_16x16x32_bf16 v[108:111], v[132:135], v[200:203], v[108:111]
	v_mfma_f32_16x16x32_bf16 v[104:107], v[140:143], v[200:203], v[104:107]
	v_mfma_f32_16x16x32_bf16 v[100:103], v[132:135], v[208:211], v[100:103]
	v_mfma_f32_16x16x32_bf16 v[96:99], v[140:143], v[208:211], v[96:99]
	s_setprio 0
	s_setprio 1
	v_mfma_f32_16x16x32_bf16 v[60:63], v[144:147], v[172:175], v[60:63]
	v_mfma_f32_16x16x32_bf16 v[56:59], v[164:167], v[172:175], v[56:59]
	v_mfma_f32_16x16x32_bf16 v[52:55], v[144:147], v[188:191], v[52:55]
	v_mfma_f32_16x16x32_bf16 v[48:51], v[164:167], v[188:191], v[48:51]
	v_mfma_f32_16x16x32_bf16 v[44:47], v[144:147], v[196:199], v[44:47]
	v_mfma_f32_16x16x32_bf16 v[40:43], v[164:167], v[196:199], v[40:43]
	v_mfma_f32_16x16x32_bf16 v[36:39], v[144:147], v[204:207], v[36:39]
	v_mfma_f32_16x16x32_bf16 v[32:35], v[164:167], v[204:207], v[32:35]
	v_mfma_f32_16x16x32_bf16 v[60:63], v[148:151], v[180:183], v[60:63]
	v_mfma_f32_16x16x32_bf16 v[56:59], v[168:171], v[180:183], v[56:59]
	v_mfma_f32_16x16x32_bf16 v[52:55], v[148:151], v[192:195], v[52:55]
	v_mfma_f32_16x16x32_bf16 v[48:51], v[168:171], v[192:195], v[48:51]
	v_mfma_f32_16x16x32_bf16 v[44:47], v[148:151], v[200:203], v[44:47]
	v_mfma_f32_16x16x32_bf16 v[40:43], v[168:171], v[200:203], v[40:43]
	v_mfma_f32_16x16x32_bf16 v[36:39], v[148:151], v[208:211], v[36:39]
	v_mfma_f32_16x16x32_bf16 v[32:35], v[168:171], v[208:211], v[32:35]
	s_setprio 0
	s_barrier
	s_add_i32 s84, s78, s56
	v_lshl_add_u64 v[184:185], s[14:15], 0, v[154:155]
	s_mov_b32 m0, s84
	ds_read_b128 v[172:175], v179 offset:16384
	ds_read_b128 v[180:183], v179 offset:17408
	ds_read_b128 v[188:191], v179 offset:18432
	ds_read_b128 v[192:195], v179 offset:19456
	ds_read_b128 v[196:199], v179 offset:20480
	ds_read_b128 v[200:203], v179 offset:21504
	ds_read_b128 v[204:207], v179 offset:22528
	ds_read_b128 v[208:211], v179 offset:23552
	global_load_lds_dwordx4 v[184:185], off
	s_add_i32 m0, s84, 0x2000
	s_add_u32 s84, s14, 0x40000
	v_lshl_add_u64 v[186:187], s[14:15], 0, v[158:159]
	s_addc_u32 s85, s15, 0
	s_add_i32 s86, s79, s56
	global_load_lds_dwordx4 v[186:187], off
	v_lshl_add_u64 v[212:213], s[84:85], 0, v[154:155]
	s_mov_b32 m0, s86
	v_lshl_add_u64 v[214:215], s[46:47], 0, v[156:157]
	global_load_lds_dwordx4 v[212:213], off
	v_lshl_add_u64 v[212:213], s[84:85], 0, v[158:159]
	s_add_i32 m0, s86, 0x2000
	s_nop 0
	global_load_lds_dwordx4 v[212:213], off
	v_lshl_add_u64 v[212:213], s[46:47], 0, v[152:153]
	s_mov_b32 m0, s57
	s_nop 0
	global_load_lds_dwordx4 v[212:213], off
	s_mov_b32 m0, s58
	s_nop 0
	global_load_lds_dwordx4 v[214:215], off
	s_waitcnt vmcnt(8)
	s_waitcnt lgkmcnt(0)
	s_barrier
	s_setprio 1
	v_mfma_f32_16x16x32_bf16 v[92:95], v[128:131], v[172:175], v[92:95]
	v_mfma_f32_16x16x32_bf16 v[88:91], v[136:139], v[172:175], v[88:91]
	v_mfma_f32_16x16x32_bf16 v[84:87], v[128:131], v[188:191], v[84:87]
	v_mfma_f32_16x16x32_bf16 v[80:83], v[136:139], v[188:191], v[80:83]
	v_mfma_f32_16x16x32_bf16 v[76:79], v[128:131], v[196:199], v[76:79]
	v_mfma_f32_16x16x32_bf16 v[72:75], v[136:139], v[196:199], v[72:75]
	v_mfma_f32_16x16x32_bf16 v[68:71], v[128:131], v[204:207], v[68:71]
	v_mfma_f32_16x16x32_bf16 v[64:67], v[136:139], v[204:207], v[64:67]
	v_mfma_f32_16x16x32_bf16 v[92:95], v[132:135], v[180:183], v[92:95]
	v_mfma_f32_16x16x32_bf16 v[88:91], v[140:143], v[180:183], v[88:91]
	v_mfma_f32_16x16x32_bf16 v[84:87], v[132:135], v[192:195], v[84:87]
	v_mfma_f32_16x16x32_bf16 v[80:83], v[140:143], v[192:195], v[80:83]
	v_mfma_f32_16x16x32_bf16 v[76:79], v[132:135], v[200:203], v[76:79]
	v_mfma_f32_16x16x32_bf16 v[72:75], v[140:143], v[200:203], v[72:75]
	v_mfma_f32_16x16x32_bf16 v[68:71], v[132:135], v[208:211], v[68:71]
	v_mfma_f32_16x16x32_bf16 v[64:67], v[140:143], v[208:211], v[64:67]
	s_setprio 0
	s_setprio 1
	v_mfma_f32_16x16x32_bf16 v[28:31], v[144:147], v[172:175], v[28:31]
	v_mfma_f32_16x16x32_bf16 v[24:27], v[164:167], v[172:175], v[24:27]
	v_mfma_f32_16x16x32_bf16 v[20:23], v[144:147], v[188:191], v[20:23]
	v_mfma_f32_16x16x32_bf16 v[16:19], v[164:167], v[188:191], v[16:19]
	v_mfma_f32_16x16x32_bf16 v[12:15], v[144:147], v[196:199], v[12:15]
	v_mfma_f32_16x16x32_bf16 v[8:11], v[164:167], v[196:199], v[8:11]
	v_mfma_f32_16x16x32_bf16 v[4:7], v[144:147], v[204:207], v[4:7]
	v_mfma_f32_16x16x32_bf16 v[0:3], v[164:167], v[204:207], v[0:3]
	v_mfma_f32_16x16x32_bf16 v[28:31], v[148:151], v[180:183], v[28:31]
	v_mfma_f32_16x16x32_bf16 v[24:27], v[168:171], v[180:183], v[24:27]
	v_mfma_f32_16x16x32_bf16 v[20:23], v[148:151], v[192:195], v[20:23]
	v_mfma_f32_16x16x32_bf16 v[16:19], v[168:171], v[192:195], v[16:19]
	v_mfma_f32_16x16x32_bf16 v[12:15], v[148:151], v[200:203], v[12:15]
	v_mfma_f32_16x16x32_bf16 v[8:11], v[168:171], v[200:203], v[8:11]
	v_mfma_f32_16x16x32_bf16 v[4:7], v[148:151], v[208:211], v[4:7]
	v_mfma_f32_16x16x32_bf16 v[0:3], v[168:171], v[208:211], v[0:3]
	s_setprio 0
	s_barrier
; #define G_STAGE(bufoff, gbase, voff) do { _Pragma("unroll") for (int _i = 0; _i < 2; ++_i) \
;         __builtin_amdgcn_global_load_lds((const unsigned*)((const char*)(gbase) + voff[_i]), (LAS unsigned*)(lds + (bufoff) + ldsw + _i * 8192), 16, 0, 0); } while (0)
; #define G_LDA(dst, b, h) do { _Pragma("unroll") for (int m = 0; m < 4; ++m) _Pragma("unroll") for (int k = 0; k < 2; ++k) dst[m][k] = *(const LAS bf16x8*)(lds + G_SA(b, h) + aoff + m * 2048 + k * 1024); } while (0)
; #define G_LDB(dst, b, h) do { _Pragma("unroll") for (int n = 0; n < 2; ++n) _Pragma("unroll") for (int k = 0; k < 2; ++k) dst[n][k] = *(const LAS bf16x8*)(lds + G_SB(b, h) + boff + n * 2048 + k * 1024); } while (0)
; #define G_MMA(ai, bj, At_, Bt_) do { __builtin_amdgcn_s_setprio(1); _Pragma("unroll") for (int m = 0; m < 4; ++m) _Pragma("unroll") for (int n = 0; n < 2; ++n) _Pragma("unroll") for (int k = 0; k < 2; ++k) \
;         acc[ai][bj][m][n] = __builtin_amdgcn_mfma_f32_16x16x32_bf16(Bt_[n][k], At_[m][k], acc[ai][bj][m][n], 0, 0, 0); __builtin_amdgcn_s_setprio(0); } while (0)
; #define WAIT_V(n) asm volatile("s_waitcnt vmcnt(" #n ")" ::: "memory")
; #define WAIT_L(n) asm volatile("s_waitcnt lgkmcnt(" #n ")" ::: "memory")
; #define BAR __builtin_amdgcn_s_barrier()
; #define SCHED __builtin_amdgcn_sched_barrier(0)
; template <class Get, class Epi>
; DI void gemm_loop(int ntiles, int ld, char* shm, const Get& get, const Epi& epi) {
;     ...
;             G_LDB(B0, 1, 0); G_LDB(B1, 1, 1); SCHED; G_LDA(At, 1, 0); G_STAGE(G_SA(0, 1), a2 + hstep, voffA);
;             WAIT_V(8); WAIT_L(0); BAR; G_MMA(0, 0, At, B0); G_MMA(0, 1, At, B1); BAR; SCHED;
	s_add_i32 s84, 0, 0x18000
	s_add_i32 s85, 0, 0x1c000
	v_add_u32_e32 v140, s84, v176
	v_add_u32_e32 v168, s85, v176
	ds_read_b128 v[128:131], v140
	ds_read_b128 v[132:135], v140 offset:1024
	ds_read_b128 v[136:139], v140 offset:2048
	ds_read_b128 v[140:143], v140 offset:3072
	ds_read_b128 v[144:147], v168
	ds_read_b128 v[148:151], v168 offset:1024
	ds_read_b128 v[164:167], v168 offset:2048
	ds_read_b128 v[168:171], v168 offset:3072
	s_add_u32 s46, s46, 0x40000
	s_addc_u32 s47, s47, 0
	s_mov_b32 m0, s59
	v_lshl_add_u64 v[216:217], s[46:47], 0, v[152:153]
	ds_read_b128 v[172:175], v179 offset:32768
	ds_read_b128 v[180:183], v179 offset:33792
	ds_read_b128 v[188:191], v179 offset:34816
	ds_read_b128 v[192:195], v179 offset:35840
	ds_read_b128 v[196:199], v179 offset:36864
	ds_read_b128 v[200:203], v179 offset:37888
	ds_read_b128 v[204:207], v179 offset:38912
	ds_read_b128 v[208:211], v179 offset:39936
	global_load_lds_dwordx4 v[216:217], off
	v_lshl_add_u64 v[216:217], s[46:47], 0, v[156:157]
	s_mov_b32 m0, s72
	s_nop 0
	global_load_lds_dwordx4 v[216:217], off
	s_waitcnt vmcnt(8)
	s_waitcnt lgkmcnt(0)
	s_barrier
	s_setprio 1
	v_mfma_f32_16x16x32_bf16 v[124:127], v[128:131], v[172:175], v[124:127]
	v_mfma_f32_16x16x32_bf16 v[120:123], v[136:139], v[172:175], v[120:123]
	v_mfma_f32_16x16x32_bf16 v[116:119], v[128:131], v[188:191], v[116:119]
	v_mfma_f32_16x16x32_bf16 v[112:115], v[136:139], v[188:191], v[112:115]
	v_mfma_f32_16x16x32_bf16 v[108:111], v[128:131], v[196:199], v[108:111]
	v_mfma_f32_16x16x32_bf16 v[104:107], v[136:139], v[196:199], v[104:107]
	v_mfma_f32_16x16x32_bf16 v[100:103], v[128:131], v[204:207], v[100:103]
	v_mfma_f32_16x16x32_bf16 v[96:99], v[136:139], v[204:207], v[96:99]
	v_mfma_f32_16x16x32_bf16 v[124:127], v[132:135], v[180:183], v[124:127]
	v_mfma_f32_16x16x32_bf16 v[120:123], v[140:143], v[180:183], v[120:123]
	v_mfma_f32_16x16x32_bf16 v[116:119], v[132:135], v[192:195], v[116:119]
	v_mfma_f32_16x16x32_bf16 v[112:115], v[140:143], v[192:195], v[112:115]
	v_mfma_f32_16x16x32_bf16 v[108:111], v[132:135], v[200:203], v[108:111]
	v_mfma_f32_16x16x32_bf16 v[104:107], v[140:143], v[200:203], v[104:107]
	v_mfma_f32_16x16x32_bf16 v[100:103], v[132:135], v[208:211], v[100:103]
	v_mfma_f32_16x16x32_bf16 v[96:99], v[140:143], v[208:211], v[96:99]
	s_setprio 0
	s_setprio 1
	v_mfma_f32_16x16x32_bf16 v[60:63], v[144:147], v[172:175], v[60:63]
	v_mfma_f32_16x16x32_bf16 v[56:59], v[164:167], v[172:175], v[56:59]
	v_mfma_f32_16x16x32_bf16 v[52:55], v[144:147], v[188:191], v[52:55]
	v_mfma_f32_16x16x32_bf16 v[48:51], v[164:167], v[188:191], v[48:51]
	v_mfma_f32_16x16x32_bf16 v[44:47], v[144:147], v[196:199], v[44:47]
	v_mfma_f32_16x16x32_bf16 v[40:43], v[164:167], v[196:199], v[40:43]
	v_mfma_f32_16x16x32_bf16 v[36:39], v[144:147], v[204:207], v[36:39]
	v_mfma_f32_16x16x32_bf16 v[32:35], v[164:167], v[204:207], v[32:35]
	v_mfma_f32_16x16x32_bf16 v[60:63], v[148:151], v[180:183], v[60:63]
	v_mfma_f32_16x16x32_bf16 v[56:59], v[168:171], v[180:183], v[56:59]
	v_mfma_f32_16x16x32_bf16 v[52:55], v[148:151], v[192:195], v[52:55]
	v_mfma_f32_16x16x32_bf16 v[48:51], v[168:171], v[192:195], v[48:51]
	v_mfma_f32_16x16x32_bf16 v[44:47], v[148:151], v[200:203], v[44:47]
	v_mfma_f32_16x16x32_bf16 v[40:43], v[168:171], v[200:203], v[40:43]
	v_mfma_f32_16x16x32_bf16 v[36:39], v[148:151], v[208:211], v[36:39]
	v_mfma_f32_16x16x32_bf16 v[32:35], v[168:171], v[208:211], v[32:35]
	s_setprio 0
	s_barrier
; #define G_STAGE(bufoff, gbase, voff) do { _Pragma("unroll") for (int _i = 0; _i < 2; ++_i) \
;         __builtin_amdgcn_global_load_lds((const unsigned*)((const char*)(gbase) + voff[_i]), (LAS unsigned*)(lds + (bufoff) + ldsw + _i * 8192), 16, 0, 0); } while (0)
; #define G_LDA(dst, b, h) do { _Pragma("unroll") for (int m = 0; m < 4; ++m) _Pragma("unroll") for (int k = 0; k < 2; ++k) dst[m][k] = *(const LAS bf16x8*)(lds + G_SA(b, h) + aoff + m * 2048 + k * 1024); } while (0)
; #define G_MMA(ai, bj, At_, Bt_) do { __builtin_amdgcn_s_setprio(1); _Pragma("unroll") for (int m = 0; m < 4; ++m) _Pragma("unroll") for (int n = 0; n < 2; ++n) _Pragma("unroll") for (int k = 0; k < 2; ++k) \
;         acc[ai][bj][m][n] = __builtin_amdgcn_mfma_f32_16x16x32_bf16(Bt_[n][k], At_[m][k], acc[ai][bj][m][n], 0, 0, 0); __builtin_amdgcn_s_setprio(0); } while (0)
; #define WAIT_V(n) asm volatile("s_waitcnt vmcnt(" #n ")" ::: "memory")
; #define WAIT_L(n) asm volatile("s_waitcnt lgkmcnt(" #n ")" ::: "memory")
; #define BAR __builtin_amdgcn_s_barrier()
; #define SCHED __builtin_amdgcn_sched_barrier(0)
; template <class Get, class Epi>
; DI void gemm_loop(int ntiles, int ld, char* shm, const Get& get, const Epi& epi) {
;     ...
;         for (int t = 0; t < nt; t += 2) {
;             const bool last = (t == nt - 2);
;     ...
;             G_LDA(At, 1, 1); G_STAGE(G_SB(1, 0), b3, voffB); G_STAGE(G_SB(1, 1), b3 + hstep, voffB); G_STAGE(G_SA(1, 0), a3, voffA);
;             WAIT_V(8); WAIT_L(0); BAR; G_MMA(1, 0, At, B0); G_MMA(1, 1, At, B1); BAR; SCHED;
	s_add_i32 s46, s84, s56
	v_lshl_add_u64 v[184:185], v[184:185], 0, s[10:11]
	s_mov_b32 m0, s46
	ds_read_b128 v[172:175], v179 offset:49152
	ds_read_b128 v[180:183], v179 offset:50176
	ds_read_b128 v[188:191], v179 offset:51200
	ds_read_b128 v[192:195], v179 offset:52224
	ds_read_b128 v[196:199], v179 offset:53248
	ds_read_b128 v[200:203], v179 offset:54272
	ds_read_b128 v[204:207], v179 offset:55296
	ds_read_b128 v[208:211], v179 offset:56320
	global_load_lds_dwordx4 v[184:185], off
	s_add_i32 m0, s46, 0x2000
	s_add_u32 s14, s14, 0x40080
	v_lshl_add_u64 v[184:185], v[186:187], 0, s[10:11]
	s_addc_u32 s15, s15, 0
	s_add_i32 s46, s85, s56
	global_load_lds_dwordx4 v[184:185], off
	v_lshl_add_u64 v[184:185], s[14:15], 0, v[154:155]
	s_mov_b32 m0, s46
	s_nop 0
	global_load_lds_dwordx4 v[184:185], off
	v_lshl_add_u64 v[184:185], s[14:15], 0, v[158:159]
	s_add_i32 m0, s46, 0x2000
	s_nop 0
	global_load_lds_dwordx4 v[184:185], off
	v_lshl_add_u64 v[184:185], v[212:213], 0, s[10:11]
	s_mov_b32 m0, s75
	s_nop 0
	global_load_lds_dwordx4 v[184:185], off
	v_lshl_add_u64 v[184:185], v[214:215], 0, s[10:11]
	s_mov_b32 m0, s76
	s_nop 0
	global_load_lds_dwordx4 v[184:185], off
	s_waitcnt vmcnt(8)
	s_waitcnt lgkmcnt(0)
	s_barrier
	s_setprio 1
	v_mfma_f32_16x16x32_bf16 v[92:95], v[128:131], v[172:175], v[92:95]
	v_mfma_f32_16x16x32_bf16 v[88:91], v[136:139], v[172:175], v[88:91]
	v_mfma_f32_16x16x32_bf16 v[84:87], v[128:131], v[188:191], v[84:87]
	v_mfma_f32_16x16x32_bf16 v[80:83], v[136:139], v[188:191], v[80:83]
	v_mfma_f32_16x16x32_bf16 v[76:79], v[128:131], v[196:199], v[76:79]
	v_mfma_f32_16x16x32_bf16 v[72:75], v[136:139], v[196:199], v[72:75]
	v_mfma_f32_16x16x32_bf16 v[68:71], v[128:131], v[204:207], v[68:71]
	v_mfma_f32_16x16x32_bf16 v[64:67], v[136:139], v[204:207], v[64:67]
	v_mfma_f32_16x16x32_bf16 v[92:95], v[132:135], v[180:183], v[92:95]
	v_mfma_f32_16x16x32_bf16 v[88:91], v[140:143], v[180:183], v[88:91]
	v_mfma_f32_16x16x32_bf16 v[84:87], v[132:135], v[192:195], v[84:87]
	v_mfma_f32_16x16x32_bf16 v[80:83], v[140:143], v[192:195], v[80:83]
	v_mfma_f32_16x16x32_bf16 v[76:79], v[132:135], v[200:203], v[76:79]
	v_mfma_f32_16x16x32_bf16 v[72:75], v[140:143], v[200:203], v[72:75]
	v_mfma_f32_16x16x32_bf16 v[68:71], v[132:135], v[208:211], v[68:71]
	v_mfma_f32_16x16x32_bf16 v[64:67], v[140:143], v[208:211], v[64:67]
	s_setprio 0
	s_setprio 1
	v_mfma_f32_16x16x32_bf16 v[28:31], v[144:147], v[172:175], v[28:31]
	v_mfma_f32_16x16x32_bf16 v[24:27], v[164:167], v[172:175], v[24:27]
	v_mfma_f32_16x16x32_bf16 v[20:23], v[144:147], v[188:191], v[20:23]
	v_mfma_f32_16x16x32_bf16 v[16:19], v[164:167], v[188:191], v[16:19]
	v_mfma_f32_16x16x32_bf16 v[12:15], v[144:147], v[196:199], v[12:15]
	v_mfma_f32_16x16x32_bf16 v[8:11], v[164:167], v[196:199], v[8:11]
	v_mfma_f32_16x16x32_bf16 v[4:7], v[144:147], v[204:207], v[4:7]
	v_mfma_f32_16x16x32_bf16 v[0:3], v[164:167], v[204:207], v[0:3]
	v_mfma_f32_16x16x32_bf16 v[28:31], v[148:151], v[180:183], v[28:31]
	v_mfma_f32_16x16x32_bf16 v[24:27], v[168:171], v[180:183], v[24:27]
	v_mfma_f32_16x16x32_bf16 v[20:23], v[148:151], v[192:195], v[20:23]
	v_mfma_f32_16x16x32_bf16 v[16:19], v[168:171], v[192:195], v[16:19]
	v_mfma_f32_16x16x32_bf16 v[12:15], v[148:151], v[200:203], v[12:15]
	v_mfma_f32_16x16x32_bf16 v[8:11], v[168:171], v[200:203], v[8:11]
	v_mfma_f32_16x16x32_bf16 v[4:7], v[148:151], v[208:211], v[4:7]
	v_mfma_f32_16x16x32_bf16 v[0:3], v[168:171], v[208:211], v[0:3]
	s_setprio 0
	s_barrier
	s_add_u32 s44, s44, 0x100
	s_addc_u32 s45, s45, 0
	s_add_u32 s55, s55, 0x100
	s_addc_u32 s82, s82, 0
	s_cmp_ge_u32 s83, s51
	s_mov_b32 s14, s83
	s_cbranch_scc0 .LBB0_528

; #define G_STAGE(bufoff, gbase, voff) do { _Pragma("unroll") for (int _i = 0; _i < 2; ++_i) \
;         __builtin_amdgcn_global_load_lds((const unsigned*)((const char*)(gbase) + voff[_i]), (LAS unsigned*)(lds + (bufoff) + ldsw + _i * 8192), 16, 0, 0); } while (0)
; #define G_LDA(dst, b, h) do { _Pragma("unroll") for (int m = 0; m < 4; ++m) _Pragma("unroll") for (int k = 0; k < 2; ++k) dst[m][k] = *(const LAS bf16x8*)(lds + G_SA(b, h) + aoff + m * 2048 + k * 1024); } while (0)
; #define G_MMA(ai, bj, At_, Bt_) do { __builtin_amdgcn_s_setprio(1); _Pragma("unroll") for (int m = 0; m < 4; ++m) _Pragma("unroll") for (int n = 0; n < 2; ++n) _Pragma("unroll") for (int k = 0; k < 2; ++k) \
;         acc[ai][bj][m][n] = __builtin_amdgcn_mfma_f32_16x16x32_bf16(Bt_[n][k], At_[m][k], acc[ai][bj][m][n], 0, 0, 0); __builtin_amdgcn_s_setprio(0); } while (0)
; #define WAIT_V(n) asm volatile("s_waitcnt vmcnt(" #n ")" ::: "memory")
; #define WAIT_L(n) asm volatile("s_waitcnt lgkmcnt(" #n ")" ::: "memory")
; #define BAR __builtin_amdgcn_s_barrier()
; #define SCHED __builtin_amdgcn_sched_barrier(0)
; template <class Get, class Epi>
; DI void gemm_loop(int ntiles, int ld, char* shm, const Get& get, const Epi& epi) {
;     ...
;             WAIT_V(8); WAIT_L(0); BAR; G_MMA(0, 0, At, B0); G_MMA(0, 1, At, B1); BAR; SCHED;
;             G_LDA(At, 0, 1); G_STAGE(G_SB(0, 0), b2, voffB); G_STAGE(G_SB(0, 1), b2 + hstep, voffB); G_STAGE(G_SA(0, 0), a2, voffA);
.Lrj_763_0:
	s_waitcnt lgkmcnt(0)
	s_barrier
	s_setprio 1
	v_mfma_f32_16x16x32_bf16 v[124:127], v[144:147], v[176:179], 0
	v_mfma_f32_16x16x32_bf16 v[120:123], v[152:155], v[176:179], 0
	v_mfma_f32_16x16x32_bf16 v[108:111], v[144:147], v[188:191], 0
	v_mfma_f32_16x16x32_bf16 v[104:107], v[152:155], v[188:191], 0
	v_mfma_f32_16x16x32_bf16 v[92:95], v[144:147], v[196:199], 0
	v_mfma_f32_16x16x32_bf16 v[88:91], v[152:155], v[196:199], 0
	v_mfma_f32_16x16x32_bf16 v[76:79], v[144:147], v[204:207], 0
	v_mfma_f32_16x16x32_bf16 v[72:75], v[152:155], v[204:207], 0
	v_mfma_f32_16x16x32_bf16 v[124:127], v[148:151], v[180:183], v[124:127]
	v_mfma_f32_16x16x32_bf16 v[120:123], v[156:159], v[180:183], v[120:123]
	v_mfma_f32_16x16x32_bf16 v[108:111], v[148:151], v[192:195], v[108:111]
	v_mfma_f32_16x16x32_bf16 v[104:107], v[156:159], v[192:195], v[104:107]
	v_mfma_f32_16x16x32_bf16 v[92:95], v[148:151], v[200:203], v[92:95]
	v_mfma_f32_16x16x32_bf16 v[88:91], v[156:159], v[200:203], v[88:91]
	v_mfma_f32_16x16x32_bf16 v[76:79], v[148:151], v[208:211], v[76:79]
	v_mfma_f32_16x16x32_bf16 v[72:75], v[156:159], v[208:211], v[72:75]
	s_setprio 0
	s_setprio 1
	v_mfma_f32_16x16x32_bf16 v[116:119], v[160:163], v[176:179], 0
	v_mfma_f32_16x16x32_bf16 v[112:115], v[168:171], v[176:179], 0
	v_mfma_f32_16x16x32_bf16 v[100:103], v[160:163], v[188:191], 0
	v_mfma_f32_16x16x32_bf16 v[96:99], v[168:171], v[188:191], 0
	v_mfma_f32_16x16x32_bf16 v[84:87], v[160:163], v[196:199], 0
	v_mfma_f32_16x16x32_bf16 v[80:83], v[168:171], v[196:199], 0
	v_mfma_f32_16x16x32_bf16 v[68:71], v[160:163], v[204:207], 0
	v_mfma_f32_16x16x32_bf16 v[64:67], v[168:171], v[204:207], 0
	v_mfma_f32_16x16x32_bf16 v[116:119], v[164:167], v[180:183], v[116:119]
	v_mfma_f32_16x16x32_bf16 v[112:115], v[172:175], v[180:183], v[112:115]
	v_mfma_f32_16x16x32_bf16 v[100:103], v[164:167], v[192:195], v[100:103]
	v_mfma_f32_16x16x32_bf16 v[96:99], v[172:175], v[192:195], v[96:99]
	v_mfma_f32_16x16x32_bf16 v[84:87], v[164:167], v[200:203], v[84:87]
	v_mfma_f32_16x16x32_bf16 v[80:83], v[172:175], v[200:203], v[80:83]
	v_mfma_f32_16x16x32_bf16 v[68:71], v[164:167], v[208:211], v[68:71]
	v_mfma_f32_16x16x32_bf16 v[64:67], v[172:175], v[208:211], v[64:67]
	s_setprio 0
	s_barrier
	s_add_i32 s55, s45, s26
	v_lshl_add_u64 v[184:185], s[14:15], 0, v[132:133]
	s_mov_b32 m0, s55
	ds_read_b128 v[176:179], v143 offset:16384
	ds_read_b128 v[180:183], v143 offset:17408
	ds_read_b128 v[188:191], v143 offset:18432
	ds_read_b128 v[192:195], v143 offset:19456
	ds_read_b128 v[196:199], v143 offset:20480
	ds_read_b128 v[200:203], v143 offset:21504
	ds_read_b128 v[204:207], v143 offset:22528
	ds_read_b128 v[208:211], v143 offset:23552
	global_load_lds_dwordx4 v[184:185], off
	s_add_i32 m0, s55, 0x2000
	s_add_u32 s56, s14, 0x40000
	v_lshl_add_u64 v[186:187], s[14:15], 0, v[128:129]
	s_addc_u32 s57, s15, 0
	s_add_i32 s55, s46, s26
	global_load_lds_dwordx4 v[186:187], off
	v_lshl_add_u64 v[212:213], s[56:57], 0, v[132:133]
	s_mov_b32 m0, s55
	v_lshl_add_u64 v[214:215], s[38:39], 0, v[130:131]
	global_load_lds_dwordx4 v[212:213], off
	v_lshl_add_u64 v[212:213], s[56:57], 0, v[128:129]
	s_add_i32 m0, s55, 0x2000
	s_nop 0
	global_load_lds_dwordx4 v[212:213], off
	v_lshl_add_u64 v[212:213], s[38:39], 0, v[134:135]
	s_mov_b32 m0, s31
	s_nop 0
	global_load_lds_dwordx4 v[212:213], off
	s_mov_b32 m0, s35
	s_nop 0
	global_load_lds_dwordx4 v[214:215], off
	s_cmp_lg_u32 s100, 0
	s_cbranch_scc0 .Lrf_763_1
	s_waitcnt vmcnt(16)
	s_branch .Lrj_763_1

; #define G_STAGE(bufoff, gbase, voff) do { _Pragma("unroll") for (int _i = 0; _i < 2; ++_i) \
;         __builtin_amdgcn_global_load_lds((const unsigned*)((const char*)(gbase) + voff[_i]), (LAS unsigned*)(lds + (bufoff) + ldsw + _i * 8192), 16, 0, 0); } while (0)
; #define G_LDA(dst, b, h) do { _Pragma("unroll") for (int m = 0; m < 4; ++m) _Pragma("unroll") for (int k = 0; k < 2; ++k) dst[m][k] = *(const LAS bf16x8*)(lds + G_SA(b, h) + aoff + m * 2048 + k * 1024); } while (0)
; #define G_LDB(dst, b, h) do { _Pragma("unroll") for (int n = 0; n < 2; ++n) _Pragma("unroll") for (int k = 0; k < 2; ++k) dst[n][k] = *(const LAS bf16x8*)(lds + G_SB(b, h) + boff + n * 2048 + k * 1024); } while (0)
; #define G_MMA(ai, bj, At_, Bt_) do { __builtin_amdgcn_s_setprio(1); _Pragma("unroll") for (int m = 0; m < 4; ++m) _Pragma("unroll") for (int n = 0; n < 2; ++n) _Pragma("unroll") for (int k = 0; k < 2; ++k) \
;         acc[ai][bj][m][n] = __builtin_amdgcn_mfma_f32_16x16x32_bf16(Bt_[n][k], At_[m][k], acc[ai][bj][m][n], 0, 0, 0); __builtin_amdgcn_s_setprio(0); } while (0)
; #define WAIT_V(n) asm volatile("s_waitcnt vmcnt(" #n ")" ::: "memory")
; #define WAIT_L(n) asm volatile("s_waitcnt lgkmcnt(" #n ")" ::: "memory")
; #define BAR __builtin_amdgcn_s_barrier()
; #define SCHED __builtin_amdgcn_sched_barrier(0)
; template <class Get, class Epi>
; DI void gemm_loop(int ntiles, int ld, char* shm, const Get& get, const Epi& epi) {
;     ...
;             WAIT_V(8); WAIT_L(0); BAR; G_MMA(1, 0, At, B0); G_MMA(1, 1, At, B1); BAR; SCHED;
;             G_LDB(B0, 1, 0); G_LDB(B1, 1, 1); SCHED; G_LDA(At, 1, 0); G_STAGE(G_SA(0, 1), a2 + hstep, voffA);
;             WAIT_V(8); WAIT_L(0); BAR; G_MMA(0, 0, At, B0); G_MMA(0, 1, At, B1); BAR; SCHED;
.Lrj_763_1:
	s_waitcnt lgkmcnt(0)
	s_barrier
	s_setprio 1
	v_mfma_f32_16x16x32_bf16 v[60:63], v[144:147], v[176:179], 0
	v_mfma_f32_16x16x32_bf16 v[56:59], v[152:155], v[176:179], 0
	v_mfma_f32_16x16x32_bf16 v[44:47], v[144:147], v[188:191], 0
	v_mfma_f32_16x16x32_bf16 v[40:43], v[152:155], v[188:191], 0
	v_mfma_f32_16x16x32_bf16 v[28:31], v[144:147], v[196:199], 0
	v_mfma_f32_16x16x32_bf16 v[24:27], v[152:155], v[196:199], 0
	v_mfma_f32_16x16x32_bf16 v[12:15], v[144:147], v[204:207], 0
	v_mfma_f32_16x16x32_bf16 v[8:11], v[152:155], v[204:207], 0
	v_mfma_f32_16x16x32_bf16 v[60:63], v[148:151], v[180:183], v[60:63]
	v_mfma_f32_16x16x32_bf16 v[56:59], v[156:159], v[180:183], v[56:59]
	v_mfma_f32_16x16x32_bf16 v[44:47], v[148:151], v[192:195], v[44:47]
	v_mfma_f32_16x16x32_bf16 v[40:43], v[156:159], v[192:195], v[40:43]
	v_mfma_f32_16x16x32_bf16 v[28:31], v[148:151], v[200:203], v[28:31]
	v_mfma_f32_16x16x32_bf16 v[24:27], v[156:159], v[200:203], v[24:27]
	v_mfma_f32_16x16x32_bf16 v[12:15], v[148:151], v[208:211], v[12:15]
	v_mfma_f32_16x16x32_bf16 v[8:11], v[156:159], v[208:211], v[8:11]
	s_setprio 0
	s_setprio 1
	v_mfma_f32_16x16x32_bf16 v[52:55], v[160:163], v[176:179], 0
	v_mfma_f32_16x16x32_bf16 v[48:51], v[168:171], v[176:179], 0
	v_mfma_f32_16x16x32_bf16 v[36:39], v[160:163], v[188:191], 0
	v_mfma_f32_16x16x32_bf16 v[32:35], v[168:171], v[188:191], 0
	v_mfma_f32_16x16x32_bf16 v[20:23], v[160:163], v[196:199], 0
	v_mfma_f32_16x16x32_bf16 v[16:19], v[168:171], v[196:199], 0
	v_mfma_f32_16x16x32_bf16 v[4:7], v[160:163], v[204:207], 0
	v_mfma_f32_16x16x32_bf16 v[0:3], v[168:171], v[204:207], 0
	v_mfma_f32_16x16x32_bf16 v[52:55], v[164:167], v[180:183], v[52:55]
	v_mfma_f32_16x16x32_bf16 v[48:51], v[172:175], v[180:183], v[48:51]
	v_mfma_f32_16x16x32_bf16 v[36:39], v[164:167], v[192:195], v[36:39]
	v_mfma_f32_16x16x32_bf16 v[32:35], v[172:175], v[192:195], v[32:35]
	v_mfma_f32_16x16x32_bf16 v[20:23], v[164:167], v[200:203], v[20:23]
	v_mfma_f32_16x16x32_bf16 v[16:19], v[172:175], v[200:203], v[16:19]
	v_mfma_f32_16x16x32_bf16 v[4:7], v[164:167], v[208:211], v[4:7]
	v_mfma_f32_16x16x32_bf16 v[0:3], v[172:175], v[208:211], v[0:3]
	s_setprio 0
	s_barrier
	s_add_i32 s55, 0, 0x18000
	s_add_i32 s56, 0, 0x1c000
	v_add_u32_e32 v156, s55, v140
	v_add_u32_e32 v172, s56, v140
	ds_read_b128 v[144:147], v156
	ds_read_b128 v[148:151], v156 offset:1024
	ds_read_b128 v[152:155], v156 offset:2048
	ds_read_b128 v[156:159], v156 offset:3072
	ds_read_b128 v[160:163], v172
	ds_read_b128 v[164:167], v172 offset:1024
	ds_read_b128 v[168:171], v172 offset:2048
	ds_read_b128 v[172:175], v172 offset:3072
	s_add_u32 s38, s38, 0x40000
	s_addc_u32 s39, s39, 0
	s_mov_b32 m0, s41
	v_lshl_add_u64 v[216:217], s[38:39], 0, v[134:135]
	ds_read_b128 v[176:179], v143 offset:32768
	ds_read_b128 v[180:183], v143 offset:33792
	ds_read_b128 v[188:191], v143 offset:34816
	ds_read_b128 v[192:195], v143 offset:35840
	ds_read_b128 v[196:199], v143 offset:36864
	ds_read_b128 v[200:203], v143 offset:37888
	ds_read_b128 v[204:207], v143 offset:38912
	ds_read_b128 v[208:211], v143 offset:39936
	global_load_lds_dwordx4 v[216:217], off
	v_lshl_add_u64 v[216:217], s[38:39], 0, v[130:131]
	s_mov_b32 m0, s42
	s_nop 0
	global_load_lds_dwordx4 v[216:217], off
	s_waitcnt vmcnt(8)
	s_waitcnt lgkmcnt(0)
	s_barrier
	s_setprio 1
	v_mfma_f32_16x16x32_bf16 v[124:127], v[144:147], v[176:179], v[124:127]
	v_mfma_f32_16x16x32_bf16 v[120:123], v[152:155], v[176:179], v[120:123]
	v_mfma_f32_16x16x32_bf16 v[108:111], v[144:147], v[188:191], v[108:111]
	v_mfma_f32_16x16x32_bf16 v[104:107], v[152:155], v[188:191], v[104:107]
	v_mfma_f32_16x16x32_bf16 v[92:95], v[144:147], v[196:199], v[92:95]
	v_mfma_f32_16x16x32_bf16 v[88:91], v[152:155], v[196:199], v[88:91]
	v_mfma_f32_16x16x32_bf16 v[76:79], v[144:147], v[204:207], v[76:79]
	v_mfma_f32_16x16x32_bf16 v[72:75], v[152:155], v[204:207], v[72:75]
	v_mfma_f32_16x16x32_bf16 v[124:127], v[148:151], v[180:183], v[124:127]
	v_mfma_f32_16x16x32_bf16 v[120:123], v[156:159], v[180:183], v[120:123]
	v_mfma_f32_16x16x32_bf16 v[108:111], v[148:151], v[192:195], v[108:111]
	v_mfma_f32_16x16x32_bf16 v[104:107], v[156:159], v[192:195], v[104:107]
	v_mfma_f32_16x16x32_bf16 v[92:95], v[148:151], v[200:203], v[92:95]
	v_mfma_f32_16x16x32_bf16 v[88:91], v[156:159], v[200:203], v[88:91]
	v_mfma_f32_16x16x32_bf16 v[76:79], v[148:151], v[208:211], v[76:79]
	v_mfma_f32_16x16x32_bf16 v[72:75], v[156:159], v[208:211], v[72:75]
	s_setprio 0
	s_setprio 1
	v_mfma_f32_16x16x32_bf16 v[116:119], v[160:163], v[176:179], v[116:119]
	v_mfma_f32_16x16x32_bf16 v[112:115], v[168:171], v[176:179], v[112:115]
	v_mfma_f32_16x16x32_bf16 v[100:103], v[160:163], v[188:191], v[100:103]
	v_mfma_f32_16x16x32_bf16 v[96:99], v[168:171], v[188:191], v[96:99]
	v_mfma_f32_16x16x32_bf16 v[84:87], v[160:163], v[196:199], v[84:87]
	v_mfma_f32_16x16x32_bf16 v[80:83], v[168:171], v[196:199], v[80:83]
	v_mfma_f32_16x16x32_bf16 v[68:71], v[160:163], v[204:207], v[68:71]
	v_mfma_f32_16x16x32_bf16 v[64:67], v[168:171], v[204:207], v[64:67]
	v_mfma_f32_16x16x32_bf16 v[116:119], v[164:167], v[180:183], v[116:119]
	v_mfma_f32_16x16x32_bf16 v[112:115], v[172:175], v[180:183], v[112:115]
	v_mfma_f32_16x16x32_bf16 v[100:103], v[164:167], v[192:195], v[100:103]
	v_mfma_f32_16x16x32_bf16 v[96:99], v[172:175], v[192:195], v[96:99]
	v_mfma_f32_16x16x32_bf16 v[84:87], v[164:167], v[200:203], v[84:87]
	v_mfma_f32_16x16x32_bf16 v[80:83], v[172:175], v[200:203], v[80:83]
	v_mfma_f32_16x16x32_bf16 v[68:71], v[164:167], v[208:211], v[68:71]
	v_mfma_f32_16x16x32_bf16 v[64:67], v[172:175], v[208:211], v[64:67]
	s_setprio 0
	s_barrier
; #define G_STAGE(bufoff, gbase, voff) do { _Pragma("unroll") for (int _i = 0; _i < 2; ++_i) \
;         __builtin_amdgcn_global_load_lds((const unsigned*)((const char*)(gbase) + voff[_i]), (LAS unsigned*)(lds + (bufoff) + ldsw + _i * 8192), 16, 0, 0); } while (0)
; #define G_LDA(dst, b, h) do { _Pragma("unroll") for (int m = 0; m < 4; ++m) _Pragma("unroll") for (int k = 0; k < 2; ++k) dst[m][k] = *(const LAS bf16x8*)(lds + G_SA(b, h) + aoff + m * 2048 + k * 1024); } while (0)
; #define G_LDB(dst, b, h) do { _Pragma("unroll") for (int n = 0; n < 2; ++n) _Pragma("unroll") for (int k = 0; k < 2; ++k) dst[n][k] = *(const LAS bf16x8*)(lds + G_SB(b, h) + boff + n * 2048 + k * 1024); } while (0)
; #define G_MMA(ai, bj, At_, Bt_) do { __builtin_amdgcn_s_setprio(1); _Pragma("unroll") for (int m = 0; m < 4; ++m) _Pragma("unroll") for (int n = 0; n < 2; ++n) _Pragma("unroll") for (int k = 0; k < 2; ++k) \
;         acc[ai][bj][m][n] = __builtin_amdgcn_mfma_f32_16x16x32_bf16(Bt_[n][k], At_[m][k], acc[ai][bj][m][n], 0, 0, 0); __builtin_amdgcn_s_setprio(0); } while (0)
; #define WAIT_V(n) asm volatile("s_waitcnt vmcnt(" #n ")" ::: "memory")
; #define WAIT_L(n) asm volatile("s_waitcnt lgkmcnt(" #n ")" ::: "memory")
; #define BAR __builtin_amdgcn_s_barrier()
; #define SCHED __builtin_amdgcn_sched_barrier(0)
; template <class Get, class Epi>
; DI void gemm_loop(int ntiles, int ld, char* shm, const Get& get, const Epi& epi) {
;     ...
;         for (int t = 0; t < nt; t += 2) {
;             const bool last = (t == nt - 2);
;             const char* a1 = cA + (size_t)(t + 1) * kstep;
;             const char* a2 = last ? nA : cA + (size_t)(t + 2) * kstep; const char* b2 = last ? nB : cB + (size_t)(t + 2) * kstep;
;             const char* a3 = a2 + kstep; const char* b3 = b2 + kstep;
;             G_LDB(B0, 0, 0); G_LDB(B1, 0, 1); SCHED; G_LDA(At, 0, 0); G_STAGE(G_SA(1, 1), a1 + hstep, voffA);
;     ...
;             G_LDA(At, 1, 1); G_STAGE(G_SB(1, 0), b3, voffB); G_STAGE(G_SB(1, 1), b3 + hstep, voffB); G_STAGE(G_SA(1, 0), a3, voffA);
;             WAIT_V(8); WAIT_L(0); BAR; G_MMA(1, 0, At, B0); G_MMA(1, 1, At, B1); BAR; SCHED;
	s_add_i32 s38, s55, s26
	v_lshl_add_u64 v[184:185], v[184:185], 0, s[2:3]
	s_mov_b32 m0, s38
	ds_read_b128 v[176:179], v143 offset:49152
	ds_read_b128 v[180:183], v143 offset:50176
	ds_read_b128 v[188:191], v143 offset:51200
	ds_read_b128 v[192:195], v143 offset:52224
	ds_read_b128 v[196:199], v143 offset:53248
	ds_read_b128 v[200:203], v143 offset:54272
	ds_read_b128 v[204:207], v143 offset:55296
	ds_read_b128 v[208:211], v143 offset:56320
	global_load_lds_dwordx4 v[184:185], off
	s_add_i32 m0, s38, 0x2000
	s_add_u32 s14, s14, 0x40080
	v_lshl_add_u64 v[184:185], v[186:187], 0, s[2:3]
	s_addc_u32 s15, s15, 0
	s_add_i32 s38, s56, s26
	global_load_lds_dwordx4 v[184:185], off
	v_lshl_add_u64 v[184:185], s[14:15], 0, v[132:133]
	s_mov_b32 m0, s38
	s_nop 0
	global_load_lds_dwordx4 v[184:185], off
	v_lshl_add_u64 v[184:185], s[14:15], 0, v[128:129]
	s_add_i32 m0, s38, 0x2000
	s_nop 0
	global_load_lds_dwordx4 v[184:185], off
	v_lshl_add_u64 v[184:185], v[212:213], 0, s[2:3]
	s_mov_b32 m0, s43
	s_nop 0
	global_load_lds_dwordx4 v[184:185], off
	v_lshl_add_u64 v[184:185], v[214:215], 0, s[2:3]
	s_mov_b32 m0, s44
	s_nop 0
	global_load_lds_dwordx4 v[184:185], off
	s_waitcnt vmcnt(8)
	s_waitcnt lgkmcnt(0)
	s_barrier
	s_setprio 1
	v_mfma_f32_16x16x32_bf16 v[60:63], v[144:147], v[176:179], v[60:63]
	v_mfma_f32_16x16x32_bf16 v[56:59], v[152:155], v[176:179], v[56:59]
	v_mfma_f32_16x16x32_bf16 v[44:47], v[144:147], v[188:191], v[44:47]
	v_mfma_f32_16x16x32_bf16 v[40:43], v[152:155], v[188:191], v[40:43]
	v_mfma_f32_16x16x32_bf16 v[28:31], v[144:147], v[196:199], v[28:31]
	v_mfma_f32_16x16x32_bf16 v[24:27], v[152:155], v[196:199], v[24:27]
	v_mfma_f32_16x16x32_bf16 v[12:15], v[144:147], v[204:207], v[12:15]
	v_mfma_f32_16x16x32_bf16 v[8:11], v[152:155], v[204:207], v[8:11]
	v_mfma_f32_16x16x32_bf16 v[60:63], v[148:151], v[180:183], v[60:63]
	v_mfma_f32_16x16x32_bf16 v[56:59], v[156:159], v[180:183], v[56:59]
	v_mfma_f32_16x16x32_bf16 v[44:47], v[148:151], v[192:195], v[44:47]
	v_mfma_f32_16x16x32_bf16 v[40:43], v[156:159], v[192:195], v[40:43]
	v_mfma_f32_16x16x32_bf16 v[28:31], v[148:151], v[200:203], v[28:31]
	v_mfma_f32_16x16x32_bf16 v[24:27], v[156:159], v[200:203], v[24:27]
	v_mfma_f32_16x16x32_bf16 v[12:15], v[148:151], v[208:211], v[12:15]
	v_mfma_f32_16x16x32_bf16 v[8:11], v[156:159], v[208:211], v[8:11]
	s_setprio 0
	s_setprio 1
	v_mfma_f32_16x16x32_bf16 v[52:55], v[160:163], v[176:179], v[52:55]
	v_mfma_f32_16x16x32_bf16 v[48:51], v[168:171], v[176:179], v[48:51]
	v_mfma_f32_16x16x32_bf16 v[36:39], v[160:163], v[188:191], v[36:39]
	v_mfma_f32_16x16x32_bf16 v[32:35], v[168:171], v[188:191], v[32:35]
	v_mfma_f32_16x16x32_bf16 v[20:23], v[160:163], v[196:199], v[20:23]
	v_mfma_f32_16x16x32_bf16 v[16:19], v[168:171], v[196:199], v[16:19]
	v_mfma_f32_16x16x32_bf16 v[4:7], v[160:163], v[204:207], v[4:7]
	v_mfma_f32_16x16x32_bf16 v[0:3], v[168:171], v[204:207], v[0:3]
	v_mfma_f32_16x16x32_bf16 v[52:55], v[164:167], v[180:183], v[52:55]
	v_mfma_f32_16x16x32_bf16 v[48:51], v[172:175], v[180:183], v[48:51]
	v_mfma_f32_16x16x32_bf16 v[36:39], v[164:167], v[192:195], v[36:39]
	v_mfma_f32_16x16x32_bf16 v[32:35], v[172:175], v[192:195], v[32:35]
	v_mfma_f32_16x16x32_bf16 v[20:23], v[164:167], v[200:203], v[20:23]
	v_mfma_f32_16x16x32_bf16 v[16:19], v[172:175], v[200:203], v[16:19]
	v_mfma_f32_16x16x32_bf16 v[4:7], v[164:167], v[208:211], v[4:7]
	v_mfma_f32_16x16x32_bf16 v[0:3], v[172:175], v[208:211], v[0:3]
	s_setprio 0
	s_barrier
	s_add_i32 s54, s54, 2
	s_add_u32 s36, s36, 0x100
	s_addc_u32 s37, s37, 0
	s_add_u32 s52, s52, 0x100
	s_addc_u32 s53, s53, 0
	s_cmp_gt_u32 s54, 13
	s_cbranch_scc0 .LBB0_763
	s_branch .Lpost_763
.LBB0_763:
	ds_read_b128 v[144:147], v141
	ds_read_b128 v[148:151], v141 offset:1024
	ds_read_b128 v[152:155], v141 offset:2048
	ds_read_b128 v[156:159], v141 offset:3072
	ds_read_b128 v[160:163], v142
	ds_read_b128 v[164:167], v142 offset:1024
	ds_read_b128 v[168:171], v142 offset:2048
	ds_read_b128 v[172:175], v142 offset:3072
	s_add_u32 s14, s36, 0xfffc0080
	s_addc_u32 s15, s37, -1
	s_cmp_eq_u32 s54, 12
	s_cselect_b32 s39, s9, s15
	s_cselect_b32 s38, s50, s14
	s_cselect_b32 s15, s11, s53
	s_cselect_b32 s14, s51, s52
	v_lshl_add_u64 v[184:185], s[36:37], 0, v[136:137]
	s_add_i32 m0, s31, 0xc000
	ds_read_b128 v[176:179], v143
	ds_read_b128 v[180:183], v143 offset:1024
	ds_read_b128 v[188:191], v143 offset:2048
	ds_read_b128 v[192:195], v143 offset:3072
	ds_read_b128 v[196:199], v143 offset:4096
	ds_read_b128 v[200:203], v143 offset:5120
	ds_read_b128 v[204:207], v143 offset:6144
	ds_read_b128 v[208:211], v143 offset:7168
	global_load_lds_dwordx4 v[184:185], off
	v_lshl_add_u64 v[184:185], s[36:37], 0, v[138:139]
	s_add_i32 m0, s31, 0xe000
	s_nop 0
	global_load_lds_dwordx4 v[184:185], off
	s_waitcnt vmcnt(8)
	s_waitcnt lgkmcnt(0)
	s_barrier
; #define G_STAGE(bufoff, gbase, voff) do { _Pragma("unroll") for (int _i = 0; _i < 2; ++_i) \
;         __builtin_amdgcn_global_load_lds((const unsigned*)((const char*)(gbase) + voff[_i]), (LAS unsigned*)(lds + (bufoff) + ldsw + _i * 8192), 16, 0, 0); } while (0)
; #define G_LDA(dst, b, h) do { _Pragma("unroll") for (int m = 0; m < 4; ++m) _Pragma("unroll") for (int k = 0; k < 2; ++k) dst[m][k] = *(const LAS bf16x8*)(lds + G_SA(b, h) + aoff + m * 2048 + k * 1024); } while (0)
; #define G_MMA(ai, bj, At_, Bt_) do { __builtin_amdgcn_s_setprio(1); _Pragma("unroll") for (int m = 0; m < 4; ++m) _Pragma("unroll") for (int n = 0; n < 2; ++n) _Pragma("unroll") for (int k = 0; k < 2; ++k) \
;         acc[ai][bj][m][n] = __builtin_amdgcn_mfma_f32_16x16x32_bf16(Bt_[n][k], At_[m][k], acc[ai][bj][m][n], 0, 0, 0); __builtin_amdgcn_s_setprio(0); } while (0)
; #define WAIT_V(n) asm volatile("s_waitcnt vmcnt(" #n ")" ::: "memory")
; #define WAIT_L(n) asm volatile("s_waitcnt lgkmcnt(" #n ")" ::: "memory")
; #define BAR __builtin_amdgcn_s_barrier()
; #define SCHED __builtin_amdgcn_sched_barrier(0)
; template <class Get, class Epi>
; DI void gemm_loop(int ntiles, int ld, char* shm, const Get& get, const Epi& epi) {
;     ...
;             WAIT_V(8); WAIT_L(0); BAR; G_MMA(0, 0, At, B0); G_MMA(0, 1, At, B1); BAR; SCHED;
;             G_LDA(At, 0, 1); G_STAGE(G_SB(0, 0), b2, voffB); G_STAGE(G_SB(0, 1), b2 + hstep, voffB); G_STAGE(G_SA(0, 0), a2, voffA);
;             WAIT_V(8); WAIT_L(0); BAR; G_MMA(1, 0, At, B0); G_MMA(1, 1, At, B1); BAR; SCHED;
	s_setprio 1
	v_mfma_f32_16x16x32_bf16 v[124:127], v[144:147], v[176:179], v[124:127]
	v_mfma_f32_16x16x32_bf16 v[120:123], v[152:155], v[176:179], v[120:123]
	v_mfma_f32_16x16x32_bf16 v[108:111], v[144:147], v[188:191], v[108:111]
	v_mfma_f32_16x16x32_bf16 v[104:107], v[152:155], v[188:191], v[104:107]
	v_mfma_f32_16x16x32_bf16 v[92:95], v[144:147], v[196:199], v[92:95]
	v_mfma_f32_16x16x32_bf16 v[88:91], v[152:155], v[196:199], v[88:91]
	v_mfma_f32_16x16x32_bf16 v[76:79], v[144:147], v[204:207], v[76:79]
	v_mfma_f32_16x16x32_bf16 v[72:75], v[152:155], v[204:207], v[72:75]
	v_mfma_f32_16x16x32_bf16 v[124:127], v[148:151], v[180:183], v[124:127]
	v_mfma_f32_16x16x32_bf16 v[120:123], v[156:159], v[180:183], v[120:123]
	v_mfma_f32_16x16x32_bf16 v[108:111], v[148:151], v[192:195], v[108:111]
	v_mfma_f32_16x16x32_bf16 v[104:107], v[156:159], v[192:195], v[104:107]
	v_mfma_f32_16x16x32_bf16 v[92:95], v[148:151], v[200:203], v[92:95]
	v_mfma_f32_16x16x32_bf16 v[88:91], v[156:159], v[200:203], v[88:91]
	v_mfma_f32_16x16x32_bf16 v[76:79], v[148:151], v[208:211], v[76:79]
	v_mfma_f32_16x16x32_bf16 v[72:75], v[156:159], v[208:211], v[72:75]
	s_setprio 0
	s_setprio 1
	v_mfma_f32_16x16x32_bf16 v[116:119], v[160:163], v[176:179], v[116:119]
	v_mfma_f32_16x16x32_bf16 v[112:115], v[168:171], v[176:179], v[112:115]
	v_mfma_f32_16x16x32_bf16 v[100:103], v[160:163], v[188:191], v[100:103]
	v_mfma_f32_16x16x32_bf16 v[96:99], v[168:171], v[188:191], v[96:99]
	v_mfma_f32_16x16x32_bf16 v[84:87], v[160:163], v[196:199], v[84:87]
	v_mfma_f32_16x16x32_bf16 v[80:83], v[168:171], v[196:199], v[80:83]
	v_mfma_f32_16x16x32_bf16 v[68:71], v[160:163], v[204:207], v[68:71]
	v_mfma_f32_16x16x32_bf16 v[64:67], v[168:171], v[204:207], v[64:67]
	v_mfma_f32_16x16x32_bf16 v[116:119], v[164:167], v[180:183], v[116:119]
	v_mfma_f32_16x16x32_bf16 v[112:115], v[172:175], v[180:183], v[112:115]
	v_mfma_f32_16x16x32_bf16 v[100:103], v[164:167], v[192:195], v[100:103]
	v_mfma_f32_16x16x32_bf16 v[96:99], v[172:175], v[192:195], v[96:99]
	v_mfma_f32_16x16x32_bf16 v[84:87], v[164:167], v[200:203], v[84:87]
	v_mfma_f32_16x16x32_bf16 v[80:83], v[172:175], v[200:203], v[80:83]
	v_mfma_f32_16x16x32_bf16 v[68:71], v[164:167], v[208:211], v[68:71]
	v_mfma_f32_16x16x32_bf16 v[64:67], v[172:175], v[208:211], v[64:67]
	s_setprio 0
	s_barrier
	s_add_i32 s55, s45, s26
	v_lshl_add_u64 v[184:185], s[14:15], 0, v[132:133]
	s_mov_b32 m0, s55
	ds_read_b128 v[176:179], v143 offset:16384
	ds_read_b128 v[180:183], v143 offset:17408
	ds_read_b128 v[188:191], v143 offset:18432
	ds_read_b128 v[192:195], v143 offset:19456
	ds_read_b128 v[196:199], v143 offset:20480
	ds_read_b128 v[200:203], v143 offset:21504
	ds_read_b128 v[204:207], v143 offset:22528
	ds_read_b128 v[208:211], v143 offset:23552
	global_load_lds_dwordx4 v[184:185], off
	s_add_i32 m0, s55, 0x2000
	s_add_u32 s56, s14, 0x40000
	v_lshl_add_u64 v[186:187], s[14:15], 0, v[128:129]
	s_addc_u32 s57, s15, 0
	s_add_i32 s55, s46, s26
	global_load_lds_dwordx4 v[186:187], off
	v_lshl_add_u64 v[212:213], s[56:57], 0, v[132:133]
	s_mov_b32 m0, s55
	v_lshl_add_u64 v[214:215], s[38:39], 0, v[130:131]
	global_load_lds_dwordx4 v[212:213], off
	v_lshl_add_u64 v[212:213], s[56:57], 0, v[128:129]
	s_add_i32 m0, s55, 0x2000
	s_nop 0
	global_load_lds_dwordx4 v[212:213], off
	v_lshl_add_u64 v[212:213], s[38:39], 0, v[134:135]
	s_mov_b32 m0, s31
	s_nop 0
	global_load_lds_dwordx4 v[212:213], off
	s_mov_b32 m0, s35
	s_nop 0
	global_load_lds_dwordx4 v[214:215], off
	s_waitcnt vmcnt(8)
	s_waitcnt lgkmcnt(0)
	s_barrier
	s_setprio 1
	v_mfma_f32_16x16x32_bf16 v[60:63], v[144:147], v[176:179], v[60:63]
	v_mfma_f32_16x16x32_bf16 v[56:59], v[152:155], v[176:179], v[56:59]
	v_mfma_f32_16x16x32_bf16 v[44:47], v[144:147], v[188:191], v[44:47]
	v_mfma_f32_16x16x32_bf16 v[40:43], v[152:155], v[188:191], v[40:43]
	v_mfma_f32_16x16x32_bf16 v[28:31], v[144:147], v[196:199], v[28:31]
	v_mfma_f32_16x16x32_bf16 v[24:27], v[152:155], v[196:199], v[24:27]
	v_mfma_f32_16x16x32_bf16 v[12:15], v[144:147], v[204:207], v[12:15]
	v_mfma_f32_16x16x32_bf16 v[8:11], v[152:155], v[204:207], v[8:11]
	v_mfma_f32_16x16x32_bf16 v[60:63], v[148:151], v[180:183], v[60:63]
	v_mfma_f32_16x16x32_bf16 v[56:59], v[156:159], v[180:183], v[56:59]
	v_mfma_f32_16x16x32_bf16 v[44:47], v[148:151], v[192:195], v[44:47]
	v_mfma_f32_16x16x32_bf16 v[40:43], v[156:159], v[192:195], v[40:43]
	v_mfma_f32_16x16x32_bf16 v[28:31], v[148:151], v[200:203], v[28:31]
	v_mfma_f32_16x16x32_bf16 v[24:27], v[156:159], v[200:203], v[24:27]
	v_mfma_f32_16x16x32_bf16 v[12:15], v[148:151], v[208:211], v[12:15]
	v_mfma_f32_16x16x32_bf16 v[8:11], v[156:159], v[208:211], v[8:11]
	s_setprio 0
	s_setprio 1
	v_mfma_f32_16x16x32_bf16 v[52:55], v[160:163], v[176:179], v[52:55]
	v_mfma_f32_16x16x32_bf16 v[48:51], v[168:171], v[176:179], v[48:51]
	v_mfma_f32_16x16x32_bf16 v[36:39], v[160:163], v[188:191], v[36:39]
	v_mfma_f32_16x16x32_bf16 v[32:35], v[168:171], v[188:191], v[32:35]
	v_mfma_f32_16x16x32_bf16 v[20:23], v[160:163], v[196:199], v[20:23]
	v_mfma_f32_16x16x32_bf16 v[16:19], v[168:171], v[196:199], v[16:19]
	v_mfma_f32_16x16x32_bf16 v[4:7], v[160:163], v[204:207], v[4:7]
	v_mfma_f32_16x16x32_bf16 v[0:3], v[168:171], v[204:207], v[0:3]
	v_mfma_f32_16x16x32_bf16 v[52:55], v[164:167], v[180:183], v[52:55]
	v_mfma_f32_16x16x32_bf16 v[48:51], v[172:175], v[180:183], v[48:51]
	v_mfma_f32_16x16x32_bf16 v[36:39], v[164:167], v[192:195], v[36:39]
	v_mfma_f32_16x16x32_bf16 v[32:35], v[172:175], v[192:195], v[32:35]
	v_mfma_f32_16x16x32_bf16 v[20:23], v[164:167], v[200:203], v[20:23]
	v_mfma_f32_16x16x32_bf16 v[16:19], v[172:175], v[200:203], v[16:19]
	v_mfma_f32_16x16x32_bf16 v[4:7], v[164:167], v[208:211], v[4:7]
	v_mfma_f32_16x16x32_bf16 v[0:3], v[172:175], v[208:211], v[0:3]
	s_setprio 0
	s_barrier
; #define G_STAGE(bufoff, gbase, voff) do { _Pragma("unroll") for (int _i = 0; _i < 2; ++_i) \
;         __builtin_amdgcn_global_load_lds((const unsigned*)((const char*)(gbase) + voff[_i]), (LAS unsigned*)(lds + (bufoff) + ldsw + _i * 8192), 16, 0, 0); } while (0)
; #define G_LDA(dst, b, h) do { _Pragma("unroll") for (int m = 0; m < 4; ++m) _Pragma("unroll") for (int k = 0; k < 2; ++k) dst[m][k] = *(const LAS bf16x8*)(lds + G_SA(b, h) + aoff + m * 2048 + k * 1024); } while (0)
; #define G_LDB(dst, b, h) do { _Pragma("unroll") for (int n = 0; n < 2; ++n) _Pragma("unroll") for (int k = 0; k < 2; ++k) dst[n][k] = *(const LAS bf16x8*)(lds + G_SB(b, h) + boff + n * 2048 + k * 1024); } while (0)
; #define G_MMA(ai, bj, At_, Bt_) do { __builtin_amdgcn_s_setprio(1); _Pragma("unroll") for (int m = 0; m < 4; ++m) _Pragma("unroll") for (int n = 0; n < 2; ++n) _Pragma("unroll") for (int k = 0; k < 2; ++k) \
;         acc[ai][bj][m][n] = __builtin_amdgcn_mfma_f32_16x16x32_bf16(Bt_[n][k], At_[m][k], acc[ai][bj][m][n], 0, 0, 0); __builtin_amdgcn_s_setprio(0); } while (0)
; #define WAIT_V(n) asm volatile("s_waitcnt vmcnt(" #n ")" ::: "memory")
; #define WAIT_L(n) asm volatile("s_waitcnt lgkmcnt(" #n ")" ::: "memory")
; #define BAR __builtin_amdgcn_s_barrier()
; #define SCHED __builtin_amdgcn_sched_barrier(0)
; template <class Get, class Epi>
; DI void gemm_loop(int ntiles, int ld, char* shm, const Get& get, const Epi& epi) {
;     ...
;             G_LDB(B0, 1, 0); G_LDB(B1, 1, 1); SCHED; G_LDA(At, 1, 0); G_STAGE(G_SA(0, 1), a2 + hstep, voffA);
;             WAIT_V(8); WAIT_L(0); BAR; G_MMA(0, 0, At, B0); G_MMA(0, 1, At, B1); BAR; SCHED;
	s_add_i32 s55, 0, 0x18000
	s_add_i32 s56, 0, 0x1c000
	v_add_u32_e32 v156, s55, v140
	v_add_u32_e32 v172, s56, v140
	ds_read_b128 v[144:147], v156
	ds_read_b128 v[148:151], v156 offset:1024
	ds_read_b128 v[152:155], v156 offset:2048
	ds_read_b128 v[156:159], v156 offset:3072
	ds_read_b128 v[160:163], v172
	ds_read_b128 v[164:167], v172 offset:1024
	ds_read_b128 v[168:171], v172 offset:2048
	ds_read_b128 v[172:175], v172 offset:3072
	s_add_u32 s38, s38, 0x40000
	s_addc_u32 s39, s39, 0
	s_mov_b32 m0, s41
	v_lshl_add_u64 v[216:217], s[38:39], 0, v[134:135]
	ds_read_b128 v[176:179], v143 offset:32768
	ds_read_b128 v[180:183], v143 offset:33792
	ds_read_b128 v[188:191], v143 offset:34816
	ds_read_b128 v[192:195], v143 offset:35840
	ds_read_b128 v[196:199], v143 offset:36864
	ds_read_b128 v[200:203], v143 offset:37888
	ds_read_b128 v[204:207], v143 offset:38912
	ds_read_b128 v[208:211], v143 offset:39936
	global_load_lds_dwordx4 v[216:217], off
	v_lshl_add_u64 v[216:217], s[38:39], 0, v[130:131]
	s_mov_b32 m0, s42
	s_nop 0
	global_load_lds_dwordx4 v[216:217], off
	s_waitcnt vmcnt(8)
	s_waitcnt lgkmcnt(0)
	s_barrier
	s_setprio 1
	v_mfma_f32_16x16x32_bf16 v[124:127], v[144:147], v[176:179], v[124:127]
	v_mfma_f32_16x16x32_bf16 v[120:123], v[152:155], v[176:179], v[120:123]
	v_mfma_f32_16x16x32_bf16 v[108:111], v[144:147], v[188:191], v[108:111]
	v_mfma_f32_16x16x32_bf16 v[104:107], v[152:155], v[188:191], v[104:107]
	v_mfma_f32_16x16x32_bf16 v[92:95], v[144:147], v[196:199], v[92:95]
	v_mfma_f32_16x16x32_bf16 v[88:91], v[152:155], v[196:199], v[88:91]
	v_mfma_f32_16x16x32_bf16 v[76:79], v[144:147], v[204:207], v[76:79]
	v_mfma_f32_16x16x32_bf16 v[72:75], v[152:155], v[204:207], v[72:75]
	v_mfma_f32_16x16x32_bf16 v[124:127], v[148:151], v[180:183], v[124:127]
	v_mfma_f32_16x16x32_bf16 v[120:123], v[156:159], v[180:183], v[120:123]
	v_mfma_f32_16x16x32_bf16 v[108:111], v[148:151], v[192:195], v[108:111]
	v_mfma_f32_16x16x32_bf16 v[104:107], v[156:159], v[192:195], v[104:107]
	v_mfma_f32_16x16x32_bf16 v[92:95], v[148:151], v[200:203], v[92:95]
	v_mfma_f32_16x16x32_bf16 v[88:91], v[156:159], v[200:203], v[88:91]
	v_mfma_f32_16x16x32_bf16 v[76:79], v[148:151], v[208:211], v[76:79]
	v_mfma_f32_16x16x32_bf16 v[72:75], v[156:159], v[208:211], v[72:75]
	s_setprio 0
	s_setprio 1
	v_mfma_f32_16x16x32_bf16 v[116:119], v[160:163], v[176:179], v[116:119]
	v_mfma_f32_16x16x32_bf16 v[112:115], v[168:171], v[176:179], v[112:115]
	v_mfma_f32_16x16x32_bf16 v[100:103], v[160:163], v[188:191], v[100:103]
	v_mfma_f32_16x16x32_bf16 v[96:99], v[168:171], v[188:191], v[96:99]
	v_mfma_f32_16x16x32_bf16 v[84:87], v[160:163], v[196:199], v[84:87]
	v_mfma_f32_16x16x32_bf16 v[80:83], v[168:171], v[196:199], v[80:83]
	v_mfma_f32_16x16x32_bf16 v[68:71], v[160:163], v[204:207], v[68:71]
	v_mfma_f32_16x16x32_bf16 v[64:67], v[168:171], v[204:207], v[64:67]
	v_mfma_f32_16x16x32_bf16 v[116:119], v[164:167], v[180:183], v[116:119]
	v_mfma_f32_16x16x32_bf16 v[112:115], v[172:175], v[180:183], v[112:115]
	v_mfma_f32_16x16x32_bf16 v[100:103], v[164:167], v[192:195], v[100:103]
	v_mfma_f32_16x16x32_bf16 v[96:99], v[172:175], v[192:195], v[96:99]
	v_mfma_f32_16x16x32_bf16 v[84:87], v[164:167], v[200:203], v[84:87]
	v_mfma_f32_16x16x32_bf16 v[80:83], v[172:175], v[200:203], v[80:83]
	v_mfma_f32_16x16x32_bf16 v[68:71], v[164:167], v[208:211], v[68:71]
	v_mfma_f32_16x16x32_bf16 v[64:67], v[172:175], v[208:211], v[64:67]
	s_setprio 0
	s_barrier
; #define G_STAGE(bufoff, gbase, voff) do { _Pragma("unroll") for (int _i = 0; _i < 2; ++_i) \
;         __builtin_amdgcn_global_load_lds((const unsigned*)((const char*)(gbase) + voff[_i]), (LAS unsigned*)(lds + (bufoff) + ldsw + _i * 8192), 16, 0, 0); } while (0)
; #define G_LDA(dst, b, h) do { _Pragma("unroll") for (int m = 0; m < 4; ++m) _Pragma("unroll") for (int k = 0; k < 2; ++k) dst[m][k] = *(const LAS bf16x8*)(lds + G_SA(b, h) + aoff + m * 2048 + k * 1024); } while (0)
; #define G_MMA(ai, bj, At_, Bt_) do { __builtin_amdgcn_s_setprio(1); _Pragma("unroll") for (int m = 0; m < 4; ++m) _Pragma("unroll") for (int n = 0; n < 2; ++n) _Pragma("unroll") for (int k = 0; k < 2; ++k) \
;         acc[ai][bj][m][n] = __builtin_amdgcn_mfma_f32_16x16x32_bf16(Bt_[n][k], At_[m][k], acc[ai][bj][m][n], 0, 0, 0); __builtin_amdgcn_s_setprio(0); } while (0)
; #define WAIT_V(n) asm volatile("s_waitcnt vmcnt(" #n ")" ::: "memory")
; #define WAIT_L(n) asm volatile("s_waitcnt lgkmcnt(" #n ")" ::: "memory")
; #define BAR __builtin_amdgcn_s_barrier()
; #define SCHED __builtin_amdgcn_sched_barrier(0)
; template <class Get, class Epi>
; DI void gemm_loop(int ntiles, int ld, char* shm, const Get& get, const Epi& epi) {
;     ...
;         for (int t = 0; t < nt; t += 2) {
;             const bool last = (t == nt - 2);
;     ...
;             G_LDA(At, 1, 1); G_STAGE(G_SB(1, 0), b3, voffB); G_STAGE(G_SB(1, 1), b3 + hstep, voffB); G_STAGE(G_SA(1, 0), a3, voffA);
;             WAIT_V(8); WAIT_L(0); BAR; G_MMA(1, 0, At, B0); G_MMA(1, 1, At, B1); BAR; SCHED;
	s_add_i32 s38, s55, s26
	v_lshl_add_u64 v[184:185], v[184:185], 0, s[2:3]
	s_mov_b32 m0, s38
	ds_read_b128 v[176:179], v143 offset:49152
	ds_read_b128 v[180:183], v143 offset:50176
	ds_read_b128 v[188:191], v143 offset:51200
	ds_read_b128 v[192:195], v143 offset:52224
	ds_read_b128 v[196:199], v143 offset:53248
	ds_read_b128 v[200:203], v143 offset:54272
	ds_read_b128 v[204:207], v143 offset:55296
	ds_read_b128 v[208:211], v143 offset:56320
	global_load_lds_dwordx4 v[184:185], off
	s_add_i32 m0, s38, 0x2000
	s_add_u32 s14, s14, 0x40080
	v_lshl_add_u64 v[184:185], v[186:187], 0, s[2:3]
	s_addc_u32 s15, s15, 0
	s_add_i32 s38, s56, s26
	global_load_lds_dwordx4 v[184:185], off
	v_lshl_add_u64 v[184:185], s[14:15], 0, v[132:133]
	s_mov_b32 m0, s38
	s_nop 0
	global_load_lds_dwordx4 v[184:185], off
	v_lshl_add_u64 v[184:185], s[14:15], 0, v[128:129]
	s_add_i32 m0, s38, 0x2000
	s_nop 0
	global_load_lds_dwordx4 v[184:185], off
	v_lshl_add_u64 v[184:185], v[212:213], 0, s[2:3]
	s_mov_b32 m0, s43
	s_nop 0
	global_load_lds_dwordx4 v[184:185], off
	v_lshl_add_u64 v[184:185], v[214:215], 0, s[2:3]
	s_mov_b32 m0, s44
	s_nop 0
	global_load_lds_dwordx4 v[184:185], off
	s_waitcnt vmcnt(8)
	s_waitcnt lgkmcnt(0)
	s_barrier
	s_setprio 1
	v_mfma_f32_16x16x32_bf16 v[60:63], v[144:147], v[176:179], v[60:63]
	v_mfma_f32_16x16x32_bf16 v[56:59], v[152:155], v[176:179], v[56:59]
	v_mfma_f32_16x16x32_bf16 v[44:47], v[144:147], v[188:191], v[44:47]
	v_mfma_f32_16x16x32_bf16 v[40:43], v[152:155], v[188:191], v[40:43]
	v_mfma_f32_16x16x32_bf16 v[28:31], v[144:147], v[196:199], v[28:31]
	v_mfma_f32_16x16x32_bf16 v[24:27], v[152:155], v[196:199], v[24:27]
	v_mfma_f32_16x16x32_bf16 v[12:15], v[144:147], v[204:207], v[12:15]
	v_mfma_f32_16x16x32_bf16 v[8:11], v[152:155], v[204:207], v[8:11]
	v_mfma_f32_16x16x32_bf16 v[60:63], v[148:151], v[180:183], v[60:63]
	v_mfma_f32_16x16x32_bf16 v[56:59], v[156:159], v[180:183], v[56:59]
	v_mfma_f32_16x16x32_bf16 v[44:47], v[148:151], v[192:195], v[44:47]
	v_mfma_f32_16x16x32_bf16 v[40:43], v[156:159], v[192:195], v[40:43]
	v_mfma_f32_16x16x32_bf16 v[28:31], v[148:151], v[200:203], v[28:31]
	v_mfma_f32_16x16x32_bf16 v[24:27], v[156:159], v[200:203], v[24:27]
	v_mfma_f32_16x16x32_bf16 v[12:15], v[148:151], v[208:211], v[12:15]
	v_mfma_f32_16x16x32_bf16 v[8:11], v[156:159], v[208:211], v[8:11]
	s_setprio 0
	s_setprio 1
	v_mfma_f32_16x16x32_bf16 v[52:55], v[160:163], v[176:179], v[52:55]
	v_mfma_f32_16x16x32_bf16 v[48:51], v[168:171], v[176:179], v[48:51]
	v_mfma_f32_16x16x32_bf16 v[36:39], v[160:163], v[188:191], v[36:39]
	v_mfma_f32_16x16x32_bf16 v[32:35], v[168:171], v[188:191], v[32:35]
	v_mfma_f32_16x16x32_bf16 v[20:23], v[160:163], v[196:199], v[20:23]
	v_mfma_f32_16x16x32_bf16 v[16:19], v[168:171], v[196:199], v[16:19]
	v_mfma_f32_16x16x32_bf16 v[4:7], v[160:163], v[204:207], v[4:7]
	v_mfma_f32_16x16x32_bf16 v[0:3], v[168:171], v[204:207], v[0:3]
	v_mfma_f32_16x16x32_bf16 v[52:55], v[164:167], v[180:183], v[52:55]
	v_mfma_f32_16x16x32_bf16 v[48:51], v[172:175], v[180:183], v[48:51]
	v_mfma_f32_16x16x32_bf16 v[36:39], v[164:167], v[192:195], v[36:39]
	v_mfma_f32_16x16x32_bf16 v[32:35], v[172:175], v[192:195], v[32:35]
	v_mfma_f32_16x16x32_bf16 v[20:23], v[164:167], v[200:203], v[20:23]
	v_mfma_f32_16x16x32_bf16 v[16:19], v[172:175], v[200:203], v[16:19]
	v_mfma_f32_16x16x32_bf16 v[4:7], v[164:167], v[208:211], v[4:7]
	v_mfma_f32_16x16x32_bf16 v[0:3], v[172:175], v[208:211], v[0:3]
	s_setprio 0
	s_barrier
	s_add_i32 s54, s54, 2
	s_add_u32 s36, s36, 0x100
	s_addc_u32 s37, s37, 0
	s_add_u32 s52, s52, 0x100
	s_addc_u32 s53, s53, 0
	s_cmp_gt_u32 s54, 13
	s_cbranch_scc0 .LBB0_763

; #define G_STAGE(bufoff, gbase, voff) do { _Pragma("unroll") for (int _i = 0; _i < 2; ++_i) \
;         __builtin_amdgcn_global_load_lds((const unsigned*)((const char*)(gbase) + voff[_i]), (LAS unsigned*)(lds + (bufoff) + ldsw + _i * 8192), 16, 0, 0); } while (0)
; #define G_LDA(dst, b, h) do { _Pragma("unroll") for (int m = 0; m < 4; ++m) _Pragma("unroll") for (int k = 0; k < 2; ++k) dst[m][k] = *(const LAS bf16x8*)(lds + G_SA(b, h) + aoff + m * 2048 + k * 1024); } while (0)
; #define G_MMA(ai, bj, At_, Bt_) do { __builtin_amdgcn_s_setprio(1); _Pragma("unroll") for (int m = 0; m < 4; ++m) _Pragma("unroll") for (int n = 0; n < 2; ++n) _Pragma("unroll") for (int k = 0; k < 2; ++k) \
;         acc[ai][bj][m][n] = __builtin_amdgcn_mfma_f32_16x16x32_bf16(Bt_[n][k], At_[m][k], acc[ai][bj][m][n], 0, 0, 0); __builtin_amdgcn_s_setprio(0); } while (0)
; #define WAIT_V(n) asm volatile("s_waitcnt vmcnt(" #n ")" ::: "memory")
; #define WAIT_L(n) asm volatile("s_waitcnt lgkmcnt(" #n ")" ::: "memory")
; #define BAR __builtin_amdgcn_s_barrier()
; #define SCHED __builtin_amdgcn_sched_barrier(0)
; template <class Get, class Epi>
; DI void gemm_loop(int ntiles, int ld, char* shm, const Get& get, const Epi& epi) {
;     ...
;             WAIT_V(8); WAIT_L(0); BAR; G_MMA(0, 0, At, B0); G_MMA(0, 1, At, B1); BAR; SCHED;
;             G_LDA(At, 0, 1); G_STAGE(G_SB(0, 0), b2, voffB); G_STAGE(G_SB(0, 1), b2 + hstep, voffB); G_STAGE(G_SA(0, 0), a2, voffA);
.Lrj_850_0:
	s_waitcnt lgkmcnt(0)
	s_barrier
	s_setprio 1
	v_mfma_f32_16x16x32_bf16 v[124:127], v[128:131], v[180:183], 0
	v_mfma_f32_16x16x32_bf16 v[120:123], v[136:139], v[180:183], 0
	v_mfma_f32_16x16x32_bf16 v[116:119], v[128:131], v[192:195], 0
	v_mfma_f32_16x16x32_bf16 v[112:115], v[136:139], v[192:195], 0
	v_mfma_f32_16x16x32_bf16 v[108:111], v[128:131], v[200:203], 0
	v_mfma_f32_16x16x32_bf16 v[104:107], v[136:139], v[200:203], 0
	v_mfma_f32_16x16x32_bf16 v[100:103], v[128:131], v[208:211], 0
	v_mfma_f32_16x16x32_bf16 v[96:99], v[136:139], v[208:211], 0
	v_mfma_f32_16x16x32_bf16 v[124:127], v[132:135], v[188:191], v[124:127]
	v_mfma_f32_16x16x32_bf16 v[120:123], v[140:143], v[188:191], v[120:123]
	v_mfma_f32_16x16x32_bf16 v[116:119], v[132:135], v[196:199], v[116:119]
	v_mfma_f32_16x16x32_bf16 v[112:115], v[140:143], v[196:199], v[112:115]
	v_mfma_f32_16x16x32_bf16 v[108:111], v[132:135], v[204:207], v[108:111]
	v_mfma_f32_16x16x32_bf16 v[104:107], v[140:143], v[204:207], v[104:107]
	v_mfma_f32_16x16x32_bf16 v[100:103], v[132:135], v[212:215], v[100:103]
	v_mfma_f32_16x16x32_bf16 v[96:99], v[140:143], v[212:215], v[96:99]
	s_setprio 0
	s_setprio 1
	v_mfma_f32_16x16x32_bf16 v[60:63], v[158:161], v[180:183], 0
	v_mfma_f32_16x16x32_bf16 v[56:59], v[172:175], v[180:183], 0
	v_mfma_f32_16x16x32_bf16 v[52:55], v[158:161], v[192:195], 0
	v_mfma_f32_16x16x32_bf16 v[48:51], v[172:175], v[192:195], 0
	v_mfma_f32_16x16x32_bf16 v[44:47], v[158:161], v[200:203], 0
	v_mfma_f32_16x16x32_bf16 v[40:43], v[172:175], v[200:203], 0
	v_mfma_f32_16x16x32_bf16 v[36:39], v[158:161], v[208:211], 0
	v_mfma_f32_16x16x32_bf16 v[32:35], v[172:175], v[208:211], 0
	v_mfma_f32_16x16x32_bf16 v[60:63], v[162:165], v[188:191], v[60:63]
	v_mfma_f32_16x16x32_bf16 v[56:59], v[176:179], v[188:191], v[56:59]
	v_mfma_f32_16x16x32_bf16 v[52:55], v[162:165], v[196:199], v[52:55]
	v_mfma_f32_16x16x32_bf16 v[48:51], v[176:179], v[196:199], v[48:51]
	v_mfma_f32_16x16x32_bf16 v[44:47], v[162:165], v[204:207], v[44:47]
	v_mfma_f32_16x16x32_bf16 v[40:43], v[176:179], v[204:207], v[40:43]
	v_mfma_f32_16x16x32_bf16 v[36:39], v[162:165], v[212:215], v[36:39]
	v_mfma_f32_16x16x32_bf16 v[32:35], v[176:179], v[212:215], v[32:35]
	s_setprio 0
	s_barrier
	s_add_i32 s4, s50, s26
	v_lshl_add_u64 v[144:145], s[38:39], 0, v[148:149]
	s_mov_b32 m0, s4
	ds_read_b128 v[180:183], v171 offset:16384
	ds_read_b128 v[188:191], v171 offset:17408
	ds_read_b128 v[192:195], v171 offset:18432
	ds_read_b128 v[196:199], v171 offset:19456
	ds_read_b128 v[200:203], v171 offset:20480
	ds_read_b128 v[204:207], v171 offset:21504
	ds_read_b128 v[208:211], v171 offset:22528
	ds_read_b128 v[212:215], v171 offset:23552
	global_load_lds_dwordx4 v[144:145], off
	s_add_i32 m0, s4, 0x2000
	s_add_u32 s4, s38, 0xb0000
	v_lshl_add_u64 v[166:167], s[38:39], 0, v[152:153]
	s_addc_u32 s5, s39, 0
	s_add_i32 s76, s51, s26
	global_load_lds_dwordx4 v[166:167], off
	v_lshl_add_u64 v[184:185], s[4:5], 0, v[148:149]
	s_mov_b32 m0, s76
	v_lshl_add_u64 v[186:187], s[40:41], 0, v[150:151]
	global_load_lds_dwordx4 v[184:185], off
	v_lshl_add_u64 v[184:185], s[4:5], 0, v[152:153]
	s_add_i32 m0, s76, 0x2000
	s_nop 0
	global_load_lds_dwordx4 v[184:185], off
	v_lshl_add_u64 v[184:185], s[40:41], 0, v[146:147]
	s_mov_b32 m0, s42
	s_nop 0
	global_load_lds_dwordx4 v[184:185], off
	s_mov_b32 m0, s43
	s_nop 0
	global_load_lds_dwordx4 v[186:187], off
	s_cmp_lg_u32 s100, 0
	s_cbranch_scc0 .Lrf_850_1
	s_waitcnt vmcnt(16)
	s_branch .Lrj_850_1

; #define G_STAGE(bufoff, gbase, voff) do { _Pragma("unroll") for (int _i = 0; _i < 2; ++_i) \
;         __builtin_amdgcn_global_load_lds((const unsigned*)((const char*)(gbase) + voff[_i]), (LAS unsigned*)(lds + (bufoff) + ldsw + _i * 8192), 16, 0, 0); } while (0)
; #define G_LDA(dst, b, h) do { _Pragma("unroll") for (int m = 0; m < 4; ++m) _Pragma("unroll") for (int k = 0; k < 2; ++k) dst[m][k] = *(const LAS bf16x8*)(lds + G_SA(b, h) + aoff + m * 2048 + k * 1024); } while (0)
; #define G_LDB(dst, b, h) do { _Pragma("unroll") for (int n = 0; n < 2; ++n) _Pragma("unroll") for (int k = 0; k < 2; ++k) dst[n][k] = *(const LAS bf16x8*)(lds + G_SB(b, h) + boff + n * 2048 + k * 1024); } while (0)
; #define G_MMA(ai, bj, At_, Bt_) do { __builtin_amdgcn_s_setprio(1); _Pragma("unroll") for (int m = 0; m < 4; ++m) _Pragma("unroll") for (int n = 0; n < 2; ++n) _Pragma("unroll") for (int k = 0; k < 2; ++k) \
;         acc[ai][bj][m][n] = __builtin_amdgcn_mfma_f32_16x16x32_bf16(Bt_[n][k], At_[m][k], acc[ai][bj][m][n], 0, 0, 0); __builtin_amdgcn_s_setprio(0); } while (0)
; #define WAIT_V(n) asm volatile("s_waitcnt vmcnt(" #n ")" ::: "memory")
; #define WAIT_L(n) asm volatile("s_waitcnt lgkmcnt(" #n ")" ::: "memory")
; #define BAR __builtin_amdgcn_s_barrier()
; #define SCHED __builtin_amdgcn_sched_barrier(0)
; template <class Get, class Epi>
; DI void gemm_loop(int ntiles, int ld, char* shm, const Get& get, const Epi& epi) {
;     ...
;             WAIT_V(8); WAIT_L(0); BAR; G_MMA(1, 0, At, B0); G_MMA(1, 1, At, B1); BAR; SCHED;
;             G_LDB(B0, 1, 0); G_LDB(B1, 1, 1); SCHED; G_LDA(At, 1, 0); G_STAGE(G_SA(0, 1), a2 + hstep, voffA);
;             WAIT_V(8); WAIT_L(0); BAR; G_MMA(0, 0, At, B0); G_MMA(0, 1, At, B1); BAR; SCHED;
.Lrj_850_1:
	s_waitcnt lgkmcnt(0)
	s_barrier
	s_setprio 1
	v_mfma_f32_16x16x32_bf16 v[92:95], v[128:131], v[180:183], 0
	v_mfma_f32_16x16x32_bf16 v[88:91], v[136:139], v[180:183], 0
	v_mfma_f32_16x16x32_bf16 v[84:87], v[128:131], v[192:195], 0
	v_mfma_f32_16x16x32_bf16 v[80:83], v[136:139], v[192:195], 0
	v_mfma_f32_16x16x32_bf16 v[76:79], v[128:131], v[200:203], 0
	v_mfma_f32_16x16x32_bf16 v[72:75], v[136:139], v[200:203], 0
	v_mfma_f32_16x16x32_bf16 v[68:71], v[128:131], v[208:211], 0
	v_mfma_f32_16x16x32_bf16 v[64:67], v[136:139], v[208:211], 0
	v_mfma_f32_16x16x32_bf16 v[92:95], v[132:135], v[188:191], v[92:95]
	v_mfma_f32_16x16x32_bf16 v[88:91], v[140:143], v[188:191], v[88:91]
	v_mfma_f32_16x16x32_bf16 v[84:87], v[132:135], v[196:199], v[84:87]
	v_mfma_f32_16x16x32_bf16 v[80:83], v[140:143], v[196:199], v[80:83]
	v_mfma_f32_16x16x32_bf16 v[76:79], v[132:135], v[204:207], v[76:79]
	v_mfma_f32_16x16x32_bf16 v[72:75], v[140:143], v[204:207], v[72:75]
	v_mfma_f32_16x16x32_bf16 v[68:71], v[132:135], v[212:215], v[68:71]
	v_mfma_f32_16x16x32_bf16 v[64:67], v[140:143], v[212:215], v[64:67]
	s_setprio 0
	s_setprio 1
	v_mfma_f32_16x16x32_bf16 v[28:31], v[158:161], v[180:183], 0
	v_mfma_f32_16x16x32_bf16 v[24:27], v[172:175], v[180:183], 0
	v_mfma_f32_16x16x32_bf16 v[20:23], v[158:161], v[192:195], 0
	v_mfma_f32_16x16x32_bf16 v[16:19], v[172:175], v[192:195], 0
	v_mfma_f32_16x16x32_bf16 v[12:15], v[158:161], v[200:203], 0
	v_mfma_f32_16x16x32_bf16 v[8:11], v[172:175], v[200:203], 0
	v_mfma_f32_16x16x32_bf16 v[4:7], v[158:161], v[208:211], 0
	v_mfma_f32_16x16x32_bf16 v[0:3], v[172:175], v[208:211], 0
	v_mfma_f32_16x16x32_bf16 v[28:31], v[162:165], v[188:191], v[28:31]
	v_mfma_f32_16x16x32_bf16 v[24:27], v[176:179], v[188:191], v[24:27]
	v_mfma_f32_16x16x32_bf16 v[20:23], v[162:165], v[196:199], v[20:23]
	v_mfma_f32_16x16x32_bf16 v[16:19], v[176:179], v[196:199], v[16:19]
	v_mfma_f32_16x16x32_bf16 v[12:15], v[162:165], v[204:207], v[12:15]
	v_mfma_f32_16x16x32_bf16 v[8:11], v[176:179], v[204:207], v[8:11]
	v_mfma_f32_16x16x32_bf16 v[4:7], v[162:165], v[212:215], v[4:7]
	v_mfma_f32_16x16x32_bf16 v[0:3], v[176:179], v[212:215], v[0:3]
	s_setprio 0
	s_barrier
	s_add_i32 s76, 0, 0x18000
	s_add_i32 s78, 0, 0x1c000
	v_add_u32_e32 v140, s76, v168
	v_add_u32_e32 v176, s78, v168
	ds_read_b128 v[128:131], v140
	ds_read_b128 v[132:135], v140 offset:1024
	ds_read_b128 v[136:139], v140 offset:2048
	ds_read_b128 v[140:143], v140 offset:3072
	ds_read_b128 v[158:161], v176
	ds_read_b128 v[162:165], v176 offset:1024
	ds_read_b128 v[172:175], v176 offset:2048
	ds_read_b128 v[176:179], v176 offset:3072
	s_add_u32 s4, s40, 0xb0000
	s_addc_u32 s5, s41, 0
	s_mov_b32 m0, s44
	v_lshl_add_u64 v[216:217], s[4:5], 0, v[146:147]
	ds_read_b128 v[180:183], v171 offset:32768
	ds_read_b128 v[188:191], v171 offset:33792
	ds_read_b128 v[192:195], v171 offset:34816
	ds_read_b128 v[196:199], v171 offset:35840
	ds_read_b128 v[200:203], v171 offset:36864
	ds_read_b128 v[204:207], v171 offset:37888
	ds_read_b128 v[208:211], v171 offset:38912
	ds_read_b128 v[212:215], v171 offset:39936
	global_load_lds_dwordx4 v[216:217], off
	v_lshl_add_u64 v[216:217], s[4:5], 0, v[150:151]
	s_mov_b32 m0, s45
	s_nop 0
	global_load_lds_dwordx4 v[216:217], off
	s_waitcnt vmcnt(8)
	s_waitcnt lgkmcnt(0)
	s_barrier
	s_setprio 1
	v_mfma_f32_16x16x32_bf16 v[124:127], v[128:131], v[180:183], v[124:127]
	v_mfma_f32_16x16x32_bf16 v[120:123], v[136:139], v[180:183], v[120:123]
	v_mfma_f32_16x16x32_bf16 v[116:119], v[128:131], v[192:195], v[116:119]
	v_mfma_f32_16x16x32_bf16 v[112:115], v[136:139], v[192:195], v[112:115]
	v_mfma_f32_16x16x32_bf16 v[108:111], v[128:131], v[200:203], v[108:111]
	v_mfma_f32_16x16x32_bf16 v[104:107], v[136:139], v[200:203], v[104:107]
	v_mfma_f32_16x16x32_bf16 v[100:103], v[128:131], v[208:211], v[100:103]
	v_mfma_f32_16x16x32_bf16 v[96:99], v[136:139], v[208:211], v[96:99]
	v_mfma_f32_16x16x32_bf16 v[124:127], v[132:135], v[188:191], v[124:127]
	v_mfma_f32_16x16x32_bf16 v[120:123], v[140:143], v[188:191], v[120:123]
	v_mfma_f32_16x16x32_bf16 v[116:119], v[132:135], v[196:199], v[116:119]
	v_mfma_f32_16x16x32_bf16 v[112:115], v[140:143], v[196:199], v[112:115]
	v_mfma_f32_16x16x32_bf16 v[108:111], v[132:135], v[204:207], v[108:111]
	v_mfma_f32_16x16x32_bf16 v[104:107], v[140:143], v[204:207], v[104:107]
	v_mfma_f32_16x16x32_bf16 v[100:103], v[132:135], v[212:215], v[100:103]
	v_mfma_f32_16x16x32_bf16 v[96:99], v[140:143], v[212:215], v[96:99]
	s_setprio 0
	s_setprio 1
	v_mfma_f32_16x16x32_bf16 v[60:63], v[158:161], v[180:183], v[60:63]
	v_mfma_f32_16x16x32_bf16 v[56:59], v[172:175], v[180:183], v[56:59]
	v_mfma_f32_16x16x32_bf16 v[52:55], v[158:161], v[192:195], v[52:55]
	v_mfma_f32_16x16x32_bf16 v[48:51], v[172:175], v[192:195], v[48:51]
	v_mfma_f32_16x16x32_bf16 v[44:47], v[158:161], v[200:203], v[44:47]
	v_mfma_f32_16x16x32_bf16 v[40:43], v[172:175], v[200:203], v[40:43]
	v_mfma_f32_16x16x32_bf16 v[36:39], v[158:161], v[208:211], v[36:39]
	v_mfma_f32_16x16x32_bf16 v[32:35], v[172:175], v[208:211], v[32:35]
	v_mfma_f32_16x16x32_bf16 v[60:63], v[162:165], v[188:191], v[60:63]
	v_mfma_f32_16x16x32_bf16 v[56:59], v[176:179], v[188:191], v[56:59]
	v_mfma_f32_16x16x32_bf16 v[52:55], v[162:165], v[196:199], v[52:55]
	v_mfma_f32_16x16x32_bf16 v[48:51], v[176:179], v[196:199], v[48:51]
	v_mfma_f32_16x16x32_bf16 v[44:47], v[162:165], v[204:207], v[44:47]
	v_mfma_f32_16x16x32_bf16 v[40:43], v[176:179], v[204:207], v[40:43]
	v_mfma_f32_16x16x32_bf16 v[36:39], v[162:165], v[212:215], v[36:39]
	v_mfma_f32_16x16x32_bf16 v[32:35], v[176:179], v[212:215], v[32:35]
	s_setprio 0
	s_barrier
; #define G_STAGE(bufoff, gbase, voff) do { _Pragma("unroll") for (int _i = 0; _i < 2; ++_i) \
;         __builtin_amdgcn_global_load_lds((const unsigned*)((const char*)(gbase) + voff[_i]), (LAS unsigned*)(lds + (bufoff) + ldsw + _i * 8192), 16, 0, 0); } while (0)
; #define G_LDA(dst, b, h) do { _Pragma("unroll") for (int m = 0; m < 4; ++m) _Pragma("unroll") for (int k = 0; k < 2; ++k) dst[m][k] = *(const LAS bf16x8*)(lds + G_SA(b, h) + aoff + m * 2048 + k * 1024); } while (0)
; #define G_LDB(dst, b, h) do { _Pragma("unroll") for (int n = 0; n < 2; ++n) _Pragma("unroll") for (int k = 0; k < 2; ++k) dst[n][k] = *(const LAS bf16x8*)(lds + G_SB(b, h) + boff + n * 2048 + k * 1024); } while (0)
; #define G_MMA(ai, bj, At_, Bt_) do { __builtin_amdgcn_s_setprio(1); _Pragma("unroll") for (int m = 0; m < 4; ++m) _Pragma("unroll") for (int n = 0; n < 2; ++n) _Pragma("unroll") for (int k = 0; k < 2; ++k) \
;         acc[ai][bj][m][n] = __builtin_amdgcn_mfma_f32_16x16x32_bf16(Bt_[n][k], At_[m][k], acc[ai][bj][m][n], 0, 0, 0); __builtin_amdgcn_s_setprio(0); } while (0)
; #define WAIT_V(n) asm volatile("s_waitcnt vmcnt(" #n ")" ::: "memory")
; #define WAIT_L(n) asm volatile("s_waitcnt lgkmcnt(" #n ")" ::: "memory")
; #define BAR __builtin_amdgcn_s_barrier()
; #define SCHED __builtin_amdgcn_sched_barrier(0)
; template <class Get, class Epi>
; DI void gemm_loop(int ntiles, int ld, char* shm, const Get& get, const Epi& epi) {
;     ...
;         for (int t = 0; t < nt; t += 2) {
;             const bool last = (t == nt - 2);
;             const char* a1 = cA + (size_t)(t + 1) * kstep;
;             const char* a2 = last ? nA : cA + (size_t)(t + 2) * kstep; const char* b2 = last ? nB : cB + (size_t)(t + 2) * kstep;
;             const char* a3 = a2 + kstep; const char* b3 = b2 + kstep;
;             G_LDB(B0, 0, 0); G_LDB(B1, 0, 1); SCHED; G_LDA(At, 0, 0); G_STAGE(G_SA(1, 1), a1 + hstep, voffA);
;     ...
;             G_LDA(At, 1, 1); G_STAGE(G_SB(1, 0), b3, voffB); G_STAGE(G_SB(1, 1), b3 + hstep, voffB); G_STAGE(G_SA(1, 0), a3, voffA);
;             WAIT_V(8); WAIT_L(0); BAR; G_MMA(1, 0, At, B0); G_MMA(1, 1, At, B1); BAR; SCHED;
	s_add_i32 s4, s76, s26
	v_lshl_add_u64 v[144:145], v[144:145], 0, s[10:11]
	s_mov_b32 m0, s4
	ds_read_b128 v[180:183], v171 offset:49152
	ds_read_b128 v[188:191], v171 offset:50176
	ds_read_b128 v[192:195], v171 offset:51200
	ds_read_b128 v[196:199], v171 offset:52224
	ds_read_b128 v[200:203], v171 offset:53248
	ds_read_b128 v[204:207], v171 offset:54272
	ds_read_b128 v[208:211], v171 offset:55296
	ds_read_b128 v[212:215], v171 offset:56320
	global_load_lds_dwordx4 v[144:145], off
	s_add_i32 m0, s4, 0x2000
	s_add_u32 s4, s38, 0xb0080
	v_lshl_add_u64 v[144:145], v[166:167], 0, s[10:11]
	s_addc_u32 s5, s39, 0
	s_add_i32 s38, s78, s26
	global_load_lds_dwordx4 v[144:145], off
	v_lshl_add_u64 v[144:145], s[4:5], 0, v[148:149]
	s_mov_b32 m0, s38
	s_nop 0
	global_load_lds_dwordx4 v[144:145], off
	v_lshl_add_u64 v[144:145], s[4:5], 0, v[152:153]
	s_add_i32 m0, s38, 0x2000
	s_nop 0
	global_load_lds_dwordx4 v[144:145], off
	v_lshl_add_u64 v[144:145], v[184:185], 0, s[10:11]
	s_mov_b32 m0, s48
	s_nop 0
	global_load_lds_dwordx4 v[144:145], off
	v_lshl_add_u64 v[144:145], v[186:187], 0, s[10:11]
	s_mov_b32 m0, s49
	s_nop 0
	global_load_lds_dwordx4 v[144:145], off
	s_waitcnt vmcnt(8)
	s_waitcnt lgkmcnt(0)
	s_barrier
	s_setprio 1
	v_mfma_f32_16x16x32_bf16 v[92:95], v[128:131], v[180:183], v[92:95]
	v_mfma_f32_16x16x32_bf16 v[88:91], v[136:139], v[180:183], v[88:91]
	v_mfma_f32_16x16x32_bf16 v[84:87], v[128:131], v[192:195], v[84:87]
	v_mfma_f32_16x16x32_bf16 v[80:83], v[136:139], v[192:195], v[80:83]
	v_mfma_f32_16x16x32_bf16 v[76:79], v[128:131], v[200:203], v[76:79]
	v_mfma_f32_16x16x32_bf16 v[72:75], v[136:139], v[200:203], v[72:75]
	v_mfma_f32_16x16x32_bf16 v[68:71], v[128:131], v[208:211], v[68:71]
	v_mfma_f32_16x16x32_bf16 v[64:67], v[136:139], v[208:211], v[64:67]
	v_mfma_f32_16x16x32_bf16 v[92:95], v[132:135], v[188:191], v[92:95]
	v_mfma_f32_16x16x32_bf16 v[88:91], v[140:143], v[188:191], v[88:91]
	v_mfma_f32_16x16x32_bf16 v[84:87], v[132:135], v[196:199], v[84:87]
	v_mfma_f32_16x16x32_bf16 v[80:83], v[140:143], v[196:199], v[80:83]
	v_mfma_f32_16x16x32_bf16 v[76:79], v[132:135], v[204:207], v[76:79]
	v_mfma_f32_16x16x32_bf16 v[72:75], v[140:143], v[204:207], v[72:75]
	v_mfma_f32_16x16x32_bf16 v[68:71], v[132:135], v[212:215], v[68:71]
	v_mfma_f32_16x16x32_bf16 v[64:67], v[140:143], v[212:215], v[64:67]
	s_setprio 0
	s_setprio 1
	v_mfma_f32_16x16x32_bf16 v[28:31], v[158:161], v[180:183], v[28:31]
	v_mfma_f32_16x16x32_bf16 v[24:27], v[172:175], v[180:183], v[24:27]
	v_mfma_f32_16x16x32_bf16 v[20:23], v[158:161], v[192:195], v[20:23]
	v_mfma_f32_16x16x32_bf16 v[16:19], v[172:175], v[192:195], v[16:19]
	v_mfma_f32_16x16x32_bf16 v[12:15], v[158:161], v[200:203], v[12:15]
	v_mfma_f32_16x16x32_bf16 v[8:11], v[172:175], v[200:203], v[8:11]
	v_mfma_f32_16x16x32_bf16 v[4:7], v[158:161], v[208:211], v[4:7]
	v_mfma_f32_16x16x32_bf16 v[0:3], v[172:175], v[208:211], v[0:3]
	v_mfma_f32_16x16x32_bf16 v[28:31], v[162:165], v[188:191], v[28:31]
	v_mfma_f32_16x16x32_bf16 v[24:27], v[176:179], v[188:191], v[24:27]
	v_mfma_f32_16x16x32_bf16 v[20:23], v[162:165], v[196:199], v[20:23]
	v_mfma_f32_16x16x32_bf16 v[16:19], v[176:179], v[196:199], v[16:19]
	v_mfma_f32_16x16x32_bf16 v[12:15], v[162:165], v[204:207], v[12:15]
	v_mfma_f32_16x16x32_bf16 v[8:11], v[176:179], v[204:207], v[8:11]
	v_mfma_f32_16x16x32_bf16 v[4:7], v[162:165], v[212:215], v[4:7]
	v_mfma_f32_16x16x32_bf16 v[0:3], v[176:179], v[212:215], v[0:3]
	s_setprio 0
	s_barrier
	s_add_u32 s73, s73, 0x100
	s_addc_u32 s74, s74, 0
	s_cmp_ge_u32 s75, s59
	s_mov_b64 s[4:5], s[14:15]
	s_mov_b32 s38, s75
	s_cbranch_scc0 .LBB0_850
	s_branch .Lpost_850
.LBB0_850:
	ds_read_b128 v[128:131], v169
	ds_read_b128 v[132:135], v169 offset:1024
	ds_read_b128 v[136:139], v169 offset:2048
	ds_read_b128 v[140:143], v169 offset:3072
	ds_read_b128 v[158:161], v170
	ds_read_b128 v[162:165], v170 offset:1024
	ds_read_b128 v[172:175], v170 offset:2048
	ds_read_b128 v[176:179], v170 offset:3072
	s_add_i32 s75, s38, 2
	s_add_u32 s14, s4, 0x100
	s_addc_u32 s15, s5, 0
	s_cmp_eq_u32 s72, s38
	s_cselect_b32 s38, s36, s73
	s_cselect_b32 s41, s35, s15
	s_cselect_b32 s40, s34, s14
	s_cselect_b32 s39, s37, s74
	v_lshl_add_u64 v[144:145], s[4:5], 0, v[154:155]
	s_add_i32 m0, s42, 0xc000
	ds_read_b128 v[180:183], v171
	ds_read_b128 v[188:191], v171 offset:1024
	ds_read_b128 v[192:195], v171 offset:2048
	ds_read_b128 v[196:199], v171 offset:3072
	ds_read_b128 v[200:203], v171 offset:4096
	ds_read_b128 v[204:207], v171 offset:5120
	ds_read_b128 v[208:211], v171 offset:6144
	ds_read_b128 v[212:215], v171 offset:7168
	global_load_lds_dwordx4 v[144:145], off
	v_lshl_add_u64 v[144:145], s[4:5], 0, v[156:157]
	s_add_i32 m0, s42, 0xe000
	s_nop 0
	global_load_lds_dwordx4 v[144:145], off
	s_waitcnt vmcnt(8)
	s_waitcnt lgkmcnt(0)
	s_barrier
; #define G_STAGE(bufoff, gbase, voff) do { _Pragma("unroll") for (int _i = 0; _i < 2; ++_i) \
;         __builtin_amdgcn_global_load_lds((const unsigned*)((const char*)(gbase) + voff[_i]), (LAS unsigned*)(lds + (bufoff) + ldsw + _i * 8192), 16, 0, 0); } while (0)
; #define G_LDA(dst, b, h) do { _Pragma("unroll") for (int m = 0; m < 4; ++m) _Pragma("unroll") for (int k = 0; k < 2; ++k) dst[m][k] = *(const LAS bf16x8*)(lds + G_SA(b, h) + aoff + m * 2048 + k * 1024); } while (0)
; #define G_MMA(ai, bj, At_, Bt_) do { __builtin_amdgcn_s_setprio(1); _Pragma("unroll") for (int m = 0; m < 4; ++m) _Pragma("unroll") for (int n = 0; n < 2; ++n) _Pragma("unroll") for (int k = 0; k < 2; ++k) \
;         acc[ai][bj][m][n] = __builtin_amdgcn_mfma_f32_16x16x32_bf16(Bt_[n][k], At_[m][k], acc[ai][bj][m][n], 0, 0, 0); __builtin_amdgcn_s_setprio(0); } while (0)
; #define WAIT_V(n) asm volatile("s_waitcnt vmcnt(" #n ")" ::: "memory")
; #define WAIT_L(n) asm volatile("s_waitcnt lgkmcnt(" #n ")" ::: "memory")
; #define BAR __builtin_amdgcn_s_barrier()
; #define SCHED __builtin_amdgcn_sched_barrier(0)
; template <class Get, class Epi>
; DI void gemm_loop(int ntiles, int ld, char* shm, const Get& get, const Epi& epi) {
;     ...
;             WAIT_V(8); WAIT_L(0); BAR; G_MMA(0, 0, At, B0); G_MMA(0, 1, At, B1); BAR; SCHED;
;             G_LDA(At, 0, 1); G_STAGE(G_SB(0, 0), b2, voffB); G_STAGE(G_SB(0, 1), b2 + hstep, voffB); G_STAGE(G_SA(0, 0), a2, voffA);
;             WAIT_V(8); WAIT_L(0); BAR; G_MMA(1, 0, At, B0); G_MMA(1, 1, At, B1); BAR; SCHED;
	s_setprio 1
	v_mfma_f32_16x16x32_bf16 v[124:127], v[128:131], v[180:183], v[124:127]
	v_mfma_f32_16x16x32_bf16 v[120:123], v[136:139], v[180:183], v[120:123]
	v_mfma_f32_16x16x32_bf16 v[116:119], v[128:131], v[192:195], v[116:119]
	v_mfma_f32_16x16x32_bf16 v[112:115], v[136:139], v[192:195], v[112:115]
	v_mfma_f32_16x16x32_bf16 v[108:111], v[128:131], v[200:203], v[108:111]
	v_mfma_f32_16x16x32_bf16 v[104:107], v[136:139], v[200:203], v[104:107]
	v_mfma_f32_16x16x32_bf16 v[100:103], v[128:131], v[208:211], v[100:103]
	v_mfma_f32_16x16x32_bf16 v[96:99], v[136:139], v[208:211], v[96:99]
	v_mfma_f32_16x16x32_bf16 v[124:127], v[132:135], v[188:191], v[124:127]
	v_mfma_f32_16x16x32_bf16 v[120:123], v[140:143], v[188:191], v[120:123]
	v_mfma_f32_16x16x32_bf16 v[116:119], v[132:135], v[196:199], v[116:119]
	v_mfma_f32_16x16x32_bf16 v[112:115], v[140:143], v[196:199], v[112:115]
	v_mfma_f32_16x16x32_bf16 v[108:111], v[132:135], v[204:207], v[108:111]
	v_mfma_f32_16x16x32_bf16 v[104:107], v[140:143], v[204:207], v[104:107]
	v_mfma_f32_16x16x32_bf16 v[100:103], v[132:135], v[212:215], v[100:103]
	v_mfma_f32_16x16x32_bf16 v[96:99], v[140:143], v[212:215], v[96:99]
	s_setprio 0
	s_setprio 1
	v_mfma_f32_16x16x32_bf16 v[60:63], v[158:161], v[180:183], v[60:63]
	v_mfma_f32_16x16x32_bf16 v[56:59], v[172:175], v[180:183], v[56:59]
	v_mfma_f32_16x16x32_bf16 v[52:55], v[158:161], v[192:195], v[52:55]
	v_mfma_f32_16x16x32_bf16 v[48:51], v[172:175], v[192:195], v[48:51]
	v_mfma_f32_16x16x32_bf16 v[44:47], v[158:161], v[200:203], v[44:47]
	v_mfma_f32_16x16x32_bf16 v[40:43], v[172:175], v[200:203], v[40:43]
	v_mfma_f32_16x16x32_bf16 v[36:39], v[158:161], v[208:211], v[36:39]
	v_mfma_f32_16x16x32_bf16 v[32:35], v[172:175], v[208:211], v[32:35]
	v_mfma_f32_16x16x32_bf16 v[60:63], v[162:165], v[188:191], v[60:63]
	v_mfma_f32_16x16x32_bf16 v[56:59], v[176:179], v[188:191], v[56:59]
	v_mfma_f32_16x16x32_bf16 v[52:55], v[162:165], v[196:199], v[52:55]
	v_mfma_f32_16x16x32_bf16 v[48:51], v[176:179], v[196:199], v[48:51]
	v_mfma_f32_16x16x32_bf16 v[44:47], v[162:165], v[204:207], v[44:47]
	v_mfma_f32_16x16x32_bf16 v[40:43], v[176:179], v[204:207], v[40:43]
	v_mfma_f32_16x16x32_bf16 v[36:39], v[162:165], v[212:215], v[36:39]
	v_mfma_f32_16x16x32_bf16 v[32:35], v[176:179], v[212:215], v[32:35]
	s_setprio 0
	s_barrier
	s_add_i32 s4, s50, s26
	v_lshl_add_u64 v[144:145], s[38:39], 0, v[148:149]
	s_mov_b32 m0, s4
	ds_read_b128 v[180:183], v171 offset:16384
	ds_read_b128 v[188:191], v171 offset:17408
	ds_read_b128 v[192:195], v171 offset:18432
	ds_read_b128 v[196:199], v171 offset:19456
	ds_read_b128 v[200:203], v171 offset:20480
	ds_read_b128 v[204:207], v171 offset:21504
	ds_read_b128 v[208:211], v171 offset:22528
	ds_read_b128 v[212:215], v171 offset:23552
	global_load_lds_dwordx4 v[144:145], off
	s_add_i32 m0, s4, 0x2000
	s_add_u32 s4, s38, 0xb0000
	v_lshl_add_u64 v[166:167], s[38:39], 0, v[152:153]
	s_addc_u32 s5, s39, 0
	s_add_i32 s76, s51, s26
	global_load_lds_dwordx4 v[166:167], off
	v_lshl_add_u64 v[184:185], s[4:5], 0, v[148:149]
	s_mov_b32 m0, s76
	v_lshl_add_u64 v[186:187], s[40:41], 0, v[150:151]
	global_load_lds_dwordx4 v[184:185], off
	v_lshl_add_u64 v[184:185], s[4:5], 0, v[152:153]
	s_add_i32 m0, s76, 0x2000
	s_nop 0
	global_load_lds_dwordx4 v[184:185], off
	v_lshl_add_u64 v[184:185], s[40:41], 0, v[146:147]
	s_mov_b32 m0, s42
	s_nop 0
	global_load_lds_dwordx4 v[184:185], off
	s_mov_b32 m0, s43
	s_nop 0
	global_load_lds_dwordx4 v[186:187], off
	s_waitcnt vmcnt(8)
	s_waitcnt lgkmcnt(0)
	s_barrier
	s_setprio 1
	v_mfma_f32_16x16x32_bf16 v[92:95], v[128:131], v[180:183], v[92:95]
	v_mfma_f32_16x16x32_bf16 v[88:91], v[136:139], v[180:183], v[88:91]
	v_mfma_f32_16x16x32_bf16 v[84:87], v[128:131], v[192:195], v[84:87]
	v_mfma_f32_16x16x32_bf16 v[80:83], v[136:139], v[192:195], v[80:83]
	v_mfma_f32_16x16x32_bf16 v[76:79], v[128:131], v[200:203], v[76:79]
	v_mfma_f32_16x16x32_bf16 v[72:75], v[136:139], v[200:203], v[72:75]
	v_mfma_f32_16x16x32_bf16 v[68:71], v[128:131], v[208:211], v[68:71]
	v_mfma_f32_16x16x32_bf16 v[64:67], v[136:139], v[208:211], v[64:67]
	v_mfma_f32_16x16x32_bf16 v[92:95], v[132:135], v[188:191], v[92:95]
	v_mfma_f32_16x16x32_bf16 v[88:91], v[140:143], v[188:191], v[88:91]
	v_mfma_f32_16x16x32_bf16 v[84:87], v[132:135], v[196:199], v[84:87]
	v_mfma_f32_16x16x32_bf16 v[80:83], v[140:143], v[196:199], v[80:83]
	v_mfma_f32_16x16x32_bf16 v[76:79], v[132:135], v[204:207], v[76:79]
	v_mfma_f32_16x16x32_bf16 v[72:75], v[140:143], v[204:207], v[72:75]
	v_mfma_f32_16x16x32_bf16 v[68:71], v[132:135], v[212:215], v[68:71]
	v_mfma_f32_16x16x32_bf16 v[64:67], v[140:143], v[212:215], v[64:67]
	s_setprio 0
	s_setprio 1
	v_mfma_f32_16x16x32_bf16 v[28:31], v[158:161], v[180:183], v[28:31]
	v_mfma_f32_16x16x32_bf16 v[24:27], v[172:175], v[180:183], v[24:27]
	v_mfma_f32_16x16x32_bf16 v[20:23], v[158:161], v[192:195], v[20:23]
	v_mfma_f32_16x16x32_bf16 v[16:19], v[172:175], v[192:195], v[16:19]
	v_mfma_f32_16x16x32_bf16 v[12:15], v[158:161], v[200:203], v[12:15]
	v_mfma_f32_16x16x32_bf16 v[8:11], v[172:175], v[200:203], v[8:11]
	v_mfma_f32_16x16x32_bf16 v[4:7], v[158:161], v[208:211], v[4:7]
	v_mfma_f32_16x16x32_bf16 v[0:3], v[172:175], v[208:211], v[0:3]
	v_mfma_f32_16x16x32_bf16 v[28:31], v[162:165], v[188:191], v[28:31]
	v_mfma_f32_16x16x32_bf16 v[24:27], v[176:179], v[188:191], v[24:27]
	v_mfma_f32_16x16x32_bf16 v[20:23], v[162:165], v[196:199], v[20:23]
	v_mfma_f32_16x16x32_bf16 v[16:19], v[176:179], v[196:199], v[16:19]
	v_mfma_f32_16x16x32_bf16 v[12:15], v[162:165], v[204:207], v[12:15]
	v_mfma_f32_16x16x32_bf16 v[8:11], v[176:179], v[204:207], v[8:11]
	v_mfma_f32_16x16x32_bf16 v[4:7], v[162:165], v[212:215], v[4:7]
	v_mfma_f32_16x16x32_bf16 v[0:3], v[176:179], v[212:215], v[0:3]
	s_setprio 0
	s_barrier
; #define G_STAGE(bufoff, gbase, voff) do { _Pragma("unroll") for (int _i = 0; _i < 2; ++_i) \
;         __builtin_amdgcn_global_load_lds((const unsigned*)((const char*)(gbase) + voff[_i]), (LAS unsigned*)(lds + (bufoff) + ldsw + _i * 8192), 16, 0, 0); } while (0)
; #define G_LDA(dst, b, h) do { _Pragma("unroll") for (int m = 0; m < 4; ++m) _Pragma("unroll") for (int k = 0; k < 2; ++k) dst[m][k] = *(const LAS bf16x8*)(lds + G_SA(b, h) + aoff + m * 2048 + k * 1024); } while (0)
; #define G_LDB(dst, b, h) do { _Pragma("unroll") for (int n = 0; n < 2; ++n) _Pragma("unroll") for (int k = 0; k < 2; ++k) dst[n][k] = *(const LAS bf16x8*)(lds + G_SB(b, h) + boff + n * 2048 + k * 1024); } while (0)
; #define G_MMA(ai, bj, At_, Bt_) do { __builtin_amdgcn_s_setprio(1); _Pragma("unroll") for (int m = 0; m < 4; ++m) _Pragma("unroll") for (int n = 0; n < 2; ++n) _Pragma("unroll") for (int k = 0; k < 2; ++k) \
;         acc[ai][bj][m][n] = __builtin_amdgcn_mfma_f32_16x16x32_bf16(Bt_[n][k], At_[m][k], acc[ai][bj][m][n], 0, 0, 0); __builtin_amdgcn_s_setprio(0); } while (0)
; #define WAIT_V(n) asm volatile("s_waitcnt vmcnt(" #n ")" ::: "memory")
; #define WAIT_L(n) asm volatile("s_waitcnt lgkmcnt(" #n ")" ::: "memory")
; #define BAR __builtin_amdgcn_s_barrier()
; #define SCHED __builtin_amdgcn_sched_barrier(0)
; template <class Get, class Epi>
; DI void gemm_loop(int ntiles, int ld, char* shm, const Get& get, const Epi& epi) {
;     ...
;             G_LDB(B0, 1, 0); G_LDB(B1, 1, 1); SCHED; G_LDA(At, 1, 0); G_STAGE(G_SA(0, 1), a2 + hstep, voffA);
;             WAIT_V(8); WAIT_L(0); BAR; G_MMA(0, 0, At, B0); G_MMA(0, 1, At, B1); BAR; SCHED;
	s_add_i32 s76, 0, 0x18000
	s_add_i32 s78, 0, 0x1c000
	v_add_u32_e32 v140, s76, v168
	v_add_u32_e32 v176, s78, v168
	ds_read_b128 v[128:131], v140
	ds_read_b128 v[132:135], v140 offset:1024
	ds_read_b128 v[136:139], v140 offset:2048
	ds_read_b128 v[140:143], v140 offset:3072
	ds_read_b128 v[158:161], v176
	ds_read_b128 v[162:165], v176 offset:1024
	ds_read_b128 v[172:175], v176 offset:2048
	ds_read_b128 v[176:179], v176 offset:3072
	s_add_u32 s4, s40, 0xb0000
	s_addc_u32 s5, s41, 0
	s_mov_b32 m0, s44
	v_lshl_add_u64 v[216:217], s[4:5], 0, v[146:147]
	ds_read_b128 v[180:183], v171 offset:32768
	ds_read_b128 v[188:191], v171 offset:33792
	ds_read_b128 v[192:195], v171 offset:34816
	ds_read_b128 v[196:199], v171 offset:35840
	ds_read_b128 v[200:203], v171 offset:36864
	ds_read_b128 v[204:207], v171 offset:37888
	ds_read_b128 v[208:211], v171 offset:38912
	ds_read_b128 v[212:215], v171 offset:39936
	global_load_lds_dwordx4 v[216:217], off
	v_lshl_add_u64 v[216:217], s[4:5], 0, v[150:151]
	s_mov_b32 m0, s45
	s_nop 0
	global_load_lds_dwordx4 v[216:217], off
	s_waitcnt vmcnt(8)
	s_waitcnt lgkmcnt(0)
	s_barrier
	s_setprio 1
	v_mfma_f32_16x16x32_bf16 v[124:127], v[128:131], v[180:183], v[124:127]
	v_mfma_f32_16x16x32_bf16 v[120:123], v[136:139], v[180:183], v[120:123]
	v_mfma_f32_16x16x32_bf16 v[116:119], v[128:131], v[192:195], v[116:119]
	v_mfma_f32_16x16x32_bf16 v[112:115], v[136:139], v[192:195], v[112:115]
	v_mfma_f32_16x16x32_bf16 v[108:111], v[128:131], v[200:203], v[108:111]
	v_mfma_f32_16x16x32_bf16 v[104:107], v[136:139], v[200:203], v[104:107]
	v_mfma_f32_16x16x32_bf16 v[100:103], v[128:131], v[208:211], v[100:103]
	v_mfma_f32_16x16x32_bf16 v[96:99], v[136:139], v[208:211], v[96:99]
	v_mfma_f32_16x16x32_bf16 v[124:127], v[132:135], v[188:191], v[124:127]
	v_mfma_f32_16x16x32_bf16 v[120:123], v[140:143], v[188:191], v[120:123]
	v_mfma_f32_16x16x32_bf16 v[116:119], v[132:135], v[196:199], v[116:119]
	v_mfma_f32_16x16x32_bf16 v[112:115], v[140:143], v[196:199], v[112:115]
	v_mfma_f32_16x16x32_bf16 v[108:111], v[132:135], v[204:207], v[108:111]
	v_mfma_f32_16x16x32_bf16 v[104:107], v[140:143], v[204:207], v[104:107]
	v_mfma_f32_16x16x32_bf16 v[100:103], v[132:135], v[212:215], v[100:103]
	v_mfma_f32_16x16x32_bf16 v[96:99], v[140:143], v[212:215], v[96:99]
	s_setprio 0
	s_setprio 1
	v_mfma_f32_16x16x32_bf16 v[60:63], v[158:161], v[180:183], v[60:63]
	v_mfma_f32_16x16x32_bf16 v[56:59], v[172:175], v[180:183], v[56:59]
	v_mfma_f32_16x16x32_bf16 v[52:55], v[158:161], v[192:195], v[52:55]
	v_mfma_f32_16x16x32_bf16 v[48:51], v[172:175], v[192:195], v[48:51]
	v_mfma_f32_16x16x32_bf16 v[44:47], v[158:161], v[200:203], v[44:47]
	v_mfma_f32_16x16x32_bf16 v[40:43], v[172:175], v[200:203], v[40:43]
	v_mfma_f32_16x16x32_bf16 v[36:39], v[158:161], v[208:211], v[36:39]
	v_mfma_f32_16x16x32_bf16 v[32:35], v[172:175], v[208:211], v[32:35]
	v_mfma_f32_16x16x32_bf16 v[60:63], v[162:165], v[188:191], v[60:63]
	v_mfma_f32_16x16x32_bf16 v[56:59], v[176:179], v[188:191], v[56:59]
	v_mfma_f32_16x16x32_bf16 v[52:55], v[162:165], v[196:199], v[52:55]
	v_mfma_f32_16x16x32_bf16 v[48:51], v[176:179], v[196:199], v[48:51]
	v_mfma_f32_16x16x32_bf16 v[44:47], v[162:165], v[204:207], v[44:47]
	v_mfma_f32_16x16x32_bf16 v[40:43], v[176:179], v[204:207], v[40:43]
	v_mfma_f32_16x16x32_bf16 v[36:39], v[162:165], v[212:215], v[36:39]
	v_mfma_f32_16x16x32_bf16 v[32:35], v[176:179], v[212:215], v[32:35]
	s_setprio 0
	s_barrier
; #define G_STAGE(bufoff, gbase, voff) do { _Pragma("unroll") for (int _i = 0; _i < 2; ++_i) \
;         __builtin_amdgcn_global_load_lds((const unsigned*)((const char*)(gbase) + voff[_i]), (LAS unsigned*)(lds + (bufoff) + ldsw + _i * 8192), 16, 0, 0); } while (0)
; #define G_LDA(dst, b, h) do { _Pragma("unroll") for (int m = 0; m < 4; ++m) _Pragma("unroll") for (int k = 0; k < 2; ++k) dst[m][k] = *(const LAS bf16x8*)(lds + G_SA(b, h) + aoff + m * 2048 + k * 1024); } while (0)
; #define G_MMA(ai, bj, At_, Bt_) do { __builtin_amdgcn_s_setprio(1); _Pragma("unroll") for (int m = 0; m < 4; ++m) _Pragma("unroll") for (int n = 0; n < 2; ++n) _Pragma("unroll") for (int k = 0; k < 2; ++k) \
;         acc[ai][bj][m][n] = __builtin_amdgcn_mfma_f32_16x16x32_bf16(Bt_[n][k], At_[m][k], acc[ai][bj][m][n], 0, 0, 0); __builtin_amdgcn_s_setprio(0); } while (0)
; #define WAIT_V(n) asm volatile("s_waitcnt vmcnt(" #n ")" ::: "memory")
; #define WAIT_L(n) asm volatile("s_waitcnt lgkmcnt(" #n ")" ::: "memory")
; #define BAR __builtin_amdgcn_s_barrier()
; #define SCHED __builtin_amdgcn_sched_barrier(0)
; template <class Get, class Epi>
; DI void gemm_loop(int ntiles, int ld, char* shm, const Get& get, const Epi& epi) {
;     ...
;             G_LDA(At, 1, 1); G_STAGE(G_SB(1, 0), b3, voffB); G_STAGE(G_SB(1, 1), b3 + hstep, voffB); G_STAGE(G_SA(1, 0), a3, voffA);
;             WAIT_V(8); WAIT_L(0); BAR; G_MMA(1, 0, At, B0); G_MMA(1, 1, At, B1); BAR; SCHED;
	s_add_i32 s4, s76, s26
	v_lshl_add_u64 v[144:145], v[144:145], 0, s[10:11]
	s_mov_b32 m0, s4
	ds_read_b128 v[180:183], v171 offset:49152
	ds_read_b128 v[188:191], v171 offset:50176
	ds_read_b128 v[192:195], v171 offset:51200
	ds_read_b128 v[196:199], v171 offset:52224
	ds_read_b128 v[200:203], v171 offset:53248
	ds_read_b128 v[204:207], v171 offset:54272
	ds_read_b128 v[208:211], v171 offset:55296
	ds_read_b128 v[212:215], v171 offset:56320
	global_load_lds_dwordx4 v[144:145], off
	s_add_i32 m0, s4, 0x2000
	s_add_u32 s4, s38, 0xb0080
	v_lshl_add_u64 v[144:145], v[166:167], 0, s[10:11]
	s_addc_u32 s5, s39, 0
	s_add_i32 s38, s78, s26
	global_load_lds_dwordx4 v[144:145], off
	v_lshl_add_u64 v[144:145], s[4:5], 0, v[148:149]
	s_mov_b32 m0, s38
	s_nop 0
	global_load_lds_dwordx4 v[144:145], off
	v_lshl_add_u64 v[144:145], s[4:5], 0, v[152:153]
	s_add_i32 m0, s38, 0x2000
	s_nop 0
	global_load_lds_dwordx4 v[144:145], off
	v_lshl_add_u64 v[144:145], v[184:185], 0, s[10:11]
	s_mov_b32 m0, s48
	s_nop 0
	global_load_lds_dwordx4 v[144:145], off
	v_lshl_add_u64 v[144:145], v[186:187], 0, s[10:11]
	s_mov_b32 m0, s49
	s_nop 0
	global_load_lds_dwordx4 v[144:145], off
	s_waitcnt vmcnt(8)
	s_waitcnt lgkmcnt(0)
	s_barrier
	s_setprio 1
	v_mfma_f32_16x16x32_bf16 v[92:95], v[128:131], v[180:183], v[92:95]
	v_mfma_f32_16x16x32_bf16 v[88:91], v[136:139], v[180:183], v[88:91]
	v_mfma_f32_16x16x32_bf16 v[84:87], v[128:131], v[192:195], v[84:87]
	v_mfma_f32_16x16x32_bf16 v[80:83], v[136:139], v[192:195], v[80:83]
	v_mfma_f32_16x16x32_bf16 v[76:79], v[128:131], v[200:203], v[76:79]
	v_mfma_f32_16x16x32_bf16 v[72:75], v[136:139], v[200:203], v[72:75]
	v_mfma_f32_16x16x32_bf16 v[68:71], v[128:131], v[208:211], v[68:71]
	v_mfma_f32_16x16x32_bf16 v[64:67], v[136:139], v[208:211], v[64:67]
	v_mfma_f32_16x16x32_bf16 v[92:95], v[132:135], v[188:191], v[92:95]
	v_mfma_f32_16x16x32_bf16 v[88:91], v[140:143], v[188:191], v[88:91]
	v_mfma_f32_16x16x32_bf16 v[84:87], v[132:135], v[196:199], v[84:87]
	v_mfma_f32_16x16x32_bf16 v[80:83], v[140:143], v[196:199], v[80:83]
	v_mfma_f32_16x16x32_bf16 v[76:79], v[132:135], v[204:207], v[76:79]
	v_mfma_f32_16x16x32_bf16 v[72:75], v[140:143], v[204:207], v[72:75]
	v_mfma_f32_16x16x32_bf16 v[68:71], v[132:135], v[212:215], v[68:71]
	v_mfma_f32_16x16x32_bf16 v[64:67], v[140:143], v[212:215], v[64:67]
	s_setprio 0
	s_setprio 1
	v_mfma_f32_16x16x32_bf16 v[28:31], v[158:161], v[180:183], v[28:31]
	v_mfma_f32_16x16x32_bf16 v[24:27], v[172:175], v[180:183], v[24:27]
	v_mfma_f32_16x16x32_bf16 v[20:23], v[158:161], v[192:195], v[20:23]
	v_mfma_f32_16x16x32_bf16 v[16:19], v[172:175], v[192:195], v[16:19]
	v_mfma_f32_16x16x32_bf16 v[12:15], v[158:161], v[200:203], v[12:15]
	v_mfma_f32_16x16x32_bf16 v[8:11], v[172:175], v[200:203], v[8:11]
	v_mfma_f32_16x16x32_bf16 v[4:7], v[158:161], v[208:211], v[4:7]
	v_mfma_f32_16x16x32_bf16 v[0:3], v[172:175], v[208:211], v[0:3]
	v_mfma_f32_16x16x32_bf16 v[28:31], v[162:165], v[188:191], v[28:31]
	v_mfma_f32_16x16x32_bf16 v[24:27], v[176:179], v[188:191], v[24:27]
	v_mfma_f32_16x16x32_bf16 v[20:23], v[162:165], v[196:199], v[20:23]
	v_mfma_f32_16x16x32_bf16 v[16:19], v[176:179], v[196:199], v[16:19]
	v_mfma_f32_16x16x32_bf16 v[12:15], v[162:165], v[204:207], v[12:15]
	v_mfma_f32_16x16x32_bf16 v[8:11], v[176:179], v[204:207], v[8:11]
	v_mfma_f32_16x16x32_bf16 v[4:7], v[162:165], v[212:215], v[4:7]
	v_mfma_f32_16x16x32_bf16 v[0:3], v[176:179], v[212:215], v[0:3]
	s_setprio 0
	s_barrier
	s_add_u32 s73, s73, 0x100
	s_addc_u32 s74, s74, 0
	s_cmp_ge_u32 s75, s59
	s_mov_b64 s[4:5], s[14:15]
	s_mov_b32 s38, s75
	s_cbranch_scc0 .LBB0_850

; #define G_STAGE(bufoff, gbase, voff) do { _Pragma("unroll") for (int _i = 0; _i < 2; ++_i) \
;         __builtin_amdgcn_global_load_lds((const unsigned*)((const char*)(gbase) + voff[_i]), (LAS unsigned*)(lds + (bufoff) + ldsw + _i * 8192), 16, 0, 0); } while (0)
; #define G_LDA(dst, b, h) do { _Pragma("unroll") for (int m = 0; m < 4; ++m) _Pragma("unroll") for (int k = 0; k < 2; ++k) dst[m][k] = *(const LAS bf16x8*)(lds + G_SA(b, h) + aoff + m * 2048 + k * 1024); } while (0)
; #define G_MMA(ai, bj, At_, Bt_) do { __builtin_amdgcn_s_setprio(1); _Pragma("unroll") for (int m = 0; m < 4; ++m) _Pragma("unroll") for (int n = 0; n < 2; ++n) _Pragma("unroll") for (int k = 0; k < 2; ++k) \
;         acc[ai][bj][m][n] = __builtin_amdgcn_mfma_f32_16x16x32_bf16(Bt_[n][k], At_[m][k], acc[ai][bj][m][n], 0, 0, 0); __builtin_amdgcn_s_setprio(0); } while (0)
; #define WAIT_V(n) asm volatile("s_waitcnt vmcnt(" #n ")" ::: "memory")
; #define WAIT_L(n) asm volatile("s_waitcnt lgkmcnt(" #n ")" ::: "memory")
; #define BAR __builtin_amdgcn_s_barrier()
; #define SCHED __builtin_amdgcn_sched_barrier(0)
; template <class Get, class Epi>
; DI void gemm_loop(int ntiles, int ld, char* shm, const Get& get, const Epi& epi) {
;     ...
;             WAIT_V(8); WAIT_L(0); BAR; G_MMA(0, 0, At, B0); G_MMA(0, 1, At, B1); BAR; SCHED;
;             G_LDA(At, 0, 1); G_STAGE(G_SB(0, 0), b2, voffB); G_STAGE(G_SB(0, 1), b2 + hstep, voffB); G_STAGE(G_SA(0, 0), a2, voffA);
.Lrj_1099_0:
	s_waitcnt lgkmcnt(0)
	s_barrier
	s_setprio 1
	v_mfma_f32_16x16x32_bf16 v[124:127], v[140:143], v[176:179], 0
	v_mfma_f32_16x16x32_bf16 v[120:123], v[152:155], v[176:179], 0
	v_mfma_f32_16x16x32_bf16 v[116:119], v[140:143], v[184:187], 0
	v_mfma_f32_16x16x32_bf16 v[112:115], v[152:155], v[184:187], 0
	v_mfma_f32_16x16x32_bf16 v[108:111], v[140:143], v[192:195], 0
	v_mfma_f32_16x16x32_bf16 v[100:103], v[152:155], v[192:195], 0
	v_mfma_f32_16x16x32_bf16 v[92:95], v[140:143], v[200:203], 0
	v_mfma_f32_16x16x32_bf16 v[84:87], v[152:155], v[200:203], 0
	v_mfma_f32_16x16x32_bf16 v[124:127], v[148:151], v[180:183], v[124:127]
	v_mfma_f32_16x16x32_bf16 v[120:123], v[156:159], v[180:183], v[120:123]
	v_mfma_f32_16x16x32_bf16 v[116:119], v[148:151], v[188:191], v[116:119]
	v_mfma_f32_16x16x32_bf16 v[112:115], v[156:159], v[188:191], v[112:115]
	v_mfma_f32_16x16x32_bf16 v[108:111], v[148:151], v[196:199], v[108:111]
	v_mfma_f32_16x16x32_bf16 v[100:103], v[156:159], v[196:199], v[100:103]
	v_mfma_f32_16x16x32_bf16 v[92:95], v[148:151], v[204:207], v[92:95]
	v_mfma_f32_16x16x32_bf16 v[84:87], v[156:159], v[204:207], v[84:87]
	s_setprio 0
	s_setprio 1
	v_mfma_f32_16x16x32_bf16 v[104:107], v[160:163], v[176:179], 0
	v_mfma_f32_16x16x32_bf16 v[96:99], v[168:171], v[176:179], 0
	v_mfma_f32_16x16x32_bf16 v[88:91], v[160:163], v[184:187], 0
	v_mfma_f32_16x16x32_bf16 v[80:83], v[168:171], v[184:187], 0
	v_mfma_f32_16x16x32_bf16 v[76:79], v[160:163], v[192:195], 0
	v_mfma_f32_16x16x32_bf16 v[72:75], v[168:171], v[192:195], 0
	v_mfma_f32_16x16x32_bf16 v[68:71], v[160:163], v[200:203], 0
	v_mfma_f32_16x16x32_bf16 v[64:67], v[168:171], v[200:203], 0
	v_mfma_f32_16x16x32_bf16 v[104:107], v[164:167], v[180:183], v[104:107]
	v_mfma_f32_16x16x32_bf16 v[96:99], v[172:175], v[180:183], v[96:99]
	v_mfma_f32_16x16x32_bf16 v[88:91], v[164:167], v[188:191], v[88:91]
	v_mfma_f32_16x16x32_bf16 v[80:83], v[172:175], v[188:191], v[80:83]
	v_mfma_f32_16x16x32_bf16 v[76:79], v[164:167], v[196:199], v[76:79]
	v_mfma_f32_16x16x32_bf16 v[72:75], v[172:175], v[196:199], v[72:75]
	v_mfma_f32_16x16x32_bf16 v[68:71], v[164:167], v[204:207], v[68:71]
	v_mfma_f32_16x16x32_bf16 v[64:67], v[172:175], v[204:207], v[64:67]
	s_setprio 0
	s_barrier
	s_add_i32 s77, s57, s7
	v_lshl_add_u64 v[208:209], s[14:15], 0, v[130:131]
	s_mov_b32 m0, s77
	ds_read_b128 v[176:179], v147 offset:16384
	ds_read_b128 v[180:183], v147 offset:17408
	ds_read_b128 v[184:187], v147 offset:18432
	ds_read_b128 v[188:191], v147 offset:19456
	ds_read_b128 v[192:195], v147 offset:20480
	ds_read_b128 v[196:199], v147 offset:21504
	ds_read_b128 v[200:203], v147 offset:22528
	ds_read_b128 v[204:207], v147 offset:23552
	global_load_lds_dwordx4 v[208:209], off
	s_add_i32 m0, s77, 0x2000
	s_add_u32 s78, s14, 0x40000
	v_lshl_add_u64 v[210:211], s[14:15], 0, v[134:135]
	s_addc_u32 s79, s15, 0
	s_add_i32 s77, s58, s7
	global_load_lds_dwordx4 v[210:211], off
	v_lshl_add_u64 v[212:213], s[78:79], 0, v[130:131]
	s_mov_b32 m0, s77
	v_lshl_add_u64 v[214:215], s[46:47], 0, v[132:133]
	global_load_lds_dwordx4 v[212:213], off
	v_lshl_add_u64 v[212:213], s[78:79], 0, v[134:135]
	s_add_i32 m0, s77, 0x2000
	s_nop 0
	global_load_lds_dwordx4 v[212:213], off
	v_lshl_add_u64 v[212:213], s[46:47], 0, v[128:129]
	s_mov_b32 m0, s45
	s_nop 0
	global_load_lds_dwordx4 v[212:213], off
	s_mov_b32 m0, s49
	s_nop 0
	global_load_lds_dwordx4 v[214:215], off
	s_cmp_lg_u32 s100, 0
	s_cbranch_scc0 .Lrf_1099_1
	s_waitcnt vmcnt(16)
	s_branch .Lrj_1099_1

; #define G_STAGE(bufoff, gbase, voff) do { _Pragma("unroll") for (int _i = 0; _i < 2; ++_i) \
;         __builtin_amdgcn_global_load_lds((const unsigned*)((const char*)(gbase) + voff[_i]), (LAS unsigned*)(lds + (bufoff) + ldsw + _i * 8192), 16, 0, 0); } while (0)
; #define G_LDA(dst, b, h) do { _Pragma("unroll") for (int m = 0; m < 4; ++m) _Pragma("unroll") for (int k = 0; k < 2; ++k) dst[m][k] = *(const LAS bf16x8*)(lds + G_SA(b, h) + aoff + m * 2048 + k * 1024); } while (0)
; #define G_LDB(dst, b, h) do { _Pragma("unroll") for (int n = 0; n < 2; ++n) _Pragma("unroll") for (int k = 0; k < 2; ++k) dst[n][k] = *(const LAS bf16x8*)(lds + G_SB(b, h) + boff + n * 2048 + k * 1024); } while (0)
; #define G_MMA(ai, bj, At_, Bt_) do { __builtin_amdgcn_s_setprio(1); _Pragma("unroll") for (int m = 0; m < 4; ++m) _Pragma("unroll") for (int n = 0; n < 2; ++n) _Pragma("unroll") for (int k = 0; k < 2; ++k) \
;         acc[ai][bj][m][n] = __builtin_amdgcn_mfma_f32_16x16x32_bf16(Bt_[n][k], At_[m][k], acc[ai][bj][m][n], 0, 0, 0); __builtin_amdgcn_s_setprio(0); } while (0)
; #define WAIT_V(n) asm volatile("s_waitcnt vmcnt(" #n ")" ::: "memory")
; #define WAIT_L(n) asm volatile("s_waitcnt lgkmcnt(" #n ")" ::: "memory")
; #define BAR __builtin_amdgcn_s_barrier()
; #define SCHED __builtin_amdgcn_sched_barrier(0)
; template <class Get, class Epi>
; DI void gemm_loop(int ntiles, int ld, char* shm, const Get& get, const Epi& epi) {
;     ...
;             WAIT_V(8); WAIT_L(0); BAR; G_MMA(1, 0, At, B0); G_MMA(1, 1, At, B1); BAR; SCHED;
;             G_LDB(B0, 1, 0); G_LDB(B1, 1, 1); SCHED; G_LDA(At, 1, 0); G_STAGE(G_SA(0, 1), a2 + hstep, voffA);
;             WAIT_V(8); WAIT_L(0); BAR; G_MMA(0, 0, At, B0); G_MMA(0, 1, At, B1); BAR; SCHED;
.Lrj_1099_1:
	s_waitcnt lgkmcnt(0)
	s_barrier
	s_setprio 1
	v_mfma_f32_16x16x32_bf16 v[60:63], v[140:143], v[176:179], 0
	v_mfma_f32_16x16x32_bf16 v[56:59], v[152:155], v[176:179], 0
	v_mfma_f32_16x16x32_bf16 v[52:55], v[140:143], v[184:187], 0
	v_mfma_f32_16x16x32_bf16 v[48:51], v[152:155], v[184:187], 0
	v_mfma_f32_16x16x32_bf16 v[44:47], v[140:143], v[192:195], 0
	v_mfma_f32_16x16x32_bf16 v[36:39], v[152:155], v[192:195], 0
	v_mfma_f32_16x16x32_bf16 v[28:31], v[140:143], v[200:203], 0
	v_mfma_f32_16x16x32_bf16 v[20:23], v[152:155], v[200:203], 0
	v_mfma_f32_16x16x32_bf16 v[60:63], v[148:151], v[180:183], v[60:63]
	v_mfma_f32_16x16x32_bf16 v[56:59], v[156:159], v[180:183], v[56:59]
	v_mfma_f32_16x16x32_bf16 v[52:55], v[148:151], v[188:191], v[52:55]
	v_mfma_f32_16x16x32_bf16 v[48:51], v[156:159], v[188:191], v[48:51]
	v_mfma_f32_16x16x32_bf16 v[44:47], v[148:151], v[196:199], v[44:47]
	v_mfma_f32_16x16x32_bf16 v[36:39], v[156:159], v[196:199], v[36:39]
	v_mfma_f32_16x16x32_bf16 v[28:31], v[148:151], v[204:207], v[28:31]
	v_mfma_f32_16x16x32_bf16 v[20:23], v[156:159], v[204:207], v[20:23]
	s_setprio 0
	s_setprio 1
	v_mfma_f32_16x16x32_bf16 v[40:43], v[160:163], v[176:179], 0
	v_mfma_f32_16x16x32_bf16 v[32:35], v[168:171], v[176:179], 0
	v_mfma_f32_16x16x32_bf16 v[24:27], v[160:163], v[184:187], 0
	v_mfma_f32_16x16x32_bf16 v[16:19], v[168:171], v[184:187], 0
	v_mfma_f32_16x16x32_bf16 v[12:15], v[160:163], v[192:195], 0
	v_mfma_f32_16x16x32_bf16 v[8:11], v[168:171], v[192:195], 0
	v_mfma_f32_16x16x32_bf16 v[4:7], v[160:163], v[200:203], 0
	v_mfma_f32_16x16x32_bf16 v[0:3], v[168:171], v[200:203], 0
	v_mfma_f32_16x16x32_bf16 v[40:43], v[164:167], v[180:183], v[40:43]
	v_mfma_f32_16x16x32_bf16 v[32:35], v[172:175], v[180:183], v[32:35]
	v_mfma_f32_16x16x32_bf16 v[24:27], v[164:167], v[188:191], v[24:27]
	v_mfma_f32_16x16x32_bf16 v[16:19], v[172:175], v[188:191], v[16:19]
	v_mfma_f32_16x16x32_bf16 v[12:15], v[164:167], v[196:199], v[12:15]
	v_mfma_f32_16x16x32_bf16 v[8:11], v[172:175], v[196:199], v[8:11]
	v_mfma_f32_16x16x32_bf16 v[4:7], v[164:167], v[204:207], v[4:7]
	v_mfma_f32_16x16x32_bf16 v[0:3], v[172:175], v[204:207], v[0:3]
	s_setprio 0
	s_barrier
	s_add_i32 s77, 0, 0x18000
	s_add_i32 s78, 0, 0x1c000
	v_add_u32_e32 v156, s77, v144
	v_add_u32_e32 v172, s78, v144
	ds_read_b128 v[140:143], v156
	ds_read_b128 v[148:151], v156 offset:1024
	ds_read_b128 v[152:155], v156 offset:2048
	ds_read_b128 v[156:159], v156 offset:3072
	ds_read_b128 v[160:163], v172
	ds_read_b128 v[164:167], v172 offset:1024
	ds_read_b128 v[168:171], v172 offset:2048
	ds_read_b128 v[172:175], v172 offset:3072
	s_add_u32 s46, s46, 0x40000
	s_addc_u32 s47, s47, 0
	s_mov_b32 m0, s50
	v_lshl_add_u64 v[216:217], s[46:47], 0, v[128:129]
	ds_read_b128 v[176:179], v147 offset:32768
	ds_read_b128 v[180:183], v147 offset:33792
	ds_read_b128 v[184:187], v147 offset:34816
	ds_read_b128 v[188:191], v147 offset:35840
	ds_read_b128 v[192:195], v147 offset:36864
	ds_read_b128 v[196:199], v147 offset:37888
	ds_read_b128 v[200:203], v147 offset:38912
	ds_read_b128 v[204:207], v147 offset:39936
	global_load_lds_dwordx4 v[216:217], off
	v_lshl_add_u64 v[216:217], s[46:47], 0, v[132:133]
	s_mov_b32 m0, s51
	s_nop 0
	global_load_lds_dwordx4 v[216:217], off
	s_waitcnt vmcnt(8)
	s_waitcnt lgkmcnt(0)
	s_barrier
	s_setprio 1
	v_mfma_f32_16x16x32_bf16 v[124:127], v[140:143], v[176:179], v[124:127]
	v_mfma_f32_16x16x32_bf16 v[120:123], v[152:155], v[176:179], v[120:123]
	v_mfma_f32_16x16x32_bf16 v[116:119], v[140:143], v[184:187], v[116:119]
	v_mfma_f32_16x16x32_bf16 v[112:115], v[152:155], v[184:187], v[112:115]
	v_mfma_f32_16x16x32_bf16 v[108:111], v[140:143], v[192:195], v[108:111]
	v_mfma_f32_16x16x32_bf16 v[100:103], v[152:155], v[192:195], v[100:103]
	v_mfma_f32_16x16x32_bf16 v[92:95], v[140:143], v[200:203], v[92:95]
	v_mfma_f32_16x16x32_bf16 v[84:87], v[152:155], v[200:203], v[84:87]
	v_mfma_f32_16x16x32_bf16 v[124:127], v[148:151], v[180:183], v[124:127]
	v_mfma_f32_16x16x32_bf16 v[120:123], v[156:159], v[180:183], v[120:123]
	v_mfma_f32_16x16x32_bf16 v[116:119], v[148:151], v[188:191], v[116:119]
	v_mfma_f32_16x16x32_bf16 v[112:115], v[156:159], v[188:191], v[112:115]
	v_mfma_f32_16x16x32_bf16 v[108:111], v[148:151], v[196:199], v[108:111]
	v_mfma_f32_16x16x32_bf16 v[100:103], v[156:159], v[196:199], v[100:103]
	v_mfma_f32_16x16x32_bf16 v[92:95], v[148:151], v[204:207], v[92:95]
	v_mfma_f32_16x16x32_bf16 v[84:87], v[156:159], v[204:207], v[84:87]
	s_setprio 0
	s_setprio 1
	v_mfma_f32_16x16x32_bf16 v[104:107], v[160:163], v[176:179], v[104:107]
	v_mfma_f32_16x16x32_bf16 v[96:99], v[168:171], v[176:179], v[96:99]
	v_mfma_f32_16x16x32_bf16 v[88:91], v[160:163], v[184:187], v[88:91]
	v_mfma_f32_16x16x32_bf16 v[80:83], v[168:171], v[184:187], v[80:83]
	v_mfma_f32_16x16x32_bf16 v[76:79], v[160:163], v[192:195], v[76:79]
	v_mfma_f32_16x16x32_bf16 v[72:75], v[168:171], v[192:195], v[72:75]
	v_mfma_f32_16x16x32_bf16 v[68:71], v[160:163], v[200:203], v[68:71]
	v_mfma_f32_16x16x32_bf16 v[64:67], v[168:171], v[200:203], v[64:67]
	v_mfma_f32_16x16x32_bf16 v[104:107], v[164:167], v[180:183], v[104:107]
	v_mfma_f32_16x16x32_bf16 v[96:99], v[172:175], v[180:183], v[96:99]
	v_mfma_f32_16x16x32_bf16 v[88:91], v[164:167], v[188:191], v[88:91]
	v_mfma_f32_16x16x32_bf16 v[80:83], v[172:175], v[188:191], v[80:83]
	v_mfma_f32_16x16x32_bf16 v[76:79], v[164:167], v[196:199], v[76:79]
	v_mfma_f32_16x16x32_bf16 v[72:75], v[172:175], v[196:199], v[72:75]
	v_mfma_f32_16x16x32_bf16 v[68:71], v[164:167], v[204:207], v[68:71]
	v_mfma_f32_16x16x32_bf16 v[64:67], v[172:175], v[204:207], v[64:67]
	s_setprio 0
	s_barrier
; #define G_STAGE(bufoff, gbase, voff) do { _Pragma("unroll") for (int _i = 0; _i < 2; ++_i) \
;         __builtin_amdgcn_global_load_lds((const unsigned*)((const char*)(gbase) + voff[_i]), (LAS unsigned*)(lds + (bufoff) + ldsw + _i * 8192), 16, 0, 0); } while (0)
; #define G_LDA(dst, b, h) do { _Pragma("unroll") for (int m = 0; m < 4; ++m) _Pragma("unroll") for (int k = 0; k < 2; ++k) dst[m][k] = *(const LAS bf16x8*)(lds + G_SA(b, h) + aoff + m * 2048 + k * 1024); } while (0)
; #define G_LDB(dst, b, h) do { _Pragma("unroll") for (int n = 0; n < 2; ++n) _Pragma("unroll") for (int k = 0; k < 2; ++k) dst[n][k] = *(const LAS bf16x8*)(lds + G_SB(b, h) + boff + n * 2048 + k * 1024); } while (0)
; #define G_MMA(ai, bj, At_, Bt_) do { __builtin_amdgcn_s_setprio(1); _Pragma("unroll") for (int m = 0; m < 4; ++m) _Pragma("unroll") for (int n = 0; n < 2; ++n) _Pragma("unroll") for (int k = 0; k < 2; ++k) \
;         acc[ai][bj][m][n] = __builtin_amdgcn_mfma_f32_16x16x32_bf16(Bt_[n][k], At_[m][k], acc[ai][bj][m][n], 0, 0, 0); __builtin_amdgcn_s_setprio(0); } while (0)
; #define WAIT_V(n) asm volatile("s_waitcnt vmcnt(" #n ")" ::: "memory")
; #define WAIT_L(n) asm volatile("s_waitcnt lgkmcnt(" #n ")" ::: "memory")
; #define BAR __builtin_amdgcn_s_barrier()
; #define SCHED __builtin_amdgcn_sched_barrier(0)
; template <class Get, class Epi>
; DI void gemm_loop(int ntiles, int ld, char* shm, const Get& get, const Epi& epi) {
;     ...
;             const char* a2 = last ? nA : cA + (size_t)(t + 2) * kstep; const char* b2 = last ? nB : cB + (size_t)(t + 2) * kstep;
;             const char* a3 = a2 + kstep; const char* b3 = b2 + kstep;
;             G_LDB(B0, 0, 0); G_LDB(B1, 0, 1); SCHED; G_LDA(At, 0, 0); G_STAGE(G_SA(1, 1), a1 + hstep, voffA);
;             WAIT_V(8); WAIT_L(0); BAR; G_MMA(0, 0, At, B0); G_MMA(0, 1, At, B1); BAR; SCHED;
;     ...
;             G_LDA(At, 1, 1); G_STAGE(G_SB(1, 0), b3, voffB); G_STAGE(G_SB(1, 1), b3 + hstep, voffB); G_STAGE(G_SA(1, 0), a3, voffA);
;             WAIT_V(8); WAIT_L(0); BAR; G_MMA(1, 0, At, B0); G_MMA(1, 1, At, B1); BAR; SCHED;
	s_add_i32 s46, s77, s7
	v_lshl_add_u64 v[208:209], v[208:209], 0, s[10:11]
	s_mov_b32 m0, s46
	ds_read_b128 v[176:179], v147 offset:49152
	ds_read_b128 v[180:183], v147 offset:50176
	ds_read_b128 v[184:187], v147 offset:51200
	ds_read_b128 v[188:191], v147 offset:52224
	ds_read_b128 v[192:195], v147 offset:53248
	ds_read_b128 v[196:199], v147 offset:54272
	ds_read_b128 v[200:203], v147 offset:55296
	ds_read_b128 v[204:207], v147 offset:56320
	global_load_lds_dwordx4 v[208:209], off
	s_add_i32 m0, s46, 0x2000
	s_add_u32 s14, s14, 0x40080
	v_lshl_add_u64 v[208:209], v[210:211], 0, s[10:11]
	s_addc_u32 s15, s15, 0
	s_add_i32 s46, s78, s7
	global_load_lds_dwordx4 v[208:209], off
	v_lshl_add_u64 v[208:209], s[14:15], 0, v[130:131]
	s_mov_b32 m0, s46
	s_nop 0
	global_load_lds_dwordx4 v[208:209], off
	v_lshl_add_u64 v[208:209], s[14:15], 0, v[134:135]
	s_add_i32 m0, s46, 0x2000
	s_nop 0
	global_load_lds_dwordx4 v[208:209], off
	v_lshl_add_u64 v[208:209], v[212:213], 0, s[10:11]
	s_mov_b32 m0, s54
	s_nop 0
	global_load_lds_dwordx4 v[208:209], off
	v_lshl_add_u64 v[208:209], v[214:215], 0, s[10:11]
	s_mov_b32 m0, s55
	s_nop 0
	global_load_lds_dwordx4 v[208:209], off
	s_waitcnt vmcnt(8)
	s_waitcnt lgkmcnt(0)
	s_barrier
	s_setprio 1
	v_mfma_f32_16x16x32_bf16 v[60:63], v[140:143], v[176:179], v[60:63]
	v_mfma_f32_16x16x32_bf16 v[56:59], v[152:155], v[176:179], v[56:59]
	v_mfma_f32_16x16x32_bf16 v[52:55], v[140:143], v[184:187], v[52:55]
	v_mfma_f32_16x16x32_bf16 v[48:51], v[152:155], v[184:187], v[48:51]
	v_mfma_f32_16x16x32_bf16 v[44:47], v[140:143], v[192:195], v[44:47]
	v_mfma_f32_16x16x32_bf16 v[36:39], v[152:155], v[192:195], v[36:39]
	v_mfma_f32_16x16x32_bf16 v[28:31], v[140:143], v[200:203], v[28:31]
	v_mfma_f32_16x16x32_bf16 v[20:23], v[152:155], v[200:203], v[20:23]
	v_mfma_f32_16x16x32_bf16 v[60:63], v[148:151], v[180:183], v[60:63]
	v_mfma_f32_16x16x32_bf16 v[56:59], v[156:159], v[180:183], v[56:59]
	v_mfma_f32_16x16x32_bf16 v[52:55], v[148:151], v[188:191], v[52:55]
	v_mfma_f32_16x16x32_bf16 v[48:51], v[156:159], v[188:191], v[48:51]
	v_mfma_f32_16x16x32_bf16 v[44:47], v[148:151], v[196:199], v[44:47]
	v_mfma_f32_16x16x32_bf16 v[36:39], v[156:159], v[196:199], v[36:39]
	v_mfma_f32_16x16x32_bf16 v[28:31], v[148:151], v[204:207], v[28:31]
	v_mfma_f32_16x16x32_bf16 v[20:23], v[156:159], v[204:207], v[20:23]
	s_setprio 0
	s_setprio 1
	v_mfma_f32_16x16x32_bf16 v[40:43], v[160:163], v[176:179], v[40:43]
	v_mfma_f32_16x16x32_bf16 v[32:35], v[168:171], v[176:179], v[32:35]
	v_mfma_f32_16x16x32_bf16 v[24:27], v[160:163], v[184:187], v[24:27]
	v_mfma_f32_16x16x32_bf16 v[16:19], v[168:171], v[184:187], v[16:19]
	v_mfma_f32_16x16x32_bf16 v[12:15], v[160:163], v[192:195], v[12:15]
	v_mfma_f32_16x16x32_bf16 v[8:11], v[168:171], v[192:195], v[8:11]
	v_mfma_f32_16x16x32_bf16 v[4:7], v[160:163], v[200:203], v[4:7]
	v_mfma_f32_16x16x32_bf16 v[0:3], v[168:171], v[200:203], v[0:3]
	v_mfma_f32_16x16x32_bf16 v[40:43], v[164:167], v[180:183], v[40:43]
	v_mfma_f32_16x16x32_bf16 v[32:35], v[172:175], v[180:183], v[32:35]
	v_mfma_f32_16x16x32_bf16 v[24:27], v[164:167], v[188:191], v[24:27]
	v_mfma_f32_16x16x32_bf16 v[16:19], v[172:175], v[188:191], v[16:19]
	v_mfma_f32_16x16x32_bf16 v[12:15], v[164:167], v[196:199], v[12:15]
	v_mfma_f32_16x16x32_bf16 v[8:11], v[172:175], v[196:199], v[8:11]
	v_mfma_f32_16x16x32_bf16 v[4:7], v[164:167], v[204:207], v[4:7]
	v_mfma_f32_16x16x32_bf16 v[0:3], v[172:175], v[204:207], v[0:3]
	s_setprio 0
	s_barrier
	s_add_i32 s76, s76, 2
	s_add_u32 s52, s52, 0x100
	s_addc_u32 s53, s53, 0
	s_add_u32 s74, s74, 0x100
	s_addc_u32 s75, s75, 0
	s_cmp_gt_u32 s76, 13
	s_cbranch_scc0 .LBB0_1099
	s_branch .Lpost_1099
.LBB0_1099:
	ds_read_b128 v[140:143], v145
	ds_read_b128 v[148:151], v145 offset:1024
	ds_read_b128 v[152:155], v145 offset:2048
	ds_read_b128 v[156:159], v145 offset:3072
	ds_read_b128 v[160:163], v146
	ds_read_b128 v[164:167], v146 offset:1024
	ds_read_b128 v[168:171], v146 offset:2048
	ds_read_b128 v[172:175], v146 offset:3072
	s_add_u32 s14, s52, 0xfffc0080
	s_addc_u32 s15, s53, -1
	s_cmp_eq_u32 s76, 12
	s_cselect_b32 s47, s39, s15
	s_cselect_b32 s46, s72, s14
	s_cselect_b32 s15, s37, s75
	s_cselect_b32 s14, s73, s74
	v_lshl_add_u64 v[208:209], s[52:53], 0, v[136:137]
	s_add_i32 m0, s45, 0xc000
	ds_read_b128 v[176:179], v147
	ds_read_b128 v[180:183], v147 offset:1024
	ds_read_b128 v[184:187], v147 offset:2048
	ds_read_b128 v[188:191], v147 offset:3072
	ds_read_b128 v[192:195], v147 offset:4096
	ds_read_b128 v[196:199], v147 offset:5120
	ds_read_b128 v[200:203], v147 offset:6144
	ds_read_b128 v[204:207], v147 offset:7168
	global_load_lds_dwordx4 v[208:209], off
	v_lshl_add_u64 v[208:209], s[52:53], 0, v[138:139]
	s_add_i32 m0, s45, 0xe000
	s_nop 0
	global_load_lds_dwordx4 v[208:209], off
	s_waitcnt vmcnt(8)
	s_waitcnt lgkmcnt(0)
	s_barrier
; #define G_STAGE(bufoff, gbase, voff) do { _Pragma("unroll") for (int _i = 0; _i < 2; ++_i) \
;         __builtin_amdgcn_global_load_lds((const unsigned*)((const char*)(gbase) + voff[_i]), (LAS unsigned*)(lds + (bufoff) + ldsw + _i * 8192), 16, 0, 0); } while (0)
; #define G_LDA(dst, b, h) do { _Pragma("unroll") for (int m = 0; m < 4; ++m) _Pragma("unroll") for (int k = 0; k < 2; ++k) dst[m][k] = *(const LAS bf16x8*)(lds + G_SA(b, h) + aoff + m * 2048 + k * 1024); } while (0)
; #define G_MMA(ai, bj, At_, Bt_) do { __builtin_amdgcn_s_setprio(1); _Pragma("unroll") for (int m = 0; m < 4; ++m) _Pragma("unroll") for (int n = 0; n < 2; ++n) _Pragma("unroll") for (int k = 0; k < 2; ++k) \
;         acc[ai][bj][m][n] = __builtin_amdgcn_mfma_f32_16x16x32_bf16(Bt_[n][k], At_[m][k], acc[ai][bj][m][n], 0, 0, 0); __builtin_amdgcn_s_setprio(0); } while (0)
; #define WAIT_V(n) asm volatile("s_waitcnt vmcnt(" #n ")" ::: "memory")
; #define WAIT_L(n) asm volatile("s_waitcnt lgkmcnt(" #n ")" ::: "memory")
; #define BAR __builtin_amdgcn_s_barrier()
; #define SCHED __builtin_amdgcn_sched_barrier(0)
; template <class Get, class Epi>
; DI void gemm_loop(int ntiles, int ld, char* shm, const Get& get, const Epi& epi) {
;     ...
;             WAIT_V(8); WAIT_L(0); BAR; G_MMA(0, 0, At, B0); G_MMA(0, 1, At, B1); BAR; SCHED;
;             G_LDA(At, 0, 1); G_STAGE(G_SB(0, 0), b2, voffB); G_STAGE(G_SB(0, 1), b2 + hstep, voffB); G_STAGE(G_SA(0, 0), a2, voffA);
;             WAIT_V(8); WAIT_L(0); BAR; G_MMA(1, 0, At, B0); G_MMA(1, 1, At, B1); BAR; SCHED;
	s_setprio 1
	v_mfma_f32_16x16x32_bf16 v[124:127], v[140:143], v[176:179], v[124:127]
	v_mfma_f32_16x16x32_bf16 v[120:123], v[152:155], v[176:179], v[120:123]
	v_mfma_f32_16x16x32_bf16 v[116:119], v[140:143], v[184:187], v[116:119]
	v_mfma_f32_16x16x32_bf16 v[112:115], v[152:155], v[184:187], v[112:115]
	v_mfma_f32_16x16x32_bf16 v[108:111], v[140:143], v[192:195], v[108:111]
	v_mfma_f32_16x16x32_bf16 v[100:103], v[152:155], v[192:195], v[100:103]
	v_mfma_f32_16x16x32_bf16 v[92:95], v[140:143], v[200:203], v[92:95]
	v_mfma_f32_16x16x32_bf16 v[84:87], v[152:155], v[200:203], v[84:87]
	v_mfma_f32_16x16x32_bf16 v[124:127], v[148:151], v[180:183], v[124:127]
	v_mfma_f32_16x16x32_bf16 v[120:123], v[156:159], v[180:183], v[120:123]
	v_mfma_f32_16x16x32_bf16 v[116:119], v[148:151], v[188:191], v[116:119]
	v_mfma_f32_16x16x32_bf16 v[112:115], v[156:159], v[188:191], v[112:115]
	v_mfma_f32_16x16x32_bf16 v[108:111], v[148:151], v[196:199], v[108:111]
	v_mfma_f32_16x16x32_bf16 v[100:103], v[156:159], v[196:199], v[100:103]
	v_mfma_f32_16x16x32_bf16 v[92:95], v[148:151], v[204:207], v[92:95]
	v_mfma_f32_16x16x32_bf16 v[84:87], v[156:159], v[204:207], v[84:87]
	s_setprio 0
	s_setprio 1
	v_mfma_f32_16x16x32_bf16 v[104:107], v[160:163], v[176:179], v[104:107]
	v_mfma_f32_16x16x32_bf16 v[96:99], v[168:171], v[176:179], v[96:99]
	v_mfma_f32_16x16x32_bf16 v[88:91], v[160:163], v[184:187], v[88:91]
	v_mfma_f32_16x16x32_bf16 v[80:83], v[168:171], v[184:187], v[80:83]
	v_mfma_f32_16x16x32_bf16 v[76:79], v[160:163], v[192:195], v[76:79]
	v_mfma_f32_16x16x32_bf16 v[72:75], v[168:171], v[192:195], v[72:75]
	v_mfma_f32_16x16x32_bf16 v[68:71], v[160:163], v[200:203], v[68:71]
	v_mfma_f32_16x16x32_bf16 v[64:67], v[168:171], v[200:203], v[64:67]
	v_mfma_f32_16x16x32_bf16 v[104:107], v[164:167], v[180:183], v[104:107]
	v_mfma_f32_16x16x32_bf16 v[96:99], v[172:175], v[180:183], v[96:99]
	v_mfma_f32_16x16x32_bf16 v[88:91], v[164:167], v[188:191], v[88:91]
	v_mfma_f32_16x16x32_bf16 v[80:83], v[172:175], v[188:191], v[80:83]
	v_mfma_f32_16x16x32_bf16 v[76:79], v[164:167], v[196:199], v[76:79]
	v_mfma_f32_16x16x32_bf16 v[72:75], v[172:175], v[196:199], v[72:75]
	v_mfma_f32_16x16x32_bf16 v[68:71], v[164:167], v[204:207], v[68:71]
	v_mfma_f32_16x16x32_bf16 v[64:67], v[172:175], v[204:207], v[64:67]
	s_setprio 0
	s_barrier
	s_add_i32 s77, s57, s7
	v_lshl_add_u64 v[208:209], s[14:15], 0, v[130:131]
	s_mov_b32 m0, s77
	ds_read_b128 v[176:179], v147 offset:16384
	ds_read_b128 v[180:183], v147 offset:17408
	ds_read_b128 v[184:187], v147 offset:18432
	ds_read_b128 v[188:191], v147 offset:19456
	ds_read_b128 v[192:195], v147 offset:20480
	ds_read_b128 v[196:199], v147 offset:21504
	ds_read_b128 v[200:203], v147 offset:22528
	ds_read_b128 v[204:207], v147 offset:23552
	global_load_lds_dwordx4 v[208:209], off
	s_add_i32 m0, s77, 0x2000
	s_add_u32 s78, s14, 0x40000
	v_lshl_add_u64 v[210:211], s[14:15], 0, v[134:135]
	s_addc_u32 s79, s15, 0
	s_add_i32 s77, s58, s7
	global_load_lds_dwordx4 v[210:211], off
	v_lshl_add_u64 v[212:213], s[78:79], 0, v[130:131]
	s_mov_b32 m0, s77
	v_lshl_add_u64 v[214:215], s[46:47], 0, v[132:133]
	global_load_lds_dwordx4 v[212:213], off
	v_lshl_add_u64 v[212:213], s[78:79], 0, v[134:135]
	s_add_i32 m0, s77, 0x2000
	s_nop 0
	global_load_lds_dwordx4 v[212:213], off
	v_lshl_add_u64 v[212:213], s[46:47], 0, v[128:129]
	s_mov_b32 m0, s45
	s_nop 0
	global_load_lds_dwordx4 v[212:213], off
	s_mov_b32 m0, s49
	s_nop 0
	global_load_lds_dwordx4 v[214:215], off
	s_waitcnt vmcnt(8)
	s_waitcnt lgkmcnt(0)
	s_barrier
	s_setprio 1
	v_mfma_f32_16x16x32_bf16 v[60:63], v[140:143], v[176:179], v[60:63]
	v_mfma_f32_16x16x32_bf16 v[56:59], v[152:155], v[176:179], v[56:59]
	v_mfma_f32_16x16x32_bf16 v[52:55], v[140:143], v[184:187], v[52:55]
	v_mfma_f32_16x16x32_bf16 v[48:51], v[152:155], v[184:187], v[48:51]
	v_mfma_f32_16x16x32_bf16 v[44:47], v[140:143], v[192:195], v[44:47]
	v_mfma_f32_16x16x32_bf16 v[36:39], v[152:155], v[192:195], v[36:39]
	v_mfma_f32_16x16x32_bf16 v[28:31], v[140:143], v[200:203], v[28:31]
	v_mfma_f32_16x16x32_bf16 v[20:23], v[152:155], v[200:203], v[20:23]
	v_mfma_f32_16x16x32_bf16 v[60:63], v[148:151], v[180:183], v[60:63]
	v_mfma_f32_16x16x32_bf16 v[56:59], v[156:159], v[180:183], v[56:59]
	v_mfma_f32_16x16x32_bf16 v[52:55], v[148:151], v[188:191], v[52:55]
	v_mfma_f32_16x16x32_bf16 v[48:51], v[156:159], v[188:191], v[48:51]
	v_mfma_f32_16x16x32_bf16 v[44:47], v[148:151], v[196:199], v[44:47]
	v_mfma_f32_16x16x32_bf16 v[36:39], v[156:159], v[196:199], v[36:39]
	v_mfma_f32_16x16x32_bf16 v[28:31], v[148:151], v[204:207], v[28:31]
	v_mfma_f32_16x16x32_bf16 v[20:23], v[156:159], v[204:207], v[20:23]
	s_setprio 0
	s_setprio 1
	v_mfma_f32_16x16x32_bf16 v[40:43], v[160:163], v[176:179], v[40:43]
	v_mfma_f32_16x16x32_bf16 v[32:35], v[168:171], v[176:179], v[32:35]
	v_mfma_f32_16x16x32_bf16 v[24:27], v[160:163], v[184:187], v[24:27]
	v_mfma_f32_16x16x32_bf16 v[16:19], v[168:171], v[184:187], v[16:19]
	v_mfma_f32_16x16x32_bf16 v[12:15], v[160:163], v[192:195], v[12:15]
	v_mfma_f32_16x16x32_bf16 v[8:11], v[168:171], v[192:195], v[8:11]
	v_mfma_f32_16x16x32_bf16 v[4:7], v[160:163], v[200:203], v[4:7]
	v_mfma_f32_16x16x32_bf16 v[0:3], v[168:171], v[200:203], v[0:3]
	v_mfma_f32_16x16x32_bf16 v[40:43], v[164:167], v[180:183], v[40:43]
	v_mfma_f32_16x16x32_bf16 v[32:35], v[172:175], v[180:183], v[32:35]
	v_mfma_f32_16x16x32_bf16 v[24:27], v[164:167], v[188:191], v[24:27]
	v_mfma_f32_16x16x32_bf16 v[16:19], v[172:175], v[188:191], v[16:19]
	v_mfma_f32_16x16x32_bf16 v[12:15], v[164:167], v[196:199], v[12:15]
	v_mfma_f32_16x16x32_bf16 v[8:11], v[172:175], v[196:199], v[8:11]
	v_mfma_f32_16x16x32_bf16 v[4:7], v[164:167], v[204:207], v[4:7]
	v_mfma_f32_16x16x32_bf16 v[0:3], v[172:175], v[204:207], v[0:3]
	s_setprio 0
	s_barrier
; #define G_STAGE(bufoff, gbase, voff) do { _Pragma("unroll") for (int _i = 0; _i < 2; ++_i) \
;         __builtin_amdgcn_global_load_lds((const unsigned*)((const char*)(gbase) + voff[_i]), (LAS unsigned*)(lds + (bufoff) + ldsw + _i * 8192), 16, 0, 0); } while (0)
; #define G_LDA(dst, b, h) do { _Pragma("unroll") for (int m = 0; m < 4; ++m) _Pragma("unroll") for (int k = 0; k < 2; ++k) dst[m][k] = *(const LAS bf16x8*)(lds + G_SA(b, h) + aoff + m * 2048 + k * 1024); } while (0)
; #define G_LDB(dst, b, h) do { _Pragma("unroll") for (int n = 0; n < 2; ++n) _Pragma("unroll") for (int k = 0; k < 2; ++k) dst[n][k] = *(const LAS bf16x8*)(lds + G_SB(b, h) + boff + n * 2048 + k * 1024); } while (0)
; #define G_MMA(ai, bj, At_, Bt_) do { __builtin_amdgcn_s_setprio(1); _Pragma("unroll") for (int m = 0; m < 4; ++m) _Pragma("unroll") for (int n = 0; n < 2; ++n) _Pragma("unroll") for (int k = 0; k < 2; ++k) \
;         acc[ai][bj][m][n] = __builtin_amdgcn_mfma_f32_16x16x32_bf16(Bt_[n][k], At_[m][k], acc[ai][bj][m][n], 0, 0, 0); __builtin_amdgcn_s_setprio(0); } while (0)
; #define WAIT_V(n) asm volatile("s_waitcnt vmcnt(" #n ")" ::: "memory")
; #define WAIT_L(n) asm volatile("s_waitcnt lgkmcnt(" #n ")" ::: "memory")
; #define BAR __builtin_amdgcn_s_barrier()
; #define SCHED __builtin_amdgcn_sched_barrier(0)
; template <class Get, class Epi>
; DI void gemm_loop(int ntiles, int ld, char* shm, const Get& get, const Epi& epi) {
;     ...
;             G_LDB(B0, 1, 0); G_LDB(B1, 1, 1); SCHED; G_LDA(At, 1, 0); G_STAGE(G_SA(0, 1), a2 + hstep, voffA);
;             WAIT_V(8); WAIT_L(0); BAR; G_MMA(0, 0, At, B0); G_MMA(0, 1, At, B1); BAR; SCHED;
	s_add_i32 s77, 0, 0x18000
	s_add_i32 s78, 0, 0x1c000
	v_add_u32_e32 v156, s77, v144
	v_add_u32_e32 v172, s78, v144
	ds_read_b128 v[140:143], v156
	ds_read_b128 v[148:151], v156 offset:1024
	ds_read_b128 v[152:155], v156 offset:2048
	ds_read_b128 v[156:159], v156 offset:3072
	ds_read_b128 v[160:163], v172
	ds_read_b128 v[164:167], v172 offset:1024
	ds_read_b128 v[168:171], v172 offset:2048
	ds_read_b128 v[172:175], v172 offset:3072
	s_add_u32 s46, s46, 0x40000
	s_addc_u32 s47, s47, 0
	s_mov_b32 m0, s50
	v_lshl_add_u64 v[216:217], s[46:47], 0, v[128:129]
	ds_read_b128 v[176:179], v147 offset:32768
	ds_read_b128 v[180:183], v147 offset:33792
	ds_read_b128 v[184:187], v147 offset:34816
	ds_read_b128 v[188:191], v147 offset:35840
	ds_read_b128 v[192:195], v147 offset:36864
	ds_read_b128 v[196:199], v147 offset:37888
	ds_read_b128 v[200:203], v147 offset:38912
	ds_read_b128 v[204:207], v147 offset:39936
	global_load_lds_dwordx4 v[216:217], off
	v_lshl_add_u64 v[216:217], s[46:47], 0, v[132:133]
	s_mov_b32 m0, s51
	s_nop 0
	global_load_lds_dwordx4 v[216:217], off
	s_waitcnt vmcnt(8)
	s_waitcnt lgkmcnt(0)
	s_barrier
	s_setprio 1
	v_mfma_f32_16x16x32_bf16 v[124:127], v[140:143], v[176:179], v[124:127]
	v_mfma_f32_16x16x32_bf16 v[120:123], v[152:155], v[176:179], v[120:123]
	v_mfma_f32_16x16x32_bf16 v[116:119], v[140:143], v[184:187], v[116:119]
	v_mfma_f32_16x16x32_bf16 v[112:115], v[152:155], v[184:187], v[112:115]
	v_mfma_f32_16x16x32_bf16 v[108:111], v[140:143], v[192:195], v[108:111]
	v_mfma_f32_16x16x32_bf16 v[100:103], v[152:155], v[192:195], v[100:103]
	v_mfma_f32_16x16x32_bf16 v[92:95], v[140:143], v[200:203], v[92:95]
	v_mfma_f32_16x16x32_bf16 v[84:87], v[152:155], v[200:203], v[84:87]
	v_mfma_f32_16x16x32_bf16 v[124:127], v[148:151], v[180:183], v[124:127]
	v_mfma_f32_16x16x32_bf16 v[120:123], v[156:159], v[180:183], v[120:123]
	v_mfma_f32_16x16x32_bf16 v[116:119], v[148:151], v[188:191], v[116:119]
	v_mfma_f32_16x16x32_bf16 v[112:115], v[156:159], v[188:191], v[112:115]
	v_mfma_f32_16x16x32_bf16 v[108:111], v[148:151], v[196:199], v[108:111]
	v_mfma_f32_16x16x32_bf16 v[100:103], v[156:159], v[196:199], v[100:103]
	v_mfma_f32_16x16x32_bf16 v[92:95], v[148:151], v[204:207], v[92:95]
	v_mfma_f32_16x16x32_bf16 v[84:87], v[156:159], v[204:207], v[84:87]
	s_setprio 0
	s_setprio 1
	v_mfma_f32_16x16x32_bf16 v[104:107], v[160:163], v[176:179], v[104:107]
	v_mfma_f32_16x16x32_bf16 v[96:99], v[168:171], v[176:179], v[96:99]
	v_mfma_f32_16x16x32_bf16 v[88:91], v[160:163], v[184:187], v[88:91]
	v_mfma_f32_16x16x32_bf16 v[80:83], v[168:171], v[184:187], v[80:83]
	v_mfma_f32_16x16x32_bf16 v[76:79], v[160:163], v[192:195], v[76:79]
	v_mfma_f32_16x16x32_bf16 v[72:75], v[168:171], v[192:195], v[72:75]
	v_mfma_f32_16x16x32_bf16 v[68:71], v[160:163], v[200:203], v[68:71]
	v_mfma_f32_16x16x32_bf16 v[64:67], v[168:171], v[200:203], v[64:67]
	v_mfma_f32_16x16x32_bf16 v[104:107], v[164:167], v[180:183], v[104:107]
	v_mfma_f32_16x16x32_bf16 v[96:99], v[172:175], v[180:183], v[96:99]
	v_mfma_f32_16x16x32_bf16 v[88:91], v[164:167], v[188:191], v[88:91]
	v_mfma_f32_16x16x32_bf16 v[80:83], v[172:175], v[188:191], v[80:83]
	v_mfma_f32_16x16x32_bf16 v[76:79], v[164:167], v[196:199], v[76:79]
	v_mfma_f32_16x16x32_bf16 v[72:75], v[172:175], v[196:199], v[72:75]
	v_mfma_f32_16x16x32_bf16 v[68:71], v[164:167], v[204:207], v[68:71]
	v_mfma_f32_16x16x32_bf16 v[64:67], v[172:175], v[204:207], v[64:67]
	s_setprio 0
	s_barrier
; #define G_STAGE(bufoff, gbase, voff) do { _Pragma("unroll") for (int _i = 0; _i < 2; ++_i) \
;         __builtin_amdgcn_global_load_lds((const unsigned*)((const char*)(gbase) + voff[_i]), (LAS unsigned*)(lds + (bufoff) + ldsw + _i * 8192), 16, 0, 0); } while (0)
; #define G_LDA(dst, b, h) do { _Pragma("unroll") for (int m = 0; m < 4; ++m) _Pragma("unroll") for (int k = 0; k < 2; ++k) dst[m][k] = *(const LAS bf16x8*)(lds + G_SA(b, h) + aoff + m * 2048 + k * 1024); } while (0)
; #define G_MMA(ai, bj, At_, Bt_) do { __builtin_amdgcn_s_setprio(1); _Pragma("unroll") for (int m = 0; m < 4; ++m) _Pragma("unroll") for (int n = 0; n < 2; ++n) _Pragma("unroll") for (int k = 0; k < 2; ++k) \
;         acc[ai][bj][m][n] = __builtin_amdgcn_mfma_f32_16x16x32_bf16(Bt_[n][k], At_[m][k], acc[ai][bj][m][n], 0, 0, 0); __builtin_amdgcn_s_setprio(0); } while (0)
; #define WAIT_V(n) asm volatile("s_waitcnt vmcnt(" #n ")" ::: "memory")
; #define WAIT_L(n) asm volatile("s_waitcnt lgkmcnt(" #n ")" ::: "memory")
; #define BAR __builtin_amdgcn_s_barrier()
; #define SCHED __builtin_amdgcn_sched_barrier(0)
; template <class Get, class Epi>
; DI void gemm_loop(int ntiles, int ld, char* shm, const Get& get, const Epi& epi) {
;     ...
;             G_LDA(At, 1, 1); G_STAGE(G_SB(1, 0), b3, voffB); G_STAGE(G_SB(1, 1), b3 + hstep, voffB); G_STAGE(G_SA(1, 0), a3, voffA);
;             WAIT_V(8); WAIT_L(0); BAR; G_MMA(1, 0, At, B0); G_MMA(1, 1, At, B1); BAR; SCHED;
	s_add_i32 s46, s77, s7
	v_lshl_add_u64 v[208:209], v[208:209], 0, s[10:11]
	s_mov_b32 m0, s46
	ds_read_b128 v[176:179], v147 offset:49152
	ds_read_b128 v[180:183], v147 offset:50176
	ds_read_b128 v[184:187], v147 offset:51200
	ds_read_b128 v[188:191], v147 offset:52224
	ds_read_b128 v[192:195], v147 offset:53248
	ds_read_b128 v[196:199], v147 offset:54272
	ds_read_b128 v[200:203], v147 offset:55296
	ds_read_b128 v[204:207], v147 offset:56320
	global_load_lds_dwordx4 v[208:209], off
	s_add_i32 m0, s46, 0x2000
	s_add_u32 s14, s14, 0x40080
	v_lshl_add_u64 v[208:209], v[210:211], 0, s[10:11]
	s_addc_u32 s15, s15, 0
	s_add_i32 s46, s78, s7
	global_load_lds_dwordx4 v[208:209], off
	v_lshl_add_u64 v[208:209], s[14:15], 0, v[130:131]
	s_mov_b32 m0, s46
	s_nop 0
	global_load_lds_dwordx4 v[208:209], off
	v_lshl_add_u64 v[208:209], s[14:15], 0, v[134:135]
	s_add_i32 m0, s46, 0x2000
	s_nop 0
	global_load_lds_dwordx4 v[208:209], off
	v_lshl_add_u64 v[208:209], v[212:213], 0, s[10:11]
	s_mov_b32 m0, s54
	s_nop 0
	global_load_lds_dwordx4 v[208:209], off
	v_lshl_add_u64 v[208:209], v[214:215], 0, s[10:11]
	s_mov_b32 m0, s55
	s_nop 0
	global_load_lds_dwordx4 v[208:209], off
	s_waitcnt vmcnt(8)
	s_waitcnt lgkmcnt(0)
	s_barrier
	s_setprio 1
	v_mfma_f32_16x16x32_bf16 v[60:63], v[140:143], v[176:179], v[60:63]
	v_mfma_f32_16x16x32_bf16 v[56:59], v[152:155], v[176:179], v[56:59]
	v_mfma_f32_16x16x32_bf16 v[52:55], v[140:143], v[184:187], v[52:55]
	v_mfma_f32_16x16x32_bf16 v[48:51], v[152:155], v[184:187], v[48:51]
	v_mfma_f32_16x16x32_bf16 v[44:47], v[140:143], v[192:195], v[44:47]
	v_mfma_f32_16x16x32_bf16 v[36:39], v[152:155], v[192:195], v[36:39]
	v_mfma_f32_16x16x32_bf16 v[28:31], v[140:143], v[200:203], v[28:31]
	v_mfma_f32_16x16x32_bf16 v[20:23], v[152:155], v[200:203], v[20:23]
	v_mfma_f32_16x16x32_bf16 v[60:63], v[148:151], v[180:183], v[60:63]
	v_mfma_f32_16x16x32_bf16 v[56:59], v[156:159], v[180:183], v[56:59]
	v_mfma_f32_16x16x32_bf16 v[52:55], v[148:151], v[188:191], v[52:55]
	v_mfma_f32_16x16x32_bf16 v[48:51], v[156:159], v[188:191], v[48:51]
	v_mfma_f32_16x16x32_bf16 v[44:47], v[148:151], v[196:199], v[44:47]
	v_mfma_f32_16x16x32_bf16 v[36:39], v[156:159], v[196:199], v[36:39]
	v_mfma_f32_16x16x32_bf16 v[28:31], v[148:151], v[204:207], v[28:31]
	v_mfma_f32_16x16x32_bf16 v[20:23], v[156:159], v[204:207], v[20:23]
	s_setprio 0
	s_setprio 1
	v_mfma_f32_16x16x32_bf16 v[40:43], v[160:163], v[176:179], v[40:43]
	v_mfma_f32_16x16x32_bf16 v[32:35], v[168:171], v[176:179], v[32:35]
	v_mfma_f32_16x16x32_bf16 v[24:27], v[160:163], v[184:187], v[24:27]
	v_mfma_f32_16x16x32_bf16 v[16:19], v[168:171], v[184:187], v[16:19]
	v_mfma_f32_16x16x32_bf16 v[12:15], v[160:163], v[192:195], v[12:15]
	v_mfma_f32_16x16x32_bf16 v[8:11], v[168:171], v[192:195], v[8:11]
	v_mfma_f32_16x16x32_bf16 v[4:7], v[160:163], v[200:203], v[4:7]
	v_mfma_f32_16x16x32_bf16 v[0:3], v[168:171], v[200:203], v[0:3]
	v_mfma_f32_16x16x32_bf16 v[40:43], v[164:167], v[180:183], v[40:43]
	v_mfma_f32_16x16x32_bf16 v[32:35], v[172:175], v[180:183], v[32:35]
	v_mfma_f32_16x16x32_bf16 v[24:27], v[164:167], v[188:191], v[24:27]
	v_mfma_f32_16x16x32_bf16 v[16:19], v[172:175], v[188:191], v[16:19]
	v_mfma_f32_16x16x32_bf16 v[12:15], v[164:167], v[196:199], v[12:15]
	v_mfma_f32_16x16x32_bf16 v[8:11], v[172:175], v[196:199], v[8:11]
	v_mfma_f32_16x16x32_bf16 v[4:7], v[164:167], v[204:207], v[4:7]
	v_mfma_f32_16x16x32_bf16 v[0:3], v[172:175], v[204:207], v[0:3]
	s_setprio 0
	s_barrier
	s_add_i32 s76, s76, 2
	s_add_u32 s52, s52, 0x100
	s_addc_u32 s53, s53, 0
	s_add_u32 s74, s74, 0x100
	s_addc_u32 s75, s75, 0
	s_cmp_gt_u32 s76, 13
	s_cbranch_scc0 .LBB0_1099

; #define G_STAGE(bufoff, gbase, voff) do { _Pragma("unroll") for (int _i = 0; _i < 2; ++_i) \
;         __builtin_amdgcn_global_load_lds((const unsigned*)((const char*)(gbase) + voff[_i]), (LAS unsigned*)(lds + (bufoff) + ldsw + _i * 8192), 16, 0, 0); } while (0)
; #define G_LDA(dst, b, h) do { _Pragma("unroll") for (int m = 0; m < 4; ++m) _Pragma("unroll") for (int k = 0; k < 2; ++k) dst[m][k] = *(const LAS bf16x8*)(lds + G_SA(b, h) + aoff + m * 2048 + k * 1024); } while (0)
; #define G_MMA(ai, bj, At_, Bt_) do { __builtin_amdgcn_s_setprio(1); _Pragma("unroll") for (int m = 0; m < 4; ++m) _Pragma("unroll") for (int n = 0; n < 2; ++n) _Pragma("unroll") for (int k = 0; k < 2; ++k) \
;         acc[ai][bj][m][n] = __builtin_amdgcn_mfma_f32_16x16x32_bf16(Bt_[n][k], At_[m][k], acc[ai][bj][m][n], 0, 0, 0); __builtin_amdgcn_s_setprio(0); } while (0)
; #define WAIT_V(n) asm volatile("s_waitcnt vmcnt(" #n ")" ::: "memory")
; #define WAIT_L(n) asm volatile("s_waitcnt lgkmcnt(" #n ")" ::: "memory")
; #define BAR __builtin_amdgcn_s_barrier()
; #define SCHED __builtin_amdgcn_sched_barrier(0)
; template <class Get, class Epi>
; DI void gemm_loop(int ntiles, int ld, char* shm, const Get& get, const Epi& epi) {
;     ...
;             WAIT_V(8); WAIT_L(0); BAR; G_MMA(0, 0, At, B0); G_MMA(0, 1, At, B1); BAR; SCHED;
;             G_LDA(At, 0, 1); G_STAGE(G_SB(0, 0), b2, voffB); G_STAGE(G_SB(0, 1), b2 + hstep, voffB); G_STAGE(G_SA(0, 0), a2, voffA);
.Lrj_1463_0:
	s_waitcnt lgkmcnt(0)
	s_barrier
	s_setprio 1
	v_mfma_f32_16x16x32_bf16 v[124:127], v[128:131], v[180:183], 0
	v_mfma_f32_16x16x32_bf16 v[120:123], v[136:139], v[180:183], 0
	v_mfma_f32_16x16x32_bf16 v[116:119], v[128:131], v[188:191], 0
	v_mfma_f32_16x16x32_bf16 v[112:115], v[136:139], v[188:191], 0
	v_mfma_f32_16x16x32_bf16 v[108:111], v[128:131], v[196:199], 0
	v_mfma_f32_16x16x32_bf16 v[104:107], v[136:139], v[196:199], 0
	v_mfma_f32_16x16x32_bf16 v[100:103], v[128:131], v[204:207], 0
	v_mfma_f32_16x16x32_bf16 v[96:99], v[136:139], v[204:207], 0
	v_mfma_f32_16x16x32_bf16 v[124:127], v[132:135], v[184:187], v[124:127]
	v_mfma_f32_16x16x32_bf16 v[120:123], v[140:143], v[184:187], v[120:123]
	v_mfma_f32_16x16x32_bf16 v[116:119], v[132:135], v[192:195], v[116:119]
	v_mfma_f32_16x16x32_bf16 v[112:115], v[140:143], v[192:195], v[112:115]
	v_mfma_f32_16x16x32_bf16 v[108:111], v[132:135], v[200:203], v[108:111]
	v_mfma_f32_16x16x32_bf16 v[104:107], v[140:143], v[200:203], v[104:107]
	v_mfma_f32_16x16x32_bf16 v[100:103], v[132:135], v[208:211], v[100:103]
	v_mfma_f32_16x16x32_bf16 v[96:99], v[140:143], v[208:211], v[96:99]
	s_setprio 0
	s_setprio 1
	v_mfma_f32_16x16x32_bf16 v[60:63], v[158:161], v[180:183], 0
	v_mfma_f32_16x16x32_bf16 v[56:59], v[172:175], v[180:183], 0
	v_mfma_f32_16x16x32_bf16 v[52:55], v[158:161], v[188:191], 0
	v_mfma_f32_16x16x32_bf16 v[48:51], v[172:175], v[188:191], 0
	v_mfma_f32_16x16x32_bf16 v[44:47], v[158:161], v[196:199], 0
	v_mfma_f32_16x16x32_bf16 v[40:43], v[172:175], v[196:199], 0
	v_mfma_f32_16x16x32_bf16 v[36:39], v[158:161], v[204:207], 0
	v_mfma_f32_16x16x32_bf16 v[32:35], v[172:175], v[204:207], 0
	v_mfma_f32_16x16x32_bf16 v[60:63], v[162:165], v[184:187], v[60:63]
	v_mfma_f32_16x16x32_bf16 v[56:59], v[176:179], v[184:187], v[56:59]
	v_mfma_f32_16x16x32_bf16 v[52:55], v[162:165], v[192:195], v[52:55]
	v_mfma_f32_16x16x32_bf16 v[48:51], v[176:179], v[192:195], v[48:51]
	v_mfma_f32_16x16x32_bf16 v[44:47], v[162:165], v[200:203], v[44:47]
	v_mfma_f32_16x16x32_bf16 v[40:43], v[176:179], v[200:203], v[40:43]
	v_mfma_f32_16x16x32_bf16 v[36:39], v[162:165], v[208:211], v[36:39]
	v_mfma_f32_16x16x32_bf16 v[32:35], v[176:179], v[208:211], v[32:35]
	s_setprio 0
	s_barrier
	s_add_i32 s79, s57, s7
	v_lshl_add_u64 v[144:145], s[14:15], 0, v[148:149]
	s_mov_b32 m0, s79
	ds_read_b128 v[180:183], v171 offset:16384
	ds_read_b128 v[184:187], v171 offset:17408
	ds_read_b128 v[188:191], v171 offset:18432
	ds_read_b128 v[192:195], v171 offset:19456
	ds_read_b128 v[196:199], v171 offset:20480
	ds_read_b128 v[200:203], v171 offset:21504
	ds_read_b128 v[204:207], v171 offset:22528
	ds_read_b128 v[208:211], v171 offset:23552
	global_load_lds_dwordx4 v[144:145], off
	s_add_i32 m0, s79, 0x2000
	s_add_u32 s80, s14, 0x40000
	v_lshl_add_u64 v[166:167], s[14:15], 0, v[152:153]
	s_addc_u32 s81, s15, 0
	s_add_i32 s79, s58, s7
	global_load_lds_dwordx4 v[166:167], off
	v_lshl_add_u64 v[212:213], s[80:81], 0, v[148:149]
	s_mov_b32 m0, s79
	v_lshl_add_u64 v[214:215], s[46:47], 0, v[150:151]
	global_load_lds_dwordx4 v[212:213], off
	v_lshl_add_u64 v[212:213], s[80:81], 0, v[152:153]
	s_add_i32 m0, s79, 0x2000
	s_nop 0
	global_load_lds_dwordx4 v[212:213], off
	v_lshl_add_u64 v[212:213], s[46:47], 0, v[146:147]
	s_mov_b32 m0, s45
	s_nop 0
	global_load_lds_dwordx4 v[212:213], off
	s_mov_b32 m0, s50
	s_nop 0
	global_load_lds_dwordx4 v[214:215], off
	s_cmp_lg_u32 s100, 0
	s_cbranch_scc0 .Lrf_1463_1
	s_waitcnt vmcnt(16)
	s_branch .Lrj_1463_1

; #define G_STAGE(bufoff, gbase, voff) do { _Pragma("unroll") for (int _i = 0; _i < 2; ++_i) \
;         __builtin_amdgcn_global_load_lds((const unsigned*)((const char*)(gbase) + voff[_i]), (LAS unsigned*)(lds + (bufoff) + ldsw + _i * 8192), 16, 0, 0); } while (0)
; #define G_LDA(dst, b, h) do { _Pragma("unroll") for (int m = 0; m < 4; ++m) _Pragma("unroll") for (int k = 0; k < 2; ++k) dst[m][k] = *(const LAS bf16x8*)(lds + G_SA(b, h) + aoff + m * 2048 + k * 1024); } while (0)
; #define G_LDB(dst, b, h) do { _Pragma("unroll") for (int n = 0; n < 2; ++n) _Pragma("unroll") for (int k = 0; k < 2; ++k) dst[n][k] = *(const LAS bf16x8*)(lds + G_SB(b, h) + boff + n * 2048 + k * 1024); } while (0)
; #define G_MMA(ai, bj, At_, Bt_) do { __builtin_amdgcn_s_setprio(1); _Pragma("unroll") for (int m = 0; m < 4; ++m) _Pragma("unroll") for (int n = 0; n < 2; ++n) _Pragma("unroll") for (int k = 0; k < 2; ++k) \
;         acc[ai][bj][m][n] = __builtin_amdgcn_mfma_f32_16x16x32_bf16(Bt_[n][k], At_[m][k], acc[ai][bj][m][n], 0, 0, 0); __builtin_amdgcn_s_setprio(0); } while (0)
; #define WAIT_V(n) asm volatile("s_waitcnt vmcnt(" #n ")" ::: "memory")
; #define WAIT_L(n) asm volatile("s_waitcnt lgkmcnt(" #n ")" ::: "memory")
; #define BAR __builtin_amdgcn_s_barrier()
; #define SCHED __builtin_amdgcn_sched_barrier(0)
; template <class Get, class Epi>
; DI void gemm_loop(int ntiles, int ld, char* shm, const Get& get, const Epi& epi) {
;     ...
;             WAIT_V(8); WAIT_L(0); BAR; G_MMA(1, 0, At, B0); G_MMA(1, 1, At, B1); BAR; SCHED;
;             G_LDB(B0, 1, 0); G_LDB(B1, 1, 1); SCHED; G_LDA(At, 1, 0); G_STAGE(G_SA(0, 1), a2 + hstep, voffA);
;             WAIT_V(8); WAIT_L(0); BAR; G_MMA(0, 0, At, B0); G_MMA(0, 1, At, B1); BAR; SCHED;
.Lrj_1463_1:
	s_waitcnt lgkmcnt(0)
	s_barrier
	s_setprio 1
	v_mfma_f32_16x16x32_bf16 v[92:95], v[128:131], v[180:183], 0
	v_mfma_f32_16x16x32_bf16 v[88:91], v[136:139], v[180:183], 0
	v_mfma_f32_16x16x32_bf16 v[84:87], v[128:131], v[188:191], 0
	v_mfma_f32_16x16x32_bf16 v[80:83], v[136:139], v[188:191], 0
	v_mfma_f32_16x16x32_bf16 v[76:79], v[128:131], v[196:199], 0
	v_mfma_f32_16x16x32_bf16 v[72:75], v[136:139], v[196:199], 0
	v_mfma_f32_16x16x32_bf16 v[68:71], v[128:131], v[204:207], 0
	v_mfma_f32_16x16x32_bf16 v[64:67], v[136:139], v[204:207], 0
	v_mfma_f32_16x16x32_bf16 v[92:95], v[132:135], v[184:187], v[92:95]
	v_mfma_f32_16x16x32_bf16 v[88:91], v[140:143], v[184:187], v[88:91]
	v_mfma_f32_16x16x32_bf16 v[84:87], v[132:135], v[192:195], v[84:87]
	v_mfma_f32_16x16x32_bf16 v[80:83], v[140:143], v[192:195], v[80:83]
	v_mfma_f32_16x16x32_bf16 v[76:79], v[132:135], v[200:203], v[76:79]
	v_mfma_f32_16x16x32_bf16 v[72:75], v[140:143], v[200:203], v[72:75]
	v_mfma_f32_16x16x32_bf16 v[68:71], v[132:135], v[208:211], v[68:71]
	v_mfma_f32_16x16x32_bf16 v[64:67], v[140:143], v[208:211], v[64:67]
	s_setprio 0
	s_setprio 1
	v_mfma_f32_16x16x32_bf16 v[28:31], v[158:161], v[180:183], 0
	v_mfma_f32_16x16x32_bf16 v[24:27], v[172:175], v[180:183], 0
	v_mfma_f32_16x16x32_bf16 v[20:23], v[158:161], v[188:191], 0
	v_mfma_f32_16x16x32_bf16 v[16:19], v[172:175], v[188:191], 0
	v_mfma_f32_16x16x32_bf16 v[12:15], v[158:161], v[196:199], 0
	v_mfma_f32_16x16x32_bf16 v[8:11], v[172:175], v[196:199], 0
	v_mfma_f32_16x16x32_bf16 v[4:7], v[158:161], v[204:207], 0
	v_mfma_f32_16x16x32_bf16 v[0:3], v[172:175], v[204:207], 0
	v_mfma_f32_16x16x32_bf16 v[28:31], v[162:165], v[184:187], v[28:31]
	v_mfma_f32_16x16x32_bf16 v[24:27], v[176:179], v[184:187], v[24:27]
	v_mfma_f32_16x16x32_bf16 v[20:23], v[162:165], v[192:195], v[20:23]
	v_mfma_f32_16x16x32_bf16 v[16:19], v[176:179], v[192:195], v[16:19]
	v_mfma_f32_16x16x32_bf16 v[12:15], v[162:165], v[200:203], v[12:15]
	v_mfma_f32_16x16x32_bf16 v[8:11], v[176:179], v[200:203], v[8:11]
	v_mfma_f32_16x16x32_bf16 v[4:7], v[162:165], v[208:211], v[4:7]
	v_mfma_f32_16x16x32_bf16 v[0:3], v[176:179], v[208:211], v[0:3]
	s_setprio 0
	s_barrier
	s_add_i32 s79, 0, 0x18000
	s_add_i32 s80, 0, 0x1c000
	v_add_u32_e32 v140, s79, v168
	v_add_u32_e32 v176, s80, v168
	ds_read_b128 v[128:131], v140
	ds_read_b128 v[132:135], v140 offset:1024
	ds_read_b128 v[136:139], v140 offset:2048
	ds_read_b128 v[140:143], v140 offset:3072
	ds_read_b128 v[158:161], v176
	ds_read_b128 v[162:165], v176 offset:1024
	ds_read_b128 v[172:175], v176 offset:2048
	ds_read_b128 v[176:179], v176 offset:3072
	s_add_u32 s46, s46, 0x40000
	s_addc_u32 s47, s47, 0
	s_mov_b32 m0, s51
	v_lshl_add_u64 v[216:217], s[46:47], 0, v[146:147]
	ds_read_b128 v[180:183], v171 offset:32768
	ds_read_b128 v[184:187], v171 offset:33792
	ds_read_b128 v[188:191], v171 offset:34816
	ds_read_b128 v[192:195], v171 offset:35840
	ds_read_b128 v[196:199], v171 offset:36864
	ds_read_b128 v[200:203], v171 offset:37888
	ds_read_b128 v[204:207], v171 offset:38912
	ds_read_b128 v[208:211], v171 offset:39936
	global_load_lds_dwordx4 v[216:217], off
	v_lshl_add_u64 v[216:217], s[46:47], 0, v[150:151]
	s_mov_b32 m0, s52
	s_nop 0
	global_load_lds_dwordx4 v[216:217], off
	s_waitcnt vmcnt(8)
	s_waitcnt lgkmcnt(0)
	s_barrier
	s_setprio 1
	v_mfma_f32_16x16x32_bf16 v[124:127], v[128:131], v[180:183], v[124:127]
	v_mfma_f32_16x16x32_bf16 v[120:123], v[136:139], v[180:183], v[120:123]
	v_mfma_f32_16x16x32_bf16 v[116:119], v[128:131], v[188:191], v[116:119]
	v_mfma_f32_16x16x32_bf16 v[112:115], v[136:139], v[188:191], v[112:115]
	v_mfma_f32_16x16x32_bf16 v[108:111], v[128:131], v[196:199], v[108:111]
	v_mfma_f32_16x16x32_bf16 v[104:107], v[136:139], v[196:199], v[104:107]
	v_mfma_f32_16x16x32_bf16 v[100:103], v[128:131], v[204:207], v[100:103]
	v_mfma_f32_16x16x32_bf16 v[96:99], v[136:139], v[204:207], v[96:99]
	v_mfma_f32_16x16x32_bf16 v[124:127], v[132:135], v[184:187], v[124:127]
	v_mfma_f32_16x16x32_bf16 v[120:123], v[140:143], v[184:187], v[120:123]
	v_mfma_f32_16x16x32_bf16 v[116:119], v[132:135], v[192:195], v[116:119]
	v_mfma_f32_16x16x32_bf16 v[112:115], v[140:143], v[192:195], v[112:115]
	v_mfma_f32_16x16x32_bf16 v[108:111], v[132:135], v[200:203], v[108:111]
	v_mfma_f32_16x16x32_bf16 v[104:107], v[140:143], v[200:203], v[104:107]
	v_mfma_f32_16x16x32_bf16 v[100:103], v[132:135], v[208:211], v[100:103]
	v_mfma_f32_16x16x32_bf16 v[96:99], v[140:143], v[208:211], v[96:99]
	s_setprio 0
	s_setprio 1
	v_mfma_f32_16x16x32_bf16 v[60:63], v[158:161], v[180:183], v[60:63]
	v_mfma_f32_16x16x32_bf16 v[56:59], v[172:175], v[180:183], v[56:59]
	v_mfma_f32_16x16x32_bf16 v[52:55], v[158:161], v[188:191], v[52:55]
	v_mfma_f32_16x16x32_bf16 v[48:51], v[172:175], v[188:191], v[48:51]
	v_mfma_f32_16x16x32_bf16 v[44:47], v[158:161], v[196:199], v[44:47]
	v_mfma_f32_16x16x32_bf16 v[40:43], v[172:175], v[196:199], v[40:43]
	v_mfma_f32_16x16x32_bf16 v[36:39], v[158:161], v[204:207], v[36:39]
	v_mfma_f32_16x16x32_bf16 v[32:35], v[172:175], v[204:207], v[32:35]
	v_mfma_f32_16x16x32_bf16 v[60:63], v[162:165], v[184:187], v[60:63]
	v_mfma_f32_16x16x32_bf16 v[56:59], v[176:179], v[184:187], v[56:59]
	v_mfma_f32_16x16x32_bf16 v[52:55], v[162:165], v[192:195], v[52:55]
	v_mfma_f32_16x16x32_bf16 v[48:51], v[176:179], v[192:195], v[48:51]
	v_mfma_f32_16x16x32_bf16 v[44:47], v[162:165], v[200:203], v[44:47]
	v_mfma_f32_16x16x32_bf16 v[40:43], v[176:179], v[200:203], v[40:43]
	v_mfma_f32_16x16x32_bf16 v[36:39], v[162:165], v[208:211], v[36:39]
	v_mfma_f32_16x16x32_bf16 v[32:35], v[176:179], v[208:211], v[32:35]
	s_setprio 0
	s_barrier
; #define G_STAGE(bufoff, gbase, voff) do { _Pragma("unroll") for (int _i = 0; _i < 2; ++_i) \
;         __builtin_amdgcn_global_load_lds((const unsigned*)((const char*)(gbase) + voff[_i]), (LAS unsigned*)(lds + (bufoff) + ldsw + _i * 8192), 16, 0, 0); } while (0)
; #define G_LDA(dst, b, h) do { _Pragma("unroll") for (int m = 0; m < 4; ++m) _Pragma("unroll") for (int k = 0; k < 2; ++k) dst[m][k] = *(const LAS bf16x8*)(lds + G_SA(b, h) + aoff + m * 2048 + k * 1024); } while (0)
; #define G_LDB(dst, b, h) do { _Pragma("unroll") for (int n = 0; n < 2; ++n) _Pragma("unroll") for (int k = 0; k < 2; ++k) dst[n][k] = *(const LAS bf16x8*)(lds + G_SB(b, h) + boff + n * 2048 + k * 1024); } while (0)
; #define G_MMA(ai, bj, At_, Bt_) do { __builtin_amdgcn_s_setprio(1); _Pragma("unroll") for (int m = 0; m < 4; ++m) _Pragma("unroll") for (int n = 0; n < 2; ++n) _Pragma("unroll") for (int k = 0; k < 2; ++k) \
;         acc[ai][bj][m][n] = __builtin_amdgcn_mfma_f32_16x16x32_bf16(Bt_[n][k], At_[m][k], acc[ai][bj][m][n], 0, 0, 0); __builtin_amdgcn_s_setprio(0); } while (0)
; #define WAIT_V(n) asm volatile("s_waitcnt vmcnt(" #n ")" ::: "memory")
; #define WAIT_L(n) asm volatile("s_waitcnt lgkmcnt(" #n ")" ::: "memory")
; #define BAR __builtin_amdgcn_s_barrier()
; #define SCHED __builtin_amdgcn_sched_barrier(0)
; template <class Get, class Epi>
; DI void gemm_loop(int ntiles, int ld, char* shm, const Get& get, const Epi& epi) {
;     ...
;             const char* a2 = last ? nA : cA + (size_t)(t + 2) * kstep; const char* b2 = last ? nB : cB + (size_t)(t + 2) * kstep;
;             const char* a3 = a2 + kstep; const char* b3 = b2 + kstep;
;             G_LDB(B0, 0, 0); G_LDB(B1, 0, 1); SCHED; G_LDA(At, 0, 0); G_STAGE(G_SA(1, 1), a1 + hstep, voffA);
;             WAIT_V(8); WAIT_L(0); BAR; G_MMA(0, 0, At, B0); G_MMA(0, 1, At, B1); BAR; SCHED;
;     ...
;             G_LDA(At, 1, 1); G_STAGE(G_SB(1, 0), b3, voffB); G_STAGE(G_SB(1, 1), b3 + hstep, voffB); G_STAGE(G_SA(1, 0), a3, voffA);
;             WAIT_V(8); WAIT_L(0); BAR; G_MMA(1, 0, At, B0); G_MMA(1, 1, At, B1); BAR; SCHED;
	s_add_i32 s46, s79, s7
	v_lshl_add_u64 v[144:145], v[144:145], 0, s[10:11]
	s_mov_b32 m0, s46
	ds_read_b128 v[180:183], v171 offset:49152
	ds_read_b128 v[184:187], v171 offset:50176
	ds_read_b128 v[188:191], v171 offset:51200
	ds_read_b128 v[192:195], v171 offset:52224
	ds_read_b128 v[196:199], v171 offset:53248
	ds_read_b128 v[200:203], v171 offset:54272
	ds_read_b128 v[204:207], v171 offset:55296
	ds_read_b128 v[208:211], v171 offset:56320
	global_load_lds_dwordx4 v[144:145], off
	s_add_i32 m0, s46, 0x2000
	s_add_u32 s14, s14, 0x40080
	v_lshl_add_u64 v[144:145], v[166:167], 0, s[10:11]
	s_addc_u32 s15, s15, 0
	s_add_i32 s46, s80, s7
	global_load_lds_dwordx4 v[144:145], off
	v_lshl_add_u64 v[144:145], s[14:15], 0, v[148:149]
	s_mov_b32 m0, s46
	s_nop 0
	global_load_lds_dwordx4 v[144:145], off
	v_lshl_add_u64 v[144:145], s[14:15], 0, v[152:153]
	s_add_i32 m0, s46, 0x2000
	s_nop 0
	global_load_lds_dwordx4 v[144:145], off
	v_lshl_add_u64 v[144:145], v[212:213], 0, s[10:11]
	s_mov_b32 m0, s55
	s_nop 0
	global_load_lds_dwordx4 v[144:145], off
	v_lshl_add_u64 v[144:145], v[214:215], 0, s[10:11]
	s_mov_b32 m0, s56
	s_nop 0
	global_load_lds_dwordx4 v[144:145], off
	s_waitcnt vmcnt(8)
	s_waitcnt lgkmcnt(0)
	s_barrier
	s_setprio 1
	v_mfma_f32_16x16x32_bf16 v[92:95], v[128:131], v[180:183], v[92:95]
	v_mfma_f32_16x16x32_bf16 v[88:91], v[136:139], v[180:183], v[88:91]
	v_mfma_f32_16x16x32_bf16 v[84:87], v[128:131], v[188:191], v[84:87]
	v_mfma_f32_16x16x32_bf16 v[80:83], v[136:139], v[188:191], v[80:83]
	v_mfma_f32_16x16x32_bf16 v[76:79], v[128:131], v[196:199], v[76:79]
	v_mfma_f32_16x16x32_bf16 v[72:75], v[136:139], v[196:199], v[72:75]
	v_mfma_f32_16x16x32_bf16 v[68:71], v[128:131], v[204:207], v[68:71]
	v_mfma_f32_16x16x32_bf16 v[64:67], v[136:139], v[204:207], v[64:67]
	v_mfma_f32_16x16x32_bf16 v[92:95], v[132:135], v[184:187], v[92:95]
	v_mfma_f32_16x16x32_bf16 v[88:91], v[140:143], v[184:187], v[88:91]
	v_mfma_f32_16x16x32_bf16 v[84:87], v[132:135], v[192:195], v[84:87]
	v_mfma_f32_16x16x32_bf16 v[80:83], v[140:143], v[192:195], v[80:83]
	v_mfma_f32_16x16x32_bf16 v[76:79], v[132:135], v[200:203], v[76:79]
	v_mfma_f32_16x16x32_bf16 v[72:75], v[140:143], v[200:203], v[72:75]
	v_mfma_f32_16x16x32_bf16 v[68:71], v[132:135], v[208:211], v[68:71]
	v_mfma_f32_16x16x32_bf16 v[64:67], v[140:143], v[208:211], v[64:67]
	s_setprio 0
	s_setprio 1
	v_mfma_f32_16x16x32_bf16 v[28:31], v[158:161], v[180:183], v[28:31]
	v_mfma_f32_16x16x32_bf16 v[24:27], v[172:175], v[180:183], v[24:27]
	v_mfma_f32_16x16x32_bf16 v[20:23], v[158:161], v[188:191], v[20:23]
	v_mfma_f32_16x16x32_bf16 v[16:19], v[172:175], v[188:191], v[16:19]
	v_mfma_f32_16x16x32_bf16 v[12:15], v[158:161], v[196:199], v[12:15]
	v_mfma_f32_16x16x32_bf16 v[8:11], v[172:175], v[196:199], v[8:11]
	v_mfma_f32_16x16x32_bf16 v[4:7], v[158:161], v[204:207], v[4:7]
	v_mfma_f32_16x16x32_bf16 v[0:3], v[172:175], v[204:207], v[0:3]
	v_mfma_f32_16x16x32_bf16 v[28:31], v[162:165], v[184:187], v[28:31]
	v_mfma_f32_16x16x32_bf16 v[24:27], v[176:179], v[184:187], v[24:27]
	v_mfma_f32_16x16x32_bf16 v[20:23], v[162:165], v[192:195], v[20:23]
	v_mfma_f32_16x16x32_bf16 v[16:19], v[176:179], v[192:195], v[16:19]
	v_mfma_f32_16x16x32_bf16 v[12:15], v[162:165], v[200:203], v[12:15]
	v_mfma_f32_16x16x32_bf16 v[8:11], v[176:179], v[200:203], v[8:11]
	v_mfma_f32_16x16x32_bf16 v[4:7], v[162:165], v[208:211], v[4:7]
	v_mfma_f32_16x16x32_bf16 v[0:3], v[176:179], v[208:211], v[0:3]
	s_setprio 0
	s_barrier
	s_add_u32 s48, s48, 0x100
	s_addc_u32 s49, s49, 0
	s_add_u32 s76, s76, 0x100
	s_addc_u32 s77, s77, 0
	s_cmp_ge_u32 s78, s74
	s_mov_b32 s14, s78
	s_cbranch_scc0 .LBB0_1463
	s_branch .Lpost_1463
.LBB0_1463:
	ds_read_b128 v[128:131], v169
	ds_read_b128 v[132:135], v169 offset:1024
	ds_read_b128 v[136:139], v169 offset:2048
	ds_read_b128 v[140:143], v169 offset:3072
	ds_read_b128 v[158:161], v170
	ds_read_b128 v[162:165], v170 offset:1024
	ds_read_b128 v[172:175], v170 offset:2048
	ds_read_b128 v[176:179], v170 offset:3072
	s_add_i32 s78, s14, 2
	s_add_u32 s15, s48, 0xfffc0080
	s_addc_u32 s46, s49, -1
	s_cmp_eq_u32 s75, s14
	s_cselect_b32 s14, s73, s76
	s_cselect_b32 s47, s3, s46
	s_cselect_b32 s46, s37, s15
	s_cselect_b32 s15, s39, s77
	v_lshl_add_u64 v[144:145], s[48:49], 0, v[154:155]
	s_add_i32 m0, s45, 0xc000
	ds_read_b128 v[180:183], v171
	ds_read_b128 v[184:187], v171 offset:1024
	ds_read_b128 v[188:191], v171 offset:2048
	ds_read_b128 v[192:195], v171 offset:3072
	ds_read_b128 v[196:199], v171 offset:4096
	ds_read_b128 v[200:203], v171 offset:5120
	ds_read_b128 v[204:207], v171 offset:6144
	ds_read_b128 v[208:211], v171 offset:7168
	global_load_lds_dwordx4 v[144:145], off
	v_lshl_add_u64 v[144:145], s[48:49], 0, v[156:157]
	s_add_i32 m0, s45, 0xe000
	s_nop 0
	global_load_lds_dwordx4 v[144:145], off
	s_waitcnt vmcnt(8)
	s_waitcnt lgkmcnt(0)
	s_barrier
; #define G_STAGE(bufoff, gbase, voff) do { _Pragma("unroll") for (int _i = 0; _i < 2; ++_i) \
;         __builtin_amdgcn_global_load_lds((const unsigned*)((const char*)(gbase) + voff[_i]), (LAS unsigned*)(lds + (bufoff) + ldsw + _i * 8192), 16, 0, 0); } while (0)
; #define G_LDA(dst, b, h) do { _Pragma("unroll") for (int m = 0; m < 4; ++m) _Pragma("unroll") for (int k = 0; k < 2; ++k) dst[m][k] = *(const LAS bf16x8*)(lds + G_SA(b, h) + aoff + m * 2048 + k * 1024); } while (0)
; #define G_MMA(ai, bj, At_, Bt_) do { __builtin_amdgcn_s_setprio(1); _Pragma("unroll") for (int m = 0; m < 4; ++m) _Pragma("unroll") for (int n = 0; n < 2; ++n) _Pragma("unroll") for (int k = 0; k < 2; ++k) \
;         acc[ai][bj][m][n] = __builtin_amdgcn_mfma_f32_16x16x32_bf16(Bt_[n][k], At_[m][k], acc[ai][bj][m][n], 0, 0, 0); __builtin_amdgcn_s_setprio(0); } while (0)
; #define WAIT_V(n) asm volatile("s_waitcnt vmcnt(" #n ")" ::: "memory")
; #define WAIT_L(n) asm volatile("s_waitcnt lgkmcnt(" #n ")" ::: "memory")
; #define BAR __builtin_amdgcn_s_barrier()
; #define SCHED __builtin_amdgcn_sched_barrier(0)
; template <class Get, class Epi>
; DI void gemm_loop(int ntiles, int ld, char* shm, const Get& get, const Epi& epi) {
;     ...
;             WAIT_V(8); WAIT_L(0); BAR; G_MMA(0, 0, At, B0); G_MMA(0, 1, At, B1); BAR; SCHED;
;             G_LDA(At, 0, 1); G_STAGE(G_SB(0, 0), b2, voffB); G_STAGE(G_SB(0, 1), b2 + hstep, voffB); G_STAGE(G_SA(0, 0), a2, voffA);
;             WAIT_V(8); WAIT_L(0); BAR; G_MMA(1, 0, At, B0); G_MMA(1, 1, At, B1); BAR; SCHED;
	s_setprio 1
	v_mfma_f32_16x16x32_bf16 v[124:127], v[128:131], v[180:183], v[124:127]
	v_mfma_f32_16x16x32_bf16 v[120:123], v[136:139], v[180:183], v[120:123]
	v_mfma_f32_16x16x32_bf16 v[116:119], v[128:131], v[188:191], v[116:119]
	v_mfma_f32_16x16x32_bf16 v[112:115], v[136:139], v[188:191], v[112:115]
	v_mfma_f32_16x16x32_bf16 v[108:111], v[128:131], v[196:199], v[108:111]
	v_mfma_f32_16x16x32_bf16 v[104:107], v[136:139], v[196:199], v[104:107]
	v_mfma_f32_16x16x32_bf16 v[100:103], v[128:131], v[204:207], v[100:103]
	v_mfma_f32_16x16x32_bf16 v[96:99], v[136:139], v[204:207], v[96:99]
	v_mfma_f32_16x16x32_bf16 v[124:127], v[132:135], v[184:187], v[124:127]
	v_mfma_f32_16x16x32_bf16 v[120:123], v[140:143], v[184:187], v[120:123]
	v_mfma_f32_16x16x32_bf16 v[116:119], v[132:135], v[192:195], v[116:119]
	v_mfma_f32_16x16x32_bf16 v[112:115], v[140:143], v[192:195], v[112:115]
	v_mfma_f32_16x16x32_bf16 v[108:111], v[132:135], v[200:203], v[108:111]
	v_mfma_f32_16x16x32_bf16 v[104:107], v[140:143], v[200:203], v[104:107]
	v_mfma_f32_16x16x32_bf16 v[100:103], v[132:135], v[208:211], v[100:103]
	v_mfma_f32_16x16x32_bf16 v[96:99], v[140:143], v[208:211], v[96:99]
	s_setprio 0
	s_setprio 1
	v_mfma_f32_16x16x32_bf16 v[60:63], v[158:161], v[180:183], v[60:63]
	v_mfma_f32_16x16x32_bf16 v[56:59], v[172:175], v[180:183], v[56:59]
	v_mfma_f32_16x16x32_bf16 v[52:55], v[158:161], v[188:191], v[52:55]
	v_mfma_f32_16x16x32_bf16 v[48:51], v[172:175], v[188:191], v[48:51]
	v_mfma_f32_16x16x32_bf16 v[44:47], v[158:161], v[196:199], v[44:47]
	v_mfma_f32_16x16x32_bf16 v[40:43], v[172:175], v[196:199], v[40:43]
	v_mfma_f32_16x16x32_bf16 v[36:39], v[158:161], v[204:207], v[36:39]
	v_mfma_f32_16x16x32_bf16 v[32:35], v[172:175], v[204:207], v[32:35]
	v_mfma_f32_16x16x32_bf16 v[60:63], v[162:165], v[184:187], v[60:63]
	v_mfma_f32_16x16x32_bf16 v[56:59], v[176:179], v[184:187], v[56:59]
	v_mfma_f32_16x16x32_bf16 v[52:55], v[162:165], v[192:195], v[52:55]
	v_mfma_f32_16x16x32_bf16 v[48:51], v[176:179], v[192:195], v[48:51]
	v_mfma_f32_16x16x32_bf16 v[44:47], v[162:165], v[200:203], v[44:47]
	v_mfma_f32_16x16x32_bf16 v[40:43], v[176:179], v[200:203], v[40:43]
	v_mfma_f32_16x16x32_bf16 v[36:39], v[162:165], v[208:211], v[36:39]
	v_mfma_f32_16x16x32_bf16 v[32:35], v[176:179], v[208:211], v[32:35]
	s_setprio 0
	s_barrier
	s_add_i32 s79, s57, s7
	v_lshl_add_u64 v[144:145], s[14:15], 0, v[148:149]
	s_mov_b32 m0, s79
	ds_read_b128 v[180:183], v171 offset:16384
	ds_read_b128 v[184:187], v171 offset:17408
	ds_read_b128 v[188:191], v171 offset:18432
	ds_read_b128 v[192:195], v171 offset:19456
	ds_read_b128 v[196:199], v171 offset:20480
	ds_read_b128 v[200:203], v171 offset:21504
	ds_read_b128 v[204:207], v171 offset:22528
	ds_read_b128 v[208:211], v171 offset:23552
	global_load_lds_dwordx4 v[144:145], off
	s_add_i32 m0, s79, 0x2000
	s_add_u32 s80, s14, 0x40000
	v_lshl_add_u64 v[166:167], s[14:15], 0, v[152:153]
	s_addc_u32 s81, s15, 0
	s_add_i32 s79, s58, s7
	global_load_lds_dwordx4 v[166:167], off
	v_lshl_add_u64 v[212:213], s[80:81], 0, v[148:149]
	s_mov_b32 m0, s79
	v_lshl_add_u64 v[214:215], s[46:47], 0, v[150:151]
	global_load_lds_dwordx4 v[212:213], off
	v_lshl_add_u64 v[212:213], s[80:81], 0, v[152:153]
	s_add_i32 m0, s79, 0x2000
	s_nop 0
	global_load_lds_dwordx4 v[212:213], off
	v_lshl_add_u64 v[212:213], s[46:47], 0, v[146:147]
	s_mov_b32 m0, s45
	s_nop 0
	global_load_lds_dwordx4 v[212:213], off
	s_mov_b32 m0, s50
	s_nop 0
	global_load_lds_dwordx4 v[214:215], off
	s_waitcnt vmcnt(8)
	s_waitcnt lgkmcnt(0)
	s_barrier
	s_setprio 1
	v_mfma_f32_16x16x32_bf16 v[92:95], v[128:131], v[180:183], v[92:95]
	v_mfma_f32_16x16x32_bf16 v[88:91], v[136:139], v[180:183], v[88:91]
	v_mfma_f32_16x16x32_bf16 v[84:87], v[128:131], v[188:191], v[84:87]
	v_mfma_f32_16x16x32_bf16 v[80:83], v[136:139], v[188:191], v[80:83]
	v_mfma_f32_16x16x32_bf16 v[76:79], v[128:131], v[196:199], v[76:79]
	v_mfma_f32_16x16x32_bf16 v[72:75], v[136:139], v[196:199], v[72:75]
	v_mfma_f32_16x16x32_bf16 v[68:71], v[128:131], v[204:207], v[68:71]
	v_mfma_f32_16x16x32_bf16 v[64:67], v[136:139], v[204:207], v[64:67]
	v_mfma_f32_16x16x32_bf16 v[92:95], v[132:135], v[184:187], v[92:95]
	v_mfma_f32_16x16x32_bf16 v[88:91], v[140:143], v[184:187], v[88:91]
	v_mfma_f32_16x16x32_bf16 v[84:87], v[132:135], v[192:195], v[84:87]
	v_mfma_f32_16x16x32_bf16 v[80:83], v[140:143], v[192:195], v[80:83]
	v_mfma_f32_16x16x32_bf16 v[76:79], v[132:135], v[200:203], v[76:79]
	v_mfma_f32_16x16x32_bf16 v[72:75], v[140:143], v[200:203], v[72:75]
	v_mfma_f32_16x16x32_bf16 v[68:71], v[132:135], v[208:211], v[68:71]
	v_mfma_f32_16x16x32_bf16 v[64:67], v[140:143], v[208:211], v[64:67]
	s_setprio 0
	s_setprio 1
	v_mfma_f32_16x16x32_bf16 v[28:31], v[158:161], v[180:183], v[28:31]
	v_mfma_f32_16x16x32_bf16 v[24:27], v[172:175], v[180:183], v[24:27]
	v_mfma_f32_16x16x32_bf16 v[20:23], v[158:161], v[188:191], v[20:23]
	v_mfma_f32_16x16x32_bf16 v[16:19], v[172:175], v[188:191], v[16:19]
	v_mfma_f32_16x16x32_bf16 v[12:15], v[158:161], v[196:199], v[12:15]
	v_mfma_f32_16x16x32_bf16 v[8:11], v[172:175], v[196:199], v[8:11]
	v_mfma_f32_16x16x32_bf16 v[4:7], v[158:161], v[204:207], v[4:7]
	v_mfma_f32_16x16x32_bf16 v[0:3], v[172:175], v[204:207], v[0:3]
	v_mfma_f32_16x16x32_bf16 v[28:31], v[162:165], v[184:187], v[28:31]
	v_mfma_f32_16x16x32_bf16 v[24:27], v[176:179], v[184:187], v[24:27]
	v_mfma_f32_16x16x32_bf16 v[20:23], v[162:165], v[192:195], v[20:23]
	v_mfma_f32_16x16x32_bf16 v[16:19], v[176:179], v[192:195], v[16:19]
	v_mfma_f32_16x16x32_bf16 v[12:15], v[162:165], v[200:203], v[12:15]
	v_mfma_f32_16x16x32_bf16 v[8:11], v[176:179], v[200:203], v[8:11]
	v_mfma_f32_16x16x32_bf16 v[4:7], v[162:165], v[208:211], v[4:7]
	v_mfma_f32_16x16x32_bf16 v[0:3], v[176:179], v[208:211], v[0:3]
	s_setprio 0
	s_barrier
; #define G_STAGE(bufoff, gbase, voff) do { _Pragma("unroll") for (int _i = 0; _i < 2; ++_i) \
;         __builtin_amdgcn_global_load_lds((const unsigned*)((const char*)(gbase) + voff[_i]), (LAS unsigned*)(lds + (bufoff) + ldsw + _i * 8192), 16, 0, 0); } while (0)
; #define G_LDA(dst, b, h) do { _Pragma("unroll") for (int m = 0; m < 4; ++m) _Pragma("unroll") for (int k = 0; k < 2; ++k) dst[m][k] = *(const LAS bf16x8*)(lds + G_SA(b, h) + aoff + m * 2048 + k * 1024); } while (0)
; #define G_LDB(dst, b, h) do { _Pragma("unroll") for (int n = 0; n < 2; ++n) _Pragma("unroll") for (int k = 0; k < 2; ++k) dst[n][k] = *(const LAS bf16x8*)(lds + G_SB(b, h) + boff + n * 2048 + k * 1024); } while (0)
; #define G_MMA(ai, bj, At_, Bt_) do { __builtin_amdgcn_s_setprio(1); _Pragma("unroll") for (int m = 0; m < 4; ++m) _Pragma("unroll") for (int n = 0; n < 2; ++n) _Pragma("unroll") for (int k = 0; k < 2; ++k) \
;         acc[ai][bj][m][n] = __builtin_amdgcn_mfma_f32_16x16x32_bf16(Bt_[n][k], At_[m][k], acc[ai][bj][m][n], 0, 0, 0); __builtin_amdgcn_s_setprio(0); } while (0)
; #define WAIT_V(n) asm volatile("s_waitcnt vmcnt(" #n ")" ::: "memory")
; #define WAIT_L(n) asm volatile("s_waitcnt lgkmcnt(" #n ")" ::: "memory")
; #define BAR __builtin_amdgcn_s_barrier()
; #define SCHED __builtin_amdgcn_sched_barrier(0)
; template <class Get, class Epi>
; DI void gemm_loop(int ntiles, int ld, char* shm, const Get& get, const Epi& epi) {
;     ...
;             G_LDB(B0, 1, 0); G_LDB(B1, 1, 1); SCHED; G_LDA(At, 1, 0); G_STAGE(G_SA(0, 1), a2 + hstep, voffA);
;             WAIT_V(8); WAIT_L(0); BAR; G_MMA(0, 0, At, B0); G_MMA(0, 1, At, B1); BAR; SCHED;
	s_add_i32 s79, 0, 0x18000
	s_add_i32 s80, 0, 0x1c000
	v_add_u32_e32 v140, s79, v168
	v_add_u32_e32 v176, s80, v168
	ds_read_b128 v[128:131], v140
	ds_read_b128 v[132:135], v140 offset:1024
	ds_read_b128 v[136:139], v140 offset:2048
	ds_read_b128 v[140:143], v140 offset:3072
	ds_read_b128 v[158:161], v176
	ds_read_b128 v[162:165], v176 offset:1024
	ds_read_b128 v[172:175], v176 offset:2048
	ds_read_b128 v[176:179], v176 offset:3072
	s_add_u32 s46, s46, 0x40000
	s_addc_u32 s47, s47, 0
	s_mov_b32 m0, s51
	v_lshl_add_u64 v[216:217], s[46:47], 0, v[146:147]
	ds_read_b128 v[180:183], v171 offset:32768
	ds_read_b128 v[184:187], v171 offset:33792
	ds_read_b128 v[188:191], v171 offset:34816
	ds_read_b128 v[192:195], v171 offset:35840
	ds_read_b128 v[196:199], v171 offset:36864
	ds_read_b128 v[200:203], v171 offset:37888
	ds_read_b128 v[204:207], v171 offset:38912
	ds_read_b128 v[208:211], v171 offset:39936
	global_load_lds_dwordx4 v[216:217], off
	v_lshl_add_u64 v[216:217], s[46:47], 0, v[150:151]
	s_mov_b32 m0, s52
	s_nop 0
	global_load_lds_dwordx4 v[216:217], off
	s_waitcnt vmcnt(8)
	s_waitcnt lgkmcnt(0)
	s_barrier
	s_setprio 1
	v_mfma_f32_16x16x32_bf16 v[124:127], v[128:131], v[180:183], v[124:127]
	v_mfma_f32_16x16x32_bf16 v[120:123], v[136:139], v[180:183], v[120:123]
	v_mfma_f32_16x16x32_bf16 v[116:119], v[128:131], v[188:191], v[116:119]
	v_mfma_f32_16x16x32_bf16 v[112:115], v[136:139], v[188:191], v[112:115]
	v_mfma_f32_16x16x32_bf16 v[108:111], v[128:131], v[196:199], v[108:111]
	v_mfma_f32_16x16x32_bf16 v[104:107], v[136:139], v[196:199], v[104:107]
	v_mfma_f32_16x16x32_bf16 v[100:103], v[128:131], v[204:207], v[100:103]
	v_mfma_f32_16x16x32_bf16 v[96:99], v[136:139], v[204:207], v[96:99]
	v_mfma_f32_16x16x32_bf16 v[124:127], v[132:135], v[184:187], v[124:127]
	v_mfma_f32_16x16x32_bf16 v[120:123], v[140:143], v[184:187], v[120:123]
	v_mfma_f32_16x16x32_bf16 v[116:119], v[132:135], v[192:195], v[116:119]
	v_mfma_f32_16x16x32_bf16 v[112:115], v[140:143], v[192:195], v[112:115]
	v_mfma_f32_16x16x32_bf16 v[108:111], v[132:135], v[200:203], v[108:111]
	v_mfma_f32_16x16x32_bf16 v[104:107], v[140:143], v[200:203], v[104:107]
	v_mfma_f32_16x16x32_bf16 v[100:103], v[132:135], v[208:211], v[100:103]
	v_mfma_f32_16x16x32_bf16 v[96:99], v[140:143], v[208:211], v[96:99]
	s_setprio 0
	s_setprio 1
	v_mfma_f32_16x16x32_bf16 v[60:63], v[158:161], v[180:183], v[60:63]
	v_mfma_f32_16x16x32_bf16 v[56:59], v[172:175], v[180:183], v[56:59]
	v_mfma_f32_16x16x32_bf16 v[52:55], v[158:161], v[188:191], v[52:55]
	v_mfma_f32_16x16x32_bf16 v[48:51], v[172:175], v[188:191], v[48:51]
	v_mfma_f32_16x16x32_bf16 v[44:47], v[158:161], v[196:199], v[44:47]
	v_mfma_f32_16x16x32_bf16 v[40:43], v[172:175], v[196:199], v[40:43]
	v_mfma_f32_16x16x32_bf16 v[36:39], v[158:161], v[204:207], v[36:39]
	v_mfma_f32_16x16x32_bf16 v[32:35], v[172:175], v[204:207], v[32:35]
	v_mfma_f32_16x16x32_bf16 v[60:63], v[162:165], v[184:187], v[60:63]
	v_mfma_f32_16x16x32_bf16 v[56:59], v[176:179], v[184:187], v[56:59]
	v_mfma_f32_16x16x32_bf16 v[52:55], v[162:165], v[192:195], v[52:55]
	v_mfma_f32_16x16x32_bf16 v[48:51], v[176:179], v[192:195], v[48:51]
	v_mfma_f32_16x16x32_bf16 v[44:47], v[162:165], v[200:203], v[44:47]
	v_mfma_f32_16x16x32_bf16 v[40:43], v[176:179], v[200:203], v[40:43]
	v_mfma_f32_16x16x32_bf16 v[36:39], v[162:165], v[208:211], v[36:39]
	v_mfma_f32_16x16x32_bf16 v[32:35], v[176:179], v[208:211], v[32:35]
	s_setprio 0
	s_barrier
; #define G_STAGE(bufoff, gbase, voff) do { _Pragma("unroll") for (int _i = 0; _i < 2; ++_i) \
;         __builtin_amdgcn_global_load_lds((const unsigned*)((const char*)(gbase) + voff[_i]), (LAS unsigned*)(lds + (bufoff) + ldsw + _i * 8192), 16, 0, 0); } while (0)
; #define G_LDA(dst, b, h) do { _Pragma("unroll") for (int m = 0; m < 4; ++m) _Pragma("unroll") for (int k = 0; k < 2; ++k) dst[m][k] = *(const LAS bf16x8*)(lds + G_SA(b, h) + aoff + m * 2048 + k * 1024); } while (0)
; #define G_MMA(ai, bj, At_, Bt_) do { __builtin_amdgcn_s_setprio(1); _Pragma("unroll") for (int m = 0; m < 4; ++m) _Pragma("unroll") for (int n = 0; n < 2; ++n) _Pragma("unroll") for (int k = 0; k < 2; ++k) \
;         acc[ai][bj][m][n] = __builtin_amdgcn_mfma_f32_16x16x32_bf16(Bt_[n][k], At_[m][k], acc[ai][bj][m][n], 0, 0, 0); __builtin_amdgcn_s_setprio(0); } while (0)
; #define WAIT_V(n) asm volatile("s_waitcnt vmcnt(" #n ")" ::: "memory")
; #define WAIT_L(n) asm volatile("s_waitcnt lgkmcnt(" #n ")" ::: "memory")
; #define BAR __builtin_amdgcn_s_barrier()
; #define SCHED __builtin_amdgcn_sched_barrier(0)
; template <class Get, class Epi>
; DI void gemm_loop(int ntiles, int ld, char* shm, const Get& get, const Epi& epi) {
;     ...
;             G_LDA(At, 1, 1); G_STAGE(G_SB(1, 0), b3, voffB); G_STAGE(G_SB(1, 1), b3 + hstep, voffB); G_STAGE(G_SA(1, 0), a3, voffA);
;             WAIT_V(8); WAIT_L(0); BAR; G_MMA(1, 0, At, B0); G_MMA(1, 1, At, B1); BAR; SCHED;
	s_add_i32 s46, s79, s7
	v_lshl_add_u64 v[144:145], v[144:145], 0, s[10:11]
	s_mov_b32 m0, s46
	ds_read_b128 v[180:183], v171 offset:49152
	ds_read_b128 v[184:187], v171 offset:50176
	ds_read_b128 v[188:191], v171 offset:51200
	ds_read_b128 v[192:195], v171 offset:52224
	ds_read_b128 v[196:199], v171 offset:53248
	ds_read_b128 v[200:203], v171 offset:54272
	ds_read_b128 v[204:207], v171 offset:55296
	ds_read_b128 v[208:211], v171 offset:56320
	global_load_lds_dwordx4 v[144:145], off
	s_add_i32 m0, s46, 0x2000
	s_add_u32 s14, s14, 0x40080
	v_lshl_add_u64 v[144:145], v[166:167], 0, s[10:11]
	s_addc_u32 s15, s15, 0
	s_add_i32 s46, s80, s7
	global_load_lds_dwordx4 v[144:145], off
	v_lshl_add_u64 v[144:145], s[14:15], 0, v[148:149]
	s_mov_b32 m0, s46
	s_nop 0
	global_load_lds_dwordx4 v[144:145], off
	v_lshl_add_u64 v[144:145], s[14:15], 0, v[152:153]
	s_add_i32 m0, s46, 0x2000
	s_nop 0
	global_load_lds_dwordx4 v[144:145], off
	v_lshl_add_u64 v[144:145], v[212:213], 0, s[10:11]
	s_mov_b32 m0, s55
	s_nop 0
	global_load_lds_dwordx4 v[144:145], off
	v_lshl_add_u64 v[144:145], v[214:215], 0, s[10:11]
	s_mov_b32 m0, s56
	s_nop 0
	global_load_lds_dwordx4 v[144:145], off
	s_waitcnt vmcnt(8)
	s_waitcnt lgkmcnt(0)
	s_barrier
	s_setprio 1
	v_mfma_f32_16x16x32_bf16 v[92:95], v[128:131], v[180:183], v[92:95]
	v_mfma_f32_16x16x32_bf16 v[88:91], v[136:139], v[180:183], v[88:91]
	v_mfma_f32_16x16x32_bf16 v[84:87], v[128:131], v[188:191], v[84:87]
	v_mfma_f32_16x16x32_bf16 v[80:83], v[136:139], v[188:191], v[80:83]
	v_mfma_f32_16x16x32_bf16 v[76:79], v[128:131], v[196:199], v[76:79]
	v_mfma_f32_16x16x32_bf16 v[72:75], v[136:139], v[196:199], v[72:75]
	v_mfma_f32_16x16x32_bf16 v[68:71], v[128:131], v[204:207], v[68:71]
	v_mfma_f32_16x16x32_bf16 v[64:67], v[136:139], v[204:207], v[64:67]
	v_mfma_f32_16x16x32_bf16 v[92:95], v[132:135], v[184:187], v[92:95]
	v_mfma_f32_16x16x32_bf16 v[88:91], v[140:143], v[184:187], v[88:91]
	v_mfma_f32_16x16x32_bf16 v[84:87], v[132:135], v[192:195], v[84:87]
	v_mfma_f32_16x16x32_bf16 v[80:83], v[140:143], v[192:195], v[80:83]
	v_mfma_f32_16x16x32_bf16 v[76:79], v[132:135], v[200:203], v[76:79]
	v_mfma_f32_16x16x32_bf16 v[72:75], v[140:143], v[200:203], v[72:75]
	v_mfma_f32_16x16x32_bf16 v[68:71], v[132:135], v[208:211], v[68:71]
	v_mfma_f32_16x16x32_bf16 v[64:67], v[140:143], v[208:211], v[64:67]
	s_setprio 0
	s_setprio 1
	v_mfma_f32_16x16x32_bf16 v[28:31], v[158:161], v[180:183], v[28:31]
	v_mfma_f32_16x16x32_bf16 v[24:27], v[172:175], v[180:183], v[24:27]
	v_mfma_f32_16x16x32_bf16 v[20:23], v[158:161], v[188:191], v[20:23]
	v_mfma_f32_16x16x32_bf16 v[16:19], v[172:175], v[188:191], v[16:19]
	v_mfma_f32_16x16x32_bf16 v[12:15], v[158:161], v[196:199], v[12:15]
	v_mfma_f32_16x16x32_bf16 v[8:11], v[172:175], v[196:199], v[8:11]
	v_mfma_f32_16x16x32_bf16 v[4:7], v[158:161], v[204:207], v[4:7]
	v_mfma_f32_16x16x32_bf16 v[0:3], v[172:175], v[204:207], v[0:3]
	v_mfma_f32_16x16x32_bf16 v[28:31], v[162:165], v[184:187], v[28:31]
	v_mfma_f32_16x16x32_bf16 v[24:27], v[176:179], v[184:187], v[24:27]
	v_mfma_f32_16x16x32_bf16 v[20:23], v[162:165], v[192:195], v[20:23]
	v_mfma_f32_16x16x32_bf16 v[16:19], v[176:179], v[192:195], v[16:19]
	v_mfma_f32_16x16x32_bf16 v[12:15], v[162:165], v[200:203], v[12:15]
	v_mfma_f32_16x16x32_bf16 v[8:11], v[176:179], v[200:203], v[8:11]
	v_mfma_f32_16x16x32_bf16 v[4:7], v[162:165], v[208:211], v[4:7]
	v_mfma_f32_16x16x32_bf16 v[0:3], v[176:179], v[208:211], v[0:3]
	s_setprio 0
	s_barrier
	s_add_u32 s48, s48, 0x100
	s_addc_u32 s49, s49, 0
	s_add_u32 s76, s76, 0x100
	s_addc_u32 s77, s77, 0
	s_cmp_ge_u32 s78, s74
	s_mov_b32 s14, s78
	s_cbranch_scc0 .LBB0_1463

; #define G_STAGE(bufoff, gbase, voff) do { _Pragma("unroll") for (int _i = 0; _i < 2; ++_i) \
;         __builtin_amdgcn_global_load_lds((const unsigned*)((const char*)(gbase) + voff[_i]), (LAS unsigned*)(lds + (bufoff) + ldsw + _i * 8192), 16, 0, 0); } while (0)
; #define G_LDA(dst, b, h) do { _Pragma("unroll") for (int m = 0; m < 4; ++m) _Pragma("unroll") for (int k = 0; k < 2; ++k) dst[m][k] = *(const LAS bf16x8*)(lds + G_SA(b, h) + aoff + m * 2048 + k * 1024); } while (0)
; #define G_MMA(ai, bj, At_, Bt_) do { __builtin_amdgcn_s_setprio(1); _Pragma("unroll") for (int m = 0; m < 4; ++m) _Pragma("unroll") for (int n = 0; n < 2; ++n) _Pragma("unroll") for (int k = 0; k < 2; ++k) \
;         acc[ai][bj][m][n] = __builtin_amdgcn_mfma_f32_16x16x32_bf16(Bt_[n][k], At_[m][k], acc[ai][bj][m][n], 0, 0, 0); __builtin_amdgcn_s_setprio(0); } while (0)
; #define WAIT_V(n) asm volatile("s_waitcnt vmcnt(" #n ")" ::: "memory")
; #define WAIT_L(n) asm volatile("s_waitcnt lgkmcnt(" #n ")" ::: "memory")
; #define BAR __builtin_amdgcn_s_barrier()
; #define SCHED __builtin_amdgcn_sched_barrier(0)
; template <class Get, class Epi>
; DI void gemm_loop(int ntiles, int ld, char* shm, const Get& get, const Epi& epi) {
;     ...
;             WAIT_V(8); WAIT_L(0); BAR; G_MMA(0, 0, At, B0); G_MMA(0, 1, At, B1); BAR; SCHED;
;             G_LDA(At, 0, 1); G_STAGE(G_SB(0, 0), b2, voffB); G_STAGE(G_SB(0, 1), b2 + hstep, voffB); G_STAGE(G_SA(0, 0), a2, voffA);
.Lrj_1694_0:
	s_waitcnt lgkmcnt(0)
	s_barrier
	s_setprio 1
	v_mfma_f32_16x16x32_bf16 v[124:127], v[144:147], v[176:179], 0
	v_mfma_f32_16x16x32_bf16 v[120:123], v[152:155], v[176:179], 0
	v_mfma_f32_16x16x32_bf16 v[108:111], v[144:147], v[184:187], 0
	v_mfma_f32_16x16x32_bf16 v[104:107], v[152:155], v[184:187], 0
	v_mfma_f32_16x16x32_bf16 v[92:95], v[144:147], v[192:195], 0
	v_mfma_f32_16x16x32_bf16 v[88:91], v[152:155], v[192:195], 0
	v_mfma_f32_16x16x32_bf16 v[76:79], v[144:147], v[200:203], 0
	v_mfma_f32_16x16x32_bf16 v[72:75], v[152:155], v[200:203], 0
	v_mfma_f32_16x16x32_bf16 v[124:127], v[148:151], v[180:183], v[124:127]
	v_mfma_f32_16x16x32_bf16 v[120:123], v[156:159], v[180:183], v[120:123]
	v_mfma_f32_16x16x32_bf16 v[108:111], v[148:151], v[188:191], v[108:111]
	v_mfma_f32_16x16x32_bf16 v[104:107], v[156:159], v[188:191], v[104:107]
	v_mfma_f32_16x16x32_bf16 v[92:95], v[148:151], v[196:199], v[92:95]
	v_mfma_f32_16x16x32_bf16 v[88:91], v[156:159], v[196:199], v[88:91]
	v_mfma_f32_16x16x32_bf16 v[76:79], v[148:151], v[204:207], v[76:79]
	v_mfma_f32_16x16x32_bf16 v[72:75], v[156:159], v[204:207], v[72:75]
	s_setprio 0
	s_setprio 1
	v_mfma_f32_16x16x32_bf16 v[116:119], v[160:163], v[176:179], 0
	v_mfma_f32_16x16x32_bf16 v[112:115], v[168:171], v[176:179], 0
	v_mfma_f32_16x16x32_bf16 v[100:103], v[160:163], v[184:187], 0
	v_mfma_f32_16x16x32_bf16 v[96:99], v[168:171], v[184:187], 0
	v_mfma_f32_16x16x32_bf16 v[84:87], v[160:163], v[192:195], 0
	v_mfma_f32_16x16x32_bf16 v[80:83], v[168:171], v[192:195], 0
	v_mfma_f32_16x16x32_bf16 v[68:71], v[160:163], v[200:203], 0
	v_mfma_f32_16x16x32_bf16 v[64:67], v[168:171], v[200:203], 0
	v_mfma_f32_16x16x32_bf16 v[116:119], v[164:167], v[180:183], v[116:119]
	v_mfma_f32_16x16x32_bf16 v[112:115], v[172:175], v[180:183], v[112:115]
	v_mfma_f32_16x16x32_bf16 v[100:103], v[164:167], v[188:191], v[100:103]
	v_mfma_f32_16x16x32_bf16 v[96:99], v[172:175], v[188:191], v[96:99]
	v_mfma_f32_16x16x32_bf16 v[84:87], v[164:167], v[196:199], v[84:87]
	v_mfma_f32_16x16x32_bf16 v[80:83], v[172:175], v[196:199], v[80:83]
	v_mfma_f32_16x16x32_bf16 v[68:71], v[164:167], v[204:207], v[68:71]
	v_mfma_f32_16x16x32_bf16 v[64:67], v[172:175], v[204:207], v[64:67]
	s_setprio 0
	s_barrier
	s_add_i32 s58, s48, s42
	v_lshl_add_u64 v[208:209], s[14:15], 0, v[132:133]
	s_mov_b32 m0, s58
	ds_read_b128 v[176:179], v143 offset:16384
	ds_read_b128 v[180:183], v143 offset:17408
	ds_read_b128 v[184:187], v143 offset:18432
	ds_read_b128 v[188:191], v143 offset:19456
	ds_read_b128 v[192:195], v143 offset:20480
	ds_read_b128 v[196:199], v143 offset:21504
	ds_read_b128 v[200:203], v143 offset:22528
	ds_read_b128 v[204:207], v143 offset:23552
	global_load_lds_dwordx4 v[208:209], off
	s_add_i32 m0, s58, 0x2000
	s_add_u32 s58, s14, 0x40000
	v_lshl_add_u64 v[210:211], s[14:15], 0, v[128:129]
	s_addc_u32 s59, s15, 0
	s_add_i32 s71, s49, s42
	global_load_lds_dwordx4 v[210:211], off
	v_lshl_add_u64 v[212:213], s[58:59], 0, v[132:133]
	s_mov_b32 m0, s71
	v_lshl_add_u64 v[214:215], s[40:41], 0, v[130:131]
	global_load_lds_dwordx4 v[212:213], off
	v_lshl_add_u64 v[212:213], s[58:59], 0, v[128:129]
	s_add_i32 m0, s71, 0x2000
	s_nop 0
	global_load_lds_dwordx4 v[212:213], off
	v_lshl_add_u64 v[212:213], s[40:41], 0, v[134:135]
	s_mov_b32 m0, s35
	s_nop 0
	global_load_lds_dwordx4 v[212:213], off
	s_mov_b32 m0, s37
	s_nop 0
	global_load_lds_dwordx4 v[214:215], off
	s_cmp_lg_u32 s100, 0
	s_cbranch_scc0 .Lrf_1694_1
	s_waitcnt vmcnt(16)
	s_branch .Lrj_1694_1

; #define G_STAGE(bufoff, gbase, voff) do { _Pragma("unroll") for (int _i = 0; _i < 2; ++_i) \
;         __builtin_amdgcn_global_load_lds((const unsigned*)((const char*)(gbase) + voff[_i]), (LAS unsigned*)(lds + (bufoff) + ldsw + _i * 8192), 16, 0, 0); } while (0)
; #define G_LDA(dst, b, h) do { _Pragma("unroll") for (int m = 0; m < 4; ++m) _Pragma("unroll") for (int k = 0; k < 2; ++k) dst[m][k] = *(const LAS bf16x8*)(lds + G_SA(b, h) + aoff + m * 2048 + k * 1024); } while (0)
; #define G_LDB(dst, b, h) do { _Pragma("unroll") for (int n = 0; n < 2; ++n) _Pragma("unroll") for (int k = 0; k < 2; ++k) dst[n][k] = *(const LAS bf16x8*)(lds + G_SB(b, h) + boff + n * 2048 + k * 1024); } while (0)
; #define G_MMA(ai, bj, At_, Bt_) do { __builtin_amdgcn_s_setprio(1); _Pragma("unroll") for (int m = 0; m < 4; ++m) _Pragma("unroll") for (int n = 0; n < 2; ++n) _Pragma("unroll") for (int k = 0; k < 2; ++k) \
;         acc[ai][bj][m][n] = __builtin_amdgcn_mfma_f32_16x16x32_bf16(Bt_[n][k], At_[m][k], acc[ai][bj][m][n], 0, 0, 0); __builtin_amdgcn_s_setprio(0); } while (0)
; #define WAIT_V(n) asm volatile("s_waitcnt vmcnt(" #n ")" ::: "memory")
; #define WAIT_L(n) asm volatile("s_waitcnt lgkmcnt(" #n ")" ::: "memory")
; #define BAR __builtin_amdgcn_s_barrier()
; #define SCHED __builtin_amdgcn_sched_barrier(0)
; template <class Get, class Epi>
; DI void gemm_loop(int ntiles, int ld, char* shm, const Get& get, const Epi& epi) {
;     ...
;             WAIT_V(8); WAIT_L(0); BAR; G_MMA(1, 0, At, B0); G_MMA(1, 1, At, B1); BAR; SCHED;
;             G_LDB(B0, 1, 0); G_LDB(B1, 1, 1); SCHED; G_LDA(At, 1, 0); G_STAGE(G_SA(0, 1), a2 + hstep, voffA);
;             WAIT_V(8); WAIT_L(0); BAR; G_MMA(0, 0, At, B0); G_MMA(0, 1, At, B1); BAR; SCHED;
.Lrj_1694_1:
	s_waitcnt lgkmcnt(0)
	s_barrier
	s_setprio 1
	v_mfma_f32_16x16x32_bf16 v[60:63], v[144:147], v[176:179], 0
	v_mfma_f32_16x16x32_bf16 v[56:59], v[152:155], v[176:179], 0
	v_mfma_f32_16x16x32_bf16 v[44:47], v[144:147], v[184:187], 0
	v_mfma_f32_16x16x32_bf16 v[40:43], v[152:155], v[184:187], 0
	v_mfma_f32_16x16x32_bf16 v[28:31], v[144:147], v[192:195], 0
	v_mfma_f32_16x16x32_bf16 v[24:27], v[152:155], v[192:195], 0
	v_mfma_f32_16x16x32_bf16 v[12:15], v[144:147], v[200:203], 0
	v_mfma_f32_16x16x32_bf16 v[8:11], v[152:155], v[200:203], 0
	v_mfma_f32_16x16x32_bf16 v[60:63], v[148:151], v[180:183], v[60:63]
	v_mfma_f32_16x16x32_bf16 v[56:59], v[156:159], v[180:183], v[56:59]
	v_mfma_f32_16x16x32_bf16 v[44:47], v[148:151], v[188:191], v[44:47]
	v_mfma_f32_16x16x32_bf16 v[40:43], v[156:159], v[188:191], v[40:43]
	v_mfma_f32_16x16x32_bf16 v[28:31], v[148:151], v[196:199], v[28:31]
	v_mfma_f32_16x16x32_bf16 v[24:27], v[156:159], v[196:199], v[24:27]
	v_mfma_f32_16x16x32_bf16 v[12:15], v[148:151], v[204:207], v[12:15]
	v_mfma_f32_16x16x32_bf16 v[8:11], v[156:159], v[204:207], v[8:11]
	s_setprio 0
	s_setprio 1
	v_mfma_f32_16x16x32_bf16 v[52:55], v[160:163], v[176:179], 0
	v_mfma_f32_16x16x32_bf16 v[48:51], v[168:171], v[176:179], 0
	v_mfma_f32_16x16x32_bf16 v[36:39], v[160:163], v[184:187], 0
	v_mfma_f32_16x16x32_bf16 v[32:35], v[168:171], v[184:187], 0
	v_mfma_f32_16x16x32_bf16 v[20:23], v[160:163], v[192:195], 0
	v_mfma_f32_16x16x32_bf16 v[16:19], v[168:171], v[192:195], 0
	v_mfma_f32_16x16x32_bf16 v[4:7], v[160:163], v[200:203], 0
	v_mfma_f32_16x16x32_bf16 v[0:3], v[168:171], v[200:203], 0
	v_mfma_f32_16x16x32_bf16 v[52:55], v[164:167], v[180:183], v[52:55]
	v_mfma_f32_16x16x32_bf16 v[48:51], v[172:175], v[180:183], v[48:51]
	v_mfma_f32_16x16x32_bf16 v[36:39], v[164:167], v[188:191], v[36:39]
	v_mfma_f32_16x16x32_bf16 v[32:35], v[172:175], v[188:191], v[32:35]
	v_mfma_f32_16x16x32_bf16 v[20:23], v[164:167], v[196:199], v[20:23]
	v_mfma_f32_16x16x32_bf16 v[16:19], v[172:175], v[196:199], v[16:19]
	v_mfma_f32_16x16x32_bf16 v[4:7], v[164:167], v[204:207], v[4:7]
	v_mfma_f32_16x16x32_bf16 v[0:3], v[172:175], v[204:207], v[0:3]
	s_setprio 0
	s_barrier
	s_add_i32 s58, 0, 0x18000
	s_add_i32 s59, 0, 0x1c000
	v_add_u32_e32 v156, s58, v140
	v_add_u32_e32 v172, s59, v140
	ds_read_b128 v[144:147], v156
	ds_read_b128 v[148:151], v156 offset:1024
	ds_read_b128 v[152:155], v156 offset:2048
	ds_read_b128 v[156:159], v156 offset:3072
	ds_read_b128 v[160:163], v172
	ds_read_b128 v[164:167], v172 offset:1024
	ds_read_b128 v[168:171], v172 offset:2048
	ds_read_b128 v[172:175], v172 offset:3072
	s_add_u32 s40, s40, 0x40000
	s_addc_u32 s41, s41, 0
	s_mov_b32 m0, s44
	v_lshl_add_u64 v[216:217], s[40:41], 0, v[134:135]
	ds_read_b128 v[176:179], v143 offset:32768
	ds_read_b128 v[180:183], v143 offset:33792
	ds_read_b128 v[184:187], v143 offset:34816
	ds_read_b128 v[188:191], v143 offset:35840
	ds_read_b128 v[192:195], v143 offset:36864
	ds_read_b128 v[196:199], v143 offset:37888
	ds_read_b128 v[200:203], v143 offset:38912
	ds_read_b128 v[204:207], v143 offset:39936
	global_load_lds_dwordx4 v[216:217], off
	v_lshl_add_u64 v[216:217], s[40:41], 0, v[130:131]
	s_mov_b32 m0, s45
	s_nop 0
	global_load_lds_dwordx4 v[216:217], off
	s_waitcnt vmcnt(8)
	s_waitcnt lgkmcnt(0)
	s_barrier
	s_setprio 1
	v_mfma_f32_16x16x32_bf16 v[124:127], v[144:147], v[176:179], v[124:127]
	v_mfma_f32_16x16x32_bf16 v[120:123], v[152:155], v[176:179], v[120:123]
	v_mfma_f32_16x16x32_bf16 v[108:111], v[144:147], v[184:187], v[108:111]
	v_mfma_f32_16x16x32_bf16 v[104:107], v[152:155], v[184:187], v[104:107]
	v_mfma_f32_16x16x32_bf16 v[92:95], v[144:147], v[192:195], v[92:95]
	v_mfma_f32_16x16x32_bf16 v[88:91], v[152:155], v[192:195], v[88:91]
	v_mfma_f32_16x16x32_bf16 v[76:79], v[144:147], v[200:203], v[76:79]
	v_mfma_f32_16x16x32_bf16 v[72:75], v[152:155], v[200:203], v[72:75]
	v_mfma_f32_16x16x32_bf16 v[124:127], v[148:151], v[180:183], v[124:127]
	v_mfma_f32_16x16x32_bf16 v[120:123], v[156:159], v[180:183], v[120:123]
	v_mfma_f32_16x16x32_bf16 v[108:111], v[148:151], v[188:191], v[108:111]
	v_mfma_f32_16x16x32_bf16 v[104:107], v[156:159], v[188:191], v[104:107]
	v_mfma_f32_16x16x32_bf16 v[92:95], v[148:151], v[196:199], v[92:95]
	v_mfma_f32_16x16x32_bf16 v[88:91], v[156:159], v[196:199], v[88:91]
	v_mfma_f32_16x16x32_bf16 v[76:79], v[148:151], v[204:207], v[76:79]
	v_mfma_f32_16x16x32_bf16 v[72:75], v[156:159], v[204:207], v[72:75]
	s_setprio 0
	s_setprio 1
	v_mfma_f32_16x16x32_bf16 v[116:119], v[160:163], v[176:179], v[116:119]
	v_mfma_f32_16x16x32_bf16 v[112:115], v[168:171], v[176:179], v[112:115]
	v_mfma_f32_16x16x32_bf16 v[100:103], v[160:163], v[184:187], v[100:103]
	v_mfma_f32_16x16x32_bf16 v[96:99], v[168:171], v[184:187], v[96:99]
	v_mfma_f32_16x16x32_bf16 v[84:87], v[160:163], v[192:195], v[84:87]
	v_mfma_f32_16x16x32_bf16 v[80:83], v[168:171], v[192:195], v[80:83]
	v_mfma_f32_16x16x32_bf16 v[68:71], v[160:163], v[200:203], v[68:71]
	v_mfma_f32_16x16x32_bf16 v[64:67], v[168:171], v[200:203], v[64:67]
	v_mfma_f32_16x16x32_bf16 v[116:119], v[164:167], v[180:183], v[116:119]
	v_mfma_f32_16x16x32_bf16 v[112:115], v[172:175], v[180:183], v[112:115]
	v_mfma_f32_16x16x32_bf16 v[100:103], v[164:167], v[188:191], v[100:103]
	v_mfma_f32_16x16x32_bf16 v[96:99], v[172:175], v[188:191], v[96:99]
	v_mfma_f32_16x16x32_bf16 v[84:87], v[164:167], v[196:199], v[84:87]
	v_mfma_f32_16x16x32_bf16 v[80:83], v[172:175], v[196:199], v[80:83]
	v_mfma_f32_16x16x32_bf16 v[68:71], v[164:167], v[204:207], v[68:71]
	v_mfma_f32_16x16x32_bf16 v[64:67], v[172:175], v[204:207], v[64:67]
	s_setprio 0
	s_barrier
; #define G_STAGE(bufoff, gbase, voff) do { _Pragma("unroll") for (int _i = 0; _i < 2; ++_i) \
;         __builtin_amdgcn_global_load_lds((const unsigned*)((const char*)(gbase) + voff[_i]), (LAS unsigned*)(lds + (bufoff) + ldsw + _i * 8192), 16, 0, 0); } while (0)
; #define G_LDA(dst, b, h) do { _Pragma("unroll") for (int m = 0; m < 4; ++m) _Pragma("unroll") for (int k = 0; k < 2; ++k) dst[m][k] = *(const LAS bf16x8*)(lds + G_SA(b, h) + aoff + m * 2048 + k * 1024); } while (0)
; #define G_LDB(dst, b, h) do { _Pragma("unroll") for (int n = 0; n < 2; ++n) _Pragma("unroll") for (int k = 0; k < 2; ++k) dst[n][k] = *(const LAS bf16x8*)(lds + G_SB(b, h) + boff + n * 2048 + k * 1024); } while (0)
; #define G_MMA(ai, bj, At_, Bt_) do { __builtin_amdgcn_s_setprio(1); _Pragma("unroll") for (int m = 0; m < 4; ++m) _Pragma("unroll") for (int n = 0; n < 2; ++n) _Pragma("unroll") for (int k = 0; k < 2; ++k) \
;         acc[ai][bj][m][n] = __builtin_amdgcn_mfma_f32_16x16x32_bf16(Bt_[n][k], At_[m][k], acc[ai][bj][m][n], 0, 0, 0); __builtin_amdgcn_s_setprio(0); } while (0)
; #define WAIT_V(n) asm volatile("s_waitcnt vmcnt(" #n ")" ::: "memory")
; #define WAIT_L(n) asm volatile("s_waitcnt lgkmcnt(" #n ")" ::: "memory")
; #define BAR __builtin_amdgcn_s_barrier()
; #define SCHED __builtin_amdgcn_sched_barrier(0)
; template <class Get, class Epi>
; DI void gemm_loop(int ntiles, int ld, char* shm, const Get& get, const Epi& epi) {
;     ...
;             const char* a2 = last ? nA : cA + (size_t)(t + 2) * kstep; const char* b2 = last ? nB : cB + (size_t)(t + 2) * kstep;
;             const char* a3 = a2 + kstep; const char* b3 = b2 + kstep;
;             G_LDB(B0, 0, 0); G_LDB(B1, 0, 1); SCHED; G_LDA(At, 0, 0); G_STAGE(G_SA(1, 1), a1 + hstep, voffA);
;             WAIT_V(8); WAIT_L(0); BAR; G_MMA(0, 0, At, B0); G_MMA(0, 1, At, B1); BAR; SCHED;
;     ...
;             G_LDA(At, 1, 1); G_STAGE(G_SB(1, 0), b3, voffB); G_STAGE(G_SB(1, 1), b3 + hstep, voffB); G_STAGE(G_SA(1, 0), a3, voffA);
;             WAIT_V(8); WAIT_L(0); BAR; G_MMA(1, 0, At, B0); G_MMA(1, 1, At, B1); BAR; SCHED;
	s_add_i32 s40, s58, s42
	v_lshl_add_u64 v[208:209], v[208:209], 0, s[2:3]
	s_mov_b32 m0, s40
	ds_read_b128 v[176:179], v143 offset:49152
	ds_read_b128 v[180:183], v143 offset:50176
	ds_read_b128 v[184:187], v143 offset:51200
	ds_read_b128 v[188:191], v143 offset:52224
	ds_read_b128 v[192:195], v143 offset:53248
	ds_read_b128 v[196:199], v143 offset:54272
	ds_read_b128 v[200:203], v143 offset:55296
	ds_read_b128 v[204:207], v143 offset:56320
	global_load_lds_dwordx4 v[208:209], off
	s_add_i32 m0, s40, 0x2000
	s_add_u32 s14, s14, 0x40080
	v_lshl_add_u64 v[208:209], v[210:211], 0, s[2:3]
	s_addc_u32 s15, s15, 0
	s_add_i32 s40, s59, s42
	global_load_lds_dwordx4 v[208:209], off
	v_lshl_add_u64 v[208:209], s[14:15], 0, v[132:133]
	s_mov_b32 m0, s40
	s_nop 0
	global_load_lds_dwordx4 v[208:209], off
	v_lshl_add_u64 v[208:209], s[14:15], 0, v[128:129]
	s_add_i32 m0, s40, 0x2000
	s_nop 0
	global_load_lds_dwordx4 v[208:209], off
	v_lshl_add_u64 v[208:209], v[212:213], 0, s[2:3]
	s_mov_b32 m0, s46
	s_nop 0
	global_load_lds_dwordx4 v[208:209], off
	v_lshl_add_u64 v[208:209], v[214:215], 0, s[2:3]
	s_mov_b32 m0, s47
	s_nop 0
	global_load_lds_dwordx4 v[208:209], off
	s_waitcnt vmcnt(8)
	s_waitcnt lgkmcnt(0)
	s_barrier
	s_setprio 1
	v_mfma_f32_16x16x32_bf16 v[60:63], v[144:147], v[176:179], v[60:63]
	v_mfma_f32_16x16x32_bf16 v[56:59], v[152:155], v[176:179], v[56:59]
	v_mfma_f32_16x16x32_bf16 v[44:47], v[144:147], v[184:187], v[44:47]
	v_mfma_f32_16x16x32_bf16 v[40:43], v[152:155], v[184:187], v[40:43]
	v_mfma_f32_16x16x32_bf16 v[28:31], v[144:147], v[192:195], v[28:31]
	v_mfma_f32_16x16x32_bf16 v[24:27], v[152:155], v[192:195], v[24:27]
	v_mfma_f32_16x16x32_bf16 v[12:15], v[144:147], v[200:203], v[12:15]
	v_mfma_f32_16x16x32_bf16 v[8:11], v[152:155], v[200:203], v[8:11]
	v_mfma_f32_16x16x32_bf16 v[60:63], v[148:151], v[180:183], v[60:63]
	v_mfma_f32_16x16x32_bf16 v[56:59], v[156:159], v[180:183], v[56:59]
	v_mfma_f32_16x16x32_bf16 v[44:47], v[148:151], v[188:191], v[44:47]
	v_mfma_f32_16x16x32_bf16 v[40:43], v[156:159], v[188:191], v[40:43]
	v_mfma_f32_16x16x32_bf16 v[28:31], v[148:151], v[196:199], v[28:31]
	v_mfma_f32_16x16x32_bf16 v[24:27], v[156:159], v[196:199], v[24:27]
	v_mfma_f32_16x16x32_bf16 v[12:15], v[148:151], v[204:207], v[12:15]
	v_mfma_f32_16x16x32_bf16 v[8:11], v[156:159], v[204:207], v[8:11]
	s_setprio 0
	s_setprio 1
	v_mfma_f32_16x16x32_bf16 v[52:55], v[160:163], v[176:179], v[52:55]
	v_mfma_f32_16x16x32_bf16 v[48:51], v[168:171], v[176:179], v[48:51]
	v_mfma_f32_16x16x32_bf16 v[36:39], v[160:163], v[184:187], v[36:39]
	v_mfma_f32_16x16x32_bf16 v[32:35], v[168:171], v[184:187], v[32:35]
	v_mfma_f32_16x16x32_bf16 v[20:23], v[160:163], v[192:195], v[20:23]
	v_mfma_f32_16x16x32_bf16 v[16:19], v[168:171], v[192:195], v[16:19]
	v_mfma_f32_16x16x32_bf16 v[4:7], v[160:163], v[200:203], v[4:7]
	v_mfma_f32_16x16x32_bf16 v[0:3], v[168:171], v[200:203], v[0:3]
	v_mfma_f32_16x16x32_bf16 v[52:55], v[164:167], v[180:183], v[52:55]
	v_mfma_f32_16x16x32_bf16 v[48:51], v[172:175], v[180:183], v[48:51]
	v_mfma_f32_16x16x32_bf16 v[36:39], v[164:167], v[188:191], v[36:39]
	v_mfma_f32_16x16x32_bf16 v[32:35], v[172:175], v[188:191], v[32:35]
	v_mfma_f32_16x16x32_bf16 v[20:23], v[164:167], v[196:199], v[20:23]
	v_mfma_f32_16x16x32_bf16 v[16:19], v[172:175], v[196:199], v[16:19]
	v_mfma_f32_16x16x32_bf16 v[4:7], v[164:167], v[204:207], v[4:7]
	v_mfma_f32_16x16x32_bf16 v[0:3], v[172:175], v[204:207], v[0:3]
	s_setprio 0
	s_barrier
	s_add_i32 s57, s57, 2
	s_add_u32 s38, s38, 0x100
	s_addc_u32 s39, s39, 0
	s_add_u32 s55, s55, 0x100
	s_addc_u32 s56, s56, 0
	s_cmp_gt_u32 s57, 13
	s_cbranch_scc0 .LBB0_1694
	s_branch .Lpost_1694
.LBB0_1694:
	ds_read_b128 v[144:147], v141
	ds_read_b128 v[148:151], v141 offset:1024
	ds_read_b128 v[152:155], v141 offset:2048
	ds_read_b128 v[156:159], v141 offset:3072
	ds_read_b128 v[160:163], v142
	ds_read_b128 v[164:167], v142 offset:1024
	ds_read_b128 v[168:171], v142 offset:2048
	ds_read_b128 v[172:175], v142 offset:3072
	s_add_u32 s14, s38, 0xfffc0080
	s_addc_u32 s15, s39, -1
	s_cmp_eq_u32 s57, 12
	s_cselect_b32 s41, s9, s15
	s_cselect_b32 s40, s53, s14
	s_cselect_b32 s15, s11, s56
	s_cselect_b32 s14, s54, s55
	v_lshl_add_u64 v[208:209], s[38:39], 0, v[136:137]
	s_add_i32 m0, s35, 0xc000
	ds_read_b128 v[176:179], v143
	ds_read_b128 v[180:183], v143 offset:1024
	ds_read_b128 v[184:187], v143 offset:2048
	ds_read_b128 v[188:191], v143 offset:3072
	ds_read_b128 v[192:195], v143 offset:4096
	ds_read_b128 v[196:199], v143 offset:5120
	ds_read_b128 v[200:203], v143 offset:6144
	ds_read_b128 v[204:207], v143 offset:7168
	global_load_lds_dwordx4 v[208:209], off
	v_lshl_add_u64 v[208:209], s[38:39], 0, v[138:139]
	s_add_i32 m0, s35, 0xe000
	s_nop 0
	global_load_lds_dwordx4 v[208:209], off
	s_waitcnt vmcnt(8)
	s_waitcnt lgkmcnt(0)
	s_barrier
; #define G_STAGE(bufoff, gbase, voff) do { _Pragma("unroll") for (int _i = 0; _i < 2; ++_i) \
;         __builtin_amdgcn_global_load_lds((const unsigned*)((const char*)(gbase) + voff[_i]), (LAS unsigned*)(lds + (bufoff) + ldsw + _i * 8192), 16, 0, 0); } while (0)
; #define G_LDA(dst, b, h) do { _Pragma("unroll") for (int m = 0; m < 4; ++m) _Pragma("unroll") for (int k = 0; k < 2; ++k) dst[m][k] = *(const LAS bf16x8*)(lds + G_SA(b, h) + aoff + m * 2048 + k * 1024); } while (0)
; #define G_MMA(ai, bj, At_, Bt_) do { __builtin_amdgcn_s_setprio(1); _Pragma("unroll") for (int m = 0; m < 4; ++m) _Pragma("unroll") for (int n = 0; n < 2; ++n) _Pragma("unroll") for (int k = 0; k < 2; ++k) \
;         acc[ai][bj][m][n] = __builtin_amdgcn_mfma_f32_16x16x32_bf16(Bt_[n][k], At_[m][k], acc[ai][bj][m][n], 0, 0, 0); __builtin_amdgcn_s_setprio(0); } while (0)
; #define WAIT_V(n) asm volatile("s_waitcnt vmcnt(" #n ")" ::: "memory")
; #define WAIT_L(n) asm volatile("s_waitcnt lgkmcnt(" #n ")" ::: "memory")
; #define BAR __builtin_amdgcn_s_barrier()
; #define SCHED __builtin_amdgcn_sched_barrier(0)
; template <class Get, class Epi>
; DI void gemm_loop(int ntiles, int ld, char* shm, const Get& get, const Epi& epi) {
;     ...
;             WAIT_V(8); WAIT_L(0); BAR; G_MMA(0, 0, At, B0); G_MMA(0, 1, At, B1); BAR; SCHED;
;             G_LDA(At, 0, 1); G_STAGE(G_SB(0, 0), b2, voffB); G_STAGE(G_SB(0, 1), b2 + hstep, voffB); G_STAGE(G_SA(0, 0), a2, voffA);
;             WAIT_V(8); WAIT_L(0); BAR; G_MMA(1, 0, At, B0); G_MMA(1, 1, At, B1); BAR; SCHED;
	s_setprio 1
	v_mfma_f32_16x16x32_bf16 v[124:127], v[144:147], v[176:179], v[124:127]
	v_mfma_f32_16x16x32_bf16 v[120:123], v[152:155], v[176:179], v[120:123]
	v_mfma_f32_16x16x32_bf16 v[108:111], v[144:147], v[184:187], v[108:111]
	v_mfma_f32_16x16x32_bf16 v[104:107], v[152:155], v[184:187], v[104:107]
	v_mfma_f32_16x16x32_bf16 v[92:95], v[144:147], v[192:195], v[92:95]
	v_mfma_f32_16x16x32_bf16 v[88:91], v[152:155], v[192:195], v[88:91]
	v_mfma_f32_16x16x32_bf16 v[76:79], v[144:147], v[200:203], v[76:79]
	v_mfma_f32_16x16x32_bf16 v[72:75], v[152:155], v[200:203], v[72:75]
	v_mfma_f32_16x16x32_bf16 v[124:127], v[148:151], v[180:183], v[124:127]
	v_mfma_f32_16x16x32_bf16 v[120:123], v[156:159], v[180:183], v[120:123]
	v_mfma_f32_16x16x32_bf16 v[108:111], v[148:151], v[188:191], v[108:111]
	v_mfma_f32_16x16x32_bf16 v[104:107], v[156:159], v[188:191], v[104:107]
	v_mfma_f32_16x16x32_bf16 v[92:95], v[148:151], v[196:199], v[92:95]
	v_mfma_f32_16x16x32_bf16 v[88:91], v[156:159], v[196:199], v[88:91]
	v_mfma_f32_16x16x32_bf16 v[76:79], v[148:151], v[204:207], v[76:79]
	v_mfma_f32_16x16x32_bf16 v[72:75], v[156:159], v[204:207], v[72:75]
	s_setprio 0
	s_setprio 1
	v_mfma_f32_16x16x32_bf16 v[116:119], v[160:163], v[176:179], v[116:119]
	v_mfma_f32_16x16x32_bf16 v[112:115], v[168:171], v[176:179], v[112:115]
	v_mfma_f32_16x16x32_bf16 v[100:103], v[160:163], v[184:187], v[100:103]
	v_mfma_f32_16x16x32_bf16 v[96:99], v[168:171], v[184:187], v[96:99]
	v_mfma_f32_16x16x32_bf16 v[84:87], v[160:163], v[192:195], v[84:87]
	v_mfma_f32_16x16x32_bf16 v[80:83], v[168:171], v[192:195], v[80:83]
	v_mfma_f32_16x16x32_bf16 v[68:71], v[160:163], v[200:203], v[68:71]
	v_mfma_f32_16x16x32_bf16 v[64:67], v[168:171], v[200:203], v[64:67]
	v_mfma_f32_16x16x32_bf16 v[116:119], v[164:167], v[180:183], v[116:119]
	v_mfma_f32_16x16x32_bf16 v[112:115], v[172:175], v[180:183], v[112:115]
	v_mfma_f32_16x16x32_bf16 v[100:103], v[164:167], v[188:191], v[100:103]
	v_mfma_f32_16x16x32_bf16 v[96:99], v[172:175], v[188:191], v[96:99]
	v_mfma_f32_16x16x32_bf16 v[84:87], v[164:167], v[196:199], v[84:87]
	v_mfma_f32_16x16x32_bf16 v[80:83], v[172:175], v[196:199], v[80:83]
	v_mfma_f32_16x16x32_bf16 v[68:71], v[164:167], v[204:207], v[68:71]
	v_mfma_f32_16x16x32_bf16 v[64:67], v[172:175], v[204:207], v[64:67]
	s_setprio 0
	s_barrier
	s_add_i32 s58, s48, s42
	v_lshl_add_u64 v[208:209], s[14:15], 0, v[132:133]
	s_mov_b32 m0, s58
	ds_read_b128 v[176:179], v143 offset:16384
	ds_read_b128 v[180:183], v143 offset:17408
	ds_read_b128 v[184:187], v143 offset:18432
	ds_read_b128 v[188:191], v143 offset:19456
	ds_read_b128 v[192:195], v143 offset:20480
	ds_read_b128 v[196:199], v143 offset:21504
	ds_read_b128 v[200:203], v143 offset:22528
	ds_read_b128 v[204:207], v143 offset:23552
	global_load_lds_dwordx4 v[208:209], off
	s_add_i32 m0, s58, 0x2000
	s_add_u32 s58, s14, 0x40000
	v_lshl_add_u64 v[210:211], s[14:15], 0, v[128:129]
	s_addc_u32 s59, s15, 0
	s_add_i32 s71, s49, s42
	global_load_lds_dwordx4 v[210:211], off
	v_lshl_add_u64 v[212:213], s[58:59], 0, v[132:133]
	s_mov_b32 m0, s71
	v_lshl_add_u64 v[214:215], s[40:41], 0, v[130:131]
	global_load_lds_dwordx4 v[212:213], off
	v_lshl_add_u64 v[212:213], s[58:59], 0, v[128:129]
	s_add_i32 m0, s71, 0x2000
	s_nop 0
	global_load_lds_dwordx4 v[212:213], off
	v_lshl_add_u64 v[212:213], s[40:41], 0, v[134:135]
	s_mov_b32 m0, s35
	s_nop 0
	global_load_lds_dwordx4 v[212:213], off
	s_mov_b32 m0, s37
	s_nop 0
	global_load_lds_dwordx4 v[214:215], off
	s_waitcnt vmcnt(8)
	s_waitcnt lgkmcnt(0)
	s_barrier
	s_setprio 1
	v_mfma_f32_16x16x32_bf16 v[60:63], v[144:147], v[176:179], v[60:63]
	v_mfma_f32_16x16x32_bf16 v[56:59], v[152:155], v[176:179], v[56:59]
	v_mfma_f32_16x16x32_bf16 v[44:47], v[144:147], v[184:187], v[44:47]
	v_mfma_f32_16x16x32_bf16 v[40:43], v[152:155], v[184:187], v[40:43]
	v_mfma_f32_16x16x32_bf16 v[28:31], v[144:147], v[192:195], v[28:31]
	v_mfma_f32_16x16x32_bf16 v[24:27], v[152:155], v[192:195], v[24:27]
	v_mfma_f32_16x16x32_bf16 v[12:15], v[144:147], v[200:203], v[12:15]
	v_mfma_f32_16x16x32_bf16 v[8:11], v[152:155], v[200:203], v[8:11]
	v_mfma_f32_16x16x32_bf16 v[60:63], v[148:151], v[180:183], v[60:63]
	v_mfma_f32_16x16x32_bf16 v[56:59], v[156:159], v[180:183], v[56:59]
	v_mfma_f32_16x16x32_bf16 v[44:47], v[148:151], v[188:191], v[44:47]
	v_mfma_f32_16x16x32_bf16 v[40:43], v[156:159], v[188:191], v[40:43]
	v_mfma_f32_16x16x32_bf16 v[28:31], v[148:151], v[196:199], v[28:31]
	v_mfma_f32_16x16x32_bf16 v[24:27], v[156:159], v[196:199], v[24:27]
	v_mfma_f32_16x16x32_bf16 v[12:15], v[148:151], v[204:207], v[12:15]
	v_mfma_f32_16x16x32_bf16 v[8:11], v[156:159], v[204:207], v[8:11]
	s_setprio 0
	s_setprio 1
	v_mfma_f32_16x16x32_bf16 v[52:55], v[160:163], v[176:179], v[52:55]
	v_mfma_f32_16x16x32_bf16 v[48:51], v[168:171], v[176:179], v[48:51]
	v_mfma_f32_16x16x32_bf16 v[36:39], v[160:163], v[184:187], v[36:39]
	v_mfma_f32_16x16x32_bf16 v[32:35], v[168:171], v[184:187], v[32:35]
	v_mfma_f32_16x16x32_bf16 v[20:23], v[160:163], v[192:195], v[20:23]
	v_mfma_f32_16x16x32_bf16 v[16:19], v[168:171], v[192:195], v[16:19]
	v_mfma_f32_16x16x32_bf16 v[4:7], v[160:163], v[200:203], v[4:7]
	v_mfma_f32_16x16x32_bf16 v[0:3], v[168:171], v[200:203], v[0:3]
	v_mfma_f32_16x16x32_bf16 v[52:55], v[164:167], v[180:183], v[52:55]
	v_mfma_f32_16x16x32_bf16 v[48:51], v[172:175], v[180:183], v[48:51]
	v_mfma_f32_16x16x32_bf16 v[36:39], v[164:167], v[188:191], v[36:39]
	v_mfma_f32_16x16x32_bf16 v[32:35], v[172:175], v[188:191], v[32:35]
	v_mfma_f32_16x16x32_bf16 v[20:23], v[164:167], v[196:199], v[20:23]
	v_mfma_f32_16x16x32_bf16 v[16:19], v[172:175], v[196:199], v[16:19]
	v_mfma_f32_16x16x32_bf16 v[4:7], v[164:167], v[204:207], v[4:7]
	v_mfma_f32_16x16x32_bf16 v[0:3], v[172:175], v[204:207], v[0:3]
	s_setprio 0
	s_barrier
; #define G_STAGE(bufoff, gbase, voff) do { _Pragma("unroll") for (int _i = 0; _i < 2; ++_i) \
;         __builtin_amdgcn_global_load_lds((const unsigned*)((const char*)(gbase) + voff[_i]), (LAS unsigned*)(lds + (bufoff) + ldsw + _i * 8192), 16, 0, 0); } while (0)
; #define G_LDA(dst, b, h) do { _Pragma("unroll") for (int m = 0; m < 4; ++m) _Pragma("unroll") for (int k = 0; k < 2; ++k) dst[m][k] = *(const LAS bf16x8*)(lds + G_SA(b, h) + aoff + m * 2048 + k * 1024); } while (0)
; #define G_LDB(dst, b, h) do { _Pragma("unroll") for (int n = 0; n < 2; ++n) _Pragma("unroll") for (int k = 0; k < 2; ++k) dst[n][k] = *(const LAS bf16x8*)(lds + G_SB(b, h) + boff + n * 2048 + k * 1024); } while (0)
; #define G_MMA(ai, bj, At_, Bt_) do { __builtin_amdgcn_s_setprio(1); _Pragma("unroll") for (int m = 0; m < 4; ++m) _Pragma("unroll") for (int n = 0; n < 2; ++n) _Pragma("unroll") for (int k = 0; k < 2; ++k) \
;         acc[ai][bj][m][n] = __builtin_amdgcn_mfma_f32_16x16x32_bf16(Bt_[n][k], At_[m][k], acc[ai][bj][m][n], 0, 0, 0); __builtin_amdgcn_s_setprio(0); } while (0)
; #define WAIT_V(n) asm volatile("s_waitcnt vmcnt(" #n ")" ::: "memory")
; #define WAIT_L(n) asm volatile("s_waitcnt lgkmcnt(" #n ")" ::: "memory")
; #define BAR __builtin_amdgcn_s_barrier()
; #define SCHED __builtin_amdgcn_sched_barrier(0)
; template <class Get, class Epi>
; DI void gemm_loop(int ntiles, int ld, char* shm, const Get& get, const Epi& epi) {
;     ...
;             G_LDB(B0, 1, 0); G_LDB(B1, 1, 1); SCHED; G_LDA(At, 1, 0); G_STAGE(G_SA(0, 1), a2 + hstep, voffA);
;             WAIT_V(8); WAIT_L(0); BAR; G_MMA(0, 0, At, B0); G_MMA(0, 1, At, B1); BAR; SCHED;
	s_add_i32 s58, 0, 0x18000
	s_add_i32 s59, 0, 0x1c000
	v_add_u32_e32 v156, s58, v140
	v_add_u32_e32 v172, s59, v140
	ds_read_b128 v[144:147], v156
	ds_read_b128 v[148:151], v156 offset:1024
	ds_read_b128 v[152:155], v156 offset:2048
	ds_read_b128 v[156:159], v156 offset:3072
	ds_read_b128 v[160:163], v172
	ds_read_b128 v[164:167], v172 offset:1024
	ds_read_b128 v[168:171], v172 offset:2048
	ds_read_b128 v[172:175], v172 offset:3072
	s_add_u32 s40, s40, 0x40000
	s_addc_u32 s41, s41, 0
	s_mov_b32 m0, s44
	v_lshl_add_u64 v[216:217], s[40:41], 0, v[134:135]
	ds_read_b128 v[176:179], v143 offset:32768
	ds_read_b128 v[180:183], v143 offset:33792
	ds_read_b128 v[184:187], v143 offset:34816
	ds_read_b128 v[188:191], v143 offset:35840
	ds_read_b128 v[192:195], v143 offset:36864
	ds_read_b128 v[196:199], v143 offset:37888
	ds_read_b128 v[200:203], v143 offset:38912
	ds_read_b128 v[204:207], v143 offset:39936
	global_load_lds_dwordx4 v[216:217], off
	v_lshl_add_u64 v[216:217], s[40:41], 0, v[130:131]
	s_mov_b32 m0, s45
	s_nop 0
	global_load_lds_dwordx4 v[216:217], off
	s_waitcnt vmcnt(8)
	s_waitcnt lgkmcnt(0)
	s_barrier
	s_setprio 1
	v_mfma_f32_16x16x32_bf16 v[124:127], v[144:147], v[176:179], v[124:127]
	v_mfma_f32_16x16x32_bf16 v[120:123], v[152:155], v[176:179], v[120:123]
	v_mfma_f32_16x16x32_bf16 v[108:111], v[144:147], v[184:187], v[108:111]
	v_mfma_f32_16x16x32_bf16 v[104:107], v[152:155], v[184:187], v[104:107]
	v_mfma_f32_16x16x32_bf16 v[92:95], v[144:147], v[192:195], v[92:95]
	v_mfma_f32_16x16x32_bf16 v[88:91], v[152:155], v[192:195], v[88:91]
	v_mfma_f32_16x16x32_bf16 v[76:79], v[144:147], v[200:203], v[76:79]
	v_mfma_f32_16x16x32_bf16 v[72:75], v[152:155], v[200:203], v[72:75]
	v_mfma_f32_16x16x32_bf16 v[124:127], v[148:151], v[180:183], v[124:127]
	v_mfma_f32_16x16x32_bf16 v[120:123], v[156:159], v[180:183], v[120:123]
	v_mfma_f32_16x16x32_bf16 v[108:111], v[148:151], v[188:191], v[108:111]
	v_mfma_f32_16x16x32_bf16 v[104:107], v[156:159], v[188:191], v[104:107]
	v_mfma_f32_16x16x32_bf16 v[92:95], v[148:151], v[196:199], v[92:95]
	v_mfma_f32_16x16x32_bf16 v[88:91], v[156:159], v[196:199], v[88:91]
	v_mfma_f32_16x16x32_bf16 v[76:79], v[148:151], v[204:207], v[76:79]
	v_mfma_f32_16x16x32_bf16 v[72:75], v[156:159], v[204:207], v[72:75]
	s_setprio 0
	s_setprio 1
	v_mfma_f32_16x16x32_bf16 v[116:119], v[160:163], v[176:179], v[116:119]
	v_mfma_f32_16x16x32_bf16 v[112:115], v[168:171], v[176:179], v[112:115]
	v_mfma_f32_16x16x32_bf16 v[100:103], v[160:163], v[184:187], v[100:103]
	v_mfma_f32_16x16x32_bf16 v[96:99], v[168:171], v[184:187], v[96:99]
	v_mfma_f32_16x16x32_bf16 v[84:87], v[160:163], v[192:195], v[84:87]
	v_mfma_f32_16x16x32_bf16 v[80:83], v[168:171], v[192:195], v[80:83]
	v_mfma_f32_16x16x32_bf16 v[68:71], v[160:163], v[200:203], v[68:71]
	v_mfma_f32_16x16x32_bf16 v[64:67], v[168:171], v[200:203], v[64:67]
	v_mfma_f32_16x16x32_bf16 v[116:119], v[164:167], v[180:183], v[116:119]
	v_mfma_f32_16x16x32_bf16 v[112:115], v[172:175], v[180:183], v[112:115]
	v_mfma_f32_16x16x32_bf16 v[100:103], v[164:167], v[188:191], v[100:103]
	v_mfma_f32_16x16x32_bf16 v[96:99], v[172:175], v[188:191], v[96:99]
	v_mfma_f32_16x16x32_bf16 v[84:87], v[164:167], v[196:199], v[84:87]
	v_mfma_f32_16x16x32_bf16 v[80:83], v[172:175], v[196:199], v[80:83]
	v_mfma_f32_16x16x32_bf16 v[68:71], v[164:167], v[204:207], v[68:71]
	v_mfma_f32_16x16x32_bf16 v[64:67], v[172:175], v[204:207], v[64:67]
	s_setprio 0
	s_barrier
; #define G_STAGE(bufoff, gbase, voff) do { _Pragma("unroll") for (int _i = 0; _i < 2; ++_i) \
;         __builtin_amdgcn_global_load_lds((const unsigned*)((const char*)(gbase) + voff[_i]), (LAS unsigned*)(lds + (bufoff) + ldsw + _i * 8192), 16, 0, 0); } while (0)
; #define G_LDA(dst, b, h) do { _Pragma("unroll") for (int m = 0; m < 4; ++m) _Pragma("unroll") for (int k = 0; k < 2; ++k) dst[m][k] = *(const LAS bf16x8*)(lds + G_SA(b, h) + aoff + m * 2048 + k * 1024); } while (0)
; #define G_MMA(ai, bj, At_, Bt_) do { __builtin_amdgcn_s_setprio(1); _Pragma("unroll") for (int m = 0; m < 4; ++m) _Pragma("unroll") for (int n = 0; n < 2; ++n) _Pragma("unroll") for (int k = 0; k < 2; ++k) \
;         acc[ai][bj][m][n] = __builtin_amdgcn_mfma_f32_16x16x32_bf16(Bt_[n][k], At_[m][k], acc[ai][bj][m][n], 0, 0, 0); __builtin_amdgcn_s_setprio(0); } while (0)
; #define WAIT_V(n) asm volatile("s_waitcnt vmcnt(" #n ")" ::: "memory")
; #define WAIT_L(n) asm volatile("s_waitcnt lgkmcnt(" #n ")" ::: "memory")
; #define BAR __builtin_amdgcn_s_barrier()
; #define SCHED __builtin_amdgcn_sched_barrier(0)
; template <class Get, class Epi>
; DI void gemm_loop(int ntiles, int ld, char* shm, const Get& get, const Epi& epi) {
;     ...
;             G_LDA(At, 1, 1); G_STAGE(G_SB(1, 0), b3, voffB); G_STAGE(G_SB(1, 1), b3 + hstep, voffB); G_STAGE(G_SA(1, 0), a3, voffA);
;             WAIT_V(8); WAIT_L(0); BAR; G_MMA(1, 0, At, B0); G_MMA(1, 1, At, B1); BAR; SCHED;
	s_add_i32 s40, s58, s42
	v_lshl_add_u64 v[208:209], v[208:209], 0, s[2:3]
	s_mov_b32 m0, s40
	ds_read_b128 v[176:179], v143 offset:49152
	ds_read_b128 v[180:183], v143 offset:50176
	ds_read_b128 v[184:187], v143 offset:51200
	ds_read_b128 v[188:191], v143 offset:52224
	ds_read_b128 v[192:195], v143 offset:53248
	ds_read_b128 v[196:199], v143 offset:54272
	ds_read_b128 v[200:203], v143 offset:55296
	ds_read_b128 v[204:207], v143 offset:56320
	global_load_lds_dwordx4 v[208:209], off
	s_add_i32 m0, s40, 0x2000
	s_add_u32 s14, s14, 0x40080
	v_lshl_add_u64 v[208:209], v[210:211], 0, s[2:3]
	s_addc_u32 s15, s15, 0
	s_add_i32 s40, s59, s42
	global_load_lds_dwordx4 v[208:209], off
	v_lshl_add_u64 v[208:209], s[14:15], 0, v[132:133]
	s_mov_b32 m0, s40
	s_nop 0
	global_load_lds_dwordx4 v[208:209], off
	v_lshl_add_u64 v[208:209], s[14:15], 0, v[128:129]
	s_add_i32 m0, s40, 0x2000
	s_nop 0
	global_load_lds_dwordx4 v[208:209], off
	v_lshl_add_u64 v[208:209], v[212:213], 0, s[2:3]
	s_mov_b32 m0, s46
	s_nop 0
	global_load_lds_dwordx4 v[208:209], off
	v_lshl_add_u64 v[208:209], v[214:215], 0, s[2:3]
	s_mov_b32 m0, s47
	s_nop 0
	global_load_lds_dwordx4 v[208:209], off
	s_waitcnt vmcnt(8)
	s_waitcnt lgkmcnt(0)
	s_barrier
	s_setprio 1
	v_mfma_f32_16x16x32_bf16 v[60:63], v[144:147], v[176:179], v[60:63]
	v_mfma_f32_16x16x32_bf16 v[56:59], v[152:155], v[176:179], v[56:59]
	v_mfma_f32_16x16x32_bf16 v[44:47], v[144:147], v[184:187], v[44:47]
	v_mfma_f32_16x16x32_bf16 v[40:43], v[152:155], v[184:187], v[40:43]
	v_mfma_f32_16x16x32_bf16 v[28:31], v[144:147], v[192:195], v[28:31]
	v_mfma_f32_16x16x32_bf16 v[24:27], v[152:155], v[192:195], v[24:27]
	v_mfma_f32_16x16x32_bf16 v[12:15], v[144:147], v[200:203], v[12:15]
	v_mfma_f32_16x16x32_bf16 v[8:11], v[152:155], v[200:203], v[8:11]
	v_mfma_f32_16x16x32_bf16 v[60:63], v[148:151], v[180:183], v[60:63]
	v_mfma_f32_16x16x32_bf16 v[56:59], v[156:159], v[180:183], v[56:59]
	v_mfma_f32_16x16x32_bf16 v[44:47], v[148:151], v[188:191], v[44:47]
	v_mfma_f32_16x16x32_bf16 v[40:43], v[156:159], v[188:191], v[40:43]
	v_mfma_f32_16x16x32_bf16 v[28:31], v[148:151], v[196:199], v[28:31]
	v_mfma_f32_16x16x32_bf16 v[24:27], v[156:159], v[196:199], v[24:27]
	v_mfma_f32_16x16x32_bf16 v[12:15], v[148:151], v[204:207], v[12:15]
	v_mfma_f32_16x16x32_bf16 v[8:11], v[156:159], v[204:207], v[8:11]
	s_setprio 0
	s_setprio 1
	v_mfma_f32_16x16x32_bf16 v[52:55], v[160:163], v[176:179], v[52:55]
	v_mfma_f32_16x16x32_bf16 v[48:51], v[168:171], v[176:179], v[48:51]
	v_mfma_f32_16x16x32_bf16 v[36:39], v[160:163], v[184:187], v[36:39]
	v_mfma_f32_16x16x32_bf16 v[32:35], v[168:171], v[184:187], v[32:35]
	v_mfma_f32_16x16x32_bf16 v[20:23], v[160:163], v[192:195], v[20:23]
	v_mfma_f32_16x16x32_bf16 v[16:19], v[168:171], v[192:195], v[16:19]
	v_mfma_f32_16x16x32_bf16 v[4:7], v[160:163], v[200:203], v[4:7]
	v_mfma_f32_16x16x32_bf16 v[0:3], v[168:171], v[200:203], v[0:3]
	v_mfma_f32_16x16x32_bf16 v[52:55], v[164:167], v[180:183], v[52:55]
	v_mfma_f32_16x16x32_bf16 v[48:51], v[172:175], v[180:183], v[48:51]
	v_mfma_f32_16x16x32_bf16 v[36:39], v[164:167], v[188:191], v[36:39]
	v_mfma_f32_16x16x32_bf16 v[32:35], v[172:175], v[188:191], v[32:35]
	v_mfma_f32_16x16x32_bf16 v[20:23], v[164:167], v[196:199], v[20:23]
	v_mfma_f32_16x16x32_bf16 v[16:19], v[172:175], v[196:199], v[16:19]
	v_mfma_f32_16x16x32_bf16 v[4:7], v[164:167], v[204:207], v[4:7]
	v_mfma_f32_16x16x32_bf16 v[0:3], v[172:175], v[204:207], v[0:3]
	s_setprio 0
	s_barrier
	s_add_i32 s57, s57, 2
	s_add_u32 s38, s38, 0x100
	s_addc_u32 s39, s39, 0
	s_add_u32 s55, s55, 0x100
	s_addc_u32 s56, s56, 0
	s_cmp_gt_u32 s57, 13
	s_cbranch_scc0 .LBB0_1694

; #define G_STAGE(bufoff, gbase, voff) do { _Pragma("unroll") for (int _i = 0; _i < 2; ++_i) \
;         __builtin_amdgcn_global_load_lds((const unsigned*)((const char*)(gbase) + voff[_i]), (LAS unsigned*)(lds + (bufoff) + ldsw + _i * 8192), 16, 0, 0); } while (0)
; #define G_LDA(dst, b, h) do { _Pragma("unroll") for (int m = 0; m < 4; ++m) _Pragma("unroll") for (int k = 0; k < 2; ++k) dst[m][k] = *(const LAS bf16x8*)(lds + G_SA(b, h) + aoff + m * 2048 + k * 1024); } while (0)
; #define G_MMA(ai, bj, At_, Bt_) do { __builtin_amdgcn_s_setprio(1); _Pragma("unroll") for (int m = 0; m < 4; ++m) _Pragma("unroll") for (int n = 0; n < 2; ++n) _Pragma("unroll") for (int k = 0; k < 2; ++k) \
;         acc[ai][bj][m][n] = __builtin_amdgcn_mfma_f32_16x16x32_bf16(Bt_[n][k], At_[m][k], acc[ai][bj][m][n], 0, 0, 0); __builtin_amdgcn_s_setprio(0); } while (0)
; #define WAIT_V(n) asm volatile("s_waitcnt vmcnt(" #n ")" ::: "memory")
; #define WAIT_L(n) asm volatile("s_waitcnt lgkmcnt(" #n ")" ::: "memory")
; #define BAR __builtin_amdgcn_s_barrier()
; #define SCHED __builtin_amdgcn_sched_barrier(0)
; template <class Get, class Epi>
; DI void gemm_loop(int ntiles, int ld, char* shm, const Get& get, const Epi& epi) {
;     ...
;             WAIT_V(8); WAIT_L(0); BAR; G_MMA(0, 0, At, B0); G_MMA(0, 1, At, B1); BAR; SCHED;
;             G_LDA(At, 0, 1); G_STAGE(G_SB(0, 0), b2, voffB); G_STAGE(G_SB(0, 1), b2 + hstep, voffB); G_STAGE(G_SA(0, 0), a2, voffA);
.Lrj_1781_0:
	s_waitcnt lgkmcnt(0)
	s_barrier
	s_setprio 1
	v_mfma_f32_16x16x32_bf16 v[124:127], v[128:131], v[180:183], 0
	v_mfma_f32_16x16x32_bf16 v[120:123], v[136:139], v[180:183], 0
	v_mfma_f32_16x16x32_bf16 v[116:119], v[128:131], v[188:191], 0
	v_mfma_f32_16x16x32_bf16 v[112:115], v[136:139], v[188:191], 0
	v_mfma_f32_16x16x32_bf16 v[108:111], v[128:131], v[196:199], 0
	v_mfma_f32_16x16x32_bf16 v[104:107], v[136:139], v[196:199], 0
	v_mfma_f32_16x16x32_bf16 v[100:103], v[128:131], v[204:207], 0
	v_mfma_f32_16x16x32_bf16 v[96:99], v[136:139], v[204:207], 0
	v_mfma_f32_16x16x32_bf16 v[124:127], v[132:135], v[184:187], v[124:127]
	v_mfma_f32_16x16x32_bf16 v[120:123], v[140:143], v[184:187], v[120:123]
	v_mfma_f32_16x16x32_bf16 v[116:119], v[132:135], v[192:195], v[116:119]
	v_mfma_f32_16x16x32_bf16 v[112:115], v[140:143], v[192:195], v[112:115]
	v_mfma_f32_16x16x32_bf16 v[108:111], v[132:135], v[200:203], v[108:111]
	v_mfma_f32_16x16x32_bf16 v[104:107], v[140:143], v[200:203], v[104:107]
	v_mfma_f32_16x16x32_bf16 v[100:103], v[132:135], v[208:211], v[100:103]
	v_mfma_f32_16x16x32_bf16 v[96:99], v[140:143], v[208:211], v[96:99]
	s_setprio 0
	s_setprio 1
	v_mfma_f32_16x16x32_bf16 v[60:63], v[158:161], v[180:183], 0
	v_mfma_f32_16x16x32_bf16 v[56:59], v[172:175], v[180:183], 0
	v_mfma_f32_16x16x32_bf16 v[52:55], v[158:161], v[188:191], 0
	v_mfma_f32_16x16x32_bf16 v[48:51], v[172:175], v[188:191], 0
	v_mfma_f32_16x16x32_bf16 v[44:47], v[158:161], v[196:199], 0
	v_mfma_f32_16x16x32_bf16 v[40:43], v[172:175], v[196:199], 0
	v_mfma_f32_16x16x32_bf16 v[36:39], v[158:161], v[204:207], 0
	v_mfma_f32_16x16x32_bf16 v[32:35], v[172:175], v[204:207], 0
	v_mfma_f32_16x16x32_bf16 v[60:63], v[162:165], v[184:187], v[60:63]
	v_mfma_f32_16x16x32_bf16 v[56:59], v[176:179], v[184:187], v[56:59]
	v_mfma_f32_16x16x32_bf16 v[52:55], v[162:165], v[192:195], v[52:55]
	v_mfma_f32_16x16x32_bf16 v[48:51], v[176:179], v[192:195], v[48:51]
	v_mfma_f32_16x16x32_bf16 v[44:47], v[162:165], v[200:203], v[44:47]
	v_mfma_f32_16x16x32_bf16 v[40:43], v[176:179], v[200:203], v[40:43]
	v_mfma_f32_16x16x32_bf16 v[36:39], v[162:165], v[208:211], v[36:39]
	v_mfma_f32_16x16x32_bf16 v[32:35], v[176:179], v[208:211], v[32:35]
	s_setprio 0
	s_barrier
	s_add_i32 s4, s53, s44
	v_lshl_add_u64 v[144:145], s[40:41], 0, v[148:149]
	s_mov_b32 m0, s4
	ds_read_b128 v[180:183], v171 offset:16384
	ds_read_b128 v[184:187], v171 offset:17408
	ds_read_b128 v[188:191], v171 offset:18432
	ds_read_b128 v[192:195], v171 offset:19456
	ds_read_b128 v[196:199], v171 offset:20480
	ds_read_b128 v[200:203], v171 offset:21504
	ds_read_b128 v[204:207], v171 offset:22528
	ds_read_b128 v[208:211], v171 offset:23552
	global_load_lds_dwordx4 v[144:145], off
	s_add_i32 m0, s4, 0x2000
	s_add_u32 s4, s40, 0xb0000
	v_lshl_add_u64 v[166:167], s[40:41], 0, v[152:153]
	s_addc_u32 s5, s41, 0
	s_add_i32 s78, s54, s44
	global_load_lds_dwordx4 v[166:167], off
	v_lshl_add_u64 v[212:213], s[4:5], 0, v[148:149]
	s_mov_b32 m0, s78
	v_lshl_add_u64 v[214:215], s[42:43], 0, v[150:151]
	global_load_lds_dwordx4 v[212:213], off
	v_lshl_add_u64 v[212:213], s[4:5], 0, v[152:153]
	s_add_i32 m0, s78, 0x2000
	s_nop 0
	global_load_lds_dwordx4 v[212:213], off
	v_lshl_add_u64 v[212:213], s[42:43], 0, v[146:147]
	s_mov_b32 m0, s45
	s_nop 0
	global_load_lds_dwordx4 v[212:213], off
	s_mov_b32 m0, s46
	s_nop 0
	global_load_lds_dwordx4 v[214:215], off
	s_cmp_lg_u32 s100, 0
	s_cbranch_scc0 .Lrf_1781_1
	s_waitcnt vmcnt(16)
	s_branch .Lrj_1781_1

; #define G_STAGE(bufoff, gbase, voff) do { _Pragma("unroll") for (int _i = 0; _i < 2; ++_i) \
;         __builtin_amdgcn_global_load_lds((const unsigned*)((const char*)(gbase) + voff[_i]), (LAS unsigned*)(lds + (bufoff) + ldsw + _i * 8192), 16, 0, 0); } while (0)
; #define G_LDA(dst, b, h) do { _Pragma("unroll") for (int m = 0; m < 4; ++m) _Pragma("unroll") for (int k = 0; k < 2; ++k) dst[m][k] = *(const LAS bf16x8*)(lds + G_SA(b, h) + aoff + m * 2048 + k * 1024); } while (0)
; #define G_LDB(dst, b, h) do { _Pragma("unroll") for (int n = 0; n < 2; ++n) _Pragma("unroll") for (int k = 0; k < 2; ++k) dst[n][k] = *(const LAS bf16x8*)(lds + G_SB(b, h) + boff + n * 2048 + k * 1024); } while (0)
; #define G_MMA(ai, bj, At_, Bt_) do { __builtin_amdgcn_s_setprio(1); _Pragma("unroll") for (int m = 0; m < 4; ++m) _Pragma("unroll") for (int n = 0; n < 2; ++n) _Pragma("unroll") for (int k = 0; k < 2; ++k) \
;         acc[ai][bj][m][n] = __builtin_amdgcn_mfma_f32_16x16x32_bf16(Bt_[n][k], At_[m][k], acc[ai][bj][m][n], 0, 0, 0); __builtin_amdgcn_s_setprio(0); } while (0)
; #define WAIT_V(n) asm volatile("s_waitcnt vmcnt(" #n ")" ::: "memory")
; #define WAIT_L(n) asm volatile("s_waitcnt lgkmcnt(" #n ")" ::: "memory")
; #define BAR __builtin_amdgcn_s_barrier()
; #define SCHED __builtin_amdgcn_sched_barrier(0)
; template <class Get, class Epi>
; DI void gemm_loop(int ntiles, int ld, char* shm, const Get& get, const Epi& epi) {
;     ...
;             WAIT_V(8); WAIT_L(0); BAR; G_MMA(1, 0, At, B0); G_MMA(1, 1, At, B1); BAR; SCHED;
;             G_LDB(B0, 1, 0); G_LDB(B1, 1, 1); SCHED; G_LDA(At, 1, 0); G_STAGE(G_SA(0, 1), a2 + hstep, voffA);
;             WAIT_V(8); WAIT_L(0); BAR; G_MMA(0, 0, At, B0); G_MMA(0, 1, At, B1); BAR; SCHED;
.Lrj_1781_1:
	s_waitcnt lgkmcnt(0)
	s_barrier
	s_setprio 1
	v_mfma_f32_16x16x32_bf16 v[92:95], v[128:131], v[180:183], 0
	v_mfma_f32_16x16x32_bf16 v[88:91], v[136:139], v[180:183], 0
	v_mfma_f32_16x16x32_bf16 v[84:87], v[128:131], v[188:191], 0
	v_mfma_f32_16x16x32_bf16 v[80:83], v[136:139], v[188:191], 0
	v_mfma_f32_16x16x32_bf16 v[76:79], v[128:131], v[196:199], 0
	v_mfma_f32_16x16x32_bf16 v[72:75], v[136:139], v[196:199], 0
	v_mfma_f32_16x16x32_bf16 v[68:71], v[128:131], v[204:207], 0
	v_mfma_f32_16x16x32_bf16 v[64:67], v[136:139], v[204:207], 0
	v_mfma_f32_16x16x32_bf16 v[92:95], v[132:135], v[184:187], v[92:95]
	v_mfma_f32_16x16x32_bf16 v[88:91], v[140:143], v[184:187], v[88:91]
	v_mfma_f32_16x16x32_bf16 v[84:87], v[132:135], v[192:195], v[84:87]
	v_mfma_f32_16x16x32_bf16 v[80:83], v[140:143], v[192:195], v[80:83]
	v_mfma_f32_16x16x32_bf16 v[76:79], v[132:135], v[200:203], v[76:79]
	v_mfma_f32_16x16x32_bf16 v[72:75], v[140:143], v[200:203], v[72:75]
	v_mfma_f32_16x16x32_bf16 v[68:71], v[132:135], v[208:211], v[68:71]
	v_mfma_f32_16x16x32_bf16 v[64:67], v[140:143], v[208:211], v[64:67]
	s_setprio 0
	s_setprio 1
	v_mfma_f32_16x16x32_bf16 v[28:31], v[158:161], v[180:183], 0
	v_mfma_f32_16x16x32_bf16 v[24:27], v[172:175], v[180:183], 0
	v_mfma_f32_16x16x32_bf16 v[20:23], v[158:161], v[188:191], 0
	v_mfma_f32_16x16x32_bf16 v[16:19], v[172:175], v[188:191], 0
	v_mfma_f32_16x16x32_bf16 v[12:15], v[158:161], v[196:199], 0
	v_mfma_f32_16x16x32_bf16 v[8:11], v[172:175], v[196:199], 0
	v_mfma_f32_16x16x32_bf16 v[4:7], v[158:161], v[204:207], 0
	v_mfma_f32_16x16x32_bf16 v[0:3], v[172:175], v[204:207], 0
	v_mfma_f32_16x16x32_bf16 v[28:31], v[162:165], v[184:187], v[28:31]
	v_mfma_f32_16x16x32_bf16 v[24:27], v[176:179], v[184:187], v[24:27]
	v_mfma_f32_16x16x32_bf16 v[20:23], v[162:165], v[192:195], v[20:23]
	v_mfma_f32_16x16x32_bf16 v[16:19], v[176:179], v[192:195], v[16:19]
	v_mfma_f32_16x16x32_bf16 v[12:15], v[162:165], v[200:203], v[12:15]
	v_mfma_f32_16x16x32_bf16 v[8:11], v[176:179], v[200:203], v[8:11]
	v_mfma_f32_16x16x32_bf16 v[4:7], v[162:165], v[208:211], v[4:7]
	v_mfma_f32_16x16x32_bf16 v[0:3], v[176:179], v[208:211], v[0:3]
	s_setprio 0
	s_barrier
	s_add_i32 s78, 0, 0x18000
	s_add_i32 s79, 0, 0x1c000
	v_add_u32_e32 v140, s78, v168
	v_add_u32_e32 v176, s79, v168
	ds_read_b128 v[128:131], v140
	ds_read_b128 v[132:135], v140 offset:1024
	ds_read_b128 v[136:139], v140 offset:2048
	ds_read_b128 v[140:143], v140 offset:3072
	ds_read_b128 v[158:161], v176
	ds_read_b128 v[162:165], v176 offset:1024
	ds_read_b128 v[172:175], v176 offset:2048
	ds_read_b128 v[176:179], v176 offset:3072
	s_add_u32 s4, s42, 0xb0000
	s_addc_u32 s5, s43, 0
	s_mov_b32 m0, s47
	v_lshl_add_u64 v[216:217], s[4:5], 0, v[146:147]
	ds_read_b128 v[180:183], v171 offset:32768
	ds_read_b128 v[184:187], v171 offset:33792
	ds_read_b128 v[188:191], v171 offset:34816
	ds_read_b128 v[192:195], v171 offset:35840
	ds_read_b128 v[196:199], v171 offset:36864
	ds_read_b128 v[200:203], v171 offset:37888
	ds_read_b128 v[204:207], v171 offset:38912
	ds_read_b128 v[208:211], v171 offset:39936
	global_load_lds_dwordx4 v[216:217], off
	v_lshl_add_u64 v[216:217], s[4:5], 0, v[150:151]
	s_mov_b32 m0, s48
	s_nop 0
	global_load_lds_dwordx4 v[216:217], off
	s_waitcnt vmcnt(8)
	s_waitcnt lgkmcnt(0)
	s_barrier
	s_setprio 1
	v_mfma_f32_16x16x32_bf16 v[124:127], v[128:131], v[180:183], v[124:127]
	v_mfma_f32_16x16x32_bf16 v[120:123], v[136:139], v[180:183], v[120:123]
	v_mfma_f32_16x16x32_bf16 v[116:119], v[128:131], v[188:191], v[116:119]
	v_mfma_f32_16x16x32_bf16 v[112:115], v[136:139], v[188:191], v[112:115]
	v_mfma_f32_16x16x32_bf16 v[108:111], v[128:131], v[196:199], v[108:111]
	v_mfma_f32_16x16x32_bf16 v[104:107], v[136:139], v[196:199], v[104:107]
	v_mfma_f32_16x16x32_bf16 v[100:103], v[128:131], v[204:207], v[100:103]
	v_mfma_f32_16x16x32_bf16 v[96:99], v[136:139], v[204:207], v[96:99]
	v_mfma_f32_16x16x32_bf16 v[124:127], v[132:135], v[184:187], v[124:127]
	v_mfma_f32_16x16x32_bf16 v[120:123], v[140:143], v[184:187], v[120:123]
	v_mfma_f32_16x16x32_bf16 v[116:119], v[132:135], v[192:195], v[116:119]
	v_mfma_f32_16x16x32_bf16 v[112:115], v[140:143], v[192:195], v[112:115]
	v_mfma_f32_16x16x32_bf16 v[108:111], v[132:135], v[200:203], v[108:111]
	v_mfma_f32_16x16x32_bf16 v[104:107], v[140:143], v[200:203], v[104:107]
	v_mfma_f32_16x16x32_bf16 v[100:103], v[132:135], v[208:211], v[100:103]
	v_mfma_f32_16x16x32_bf16 v[96:99], v[140:143], v[208:211], v[96:99]
	s_setprio 0
	s_setprio 1
	v_mfma_f32_16x16x32_bf16 v[60:63], v[158:161], v[180:183], v[60:63]
	v_mfma_f32_16x16x32_bf16 v[56:59], v[172:175], v[180:183], v[56:59]
	v_mfma_f32_16x16x32_bf16 v[52:55], v[158:161], v[188:191], v[52:55]
	v_mfma_f32_16x16x32_bf16 v[48:51], v[172:175], v[188:191], v[48:51]
	v_mfma_f32_16x16x32_bf16 v[44:47], v[158:161], v[196:199], v[44:47]
	v_mfma_f32_16x16x32_bf16 v[40:43], v[172:175], v[196:199], v[40:43]
	v_mfma_f32_16x16x32_bf16 v[36:39], v[158:161], v[204:207], v[36:39]
	v_mfma_f32_16x16x32_bf16 v[32:35], v[172:175], v[204:207], v[32:35]
	v_mfma_f32_16x16x32_bf16 v[60:63], v[162:165], v[184:187], v[60:63]
	v_mfma_f32_16x16x32_bf16 v[56:59], v[176:179], v[184:187], v[56:59]
	v_mfma_f32_16x16x32_bf16 v[52:55], v[162:165], v[192:195], v[52:55]
	v_mfma_f32_16x16x32_bf16 v[48:51], v[176:179], v[192:195], v[48:51]
	v_mfma_f32_16x16x32_bf16 v[44:47], v[162:165], v[200:203], v[44:47]
	v_mfma_f32_16x16x32_bf16 v[40:43], v[176:179], v[200:203], v[40:43]
	v_mfma_f32_16x16x32_bf16 v[36:39], v[162:165], v[208:211], v[36:39]
	v_mfma_f32_16x16x32_bf16 v[32:35], v[176:179], v[208:211], v[32:35]
	s_setprio 0
	s_barrier
; #define G_STAGE(bufoff, gbase, voff) do { _Pragma("unroll") for (int _i = 0; _i < 2; ++_i) \
;         __builtin_amdgcn_global_load_lds((const unsigned*)((const char*)(gbase) + voff[_i]), (LAS unsigned*)(lds + (bufoff) + ldsw + _i * 8192), 16, 0, 0); } while (0)
; #define G_LDA(dst, b, h) do { _Pragma("unroll") for (int m = 0; m < 4; ++m) _Pragma("unroll") for (int k = 0; k < 2; ++k) dst[m][k] = *(const LAS bf16x8*)(lds + G_SA(b, h) + aoff + m * 2048 + k * 1024); } while (0)
; #define G_LDB(dst, b, h) do { _Pragma("unroll") for (int n = 0; n < 2; ++n) _Pragma("unroll") for (int k = 0; k < 2; ++k) dst[n][k] = *(const LAS bf16x8*)(lds + G_SB(b, h) + boff + n * 2048 + k * 1024); } while (0)
; #define G_MMA(ai, bj, At_, Bt_) do { __builtin_amdgcn_s_setprio(1); _Pragma("unroll") for (int m = 0; m < 4; ++m) _Pragma("unroll") for (int n = 0; n < 2; ++n) _Pragma("unroll") for (int k = 0; k < 2; ++k) \
;         acc[ai][bj][m][n] = __builtin_amdgcn_mfma_f32_16x16x32_bf16(Bt_[n][k], At_[m][k], acc[ai][bj][m][n], 0, 0, 0); __builtin_amdgcn_s_setprio(0); } while (0)
; #define WAIT_V(n) asm volatile("s_waitcnt vmcnt(" #n ")" ::: "memory")
; #define WAIT_L(n) asm volatile("s_waitcnt lgkmcnt(" #n ")" ::: "memory")
; #define BAR __builtin_amdgcn_s_barrier()
; #define SCHED __builtin_amdgcn_sched_barrier(0)
; template <class Get, class Epi>
; DI void gemm_loop(int ntiles, int ld, char* shm, const Get& get, const Epi& epi) {
;     ...
;             const char* a2 = last ? nA : cA + (size_t)(t + 2) * kstep; const char* b2 = last ? nB : cB + (size_t)(t + 2) * kstep;
;             const char* a3 = a2 + kstep; const char* b3 = b2 + kstep;
;             G_LDB(B0, 0, 0); G_LDB(B1, 0, 1); SCHED; G_LDA(At, 0, 0); G_STAGE(G_SA(1, 1), a1 + hstep, voffA);
;             WAIT_V(8); WAIT_L(0); BAR; G_MMA(0, 0, At, B0); G_MMA(0, 1, At, B1); BAR; SCHED;
;     ...
;             G_LDA(At, 1, 1); G_STAGE(G_SB(1, 0), b3, voffB); G_STAGE(G_SB(1, 1), b3 + hstep, voffB); G_STAGE(G_SA(1, 0), a3, voffA);
;             WAIT_V(8); WAIT_L(0); BAR; G_MMA(1, 0, At, B0); G_MMA(1, 1, At, B1); BAR; SCHED;
	s_add_i32 s4, s78, s44
	v_lshl_add_u64 v[144:145], v[144:145], 0, s[10:11]
	s_mov_b32 m0, s4
	ds_read_b128 v[180:183], v171 offset:49152
	ds_read_b128 v[184:187], v171 offset:50176
	ds_read_b128 v[188:191], v171 offset:51200
	ds_read_b128 v[192:195], v171 offset:52224
	ds_read_b128 v[196:199], v171 offset:53248
	ds_read_b128 v[200:203], v171 offset:54272
	ds_read_b128 v[204:207], v171 offset:55296
	ds_read_b128 v[208:211], v171 offset:56320
	global_load_lds_dwordx4 v[144:145], off
	s_add_i32 m0, s4, 0x2000
	s_add_u32 s4, s40, 0xb0080
	v_lshl_add_u64 v[144:145], v[166:167], 0, s[10:11]
	s_addc_u32 s5, s41, 0
	s_add_i32 s40, s79, s44
	global_load_lds_dwordx4 v[144:145], off
	v_lshl_add_u64 v[144:145], s[4:5], 0, v[148:149]
	s_mov_b32 m0, s40
	s_nop 0
	global_load_lds_dwordx4 v[144:145], off
	v_lshl_add_u64 v[144:145], s[4:5], 0, v[152:153]
	s_add_i32 m0, s40, 0x2000
	s_nop 0
	global_load_lds_dwordx4 v[144:145], off
	v_lshl_add_u64 v[144:145], v[212:213], 0, s[10:11]
	s_mov_b32 m0, s51
	s_nop 0
	global_load_lds_dwordx4 v[144:145], off
	v_lshl_add_u64 v[144:145], v[214:215], 0, s[10:11]
	s_mov_b32 m0, s52
	s_nop 0
	global_load_lds_dwordx4 v[144:145], off
	s_waitcnt vmcnt(8)
	s_waitcnt lgkmcnt(0)
	s_barrier
	s_setprio 1
	v_mfma_f32_16x16x32_bf16 v[92:95], v[128:131], v[180:183], v[92:95]
	v_mfma_f32_16x16x32_bf16 v[88:91], v[136:139], v[180:183], v[88:91]
	v_mfma_f32_16x16x32_bf16 v[84:87], v[128:131], v[188:191], v[84:87]
	v_mfma_f32_16x16x32_bf16 v[80:83], v[136:139], v[188:191], v[80:83]
	v_mfma_f32_16x16x32_bf16 v[76:79], v[128:131], v[196:199], v[76:79]
	v_mfma_f32_16x16x32_bf16 v[72:75], v[136:139], v[196:199], v[72:75]
	v_mfma_f32_16x16x32_bf16 v[68:71], v[128:131], v[204:207], v[68:71]
	v_mfma_f32_16x16x32_bf16 v[64:67], v[136:139], v[204:207], v[64:67]
	v_mfma_f32_16x16x32_bf16 v[92:95], v[132:135], v[184:187], v[92:95]
	v_mfma_f32_16x16x32_bf16 v[88:91], v[140:143], v[184:187], v[88:91]
	v_mfma_f32_16x16x32_bf16 v[84:87], v[132:135], v[192:195], v[84:87]
	v_mfma_f32_16x16x32_bf16 v[80:83], v[140:143], v[192:195], v[80:83]
	v_mfma_f32_16x16x32_bf16 v[76:79], v[132:135], v[200:203], v[76:79]
	v_mfma_f32_16x16x32_bf16 v[72:75], v[140:143], v[200:203], v[72:75]
	v_mfma_f32_16x16x32_bf16 v[68:71], v[132:135], v[208:211], v[68:71]
	v_mfma_f32_16x16x32_bf16 v[64:67], v[140:143], v[208:211], v[64:67]
	s_setprio 0
	s_setprio 1
	v_mfma_f32_16x16x32_bf16 v[28:31], v[158:161], v[180:183], v[28:31]
	v_mfma_f32_16x16x32_bf16 v[24:27], v[172:175], v[180:183], v[24:27]
	v_mfma_f32_16x16x32_bf16 v[20:23], v[158:161], v[188:191], v[20:23]
	v_mfma_f32_16x16x32_bf16 v[16:19], v[172:175], v[188:191], v[16:19]
	v_mfma_f32_16x16x32_bf16 v[12:15], v[158:161], v[196:199], v[12:15]
	v_mfma_f32_16x16x32_bf16 v[8:11], v[172:175], v[196:199], v[8:11]
	v_mfma_f32_16x16x32_bf16 v[4:7], v[158:161], v[204:207], v[4:7]
	v_mfma_f32_16x16x32_bf16 v[0:3], v[172:175], v[204:207], v[0:3]
	v_mfma_f32_16x16x32_bf16 v[28:31], v[162:165], v[184:187], v[28:31]
	v_mfma_f32_16x16x32_bf16 v[24:27], v[176:179], v[184:187], v[24:27]
	v_mfma_f32_16x16x32_bf16 v[20:23], v[162:165], v[192:195], v[20:23]
	v_mfma_f32_16x16x32_bf16 v[16:19], v[176:179], v[192:195], v[16:19]
	v_mfma_f32_16x16x32_bf16 v[12:15], v[162:165], v[200:203], v[12:15]
	v_mfma_f32_16x16x32_bf16 v[8:11], v[176:179], v[200:203], v[8:11]
	v_mfma_f32_16x16x32_bf16 v[4:7], v[162:165], v[208:211], v[4:7]
	v_mfma_f32_16x16x32_bf16 v[0:3], v[176:179], v[208:211], v[0:3]
	s_setprio 0
	s_barrier
	s_add_u32 s75, s75, 0x100
	s_addc_u32 s76, s76, 0
	s_cmp_ge_u32 s77, s73
	s_mov_b64 s[4:5], s[14:15]
	s_mov_b32 s40, s77
	s_cbranch_scc0 .LBB0_1781
	s_branch .Lpost_1781
.LBB0_1781:
	ds_read_b128 v[128:131], v169
	ds_read_b128 v[132:135], v169 offset:1024
	ds_read_b128 v[136:139], v169 offset:2048
	ds_read_b128 v[140:143], v169 offset:3072
	ds_read_b128 v[158:161], v170
	ds_read_b128 v[162:165], v170 offset:1024
	ds_read_b128 v[172:175], v170 offset:2048
	ds_read_b128 v[176:179], v170 offset:3072
	s_add_i32 s77, s40, 2
	s_add_u32 s14, s4, 0x100
	s_addc_u32 s15, s5, 0
	s_cmp_eq_u32 s74, s40
	s_cselect_b32 s40, s38, s75
	s_cselect_b32 s43, s37, s15
	s_cselect_b32 s42, s36, s14
	s_cselect_b32 s41, s39, s76
	v_lshl_add_u64 v[144:145], s[4:5], 0, v[154:155]
	s_add_i32 m0, s45, 0xc000
	ds_read_b128 v[180:183], v171
	ds_read_b128 v[184:187], v171 offset:1024
	ds_read_b128 v[188:191], v171 offset:2048
	ds_read_b128 v[192:195], v171 offset:3072
	ds_read_b128 v[196:199], v171 offset:4096
	ds_read_b128 v[200:203], v171 offset:5120
	ds_read_b128 v[204:207], v171 offset:6144
	ds_read_b128 v[208:211], v171 offset:7168
	global_load_lds_dwordx4 v[144:145], off
	v_lshl_add_u64 v[144:145], s[4:5], 0, v[156:157]
	s_add_i32 m0, s45, 0xe000
	s_nop 0
	global_load_lds_dwordx4 v[144:145], off
	s_waitcnt vmcnt(8)
	s_waitcnt lgkmcnt(0)
	s_barrier
; #define G_STAGE(bufoff, gbase, voff) do { _Pragma("unroll") for (int _i = 0; _i < 2; ++_i) \
;         __builtin_amdgcn_global_load_lds((const unsigned*)((const char*)(gbase) + voff[_i]), (LAS unsigned*)(lds + (bufoff) + ldsw + _i * 8192), 16, 0, 0); } while (0)
; #define G_LDA(dst, b, h) do { _Pragma("unroll") for (int m = 0; m < 4; ++m) _Pragma("unroll") for (int k = 0; k < 2; ++k) dst[m][k] = *(const LAS bf16x8*)(lds + G_SA(b, h) + aoff + m * 2048 + k * 1024); } while (0)
; #define G_MMA(ai, bj, At_, Bt_) do { __builtin_amdgcn_s_setprio(1); _Pragma("unroll") for (int m = 0; m < 4; ++m) _Pragma("unroll") for (int n = 0; n < 2; ++n) _Pragma("unroll") for (int k = 0; k < 2; ++k) \
;         acc[ai][bj][m][n] = __builtin_amdgcn_mfma_f32_16x16x32_bf16(Bt_[n][k], At_[m][k], acc[ai][bj][m][n], 0, 0, 0); __builtin_amdgcn_s_setprio(0); } while (0)
; #define WAIT_V(n) asm volatile("s_waitcnt vmcnt(" #n ")" ::: "memory")
; #define WAIT_L(n) asm volatile("s_waitcnt lgkmcnt(" #n ")" ::: "memory")
; #define BAR __builtin_amdgcn_s_barrier()
; #define SCHED __builtin_amdgcn_sched_barrier(0)
; template <class Get, class Epi>
; DI void gemm_loop(int ntiles, int ld, char* shm, const Get& get, const Epi& epi) {
;     ...
;             WAIT_V(8); WAIT_L(0); BAR; G_MMA(0, 0, At, B0); G_MMA(0, 1, At, B1); BAR; SCHED;
;             G_LDA(At, 0, 1); G_STAGE(G_SB(0, 0), b2, voffB); G_STAGE(G_SB(0, 1), b2 + hstep, voffB); G_STAGE(G_SA(0, 0), a2, voffA);
;             WAIT_V(8); WAIT_L(0); BAR; G_MMA(1, 0, At, B0); G_MMA(1, 1, At, B1); BAR; SCHED;
	s_setprio 1
	v_mfma_f32_16x16x32_bf16 v[124:127], v[128:131], v[180:183], v[124:127]
	v_mfma_f32_16x16x32_bf16 v[120:123], v[136:139], v[180:183], v[120:123]
	v_mfma_f32_16x16x32_bf16 v[116:119], v[128:131], v[188:191], v[116:119]
	v_mfma_f32_16x16x32_bf16 v[112:115], v[136:139], v[188:191], v[112:115]
	v_mfma_f32_16x16x32_bf16 v[108:111], v[128:131], v[196:199], v[108:111]
	v_mfma_f32_16x16x32_bf16 v[104:107], v[136:139], v[196:199], v[104:107]
	v_mfma_f32_16x16x32_bf16 v[100:103], v[128:131], v[204:207], v[100:103]
	v_mfma_f32_16x16x32_bf16 v[96:99], v[136:139], v[204:207], v[96:99]
	v_mfma_f32_16x16x32_bf16 v[124:127], v[132:135], v[184:187], v[124:127]
	v_mfma_f32_16x16x32_bf16 v[120:123], v[140:143], v[184:187], v[120:123]
	v_mfma_f32_16x16x32_bf16 v[116:119], v[132:135], v[192:195], v[116:119]
	v_mfma_f32_16x16x32_bf16 v[112:115], v[140:143], v[192:195], v[112:115]
	v_mfma_f32_16x16x32_bf16 v[108:111], v[132:135], v[200:203], v[108:111]
	v_mfma_f32_16x16x32_bf16 v[104:107], v[140:143], v[200:203], v[104:107]
	v_mfma_f32_16x16x32_bf16 v[100:103], v[132:135], v[208:211], v[100:103]
	v_mfma_f32_16x16x32_bf16 v[96:99], v[140:143], v[208:211], v[96:99]
	s_setprio 0
	s_setprio 1
	v_mfma_f32_16x16x32_bf16 v[60:63], v[158:161], v[180:183], v[60:63]
	v_mfma_f32_16x16x32_bf16 v[56:59], v[172:175], v[180:183], v[56:59]
	v_mfma_f32_16x16x32_bf16 v[52:55], v[158:161], v[188:191], v[52:55]
	v_mfma_f32_16x16x32_bf16 v[48:51], v[172:175], v[188:191], v[48:51]
	v_mfma_f32_16x16x32_bf16 v[44:47], v[158:161], v[196:199], v[44:47]
	v_mfma_f32_16x16x32_bf16 v[40:43], v[172:175], v[196:199], v[40:43]
	v_mfma_f32_16x16x32_bf16 v[36:39], v[158:161], v[204:207], v[36:39]
	v_mfma_f32_16x16x32_bf16 v[32:35], v[172:175], v[204:207], v[32:35]
	v_mfma_f32_16x16x32_bf16 v[60:63], v[162:165], v[184:187], v[60:63]
	v_mfma_f32_16x16x32_bf16 v[56:59], v[176:179], v[184:187], v[56:59]
	v_mfma_f32_16x16x32_bf16 v[52:55], v[162:165], v[192:195], v[52:55]
	v_mfma_f32_16x16x32_bf16 v[48:51], v[176:179], v[192:195], v[48:51]
	v_mfma_f32_16x16x32_bf16 v[44:47], v[162:165], v[200:203], v[44:47]
	v_mfma_f32_16x16x32_bf16 v[40:43], v[176:179], v[200:203], v[40:43]
	v_mfma_f32_16x16x32_bf16 v[36:39], v[162:165], v[208:211], v[36:39]
	v_mfma_f32_16x16x32_bf16 v[32:35], v[176:179], v[208:211], v[32:35]
	s_setprio 0
	s_barrier
	s_add_i32 s4, s53, s44
	v_lshl_add_u64 v[144:145], s[40:41], 0, v[148:149]
	s_mov_b32 m0, s4
	ds_read_b128 v[180:183], v171 offset:16384
	ds_read_b128 v[184:187], v171 offset:17408
	ds_read_b128 v[188:191], v171 offset:18432
	ds_read_b128 v[192:195], v171 offset:19456
	ds_read_b128 v[196:199], v171 offset:20480
	ds_read_b128 v[200:203], v171 offset:21504
	ds_read_b128 v[204:207], v171 offset:22528
	ds_read_b128 v[208:211], v171 offset:23552
	global_load_lds_dwordx4 v[144:145], off
	s_add_i32 m0, s4, 0x2000
	s_add_u32 s4, s40, 0xb0000
	v_lshl_add_u64 v[166:167], s[40:41], 0, v[152:153]
	s_addc_u32 s5, s41, 0
	s_add_i32 s78, s54, s44
	global_load_lds_dwordx4 v[166:167], off
	v_lshl_add_u64 v[212:213], s[4:5], 0, v[148:149]
	s_mov_b32 m0, s78
	v_lshl_add_u64 v[214:215], s[42:43], 0, v[150:151]
	global_load_lds_dwordx4 v[212:213], off
	v_lshl_add_u64 v[212:213], s[4:5], 0, v[152:153]
	s_add_i32 m0, s78, 0x2000
	s_nop 0
	global_load_lds_dwordx4 v[212:213], off
	v_lshl_add_u64 v[212:213], s[42:43], 0, v[146:147]
	s_mov_b32 m0, s45
	s_nop 0
	global_load_lds_dwordx4 v[212:213], off
	s_mov_b32 m0, s46
	s_nop 0
	global_load_lds_dwordx4 v[214:215], off
	s_waitcnt vmcnt(8)
	s_waitcnt lgkmcnt(0)
	s_barrier
	s_setprio 1
	v_mfma_f32_16x16x32_bf16 v[92:95], v[128:131], v[180:183], v[92:95]
	v_mfma_f32_16x16x32_bf16 v[88:91], v[136:139], v[180:183], v[88:91]
	v_mfma_f32_16x16x32_bf16 v[84:87], v[128:131], v[188:191], v[84:87]
	v_mfma_f32_16x16x32_bf16 v[80:83], v[136:139], v[188:191], v[80:83]
	v_mfma_f32_16x16x32_bf16 v[76:79], v[128:131], v[196:199], v[76:79]
	v_mfma_f32_16x16x32_bf16 v[72:75], v[136:139], v[196:199], v[72:75]
	v_mfma_f32_16x16x32_bf16 v[68:71], v[128:131], v[204:207], v[68:71]
	v_mfma_f32_16x16x32_bf16 v[64:67], v[136:139], v[204:207], v[64:67]
	v_mfma_f32_16x16x32_bf16 v[92:95], v[132:135], v[184:187], v[92:95]
	v_mfma_f32_16x16x32_bf16 v[88:91], v[140:143], v[184:187], v[88:91]
	v_mfma_f32_16x16x32_bf16 v[84:87], v[132:135], v[192:195], v[84:87]
	v_mfma_f32_16x16x32_bf16 v[80:83], v[140:143], v[192:195], v[80:83]
	v_mfma_f32_16x16x32_bf16 v[76:79], v[132:135], v[200:203], v[76:79]
	v_mfma_f32_16x16x32_bf16 v[72:75], v[140:143], v[200:203], v[72:75]
	v_mfma_f32_16x16x32_bf16 v[68:71], v[132:135], v[208:211], v[68:71]
	v_mfma_f32_16x16x32_bf16 v[64:67], v[140:143], v[208:211], v[64:67]
	s_setprio 0
	s_setprio 1
	v_mfma_f32_16x16x32_bf16 v[28:31], v[158:161], v[180:183], v[28:31]
	v_mfma_f32_16x16x32_bf16 v[24:27], v[172:175], v[180:183], v[24:27]
	v_mfma_f32_16x16x32_bf16 v[20:23], v[158:161], v[188:191], v[20:23]
	v_mfma_f32_16x16x32_bf16 v[16:19], v[172:175], v[188:191], v[16:19]
	v_mfma_f32_16x16x32_bf16 v[12:15], v[158:161], v[196:199], v[12:15]
	v_mfma_f32_16x16x32_bf16 v[8:11], v[172:175], v[196:199], v[8:11]
	v_mfma_f32_16x16x32_bf16 v[4:7], v[158:161], v[204:207], v[4:7]
	v_mfma_f32_16x16x32_bf16 v[0:3], v[172:175], v[204:207], v[0:3]
	v_mfma_f32_16x16x32_bf16 v[28:31], v[162:165], v[184:187], v[28:31]
	v_mfma_f32_16x16x32_bf16 v[24:27], v[176:179], v[184:187], v[24:27]
	v_mfma_f32_16x16x32_bf16 v[20:23], v[162:165], v[192:195], v[20:23]
	v_mfma_f32_16x16x32_bf16 v[16:19], v[176:179], v[192:195], v[16:19]
	v_mfma_f32_16x16x32_bf16 v[12:15], v[162:165], v[200:203], v[12:15]
	v_mfma_f32_16x16x32_bf16 v[8:11], v[176:179], v[200:203], v[8:11]
	v_mfma_f32_16x16x32_bf16 v[4:7], v[162:165], v[208:211], v[4:7]
	v_mfma_f32_16x16x32_bf16 v[0:3], v[176:179], v[208:211], v[0:3]
	s_setprio 0
	s_barrier
; #define G_STAGE(bufoff, gbase, voff) do { _Pragma("unroll") for (int _i = 0; _i < 2; ++_i) \
;         __builtin_amdgcn_global_load_lds((const unsigned*)((const char*)(gbase) + voff[_i]), (LAS unsigned*)(lds + (bufoff) + ldsw + _i * 8192), 16, 0, 0); } while (0)
; #define G_LDA(dst, b, h) do { _Pragma("unroll") for (int m = 0; m < 4; ++m) _Pragma("unroll") for (int k = 0; k < 2; ++k) dst[m][k] = *(const LAS bf16x8*)(lds + G_SA(b, h) + aoff + m * 2048 + k * 1024); } while (0)
; #define G_LDB(dst, b, h) do { _Pragma("unroll") for (int n = 0; n < 2; ++n) _Pragma("unroll") for (int k = 0; k < 2; ++k) dst[n][k] = *(const LAS bf16x8*)(lds + G_SB(b, h) + boff + n * 2048 + k * 1024); } while (0)
; #define G_MMA(ai, bj, At_, Bt_) do { __builtin_amdgcn_s_setprio(1); _Pragma("unroll") for (int m = 0; m < 4; ++m) _Pragma("unroll") for (int n = 0; n < 2; ++n) _Pragma("unroll") for (int k = 0; k < 2; ++k) \
;         acc[ai][bj][m][n] = __builtin_amdgcn_mfma_f32_16x16x32_bf16(Bt_[n][k], At_[m][k], acc[ai][bj][m][n], 0, 0, 0); __builtin_amdgcn_s_setprio(0); } while (0)
; #define WAIT_V(n) asm volatile("s_waitcnt vmcnt(" #n ")" ::: "memory")
; #define WAIT_L(n) asm volatile("s_waitcnt lgkmcnt(" #n ")" ::: "memory")
; #define BAR __builtin_amdgcn_s_barrier()
; #define SCHED __builtin_amdgcn_sched_barrier(0)
; template <class Get, class Epi>
; DI void gemm_loop(int ntiles, int ld, char* shm, const Get& get, const Epi& epi) {
;     ...
;             G_LDB(B0, 1, 0); G_LDB(B1, 1, 1); SCHED; G_LDA(At, 1, 0); G_STAGE(G_SA(0, 1), a2 + hstep, voffA);
;             WAIT_V(8); WAIT_L(0); BAR; G_MMA(0, 0, At, B0); G_MMA(0, 1, At, B1); BAR; SCHED;
	s_add_i32 s78, 0, 0x18000
	s_add_i32 s79, 0, 0x1c000
	v_add_u32_e32 v140, s78, v168
	v_add_u32_e32 v176, s79, v168
	ds_read_b128 v[128:131], v140
	ds_read_b128 v[132:135], v140 offset:1024
	ds_read_b128 v[136:139], v140 offset:2048
	ds_read_b128 v[140:143], v140 offset:3072
	ds_read_b128 v[158:161], v176
	ds_read_b128 v[162:165], v176 offset:1024
	ds_read_b128 v[172:175], v176 offset:2048
	ds_read_b128 v[176:179], v176 offset:3072
	s_add_u32 s4, s42, 0xb0000
	s_addc_u32 s5, s43, 0
	s_mov_b32 m0, s47
	v_lshl_add_u64 v[216:217], s[4:5], 0, v[146:147]
	ds_read_b128 v[180:183], v171 offset:32768
	ds_read_b128 v[184:187], v171 offset:33792
	ds_read_b128 v[188:191], v171 offset:34816
	ds_read_b128 v[192:195], v171 offset:35840
	ds_read_b128 v[196:199], v171 offset:36864
	ds_read_b128 v[200:203], v171 offset:37888
	ds_read_b128 v[204:207], v171 offset:38912
	ds_read_b128 v[208:211], v171 offset:39936
	global_load_lds_dwordx4 v[216:217], off
	v_lshl_add_u64 v[216:217], s[4:5], 0, v[150:151]
	s_mov_b32 m0, s48
	s_nop 0
	global_load_lds_dwordx4 v[216:217], off
	s_waitcnt vmcnt(8)
	s_waitcnt lgkmcnt(0)
	s_barrier
	s_setprio 1
	v_mfma_f32_16x16x32_bf16 v[124:127], v[128:131], v[180:183], v[124:127]
	v_mfma_f32_16x16x32_bf16 v[120:123], v[136:139], v[180:183], v[120:123]
	v_mfma_f32_16x16x32_bf16 v[116:119], v[128:131], v[188:191], v[116:119]
	v_mfma_f32_16x16x32_bf16 v[112:115], v[136:139], v[188:191], v[112:115]
	v_mfma_f32_16x16x32_bf16 v[108:111], v[128:131], v[196:199], v[108:111]
	v_mfma_f32_16x16x32_bf16 v[104:107], v[136:139], v[196:199], v[104:107]
	v_mfma_f32_16x16x32_bf16 v[100:103], v[128:131], v[204:207], v[100:103]
	v_mfma_f32_16x16x32_bf16 v[96:99], v[136:139], v[204:207], v[96:99]
	v_mfma_f32_16x16x32_bf16 v[124:127], v[132:135], v[184:187], v[124:127]
	v_mfma_f32_16x16x32_bf16 v[120:123], v[140:143], v[184:187], v[120:123]
	v_mfma_f32_16x16x32_bf16 v[116:119], v[132:135], v[192:195], v[116:119]
	v_mfma_f32_16x16x32_bf16 v[112:115], v[140:143], v[192:195], v[112:115]
	v_mfma_f32_16x16x32_bf16 v[108:111], v[132:135], v[200:203], v[108:111]
	v_mfma_f32_16x16x32_bf16 v[104:107], v[140:143], v[200:203], v[104:107]
	v_mfma_f32_16x16x32_bf16 v[100:103], v[132:135], v[208:211], v[100:103]
	v_mfma_f32_16x16x32_bf16 v[96:99], v[140:143], v[208:211], v[96:99]
	s_setprio 0
	s_setprio 1
	v_mfma_f32_16x16x32_bf16 v[60:63], v[158:161], v[180:183], v[60:63]
	v_mfma_f32_16x16x32_bf16 v[56:59], v[172:175], v[180:183], v[56:59]
	v_mfma_f32_16x16x32_bf16 v[52:55], v[158:161], v[188:191], v[52:55]
	v_mfma_f32_16x16x32_bf16 v[48:51], v[172:175], v[188:191], v[48:51]
	v_mfma_f32_16x16x32_bf16 v[44:47], v[158:161], v[196:199], v[44:47]
	v_mfma_f32_16x16x32_bf16 v[40:43], v[172:175], v[196:199], v[40:43]
	v_mfma_f32_16x16x32_bf16 v[36:39], v[158:161], v[204:207], v[36:39]
	v_mfma_f32_16x16x32_bf16 v[32:35], v[172:175], v[204:207], v[32:35]
	v_mfma_f32_16x16x32_bf16 v[60:63], v[162:165], v[184:187], v[60:63]
	v_mfma_f32_16x16x32_bf16 v[56:59], v[176:179], v[184:187], v[56:59]
	v_mfma_f32_16x16x32_bf16 v[52:55], v[162:165], v[192:195], v[52:55]
	v_mfma_f32_16x16x32_bf16 v[48:51], v[176:179], v[192:195], v[48:51]
	v_mfma_f32_16x16x32_bf16 v[44:47], v[162:165], v[200:203], v[44:47]
	v_mfma_f32_16x16x32_bf16 v[40:43], v[176:179], v[200:203], v[40:43]
	v_mfma_f32_16x16x32_bf16 v[36:39], v[162:165], v[208:211], v[36:39]
	v_mfma_f32_16x16x32_bf16 v[32:35], v[176:179], v[208:211], v[32:35]
	s_setprio 0
	s_barrier
; #define G_STAGE(bufoff, gbase, voff) do { _Pragma("unroll") for (int _i = 0; _i < 2; ++_i) \
;         __builtin_amdgcn_global_load_lds((const unsigned*)((const char*)(gbase) + voff[_i]), (LAS unsigned*)(lds + (bufoff) + ldsw + _i * 8192), 16, 0, 0); } while (0)
; #define G_LDA(dst, b, h) do { _Pragma("unroll") for (int m = 0; m < 4; ++m) _Pragma("unroll") for (int k = 0; k < 2; ++k) dst[m][k] = *(const LAS bf16x8*)(lds + G_SA(b, h) + aoff + m * 2048 + k * 1024); } while (0)
; #define G_MMA(ai, bj, At_, Bt_) do { __builtin_amdgcn_s_setprio(1); _Pragma("unroll") for (int m = 0; m < 4; ++m) _Pragma("unroll") for (int n = 0; n < 2; ++n) _Pragma("unroll") for (int k = 0; k < 2; ++k) \
;         acc[ai][bj][m][n] = __builtin_amdgcn_mfma_f32_16x16x32_bf16(Bt_[n][k], At_[m][k], acc[ai][bj][m][n], 0, 0, 0); __builtin_amdgcn_s_setprio(0); } while (0)
; #define WAIT_V(n) asm volatile("s_waitcnt vmcnt(" #n ")" ::: "memory")
; #define WAIT_L(n) asm volatile("s_waitcnt lgkmcnt(" #n ")" ::: "memory")
; #define BAR __builtin_amdgcn_s_barrier()
; #define SCHED __builtin_amdgcn_sched_barrier(0)
; template <class Get, class Epi>
; DI void gemm_loop(int ntiles, int ld, char* shm, const Get& get, const Epi& epi) {
;     ...
;             G_LDA(At, 1, 1); G_STAGE(G_SB(1, 0), b3, voffB); G_STAGE(G_SB(1, 1), b3 + hstep, voffB); G_STAGE(G_SA(1, 0), a3, voffA);
;             WAIT_V(8); WAIT_L(0); BAR; G_MMA(1, 0, At, B0); G_MMA(1, 1, At, B1); BAR; SCHED;
	s_add_i32 s4, s78, s44
	v_lshl_add_u64 v[144:145], v[144:145], 0, s[10:11]
	s_mov_b32 m0, s4
	ds_read_b128 v[180:183], v171 offset:49152
	ds_read_b128 v[184:187], v171 offset:50176
	ds_read_b128 v[188:191], v171 offset:51200
	ds_read_b128 v[192:195], v171 offset:52224
	ds_read_b128 v[196:199], v171 offset:53248
	ds_read_b128 v[200:203], v171 offset:54272
	ds_read_b128 v[204:207], v171 offset:55296
	ds_read_b128 v[208:211], v171 offset:56320
	global_load_lds_dwordx4 v[144:145], off
	s_add_i32 m0, s4, 0x2000
	s_add_u32 s4, s40, 0xb0080
	v_lshl_add_u64 v[144:145], v[166:167], 0, s[10:11]
	s_addc_u32 s5, s41, 0
	s_add_i32 s40, s79, s44
	global_load_lds_dwordx4 v[144:145], off
	v_lshl_add_u64 v[144:145], s[4:5], 0, v[148:149]
	s_mov_b32 m0, s40
	s_nop 0
	global_load_lds_dwordx4 v[144:145], off
	v_lshl_add_u64 v[144:145], s[4:5], 0, v[152:153]
	s_add_i32 m0, s40, 0x2000
	s_nop 0
	global_load_lds_dwordx4 v[144:145], off
	v_lshl_add_u64 v[144:145], v[212:213], 0, s[10:11]
	s_mov_b32 m0, s51
	s_nop 0
	global_load_lds_dwordx4 v[144:145], off
	v_lshl_add_u64 v[144:145], v[214:215], 0, s[10:11]
	s_mov_b32 m0, s52
	s_nop 0
	global_load_lds_dwordx4 v[144:145], off
	s_waitcnt vmcnt(8)
	s_waitcnt lgkmcnt(0)
	s_barrier
	s_setprio 1
	v_mfma_f32_16x16x32_bf16 v[92:95], v[128:131], v[180:183], v[92:95]
	v_mfma_f32_16x16x32_bf16 v[88:91], v[136:139], v[180:183], v[88:91]
	v_mfma_f32_16x16x32_bf16 v[84:87], v[128:131], v[188:191], v[84:87]
	v_mfma_f32_16x16x32_bf16 v[80:83], v[136:139], v[188:191], v[80:83]
	v_mfma_f32_16x16x32_bf16 v[76:79], v[128:131], v[196:199], v[76:79]
	v_mfma_f32_16x16x32_bf16 v[72:75], v[136:139], v[196:199], v[72:75]
	v_mfma_f32_16x16x32_bf16 v[68:71], v[128:131], v[204:207], v[68:71]
	v_mfma_f32_16x16x32_bf16 v[64:67], v[136:139], v[204:207], v[64:67]
	v_mfma_f32_16x16x32_bf16 v[92:95], v[132:135], v[184:187], v[92:95]
	v_mfma_f32_16x16x32_bf16 v[88:91], v[140:143], v[184:187], v[88:91]
	v_mfma_f32_16x16x32_bf16 v[84:87], v[132:135], v[192:195], v[84:87]
	v_mfma_f32_16x16x32_bf16 v[80:83], v[140:143], v[192:195], v[80:83]
	v_mfma_f32_16x16x32_bf16 v[76:79], v[132:135], v[200:203], v[76:79]
	v_mfma_f32_16x16x32_bf16 v[72:75], v[140:143], v[200:203], v[72:75]
	v_mfma_f32_16x16x32_bf16 v[68:71], v[132:135], v[208:211], v[68:71]
	v_mfma_f32_16x16x32_bf16 v[64:67], v[140:143], v[208:211], v[64:67]
	s_setprio 0
	s_setprio 1
	v_mfma_f32_16x16x32_bf16 v[28:31], v[158:161], v[180:183], v[28:31]
	v_mfma_f32_16x16x32_bf16 v[24:27], v[172:175], v[180:183], v[24:27]
	v_mfma_f32_16x16x32_bf16 v[20:23], v[158:161], v[188:191], v[20:23]
	v_mfma_f32_16x16x32_bf16 v[16:19], v[172:175], v[188:191], v[16:19]
	v_mfma_f32_16x16x32_bf16 v[12:15], v[158:161], v[196:199], v[12:15]
	v_mfma_f32_16x16x32_bf16 v[8:11], v[172:175], v[196:199], v[8:11]
	v_mfma_f32_16x16x32_bf16 v[4:7], v[158:161], v[204:207], v[4:7]
	v_mfma_f32_16x16x32_bf16 v[0:3], v[172:175], v[204:207], v[0:3]
	v_mfma_f32_16x16x32_bf16 v[28:31], v[162:165], v[184:187], v[28:31]
	v_mfma_f32_16x16x32_bf16 v[24:27], v[176:179], v[184:187], v[24:27]
	v_mfma_f32_16x16x32_bf16 v[20:23], v[162:165], v[192:195], v[20:23]
	v_mfma_f32_16x16x32_bf16 v[16:19], v[176:179], v[192:195], v[16:19]
	v_mfma_f32_16x16x32_bf16 v[12:15], v[162:165], v[200:203], v[12:15]
	v_mfma_f32_16x16x32_bf16 v[8:11], v[176:179], v[200:203], v[8:11]
	v_mfma_f32_16x16x32_bf16 v[4:7], v[162:165], v[208:211], v[4:7]
	v_mfma_f32_16x16x32_bf16 v[0:3], v[176:179], v[208:211], v[0:3]
	s_setprio 0
	s_barrier
	s_add_u32 s75, s75, 0x100
	s_addc_u32 s76, s76, 0
	s_cmp_ge_u32 s77, s73
	s_mov_b64 s[4:5], s[14:15]
	s_mov_b32 s40, s77
	s_cbranch_scc0 .LBB0_1781

; #define G_STAGE(bufoff, gbase, voff) do { _Pragma("unroll") for (int _i = 0; _i < 2; ++_i) \
;         __builtin_amdgcn_global_load_lds((const unsigned*)((const char*)(gbase) + voff[_i]), (LAS unsigned*)(lds + (bufoff) + ldsw + _i * 8192), 16, 0, 0); } while (0)
; #define G_LDA(dst, b, h) do { _Pragma("unroll") for (int m = 0; m < 4; ++m) _Pragma("unroll") for (int k = 0; k < 2; ++k) dst[m][k] = *(const LAS bf16x8*)(lds + G_SA(b, h) + aoff + m * 2048 + k * 1024); } while (0)
; #define G_MMA(ai, bj, At_, Bt_) do { __builtin_amdgcn_s_setprio(1); _Pragma("unroll") for (int m = 0; m < 4; ++m) _Pragma("unroll") for (int n = 0; n < 2; ++n) _Pragma("unroll") for (int k = 0; k < 2; ++k) \
;         acc[ai][bj][m][n] = __builtin_amdgcn_mfma_f32_16x16x32_bf16(Bt_[n][k], At_[m][k], acc[ai][bj][m][n], 0, 0, 0); __builtin_amdgcn_s_setprio(0); } while (0)
; #define WAIT_V(n) asm volatile("s_waitcnt vmcnt(" #n ")" ::: "memory")
; #define WAIT_L(n) asm volatile("s_waitcnt lgkmcnt(" #n ")" ::: "memory")
; #define BAR __builtin_amdgcn_s_barrier()
; #define SCHED __builtin_amdgcn_sched_barrier(0)
; template <class Get, class Epi>
; DI void gemm_loop(int ntiles, int ld, char* shm, const Get& get, const Epi& epi) {
;     ...
;             WAIT_V(8); WAIT_L(0); BAR; G_MMA(0, 0, At, B0); G_MMA(0, 1, At, B1); BAR; SCHED;
;             G_LDA(At, 0, 1); G_STAGE(G_SB(0, 0), b2, voffB); G_STAGE(G_SB(0, 1), b2 + hstep, voffB); G_STAGE(G_SA(0, 0), a2, voffA);
.Lrj_2022_0:
	s_waitcnt lgkmcnt(0)
	s_barrier
	s_setprio 1
	v_mfma_f32_16x16x32_bf16 v[132:135], v[96:99], v[184:187], 0
	v_mfma_f32_16x16x32_bf16 v[124:127], v[150:153], v[184:187], 0
	v_mfma_f32_16x16x32_bf16 v[128:131], v[96:99], v[192:195], 0
	v_mfma_f32_16x16x32_bf16 v[120:123], v[150:153], v[192:195], 0
	v_mfma_f32_16x16x32_bf16 v[116:119], v[96:99], v[200:203], 0
	v_mfma_f32_16x16x32_bf16 v[104:107], v[150:153], v[200:203], 0
	v_mfma_f32_16x16x32_bf16 v[112:115], v[96:99], v[208:211], 0
	v_mfma_f32_16x16x32_bf16 v[100:103], v[150:153], v[208:211], 0
	v_mfma_f32_16x16x32_bf16 v[132:135], v[108:111], v[188:191], v[132:135]
	v_mfma_f32_16x16x32_bf16 v[124:127], v[154:157], v[188:191], v[124:127]
	v_mfma_f32_16x16x32_bf16 v[128:131], v[108:111], v[196:199], v[128:131]
	v_mfma_f32_16x16x32_bf16 v[120:123], v[154:157], v[196:199], v[120:123]
	v_mfma_f32_16x16x32_bf16 v[116:119], v[108:111], v[204:207], v[116:119]
	v_mfma_f32_16x16x32_bf16 v[104:107], v[154:157], v[204:207], v[104:107]
	v_mfma_f32_16x16x32_bf16 v[112:115], v[108:111], v[212:215], v[112:115]
	v_mfma_f32_16x16x32_bf16 v[100:103], v[154:157], v[212:215], v[100:103]
	s_setprio 0
	s_setprio 1
	v_mfma_f32_16x16x32_bf16 v[60:63], v[158:161], v[184:187], 0
	v_mfma_f32_16x16x32_bf16 v[52:55], v[166:169], v[184:187], 0
	v_mfma_f32_16x16x32_bf16 v[56:59], v[158:161], v[192:195], 0
	v_mfma_f32_16x16x32_bf16 v[48:51], v[166:169], v[192:195], 0
	v_mfma_f32_16x16x32_bf16 v[44:47], v[158:161], v[200:203], 0
	v_mfma_f32_16x16x32_bf16 v[36:39], v[166:169], v[200:203], 0
	v_mfma_f32_16x16x32_bf16 v[40:43], v[158:161], v[208:211], 0
	v_mfma_f32_16x16x32_bf16 v[32:35], v[166:169], v[208:211], 0
	v_mfma_f32_16x16x32_bf16 v[60:63], v[162:165], v[188:191], v[60:63]
	v_mfma_f32_16x16x32_bf16 v[52:55], v[180:183], v[188:191], v[52:55]
	v_mfma_f32_16x16x32_bf16 v[56:59], v[162:165], v[196:199], v[56:59]
	v_mfma_f32_16x16x32_bf16 v[48:51], v[180:183], v[196:199], v[48:51]
	v_mfma_f32_16x16x32_bf16 v[44:47], v[162:165], v[204:207], v[44:47]
	v_mfma_f32_16x16x32_bf16 v[36:39], v[180:183], v[204:207], v[36:39]
	v_mfma_f32_16x16x32_bf16 v[40:43], v[162:165], v[212:215], v[40:43]
	v_mfma_f32_16x16x32_bf16 v[32:35], v[180:183], v[212:215], v[32:35]
	s_setprio 0
	s_barrier
	s_add_i32 s57, s75, s46
	v_lshl_add_u64 v[170:171], s[6:7], 0, v[140:141]
	s_mov_b32 m0, s57
	ds_read_b128 v[184:187], v175 offset:16384
	ds_read_b128 v[188:191], v175 offset:17408
	ds_read_b128 v[192:195], v175 offset:18432
	ds_read_b128 v[196:199], v175 offset:19456
	ds_read_b128 v[200:203], v175 offset:20480
	ds_read_b128 v[204:207], v175 offset:21504
	ds_read_b128 v[208:211], v175 offset:22528
	ds_read_b128 v[212:215], v175 offset:23552
	global_load_lds_dwordx4 v[170:171], off
	s_add_i32 m0, s57, 0x2000
	s_add_u32 s58, s6, 0x40000
	v_lshl_add_u64 v[216:217], s[6:7], 0, v[136:137]
	s_addc_u32 s59, s7, 0
	s_add_i32 s57, s76, s46
	global_load_lds_dwordx4 v[216:217], off
	v_lshl_add_u64 v[218:219], s[58:59], 0, v[140:141]
	s_mov_b32 m0, s57
	v_lshl_add_u64 v[220:221], s[14:15], 0, v[138:139]
	global_load_lds_dwordx4 v[218:219], off
	v_lshl_add_u64 v[218:219], s[58:59], 0, v[136:137]
	s_add_i32 m0, s57, 0x2000
	s_nop 0
	global_load_lds_dwordx4 v[218:219], off
	v_lshl_add_u64 v[218:219], s[14:15], 0, v[142:143]
	s_mov_b32 m0, s50
	s_nop 0
	global_load_lds_dwordx4 v[218:219], off
	s_mov_b32 m0, s51
	s_nop 0
	global_load_lds_dwordx4 v[220:221], off
	s_cmp_lg_u32 s100, 0
	s_cbranch_scc0 .Lrf_2022_1
	s_waitcnt vmcnt(16)
	s_branch .Lrj_2022_1

; #define G_STAGE(bufoff, gbase, voff) do { _Pragma("unroll") for (int _i = 0; _i < 2; ++_i) \
;         __builtin_amdgcn_global_load_lds((const unsigned*)((const char*)(gbase) + voff[_i]), (LAS unsigned*)(lds + (bufoff) + ldsw + _i * 8192), 16, 0, 0); } while (0)
; #define G_LDA(dst, b, h) do { _Pragma("unroll") for (int m = 0; m < 4; ++m) _Pragma("unroll") for (int k = 0; k < 2; ++k) dst[m][k] = *(const LAS bf16x8*)(lds + G_SA(b, h) + aoff + m * 2048 + k * 1024); } while (0)
; #define G_LDB(dst, b, h) do { _Pragma("unroll") for (int n = 0; n < 2; ++n) _Pragma("unroll") for (int k = 0; k < 2; ++k) dst[n][k] = *(const LAS bf16x8*)(lds + G_SB(b, h) + boff + n * 2048 + k * 1024); } while (0)
; #define G_MMA(ai, bj, At_, Bt_) do { __builtin_amdgcn_s_setprio(1); _Pragma("unroll") for (int m = 0; m < 4; ++m) _Pragma("unroll") for (int n = 0; n < 2; ++n) _Pragma("unroll") for (int k = 0; k < 2; ++k) \
;         acc[ai][bj][m][n] = __builtin_amdgcn_mfma_f32_16x16x32_bf16(Bt_[n][k], At_[m][k], acc[ai][bj][m][n], 0, 0, 0); __builtin_amdgcn_s_setprio(0); } while (0)
; #define WAIT_V(n) asm volatile("s_waitcnt vmcnt(" #n ")" ::: "memory")
; #define WAIT_L(n) asm volatile("s_waitcnt lgkmcnt(" #n ")" ::: "memory")
; #define BAR __builtin_amdgcn_s_barrier()
; #define SCHED __builtin_amdgcn_sched_barrier(0)
; template <class Get, class Epi>
; DI void gemm_loop(int ntiles, int ld, char* shm, const Get& get, const Epi& epi) {
;     ...
;             WAIT_V(8); WAIT_L(0); BAR; G_MMA(1, 0, At, B0); G_MMA(1, 1, At, B1); BAR; SCHED;
;             G_LDB(B0, 1, 0); G_LDB(B1, 1, 1); SCHED; G_LDA(At, 1, 0); G_STAGE(G_SA(0, 1), a2 + hstep, voffA);
;             WAIT_V(8); WAIT_L(0); BAR; G_MMA(0, 0, At, B0); G_MMA(0, 1, At, B1); BAR; SCHED;
.Lrj_2022_1:
	s_waitcnt lgkmcnt(0)
	s_barrier
	s_setprio 1
	v_mfma_f32_16x16x32_bf16 v[92:95], v[96:99], v[184:187], 0
	v_mfma_f32_16x16x32_bf16 v[84:87], v[150:153], v[184:187], 0
	v_mfma_f32_16x16x32_bf16 v[88:91], v[96:99], v[192:195], 0
	v_mfma_f32_16x16x32_bf16 v[80:83], v[150:153], v[192:195], 0
	v_mfma_f32_16x16x32_bf16 v[76:79], v[96:99], v[200:203], 0
	v_mfma_f32_16x16x32_bf16 v[68:71], v[150:153], v[200:203], 0
	v_mfma_f32_16x16x32_bf16 v[72:75], v[96:99], v[208:211], 0
	v_mfma_f32_16x16x32_bf16 v[64:67], v[150:153], v[208:211], 0
	v_mfma_f32_16x16x32_bf16 v[92:95], v[108:111], v[188:191], v[92:95]
	v_mfma_f32_16x16x32_bf16 v[84:87], v[154:157], v[188:191], v[84:87]
	v_mfma_f32_16x16x32_bf16 v[88:91], v[108:111], v[196:199], v[88:91]
	v_mfma_f32_16x16x32_bf16 v[80:83], v[154:157], v[196:199], v[80:83]
	v_mfma_f32_16x16x32_bf16 v[76:79], v[108:111], v[204:207], v[76:79]
	v_mfma_f32_16x16x32_bf16 v[68:71], v[154:157], v[204:207], v[68:71]
	v_mfma_f32_16x16x32_bf16 v[72:75], v[108:111], v[212:215], v[72:75]
	v_mfma_f32_16x16x32_bf16 v[64:67], v[154:157], v[212:215], v[64:67]
	s_setprio 0
	s_setprio 1
	v_mfma_f32_16x16x32_bf16 v[28:31], v[158:161], v[184:187], 0
	v_mfma_f32_16x16x32_bf16 v[20:23], v[166:169], v[184:187], 0
	v_mfma_f32_16x16x32_bf16 v[24:27], v[158:161], v[192:195], 0
	v_mfma_f32_16x16x32_bf16 v[16:19], v[166:169], v[192:195], 0
	v_mfma_f32_16x16x32_bf16 v[12:15], v[158:161], v[200:203], 0
	v_mfma_f32_16x16x32_bf16 v[4:7], v[166:169], v[200:203], 0
	v_mfma_f32_16x16x32_bf16 v[8:11], v[158:161], v[208:211], 0
	v_mfma_f32_16x16x32_bf16 v[0:3], v[166:169], v[208:211], 0
	v_mfma_f32_16x16x32_bf16 v[28:31], v[162:165], v[188:191], v[28:31]
	v_mfma_f32_16x16x32_bf16 v[20:23], v[180:183], v[188:191], v[20:23]
	v_mfma_f32_16x16x32_bf16 v[24:27], v[162:165], v[196:199], v[24:27]
	v_mfma_f32_16x16x32_bf16 v[16:19], v[180:183], v[196:199], v[16:19]
	v_mfma_f32_16x16x32_bf16 v[12:15], v[162:165], v[204:207], v[12:15]
	v_mfma_f32_16x16x32_bf16 v[4:7], v[180:183], v[204:207], v[4:7]
	v_mfma_f32_16x16x32_bf16 v[8:11], v[162:165], v[212:215], v[8:11]
	v_mfma_f32_16x16x32_bf16 v[0:3], v[180:183], v[212:215], v[0:3]
	s_setprio 0
	s_barrier
	s_add_i32 s57, 0, 0x18000
	v_add_u32_e32 v144, s57, v172
	s_add_i32 s58, 0, 0x1c000
	ds_read_b128 v[96:99], v144
	ds_read_b128 v[108:111], v144 offset:1024
	ds_read_b128 v[150:153], v144 offset:2048
	ds_read_b128 v[154:157], v144 offset:3072
	v_add_u32_e32 v144, s58, v172
	ds_read_b128 v[158:161], v144
	ds_read_b128 v[162:165], v144 offset:1024
	ds_read_b128 v[166:169], v144 offset:2048
	ds_read_b128 v[180:183], v144 offset:3072
	s_add_u32 s14, s14, 0x40000
	s_addc_u32 s15, s15, 0
	s_mov_b32 m0, s71
	v_lshl_add_u64 v[222:223], s[14:15], 0, v[142:143]
	ds_read_b128 v[184:187], v175 offset:32768
	ds_read_b128 v[188:191], v175 offset:33792
	ds_read_b128 v[192:195], v175 offset:34816
	ds_read_b128 v[196:199], v175 offset:35840
	ds_read_b128 v[200:203], v175 offset:36864
	ds_read_b128 v[204:207], v175 offset:37888
	ds_read_b128 v[208:211], v175 offset:38912
	ds_read_b128 v[212:215], v175 offset:39936
	global_load_lds_dwordx4 v[222:223], off
	v_lshl_add_u64 v[222:223], s[14:15], 0, v[138:139]
	s_mov_b32 m0, s72
	s_nop 0
	global_load_lds_dwordx4 v[222:223], off
	s_waitcnt vmcnt(8)
	s_waitcnt lgkmcnt(0)
	s_barrier
	s_setprio 1
	v_mfma_f32_16x16x32_bf16 v[132:135], v[96:99], v[184:187], v[132:135]
	v_mfma_f32_16x16x32_bf16 v[124:127], v[150:153], v[184:187], v[124:127]
	v_mfma_f32_16x16x32_bf16 v[128:131], v[96:99], v[192:195], v[128:131]
	v_mfma_f32_16x16x32_bf16 v[120:123], v[150:153], v[192:195], v[120:123]
	v_mfma_f32_16x16x32_bf16 v[116:119], v[96:99], v[200:203], v[116:119]
	v_mfma_f32_16x16x32_bf16 v[104:107], v[150:153], v[200:203], v[104:107]
	v_mfma_f32_16x16x32_bf16 v[112:115], v[96:99], v[208:211], v[112:115]
	v_mfma_f32_16x16x32_bf16 v[100:103], v[150:153], v[208:211], v[100:103]
	v_mfma_f32_16x16x32_bf16 v[132:135], v[108:111], v[188:191], v[132:135]
	v_mfma_f32_16x16x32_bf16 v[124:127], v[154:157], v[188:191], v[124:127]
	v_mfma_f32_16x16x32_bf16 v[128:131], v[108:111], v[196:199], v[128:131]
	v_mfma_f32_16x16x32_bf16 v[120:123], v[154:157], v[196:199], v[120:123]
	v_mfma_f32_16x16x32_bf16 v[116:119], v[108:111], v[204:207], v[116:119]
	v_mfma_f32_16x16x32_bf16 v[104:107], v[154:157], v[204:207], v[104:107]
	v_mfma_f32_16x16x32_bf16 v[112:115], v[108:111], v[212:215], v[112:115]
	v_mfma_f32_16x16x32_bf16 v[100:103], v[154:157], v[212:215], v[100:103]
	s_setprio 0
	s_setprio 1
	v_mfma_f32_16x16x32_bf16 v[60:63], v[158:161], v[184:187], v[60:63]
	v_mfma_f32_16x16x32_bf16 v[52:55], v[166:169], v[184:187], v[52:55]
	v_mfma_f32_16x16x32_bf16 v[56:59], v[158:161], v[192:195], v[56:59]
	v_mfma_f32_16x16x32_bf16 v[48:51], v[166:169], v[192:195], v[48:51]
	v_mfma_f32_16x16x32_bf16 v[44:47], v[158:161], v[200:203], v[44:47]
	v_mfma_f32_16x16x32_bf16 v[36:39], v[166:169], v[200:203], v[36:39]
	v_mfma_f32_16x16x32_bf16 v[40:43], v[158:161], v[208:211], v[40:43]
	v_mfma_f32_16x16x32_bf16 v[32:35], v[166:169], v[208:211], v[32:35]
	v_mfma_f32_16x16x32_bf16 v[60:63], v[162:165], v[188:191], v[60:63]
	v_mfma_f32_16x16x32_bf16 v[52:55], v[180:183], v[188:191], v[52:55]
	v_mfma_f32_16x16x32_bf16 v[56:59], v[162:165], v[196:199], v[56:59]
	v_mfma_f32_16x16x32_bf16 v[48:51], v[180:183], v[196:199], v[48:51]
	v_mfma_f32_16x16x32_bf16 v[44:47], v[162:165], v[204:207], v[44:47]
	v_mfma_f32_16x16x32_bf16 v[36:39], v[180:183], v[204:207], v[36:39]
	v_mfma_f32_16x16x32_bf16 v[40:43], v[162:165], v[212:215], v[40:43]
	v_mfma_f32_16x16x32_bf16 v[32:35], v[180:183], v[212:215], v[32:35]
	s_setprio 0
	s_barrier
; #define G_STAGE(bufoff, gbase, voff) do { _Pragma("unroll") for (int _i = 0; _i < 2; ++_i) \
;         __builtin_amdgcn_global_load_lds((const unsigned*)((const char*)(gbase) + voff[_i]), (LAS unsigned*)(lds + (bufoff) + ldsw + _i * 8192), 16, 0, 0); } while (0)
; #define G_LDA(dst, b, h) do { _Pragma("unroll") for (int m = 0; m < 4; ++m) _Pragma("unroll") for (int k = 0; k < 2; ++k) dst[m][k] = *(const LAS bf16x8*)(lds + G_SA(b, h) + aoff + m * 2048 + k * 1024); } while (0)
; #define G_LDB(dst, b, h) do { _Pragma("unroll") for (int n = 0; n < 2; ++n) _Pragma("unroll") for (int k = 0; k < 2; ++k) dst[n][k] = *(const LAS bf16x8*)(lds + G_SB(b, h) + boff + n * 2048 + k * 1024); } while (0)
; #define G_MMA(ai, bj, At_, Bt_) do { __builtin_amdgcn_s_setprio(1); _Pragma("unroll") for (int m = 0; m < 4; ++m) _Pragma("unroll") for (int n = 0; n < 2; ++n) _Pragma("unroll") for (int k = 0; k < 2; ++k) \
;         acc[ai][bj][m][n] = __builtin_amdgcn_mfma_f32_16x16x32_bf16(Bt_[n][k], At_[m][k], acc[ai][bj][m][n], 0, 0, 0); __builtin_amdgcn_s_setprio(0); } while (0)
; #define WAIT_V(n) asm volatile("s_waitcnt vmcnt(" #n ")" ::: "memory")
; #define WAIT_L(n) asm volatile("s_waitcnt lgkmcnt(" #n ")" ::: "memory")
; #define BAR __builtin_amdgcn_s_barrier()
; #define SCHED __builtin_amdgcn_sched_barrier(0)
; template <class Get, class Epi>
; DI void gemm_loop(int ntiles, int ld, char* shm, const Get& get, const Epi& epi) {
;     ...
;         for (int t = 0; t < nt; t += 2) {
;             const bool last = (t == nt - 2);
;             const char* a1 = cA + (size_t)(t + 1) * kstep;
;             const char* a2 = last ? nA : cA + (size_t)(t + 2) * kstep; const char* b2 = last ? nB : cB + (size_t)(t + 2) * kstep;
;             const char* a3 = a2 + kstep; const char* b3 = b2 + kstep;
;             G_LDB(B0, 0, 0); G_LDB(B1, 0, 1); SCHED; G_LDA(At, 0, 0); G_STAGE(G_SA(1, 1), a1 + hstep, voffA);
;     ...
;             G_LDA(At, 1, 1); G_STAGE(G_SB(1, 0), b3, voffB); G_STAGE(G_SB(1, 1), b3 + hstep, voffB); G_STAGE(G_SA(1, 0), a3, voffA);
;             WAIT_V(8); WAIT_L(0); BAR; G_MMA(1, 0, At, B0); G_MMA(1, 1, At, B1); BAR; SCHED;
	s_add_i32 s14, s57, s46
	v_lshl_add_u64 v[170:171], v[170:171], 0, s[10:11]
	s_mov_b32 m0, s14
	ds_read_b128 v[184:187], v175 offset:49152
	ds_read_b128 v[188:191], v175 offset:50176
	ds_read_b128 v[192:195], v175 offset:51200
	ds_read_b128 v[196:199], v175 offset:52224
	ds_read_b128 v[200:203], v175 offset:53248
	ds_read_b128 v[204:207], v175 offset:54272
	ds_read_b128 v[208:211], v175 offset:55296
	ds_read_b128 v[212:215], v175 offset:56320
	global_load_lds_dwordx4 v[170:171], off
	s_add_i32 m0, s14, 0x2000
	s_add_u32 s6, s6, 0x40080
	v_lshl_add_u64 v[170:171], v[216:217], 0, s[10:11]
	s_addc_u32 s7, s7, 0
	s_add_i32 s14, s58, s46
	global_load_lds_dwordx4 v[170:171], off
	v_lshl_add_u64 v[170:171], s[6:7], 0, v[140:141]
	s_mov_b32 m0, s14
	s_nop 0
	global_load_lds_dwordx4 v[170:171], off
	v_lshl_add_u64 v[170:171], s[6:7], 0, v[136:137]
	s_add_i32 m0, s14, 0x2000
	s_nop 0
	global_load_lds_dwordx4 v[170:171], off
	v_lshl_add_u64 v[170:171], v[218:219], 0, s[10:11]
	s_mov_b32 m0, s73
	s_nop 0
	global_load_lds_dwordx4 v[170:171], off
	v_lshl_add_u64 v[170:171], v[220:221], 0, s[10:11]
	s_mov_b32 m0, s74
	s_nop 0
	global_load_lds_dwordx4 v[170:171], off
	s_waitcnt vmcnt(8)
	s_waitcnt lgkmcnt(0)
	s_barrier
	s_setprio 1
	v_mfma_f32_16x16x32_bf16 v[92:95], v[96:99], v[184:187], v[92:95]
	v_mfma_f32_16x16x32_bf16 v[84:87], v[150:153], v[184:187], v[84:87]
	v_mfma_f32_16x16x32_bf16 v[88:91], v[96:99], v[192:195], v[88:91]
	v_mfma_f32_16x16x32_bf16 v[80:83], v[150:153], v[192:195], v[80:83]
	v_mfma_f32_16x16x32_bf16 v[76:79], v[96:99], v[200:203], v[76:79]
	v_mfma_f32_16x16x32_bf16 v[68:71], v[150:153], v[200:203], v[68:71]
	v_mfma_f32_16x16x32_bf16 v[72:75], v[96:99], v[208:211], v[72:75]
	v_mfma_f32_16x16x32_bf16 v[64:67], v[150:153], v[208:211], v[64:67]
	v_mfma_f32_16x16x32_bf16 v[92:95], v[108:111], v[188:191], v[92:95]
	v_mfma_f32_16x16x32_bf16 v[84:87], v[154:157], v[188:191], v[84:87]
	v_mfma_f32_16x16x32_bf16 v[88:91], v[108:111], v[196:199], v[88:91]
	v_mfma_f32_16x16x32_bf16 v[80:83], v[154:157], v[196:199], v[80:83]
	v_mfma_f32_16x16x32_bf16 v[76:79], v[108:111], v[204:207], v[76:79]
	v_mfma_f32_16x16x32_bf16 v[68:71], v[154:157], v[204:207], v[68:71]
	v_mfma_f32_16x16x32_bf16 v[72:75], v[108:111], v[212:215], v[72:75]
	v_mfma_f32_16x16x32_bf16 v[64:67], v[154:157], v[212:215], v[64:67]
	s_setprio 0
	s_setprio 1
	v_mfma_f32_16x16x32_bf16 v[28:31], v[158:161], v[184:187], v[28:31]
	v_mfma_f32_16x16x32_bf16 v[20:23], v[166:169], v[184:187], v[20:23]
	v_mfma_f32_16x16x32_bf16 v[24:27], v[158:161], v[192:195], v[24:27]
	v_mfma_f32_16x16x32_bf16 v[16:19], v[166:169], v[192:195], v[16:19]
	v_mfma_f32_16x16x32_bf16 v[12:15], v[158:161], v[200:203], v[12:15]
	v_mfma_f32_16x16x32_bf16 v[4:7], v[166:169], v[200:203], v[4:7]
	v_mfma_f32_16x16x32_bf16 v[8:11], v[158:161], v[208:211], v[8:11]
	v_mfma_f32_16x16x32_bf16 v[0:3], v[166:169], v[208:211], v[0:3]
	v_mfma_f32_16x16x32_bf16 v[28:31], v[162:165], v[188:191], v[28:31]
	v_mfma_f32_16x16x32_bf16 v[20:23], v[180:183], v[188:191], v[20:23]
	v_mfma_f32_16x16x32_bf16 v[24:27], v[162:165], v[196:199], v[24:27]
	v_mfma_f32_16x16x32_bf16 v[16:19], v[180:183], v[196:199], v[16:19]
	v_mfma_f32_16x16x32_bf16 v[12:15], v[162:165], v[204:207], v[12:15]
	v_mfma_f32_16x16x32_bf16 v[4:7], v[180:183], v[204:207], v[4:7]
	v_mfma_f32_16x16x32_bf16 v[8:11], v[162:165], v[212:215], v[8:11]
	v_mfma_f32_16x16x32_bf16 v[0:3], v[180:183], v[212:215], v[0:3]
	s_setprio 0
	s_barrier
	s_add_i32 s56, s56, 2
	s_add_u32 s4, s4, 0x100
	s_addc_u32 s5, s5, 0
	s_add_u32 s54, s54, 0x100
	s_addc_u32 s55, s55, 0
	s_cmp_gt_u32 s56, 13
	s_cbranch_scc0 .LBB0_2022
	s_branch .Lpost_2022
.LBB0_2022:
	ds_read_b128 v[96:99], v173
	ds_read_b128 v[108:111], v173 offset:1024
	ds_read_b128 v[150:153], v173 offset:2048
	ds_read_b128 v[154:157], v173 offset:3072
	ds_read_b128 v[158:161], v174
	ds_read_b128 v[162:165], v174 offset:1024
	ds_read_b128 v[166:169], v174 offset:2048
	ds_read_b128 v[180:183], v174 offset:3072
	s_add_u32 s6, s4, 0xfffc0080
	s_addc_u32 s7, s5, -1
	s_cmp_eq_u32 s56, 12
	s_cselect_b32 s15, s3, s7
	s_cselect_b32 s14, s41, s6
	s_cselect_b32 s7, s43, s55
	s_cselect_b32 s6, s53, s54
	v_lshl_add_u64 v[170:171], s[4:5], 0, v[146:147]
	s_add_i32 m0, s50, 0xc000
	ds_read_b128 v[184:187], v175
	ds_read_b128 v[188:191], v175 offset:1024
	ds_read_b128 v[192:195], v175 offset:2048
	ds_read_b128 v[196:199], v175 offset:3072
	ds_read_b128 v[200:203], v175 offset:4096
	ds_read_b128 v[204:207], v175 offset:5120
	ds_read_b128 v[208:211], v175 offset:6144
	ds_read_b128 v[212:215], v175 offset:7168
	global_load_lds_dwordx4 v[170:171], off
	v_lshl_add_u64 v[170:171], s[4:5], 0, v[148:149]
	s_add_i32 m0, s50, 0xe000
	s_nop 0
	global_load_lds_dwordx4 v[170:171], off
	s_waitcnt vmcnt(8)
	s_waitcnt lgkmcnt(0)
	s_barrier
; #define G_STAGE(bufoff, gbase, voff) do { _Pragma("unroll") for (int _i = 0; _i < 2; ++_i) \
;         __builtin_amdgcn_global_load_lds((const unsigned*)((const char*)(gbase) + voff[_i]), (LAS unsigned*)(lds + (bufoff) + ldsw + _i * 8192), 16, 0, 0); } while (0)
; #define G_LDA(dst, b, h) do { _Pragma("unroll") for (int m = 0; m < 4; ++m) _Pragma("unroll") for (int k = 0; k < 2; ++k) dst[m][k] = *(const LAS bf16x8*)(lds + G_SA(b, h) + aoff + m * 2048 + k * 1024); } while (0)
; #define G_MMA(ai, bj, At_, Bt_) do { __builtin_amdgcn_s_setprio(1); _Pragma("unroll") for (int m = 0; m < 4; ++m) _Pragma("unroll") for (int n = 0; n < 2; ++n) _Pragma("unroll") for (int k = 0; k < 2; ++k) \
;         acc[ai][bj][m][n] = __builtin_amdgcn_mfma_f32_16x16x32_bf16(Bt_[n][k], At_[m][k], acc[ai][bj][m][n], 0, 0, 0); __builtin_amdgcn_s_setprio(0); } while (0)
; #define WAIT_V(n) asm volatile("s_waitcnt vmcnt(" #n ")" ::: "memory")
; #define WAIT_L(n) asm volatile("s_waitcnt lgkmcnt(" #n ")" ::: "memory")
; #define BAR __builtin_amdgcn_s_barrier()
; #define SCHED __builtin_amdgcn_sched_barrier(0)
; template <class Get, class Epi>
; DI void gemm_loop(int ntiles, int ld, char* shm, const Get& get, const Epi& epi) {
;     ...
;             WAIT_V(8); WAIT_L(0); BAR; G_MMA(0, 0, At, B0); G_MMA(0, 1, At, B1); BAR; SCHED;
;             G_LDA(At, 0, 1); G_STAGE(G_SB(0, 0), b2, voffB); G_STAGE(G_SB(0, 1), b2 + hstep, voffB); G_STAGE(G_SA(0, 0), a2, voffA);
;             WAIT_V(8); WAIT_L(0); BAR; G_MMA(1, 0, At, B0); G_MMA(1, 1, At, B1); BAR; SCHED;
	s_setprio 1
	v_mfma_f32_16x16x32_bf16 v[132:135], v[96:99], v[184:187], v[132:135]
	v_mfma_f32_16x16x32_bf16 v[124:127], v[150:153], v[184:187], v[124:127]
	v_mfma_f32_16x16x32_bf16 v[128:131], v[96:99], v[192:195], v[128:131]
	v_mfma_f32_16x16x32_bf16 v[120:123], v[150:153], v[192:195], v[120:123]
	v_mfma_f32_16x16x32_bf16 v[116:119], v[96:99], v[200:203], v[116:119]
	v_mfma_f32_16x16x32_bf16 v[104:107], v[150:153], v[200:203], v[104:107]
	v_mfma_f32_16x16x32_bf16 v[112:115], v[96:99], v[208:211], v[112:115]
	v_mfma_f32_16x16x32_bf16 v[100:103], v[150:153], v[208:211], v[100:103]
	v_mfma_f32_16x16x32_bf16 v[132:135], v[108:111], v[188:191], v[132:135]
	v_mfma_f32_16x16x32_bf16 v[124:127], v[154:157], v[188:191], v[124:127]
	v_mfma_f32_16x16x32_bf16 v[128:131], v[108:111], v[196:199], v[128:131]
	v_mfma_f32_16x16x32_bf16 v[120:123], v[154:157], v[196:199], v[120:123]
	v_mfma_f32_16x16x32_bf16 v[116:119], v[108:111], v[204:207], v[116:119]
	v_mfma_f32_16x16x32_bf16 v[104:107], v[154:157], v[204:207], v[104:107]
	v_mfma_f32_16x16x32_bf16 v[112:115], v[108:111], v[212:215], v[112:115]
	v_mfma_f32_16x16x32_bf16 v[100:103], v[154:157], v[212:215], v[100:103]
	s_setprio 0
	s_setprio 1
	v_mfma_f32_16x16x32_bf16 v[60:63], v[158:161], v[184:187], v[60:63]
	v_mfma_f32_16x16x32_bf16 v[52:55], v[166:169], v[184:187], v[52:55]
	v_mfma_f32_16x16x32_bf16 v[56:59], v[158:161], v[192:195], v[56:59]
	v_mfma_f32_16x16x32_bf16 v[48:51], v[166:169], v[192:195], v[48:51]
	v_mfma_f32_16x16x32_bf16 v[44:47], v[158:161], v[200:203], v[44:47]
	v_mfma_f32_16x16x32_bf16 v[36:39], v[166:169], v[200:203], v[36:39]
	v_mfma_f32_16x16x32_bf16 v[40:43], v[158:161], v[208:211], v[40:43]
	v_mfma_f32_16x16x32_bf16 v[32:35], v[166:169], v[208:211], v[32:35]
	v_mfma_f32_16x16x32_bf16 v[60:63], v[162:165], v[188:191], v[60:63]
	v_mfma_f32_16x16x32_bf16 v[52:55], v[180:183], v[188:191], v[52:55]
	v_mfma_f32_16x16x32_bf16 v[56:59], v[162:165], v[196:199], v[56:59]
	v_mfma_f32_16x16x32_bf16 v[48:51], v[180:183], v[196:199], v[48:51]
	v_mfma_f32_16x16x32_bf16 v[44:47], v[162:165], v[204:207], v[44:47]
	v_mfma_f32_16x16x32_bf16 v[36:39], v[180:183], v[204:207], v[36:39]
	v_mfma_f32_16x16x32_bf16 v[40:43], v[162:165], v[212:215], v[40:43]
	v_mfma_f32_16x16x32_bf16 v[32:35], v[180:183], v[212:215], v[32:35]
	s_setprio 0
	s_barrier
	s_add_i32 s57, s75, s46
	v_lshl_add_u64 v[170:171], s[6:7], 0, v[140:141]
	s_mov_b32 m0, s57
	ds_read_b128 v[184:187], v175 offset:16384
	ds_read_b128 v[188:191], v175 offset:17408
	ds_read_b128 v[192:195], v175 offset:18432
	ds_read_b128 v[196:199], v175 offset:19456
	ds_read_b128 v[200:203], v175 offset:20480
	ds_read_b128 v[204:207], v175 offset:21504
	ds_read_b128 v[208:211], v175 offset:22528
	ds_read_b128 v[212:215], v175 offset:23552
	global_load_lds_dwordx4 v[170:171], off
	s_add_i32 m0, s57, 0x2000
	s_add_u32 s58, s6, 0x40000
	v_lshl_add_u64 v[216:217], s[6:7], 0, v[136:137]
	s_addc_u32 s59, s7, 0
	s_add_i32 s57, s76, s46
	global_load_lds_dwordx4 v[216:217], off
	v_lshl_add_u64 v[218:219], s[58:59], 0, v[140:141]
	s_mov_b32 m0, s57
	v_lshl_add_u64 v[220:221], s[14:15], 0, v[138:139]
	global_load_lds_dwordx4 v[218:219], off
	v_lshl_add_u64 v[218:219], s[58:59], 0, v[136:137]
	s_add_i32 m0, s57, 0x2000
	s_nop 0
	global_load_lds_dwordx4 v[218:219], off
	v_lshl_add_u64 v[218:219], s[14:15], 0, v[142:143]
	s_mov_b32 m0, s50
	s_nop 0
	global_load_lds_dwordx4 v[218:219], off
	s_mov_b32 m0, s51
	s_nop 0
	global_load_lds_dwordx4 v[220:221], off
	s_waitcnt vmcnt(8)
	s_waitcnt lgkmcnt(0)
	s_barrier
	s_setprio 1
	v_mfma_f32_16x16x32_bf16 v[92:95], v[96:99], v[184:187], v[92:95]
	v_mfma_f32_16x16x32_bf16 v[84:87], v[150:153], v[184:187], v[84:87]
	v_mfma_f32_16x16x32_bf16 v[88:91], v[96:99], v[192:195], v[88:91]
	v_mfma_f32_16x16x32_bf16 v[80:83], v[150:153], v[192:195], v[80:83]
	v_mfma_f32_16x16x32_bf16 v[76:79], v[96:99], v[200:203], v[76:79]
	v_mfma_f32_16x16x32_bf16 v[68:71], v[150:153], v[200:203], v[68:71]
	v_mfma_f32_16x16x32_bf16 v[72:75], v[96:99], v[208:211], v[72:75]
	v_mfma_f32_16x16x32_bf16 v[64:67], v[150:153], v[208:211], v[64:67]
	v_mfma_f32_16x16x32_bf16 v[92:95], v[108:111], v[188:191], v[92:95]
	v_mfma_f32_16x16x32_bf16 v[84:87], v[154:157], v[188:191], v[84:87]
	v_mfma_f32_16x16x32_bf16 v[88:91], v[108:111], v[196:199], v[88:91]
	v_mfma_f32_16x16x32_bf16 v[80:83], v[154:157], v[196:199], v[80:83]
	v_mfma_f32_16x16x32_bf16 v[76:79], v[108:111], v[204:207], v[76:79]
	v_mfma_f32_16x16x32_bf16 v[68:71], v[154:157], v[204:207], v[68:71]
	v_mfma_f32_16x16x32_bf16 v[72:75], v[108:111], v[212:215], v[72:75]
	v_mfma_f32_16x16x32_bf16 v[64:67], v[154:157], v[212:215], v[64:67]
	s_setprio 0
	s_setprio 1
	v_mfma_f32_16x16x32_bf16 v[28:31], v[158:161], v[184:187], v[28:31]
	v_mfma_f32_16x16x32_bf16 v[20:23], v[166:169], v[184:187], v[20:23]
	v_mfma_f32_16x16x32_bf16 v[24:27], v[158:161], v[192:195], v[24:27]
	v_mfma_f32_16x16x32_bf16 v[16:19], v[166:169], v[192:195], v[16:19]
	v_mfma_f32_16x16x32_bf16 v[12:15], v[158:161], v[200:203], v[12:15]
	v_mfma_f32_16x16x32_bf16 v[4:7], v[166:169], v[200:203], v[4:7]
	v_mfma_f32_16x16x32_bf16 v[8:11], v[158:161], v[208:211], v[8:11]
	v_mfma_f32_16x16x32_bf16 v[0:3], v[166:169], v[208:211], v[0:3]
	v_mfma_f32_16x16x32_bf16 v[28:31], v[162:165], v[188:191], v[28:31]
	v_mfma_f32_16x16x32_bf16 v[20:23], v[180:183], v[188:191], v[20:23]
	v_mfma_f32_16x16x32_bf16 v[24:27], v[162:165], v[196:199], v[24:27]
	v_mfma_f32_16x16x32_bf16 v[16:19], v[180:183], v[196:199], v[16:19]
	v_mfma_f32_16x16x32_bf16 v[12:15], v[162:165], v[204:207], v[12:15]
	v_mfma_f32_16x16x32_bf16 v[4:7], v[180:183], v[204:207], v[4:7]
	v_mfma_f32_16x16x32_bf16 v[8:11], v[162:165], v[212:215], v[8:11]
	v_mfma_f32_16x16x32_bf16 v[0:3], v[180:183], v[212:215], v[0:3]
	s_setprio 0
	s_barrier
; #define G_STAGE(bufoff, gbase, voff) do { _Pragma("unroll") for (int _i = 0; _i < 2; ++_i) \
;         __builtin_amdgcn_global_load_lds((const unsigned*)((const char*)(gbase) + voff[_i]), (LAS unsigned*)(lds + (bufoff) + ldsw + _i * 8192), 16, 0, 0); } while (0)
; #define G_LDA(dst, b, h) do { _Pragma("unroll") for (int m = 0; m < 4; ++m) _Pragma("unroll") for (int k = 0; k < 2; ++k) dst[m][k] = *(const LAS bf16x8*)(lds + G_SA(b, h) + aoff + m * 2048 + k * 1024); } while (0)
; #define G_LDB(dst, b, h) do { _Pragma("unroll") for (int n = 0; n < 2; ++n) _Pragma("unroll") for (int k = 0; k < 2; ++k) dst[n][k] = *(const LAS bf16x8*)(lds + G_SB(b, h) + boff + n * 2048 + k * 1024); } while (0)
; #define G_MMA(ai, bj, At_, Bt_) do { __builtin_amdgcn_s_setprio(1); _Pragma("unroll") for (int m = 0; m < 4; ++m) _Pragma("unroll") for (int n = 0; n < 2; ++n) _Pragma("unroll") for (int k = 0; k < 2; ++k) \
;         acc[ai][bj][m][n] = __builtin_amdgcn_mfma_f32_16x16x32_bf16(Bt_[n][k], At_[m][k], acc[ai][bj][m][n], 0, 0, 0); __builtin_amdgcn_s_setprio(0); } while (0)
; #define WAIT_V(n) asm volatile("s_waitcnt vmcnt(" #n ")" ::: "memory")
; #define WAIT_L(n) asm volatile("s_waitcnt lgkmcnt(" #n ")" ::: "memory")
; #define BAR __builtin_amdgcn_s_barrier()
; #define SCHED __builtin_amdgcn_sched_barrier(0)
; template <class Get, class Epi>
; DI void gemm_loop(int ntiles, int ld, char* shm, const Get& get, const Epi& epi) {
;     ...
;             G_LDB(B0, 1, 0); G_LDB(B1, 1, 1); SCHED; G_LDA(At, 1, 0); G_STAGE(G_SA(0, 1), a2 + hstep, voffA);
;             WAIT_V(8); WAIT_L(0); BAR; G_MMA(0, 0, At, B0); G_MMA(0, 1, At, B1); BAR; SCHED;
	s_add_i32 s57, 0, 0x18000
	v_add_u32_e32 v144, s57, v172
	s_add_i32 s58, 0, 0x1c000
	ds_read_b128 v[96:99], v144
	ds_read_b128 v[108:111], v144 offset:1024
	ds_read_b128 v[150:153], v144 offset:2048
	ds_read_b128 v[154:157], v144 offset:3072
	v_add_u32_e32 v144, s58, v172
	ds_read_b128 v[158:161], v144
	ds_read_b128 v[162:165], v144 offset:1024
	ds_read_b128 v[166:169], v144 offset:2048
	ds_read_b128 v[180:183], v144 offset:3072
	s_add_u32 s14, s14, 0x40000
	s_addc_u32 s15, s15, 0
	s_mov_b32 m0, s71
	v_lshl_add_u64 v[222:223], s[14:15], 0, v[142:143]
	ds_read_b128 v[184:187], v175 offset:32768
	ds_read_b128 v[188:191], v175 offset:33792
	ds_read_b128 v[192:195], v175 offset:34816
	ds_read_b128 v[196:199], v175 offset:35840
	ds_read_b128 v[200:203], v175 offset:36864
	ds_read_b128 v[204:207], v175 offset:37888
	ds_read_b128 v[208:211], v175 offset:38912
	ds_read_b128 v[212:215], v175 offset:39936
	global_load_lds_dwordx4 v[222:223], off
	v_lshl_add_u64 v[222:223], s[14:15], 0, v[138:139]
	s_mov_b32 m0, s72
	s_nop 0
	global_load_lds_dwordx4 v[222:223], off
	s_waitcnt vmcnt(8)
	s_waitcnt lgkmcnt(0)
	s_barrier
	s_setprio 1
	v_mfma_f32_16x16x32_bf16 v[132:135], v[96:99], v[184:187], v[132:135]
	v_mfma_f32_16x16x32_bf16 v[124:127], v[150:153], v[184:187], v[124:127]
	v_mfma_f32_16x16x32_bf16 v[128:131], v[96:99], v[192:195], v[128:131]
	v_mfma_f32_16x16x32_bf16 v[120:123], v[150:153], v[192:195], v[120:123]
	v_mfma_f32_16x16x32_bf16 v[116:119], v[96:99], v[200:203], v[116:119]
	v_mfma_f32_16x16x32_bf16 v[104:107], v[150:153], v[200:203], v[104:107]
	v_mfma_f32_16x16x32_bf16 v[112:115], v[96:99], v[208:211], v[112:115]
	v_mfma_f32_16x16x32_bf16 v[100:103], v[150:153], v[208:211], v[100:103]
	v_mfma_f32_16x16x32_bf16 v[132:135], v[108:111], v[188:191], v[132:135]
	v_mfma_f32_16x16x32_bf16 v[124:127], v[154:157], v[188:191], v[124:127]
	v_mfma_f32_16x16x32_bf16 v[128:131], v[108:111], v[196:199], v[128:131]
	v_mfma_f32_16x16x32_bf16 v[120:123], v[154:157], v[196:199], v[120:123]
	v_mfma_f32_16x16x32_bf16 v[116:119], v[108:111], v[204:207], v[116:119]
	v_mfma_f32_16x16x32_bf16 v[104:107], v[154:157], v[204:207], v[104:107]
	v_mfma_f32_16x16x32_bf16 v[112:115], v[108:111], v[212:215], v[112:115]
	v_mfma_f32_16x16x32_bf16 v[100:103], v[154:157], v[212:215], v[100:103]
	s_setprio 0
	s_setprio 1
	v_mfma_f32_16x16x32_bf16 v[60:63], v[158:161], v[184:187], v[60:63]
	v_mfma_f32_16x16x32_bf16 v[52:55], v[166:169], v[184:187], v[52:55]
	v_mfma_f32_16x16x32_bf16 v[56:59], v[158:161], v[192:195], v[56:59]
	v_mfma_f32_16x16x32_bf16 v[48:51], v[166:169], v[192:195], v[48:51]
	v_mfma_f32_16x16x32_bf16 v[44:47], v[158:161], v[200:203], v[44:47]
	v_mfma_f32_16x16x32_bf16 v[36:39], v[166:169], v[200:203], v[36:39]
	v_mfma_f32_16x16x32_bf16 v[40:43], v[158:161], v[208:211], v[40:43]
	v_mfma_f32_16x16x32_bf16 v[32:35], v[166:169], v[208:211], v[32:35]
	v_mfma_f32_16x16x32_bf16 v[60:63], v[162:165], v[188:191], v[60:63]
	v_mfma_f32_16x16x32_bf16 v[52:55], v[180:183], v[188:191], v[52:55]
	v_mfma_f32_16x16x32_bf16 v[56:59], v[162:165], v[196:199], v[56:59]
	v_mfma_f32_16x16x32_bf16 v[48:51], v[180:183], v[196:199], v[48:51]
	v_mfma_f32_16x16x32_bf16 v[44:47], v[162:165], v[204:207], v[44:47]
	v_mfma_f32_16x16x32_bf16 v[36:39], v[180:183], v[204:207], v[36:39]
	v_mfma_f32_16x16x32_bf16 v[40:43], v[162:165], v[212:215], v[40:43]
	v_mfma_f32_16x16x32_bf16 v[32:35], v[180:183], v[212:215], v[32:35]
	s_setprio 0
	s_barrier
; #define G_STAGE(bufoff, gbase, voff) do { _Pragma("unroll") for (int _i = 0; _i < 2; ++_i) \
;         __builtin_amdgcn_global_load_lds((const unsigned*)((const char*)(gbase) + voff[_i]), (LAS unsigned*)(lds + (bufoff) + ldsw + _i * 8192), 16, 0, 0); } while (0)
; #define G_LDA(dst, b, h) do { _Pragma("unroll") for (int m = 0; m < 4; ++m) _Pragma("unroll") for (int k = 0; k < 2; ++k) dst[m][k] = *(const LAS bf16x8*)(lds + G_SA(b, h) + aoff + m * 2048 + k * 1024); } while (0)
; #define G_MMA(ai, bj, At_, Bt_) do { __builtin_amdgcn_s_setprio(1); _Pragma("unroll") for (int m = 0; m < 4; ++m) _Pragma("unroll") for (int n = 0; n < 2; ++n) _Pragma("unroll") for (int k = 0; k < 2; ++k) \
;         acc[ai][bj][m][n] = __builtin_amdgcn_mfma_f32_16x16x32_bf16(Bt_[n][k], At_[m][k], acc[ai][bj][m][n], 0, 0, 0); __builtin_amdgcn_s_setprio(0); } while (0)
; #define WAIT_V(n) asm volatile("s_waitcnt vmcnt(" #n ")" ::: "memory")
; #define WAIT_L(n) asm volatile("s_waitcnt lgkmcnt(" #n ")" ::: "memory")
; #define BAR __builtin_amdgcn_s_barrier()
; #define SCHED __builtin_amdgcn_sched_barrier(0)
; template <class Get, class Epi>
; DI void gemm_loop(int ntiles, int ld, char* shm, const Get& get, const Epi& epi) {
;     ...
;             G_LDA(At, 1, 1); G_STAGE(G_SB(1, 0), b3, voffB); G_STAGE(G_SB(1, 1), b3 + hstep, voffB); G_STAGE(G_SA(1, 0), a3, voffA);
;             WAIT_V(8); WAIT_L(0); BAR; G_MMA(1, 0, At, B0); G_MMA(1, 1, At, B1); BAR; SCHED;
;         }
	s_add_i32 s14, s57, s46
	v_lshl_add_u64 v[170:171], v[170:171], 0, s[10:11]
	s_mov_b32 m0, s14
	ds_read_b128 v[184:187], v175 offset:49152
	ds_read_b128 v[188:191], v175 offset:50176
	ds_read_b128 v[192:195], v175 offset:51200
	ds_read_b128 v[196:199], v175 offset:52224
	ds_read_b128 v[200:203], v175 offset:53248
	ds_read_b128 v[204:207], v175 offset:54272
	ds_read_b128 v[208:211], v175 offset:55296
	ds_read_b128 v[212:215], v175 offset:56320
	global_load_lds_dwordx4 v[170:171], off
	s_add_i32 m0, s14, 0x2000
	s_add_u32 s6, s6, 0x40080
	v_lshl_add_u64 v[170:171], v[216:217], 0, s[10:11]
	s_addc_u32 s7, s7, 0
	s_add_i32 s14, s58, s46
	global_load_lds_dwordx4 v[170:171], off
	v_lshl_add_u64 v[170:171], s[6:7], 0, v[140:141]
	s_mov_b32 m0, s14
	s_nop 0
	global_load_lds_dwordx4 v[170:171], off
	v_lshl_add_u64 v[170:171], s[6:7], 0, v[136:137]
	s_add_i32 m0, s14, 0x2000
	s_nop 0
	global_load_lds_dwordx4 v[170:171], off
	v_lshl_add_u64 v[170:171], v[218:219], 0, s[10:11]
	s_mov_b32 m0, s73
	s_nop 0
	global_load_lds_dwordx4 v[170:171], off
	v_lshl_add_u64 v[170:171], v[220:221], 0, s[10:11]
	s_mov_b32 m0, s74
	s_nop 0
	global_load_lds_dwordx4 v[170:171], off
	s_waitcnt vmcnt(8)
	s_waitcnt lgkmcnt(0)
	s_barrier
	s_setprio 1
	v_mfma_f32_16x16x32_bf16 v[92:95], v[96:99], v[184:187], v[92:95]
	v_mfma_f32_16x16x32_bf16 v[84:87], v[150:153], v[184:187], v[84:87]
	v_mfma_f32_16x16x32_bf16 v[88:91], v[96:99], v[192:195], v[88:91]
	v_mfma_f32_16x16x32_bf16 v[80:83], v[150:153], v[192:195], v[80:83]
	v_mfma_f32_16x16x32_bf16 v[76:79], v[96:99], v[200:203], v[76:79]
	v_mfma_f32_16x16x32_bf16 v[68:71], v[150:153], v[200:203], v[68:71]
	v_mfma_f32_16x16x32_bf16 v[72:75], v[96:99], v[208:211], v[72:75]
	v_mfma_f32_16x16x32_bf16 v[64:67], v[150:153], v[208:211], v[64:67]
	v_mfma_f32_16x16x32_bf16 v[92:95], v[108:111], v[188:191], v[92:95]
	v_mfma_f32_16x16x32_bf16 v[84:87], v[154:157], v[188:191], v[84:87]
	v_mfma_f32_16x16x32_bf16 v[88:91], v[108:111], v[196:199], v[88:91]
	v_mfma_f32_16x16x32_bf16 v[80:83], v[154:157], v[196:199], v[80:83]
	v_mfma_f32_16x16x32_bf16 v[76:79], v[108:111], v[204:207], v[76:79]
	v_mfma_f32_16x16x32_bf16 v[68:71], v[154:157], v[204:207], v[68:71]
	v_mfma_f32_16x16x32_bf16 v[72:75], v[108:111], v[212:215], v[72:75]
	v_mfma_f32_16x16x32_bf16 v[64:67], v[154:157], v[212:215], v[64:67]
	s_setprio 0
	s_setprio 1
	v_mfma_f32_16x16x32_bf16 v[28:31], v[158:161], v[184:187], v[28:31]
	v_mfma_f32_16x16x32_bf16 v[20:23], v[166:169], v[184:187], v[20:23]
	v_mfma_f32_16x16x32_bf16 v[24:27], v[158:161], v[192:195], v[24:27]
	v_mfma_f32_16x16x32_bf16 v[16:19], v[166:169], v[192:195], v[16:19]
	v_mfma_f32_16x16x32_bf16 v[12:15], v[158:161], v[200:203], v[12:15]
	v_mfma_f32_16x16x32_bf16 v[4:7], v[166:169], v[200:203], v[4:7]
	v_mfma_f32_16x16x32_bf16 v[8:11], v[158:161], v[208:211], v[8:11]
	v_mfma_f32_16x16x32_bf16 v[0:3], v[166:169], v[208:211], v[0:3]
	v_mfma_f32_16x16x32_bf16 v[28:31], v[162:165], v[188:191], v[28:31]
	v_mfma_f32_16x16x32_bf16 v[20:23], v[180:183], v[188:191], v[20:23]
	v_mfma_f32_16x16x32_bf16 v[24:27], v[162:165], v[196:199], v[24:27]
	v_mfma_f32_16x16x32_bf16 v[16:19], v[180:183], v[196:199], v[16:19]
	v_mfma_f32_16x16x32_bf16 v[12:15], v[162:165], v[204:207], v[12:15]
	v_mfma_f32_16x16x32_bf16 v[4:7], v[180:183], v[204:207], v[4:7]
	v_mfma_f32_16x16x32_bf16 v[8:11], v[162:165], v[212:215], v[8:11]
	v_mfma_f32_16x16x32_bf16 v[0:3], v[180:183], v[212:215], v[0:3]
	s_setprio 0
	s_barrier
	s_add_i32 s56, s56, 2
	s_add_u32 s4, s4, 0x100
	s_addc_u32 s5, s5, 0
	s_add_u32 s54, s54, 0x100
	s_addc_u32 s55, s55, 0
	s_cmp_gt_u32 s56, 13
	s_cbranch_scc0 .LBB0_2022

; #define G_STAGE(bufoff, gbase, voff) do { _Pragma("unroll") for (int _i = 0; _i < 2; ++_i) \
;         __builtin_amdgcn_global_load_lds((const unsigned*)((const char*)(gbase) + voff[_i]), (LAS unsigned*)(lds + (bufoff) + ldsw + _i * 8192), 16, 0, 0); } while (0)
; #define G_LDA(dst, b, h) do { _Pragma("unroll") for (int m = 0; m < 4; ++m) _Pragma("unroll") for (int k = 0; k < 2; ++k) dst[m][k] = *(const LAS bf16x8*)(lds + G_SA(b, h) + aoff + m * 2048 + k * 1024); } while (0)
; #define G_MMA(ai, bj, At_, Bt_) do { __builtin_amdgcn_s_setprio(1); _Pragma("unroll") for (int m = 0; m < 4; ++m) _Pragma("unroll") for (int n = 0; n < 2; ++n) _Pragma("unroll") for (int k = 0; k < 2; ++k) \
;         acc[ai][bj][m][n] = __builtin_amdgcn_mfma_f32_16x16x32_bf16(Bt_[n][k], At_[m][k], acc[ai][bj][m][n], 0, 0, 0); __builtin_amdgcn_s_setprio(0); } while (0)
; #define WAIT_V(n) asm volatile("s_waitcnt vmcnt(" #n ")" ::: "memory")
; #define WAIT_L(n) asm volatile("s_waitcnt lgkmcnt(" #n ")" ::: "memory")
; #define BAR __builtin_amdgcn_s_barrier()
; #define SCHED __builtin_amdgcn_sched_barrier(0)
; template <class Get, class Epi>
; DI void gemm_loop(int ntiles, int ld, char* shm, const Get& get, const Epi& epi) {
;     ...
;             WAIT_V(8); WAIT_L(0); BAR; G_MMA(0, 0, At, B0); G_MMA(0, 1, At, B1); BAR; SCHED;
;             G_LDA(At, 0, 1); G_STAGE(G_SB(0, 0), b2, voffB); G_STAGE(G_SB(0, 1), b2 + hstep, voffB); G_STAGE(G_SA(0, 0), a2, voffA);
.Lrj_2574_0:
	s_waitcnt lgkmcnt(0)
	s_barrier
	s_setprio 1
	v_mfma_f32_16x16x32_bf16 v[124:127], v[128:131], v[180:183], 0
	v_mfma_f32_16x16x32_bf16 v[120:123], v[136:139], v[180:183], 0
	v_mfma_f32_16x16x32_bf16 v[116:119], v[128:131], v[188:191], 0
	v_mfma_f32_16x16x32_bf16 v[112:115], v[136:139], v[188:191], 0
	v_mfma_f32_16x16x32_bf16 v[108:111], v[128:131], v[196:199], 0
	v_mfma_f32_16x16x32_bf16 v[104:107], v[136:139], v[196:199], 0
	v_mfma_f32_16x16x32_bf16 v[100:103], v[128:131], v[204:207], 0
	v_mfma_f32_16x16x32_bf16 v[96:99], v[136:139], v[204:207], 0
	v_mfma_f32_16x16x32_bf16 v[124:127], v[132:135], v[184:187], v[124:127]
	v_mfma_f32_16x16x32_bf16 v[120:123], v[140:143], v[184:187], v[120:123]
	v_mfma_f32_16x16x32_bf16 v[116:119], v[132:135], v[192:195], v[116:119]
	v_mfma_f32_16x16x32_bf16 v[112:115], v[140:143], v[192:195], v[112:115]
	v_mfma_f32_16x16x32_bf16 v[108:111], v[132:135], v[200:203], v[108:111]
	v_mfma_f32_16x16x32_bf16 v[104:107], v[140:143], v[200:203], v[104:107]
	v_mfma_f32_16x16x32_bf16 v[100:103], v[132:135], v[208:211], v[100:103]
	v_mfma_f32_16x16x32_bf16 v[96:99], v[140:143], v[208:211], v[96:99]
	s_setprio 0
	s_setprio 1
	v_mfma_f32_16x16x32_bf16 v[60:63], v[158:161], v[180:183], 0
	v_mfma_f32_16x16x32_bf16 v[56:59], v[172:175], v[180:183], 0
	v_mfma_f32_16x16x32_bf16 v[52:55], v[158:161], v[188:191], 0
	v_mfma_f32_16x16x32_bf16 v[48:51], v[172:175], v[188:191], 0
	v_mfma_f32_16x16x32_bf16 v[44:47], v[158:161], v[196:199], 0
	v_mfma_f32_16x16x32_bf16 v[40:43], v[172:175], v[196:199], 0
	v_mfma_f32_16x16x32_bf16 v[36:39], v[158:161], v[204:207], 0
	v_mfma_f32_16x16x32_bf16 v[32:35], v[172:175], v[204:207], 0
	v_mfma_f32_16x16x32_bf16 v[60:63], v[162:165], v[184:187], v[60:63]
	v_mfma_f32_16x16x32_bf16 v[56:59], v[176:179], v[184:187], v[56:59]
	v_mfma_f32_16x16x32_bf16 v[52:55], v[162:165], v[192:195], v[52:55]
	v_mfma_f32_16x16x32_bf16 v[48:51], v[176:179], v[192:195], v[48:51]
	v_mfma_f32_16x16x32_bf16 v[44:47], v[162:165], v[200:203], v[44:47]
	v_mfma_f32_16x16x32_bf16 v[40:43], v[176:179], v[200:203], v[40:43]
	v_mfma_f32_16x16x32_bf16 v[36:39], v[162:165], v[208:211], v[36:39]
	v_mfma_f32_16x16x32_bf16 v[32:35], v[176:179], v[208:211], v[32:35]
	s_setprio 0
	s_barrier
	s_add_i32 s83, s72, s31
	v_lshl_add_u64 v[144:145], s[14:15], 0, v[148:149]
	s_mov_b32 m0, s83
	ds_read_b128 v[180:183], v171 offset:16384
	ds_read_b128 v[184:187], v171 offset:17408
	ds_read_b128 v[188:191], v171 offset:18432
	ds_read_b128 v[192:195], v171 offset:19456
	ds_read_b128 v[196:199], v171 offset:20480
	ds_read_b128 v[200:203], v171 offset:21504
	ds_read_b128 v[204:207], v171 offset:22528
	ds_read_b128 v[208:211], v171 offset:23552
	global_load_lds_dwordx4 v[144:145], off
	s_add_i32 m0, s83, 0x2000
	s_add_u32 s84, s14, 0x40000
	v_lshl_add_u64 v[166:167], s[14:15], 0, v[152:153]
	s_addc_u32 s85, s15, 0
	s_add_i32 s83, s73, s31
	global_load_lds_dwordx4 v[166:167], off
	v_lshl_add_u64 v[212:213], s[84:85], 0, v[148:149]
	s_mov_b32 m0, s83
	v_lshl_add_u64 v[214:215], s[46:47], 0, v[150:151]
	global_load_lds_dwordx4 v[212:213], off
	v_lshl_add_u64 v[212:213], s[84:85], 0, v[152:153]
	s_add_i32 m0, s83, 0x2000
	s_nop 0
	global_load_lds_dwordx4 v[212:213], off
	v_lshl_add_u64 v[212:213], s[46:47], 0, v[146:147]
	s_mov_b32 m0, s51
	s_nop 0
	global_load_lds_dwordx4 v[212:213], off
	s_mov_b32 m0, s54
	s_nop 0
	global_load_lds_dwordx4 v[214:215], off
	s_cmp_lg_u32 s100, 0
	s_cbranch_scc0 .Lrf_2574_1
	s_waitcnt vmcnt(16)
	s_branch .Lrj_2574_1

; #define G_STAGE(bufoff, gbase, voff) do { _Pragma("unroll") for (int _i = 0; _i < 2; ++_i) \
;         __builtin_amdgcn_global_load_lds((const unsigned*)((const char*)(gbase) + voff[_i]), (LAS unsigned*)(lds + (bufoff) + ldsw + _i * 8192), 16, 0, 0); } while (0)
; #define G_LDA(dst, b, h) do { _Pragma("unroll") for (int m = 0; m < 4; ++m) _Pragma("unroll") for (int k = 0; k < 2; ++k) dst[m][k] = *(const LAS bf16x8*)(lds + G_SA(b, h) + aoff + m * 2048 + k * 1024); } while (0)
; #define G_LDB(dst, b, h) do { _Pragma("unroll") for (int n = 0; n < 2; ++n) _Pragma("unroll") for (int k = 0; k < 2; ++k) dst[n][k] = *(const LAS bf16x8*)(lds + G_SB(b, h) + boff + n * 2048 + k * 1024); } while (0)
; #define G_MMA(ai, bj, At_, Bt_) do { __builtin_amdgcn_s_setprio(1); _Pragma("unroll") for (int m = 0; m < 4; ++m) _Pragma("unroll") for (int n = 0; n < 2; ++n) _Pragma("unroll") for (int k = 0; k < 2; ++k) \
;         acc[ai][bj][m][n] = __builtin_amdgcn_mfma_f32_16x16x32_bf16(Bt_[n][k], At_[m][k], acc[ai][bj][m][n], 0, 0, 0); __builtin_amdgcn_s_setprio(0); } while (0)
; #define WAIT_V(n) asm volatile("s_waitcnt vmcnt(" #n ")" ::: "memory")
; #define WAIT_L(n) asm volatile("s_waitcnt lgkmcnt(" #n ")" ::: "memory")
; #define BAR __builtin_amdgcn_s_barrier()
; #define SCHED __builtin_amdgcn_sched_barrier(0)
; template <class Get, class Epi>
; DI void gemm_loop(int ntiles, int ld, char* shm, const Get& get, const Epi& epi) {
;     ...
;             WAIT_V(8); WAIT_L(0); BAR; G_MMA(1, 0, At, B0); G_MMA(1, 1, At, B1); BAR; SCHED;
;             G_LDB(B0, 1, 0); G_LDB(B1, 1, 1); SCHED; G_LDA(At, 1, 0); G_STAGE(G_SA(0, 1), a2 + hstep, voffA);
;             WAIT_V(8); WAIT_L(0); BAR; G_MMA(0, 0, At, B0); G_MMA(0, 1, At, B1); BAR; SCHED;
.Lrj_2574_1:
	s_waitcnt lgkmcnt(0)
	s_barrier
	s_setprio 1
	v_mfma_f32_16x16x32_bf16 v[92:95], v[128:131], v[180:183], 0
	v_mfma_f32_16x16x32_bf16 v[88:91], v[136:139], v[180:183], 0
	v_mfma_f32_16x16x32_bf16 v[84:87], v[128:131], v[188:191], 0
	v_mfma_f32_16x16x32_bf16 v[80:83], v[136:139], v[188:191], 0
	v_mfma_f32_16x16x32_bf16 v[76:79], v[128:131], v[196:199], 0
	v_mfma_f32_16x16x32_bf16 v[72:75], v[136:139], v[196:199], 0
	v_mfma_f32_16x16x32_bf16 v[68:71], v[128:131], v[204:207], 0
	v_mfma_f32_16x16x32_bf16 v[64:67], v[136:139], v[204:207], 0
	v_mfma_f32_16x16x32_bf16 v[92:95], v[132:135], v[184:187], v[92:95]
	v_mfma_f32_16x16x32_bf16 v[88:91], v[140:143], v[184:187], v[88:91]
	v_mfma_f32_16x16x32_bf16 v[84:87], v[132:135], v[192:195], v[84:87]
	v_mfma_f32_16x16x32_bf16 v[80:83], v[140:143], v[192:195], v[80:83]
	v_mfma_f32_16x16x32_bf16 v[76:79], v[132:135], v[200:203], v[76:79]
	v_mfma_f32_16x16x32_bf16 v[72:75], v[140:143], v[200:203], v[72:75]
	v_mfma_f32_16x16x32_bf16 v[68:71], v[132:135], v[208:211], v[68:71]
	v_mfma_f32_16x16x32_bf16 v[64:67], v[140:143], v[208:211], v[64:67]
	s_setprio 0
	s_setprio 1
	v_mfma_f32_16x16x32_bf16 v[28:31], v[158:161], v[180:183], 0
	v_mfma_f32_16x16x32_bf16 v[24:27], v[172:175], v[180:183], 0
	v_mfma_f32_16x16x32_bf16 v[20:23], v[158:161], v[188:191], 0
	v_mfma_f32_16x16x32_bf16 v[16:19], v[172:175], v[188:191], 0
	v_mfma_f32_16x16x32_bf16 v[12:15], v[158:161], v[196:199], 0
	v_mfma_f32_16x16x32_bf16 v[8:11], v[172:175], v[196:199], 0
	v_mfma_f32_16x16x32_bf16 v[4:7], v[158:161], v[204:207], 0
	v_mfma_f32_16x16x32_bf16 v[0:3], v[172:175], v[204:207], 0
	v_mfma_f32_16x16x32_bf16 v[28:31], v[162:165], v[184:187], v[28:31]
	v_mfma_f32_16x16x32_bf16 v[24:27], v[176:179], v[184:187], v[24:27]
	v_mfma_f32_16x16x32_bf16 v[20:23], v[162:165], v[192:195], v[20:23]
	v_mfma_f32_16x16x32_bf16 v[16:19], v[176:179], v[192:195], v[16:19]
	v_mfma_f32_16x16x32_bf16 v[12:15], v[162:165], v[200:203], v[12:15]
	v_mfma_f32_16x16x32_bf16 v[8:11], v[176:179], v[200:203], v[8:11]
	v_mfma_f32_16x16x32_bf16 v[4:7], v[162:165], v[208:211], v[4:7]
	v_mfma_f32_16x16x32_bf16 v[0:3], v[176:179], v[208:211], v[0:3]
	s_setprio 0
	s_barrier
	s_add_i32 s83, 0, 0x18000
	s_add_i32 s84, 0, 0x1c000
	v_add_u32_e32 v140, s83, v168
	v_add_u32_e32 v176, s84, v168
	ds_read_b128 v[128:131], v140
	ds_read_b128 v[132:135], v140 offset:1024
	ds_read_b128 v[136:139], v140 offset:2048
	ds_read_b128 v[140:143], v140 offset:3072
	ds_read_b128 v[158:161], v176
	ds_read_b128 v[162:165], v176 offset:1024
	ds_read_b128 v[172:175], v176 offset:2048
	ds_read_b128 v[176:179], v176 offset:3072
	s_add_u32 s46, s46, 0x40000
	s_addc_u32 s47, s47, 0
	s_mov_b32 m0, s55
	v_lshl_add_u64 v[216:217], s[46:47], 0, v[146:147]
	ds_read_b128 v[180:183], v171 offset:32768
	ds_read_b128 v[184:187], v171 offset:33792
	ds_read_b128 v[188:191], v171 offset:34816
	ds_read_b128 v[192:195], v171 offset:35840
	ds_read_b128 v[196:199], v171 offset:36864
	ds_read_b128 v[200:203], v171 offset:37888
	ds_read_b128 v[204:207], v171 offset:38912
	ds_read_b128 v[208:211], v171 offset:39936
	global_load_lds_dwordx4 v[216:217], off
	v_lshl_add_u64 v[216:217], s[46:47], 0, v[150:151]
	s_mov_b32 m0, s56
	s_nop 0
	global_load_lds_dwordx4 v[216:217], off
	s_waitcnt vmcnt(8)
	s_waitcnt lgkmcnt(0)
	s_barrier
	s_setprio 1
	v_mfma_f32_16x16x32_bf16 v[124:127], v[128:131], v[180:183], v[124:127]
	v_mfma_f32_16x16x32_bf16 v[120:123], v[136:139], v[180:183], v[120:123]
	v_mfma_f32_16x16x32_bf16 v[116:119], v[128:131], v[188:191], v[116:119]
	v_mfma_f32_16x16x32_bf16 v[112:115], v[136:139], v[188:191], v[112:115]
	v_mfma_f32_16x16x32_bf16 v[108:111], v[128:131], v[196:199], v[108:111]
	v_mfma_f32_16x16x32_bf16 v[104:107], v[136:139], v[196:199], v[104:107]
	v_mfma_f32_16x16x32_bf16 v[100:103], v[128:131], v[204:207], v[100:103]
	v_mfma_f32_16x16x32_bf16 v[96:99], v[136:139], v[204:207], v[96:99]
	v_mfma_f32_16x16x32_bf16 v[124:127], v[132:135], v[184:187], v[124:127]
	v_mfma_f32_16x16x32_bf16 v[120:123], v[140:143], v[184:187], v[120:123]
	v_mfma_f32_16x16x32_bf16 v[116:119], v[132:135], v[192:195], v[116:119]
	v_mfma_f32_16x16x32_bf16 v[112:115], v[140:143], v[192:195], v[112:115]
	v_mfma_f32_16x16x32_bf16 v[108:111], v[132:135], v[200:203], v[108:111]
	v_mfma_f32_16x16x32_bf16 v[104:107], v[140:143], v[200:203], v[104:107]
	v_mfma_f32_16x16x32_bf16 v[100:103], v[132:135], v[208:211], v[100:103]
	v_mfma_f32_16x16x32_bf16 v[96:99], v[140:143], v[208:211], v[96:99]
	s_setprio 0
	s_setprio 1
	v_mfma_f32_16x16x32_bf16 v[60:63], v[158:161], v[180:183], v[60:63]
	v_mfma_f32_16x16x32_bf16 v[56:59], v[172:175], v[180:183], v[56:59]
	v_mfma_f32_16x16x32_bf16 v[52:55], v[158:161], v[188:191], v[52:55]
	v_mfma_f32_16x16x32_bf16 v[48:51], v[172:175], v[188:191], v[48:51]
	v_mfma_f32_16x16x32_bf16 v[44:47], v[158:161], v[196:199], v[44:47]
	v_mfma_f32_16x16x32_bf16 v[40:43], v[172:175], v[196:199], v[40:43]
	v_mfma_f32_16x16x32_bf16 v[36:39], v[158:161], v[204:207], v[36:39]
	v_mfma_f32_16x16x32_bf16 v[32:35], v[172:175], v[204:207], v[32:35]
	v_mfma_f32_16x16x32_bf16 v[60:63], v[162:165], v[184:187], v[60:63]
	v_mfma_f32_16x16x32_bf16 v[56:59], v[176:179], v[184:187], v[56:59]
	v_mfma_f32_16x16x32_bf16 v[52:55], v[162:165], v[192:195], v[52:55]
	v_mfma_f32_16x16x32_bf16 v[48:51], v[176:179], v[192:195], v[48:51]
	v_mfma_f32_16x16x32_bf16 v[44:47], v[162:165], v[200:203], v[44:47]
	v_mfma_f32_16x16x32_bf16 v[40:43], v[176:179], v[200:203], v[40:43]
	v_mfma_f32_16x16x32_bf16 v[36:39], v[162:165], v[208:211], v[36:39]
	v_mfma_f32_16x16x32_bf16 v[32:35], v[176:179], v[208:211], v[32:35]
	s_setprio 0
	s_barrier
; #define G_STAGE(bufoff, gbase, voff) do { _Pragma("unroll") for (int _i = 0; _i < 2; ++_i) \
;         __builtin_amdgcn_global_load_lds((const unsigned*)((const char*)(gbase) + voff[_i]), (LAS unsigned*)(lds + (bufoff) + ldsw + _i * 8192), 16, 0, 0); } while (0)
; #define G_LDA(dst, b, h) do { _Pragma("unroll") for (int m = 0; m < 4; ++m) _Pragma("unroll") for (int k = 0; k < 2; ++k) dst[m][k] = *(const LAS bf16x8*)(lds + G_SA(b, h) + aoff + m * 2048 + k * 1024); } while (0)
; #define G_LDB(dst, b, h) do { _Pragma("unroll") for (int n = 0; n < 2; ++n) _Pragma("unroll") for (int k = 0; k < 2; ++k) dst[n][k] = *(const LAS bf16x8*)(lds + G_SB(b, h) + boff + n * 2048 + k * 1024); } while (0)
; #define G_MMA(ai, bj, At_, Bt_) do { __builtin_amdgcn_s_setprio(1); _Pragma("unroll") for (int m = 0; m < 4; ++m) _Pragma("unroll") for (int n = 0; n < 2; ++n) _Pragma("unroll") for (int k = 0; k < 2; ++k) \
;         acc[ai][bj][m][n] = __builtin_amdgcn_mfma_f32_16x16x32_bf16(Bt_[n][k], At_[m][k], acc[ai][bj][m][n], 0, 0, 0); __builtin_amdgcn_s_setprio(0); } while (0)
; #define WAIT_V(n) asm volatile("s_waitcnt vmcnt(" #n ")" ::: "memory")
; #define WAIT_L(n) asm volatile("s_waitcnt lgkmcnt(" #n ")" ::: "memory")
; #define BAR __builtin_amdgcn_s_barrier()
; #define SCHED __builtin_amdgcn_sched_barrier(0)
; template <class Get, class Epi>
; DI void gemm_loop(int ntiles, int ld, char* shm, const Get& get, const Epi& epi) {
;     ...
;         for (int t = 0; t < nt; t += 2) {
;             const bool last = (t == nt - 2);
;             const char* a1 = cA + (size_t)(t + 1) * kstep;
;             const char* a2 = last ? nA : cA + (size_t)(t + 2) * kstep; const char* b2 = last ? nB : cB + (size_t)(t + 2) * kstep;
;             const char* a3 = a2 + kstep; const char* b3 = b2 + kstep;
;             G_LDB(B0, 0, 0); G_LDB(B1, 0, 1); SCHED; G_LDA(At, 0, 0); G_STAGE(G_SA(1, 1), a1 + hstep, voffA);
;     ...
;             G_LDA(At, 1, 1); G_STAGE(G_SB(1, 0), b3, voffB); G_STAGE(G_SB(1, 1), b3 + hstep, voffB); G_STAGE(G_SA(1, 0), a3, voffA);
;             WAIT_V(8); WAIT_L(0); BAR; G_MMA(1, 0, At, B0); G_MMA(1, 1, At, B1); BAR; SCHED;
	s_add_i32 s46, s83, s31
	v_lshl_add_u64 v[144:145], v[144:145], 0, s[8:9]
	s_mov_b32 m0, s46
	ds_read_b128 v[180:183], v171 offset:49152
	ds_read_b128 v[184:187], v171 offset:50176
	ds_read_b128 v[188:191], v171 offset:51200
	ds_read_b128 v[192:195], v171 offset:52224
	ds_read_b128 v[196:199], v171 offset:53248
	ds_read_b128 v[200:203], v171 offset:54272
	ds_read_b128 v[204:207], v171 offset:55296
	ds_read_b128 v[208:211], v171 offset:56320
	global_load_lds_dwordx4 v[144:145], off
	s_add_i32 m0, s46, 0x2000
	s_add_u32 s14, s14, 0x40080
	v_lshl_add_u64 v[144:145], v[166:167], 0, s[8:9]
	s_addc_u32 s15, s15, 0
	s_add_i32 s46, s84, s31
	global_load_lds_dwordx4 v[144:145], off
	v_lshl_add_u64 v[144:145], s[14:15], 0, v[148:149]
	s_mov_b32 m0, s46
	s_nop 0
	global_load_lds_dwordx4 v[144:145], off
	v_lshl_add_u64 v[144:145], s[14:15], 0, v[152:153]
	s_add_i32 m0, s46, 0x2000
	s_nop 0
	global_load_lds_dwordx4 v[144:145], off
	v_lshl_add_u64 v[144:145], v[212:213], 0, s[8:9]
	s_mov_b32 m0, s59
	s_nop 0
	global_load_lds_dwordx4 v[144:145], off
	v_lshl_add_u64 v[144:145], v[214:215], 0, s[8:9]
	s_mov_b32 m0, s71
	s_nop 0
	global_load_lds_dwordx4 v[144:145], off
	s_waitcnt vmcnt(8)
	s_waitcnt lgkmcnt(0)
	s_barrier
	s_setprio 1
	v_mfma_f32_16x16x32_bf16 v[92:95], v[128:131], v[180:183], v[92:95]
	v_mfma_f32_16x16x32_bf16 v[88:91], v[136:139], v[180:183], v[88:91]
	v_mfma_f32_16x16x32_bf16 v[84:87], v[128:131], v[188:191], v[84:87]
	v_mfma_f32_16x16x32_bf16 v[80:83], v[136:139], v[188:191], v[80:83]
	v_mfma_f32_16x16x32_bf16 v[76:79], v[128:131], v[196:199], v[76:79]
	v_mfma_f32_16x16x32_bf16 v[72:75], v[136:139], v[196:199], v[72:75]
	v_mfma_f32_16x16x32_bf16 v[68:71], v[128:131], v[204:207], v[68:71]
	v_mfma_f32_16x16x32_bf16 v[64:67], v[136:139], v[204:207], v[64:67]
	v_mfma_f32_16x16x32_bf16 v[92:95], v[132:135], v[184:187], v[92:95]
	v_mfma_f32_16x16x32_bf16 v[88:91], v[140:143], v[184:187], v[88:91]
	v_mfma_f32_16x16x32_bf16 v[84:87], v[132:135], v[192:195], v[84:87]
	v_mfma_f32_16x16x32_bf16 v[80:83], v[140:143], v[192:195], v[80:83]
	v_mfma_f32_16x16x32_bf16 v[76:79], v[132:135], v[200:203], v[76:79]
	v_mfma_f32_16x16x32_bf16 v[72:75], v[140:143], v[200:203], v[72:75]
	v_mfma_f32_16x16x32_bf16 v[68:71], v[132:135], v[208:211], v[68:71]
	v_mfma_f32_16x16x32_bf16 v[64:67], v[140:143], v[208:211], v[64:67]
	s_setprio 0
	s_setprio 1
	v_mfma_f32_16x16x32_bf16 v[28:31], v[158:161], v[180:183], v[28:31]
	v_mfma_f32_16x16x32_bf16 v[24:27], v[172:175], v[180:183], v[24:27]
	v_mfma_f32_16x16x32_bf16 v[20:23], v[158:161], v[188:191], v[20:23]
	v_mfma_f32_16x16x32_bf16 v[16:19], v[172:175], v[188:191], v[16:19]
	v_mfma_f32_16x16x32_bf16 v[12:15], v[158:161], v[196:199], v[12:15]
	v_mfma_f32_16x16x32_bf16 v[8:11], v[172:175], v[196:199], v[8:11]
	v_mfma_f32_16x16x32_bf16 v[4:7], v[158:161], v[204:207], v[4:7]
	v_mfma_f32_16x16x32_bf16 v[0:3], v[172:175], v[204:207], v[0:3]
	v_mfma_f32_16x16x32_bf16 v[28:31], v[162:165], v[184:187], v[28:31]
	v_mfma_f32_16x16x32_bf16 v[24:27], v[176:179], v[184:187], v[24:27]
	v_mfma_f32_16x16x32_bf16 v[20:23], v[162:165], v[192:195], v[20:23]
	v_mfma_f32_16x16x32_bf16 v[16:19], v[176:179], v[192:195], v[16:19]
	v_mfma_f32_16x16x32_bf16 v[12:15], v[162:165], v[200:203], v[12:15]
	v_mfma_f32_16x16x32_bf16 v[8:11], v[176:179], v[200:203], v[8:11]
	v_mfma_f32_16x16x32_bf16 v[4:7], v[162:165], v[208:211], v[4:7]
	v_mfma_f32_16x16x32_bf16 v[0:3], v[176:179], v[208:211], v[0:3]
	s_setprio 0
	s_barrier
	s_add_u32 s52, s52, 0x100
	s_addc_u32 s53, s53, 0
	s_add_u32 s80, s80, 0x100
	s_addc_u32 s81, s81, 0
	s_cmp_ge_u32 s82, s78
	s_mov_b32 s14, s82
	s_cbranch_scc0 .LBB0_2574
	s_branch .Lpost_2574
.LBB0_2574:
	ds_read_b128 v[128:131], v169
	ds_read_b128 v[132:135], v169 offset:1024
	ds_read_b128 v[136:139], v169 offset:2048
	ds_read_b128 v[140:143], v169 offset:3072
	ds_read_b128 v[158:161], v170
	ds_read_b128 v[162:165], v170 offset:1024
	ds_read_b128 v[172:175], v170 offset:2048
	ds_read_b128 v[176:179], v170 offset:3072
	s_add_i32 s82, s14, 2
	s_add_u32 s15, s52, 0xfffc0080
	s_addc_u32 s46, s53, -1
	s_cmp_eq_u32 s79, s14
	s_cselect_b32 s14, s77, s80
	s_cselect_b32 s47, s3, s46
	s_cselect_b32 s46, s41, s15
	s_cselect_b32 s15, s43, s81
	v_lshl_add_u64 v[144:145], s[52:53], 0, v[154:155]
	s_add_i32 m0, s51, 0xc000
	ds_read_b128 v[180:183], v171
	ds_read_b128 v[184:187], v171 offset:1024
	ds_read_b128 v[188:191], v171 offset:2048
	ds_read_b128 v[192:195], v171 offset:3072
	ds_read_b128 v[196:199], v171 offset:4096
	ds_read_b128 v[200:203], v171 offset:5120
	ds_read_b128 v[204:207], v171 offset:6144
	ds_read_b128 v[208:211], v171 offset:7168
	global_load_lds_dwordx4 v[144:145], off
	v_lshl_add_u64 v[144:145], s[52:53], 0, v[156:157]
	s_add_i32 m0, s51, 0xe000
	s_nop 0
	global_load_lds_dwordx4 v[144:145], off
	s_waitcnt vmcnt(8)
	s_waitcnt lgkmcnt(0)
	s_barrier
; #define G_STAGE(bufoff, gbase, voff) do { _Pragma("unroll") for (int _i = 0; _i < 2; ++_i) \
;         __builtin_amdgcn_global_load_lds((const unsigned*)((const char*)(gbase) + voff[_i]), (LAS unsigned*)(lds + (bufoff) + ldsw + _i * 8192), 16, 0, 0); } while (0)
; #define G_LDA(dst, b, h) do { _Pragma("unroll") for (int m = 0; m < 4; ++m) _Pragma("unroll") for (int k = 0; k < 2; ++k) dst[m][k] = *(const LAS bf16x8*)(lds + G_SA(b, h) + aoff + m * 2048 + k * 1024); } while (0)
; #define G_MMA(ai, bj, At_, Bt_) do { __builtin_amdgcn_s_setprio(1); _Pragma("unroll") for (int m = 0; m < 4; ++m) _Pragma("unroll") for (int n = 0; n < 2; ++n) _Pragma("unroll") for (int k = 0; k < 2; ++k) \
;         acc[ai][bj][m][n] = __builtin_amdgcn_mfma_f32_16x16x32_bf16(Bt_[n][k], At_[m][k], acc[ai][bj][m][n], 0, 0, 0); __builtin_amdgcn_s_setprio(0); } while (0)
; #define WAIT_V(n) asm volatile("s_waitcnt vmcnt(" #n ")" ::: "memory")
; #define WAIT_L(n) asm volatile("s_waitcnt lgkmcnt(" #n ")" ::: "memory")
; #define BAR __builtin_amdgcn_s_barrier()
; #define SCHED __builtin_amdgcn_sched_barrier(0)
; template <class Get, class Epi>
; DI void gemm_loop(int ntiles, int ld, char* shm, const Get& get, const Epi& epi) {
;     ...
;             WAIT_V(8); WAIT_L(0); BAR; G_MMA(0, 0, At, B0); G_MMA(0, 1, At, B1); BAR; SCHED;
;             G_LDA(At, 0, 1); G_STAGE(G_SB(0, 0), b2, voffB); G_STAGE(G_SB(0, 1), b2 + hstep, voffB); G_STAGE(G_SA(0, 0), a2, voffA);
;             WAIT_V(8); WAIT_L(0); BAR; G_MMA(1, 0, At, B0); G_MMA(1, 1, At, B1); BAR; SCHED;
	s_setprio 1
	v_mfma_f32_16x16x32_bf16 v[124:127], v[128:131], v[180:183], v[124:127]
	v_mfma_f32_16x16x32_bf16 v[120:123], v[136:139], v[180:183], v[120:123]
	v_mfma_f32_16x16x32_bf16 v[116:119], v[128:131], v[188:191], v[116:119]
	v_mfma_f32_16x16x32_bf16 v[112:115], v[136:139], v[188:191], v[112:115]
	v_mfma_f32_16x16x32_bf16 v[108:111], v[128:131], v[196:199], v[108:111]
	v_mfma_f32_16x16x32_bf16 v[104:107], v[136:139], v[196:199], v[104:107]
	v_mfma_f32_16x16x32_bf16 v[100:103], v[128:131], v[204:207], v[100:103]
	v_mfma_f32_16x16x32_bf16 v[96:99], v[136:139], v[204:207], v[96:99]
	v_mfma_f32_16x16x32_bf16 v[124:127], v[132:135], v[184:187], v[124:127]
	v_mfma_f32_16x16x32_bf16 v[120:123], v[140:143], v[184:187], v[120:123]
	v_mfma_f32_16x16x32_bf16 v[116:119], v[132:135], v[192:195], v[116:119]
	v_mfma_f32_16x16x32_bf16 v[112:115], v[140:143], v[192:195], v[112:115]
	v_mfma_f32_16x16x32_bf16 v[108:111], v[132:135], v[200:203], v[108:111]
	v_mfma_f32_16x16x32_bf16 v[104:107], v[140:143], v[200:203], v[104:107]
	v_mfma_f32_16x16x32_bf16 v[100:103], v[132:135], v[208:211], v[100:103]
	v_mfma_f32_16x16x32_bf16 v[96:99], v[140:143], v[208:211], v[96:99]
	s_setprio 0
	s_setprio 1
	v_mfma_f32_16x16x32_bf16 v[60:63], v[158:161], v[180:183], v[60:63]
	v_mfma_f32_16x16x32_bf16 v[56:59], v[172:175], v[180:183], v[56:59]
	v_mfma_f32_16x16x32_bf16 v[52:55], v[158:161], v[188:191], v[52:55]
	v_mfma_f32_16x16x32_bf16 v[48:51], v[172:175], v[188:191], v[48:51]
	v_mfma_f32_16x16x32_bf16 v[44:47], v[158:161], v[196:199], v[44:47]
	v_mfma_f32_16x16x32_bf16 v[40:43], v[172:175], v[196:199], v[40:43]
	v_mfma_f32_16x16x32_bf16 v[36:39], v[158:161], v[204:207], v[36:39]
	v_mfma_f32_16x16x32_bf16 v[32:35], v[172:175], v[204:207], v[32:35]
	v_mfma_f32_16x16x32_bf16 v[60:63], v[162:165], v[184:187], v[60:63]
	v_mfma_f32_16x16x32_bf16 v[56:59], v[176:179], v[184:187], v[56:59]
	v_mfma_f32_16x16x32_bf16 v[52:55], v[162:165], v[192:195], v[52:55]
	v_mfma_f32_16x16x32_bf16 v[48:51], v[176:179], v[192:195], v[48:51]
	v_mfma_f32_16x16x32_bf16 v[44:47], v[162:165], v[200:203], v[44:47]
	v_mfma_f32_16x16x32_bf16 v[40:43], v[176:179], v[200:203], v[40:43]
	v_mfma_f32_16x16x32_bf16 v[36:39], v[162:165], v[208:211], v[36:39]
	v_mfma_f32_16x16x32_bf16 v[32:35], v[176:179], v[208:211], v[32:35]
	s_setprio 0
	s_barrier
	s_add_i32 s83, s72, s31
	v_lshl_add_u64 v[144:145], s[14:15], 0, v[148:149]
	s_mov_b32 m0, s83
	ds_read_b128 v[180:183], v171 offset:16384
	ds_read_b128 v[184:187], v171 offset:17408
	ds_read_b128 v[188:191], v171 offset:18432
	ds_read_b128 v[192:195], v171 offset:19456
	ds_read_b128 v[196:199], v171 offset:20480
	ds_read_b128 v[200:203], v171 offset:21504
	ds_read_b128 v[204:207], v171 offset:22528
	ds_read_b128 v[208:211], v171 offset:23552
	global_load_lds_dwordx4 v[144:145], off
	s_add_i32 m0, s83, 0x2000
	s_add_u32 s84, s14, 0x40000
	v_lshl_add_u64 v[166:167], s[14:15], 0, v[152:153]
	s_addc_u32 s85, s15, 0
	s_add_i32 s83, s73, s31
	global_load_lds_dwordx4 v[166:167], off
	v_lshl_add_u64 v[212:213], s[84:85], 0, v[148:149]
	s_mov_b32 m0, s83
	v_lshl_add_u64 v[214:215], s[46:47], 0, v[150:151]
	global_load_lds_dwordx4 v[212:213], off
	v_lshl_add_u64 v[212:213], s[84:85], 0, v[152:153]
	s_add_i32 m0, s83, 0x2000
	s_nop 0
	global_load_lds_dwordx4 v[212:213], off
	v_lshl_add_u64 v[212:213], s[46:47], 0, v[146:147]
	s_mov_b32 m0, s51
	s_nop 0
	global_load_lds_dwordx4 v[212:213], off
	s_mov_b32 m0, s54
	s_nop 0
	global_load_lds_dwordx4 v[214:215], off
	s_waitcnt vmcnt(8)
	s_waitcnt lgkmcnt(0)
	s_barrier
	s_setprio 1
	v_mfma_f32_16x16x32_bf16 v[92:95], v[128:131], v[180:183], v[92:95]
	v_mfma_f32_16x16x32_bf16 v[88:91], v[136:139], v[180:183], v[88:91]
	v_mfma_f32_16x16x32_bf16 v[84:87], v[128:131], v[188:191], v[84:87]
	v_mfma_f32_16x16x32_bf16 v[80:83], v[136:139], v[188:191], v[80:83]
	v_mfma_f32_16x16x32_bf16 v[76:79], v[128:131], v[196:199], v[76:79]
	v_mfma_f32_16x16x32_bf16 v[72:75], v[136:139], v[196:199], v[72:75]
	v_mfma_f32_16x16x32_bf16 v[68:71], v[128:131], v[204:207], v[68:71]
	v_mfma_f32_16x16x32_bf16 v[64:67], v[136:139], v[204:207], v[64:67]
	v_mfma_f32_16x16x32_bf16 v[92:95], v[132:135], v[184:187], v[92:95]
	v_mfma_f32_16x16x32_bf16 v[88:91], v[140:143], v[184:187], v[88:91]
	v_mfma_f32_16x16x32_bf16 v[84:87], v[132:135], v[192:195], v[84:87]
	v_mfma_f32_16x16x32_bf16 v[80:83], v[140:143], v[192:195], v[80:83]
	v_mfma_f32_16x16x32_bf16 v[76:79], v[132:135], v[200:203], v[76:79]
	v_mfma_f32_16x16x32_bf16 v[72:75], v[140:143], v[200:203], v[72:75]
	v_mfma_f32_16x16x32_bf16 v[68:71], v[132:135], v[208:211], v[68:71]
	v_mfma_f32_16x16x32_bf16 v[64:67], v[140:143], v[208:211], v[64:67]
	s_setprio 0
	s_setprio 1
	v_mfma_f32_16x16x32_bf16 v[28:31], v[158:161], v[180:183], v[28:31]
	v_mfma_f32_16x16x32_bf16 v[24:27], v[172:175], v[180:183], v[24:27]
	v_mfma_f32_16x16x32_bf16 v[20:23], v[158:161], v[188:191], v[20:23]
	v_mfma_f32_16x16x32_bf16 v[16:19], v[172:175], v[188:191], v[16:19]
	v_mfma_f32_16x16x32_bf16 v[12:15], v[158:161], v[196:199], v[12:15]
	v_mfma_f32_16x16x32_bf16 v[8:11], v[172:175], v[196:199], v[8:11]
	v_mfma_f32_16x16x32_bf16 v[4:7], v[158:161], v[204:207], v[4:7]
	v_mfma_f32_16x16x32_bf16 v[0:3], v[172:175], v[204:207], v[0:3]
	v_mfma_f32_16x16x32_bf16 v[28:31], v[162:165], v[184:187], v[28:31]
	v_mfma_f32_16x16x32_bf16 v[24:27], v[176:179], v[184:187], v[24:27]
	v_mfma_f32_16x16x32_bf16 v[20:23], v[162:165], v[192:195], v[20:23]
	v_mfma_f32_16x16x32_bf16 v[16:19], v[176:179], v[192:195], v[16:19]
	v_mfma_f32_16x16x32_bf16 v[12:15], v[162:165], v[200:203], v[12:15]
	v_mfma_f32_16x16x32_bf16 v[8:11], v[176:179], v[200:203], v[8:11]
	v_mfma_f32_16x16x32_bf16 v[4:7], v[162:165], v[208:211], v[4:7]
	v_mfma_f32_16x16x32_bf16 v[0:3], v[176:179], v[208:211], v[0:3]
	s_setprio 0
	s_barrier
; #define G_STAGE(bufoff, gbase, voff) do { _Pragma("unroll") for (int _i = 0; _i < 2; ++_i) \
;         __builtin_amdgcn_global_load_lds((const unsigned*)((const char*)(gbase) + voff[_i]), (LAS unsigned*)(lds + (bufoff) + ldsw + _i * 8192), 16, 0, 0); } while (0)
; #define G_LDA(dst, b, h) do { _Pragma("unroll") for (int m = 0; m < 4; ++m) _Pragma("unroll") for (int k = 0; k < 2; ++k) dst[m][k] = *(const LAS bf16x8*)(lds + G_SA(b, h) + aoff + m * 2048 + k * 1024); } while (0)
; #define G_LDB(dst, b, h) do { _Pragma("unroll") for (int n = 0; n < 2; ++n) _Pragma("unroll") for (int k = 0; k < 2; ++k) dst[n][k] = *(const LAS bf16x8*)(lds + G_SB(b, h) + boff + n * 2048 + k * 1024); } while (0)
; #define G_MMA(ai, bj, At_, Bt_) do { __builtin_amdgcn_s_setprio(1); _Pragma("unroll") for (int m = 0; m < 4; ++m) _Pragma("unroll") for (int n = 0; n < 2; ++n) _Pragma("unroll") for (int k = 0; k < 2; ++k) \
;         acc[ai][bj][m][n] = __builtin_amdgcn_mfma_f32_16x16x32_bf16(Bt_[n][k], At_[m][k], acc[ai][bj][m][n], 0, 0, 0); __builtin_amdgcn_s_setprio(0); } while (0)
; #define WAIT_V(n) asm volatile("s_waitcnt vmcnt(" #n ")" ::: "memory")
; #define WAIT_L(n) asm volatile("s_waitcnt lgkmcnt(" #n ")" ::: "memory")
; #define BAR __builtin_amdgcn_s_barrier()
; #define SCHED __builtin_amdgcn_sched_barrier(0)
; template <class Get, class Epi>
; DI void gemm_loop(int ntiles, int ld, char* shm, const Get& get, const Epi& epi) {
;     ...
;             G_LDB(B0, 1, 0); G_LDB(B1, 1, 1); SCHED; G_LDA(At, 1, 0); G_STAGE(G_SA(0, 1), a2 + hstep, voffA);
;             WAIT_V(8); WAIT_L(0); BAR; G_MMA(0, 0, At, B0); G_MMA(0, 1, At, B1); BAR; SCHED;
	s_add_i32 s83, 0, 0x18000
	s_add_i32 s84, 0, 0x1c000
	v_add_u32_e32 v140, s83, v168
	v_add_u32_e32 v176, s84, v168
	ds_read_b128 v[128:131], v140
	ds_read_b128 v[132:135], v140 offset:1024
	ds_read_b128 v[136:139], v140 offset:2048
	ds_read_b128 v[140:143], v140 offset:3072
	ds_read_b128 v[158:161], v176
	ds_read_b128 v[162:165], v176 offset:1024
	ds_read_b128 v[172:175], v176 offset:2048
	ds_read_b128 v[176:179], v176 offset:3072
	s_add_u32 s46, s46, 0x40000
	s_addc_u32 s47, s47, 0
	s_mov_b32 m0, s55
	v_lshl_add_u64 v[216:217], s[46:47], 0, v[146:147]
	ds_read_b128 v[180:183], v171 offset:32768
	ds_read_b128 v[184:187], v171 offset:33792
	ds_read_b128 v[188:191], v171 offset:34816
	ds_read_b128 v[192:195], v171 offset:35840
	ds_read_b128 v[196:199], v171 offset:36864
	ds_read_b128 v[200:203], v171 offset:37888
	ds_read_b128 v[204:207], v171 offset:38912
	ds_read_b128 v[208:211], v171 offset:39936
	global_load_lds_dwordx4 v[216:217], off
	v_lshl_add_u64 v[216:217], s[46:47], 0, v[150:151]
	s_mov_b32 m0, s56
	s_nop 0
	global_load_lds_dwordx4 v[216:217], off
	s_waitcnt vmcnt(8)
	s_waitcnt lgkmcnt(0)
	s_barrier
	s_setprio 1
	v_mfma_f32_16x16x32_bf16 v[124:127], v[128:131], v[180:183], v[124:127]
	v_mfma_f32_16x16x32_bf16 v[120:123], v[136:139], v[180:183], v[120:123]
	v_mfma_f32_16x16x32_bf16 v[116:119], v[128:131], v[188:191], v[116:119]
	v_mfma_f32_16x16x32_bf16 v[112:115], v[136:139], v[188:191], v[112:115]
	v_mfma_f32_16x16x32_bf16 v[108:111], v[128:131], v[196:199], v[108:111]
	v_mfma_f32_16x16x32_bf16 v[104:107], v[136:139], v[196:199], v[104:107]
	v_mfma_f32_16x16x32_bf16 v[100:103], v[128:131], v[204:207], v[100:103]
	v_mfma_f32_16x16x32_bf16 v[96:99], v[136:139], v[204:207], v[96:99]
	v_mfma_f32_16x16x32_bf16 v[124:127], v[132:135], v[184:187], v[124:127]
	v_mfma_f32_16x16x32_bf16 v[120:123], v[140:143], v[184:187], v[120:123]
	v_mfma_f32_16x16x32_bf16 v[116:119], v[132:135], v[192:195], v[116:119]
	v_mfma_f32_16x16x32_bf16 v[112:115], v[140:143], v[192:195], v[112:115]
	v_mfma_f32_16x16x32_bf16 v[108:111], v[132:135], v[200:203], v[108:111]
	v_mfma_f32_16x16x32_bf16 v[104:107], v[140:143], v[200:203], v[104:107]
	v_mfma_f32_16x16x32_bf16 v[100:103], v[132:135], v[208:211], v[100:103]
	v_mfma_f32_16x16x32_bf16 v[96:99], v[140:143], v[208:211], v[96:99]
	s_setprio 0
	s_setprio 1
	v_mfma_f32_16x16x32_bf16 v[60:63], v[158:161], v[180:183], v[60:63]
	v_mfma_f32_16x16x32_bf16 v[56:59], v[172:175], v[180:183], v[56:59]
	v_mfma_f32_16x16x32_bf16 v[52:55], v[158:161], v[188:191], v[52:55]
	v_mfma_f32_16x16x32_bf16 v[48:51], v[172:175], v[188:191], v[48:51]
	v_mfma_f32_16x16x32_bf16 v[44:47], v[158:161], v[196:199], v[44:47]
	v_mfma_f32_16x16x32_bf16 v[40:43], v[172:175], v[196:199], v[40:43]
	v_mfma_f32_16x16x32_bf16 v[36:39], v[158:161], v[204:207], v[36:39]
	v_mfma_f32_16x16x32_bf16 v[32:35], v[172:175], v[204:207], v[32:35]
	v_mfma_f32_16x16x32_bf16 v[60:63], v[162:165], v[184:187], v[60:63]
	v_mfma_f32_16x16x32_bf16 v[56:59], v[176:179], v[184:187], v[56:59]
	v_mfma_f32_16x16x32_bf16 v[52:55], v[162:165], v[192:195], v[52:55]
	v_mfma_f32_16x16x32_bf16 v[48:51], v[176:179], v[192:195], v[48:51]
	v_mfma_f32_16x16x32_bf16 v[44:47], v[162:165], v[200:203], v[44:47]
	v_mfma_f32_16x16x32_bf16 v[40:43], v[176:179], v[200:203], v[40:43]
	v_mfma_f32_16x16x32_bf16 v[36:39], v[162:165], v[208:211], v[36:39]
	v_mfma_f32_16x16x32_bf16 v[32:35], v[176:179], v[208:211], v[32:35]
	s_setprio 0
	s_barrier
; #define G_STAGE(bufoff, gbase, voff) do { _Pragma("unroll") for (int _i = 0; _i < 2; ++_i) \
;         __builtin_amdgcn_global_load_lds((const unsigned*)((const char*)(gbase) + voff[_i]), (LAS unsigned*)(lds + (bufoff) + ldsw + _i * 8192), 16, 0, 0); } while (0)
; #define G_LDA(dst, b, h) do { _Pragma("unroll") for (int m = 0; m < 4; ++m) _Pragma("unroll") for (int k = 0; k < 2; ++k) dst[m][k] = *(const LAS bf16x8*)(lds + G_SA(b, h) + aoff + m * 2048 + k * 1024); } while (0)
; #define G_MMA(ai, bj, At_, Bt_) do { __builtin_amdgcn_s_setprio(1); _Pragma("unroll") for (int m = 0; m < 4; ++m) _Pragma("unroll") for (int n = 0; n < 2; ++n) _Pragma("unroll") for (int k = 0; k < 2; ++k) \
;         acc[ai][bj][m][n] = __builtin_amdgcn_mfma_f32_16x16x32_bf16(Bt_[n][k], At_[m][k], acc[ai][bj][m][n], 0, 0, 0); __builtin_amdgcn_s_setprio(0); } while (0)
; #define WAIT_V(n) asm volatile("s_waitcnt vmcnt(" #n ")" ::: "memory")
; #define WAIT_L(n) asm volatile("s_waitcnt lgkmcnt(" #n ")" ::: "memory")
; #define BAR __builtin_amdgcn_s_barrier()
; #define SCHED __builtin_amdgcn_sched_barrier(0)
; template <class Get, class Epi>
; DI void gemm_loop(int ntiles, int ld, char* shm, const Get& get, const Epi& epi) {
;     ...
;             G_LDA(At, 1, 1); G_STAGE(G_SB(1, 0), b3, voffB); G_STAGE(G_SB(1, 1), b3 + hstep, voffB); G_STAGE(G_SA(1, 0), a3, voffA);
;             WAIT_V(8); WAIT_L(0); BAR; G_MMA(1, 0, At, B0); G_MMA(1, 1, At, B1); BAR; SCHED;
;         }
	s_add_i32 s46, s83, s31
	v_lshl_add_u64 v[144:145], v[144:145], 0, s[8:9]
	s_mov_b32 m0, s46
	ds_read_b128 v[180:183], v171 offset:49152
	ds_read_b128 v[184:187], v171 offset:50176
	ds_read_b128 v[188:191], v171 offset:51200
	ds_read_b128 v[192:195], v171 offset:52224
	ds_read_b128 v[196:199], v171 offset:53248
	ds_read_b128 v[200:203], v171 offset:54272
	ds_read_b128 v[204:207], v171 offset:55296
	ds_read_b128 v[208:211], v171 offset:56320
	global_load_lds_dwordx4 v[144:145], off
	s_add_i32 m0, s46, 0x2000
	s_add_u32 s14, s14, 0x40080
	v_lshl_add_u64 v[144:145], v[166:167], 0, s[8:9]
	s_addc_u32 s15, s15, 0
	s_add_i32 s46, s84, s31
	global_load_lds_dwordx4 v[144:145], off
	v_lshl_add_u64 v[144:145], s[14:15], 0, v[148:149]
	s_mov_b32 m0, s46
	s_nop 0
	global_load_lds_dwordx4 v[144:145], off
	v_lshl_add_u64 v[144:145], s[14:15], 0, v[152:153]
	s_add_i32 m0, s46, 0x2000
	s_nop 0
	global_load_lds_dwordx4 v[144:145], off
	v_lshl_add_u64 v[144:145], v[212:213], 0, s[8:9]
	s_mov_b32 m0, s59
	s_nop 0
	global_load_lds_dwordx4 v[144:145], off
	v_lshl_add_u64 v[144:145], v[214:215], 0, s[8:9]
	s_mov_b32 m0, s71
	s_nop 0
	global_load_lds_dwordx4 v[144:145], off
	s_waitcnt vmcnt(8)
	s_waitcnt lgkmcnt(0)
	s_barrier
	s_setprio 1
	v_mfma_f32_16x16x32_bf16 v[92:95], v[128:131], v[180:183], v[92:95]
	v_mfma_f32_16x16x32_bf16 v[88:91], v[136:139], v[180:183], v[88:91]
	v_mfma_f32_16x16x32_bf16 v[84:87], v[128:131], v[188:191], v[84:87]
	v_mfma_f32_16x16x32_bf16 v[80:83], v[136:139], v[188:191], v[80:83]
	v_mfma_f32_16x16x32_bf16 v[76:79], v[128:131], v[196:199], v[76:79]
	v_mfma_f32_16x16x32_bf16 v[72:75], v[136:139], v[196:199], v[72:75]
	v_mfma_f32_16x16x32_bf16 v[68:71], v[128:131], v[204:207], v[68:71]
	v_mfma_f32_16x16x32_bf16 v[64:67], v[136:139], v[204:207], v[64:67]
	v_mfma_f32_16x16x32_bf16 v[92:95], v[132:135], v[184:187], v[92:95]
	v_mfma_f32_16x16x32_bf16 v[88:91], v[140:143], v[184:187], v[88:91]
	v_mfma_f32_16x16x32_bf16 v[84:87], v[132:135], v[192:195], v[84:87]
	v_mfma_f32_16x16x32_bf16 v[80:83], v[140:143], v[192:195], v[80:83]
	v_mfma_f32_16x16x32_bf16 v[76:79], v[132:135], v[200:203], v[76:79]
	v_mfma_f32_16x16x32_bf16 v[72:75], v[140:143], v[200:203], v[72:75]
	v_mfma_f32_16x16x32_bf16 v[68:71], v[132:135], v[208:211], v[68:71]
	v_mfma_f32_16x16x32_bf16 v[64:67], v[140:143], v[208:211], v[64:67]
	s_setprio 0
	s_setprio 1
	v_mfma_f32_16x16x32_bf16 v[28:31], v[158:161], v[180:183], v[28:31]
	v_mfma_f32_16x16x32_bf16 v[24:27], v[172:175], v[180:183], v[24:27]
	v_mfma_f32_16x16x32_bf16 v[20:23], v[158:161], v[188:191], v[20:23]
	v_mfma_f32_16x16x32_bf16 v[16:19], v[172:175], v[188:191], v[16:19]
	v_mfma_f32_16x16x32_bf16 v[12:15], v[158:161], v[196:199], v[12:15]
	v_mfma_f32_16x16x32_bf16 v[8:11], v[172:175], v[196:199], v[8:11]
	v_mfma_f32_16x16x32_bf16 v[4:7], v[158:161], v[204:207], v[4:7]
	v_mfma_f32_16x16x32_bf16 v[0:3], v[172:175], v[204:207], v[0:3]
	v_mfma_f32_16x16x32_bf16 v[28:31], v[162:165], v[184:187], v[28:31]
	v_mfma_f32_16x16x32_bf16 v[24:27], v[176:179], v[184:187], v[24:27]
	v_mfma_f32_16x16x32_bf16 v[20:23], v[162:165], v[192:195], v[20:23]
	v_mfma_f32_16x16x32_bf16 v[16:19], v[176:179], v[192:195], v[16:19]
	v_mfma_f32_16x16x32_bf16 v[12:15], v[162:165], v[200:203], v[12:15]
	v_mfma_f32_16x16x32_bf16 v[8:11], v[176:179], v[200:203], v[8:11]
	v_mfma_f32_16x16x32_bf16 v[4:7], v[162:165], v[208:211], v[4:7]
	v_mfma_f32_16x16x32_bf16 v[0:3], v[176:179], v[208:211], v[0:3]
	s_setprio 0
	s_barrier
	s_add_u32 s52, s52, 0x100
	s_addc_u32 s53, s53, 0
	s_add_u32 s80, s80, 0x100
	s_addc_u32 s81, s81, 0
	s_cmp_ge_u32 s82, s78
	s_mov_b32 s14, s82
	s_cbranch_scc0 .LBB0_2574

; #define G_STAGE(bufoff, gbase, voff) do { _Pragma("unroll") for (int _i = 0; _i < 2; ++_i) \
;         __builtin_amdgcn_global_load_lds((const unsigned*)((const char*)(gbase) + voff[_i]), (LAS unsigned*)(lds + (bufoff) + ldsw + _i * 8192), 16, 0, 0); } while (0)
; #define G_LDA(dst, b, h) do { _Pragma("unroll") for (int m = 0; m < 4; ++m) _Pragma("unroll") for (int k = 0; k < 2; ++k) dst[m][k] = *(const LAS bf16x8*)(lds + G_SA(b, h) + aoff + m * 2048 + k * 1024); } while (0)
; #define G_MMA(ai, bj, At_, Bt_) do { __builtin_amdgcn_s_setprio(1); _Pragma("unroll") for (int m = 0; m < 4; ++m) _Pragma("unroll") for (int n = 0; n < 2; ++n) _Pragma("unroll") for (int k = 0; k < 2; ++k) \
;         acc[ai][bj][m][n] = __builtin_amdgcn_mfma_f32_16x16x32_bf16(Bt_[n][k], At_[m][k], acc[ai][bj][m][n], 0, 0, 0); __builtin_amdgcn_s_setprio(0); } while (0)
; #define WAIT_V(n) asm volatile("s_waitcnt vmcnt(" #n ")" ::: "memory")
; #define WAIT_L(n) asm volatile("s_waitcnt lgkmcnt(" #n ")" ::: "memory")
; #define BAR __builtin_amdgcn_s_barrier()
; #define SCHED __builtin_amdgcn_sched_barrier(0)
; template <class Get, class Epi>
; DI void gemm_loop(int ntiles, int ld, char* shm, const Get& get, const Epi& epi) {
;     ...
;             WAIT_V(8); WAIT_L(0); BAR; G_MMA(0, 0, At, B0); G_MMA(0, 1, At, B1); BAR; SCHED;
;             G_LDA(At, 0, 1); G_STAGE(G_SB(0, 0), b2, voffB); G_STAGE(G_SB(0, 1), b2 + hstep, voffB); G_STAGE(G_SA(0, 0), a2, voffA);
.Lrj_2892_0:
	s_waitcnt lgkmcnt(0)
	s_barrier
	s_setprio 1
	v_mfma_f32_16x16x32_bf16 v[124:127], v[128:131], v[180:183], 0
	v_mfma_f32_16x16x32_bf16 v[120:123], v[136:139], v[180:183], 0
	v_mfma_f32_16x16x32_bf16 v[116:119], v[128:131], v[188:191], 0
	v_mfma_f32_16x16x32_bf16 v[112:115], v[136:139], v[188:191], 0
	v_mfma_f32_16x16x32_bf16 v[108:111], v[128:131], v[196:199], 0
	v_mfma_f32_16x16x32_bf16 v[104:107], v[136:139], v[196:199], 0
	v_mfma_f32_16x16x32_bf16 v[100:103], v[128:131], v[204:207], 0
	v_mfma_f32_16x16x32_bf16 v[96:99], v[136:139], v[204:207], 0
	v_mfma_f32_16x16x32_bf16 v[124:127], v[132:135], v[184:187], v[124:127]
	v_mfma_f32_16x16x32_bf16 v[120:123], v[140:143], v[184:187], v[120:123]
	v_mfma_f32_16x16x32_bf16 v[116:119], v[132:135], v[192:195], v[116:119]
	v_mfma_f32_16x16x32_bf16 v[112:115], v[140:143], v[192:195], v[112:115]
	v_mfma_f32_16x16x32_bf16 v[108:111], v[132:135], v[200:203], v[108:111]
	v_mfma_f32_16x16x32_bf16 v[104:107], v[140:143], v[200:203], v[104:107]
	v_mfma_f32_16x16x32_bf16 v[100:103], v[132:135], v[208:211], v[100:103]
	v_mfma_f32_16x16x32_bf16 v[96:99], v[140:143], v[208:211], v[96:99]
	s_setprio 0
	s_setprio 1
	v_mfma_f32_16x16x32_bf16 v[60:63], v[158:161], v[180:183], 0
	v_mfma_f32_16x16x32_bf16 v[56:59], v[172:175], v[180:183], 0
	v_mfma_f32_16x16x32_bf16 v[52:55], v[158:161], v[188:191], 0
	v_mfma_f32_16x16x32_bf16 v[48:51], v[172:175], v[188:191], 0
	v_mfma_f32_16x16x32_bf16 v[44:47], v[158:161], v[196:199], 0
	v_mfma_f32_16x16x32_bf16 v[40:43], v[172:175], v[196:199], 0
	v_mfma_f32_16x16x32_bf16 v[36:39], v[158:161], v[204:207], 0
	v_mfma_f32_16x16x32_bf16 v[32:35], v[172:175], v[204:207], 0
	v_mfma_f32_16x16x32_bf16 v[60:63], v[162:165], v[184:187], v[60:63]
	v_mfma_f32_16x16x32_bf16 v[56:59], v[176:179], v[184:187], v[56:59]
	v_mfma_f32_16x16x32_bf16 v[52:55], v[162:165], v[192:195], v[52:55]
	v_mfma_f32_16x16x32_bf16 v[48:51], v[176:179], v[192:195], v[48:51]
	v_mfma_f32_16x16x32_bf16 v[44:47], v[162:165], v[200:203], v[44:47]
	v_mfma_f32_16x16x32_bf16 v[40:43], v[176:179], v[200:203], v[40:43]
	v_mfma_f32_16x16x32_bf16 v[36:39], v[162:165], v[208:211], v[36:39]
	v_mfma_f32_16x16x32_bf16 v[32:35], v[176:179], v[208:211], v[32:35]
	s_setprio 0
	s_barrier
	s_add_i32 s4, s58, s48
	v_lshl_add_u64 v[144:145], s[44:45], 0, v[148:149]
	s_mov_b32 m0, s4
	ds_read_b128 v[180:183], v171 offset:16384
	ds_read_b128 v[184:187], v171 offset:17408
	ds_read_b128 v[188:191], v171 offset:18432
	ds_read_b128 v[192:195], v171 offset:19456
	ds_read_b128 v[196:199], v171 offset:20480
	ds_read_b128 v[200:203], v171 offset:21504
	ds_read_b128 v[204:207], v171 offset:22528
	ds_read_b128 v[208:211], v171 offset:23552
	global_load_lds_dwordx4 v[144:145], off
	s_add_i32 m0, s4, 0x2000
	s_add_u32 s4, s44, 0xb0000
	v_lshl_add_u64 v[166:167], s[44:45], 0, v[152:153]
	s_addc_u32 s5, s45, 0
	s_add_i32 s84, s59, s48
	global_load_lds_dwordx4 v[166:167], off
	v_lshl_add_u64 v[212:213], s[4:5], 0, v[148:149]
	s_mov_b32 m0, s84
	v_lshl_add_u64 v[214:215], s[46:47], 0, v[150:151]
	global_load_lds_dwordx4 v[212:213], off
	v_lshl_add_u64 v[212:213], s[4:5], 0, v[152:153]
	s_add_i32 m0, s84, 0x2000
	s_nop 0
	global_load_lds_dwordx4 v[212:213], off
	v_lshl_add_u64 v[212:213], s[46:47], 0, v[146:147]
	s_mov_b32 m0, s49
	s_nop 0
	global_load_lds_dwordx4 v[212:213], off
	s_mov_b32 m0, s50
	s_nop 0
	global_load_lds_dwordx4 v[214:215], off
	s_cmp_lg_u32 s100, 0
	s_cbranch_scc0 .Lrf_2892_1
	s_waitcnt vmcnt(16)
	s_branch .Lrj_2892_1

; #define G_STAGE(bufoff, gbase, voff) do { _Pragma("unroll") for (int _i = 0; _i < 2; ++_i) \
;         __builtin_amdgcn_global_load_lds((const unsigned*)((const char*)(gbase) + voff[_i]), (LAS unsigned*)(lds + (bufoff) + ldsw + _i * 8192), 16, 0, 0); } while (0)
; #define G_LDA(dst, b, h) do { _Pragma("unroll") for (int m = 0; m < 4; ++m) _Pragma("unroll") for (int k = 0; k < 2; ++k) dst[m][k] = *(const LAS bf16x8*)(lds + G_SA(b, h) + aoff + m * 2048 + k * 1024); } while (0)
; #define G_LDB(dst, b, h) do { _Pragma("unroll") for (int n = 0; n < 2; ++n) _Pragma("unroll") for (int k = 0; k < 2; ++k) dst[n][k] = *(const LAS bf16x8*)(lds + G_SB(b, h) + boff + n * 2048 + k * 1024); } while (0)
; #define G_MMA(ai, bj, At_, Bt_) do { __builtin_amdgcn_s_setprio(1); _Pragma("unroll") for (int m = 0; m < 4; ++m) _Pragma("unroll") for (int n = 0; n < 2; ++n) _Pragma("unroll") for (int k = 0; k < 2; ++k) \
;         acc[ai][bj][m][n] = __builtin_amdgcn_mfma_f32_16x16x32_bf16(Bt_[n][k], At_[m][k], acc[ai][bj][m][n], 0, 0, 0); __builtin_amdgcn_s_setprio(0); } while (0)
; #define WAIT_V(n) asm volatile("s_waitcnt vmcnt(" #n ")" ::: "memory")
; #define WAIT_L(n) asm volatile("s_waitcnt lgkmcnt(" #n ")" ::: "memory")
; #define BAR __builtin_amdgcn_s_barrier()
; #define SCHED __builtin_amdgcn_sched_barrier(0)
; template <class Get, class Epi>
; DI void gemm_loop(int ntiles, int ld, char* shm, const Get& get, const Epi& epi) {
;     ...
;             WAIT_V(8); WAIT_L(0); BAR; G_MMA(1, 0, At, B0); G_MMA(1, 1, At, B1); BAR; SCHED;
;             G_LDB(B0, 1, 0); G_LDB(B1, 1, 1); SCHED; G_LDA(At, 1, 0); G_STAGE(G_SA(0, 1), a2 + hstep, voffA);
;             WAIT_V(8); WAIT_L(0); BAR; G_MMA(0, 0, At, B0); G_MMA(0, 1, At, B1); BAR; SCHED;
.Lrj_2892_1:
	s_waitcnt lgkmcnt(0)
	s_barrier
	s_setprio 1
	v_mfma_f32_16x16x32_bf16 v[92:95], v[128:131], v[180:183], 0
	v_mfma_f32_16x16x32_bf16 v[88:91], v[136:139], v[180:183], 0
	v_mfma_f32_16x16x32_bf16 v[84:87], v[128:131], v[188:191], 0
	v_mfma_f32_16x16x32_bf16 v[80:83], v[136:139], v[188:191], 0
	v_mfma_f32_16x16x32_bf16 v[76:79], v[128:131], v[196:199], 0
	v_mfma_f32_16x16x32_bf16 v[72:75], v[136:139], v[196:199], 0
	v_mfma_f32_16x16x32_bf16 v[68:71], v[128:131], v[204:207], 0
	v_mfma_f32_16x16x32_bf16 v[64:67], v[136:139], v[204:207], 0
	v_mfma_f32_16x16x32_bf16 v[92:95], v[132:135], v[184:187], v[92:95]
	v_mfma_f32_16x16x32_bf16 v[88:91], v[140:143], v[184:187], v[88:91]
	v_mfma_f32_16x16x32_bf16 v[84:87], v[132:135], v[192:195], v[84:87]
	v_mfma_f32_16x16x32_bf16 v[80:83], v[140:143], v[192:195], v[80:83]
	v_mfma_f32_16x16x32_bf16 v[76:79], v[132:135], v[200:203], v[76:79]
	v_mfma_f32_16x16x32_bf16 v[72:75], v[140:143], v[200:203], v[72:75]
	v_mfma_f32_16x16x32_bf16 v[68:71], v[132:135], v[208:211], v[68:71]
	v_mfma_f32_16x16x32_bf16 v[64:67], v[140:143], v[208:211], v[64:67]
	s_setprio 0
	s_setprio 1
	v_mfma_f32_16x16x32_bf16 v[28:31], v[158:161], v[180:183], 0
	v_mfma_f32_16x16x32_bf16 v[24:27], v[172:175], v[180:183], 0
	v_mfma_f32_16x16x32_bf16 v[20:23], v[158:161], v[188:191], 0
	v_mfma_f32_16x16x32_bf16 v[16:19], v[172:175], v[188:191], 0
	v_mfma_f32_16x16x32_bf16 v[12:15], v[158:161], v[196:199], 0
	v_mfma_f32_16x16x32_bf16 v[8:11], v[172:175], v[196:199], 0
	v_mfma_f32_16x16x32_bf16 v[4:7], v[158:161], v[204:207], 0
	v_mfma_f32_16x16x32_bf16 v[0:3], v[172:175], v[204:207], 0
	v_mfma_f32_16x16x32_bf16 v[28:31], v[162:165], v[184:187], v[28:31]
	v_mfma_f32_16x16x32_bf16 v[24:27], v[176:179], v[184:187], v[24:27]
	v_mfma_f32_16x16x32_bf16 v[20:23], v[162:165], v[192:195], v[20:23]
	v_mfma_f32_16x16x32_bf16 v[16:19], v[176:179], v[192:195], v[16:19]
	v_mfma_f32_16x16x32_bf16 v[12:15], v[162:165], v[200:203], v[12:15]
	v_mfma_f32_16x16x32_bf16 v[8:11], v[176:179], v[200:203], v[8:11]
	v_mfma_f32_16x16x32_bf16 v[4:7], v[162:165], v[208:211], v[4:7]
	v_mfma_f32_16x16x32_bf16 v[0:3], v[176:179], v[208:211], v[0:3]
	s_setprio 0
	s_barrier
	s_add_i32 s84, 0, 0x18000
	s_add_i32 s85, 0, 0x1c000
	v_add_u32_e32 v140, s84, v168
	v_add_u32_e32 v176, s85, v168
	ds_read_b128 v[128:131], v140
	ds_read_b128 v[132:135], v140 offset:1024
	ds_read_b128 v[136:139], v140 offset:2048
	ds_read_b128 v[140:143], v140 offset:3072
	ds_read_b128 v[158:161], v176
	ds_read_b128 v[162:165], v176 offset:1024
	ds_read_b128 v[172:175], v176 offset:2048
	ds_read_b128 v[176:179], v176 offset:3072
	s_add_u32 s4, s46, 0xb0000
	s_addc_u32 s5, s47, 0
	s_mov_b32 m0, s51
	v_lshl_add_u64 v[216:217], s[4:5], 0, v[146:147]
	ds_read_b128 v[180:183], v171 offset:32768
	ds_read_b128 v[184:187], v171 offset:33792
	ds_read_b128 v[188:191], v171 offset:34816
	ds_read_b128 v[192:195], v171 offset:35840
	ds_read_b128 v[196:199], v171 offset:36864
	ds_read_b128 v[200:203], v171 offset:37888
	ds_read_b128 v[204:207], v171 offset:38912
	ds_read_b128 v[208:211], v171 offset:39936
	global_load_lds_dwordx4 v[216:217], off
	v_lshl_add_u64 v[216:217], s[4:5], 0, v[150:151]
	s_mov_b32 m0, s52
	s_nop 0
	global_load_lds_dwordx4 v[216:217], off
	s_waitcnt vmcnt(8)
	s_waitcnt lgkmcnt(0)
	s_barrier
	s_setprio 1
	v_mfma_f32_16x16x32_bf16 v[124:127], v[128:131], v[180:183], v[124:127]
	v_mfma_f32_16x16x32_bf16 v[120:123], v[136:139], v[180:183], v[120:123]
	v_mfma_f32_16x16x32_bf16 v[116:119], v[128:131], v[188:191], v[116:119]
	v_mfma_f32_16x16x32_bf16 v[112:115], v[136:139], v[188:191], v[112:115]
	v_mfma_f32_16x16x32_bf16 v[108:111], v[128:131], v[196:199], v[108:111]
	v_mfma_f32_16x16x32_bf16 v[104:107], v[136:139], v[196:199], v[104:107]
	v_mfma_f32_16x16x32_bf16 v[100:103], v[128:131], v[204:207], v[100:103]
	v_mfma_f32_16x16x32_bf16 v[96:99], v[136:139], v[204:207], v[96:99]
	v_mfma_f32_16x16x32_bf16 v[124:127], v[132:135], v[184:187], v[124:127]
	v_mfma_f32_16x16x32_bf16 v[120:123], v[140:143], v[184:187], v[120:123]
	v_mfma_f32_16x16x32_bf16 v[116:119], v[132:135], v[192:195], v[116:119]
	v_mfma_f32_16x16x32_bf16 v[112:115], v[140:143], v[192:195], v[112:115]
	v_mfma_f32_16x16x32_bf16 v[108:111], v[132:135], v[200:203], v[108:111]
	v_mfma_f32_16x16x32_bf16 v[104:107], v[140:143], v[200:203], v[104:107]
	v_mfma_f32_16x16x32_bf16 v[100:103], v[132:135], v[208:211], v[100:103]
	v_mfma_f32_16x16x32_bf16 v[96:99], v[140:143], v[208:211], v[96:99]
	s_setprio 0
	s_setprio 1
	v_mfma_f32_16x16x32_bf16 v[60:63], v[158:161], v[180:183], v[60:63]
	v_mfma_f32_16x16x32_bf16 v[56:59], v[172:175], v[180:183], v[56:59]
	v_mfma_f32_16x16x32_bf16 v[52:55], v[158:161], v[188:191], v[52:55]
	v_mfma_f32_16x16x32_bf16 v[48:51], v[172:175], v[188:191], v[48:51]
	v_mfma_f32_16x16x32_bf16 v[44:47], v[158:161], v[196:199], v[44:47]
	v_mfma_f32_16x16x32_bf16 v[40:43], v[172:175], v[196:199], v[40:43]
	v_mfma_f32_16x16x32_bf16 v[36:39], v[158:161], v[204:207], v[36:39]
	v_mfma_f32_16x16x32_bf16 v[32:35], v[172:175], v[204:207], v[32:35]
	v_mfma_f32_16x16x32_bf16 v[60:63], v[162:165], v[184:187], v[60:63]
	v_mfma_f32_16x16x32_bf16 v[56:59], v[176:179], v[184:187], v[56:59]
	v_mfma_f32_16x16x32_bf16 v[52:55], v[162:165], v[192:195], v[52:55]
	v_mfma_f32_16x16x32_bf16 v[48:51], v[176:179], v[192:195], v[48:51]
	v_mfma_f32_16x16x32_bf16 v[44:47], v[162:165], v[200:203], v[44:47]
	v_mfma_f32_16x16x32_bf16 v[40:43], v[176:179], v[200:203], v[40:43]
	v_mfma_f32_16x16x32_bf16 v[36:39], v[162:165], v[208:211], v[36:39]
	v_mfma_f32_16x16x32_bf16 v[32:35], v[176:179], v[208:211], v[32:35]
	s_setprio 0
	s_barrier
; #define G_STAGE(bufoff, gbase, voff) do { _Pragma("unroll") for (int _i = 0; _i < 2; ++_i) \
;         __builtin_amdgcn_global_load_lds((const unsigned*)((const char*)(gbase) + voff[_i]), (LAS unsigned*)(lds + (bufoff) + ldsw + _i * 8192), 16, 0, 0); } while (0)
; #define G_LDA(dst, b, h) do { _Pragma("unroll") for (int m = 0; m < 4; ++m) _Pragma("unroll") for (int k = 0; k < 2; ++k) dst[m][k] = *(const LAS bf16x8*)(lds + G_SA(b, h) + aoff + m * 2048 + k * 1024); } while (0)
; #define G_LDB(dst, b, h) do { _Pragma("unroll") for (int n = 0; n < 2; ++n) _Pragma("unroll") for (int k = 0; k < 2; ++k) dst[n][k] = *(const LAS bf16x8*)(lds + G_SB(b, h) + boff + n * 2048 + k * 1024); } while (0)
; #define G_MMA(ai, bj, At_, Bt_) do { __builtin_amdgcn_s_setprio(1); _Pragma("unroll") for (int m = 0; m < 4; ++m) _Pragma("unroll") for (int n = 0; n < 2; ++n) _Pragma("unroll") for (int k = 0; k < 2; ++k) \
;         acc[ai][bj][m][n] = __builtin_amdgcn_mfma_f32_16x16x32_bf16(Bt_[n][k], At_[m][k], acc[ai][bj][m][n], 0, 0, 0); __builtin_amdgcn_s_setprio(0); } while (0)
; #define WAIT_V(n) asm volatile("s_waitcnt vmcnt(" #n ")" ::: "memory")
; #define WAIT_L(n) asm volatile("s_waitcnt lgkmcnt(" #n ")" ::: "memory")
; #define BAR __builtin_amdgcn_s_barrier()
; #define SCHED __builtin_amdgcn_sched_barrier(0)
; template <class Get, class Epi>
; DI void gemm_loop(int ntiles, int ld, char* shm, const Get& get, const Epi& epi) {
;     ...
;         for (int t = 0; t < nt; t += 2) {
;             const bool last = (t == nt - 2);
;             const char* a1 = cA + (size_t)(t + 1) * kstep;
;             const char* a2 = last ? nA : cA + (size_t)(t + 2) * kstep; const char* b2 = last ? nB : cB + (size_t)(t + 2) * kstep;
;             const char* a3 = a2 + kstep; const char* b3 = b2 + kstep;
;             G_LDB(B0, 0, 0); G_LDB(B1, 0, 1); SCHED; G_LDA(At, 0, 0); G_STAGE(G_SA(1, 1), a1 + hstep, voffA);
;     ...
;             G_LDA(At, 1, 1); G_STAGE(G_SB(1, 0), b3, voffB); G_STAGE(G_SB(1, 1), b3 + hstep, voffB); G_STAGE(G_SA(1, 0), a3, voffA);
;             WAIT_V(8); WAIT_L(0); BAR; G_MMA(1, 0, At, B0); G_MMA(1, 1, At, B1); BAR; SCHED;
	s_add_i32 s4, s84, s48
	v_lshl_add_u64 v[144:145], v[144:145], 0, s[10:11]
	s_mov_b32 m0, s4
	ds_read_b128 v[180:183], v171 offset:49152
	ds_read_b128 v[184:187], v171 offset:50176
	ds_read_b128 v[188:191], v171 offset:51200
	ds_read_b128 v[192:195], v171 offset:52224
	ds_read_b128 v[196:199], v171 offset:53248
	ds_read_b128 v[200:203], v171 offset:54272
	ds_read_b128 v[204:207], v171 offset:55296
	ds_read_b128 v[208:211], v171 offset:56320
	global_load_lds_dwordx4 v[144:145], off
	s_add_i32 m0, s4, 0x2000
	s_add_u32 s4, s44, 0xb0080
	v_lshl_add_u64 v[144:145], v[166:167], 0, s[10:11]
	s_addc_u32 s5, s45, 0
	s_add_i32 s44, s85, s48
	global_load_lds_dwordx4 v[144:145], off
	v_lshl_add_u64 v[144:145], s[4:5], 0, v[148:149]
	s_mov_b32 m0, s44
	s_nop 0
	global_load_lds_dwordx4 v[144:145], off
	v_lshl_add_u64 v[144:145], s[4:5], 0, v[152:153]
	s_add_i32 m0, s44, 0x2000
	s_nop 0
	global_load_lds_dwordx4 v[144:145], off
	v_lshl_add_u64 v[144:145], v[212:213], 0, s[10:11]
	s_mov_b32 m0, s55
	s_nop 0
	global_load_lds_dwordx4 v[144:145], off
	v_lshl_add_u64 v[144:145], v[214:215], 0, s[10:11]
	s_mov_b32 m0, s56
	s_nop 0
	global_load_lds_dwordx4 v[144:145], off
	s_waitcnt vmcnt(8)
	s_waitcnt lgkmcnt(0)
	s_barrier
	s_setprio 1
	v_mfma_f32_16x16x32_bf16 v[92:95], v[128:131], v[180:183], v[92:95]
	v_mfma_f32_16x16x32_bf16 v[88:91], v[136:139], v[180:183], v[88:91]
	v_mfma_f32_16x16x32_bf16 v[84:87], v[128:131], v[188:191], v[84:87]
	v_mfma_f32_16x16x32_bf16 v[80:83], v[136:139], v[188:191], v[80:83]
	v_mfma_f32_16x16x32_bf16 v[76:79], v[128:131], v[196:199], v[76:79]
	v_mfma_f32_16x16x32_bf16 v[72:75], v[136:139], v[196:199], v[72:75]
	v_mfma_f32_16x16x32_bf16 v[68:71], v[128:131], v[204:207], v[68:71]
	v_mfma_f32_16x16x32_bf16 v[64:67], v[136:139], v[204:207], v[64:67]
	v_mfma_f32_16x16x32_bf16 v[92:95], v[132:135], v[184:187], v[92:95]
	v_mfma_f32_16x16x32_bf16 v[88:91], v[140:143], v[184:187], v[88:91]
	v_mfma_f32_16x16x32_bf16 v[84:87], v[132:135], v[192:195], v[84:87]
	v_mfma_f32_16x16x32_bf16 v[80:83], v[140:143], v[192:195], v[80:83]
	v_mfma_f32_16x16x32_bf16 v[76:79], v[132:135], v[200:203], v[76:79]
	v_mfma_f32_16x16x32_bf16 v[72:75], v[140:143], v[200:203], v[72:75]
	v_mfma_f32_16x16x32_bf16 v[68:71], v[132:135], v[208:211], v[68:71]
	v_mfma_f32_16x16x32_bf16 v[64:67], v[140:143], v[208:211], v[64:67]
	s_setprio 0
	s_setprio 1
	v_mfma_f32_16x16x32_bf16 v[28:31], v[158:161], v[180:183], v[28:31]
	v_mfma_f32_16x16x32_bf16 v[24:27], v[172:175], v[180:183], v[24:27]
	v_mfma_f32_16x16x32_bf16 v[20:23], v[158:161], v[188:191], v[20:23]
	v_mfma_f32_16x16x32_bf16 v[16:19], v[172:175], v[188:191], v[16:19]
	v_mfma_f32_16x16x32_bf16 v[12:15], v[158:161], v[196:199], v[12:15]
	v_mfma_f32_16x16x32_bf16 v[8:11], v[172:175], v[196:199], v[8:11]
	v_mfma_f32_16x16x32_bf16 v[4:7], v[158:161], v[204:207], v[4:7]
	v_mfma_f32_16x16x32_bf16 v[0:3], v[172:175], v[204:207], v[0:3]
	v_mfma_f32_16x16x32_bf16 v[28:31], v[162:165], v[184:187], v[28:31]
	v_mfma_f32_16x16x32_bf16 v[24:27], v[176:179], v[184:187], v[24:27]
	v_mfma_f32_16x16x32_bf16 v[20:23], v[162:165], v[192:195], v[20:23]
	v_mfma_f32_16x16x32_bf16 v[16:19], v[176:179], v[192:195], v[16:19]
	v_mfma_f32_16x16x32_bf16 v[12:15], v[162:165], v[200:203], v[12:15]
	v_mfma_f32_16x16x32_bf16 v[8:11], v[176:179], v[200:203], v[8:11]
	v_mfma_f32_16x16x32_bf16 v[4:7], v[162:165], v[208:211], v[4:7]
	v_mfma_f32_16x16x32_bf16 v[0:3], v[176:179], v[208:211], v[0:3]
	s_setprio 0
	s_barrier
	s_add_u32 s81, s81, 0x100
	s_addc_u32 s82, s82, 0
	s_cmp_ge_u32 s83, s79
	s_mov_b64 s[4:5], s[14:15]
	s_mov_b32 s44, s83
	s_cbranch_scc0 .LBB0_2892
	s_branch .Lpost_2892
.LBB0_2892:
	ds_read_b128 v[128:131], v169
	ds_read_b128 v[132:135], v169 offset:1024
	ds_read_b128 v[136:139], v169 offset:2048
	ds_read_b128 v[140:143], v169 offset:3072
	ds_read_b128 v[158:161], v170
	ds_read_b128 v[162:165], v170 offset:1024
	ds_read_b128 v[172:175], v170 offset:2048
	ds_read_b128 v[176:179], v170 offset:3072
	s_add_i32 s83, s44, 2
	s_add_u32 s14, s4, 0x100
	s_addc_u32 s15, s5, 0
	s_cmp_eq_u32 s80, s44
	s_cselect_b32 s44, s42, s81
	s_cselect_b32 s47, s41, s15
	s_cselect_b32 s46, s40, s14
	s_cselect_b32 s45, s43, s82
	v_lshl_add_u64 v[144:145], s[4:5], 0, v[154:155]
	s_add_i32 m0, s49, 0xc000
	ds_read_b128 v[180:183], v171
	ds_read_b128 v[184:187], v171 offset:1024
	ds_read_b128 v[188:191], v171 offset:2048
	ds_read_b128 v[192:195], v171 offset:3072
	ds_read_b128 v[196:199], v171 offset:4096
	ds_read_b128 v[200:203], v171 offset:5120
	ds_read_b128 v[204:207], v171 offset:6144
	ds_read_b128 v[208:211], v171 offset:7168
	global_load_lds_dwordx4 v[144:145], off
	v_lshl_add_u64 v[144:145], s[4:5], 0, v[156:157]
	s_add_i32 m0, s49, 0xe000
	s_nop 0
	global_load_lds_dwordx4 v[144:145], off
	s_waitcnt vmcnt(8)
	s_waitcnt lgkmcnt(0)
	s_barrier
; #define G_STAGE(bufoff, gbase, voff) do { _Pragma("unroll") for (int _i = 0; _i < 2; ++_i) \
;         __builtin_amdgcn_global_load_lds((const unsigned*)((const char*)(gbase) + voff[_i]), (LAS unsigned*)(lds + (bufoff) + ldsw + _i * 8192), 16, 0, 0); } while (0)
; #define G_LDA(dst, b, h) do { _Pragma("unroll") for (int m = 0; m < 4; ++m) _Pragma("unroll") for (int k = 0; k < 2; ++k) dst[m][k] = *(const LAS bf16x8*)(lds + G_SA(b, h) + aoff + m * 2048 + k * 1024); } while (0)
; #define G_MMA(ai, bj, At_, Bt_) do { __builtin_amdgcn_s_setprio(1); _Pragma("unroll") for (int m = 0; m < 4; ++m) _Pragma("unroll") for (int n = 0; n < 2; ++n) _Pragma("unroll") for (int k = 0; k < 2; ++k) \
;         acc[ai][bj][m][n] = __builtin_amdgcn_mfma_f32_16x16x32_bf16(Bt_[n][k], At_[m][k], acc[ai][bj][m][n], 0, 0, 0); __builtin_amdgcn_s_setprio(0); } while (0)
; #define WAIT_V(n) asm volatile("s_waitcnt vmcnt(" #n ")" ::: "memory")
; #define WAIT_L(n) asm volatile("s_waitcnt lgkmcnt(" #n ")" ::: "memory")
; #define BAR __builtin_amdgcn_s_barrier()
; #define SCHED __builtin_amdgcn_sched_barrier(0)
; template <class Get, class Epi>
; DI void gemm_loop(int ntiles, int ld, char* shm, const Get& get, const Epi& epi) {
;     ...
;             WAIT_V(8); WAIT_L(0); BAR; G_MMA(0, 0, At, B0); G_MMA(0, 1, At, B1); BAR; SCHED;
;             G_LDA(At, 0, 1); G_STAGE(G_SB(0, 0), b2, voffB); G_STAGE(G_SB(0, 1), b2 + hstep, voffB); G_STAGE(G_SA(0, 0), a2, voffA);
;             WAIT_V(8); WAIT_L(0); BAR; G_MMA(1, 0, At, B0); G_MMA(1, 1, At, B1); BAR; SCHED;
	s_setprio 1
	v_mfma_f32_16x16x32_bf16 v[124:127], v[128:131], v[180:183], v[124:127]
	v_mfma_f32_16x16x32_bf16 v[120:123], v[136:139], v[180:183], v[120:123]
	v_mfma_f32_16x16x32_bf16 v[116:119], v[128:131], v[188:191], v[116:119]
	v_mfma_f32_16x16x32_bf16 v[112:115], v[136:139], v[188:191], v[112:115]
	v_mfma_f32_16x16x32_bf16 v[108:111], v[128:131], v[196:199], v[108:111]
	v_mfma_f32_16x16x32_bf16 v[104:107], v[136:139], v[196:199], v[104:107]
	v_mfma_f32_16x16x32_bf16 v[100:103], v[128:131], v[204:207], v[100:103]
	v_mfma_f32_16x16x32_bf16 v[96:99], v[136:139], v[204:207], v[96:99]
	v_mfma_f32_16x16x32_bf16 v[124:127], v[132:135], v[184:187], v[124:127]
	v_mfma_f32_16x16x32_bf16 v[120:123], v[140:143], v[184:187], v[120:123]
	v_mfma_f32_16x16x32_bf16 v[116:119], v[132:135], v[192:195], v[116:119]
	v_mfma_f32_16x16x32_bf16 v[112:115], v[140:143], v[192:195], v[112:115]
	v_mfma_f32_16x16x32_bf16 v[108:111], v[132:135], v[200:203], v[108:111]
	v_mfma_f32_16x16x32_bf16 v[104:107], v[140:143], v[200:203], v[104:107]
	v_mfma_f32_16x16x32_bf16 v[100:103], v[132:135], v[208:211], v[100:103]
	v_mfma_f32_16x16x32_bf16 v[96:99], v[140:143], v[208:211], v[96:99]
	s_setprio 0
	s_setprio 1
	v_mfma_f32_16x16x32_bf16 v[60:63], v[158:161], v[180:183], v[60:63]
	v_mfma_f32_16x16x32_bf16 v[56:59], v[172:175], v[180:183], v[56:59]
	v_mfma_f32_16x16x32_bf16 v[52:55], v[158:161], v[188:191], v[52:55]
	v_mfma_f32_16x16x32_bf16 v[48:51], v[172:175], v[188:191], v[48:51]
	v_mfma_f32_16x16x32_bf16 v[44:47], v[158:161], v[196:199], v[44:47]
	v_mfma_f32_16x16x32_bf16 v[40:43], v[172:175], v[196:199], v[40:43]
	v_mfma_f32_16x16x32_bf16 v[36:39], v[158:161], v[204:207], v[36:39]
	v_mfma_f32_16x16x32_bf16 v[32:35], v[172:175], v[204:207], v[32:35]
	v_mfma_f32_16x16x32_bf16 v[60:63], v[162:165], v[184:187], v[60:63]
	v_mfma_f32_16x16x32_bf16 v[56:59], v[176:179], v[184:187], v[56:59]
	v_mfma_f32_16x16x32_bf16 v[52:55], v[162:165], v[192:195], v[52:55]
	v_mfma_f32_16x16x32_bf16 v[48:51], v[176:179], v[192:195], v[48:51]
	v_mfma_f32_16x16x32_bf16 v[44:47], v[162:165], v[200:203], v[44:47]
	v_mfma_f32_16x16x32_bf16 v[40:43], v[176:179], v[200:203], v[40:43]
	v_mfma_f32_16x16x32_bf16 v[36:39], v[162:165], v[208:211], v[36:39]
	v_mfma_f32_16x16x32_bf16 v[32:35], v[176:179], v[208:211], v[32:35]
	s_setprio 0
	s_barrier
	s_add_i32 s4, s58, s48
	v_lshl_add_u64 v[144:145], s[44:45], 0, v[148:149]
	s_mov_b32 m0, s4
	ds_read_b128 v[180:183], v171 offset:16384
	ds_read_b128 v[184:187], v171 offset:17408
	ds_read_b128 v[188:191], v171 offset:18432
	ds_read_b128 v[192:195], v171 offset:19456
	ds_read_b128 v[196:199], v171 offset:20480
	ds_read_b128 v[200:203], v171 offset:21504
	ds_read_b128 v[204:207], v171 offset:22528
	ds_read_b128 v[208:211], v171 offset:23552
	global_load_lds_dwordx4 v[144:145], off
	s_add_i32 m0, s4, 0x2000
	s_add_u32 s4, s44, 0xb0000
	v_lshl_add_u64 v[166:167], s[44:45], 0, v[152:153]
	s_addc_u32 s5, s45, 0
	s_add_i32 s84, s59, s48
	global_load_lds_dwordx4 v[166:167], off
	v_lshl_add_u64 v[212:213], s[4:5], 0, v[148:149]
	s_mov_b32 m0, s84
	v_lshl_add_u64 v[214:215], s[46:47], 0, v[150:151]
	global_load_lds_dwordx4 v[212:213], off
	v_lshl_add_u64 v[212:213], s[4:5], 0, v[152:153]
	s_add_i32 m0, s84, 0x2000
	s_nop 0
	global_load_lds_dwordx4 v[212:213], off
	v_lshl_add_u64 v[212:213], s[46:47], 0, v[146:147]
	s_mov_b32 m0, s49
	s_nop 0
	global_load_lds_dwordx4 v[212:213], off
	s_mov_b32 m0, s50
	s_nop 0
	global_load_lds_dwordx4 v[214:215], off
	s_waitcnt vmcnt(8)
	s_waitcnt lgkmcnt(0)
	s_barrier
	s_setprio 1
	v_mfma_f32_16x16x32_bf16 v[92:95], v[128:131], v[180:183], v[92:95]
	v_mfma_f32_16x16x32_bf16 v[88:91], v[136:139], v[180:183], v[88:91]
	v_mfma_f32_16x16x32_bf16 v[84:87], v[128:131], v[188:191], v[84:87]
	v_mfma_f32_16x16x32_bf16 v[80:83], v[136:139], v[188:191], v[80:83]
	v_mfma_f32_16x16x32_bf16 v[76:79], v[128:131], v[196:199], v[76:79]
	v_mfma_f32_16x16x32_bf16 v[72:75], v[136:139], v[196:199], v[72:75]
	v_mfma_f32_16x16x32_bf16 v[68:71], v[128:131], v[204:207], v[68:71]
	v_mfma_f32_16x16x32_bf16 v[64:67], v[136:139], v[204:207], v[64:67]
	v_mfma_f32_16x16x32_bf16 v[92:95], v[132:135], v[184:187], v[92:95]
	v_mfma_f32_16x16x32_bf16 v[88:91], v[140:143], v[184:187], v[88:91]
	v_mfma_f32_16x16x32_bf16 v[84:87], v[132:135], v[192:195], v[84:87]
	v_mfma_f32_16x16x32_bf16 v[80:83], v[140:143], v[192:195], v[80:83]
	v_mfma_f32_16x16x32_bf16 v[76:79], v[132:135], v[200:203], v[76:79]
	v_mfma_f32_16x16x32_bf16 v[72:75], v[140:143], v[200:203], v[72:75]
	v_mfma_f32_16x16x32_bf16 v[68:71], v[132:135], v[208:211], v[68:71]
	v_mfma_f32_16x16x32_bf16 v[64:67], v[140:143], v[208:211], v[64:67]
	s_setprio 0
	s_setprio 1
	v_mfma_f32_16x16x32_bf16 v[28:31], v[158:161], v[180:183], v[28:31]
	v_mfma_f32_16x16x32_bf16 v[24:27], v[172:175], v[180:183], v[24:27]
	v_mfma_f32_16x16x32_bf16 v[20:23], v[158:161], v[188:191], v[20:23]
	v_mfma_f32_16x16x32_bf16 v[16:19], v[172:175], v[188:191], v[16:19]
	v_mfma_f32_16x16x32_bf16 v[12:15], v[158:161], v[196:199], v[12:15]
	v_mfma_f32_16x16x32_bf16 v[8:11], v[172:175], v[196:199], v[8:11]
	v_mfma_f32_16x16x32_bf16 v[4:7], v[158:161], v[204:207], v[4:7]
	v_mfma_f32_16x16x32_bf16 v[0:3], v[172:175], v[204:207], v[0:3]
	v_mfma_f32_16x16x32_bf16 v[28:31], v[162:165], v[184:187], v[28:31]
	v_mfma_f32_16x16x32_bf16 v[24:27], v[176:179], v[184:187], v[24:27]
	v_mfma_f32_16x16x32_bf16 v[20:23], v[162:165], v[192:195], v[20:23]
	v_mfma_f32_16x16x32_bf16 v[16:19], v[176:179], v[192:195], v[16:19]
	v_mfma_f32_16x16x32_bf16 v[12:15], v[162:165], v[200:203], v[12:15]
	v_mfma_f32_16x16x32_bf16 v[8:11], v[176:179], v[200:203], v[8:11]
	v_mfma_f32_16x16x32_bf16 v[4:7], v[162:165], v[208:211], v[4:7]
	v_mfma_f32_16x16x32_bf16 v[0:3], v[176:179], v[208:211], v[0:3]
	s_setprio 0
	s_barrier
; #define G_STAGE(bufoff, gbase, voff) do { _Pragma("unroll") for (int _i = 0; _i < 2; ++_i) \
;         __builtin_amdgcn_global_load_lds((const unsigned*)((const char*)(gbase) + voff[_i]), (LAS unsigned*)(lds + (bufoff) + ldsw + _i * 8192), 16, 0, 0); } while (0)
; #define G_LDA(dst, b, h) do { _Pragma("unroll") for (int m = 0; m < 4; ++m) _Pragma("unroll") for (int k = 0; k < 2; ++k) dst[m][k] = *(const LAS bf16x8*)(lds + G_SA(b, h) + aoff + m * 2048 + k * 1024); } while (0)
; #define G_LDB(dst, b, h) do { _Pragma("unroll") for (int n = 0; n < 2; ++n) _Pragma("unroll") for (int k = 0; k < 2; ++k) dst[n][k] = *(const LAS bf16x8*)(lds + G_SB(b, h) + boff + n * 2048 + k * 1024); } while (0)
; #define G_MMA(ai, bj, At_, Bt_) do { __builtin_amdgcn_s_setprio(1); _Pragma("unroll") for (int m = 0; m < 4; ++m) _Pragma("unroll") for (int n = 0; n < 2; ++n) _Pragma("unroll") for (int k = 0; k < 2; ++k) \
;         acc[ai][bj][m][n] = __builtin_amdgcn_mfma_f32_16x16x32_bf16(Bt_[n][k], At_[m][k], acc[ai][bj][m][n], 0, 0, 0); __builtin_amdgcn_s_setprio(0); } while (0)
; #define WAIT_V(n) asm volatile("s_waitcnt vmcnt(" #n ")" ::: "memory")
; #define WAIT_L(n) asm volatile("s_waitcnt lgkmcnt(" #n ")" ::: "memory")
; #define BAR __builtin_amdgcn_s_barrier()
; #define SCHED __builtin_amdgcn_sched_barrier(0)
; template <class Get, class Epi>
; DI void gemm_loop(int ntiles, int ld, char* shm, const Get& get, const Epi& epi) {
;     ...
;             G_LDB(B0, 1, 0); G_LDB(B1, 1, 1); SCHED; G_LDA(At, 1, 0); G_STAGE(G_SA(0, 1), a2 + hstep, voffA);
;             WAIT_V(8); WAIT_L(0); BAR; G_MMA(0, 0, At, B0); G_MMA(0, 1, At, B1); BAR; SCHED;
	s_add_i32 s84, 0, 0x18000
	s_add_i32 s85, 0, 0x1c000
	v_add_u32_e32 v140, s84, v168
	v_add_u32_e32 v176, s85, v168
	ds_read_b128 v[128:131], v140
	ds_read_b128 v[132:135], v140 offset:1024
	ds_read_b128 v[136:139], v140 offset:2048
	ds_read_b128 v[140:143], v140 offset:3072
	ds_read_b128 v[158:161], v176
	ds_read_b128 v[162:165], v176 offset:1024
	ds_read_b128 v[172:175], v176 offset:2048
	ds_read_b128 v[176:179], v176 offset:3072
	s_add_u32 s4, s46, 0xb0000
	s_addc_u32 s5, s47, 0
	s_mov_b32 m0, s51
	v_lshl_add_u64 v[216:217], s[4:5], 0, v[146:147]
	ds_read_b128 v[180:183], v171 offset:32768
	ds_read_b128 v[184:187], v171 offset:33792
	ds_read_b128 v[188:191], v171 offset:34816
	ds_read_b128 v[192:195], v171 offset:35840
	ds_read_b128 v[196:199], v171 offset:36864
	ds_read_b128 v[200:203], v171 offset:37888
	ds_read_b128 v[204:207], v171 offset:38912
	ds_read_b128 v[208:211], v171 offset:39936
	global_load_lds_dwordx4 v[216:217], off
	v_lshl_add_u64 v[216:217], s[4:5], 0, v[150:151]
	s_mov_b32 m0, s52
	s_nop 0
	global_load_lds_dwordx4 v[216:217], off
	s_waitcnt vmcnt(8)
	s_waitcnt lgkmcnt(0)
	s_barrier
	s_setprio 1
	v_mfma_f32_16x16x32_bf16 v[124:127], v[128:131], v[180:183], v[124:127]
	v_mfma_f32_16x16x32_bf16 v[120:123], v[136:139], v[180:183], v[120:123]
	v_mfma_f32_16x16x32_bf16 v[116:119], v[128:131], v[188:191], v[116:119]
	v_mfma_f32_16x16x32_bf16 v[112:115], v[136:139], v[188:191], v[112:115]
	v_mfma_f32_16x16x32_bf16 v[108:111], v[128:131], v[196:199], v[108:111]
	v_mfma_f32_16x16x32_bf16 v[104:107], v[136:139], v[196:199], v[104:107]
	v_mfma_f32_16x16x32_bf16 v[100:103], v[128:131], v[204:207], v[100:103]
	v_mfma_f32_16x16x32_bf16 v[96:99], v[136:139], v[204:207], v[96:99]
	v_mfma_f32_16x16x32_bf16 v[124:127], v[132:135], v[184:187], v[124:127]
	v_mfma_f32_16x16x32_bf16 v[120:123], v[140:143], v[184:187], v[120:123]
	v_mfma_f32_16x16x32_bf16 v[116:119], v[132:135], v[192:195], v[116:119]
	v_mfma_f32_16x16x32_bf16 v[112:115], v[140:143], v[192:195], v[112:115]
	v_mfma_f32_16x16x32_bf16 v[108:111], v[132:135], v[200:203], v[108:111]
	v_mfma_f32_16x16x32_bf16 v[104:107], v[140:143], v[200:203], v[104:107]
	v_mfma_f32_16x16x32_bf16 v[100:103], v[132:135], v[208:211], v[100:103]
	v_mfma_f32_16x16x32_bf16 v[96:99], v[140:143], v[208:211], v[96:99]
	s_setprio 0
	s_setprio 1
	v_mfma_f32_16x16x32_bf16 v[60:63], v[158:161], v[180:183], v[60:63]
	v_mfma_f32_16x16x32_bf16 v[56:59], v[172:175], v[180:183], v[56:59]
	v_mfma_f32_16x16x32_bf16 v[52:55], v[158:161], v[188:191], v[52:55]
	v_mfma_f32_16x16x32_bf16 v[48:51], v[172:175], v[188:191], v[48:51]
	v_mfma_f32_16x16x32_bf16 v[44:47], v[158:161], v[196:199], v[44:47]
	v_mfma_f32_16x16x32_bf16 v[40:43], v[172:175], v[196:199], v[40:43]
	v_mfma_f32_16x16x32_bf16 v[36:39], v[158:161], v[204:207], v[36:39]
	v_mfma_f32_16x16x32_bf16 v[32:35], v[172:175], v[204:207], v[32:35]
	v_mfma_f32_16x16x32_bf16 v[60:63], v[162:165], v[184:187], v[60:63]
	v_mfma_f32_16x16x32_bf16 v[56:59], v[176:179], v[184:187], v[56:59]
	v_mfma_f32_16x16x32_bf16 v[52:55], v[162:165], v[192:195], v[52:55]
	v_mfma_f32_16x16x32_bf16 v[48:51], v[176:179], v[192:195], v[48:51]
	v_mfma_f32_16x16x32_bf16 v[44:47], v[162:165], v[200:203], v[44:47]
	v_mfma_f32_16x16x32_bf16 v[40:43], v[176:179], v[200:203], v[40:43]
	v_mfma_f32_16x16x32_bf16 v[36:39], v[162:165], v[208:211], v[36:39]
	v_mfma_f32_16x16x32_bf16 v[32:35], v[176:179], v[208:211], v[32:35]
	s_setprio 0
	s_barrier
; #define G_STAGE(bufoff, gbase, voff) do { _Pragma("unroll") for (int _i = 0; _i < 2; ++_i) \
;         __builtin_amdgcn_global_load_lds((const unsigned*)((const char*)(gbase) + voff[_i]), (LAS unsigned*)(lds + (bufoff) + ldsw + _i * 8192), 16, 0, 0); } while (0)
; #define G_LDA(dst, b, h) do { _Pragma("unroll") for (int m = 0; m < 4; ++m) _Pragma("unroll") for (int k = 0; k < 2; ++k) dst[m][k] = *(const LAS bf16x8*)(lds + G_SA(b, h) + aoff + m * 2048 + k * 1024); } while (0)
; #define G_MMA(ai, bj, At_, Bt_) do { __builtin_amdgcn_s_setprio(1); _Pragma("unroll") for (int m = 0; m < 4; ++m) _Pragma("unroll") for (int n = 0; n < 2; ++n) _Pragma("unroll") for (int k = 0; k < 2; ++k) \
;         acc[ai][bj][m][n] = __builtin_amdgcn_mfma_f32_16x16x32_bf16(Bt_[n][k], At_[m][k], acc[ai][bj][m][n], 0, 0, 0); __builtin_amdgcn_s_setprio(0); } while (0)
; #define WAIT_V(n) asm volatile("s_waitcnt vmcnt(" #n ")" ::: "memory")
; #define WAIT_L(n) asm volatile("s_waitcnt lgkmcnt(" #n ")" ::: "memory")
; #define BAR __builtin_amdgcn_s_barrier()
; #define SCHED __builtin_amdgcn_sched_barrier(0)
; template <class Get, class Epi>
; DI void gemm_loop(int ntiles, int ld, char* shm, const Get& get, const Epi& epi) {
;     ...
;             G_LDA(At, 1, 1); G_STAGE(G_SB(1, 0), b3, voffB); G_STAGE(G_SB(1, 1), b3 + hstep, voffB); G_STAGE(G_SA(1, 0), a3, voffA);
;             WAIT_V(8); WAIT_L(0); BAR; G_MMA(1, 0, At, B0); G_MMA(1, 1, At, B1); BAR; SCHED;
;         }
	s_add_i32 s4, s84, s48
	v_lshl_add_u64 v[144:145], v[144:145], 0, s[10:11]
	s_mov_b32 m0, s4
	ds_read_b128 v[180:183], v171 offset:49152
	ds_read_b128 v[184:187], v171 offset:50176
	ds_read_b128 v[188:191], v171 offset:51200
	ds_read_b128 v[192:195], v171 offset:52224
	ds_read_b128 v[196:199], v171 offset:53248
	ds_read_b128 v[200:203], v171 offset:54272
	ds_read_b128 v[204:207], v171 offset:55296
	ds_read_b128 v[208:211], v171 offset:56320
	global_load_lds_dwordx4 v[144:145], off
	s_add_i32 m0, s4, 0x2000
	s_add_u32 s4, s44, 0xb0080
	v_lshl_add_u64 v[144:145], v[166:167], 0, s[10:11]
	s_addc_u32 s5, s45, 0
	s_add_i32 s44, s85, s48
	global_load_lds_dwordx4 v[144:145], off
	v_lshl_add_u64 v[144:145], s[4:5], 0, v[148:149]
	s_mov_b32 m0, s44
	s_nop 0
	global_load_lds_dwordx4 v[144:145], off
	v_lshl_add_u64 v[144:145], s[4:5], 0, v[152:153]
	s_add_i32 m0, s44, 0x2000
	s_nop 0
	global_load_lds_dwordx4 v[144:145], off
	v_lshl_add_u64 v[144:145], v[212:213], 0, s[10:11]
	s_mov_b32 m0, s55
	s_nop 0
	global_load_lds_dwordx4 v[144:145], off
	v_lshl_add_u64 v[144:145], v[214:215], 0, s[10:11]
	s_mov_b32 m0, s56
	s_nop 0
	global_load_lds_dwordx4 v[144:145], off
	s_waitcnt vmcnt(8)
	s_waitcnt lgkmcnt(0)
	s_barrier
	s_setprio 1
	v_mfma_f32_16x16x32_bf16 v[92:95], v[128:131], v[180:183], v[92:95]
	v_mfma_f32_16x16x32_bf16 v[88:91], v[136:139], v[180:183], v[88:91]
	v_mfma_f32_16x16x32_bf16 v[84:87], v[128:131], v[188:191], v[84:87]
	v_mfma_f32_16x16x32_bf16 v[80:83], v[136:139], v[188:191], v[80:83]
	v_mfma_f32_16x16x32_bf16 v[76:79], v[128:131], v[196:199], v[76:79]
	v_mfma_f32_16x16x32_bf16 v[72:75], v[136:139], v[196:199], v[72:75]
	v_mfma_f32_16x16x32_bf16 v[68:71], v[128:131], v[204:207], v[68:71]
	v_mfma_f32_16x16x32_bf16 v[64:67], v[136:139], v[204:207], v[64:67]
	v_mfma_f32_16x16x32_bf16 v[92:95], v[132:135], v[184:187], v[92:95]
	v_mfma_f32_16x16x32_bf16 v[88:91], v[140:143], v[184:187], v[88:91]
	v_mfma_f32_16x16x32_bf16 v[84:87], v[132:135], v[192:195], v[84:87]
	v_mfma_f32_16x16x32_bf16 v[80:83], v[140:143], v[192:195], v[80:83]
	v_mfma_f32_16x16x32_bf16 v[76:79], v[132:135], v[200:203], v[76:79]
	v_mfma_f32_16x16x32_bf16 v[72:75], v[140:143], v[200:203], v[72:75]
	v_mfma_f32_16x16x32_bf16 v[68:71], v[132:135], v[208:211], v[68:71]
	v_mfma_f32_16x16x32_bf16 v[64:67], v[140:143], v[208:211], v[64:67]
	s_setprio 0
	s_setprio 1
	v_mfma_f32_16x16x32_bf16 v[28:31], v[158:161], v[180:183], v[28:31]
	v_mfma_f32_16x16x32_bf16 v[24:27], v[172:175], v[180:183], v[24:27]
	v_mfma_f32_16x16x32_bf16 v[20:23], v[158:161], v[188:191], v[20:23]
	v_mfma_f32_16x16x32_bf16 v[16:19], v[172:175], v[188:191], v[16:19]
	v_mfma_f32_16x16x32_bf16 v[12:15], v[158:161], v[196:199], v[12:15]
	v_mfma_f32_16x16x32_bf16 v[8:11], v[172:175], v[196:199], v[8:11]
	v_mfma_f32_16x16x32_bf16 v[4:7], v[158:161], v[204:207], v[4:7]
	v_mfma_f32_16x16x32_bf16 v[0:3], v[172:175], v[204:207], v[0:3]
	v_mfma_f32_16x16x32_bf16 v[28:31], v[162:165], v[184:187], v[28:31]
	v_mfma_f32_16x16x32_bf16 v[24:27], v[176:179], v[184:187], v[24:27]
	v_mfma_f32_16x16x32_bf16 v[20:23], v[162:165], v[192:195], v[20:23]
	v_mfma_f32_16x16x32_bf16 v[16:19], v[176:179], v[192:195], v[16:19]
	v_mfma_f32_16x16x32_bf16 v[12:15], v[162:165], v[200:203], v[12:15]
	v_mfma_f32_16x16x32_bf16 v[8:11], v[176:179], v[200:203], v[8:11]
	v_mfma_f32_16x16x32_bf16 v[4:7], v[162:165], v[208:211], v[4:7]
	v_mfma_f32_16x16x32_bf16 v[0:3], v[176:179], v[208:211], v[0:3]
	s_setprio 0
	s_barrier
	s_add_u32 s81, s81, 0x100
	s_addc_u32 s82, s82, 0
	s_cmp_ge_u32 s83, s79
	s_mov_b64 s[4:5], s[14:15]
	s_mov_b32 s44, s83
	s_cbranch_scc0 .LBB0_2892

; #define G_STAGE(bufoff, gbase, voff) do { _Pragma("unroll") for (int _i = 0; _i < 2; ++_i) \
;         __builtin_amdgcn_global_load_lds((const unsigned*)((const char*)(gbase) + voff[_i]), (LAS unsigned*)(lds + (bufoff) + ldsw + _i * 8192), 16, 0, 0); } while (0)
; #define G_LDA(dst, b, h) do { _Pragma("unroll") for (int m = 0; m < 4; ++m) _Pragma("unroll") for (int k = 0; k < 2; ++k) dst[m][k] = *(const LAS bf16x8*)(lds + G_SA(b, h) + aoff + m * 2048 + k * 1024); } while (0)
; #define G_MMA(ai, bj, At_, Bt_) do { __builtin_amdgcn_s_setprio(1); _Pragma("unroll") for (int m = 0; m < 4; ++m) _Pragma("unroll") for (int n = 0; n < 2; ++n) _Pragma("unroll") for (int k = 0; k < 2; ++k) \
;         acc[ai][bj][m][n] = __builtin_amdgcn_mfma_f32_16x16x32_bf16(Bt_[n][k], At_[m][k], acc[ai][bj][m][n], 0, 0, 0); __builtin_amdgcn_s_setprio(0); } while (0)
; #define WAIT_V(n) asm volatile("s_waitcnt vmcnt(" #n ")" ::: "memory")
; #define WAIT_L(n) asm volatile("s_waitcnt lgkmcnt(" #n ")" ::: "memory")
; #define BAR __builtin_amdgcn_s_barrier()
; #define SCHED __builtin_amdgcn_sched_barrier(0)
; template <class Get, class Epi>
; DI void gemm_loop(int ntiles, int ld, char* shm, const Get& get, const Epi& epi) {
;     ...
;             WAIT_V(8); WAIT_L(0); BAR; G_MMA(0, 0, At, B0); G_MMA(0, 1, At, B1); BAR; SCHED;
;             G_LDA(At, 0, 1); G_STAGE(G_SB(0, 0), b2, voffB); G_STAGE(G_SB(0, 1), b2 + hstep, voffB); G_STAGE(G_SA(0, 0), a2, voffA);
.Lrj_3141_0:
	s_waitcnt lgkmcnt(0)
	s_barrier
	s_setprio 1
	v_mfma_f32_16x16x32_bf16 v[124:127], v[144:147], v[176:179], 0
	v_mfma_f32_16x16x32_bf16 v[120:123], v[152:155], v[176:179], 0
	v_mfma_f32_16x16x32_bf16 v[116:119], v[144:147], v[184:187], 0
	v_mfma_f32_16x16x32_bf16 v[112:115], v[152:155], v[184:187], 0
	v_mfma_f32_16x16x32_bf16 v[100:103], v[144:147], v[192:195], 0
	v_mfma_f32_16x16x32_bf16 v[96:99], v[152:155], v[192:195], 0
	v_mfma_f32_16x16x32_bf16 v[84:87], v[144:147], v[200:203], 0
	v_mfma_f32_16x16x32_bf16 v[80:83], v[152:155], v[200:203], 0
	v_mfma_f32_16x16x32_bf16 v[124:127], v[148:151], v[180:183], v[124:127]
	v_mfma_f32_16x16x32_bf16 v[120:123], v[156:159], v[180:183], v[120:123]
	v_mfma_f32_16x16x32_bf16 v[116:119], v[148:151], v[188:191], v[116:119]
	v_mfma_f32_16x16x32_bf16 v[112:115], v[156:159], v[188:191], v[112:115]
	v_mfma_f32_16x16x32_bf16 v[100:103], v[148:151], v[196:199], v[100:103]
	v_mfma_f32_16x16x32_bf16 v[96:99], v[156:159], v[196:199], v[96:99]
	v_mfma_f32_16x16x32_bf16 v[84:87], v[148:151], v[204:207], v[84:87]
	v_mfma_f32_16x16x32_bf16 v[80:83], v[156:159], v[204:207], v[80:83]
	s_setprio 0
	s_setprio 1
	v_mfma_f32_16x16x32_bf16 v[108:111], v[160:163], v[176:179], 0
	v_mfma_f32_16x16x32_bf16 v[104:107], v[168:171], v[176:179], 0
	v_mfma_f32_16x16x32_bf16 v[92:95], v[160:163], v[184:187], 0
	v_mfma_f32_16x16x32_bf16 v[88:91], v[168:171], v[184:187], 0
	v_mfma_f32_16x16x32_bf16 v[76:79], v[160:163], v[192:195], 0
	v_mfma_f32_16x16x32_bf16 v[72:75], v[168:171], v[192:195], 0
	v_mfma_f32_16x16x32_bf16 v[68:71], v[160:163], v[200:203], 0
	v_mfma_f32_16x16x32_bf16 v[64:67], v[168:171], v[200:203], 0
	v_mfma_f32_16x16x32_bf16 v[108:111], v[164:167], v[180:183], v[108:111]
	v_mfma_f32_16x16x32_bf16 v[104:107], v[172:175], v[180:183], v[104:107]
	v_mfma_f32_16x16x32_bf16 v[92:95], v[164:167], v[188:191], v[92:95]
	v_mfma_f32_16x16x32_bf16 v[88:91], v[172:175], v[188:191], v[88:91]
	v_mfma_f32_16x16x32_bf16 v[76:79], v[164:167], v[196:199], v[76:79]
	v_mfma_f32_16x16x32_bf16 v[72:75], v[172:175], v[196:199], v[72:75]
	v_mfma_f32_16x16x32_bf16 v[68:71], v[164:167], v[204:207], v[68:71]
	v_mfma_f32_16x16x32_bf16 v[64:67], v[172:175], v[204:207], v[64:67]
	s_setprio 0
	s_barrier
	s_add_i32 s71, s57, s50
	v_lshl_add_u64 v[208:209], s[14:15], 0, v[130:131]
	s_mov_b32 m0, s71
	ds_read_b128 v[176:179], v143 offset:16384
	ds_read_b128 v[180:183], v143 offset:17408
	ds_read_b128 v[184:187], v143 offset:18432
	ds_read_b128 v[188:191], v143 offset:19456
	ds_read_b128 v[192:195], v143 offset:20480
	ds_read_b128 v[196:199], v143 offset:21504
	ds_read_b128 v[200:203], v143 offset:22528
	ds_read_b128 v[204:207], v143 offset:23552
	global_load_lds_dwordx4 v[208:209], off
	s_add_i32 m0, s71, 0x2000
	s_add_u32 s72, s14, 0x40000
	v_lshl_add_u64 v[210:211], s[14:15], 0, v[134:135]
	s_addc_u32 s73, s15, 0
	s_add_i32 s71, s58, s50
	global_load_lds_dwordx4 v[210:211], off
	v_lshl_add_u64 v[212:213], s[72:73], 0, v[130:131]
	s_mov_b32 m0, s71
	v_lshl_add_u64 v[214:215], s[46:47], 0, v[132:133]
	global_load_lds_dwordx4 v[212:213], off
	v_lshl_add_u64 v[212:213], s[72:73], 0, v[134:135]
	s_add_i32 m0, s71, 0x2000
	s_nop 0
	global_load_lds_dwordx4 v[212:213], off
	v_lshl_add_u64 v[212:213], s[46:47], 0, v[128:129]
	s_mov_b32 m0, s35
	s_nop 0
	global_load_lds_dwordx4 v[212:213], off
	s_mov_b32 m0, s51
	s_nop 0
	global_load_lds_dwordx4 v[214:215], off
	s_cmp_lg_u32 s100, 0
	s_cbranch_scc0 .Lrf_3141_1
	s_waitcnt vmcnt(16)
	s_branch .Lrj_3141_1

; #define G_STAGE(bufoff, gbase, voff) do { _Pragma("unroll") for (int _i = 0; _i < 2; ++_i) \
;         __builtin_amdgcn_global_load_lds((const unsigned*)((const char*)(gbase) + voff[_i]), (LAS unsigned*)(lds + (bufoff) + ldsw + _i * 8192), 16, 0, 0); } while (0)
; #define G_LDA(dst, b, h) do { _Pragma("unroll") for (int m = 0; m < 4; ++m) _Pragma("unroll") for (int k = 0; k < 2; ++k) dst[m][k] = *(const LAS bf16x8*)(lds + G_SA(b, h) + aoff + m * 2048 + k * 1024); } while (0)
; #define G_LDB(dst, b, h) do { _Pragma("unroll") for (int n = 0; n < 2; ++n) _Pragma("unroll") for (int k = 0; k < 2; ++k) dst[n][k] = *(const LAS bf16x8*)(lds + G_SB(b, h) + boff + n * 2048 + k * 1024); } while (0)
; #define G_MMA(ai, bj, At_, Bt_) do { __builtin_amdgcn_s_setprio(1); _Pragma("unroll") for (int m = 0; m < 4; ++m) _Pragma("unroll") for (int n = 0; n < 2; ++n) _Pragma("unroll") for (int k = 0; k < 2; ++k) \
;         acc[ai][bj][m][n] = __builtin_amdgcn_mfma_f32_16x16x32_bf16(Bt_[n][k], At_[m][k], acc[ai][bj][m][n], 0, 0, 0); __builtin_amdgcn_s_setprio(0); } while (0)
; #define WAIT_V(n) asm volatile("s_waitcnt vmcnt(" #n ")" ::: "memory")
; #define WAIT_L(n) asm volatile("s_waitcnt lgkmcnt(" #n ")" ::: "memory")
; #define BAR __builtin_amdgcn_s_barrier()
; #define SCHED __builtin_amdgcn_sched_barrier(0)
; template <class Get, class Epi>
; DI void gemm_loop(int ntiles, int ld, char* shm, const Get& get, const Epi& epi) {
;     ...
;             WAIT_V(8); WAIT_L(0); BAR; G_MMA(1, 0, At, B0); G_MMA(1, 1, At, B1); BAR; SCHED;
;             G_LDB(B0, 1, 0); G_LDB(B1, 1, 1); SCHED; G_LDA(At, 1, 0); G_STAGE(G_SA(0, 1), a2 + hstep, voffA);
;             WAIT_V(8); WAIT_L(0); BAR; G_MMA(0, 0, At, B0); G_MMA(0, 1, At, B1); BAR; SCHED;
.Lrj_3141_1:
	s_waitcnt lgkmcnt(0)
	s_barrier
	s_setprio 1
	v_mfma_f32_16x16x32_bf16 v[60:63], v[144:147], v[176:179], 0
	v_mfma_f32_16x16x32_bf16 v[56:59], v[152:155], v[176:179], 0
	v_mfma_f32_16x16x32_bf16 v[52:55], v[144:147], v[184:187], 0
	v_mfma_f32_16x16x32_bf16 v[48:51], v[152:155], v[184:187], 0
	v_mfma_f32_16x16x32_bf16 v[36:39], v[144:147], v[192:195], 0
	v_mfma_f32_16x16x32_bf16 v[32:35], v[152:155], v[192:195], 0
	v_mfma_f32_16x16x32_bf16 v[20:23], v[144:147], v[200:203], 0
	v_mfma_f32_16x16x32_bf16 v[16:19], v[152:155], v[200:203], 0
	v_mfma_f32_16x16x32_bf16 v[60:63], v[148:151], v[180:183], v[60:63]
	v_mfma_f32_16x16x32_bf16 v[56:59], v[156:159], v[180:183], v[56:59]
	v_mfma_f32_16x16x32_bf16 v[52:55], v[148:151], v[188:191], v[52:55]
	v_mfma_f32_16x16x32_bf16 v[48:51], v[156:159], v[188:191], v[48:51]
	v_mfma_f32_16x16x32_bf16 v[36:39], v[148:151], v[196:199], v[36:39]
	v_mfma_f32_16x16x32_bf16 v[32:35], v[156:159], v[196:199], v[32:35]
	v_mfma_f32_16x16x32_bf16 v[20:23], v[148:151], v[204:207], v[20:23]
	v_mfma_f32_16x16x32_bf16 v[16:19], v[156:159], v[204:207], v[16:19]
	s_setprio 0
	s_setprio 1
	v_mfma_f32_16x16x32_bf16 v[44:47], v[160:163], v[176:179], 0
	v_mfma_f32_16x16x32_bf16 v[40:43], v[168:171], v[176:179], 0
	v_mfma_f32_16x16x32_bf16 v[28:31], v[160:163], v[184:187], 0
	v_mfma_f32_16x16x32_bf16 v[24:27], v[168:171], v[184:187], 0
	v_mfma_f32_16x16x32_bf16 v[12:15], v[160:163], v[192:195], 0
	v_mfma_f32_16x16x32_bf16 v[8:11], v[168:171], v[192:195], 0
	v_mfma_f32_16x16x32_bf16 v[4:7], v[160:163], v[200:203], 0
	v_mfma_f32_16x16x32_bf16 v[0:3], v[168:171], v[200:203], 0
	v_mfma_f32_16x16x32_bf16 v[44:47], v[164:167], v[180:183], v[44:47]
	v_mfma_f32_16x16x32_bf16 v[40:43], v[172:175], v[180:183], v[40:43]
	v_mfma_f32_16x16x32_bf16 v[28:31], v[164:167], v[188:191], v[28:31]
	v_mfma_f32_16x16x32_bf16 v[24:27], v[172:175], v[188:191], v[24:27]
	v_mfma_f32_16x16x32_bf16 v[12:15], v[164:167], v[196:199], v[12:15]
	v_mfma_f32_16x16x32_bf16 v[8:11], v[172:175], v[196:199], v[8:11]
	v_mfma_f32_16x16x32_bf16 v[4:7], v[164:167], v[204:207], v[4:7]
	v_mfma_f32_16x16x32_bf16 v[0:3], v[172:175], v[204:207], v[0:3]
	s_setprio 0
	s_barrier
	s_add_i32 s71, 0, 0x18000
	s_add_i32 s72, 0, 0x1c000
	v_add_u32_e32 v156, s71, v140
	v_add_u32_e32 v172, s72, v140
	ds_read_b128 v[144:147], v156
	ds_read_b128 v[148:151], v156 offset:1024
	ds_read_b128 v[152:155], v156 offset:2048
	ds_read_b128 v[156:159], v156 offset:3072
	ds_read_b128 v[160:163], v172
	ds_read_b128 v[164:167], v172 offset:1024
	ds_read_b128 v[168:171], v172 offset:2048
	ds_read_b128 v[172:175], v172 offset:3072
	s_add_u32 s46, s46, 0x40000
	s_addc_u32 s47, s47, 0
	s_mov_b32 m0, s52
	v_lshl_add_u64 v[216:217], s[46:47], 0, v[128:129]
	ds_read_b128 v[176:179], v143 offset:32768
	ds_read_b128 v[180:183], v143 offset:33792
	ds_read_b128 v[184:187], v143 offset:34816
	ds_read_b128 v[188:191], v143 offset:35840
	ds_read_b128 v[192:195], v143 offset:36864
	ds_read_b128 v[196:199], v143 offset:37888
	ds_read_b128 v[200:203], v143 offset:38912
	ds_read_b128 v[204:207], v143 offset:39936
	global_load_lds_dwordx4 v[216:217], off
	v_lshl_add_u64 v[216:217], s[46:47], 0, v[132:133]
	s_mov_b32 m0, s53
	s_nop 0
	global_load_lds_dwordx4 v[216:217], off
	s_waitcnt vmcnt(8)
	s_waitcnt lgkmcnt(0)
	s_barrier
	s_setprio 1
	v_mfma_f32_16x16x32_bf16 v[124:127], v[144:147], v[176:179], v[124:127]
	v_mfma_f32_16x16x32_bf16 v[120:123], v[152:155], v[176:179], v[120:123]
	v_mfma_f32_16x16x32_bf16 v[116:119], v[144:147], v[184:187], v[116:119]
	v_mfma_f32_16x16x32_bf16 v[112:115], v[152:155], v[184:187], v[112:115]
	v_mfma_f32_16x16x32_bf16 v[100:103], v[144:147], v[192:195], v[100:103]
	v_mfma_f32_16x16x32_bf16 v[96:99], v[152:155], v[192:195], v[96:99]
	v_mfma_f32_16x16x32_bf16 v[84:87], v[144:147], v[200:203], v[84:87]
	v_mfma_f32_16x16x32_bf16 v[80:83], v[152:155], v[200:203], v[80:83]
	v_mfma_f32_16x16x32_bf16 v[124:127], v[148:151], v[180:183], v[124:127]
	v_mfma_f32_16x16x32_bf16 v[120:123], v[156:159], v[180:183], v[120:123]
	v_mfma_f32_16x16x32_bf16 v[116:119], v[148:151], v[188:191], v[116:119]
	v_mfma_f32_16x16x32_bf16 v[112:115], v[156:159], v[188:191], v[112:115]
	v_mfma_f32_16x16x32_bf16 v[100:103], v[148:151], v[196:199], v[100:103]
	v_mfma_f32_16x16x32_bf16 v[96:99], v[156:159], v[196:199], v[96:99]
	v_mfma_f32_16x16x32_bf16 v[84:87], v[148:151], v[204:207], v[84:87]
	v_mfma_f32_16x16x32_bf16 v[80:83], v[156:159], v[204:207], v[80:83]
	s_setprio 0
	s_setprio 1
	v_mfma_f32_16x16x32_bf16 v[108:111], v[160:163], v[176:179], v[108:111]
	v_mfma_f32_16x16x32_bf16 v[104:107], v[168:171], v[176:179], v[104:107]
	v_mfma_f32_16x16x32_bf16 v[92:95], v[160:163], v[184:187], v[92:95]
	v_mfma_f32_16x16x32_bf16 v[88:91], v[168:171], v[184:187], v[88:91]
	v_mfma_f32_16x16x32_bf16 v[76:79], v[160:163], v[192:195], v[76:79]
	v_mfma_f32_16x16x32_bf16 v[72:75], v[168:171], v[192:195], v[72:75]
	v_mfma_f32_16x16x32_bf16 v[68:71], v[160:163], v[200:203], v[68:71]
	v_mfma_f32_16x16x32_bf16 v[64:67], v[168:171], v[200:203], v[64:67]
	v_mfma_f32_16x16x32_bf16 v[108:111], v[164:167], v[180:183], v[108:111]
	v_mfma_f32_16x16x32_bf16 v[104:107], v[172:175], v[180:183], v[104:107]
	v_mfma_f32_16x16x32_bf16 v[92:95], v[164:167], v[188:191], v[92:95]
	v_mfma_f32_16x16x32_bf16 v[88:91], v[172:175], v[188:191], v[88:91]
	v_mfma_f32_16x16x32_bf16 v[76:79], v[164:167], v[196:199], v[76:79]
	v_mfma_f32_16x16x32_bf16 v[72:75], v[172:175], v[196:199], v[72:75]
	v_mfma_f32_16x16x32_bf16 v[68:71], v[164:167], v[204:207], v[68:71]
	v_mfma_f32_16x16x32_bf16 v[64:67], v[172:175], v[204:207], v[64:67]
	s_setprio 0
	s_barrier
; #define G_STAGE(bufoff, gbase, voff) do { _Pragma("unroll") for (int _i = 0; _i < 2; ++_i) \
;         __builtin_amdgcn_global_load_lds((const unsigned*)((const char*)(gbase) + voff[_i]), (LAS unsigned*)(lds + (bufoff) + ldsw + _i * 8192), 16, 0, 0); } while (0)
; #define G_LDA(dst, b, h) do { _Pragma("unroll") for (int m = 0; m < 4; ++m) _Pragma("unroll") for (int k = 0; k < 2; ++k) dst[m][k] = *(const LAS bf16x8*)(lds + G_SA(b, h) + aoff + m * 2048 + k * 1024); } while (0)
; #define G_LDB(dst, b, h) do { _Pragma("unroll") for (int n = 0; n < 2; ++n) _Pragma("unroll") for (int k = 0; k < 2; ++k) dst[n][k] = *(const LAS bf16x8*)(lds + G_SB(b, h) + boff + n * 2048 + k * 1024); } while (0)
; #define G_MMA(ai, bj, At_, Bt_) do { __builtin_amdgcn_s_setprio(1); _Pragma("unroll") for (int m = 0; m < 4; ++m) _Pragma("unroll") for (int n = 0; n < 2; ++n) _Pragma("unroll") for (int k = 0; k < 2; ++k) \
;         acc[ai][bj][m][n] = __builtin_amdgcn_mfma_f32_16x16x32_bf16(Bt_[n][k], At_[m][k], acc[ai][bj][m][n], 0, 0, 0); __builtin_amdgcn_s_setprio(0); } while (0)
; #define WAIT_V(n) asm volatile("s_waitcnt vmcnt(" #n ")" ::: "memory")
; #define WAIT_L(n) asm volatile("s_waitcnt lgkmcnt(" #n ")" ::: "memory")
; #define BAR __builtin_amdgcn_s_barrier()
; #define SCHED __builtin_amdgcn_sched_barrier(0)
; template <class Get, class Epi>
; DI void gemm_loop(int ntiles, int ld, char* shm, const Get& get, const Epi& epi) {
;     ...
;         for (int t = 0; t < nt; t += 2) {
;             const bool last = (t == nt - 2);
;             const char* a1 = cA + (size_t)(t + 1) * kstep;
;             const char* a2 = last ? nA : cA + (size_t)(t + 2) * kstep; const char* b2 = last ? nB : cB + (size_t)(t + 2) * kstep;
;             const char* a3 = a2 + kstep; const char* b3 = b2 + kstep;
;             G_LDB(B0, 0, 0); G_LDB(B1, 0, 1); SCHED; G_LDA(At, 0, 0); G_STAGE(G_SA(1, 1), a1 + hstep, voffA);
;     ...
;             G_LDA(At, 1, 1); G_STAGE(G_SB(1, 0), b3, voffB); G_STAGE(G_SB(1, 1), b3 + hstep, voffB); G_STAGE(G_SA(1, 0), a3, voffA);
;             WAIT_V(8); WAIT_L(0); BAR; G_MMA(1, 0, At, B0); G_MMA(1, 1, At, B1); BAR; SCHED;
	s_add_i32 s46, s71, s50
	v_lshl_add_u64 v[208:209], v[208:209], 0, s[8:9]
	s_mov_b32 m0, s46
	ds_read_b128 v[176:179], v143 offset:49152
	ds_read_b128 v[180:183], v143 offset:50176
	ds_read_b128 v[184:187], v143 offset:51200
	ds_read_b128 v[188:191], v143 offset:52224
	ds_read_b128 v[192:195], v143 offset:53248
	ds_read_b128 v[196:199], v143 offset:54272
	ds_read_b128 v[200:203], v143 offset:55296
	ds_read_b128 v[204:207], v143 offset:56320
	global_load_lds_dwordx4 v[208:209], off
	s_add_i32 m0, s46, 0x2000
	s_add_u32 s14, s14, 0x40080
	v_lshl_add_u64 v[208:209], v[210:211], 0, s[8:9]
	s_addc_u32 s15, s15, 0
	s_add_i32 s46, s72, s50
	global_load_lds_dwordx4 v[208:209], off
	v_lshl_add_u64 v[208:209], s[14:15], 0, v[130:131]
	s_mov_b32 m0, s46
	s_nop 0
	global_load_lds_dwordx4 v[208:209], off
	v_lshl_add_u64 v[208:209], s[14:15], 0, v[134:135]
	s_add_i32 m0, s46, 0x2000
	s_nop 0
	global_load_lds_dwordx4 v[208:209], off
	v_lshl_add_u64 v[208:209], v[212:213], 0, s[8:9]
	s_mov_b32 m0, s55
	s_nop 0
	global_load_lds_dwordx4 v[208:209], off
	v_lshl_add_u64 v[208:209], v[214:215], 0, s[8:9]
	s_mov_b32 m0, s56
	s_nop 0
	global_load_lds_dwordx4 v[208:209], off
	s_waitcnt vmcnt(8)
	s_waitcnt lgkmcnt(0)
	s_barrier
	s_setprio 1
	v_mfma_f32_16x16x32_bf16 v[60:63], v[144:147], v[176:179], v[60:63]
	v_mfma_f32_16x16x32_bf16 v[56:59], v[152:155], v[176:179], v[56:59]
	v_mfma_f32_16x16x32_bf16 v[52:55], v[144:147], v[184:187], v[52:55]
	v_mfma_f32_16x16x32_bf16 v[48:51], v[152:155], v[184:187], v[48:51]
	v_mfma_f32_16x16x32_bf16 v[36:39], v[144:147], v[192:195], v[36:39]
	v_mfma_f32_16x16x32_bf16 v[32:35], v[152:155], v[192:195], v[32:35]
	v_mfma_f32_16x16x32_bf16 v[20:23], v[144:147], v[200:203], v[20:23]
	v_mfma_f32_16x16x32_bf16 v[16:19], v[152:155], v[200:203], v[16:19]
	v_mfma_f32_16x16x32_bf16 v[60:63], v[148:151], v[180:183], v[60:63]
	v_mfma_f32_16x16x32_bf16 v[56:59], v[156:159], v[180:183], v[56:59]
	v_mfma_f32_16x16x32_bf16 v[52:55], v[148:151], v[188:191], v[52:55]
	v_mfma_f32_16x16x32_bf16 v[48:51], v[156:159], v[188:191], v[48:51]
	v_mfma_f32_16x16x32_bf16 v[36:39], v[148:151], v[196:199], v[36:39]
	v_mfma_f32_16x16x32_bf16 v[32:35], v[156:159], v[196:199], v[32:35]
	v_mfma_f32_16x16x32_bf16 v[20:23], v[148:151], v[204:207], v[20:23]
	v_mfma_f32_16x16x32_bf16 v[16:19], v[156:159], v[204:207], v[16:19]
	s_setprio 0
	s_setprio 1
	v_mfma_f32_16x16x32_bf16 v[44:47], v[160:163], v[176:179], v[44:47]
	v_mfma_f32_16x16x32_bf16 v[40:43], v[168:171], v[176:179], v[40:43]
	v_mfma_f32_16x16x32_bf16 v[28:31], v[160:163], v[184:187], v[28:31]
	v_mfma_f32_16x16x32_bf16 v[24:27], v[168:171], v[184:187], v[24:27]
	v_mfma_f32_16x16x32_bf16 v[12:15], v[160:163], v[192:195], v[12:15]
	v_mfma_f32_16x16x32_bf16 v[8:11], v[168:171], v[192:195], v[8:11]
	v_mfma_f32_16x16x32_bf16 v[4:7], v[160:163], v[200:203], v[4:7]
	v_mfma_f32_16x16x32_bf16 v[0:3], v[168:171], v[200:203], v[0:3]
	v_mfma_f32_16x16x32_bf16 v[44:47], v[164:167], v[180:183], v[44:47]
	v_mfma_f32_16x16x32_bf16 v[40:43], v[172:175], v[180:183], v[40:43]
	v_mfma_f32_16x16x32_bf16 v[28:31], v[164:167], v[188:191], v[28:31]
	v_mfma_f32_16x16x32_bf16 v[24:27], v[172:175], v[188:191], v[24:27]
	v_mfma_f32_16x16x32_bf16 v[12:15], v[164:167], v[196:199], v[12:15]
	v_mfma_f32_16x16x32_bf16 v[8:11], v[172:175], v[196:199], v[8:11]
	v_mfma_f32_16x16x32_bf16 v[4:7], v[164:167], v[204:207], v[4:7]
	v_mfma_f32_16x16x32_bf16 v[0:3], v[172:175], v[204:207], v[0:3]
	s_setprio 0
	s_barrier
	s_add_i32 s70, s70, 2
	s_add_u32 s48, s48, 0x100
	s_addc_u32 s49, s49, 0
	s_add_u32 s64, s64, 0x100
	s_addc_u32 s65, s65, 0
	s_cmp_gt_u32 s70, 13
	s_cbranch_scc0 .LBB0_3141
	s_branch .Lpost_3141
.LBB0_3141:
	ds_read_b128 v[144:147], v141
	ds_read_b128 v[148:151], v141 offset:1024
	ds_read_b128 v[152:155], v141 offset:2048
	ds_read_b128 v[156:159], v141 offset:3072
	ds_read_b128 v[160:163], v142
	ds_read_b128 v[164:167], v142 offset:1024
	ds_read_b128 v[168:171], v142 offset:2048
	ds_read_b128 v[172:175], v142 offset:3072
	s_add_u32 s14, s48, 0xfffc0080
	s_addc_u32 s15, s49, -1
	s_cmp_eq_u32 s70, 12
	s_cselect_b32 s47, s11, s15
	s_cselect_b32 s46, s39, s14
	s_cselect_b32 s15, s41, s65
	s_cselect_b32 s14, s63, s64
	v_lshl_add_u64 v[208:209], s[48:49], 0, v[136:137]
	s_add_i32 m0, s35, 0xc000
	ds_read_b128 v[176:179], v143
	ds_read_b128 v[180:183], v143 offset:1024
	ds_read_b128 v[184:187], v143 offset:2048
	ds_read_b128 v[188:191], v143 offset:3072
	ds_read_b128 v[192:195], v143 offset:4096
	ds_read_b128 v[196:199], v143 offset:5120
	ds_read_b128 v[200:203], v143 offset:6144
	ds_read_b128 v[204:207], v143 offset:7168
	global_load_lds_dwordx4 v[208:209], off
	v_lshl_add_u64 v[208:209], s[48:49], 0, v[138:139]
	s_add_i32 m0, s35, 0xe000
	s_nop 0
	global_load_lds_dwordx4 v[208:209], off
	s_waitcnt vmcnt(8)
	s_waitcnt lgkmcnt(0)
	s_barrier
; #define G_STAGE(bufoff, gbase, voff) do { _Pragma("unroll") for (int _i = 0; _i < 2; ++_i) \
;         __builtin_amdgcn_global_load_lds((const unsigned*)((const char*)(gbase) + voff[_i]), (LAS unsigned*)(lds + (bufoff) + ldsw + _i * 8192), 16, 0, 0); } while (0)
; #define G_LDA(dst, b, h) do { _Pragma("unroll") for (int m = 0; m < 4; ++m) _Pragma("unroll") for (int k = 0; k < 2; ++k) dst[m][k] = *(const LAS bf16x8*)(lds + G_SA(b, h) + aoff + m * 2048 + k * 1024); } while (0)
; #define G_MMA(ai, bj, At_, Bt_) do { __builtin_amdgcn_s_setprio(1); _Pragma("unroll") for (int m = 0; m < 4; ++m) _Pragma("unroll") for (int n = 0; n < 2; ++n) _Pragma("unroll") for (int k = 0; k < 2; ++k) \
;         acc[ai][bj][m][n] = __builtin_amdgcn_mfma_f32_16x16x32_bf16(Bt_[n][k], At_[m][k], acc[ai][bj][m][n], 0, 0, 0); __builtin_amdgcn_s_setprio(0); } while (0)
; #define WAIT_V(n) asm volatile("s_waitcnt vmcnt(" #n ")" ::: "memory")
; #define WAIT_L(n) asm volatile("s_waitcnt lgkmcnt(" #n ")" ::: "memory")
; #define BAR __builtin_amdgcn_s_barrier()
; #define SCHED __builtin_amdgcn_sched_barrier(0)
; template <class Get, class Epi>
; DI void gemm_loop(int ntiles, int ld, char* shm, const Get& get, const Epi& epi) {
;     ...
;             WAIT_V(8); WAIT_L(0); BAR; G_MMA(0, 0, At, B0); G_MMA(0, 1, At, B1); BAR; SCHED;
;             G_LDA(At, 0, 1); G_STAGE(G_SB(0, 0), b2, voffB); G_STAGE(G_SB(0, 1), b2 + hstep, voffB); G_STAGE(G_SA(0, 0), a2, voffA);
;             WAIT_V(8); WAIT_L(0); BAR; G_MMA(1, 0, At, B0); G_MMA(1, 1, At, B1); BAR; SCHED;
	s_setprio 1
	v_mfma_f32_16x16x32_bf16 v[124:127], v[144:147], v[176:179], v[124:127]
	v_mfma_f32_16x16x32_bf16 v[120:123], v[152:155], v[176:179], v[120:123]
	v_mfma_f32_16x16x32_bf16 v[116:119], v[144:147], v[184:187], v[116:119]
	v_mfma_f32_16x16x32_bf16 v[112:115], v[152:155], v[184:187], v[112:115]
	v_mfma_f32_16x16x32_bf16 v[100:103], v[144:147], v[192:195], v[100:103]
	v_mfma_f32_16x16x32_bf16 v[96:99], v[152:155], v[192:195], v[96:99]
	v_mfma_f32_16x16x32_bf16 v[84:87], v[144:147], v[200:203], v[84:87]
	v_mfma_f32_16x16x32_bf16 v[80:83], v[152:155], v[200:203], v[80:83]
	v_mfma_f32_16x16x32_bf16 v[124:127], v[148:151], v[180:183], v[124:127]
	v_mfma_f32_16x16x32_bf16 v[120:123], v[156:159], v[180:183], v[120:123]
	v_mfma_f32_16x16x32_bf16 v[116:119], v[148:151], v[188:191], v[116:119]
	v_mfma_f32_16x16x32_bf16 v[112:115], v[156:159], v[188:191], v[112:115]
	v_mfma_f32_16x16x32_bf16 v[100:103], v[148:151], v[196:199], v[100:103]
	v_mfma_f32_16x16x32_bf16 v[96:99], v[156:159], v[196:199], v[96:99]
	v_mfma_f32_16x16x32_bf16 v[84:87], v[148:151], v[204:207], v[84:87]
	v_mfma_f32_16x16x32_bf16 v[80:83], v[156:159], v[204:207], v[80:83]
	s_setprio 0
	s_setprio 1
	v_mfma_f32_16x16x32_bf16 v[108:111], v[160:163], v[176:179], v[108:111]
	v_mfma_f32_16x16x32_bf16 v[104:107], v[168:171], v[176:179], v[104:107]
	v_mfma_f32_16x16x32_bf16 v[92:95], v[160:163], v[184:187], v[92:95]
	v_mfma_f32_16x16x32_bf16 v[88:91], v[168:171], v[184:187], v[88:91]
	v_mfma_f32_16x16x32_bf16 v[76:79], v[160:163], v[192:195], v[76:79]
	v_mfma_f32_16x16x32_bf16 v[72:75], v[168:171], v[192:195], v[72:75]
	v_mfma_f32_16x16x32_bf16 v[68:71], v[160:163], v[200:203], v[68:71]
	v_mfma_f32_16x16x32_bf16 v[64:67], v[168:171], v[200:203], v[64:67]
	v_mfma_f32_16x16x32_bf16 v[108:111], v[164:167], v[180:183], v[108:111]
	v_mfma_f32_16x16x32_bf16 v[104:107], v[172:175], v[180:183], v[104:107]
	v_mfma_f32_16x16x32_bf16 v[92:95], v[164:167], v[188:191], v[92:95]
	v_mfma_f32_16x16x32_bf16 v[88:91], v[172:175], v[188:191], v[88:91]
	v_mfma_f32_16x16x32_bf16 v[76:79], v[164:167], v[196:199], v[76:79]
	v_mfma_f32_16x16x32_bf16 v[72:75], v[172:175], v[196:199], v[72:75]
	v_mfma_f32_16x16x32_bf16 v[68:71], v[164:167], v[204:207], v[68:71]
	v_mfma_f32_16x16x32_bf16 v[64:67], v[172:175], v[204:207], v[64:67]
	s_setprio 0
	s_barrier
	s_add_i32 s71, s57, s50
	v_lshl_add_u64 v[208:209], s[14:15], 0, v[130:131]
	s_mov_b32 m0, s71
	ds_read_b128 v[176:179], v143 offset:16384
	ds_read_b128 v[180:183], v143 offset:17408
	ds_read_b128 v[184:187], v143 offset:18432
	ds_read_b128 v[188:191], v143 offset:19456
	ds_read_b128 v[192:195], v143 offset:20480
	ds_read_b128 v[196:199], v143 offset:21504
	ds_read_b128 v[200:203], v143 offset:22528
	ds_read_b128 v[204:207], v143 offset:23552
	global_load_lds_dwordx4 v[208:209], off
	s_add_i32 m0, s71, 0x2000
	s_add_u32 s72, s14, 0x40000
	v_lshl_add_u64 v[210:211], s[14:15], 0, v[134:135]
	s_addc_u32 s73, s15, 0
	s_add_i32 s71, s58, s50
	global_load_lds_dwordx4 v[210:211], off
	v_lshl_add_u64 v[212:213], s[72:73], 0, v[130:131]
	s_mov_b32 m0, s71
	v_lshl_add_u64 v[214:215], s[46:47], 0, v[132:133]
	global_load_lds_dwordx4 v[212:213], off
	v_lshl_add_u64 v[212:213], s[72:73], 0, v[134:135]
	s_add_i32 m0, s71, 0x2000
	s_nop 0
	global_load_lds_dwordx4 v[212:213], off
	v_lshl_add_u64 v[212:213], s[46:47], 0, v[128:129]
	s_mov_b32 m0, s35
	s_nop 0
	global_load_lds_dwordx4 v[212:213], off
	s_mov_b32 m0, s51
	s_nop 0
	global_load_lds_dwordx4 v[214:215], off
	s_waitcnt vmcnt(8)
	s_waitcnt lgkmcnt(0)
	s_barrier
	s_setprio 1
	v_mfma_f32_16x16x32_bf16 v[60:63], v[144:147], v[176:179], v[60:63]
	v_mfma_f32_16x16x32_bf16 v[56:59], v[152:155], v[176:179], v[56:59]
	v_mfma_f32_16x16x32_bf16 v[52:55], v[144:147], v[184:187], v[52:55]
	v_mfma_f32_16x16x32_bf16 v[48:51], v[152:155], v[184:187], v[48:51]
	v_mfma_f32_16x16x32_bf16 v[36:39], v[144:147], v[192:195], v[36:39]
	v_mfma_f32_16x16x32_bf16 v[32:35], v[152:155], v[192:195], v[32:35]
	v_mfma_f32_16x16x32_bf16 v[20:23], v[144:147], v[200:203], v[20:23]
	v_mfma_f32_16x16x32_bf16 v[16:19], v[152:155], v[200:203], v[16:19]
	v_mfma_f32_16x16x32_bf16 v[60:63], v[148:151], v[180:183], v[60:63]
	v_mfma_f32_16x16x32_bf16 v[56:59], v[156:159], v[180:183], v[56:59]
	v_mfma_f32_16x16x32_bf16 v[52:55], v[148:151], v[188:191], v[52:55]
	v_mfma_f32_16x16x32_bf16 v[48:51], v[156:159], v[188:191], v[48:51]
	v_mfma_f32_16x16x32_bf16 v[36:39], v[148:151], v[196:199], v[36:39]
	v_mfma_f32_16x16x32_bf16 v[32:35], v[156:159], v[196:199], v[32:35]
	v_mfma_f32_16x16x32_bf16 v[20:23], v[148:151], v[204:207], v[20:23]
	v_mfma_f32_16x16x32_bf16 v[16:19], v[156:159], v[204:207], v[16:19]
	s_setprio 0
	s_setprio 1
	v_mfma_f32_16x16x32_bf16 v[44:47], v[160:163], v[176:179], v[44:47]
	v_mfma_f32_16x16x32_bf16 v[40:43], v[168:171], v[176:179], v[40:43]
	v_mfma_f32_16x16x32_bf16 v[28:31], v[160:163], v[184:187], v[28:31]
	v_mfma_f32_16x16x32_bf16 v[24:27], v[168:171], v[184:187], v[24:27]
	v_mfma_f32_16x16x32_bf16 v[12:15], v[160:163], v[192:195], v[12:15]
	v_mfma_f32_16x16x32_bf16 v[8:11], v[168:171], v[192:195], v[8:11]
	v_mfma_f32_16x16x32_bf16 v[4:7], v[160:163], v[200:203], v[4:7]
	v_mfma_f32_16x16x32_bf16 v[0:3], v[168:171], v[200:203], v[0:3]
	v_mfma_f32_16x16x32_bf16 v[44:47], v[164:167], v[180:183], v[44:47]
	v_mfma_f32_16x16x32_bf16 v[40:43], v[172:175], v[180:183], v[40:43]
	v_mfma_f32_16x16x32_bf16 v[28:31], v[164:167], v[188:191], v[28:31]
	v_mfma_f32_16x16x32_bf16 v[24:27], v[172:175], v[188:191], v[24:27]
	v_mfma_f32_16x16x32_bf16 v[12:15], v[164:167], v[196:199], v[12:15]
	v_mfma_f32_16x16x32_bf16 v[8:11], v[172:175], v[196:199], v[8:11]
	v_mfma_f32_16x16x32_bf16 v[4:7], v[164:167], v[204:207], v[4:7]
	v_mfma_f32_16x16x32_bf16 v[0:3], v[172:175], v[204:207], v[0:3]
	s_setprio 0
	s_barrier
; #define G_STAGE(bufoff, gbase, voff) do { _Pragma("unroll") for (int _i = 0; _i < 2; ++_i) \
;         __builtin_amdgcn_global_load_lds((const unsigned*)((const char*)(gbase) + voff[_i]), (LAS unsigned*)(lds + (bufoff) + ldsw + _i * 8192), 16, 0, 0); } while (0)
; #define G_LDA(dst, b, h) do { _Pragma("unroll") for (int m = 0; m < 4; ++m) _Pragma("unroll") for (int k = 0; k < 2; ++k) dst[m][k] = *(const LAS bf16x8*)(lds + G_SA(b, h) + aoff + m * 2048 + k * 1024); } while (0)
; #define G_LDB(dst, b, h) do { _Pragma("unroll") for (int n = 0; n < 2; ++n) _Pragma("unroll") for (int k = 0; k < 2; ++k) dst[n][k] = *(const LAS bf16x8*)(lds + G_SB(b, h) + boff + n * 2048 + k * 1024); } while (0)
; #define G_MMA(ai, bj, At_, Bt_) do { __builtin_amdgcn_s_setprio(1); _Pragma("unroll") for (int m = 0; m < 4; ++m) _Pragma("unroll") for (int n = 0; n < 2; ++n) _Pragma("unroll") for (int k = 0; k < 2; ++k) \
;         acc[ai][bj][m][n] = __builtin_amdgcn_mfma_f32_16x16x32_bf16(Bt_[n][k], At_[m][k], acc[ai][bj][m][n], 0, 0, 0); __builtin_amdgcn_s_setprio(0); } while (0)
; #define WAIT_V(n) asm volatile("s_waitcnt vmcnt(" #n ")" ::: "memory")
; #define WAIT_L(n) asm volatile("s_waitcnt lgkmcnt(" #n ")" ::: "memory")
; #define BAR __builtin_amdgcn_s_barrier()
; #define SCHED __builtin_amdgcn_sched_barrier(0)
; template <class Get, class Epi>
; DI void gemm_loop(int ntiles, int ld, char* shm, const Get& get, const Epi& epi) {
;     ...
;             G_LDB(B0, 1, 0); G_LDB(B1, 1, 1); SCHED; G_LDA(At, 1, 0); G_STAGE(G_SA(0, 1), a2 + hstep, voffA);
;             WAIT_V(8); WAIT_L(0); BAR; G_MMA(0, 0, At, B0); G_MMA(0, 1, At, B1); BAR; SCHED;
	s_add_i32 s71, 0, 0x18000
	s_add_i32 s72, 0, 0x1c000
	v_add_u32_e32 v156, s71, v140
	v_add_u32_e32 v172, s72, v140
	ds_read_b128 v[144:147], v156
	ds_read_b128 v[148:151], v156 offset:1024
	ds_read_b128 v[152:155], v156 offset:2048
	ds_read_b128 v[156:159], v156 offset:3072
	ds_read_b128 v[160:163], v172
	ds_read_b128 v[164:167], v172 offset:1024
	ds_read_b128 v[168:171], v172 offset:2048
	ds_read_b128 v[172:175], v172 offset:3072
	s_add_u32 s46, s46, 0x40000
	s_addc_u32 s47, s47, 0
	s_mov_b32 m0, s52
	v_lshl_add_u64 v[216:217], s[46:47], 0, v[128:129]
	ds_read_b128 v[176:179], v143 offset:32768
	ds_read_b128 v[180:183], v143 offset:33792
	ds_read_b128 v[184:187], v143 offset:34816
	ds_read_b128 v[188:191], v143 offset:35840
	ds_read_b128 v[192:195], v143 offset:36864
	ds_read_b128 v[196:199], v143 offset:37888
	ds_read_b128 v[200:203], v143 offset:38912
	ds_read_b128 v[204:207], v143 offset:39936
	global_load_lds_dwordx4 v[216:217], off
	v_lshl_add_u64 v[216:217], s[46:47], 0, v[132:133]
	s_mov_b32 m0, s53
	s_nop 0
	global_load_lds_dwordx4 v[216:217], off
	s_waitcnt vmcnt(8)
	s_waitcnt lgkmcnt(0)
	s_barrier
	s_setprio 1
	v_mfma_f32_16x16x32_bf16 v[124:127], v[144:147], v[176:179], v[124:127]
	v_mfma_f32_16x16x32_bf16 v[120:123], v[152:155], v[176:179], v[120:123]
	v_mfma_f32_16x16x32_bf16 v[116:119], v[144:147], v[184:187], v[116:119]
	v_mfma_f32_16x16x32_bf16 v[112:115], v[152:155], v[184:187], v[112:115]
	v_mfma_f32_16x16x32_bf16 v[100:103], v[144:147], v[192:195], v[100:103]
	v_mfma_f32_16x16x32_bf16 v[96:99], v[152:155], v[192:195], v[96:99]
	v_mfma_f32_16x16x32_bf16 v[84:87], v[144:147], v[200:203], v[84:87]
	v_mfma_f32_16x16x32_bf16 v[80:83], v[152:155], v[200:203], v[80:83]
	v_mfma_f32_16x16x32_bf16 v[124:127], v[148:151], v[180:183], v[124:127]
	v_mfma_f32_16x16x32_bf16 v[120:123], v[156:159], v[180:183], v[120:123]
	v_mfma_f32_16x16x32_bf16 v[116:119], v[148:151], v[188:191], v[116:119]
	v_mfma_f32_16x16x32_bf16 v[112:115], v[156:159], v[188:191], v[112:115]
	v_mfma_f32_16x16x32_bf16 v[100:103], v[148:151], v[196:199], v[100:103]
	v_mfma_f32_16x16x32_bf16 v[96:99], v[156:159], v[196:199], v[96:99]
	v_mfma_f32_16x16x32_bf16 v[84:87], v[148:151], v[204:207], v[84:87]
	v_mfma_f32_16x16x32_bf16 v[80:83], v[156:159], v[204:207], v[80:83]
	s_setprio 0
	s_setprio 1
	v_mfma_f32_16x16x32_bf16 v[108:111], v[160:163], v[176:179], v[108:111]
	v_mfma_f32_16x16x32_bf16 v[104:107], v[168:171], v[176:179], v[104:107]
	v_mfma_f32_16x16x32_bf16 v[92:95], v[160:163], v[184:187], v[92:95]
	v_mfma_f32_16x16x32_bf16 v[88:91], v[168:171], v[184:187], v[88:91]
	v_mfma_f32_16x16x32_bf16 v[76:79], v[160:163], v[192:195], v[76:79]
	v_mfma_f32_16x16x32_bf16 v[72:75], v[168:171], v[192:195], v[72:75]
	v_mfma_f32_16x16x32_bf16 v[68:71], v[160:163], v[200:203], v[68:71]
	v_mfma_f32_16x16x32_bf16 v[64:67], v[168:171], v[200:203], v[64:67]
	v_mfma_f32_16x16x32_bf16 v[108:111], v[164:167], v[180:183], v[108:111]
	v_mfma_f32_16x16x32_bf16 v[104:107], v[172:175], v[180:183], v[104:107]
	v_mfma_f32_16x16x32_bf16 v[92:95], v[164:167], v[188:191], v[92:95]
	v_mfma_f32_16x16x32_bf16 v[88:91], v[172:175], v[188:191], v[88:91]
	v_mfma_f32_16x16x32_bf16 v[76:79], v[164:167], v[196:199], v[76:79]
	v_mfma_f32_16x16x32_bf16 v[72:75], v[172:175], v[196:199], v[72:75]
	v_mfma_f32_16x16x32_bf16 v[68:71], v[164:167], v[204:207], v[68:71]
	v_mfma_f32_16x16x32_bf16 v[64:67], v[172:175], v[204:207], v[64:67]
	s_setprio 0
	s_barrier
; #define G_STAGE(bufoff, gbase, voff) do { _Pragma("unroll") for (int _i = 0; _i < 2; ++_i) \
;         __builtin_amdgcn_global_load_lds((const unsigned*)((const char*)(gbase) + voff[_i]), (LAS unsigned*)(lds + (bufoff) + ldsw + _i * 8192), 16, 0, 0); } while (0)
; #define G_LDA(dst, b, h) do { _Pragma("unroll") for (int m = 0; m < 4; ++m) _Pragma("unroll") for (int k = 0; k < 2; ++k) dst[m][k] = *(const LAS bf16x8*)(lds + G_SA(b, h) + aoff + m * 2048 + k * 1024); } while (0)
; #define G_MMA(ai, bj, At_, Bt_) do { __builtin_amdgcn_s_setprio(1); _Pragma("unroll") for (int m = 0; m < 4; ++m) _Pragma("unroll") for (int n = 0; n < 2; ++n) _Pragma("unroll") for (int k = 0; k < 2; ++k) \
;         acc[ai][bj][m][n] = __builtin_amdgcn_mfma_f32_16x16x32_bf16(Bt_[n][k], At_[m][k], acc[ai][bj][m][n], 0, 0, 0); __builtin_amdgcn_s_setprio(0); } while (0)
; #define WAIT_V(n) asm volatile("s_waitcnt vmcnt(" #n ")" ::: "memory")
; #define WAIT_L(n) asm volatile("s_waitcnt lgkmcnt(" #n ")" ::: "memory")
; #define BAR __builtin_amdgcn_s_barrier()
; #define SCHED __builtin_amdgcn_sched_barrier(0)
; template <class Get, class Epi>
; DI void gemm_loop(int ntiles, int ld, char* shm, const Get& get, const Epi& epi) {
;     ...
;             G_LDA(At, 1, 1); G_STAGE(G_SB(1, 0), b3, voffB); G_STAGE(G_SB(1, 1), b3 + hstep, voffB); G_STAGE(G_SA(1, 0), a3, voffA);
;             WAIT_V(8); WAIT_L(0); BAR; G_MMA(1, 0, At, B0); G_MMA(1, 1, At, B1); BAR; SCHED;
;         }
	s_add_i32 s46, s71, s50
	v_lshl_add_u64 v[208:209], v[208:209], 0, s[8:9]
	s_mov_b32 m0, s46
	ds_read_b128 v[176:179], v143 offset:49152
	ds_read_b128 v[180:183], v143 offset:50176
	ds_read_b128 v[184:187], v143 offset:51200
	ds_read_b128 v[188:191], v143 offset:52224
	ds_read_b128 v[192:195], v143 offset:53248
	ds_read_b128 v[196:199], v143 offset:54272
	ds_read_b128 v[200:203], v143 offset:55296
	ds_read_b128 v[204:207], v143 offset:56320
	global_load_lds_dwordx4 v[208:209], off
	s_add_i32 m0, s46, 0x2000
	s_add_u32 s14, s14, 0x40080
	v_lshl_add_u64 v[208:209], v[210:211], 0, s[8:9]
	s_addc_u32 s15, s15, 0
	s_add_i32 s46, s72, s50
	global_load_lds_dwordx4 v[208:209], off
	v_lshl_add_u64 v[208:209], s[14:15], 0, v[130:131]
	s_mov_b32 m0, s46
	s_nop 0
	global_load_lds_dwordx4 v[208:209], off
	v_lshl_add_u64 v[208:209], s[14:15], 0, v[134:135]
	s_add_i32 m0, s46, 0x2000
	s_nop 0
	global_load_lds_dwordx4 v[208:209], off
	v_lshl_add_u64 v[208:209], v[212:213], 0, s[8:9]
	s_mov_b32 m0, s55
	s_nop 0
	global_load_lds_dwordx4 v[208:209], off
	v_lshl_add_u64 v[208:209], v[214:215], 0, s[8:9]
	s_mov_b32 m0, s56
	s_nop 0
	global_load_lds_dwordx4 v[208:209], off
	s_waitcnt vmcnt(8)
	s_waitcnt lgkmcnt(0)
	s_barrier
	s_setprio 1
	v_mfma_f32_16x16x32_bf16 v[60:63], v[144:147], v[176:179], v[60:63]
	v_mfma_f32_16x16x32_bf16 v[56:59], v[152:155], v[176:179], v[56:59]
	v_mfma_f32_16x16x32_bf16 v[52:55], v[144:147], v[184:187], v[52:55]
	v_mfma_f32_16x16x32_bf16 v[48:51], v[152:155], v[184:187], v[48:51]
	v_mfma_f32_16x16x32_bf16 v[36:39], v[144:147], v[192:195], v[36:39]
	v_mfma_f32_16x16x32_bf16 v[32:35], v[152:155], v[192:195], v[32:35]
	v_mfma_f32_16x16x32_bf16 v[20:23], v[144:147], v[200:203], v[20:23]
	v_mfma_f32_16x16x32_bf16 v[16:19], v[152:155], v[200:203], v[16:19]
	v_mfma_f32_16x16x32_bf16 v[60:63], v[148:151], v[180:183], v[60:63]
	v_mfma_f32_16x16x32_bf16 v[56:59], v[156:159], v[180:183], v[56:59]
	v_mfma_f32_16x16x32_bf16 v[52:55], v[148:151], v[188:191], v[52:55]
	v_mfma_f32_16x16x32_bf16 v[48:51], v[156:159], v[188:191], v[48:51]
	v_mfma_f32_16x16x32_bf16 v[36:39], v[148:151], v[196:199], v[36:39]
	v_mfma_f32_16x16x32_bf16 v[32:35], v[156:159], v[196:199], v[32:35]
	v_mfma_f32_16x16x32_bf16 v[20:23], v[148:151], v[204:207], v[20:23]
	v_mfma_f32_16x16x32_bf16 v[16:19], v[156:159], v[204:207], v[16:19]
	s_setprio 0
	s_setprio 1
	v_mfma_f32_16x16x32_bf16 v[44:47], v[160:163], v[176:179], v[44:47]
	v_mfma_f32_16x16x32_bf16 v[40:43], v[168:171], v[176:179], v[40:43]
	v_mfma_f32_16x16x32_bf16 v[28:31], v[160:163], v[184:187], v[28:31]
	v_mfma_f32_16x16x32_bf16 v[24:27], v[168:171], v[184:187], v[24:27]
	v_mfma_f32_16x16x32_bf16 v[12:15], v[160:163], v[192:195], v[12:15]
	v_mfma_f32_16x16x32_bf16 v[8:11], v[168:171], v[192:195], v[8:11]
	v_mfma_f32_16x16x32_bf16 v[4:7], v[160:163], v[200:203], v[4:7]
	v_mfma_f32_16x16x32_bf16 v[0:3], v[168:171], v[200:203], v[0:3]
	v_mfma_f32_16x16x32_bf16 v[44:47], v[164:167], v[180:183], v[44:47]
	v_mfma_f32_16x16x32_bf16 v[40:43], v[172:175], v[180:183], v[40:43]
	v_mfma_f32_16x16x32_bf16 v[28:31], v[164:167], v[188:191], v[28:31]
	v_mfma_f32_16x16x32_bf16 v[24:27], v[172:175], v[188:191], v[24:27]
	v_mfma_f32_16x16x32_bf16 v[12:15], v[164:167], v[196:199], v[12:15]
	v_mfma_f32_16x16x32_bf16 v[8:11], v[172:175], v[196:199], v[8:11]
	v_mfma_f32_16x16x32_bf16 v[4:7], v[164:167], v[204:207], v[4:7]
	v_mfma_f32_16x16x32_bf16 v[0:3], v[172:175], v[204:207], v[0:3]
	s_setprio 0
	s_barrier
	s_add_i32 s70, s70, 2
	s_add_u32 s48, s48, 0x100
	s_addc_u32 s49, s49, 0
	s_add_u32 s64, s64, 0x100
	s_addc_u32 s65, s65, 0
	s_cmp_gt_u32 s70, 13
	s_cbranch_scc0 .LBB0_3141

; #define G_STAGE(bufoff, gbase, voff) do { _Pragma("unroll") for (int _i = 0; _i < 2; ++_i) \
;         __builtin_amdgcn_global_load_lds((const unsigned*)((const char*)(gbase) + voff[_i]), (LAS unsigned*)(lds + (bufoff) + ldsw + _i * 8192), 16, 0, 0); } while (0)
; #define G_LDA(dst, b, h) do { _Pragma("unroll") for (int m = 0; m < 4; ++m) _Pragma("unroll") for (int k = 0; k < 2; ++k) dst[m][k] = *(const LAS bf16x8*)(lds + G_SA(b, h) + aoff + m * 2048 + k * 1024); } while (0)
; #define G_MMA(ai, bj, At_, Bt_) do { __builtin_amdgcn_s_setprio(1); _Pragma("unroll") for (int m = 0; m < 4; ++m) _Pragma("unroll") for (int n = 0; n < 2; ++n) _Pragma("unroll") for (int k = 0; k < 2; ++k) \
;         acc[ai][bj][m][n] = __builtin_amdgcn_mfma_f32_16x16x32_bf16(Bt_[n][k], At_[m][k], acc[ai][bj][m][n], 0, 0, 0); __builtin_amdgcn_s_setprio(0); } while (0)
; #define WAIT_V(n) asm volatile("s_waitcnt vmcnt(" #n ")" ::: "memory")
; #define WAIT_L(n) asm volatile("s_waitcnt lgkmcnt(" #n ")" ::: "memory")
; #define BAR __builtin_amdgcn_s_barrier()
; #define SCHED __builtin_amdgcn_sched_barrier(0)
; template <class Get, class Epi>
; DI void gemm_loop(int ntiles, int ld, char* shm, const Get& get, const Epi& epi) {
;     ...
;             WAIT_V(8); WAIT_L(0); BAR; G_MMA(0, 0, At, B0); G_MMA(0, 1, At, B1); BAR; SCHED;
;             G_LDA(At, 0, 1); G_STAGE(G_SB(0, 0), b2, voffB); G_STAGE(G_SB(0, 1), b2 + hstep, voffB); G_STAGE(G_SA(0, 0), a2, voffA);
.Lrj_3466_0:
	s_waitcnt lgkmcnt(0)
	s_barrier
	s_setprio 1
	v_mfma_f32_16x16x32_bf16 v[124:127], v[128:131], v[180:183], 0
	v_mfma_f32_16x16x32_bf16 v[120:123], v[136:139], v[180:183], 0
	v_mfma_f32_16x16x32_bf16 v[116:119], v[128:131], v[188:191], 0
	v_mfma_f32_16x16x32_bf16 v[112:115], v[136:139], v[188:191], 0
	v_mfma_f32_16x16x32_bf16 v[108:111], v[128:131], v[196:199], 0
	v_mfma_f32_16x16x32_bf16 v[104:107], v[136:139], v[196:199], 0
	v_mfma_f32_16x16x32_bf16 v[100:103], v[128:131], v[204:207], 0
	v_mfma_f32_16x16x32_bf16 v[96:99], v[136:139], v[204:207], 0
	v_mfma_f32_16x16x32_bf16 v[124:127], v[132:135], v[184:187], v[124:127]
	v_mfma_f32_16x16x32_bf16 v[120:123], v[140:143], v[184:187], v[120:123]
	v_mfma_f32_16x16x32_bf16 v[116:119], v[132:135], v[192:195], v[116:119]
	v_mfma_f32_16x16x32_bf16 v[112:115], v[140:143], v[192:195], v[112:115]
	v_mfma_f32_16x16x32_bf16 v[108:111], v[132:135], v[200:203], v[108:111]
	v_mfma_f32_16x16x32_bf16 v[104:107], v[140:143], v[200:203], v[104:107]
	v_mfma_f32_16x16x32_bf16 v[100:103], v[132:135], v[208:211], v[100:103]
	v_mfma_f32_16x16x32_bf16 v[96:99], v[140:143], v[208:211], v[96:99]
	s_setprio 0
	s_setprio 1
	v_mfma_f32_16x16x32_bf16 v[60:63], v[158:161], v[180:183], 0
	v_mfma_f32_16x16x32_bf16 v[56:59], v[172:175], v[180:183], 0
	v_mfma_f32_16x16x32_bf16 v[52:55], v[158:161], v[188:191], 0
	v_mfma_f32_16x16x32_bf16 v[48:51], v[172:175], v[188:191], 0
	v_mfma_f32_16x16x32_bf16 v[44:47], v[158:161], v[196:199], 0
	v_mfma_f32_16x16x32_bf16 v[40:43], v[172:175], v[196:199], 0
	v_mfma_f32_16x16x32_bf16 v[36:39], v[158:161], v[204:207], 0
	v_mfma_f32_16x16x32_bf16 v[32:35], v[172:175], v[204:207], 0
	v_mfma_f32_16x16x32_bf16 v[60:63], v[162:165], v[184:187], v[60:63]
	v_mfma_f32_16x16x32_bf16 v[56:59], v[176:179], v[184:187], v[56:59]
	v_mfma_f32_16x16x32_bf16 v[52:55], v[162:165], v[192:195], v[52:55]
	v_mfma_f32_16x16x32_bf16 v[48:51], v[176:179], v[192:195], v[48:51]
	v_mfma_f32_16x16x32_bf16 v[44:47], v[162:165], v[200:203], v[44:47]
	v_mfma_f32_16x16x32_bf16 v[40:43], v[176:179], v[200:203], v[40:43]
	v_mfma_f32_16x16x32_bf16 v[36:39], v[162:165], v[208:211], v[36:39]
	v_mfma_f32_16x16x32_bf16 v[32:35], v[176:179], v[208:211], v[32:35]
	s_setprio 0
	s_barrier
	s_add_i32 s72, s56, s48
	v_lshl_add_u64 v[144:145], s[14:15], 0, v[148:149]
	s_mov_b32 m0, s72
	ds_read_b128 v[180:183], v171 offset:16384
	ds_read_b128 v[184:187], v171 offset:17408
	ds_read_b128 v[188:191], v171 offset:18432
	ds_read_b128 v[192:195], v171 offset:19456
	ds_read_b128 v[196:199], v171 offset:20480
	ds_read_b128 v[200:203], v171 offset:21504
	ds_read_b128 v[204:207], v171 offset:22528
	ds_read_b128 v[208:211], v171 offset:23552
	global_load_lds_dwordx4 v[144:145], off
	s_add_i32 m0, s72, 0x2000
	s_add_u32 s72, s14, 0x40000
	v_lshl_add_u64 v[166:167], s[14:15], 0, v[152:153]
	s_addc_u32 s73, s15, 0
	s_add_i32 s74, s57, s48
	global_load_lds_dwordx4 v[166:167], off
	v_lshl_add_u64 v[212:213], s[72:73], 0, v[148:149]
	s_mov_b32 m0, s74
	v_lshl_add_u64 v[214:215], s[46:47], 0, v[150:151]
	global_load_lds_dwordx4 v[212:213], off
	v_lshl_add_u64 v[212:213], s[72:73], 0, v[152:153]
	s_add_i32 m0, s74, 0x2000
	s_nop 0
	global_load_lds_dwordx4 v[212:213], off
	v_lshl_add_u64 v[212:213], s[46:47], 0, v[146:147]
	s_mov_b32 m0, s43
	s_nop 0
	global_load_lds_dwordx4 v[212:213], off
	s_mov_b32 m0, s49
	s_nop 0
	global_load_lds_dwordx4 v[214:215], off
	s_cmp_lg_u32 s100, 0
	s_cbranch_scc0 .Lrf_3466_1
	s_waitcnt vmcnt(16)
	s_branch .Lrj_3466_1

; #define G_STAGE(bufoff, gbase, voff) do { _Pragma("unroll") for (int _i = 0; _i < 2; ++_i) \
;         __builtin_amdgcn_global_load_lds((const unsigned*)((const char*)(gbase) + voff[_i]), (LAS unsigned*)(lds + (bufoff) + ldsw + _i * 8192), 16, 0, 0); } while (0)
; #define G_LDA(dst, b, h) do { _Pragma("unroll") for (int m = 0; m < 4; ++m) _Pragma("unroll") for (int k = 0; k < 2; ++k) dst[m][k] = *(const LAS bf16x8*)(lds + G_SA(b, h) + aoff + m * 2048 + k * 1024); } while (0)
; #define G_LDB(dst, b, h) do { _Pragma("unroll") for (int n = 0; n < 2; ++n) _Pragma("unroll") for (int k = 0; k < 2; ++k) dst[n][k] = *(const LAS bf16x8*)(lds + G_SB(b, h) + boff + n * 2048 + k * 1024); } while (0)
; #define G_MMA(ai, bj, At_, Bt_) do { __builtin_amdgcn_s_setprio(1); _Pragma("unroll") for (int m = 0; m < 4; ++m) _Pragma("unroll") for (int n = 0; n < 2; ++n) _Pragma("unroll") for (int k = 0; k < 2; ++k) \
;         acc[ai][bj][m][n] = __builtin_amdgcn_mfma_f32_16x16x32_bf16(Bt_[n][k], At_[m][k], acc[ai][bj][m][n], 0, 0, 0); __builtin_amdgcn_s_setprio(0); } while (0)
; #define WAIT_V(n) asm volatile("s_waitcnt vmcnt(" #n ")" ::: "memory")
; #define WAIT_L(n) asm volatile("s_waitcnt lgkmcnt(" #n ")" ::: "memory")
; #define BAR __builtin_amdgcn_s_barrier()
; #define SCHED __builtin_amdgcn_sched_barrier(0)
; template <class Get, class Epi>
; DI void gemm_loop(int ntiles, int ld, char* shm, const Get& get, const Epi& epi) {
;     ...
;             WAIT_V(8); WAIT_L(0); BAR; G_MMA(1, 0, At, B0); G_MMA(1, 1, At, B1); BAR; SCHED;
;             G_LDB(B0, 1, 0); G_LDB(B1, 1, 1); SCHED; G_LDA(At, 1, 0); G_STAGE(G_SA(0, 1), a2 + hstep, voffA);
;             WAIT_V(8); WAIT_L(0); BAR; G_MMA(0, 0, At, B0); G_MMA(0, 1, At, B1); BAR; SCHED;
.Lrj_3466_1:
	s_waitcnt lgkmcnt(0)
	s_barrier
	s_setprio 1
	v_mfma_f32_16x16x32_bf16 v[92:95], v[128:131], v[180:183], 0
	v_mfma_f32_16x16x32_bf16 v[88:91], v[136:139], v[180:183], 0
	v_mfma_f32_16x16x32_bf16 v[84:87], v[128:131], v[188:191], 0
	v_mfma_f32_16x16x32_bf16 v[80:83], v[136:139], v[188:191], 0
	v_mfma_f32_16x16x32_bf16 v[76:79], v[128:131], v[196:199], 0
	v_mfma_f32_16x16x32_bf16 v[72:75], v[136:139], v[196:199], 0
	v_mfma_f32_16x16x32_bf16 v[68:71], v[128:131], v[204:207], 0
	v_mfma_f32_16x16x32_bf16 v[64:67], v[136:139], v[204:207], 0
	v_mfma_f32_16x16x32_bf16 v[92:95], v[132:135], v[184:187], v[92:95]
	v_mfma_f32_16x16x32_bf16 v[88:91], v[140:143], v[184:187], v[88:91]
	v_mfma_f32_16x16x32_bf16 v[84:87], v[132:135], v[192:195], v[84:87]
	v_mfma_f32_16x16x32_bf16 v[80:83], v[140:143], v[192:195], v[80:83]
	v_mfma_f32_16x16x32_bf16 v[76:79], v[132:135], v[200:203], v[76:79]
	v_mfma_f32_16x16x32_bf16 v[72:75], v[140:143], v[200:203], v[72:75]
	v_mfma_f32_16x16x32_bf16 v[68:71], v[132:135], v[208:211], v[68:71]
	v_mfma_f32_16x16x32_bf16 v[64:67], v[140:143], v[208:211], v[64:67]
	s_setprio 0
	s_setprio 1
	v_mfma_f32_16x16x32_bf16 v[28:31], v[158:161], v[180:183], 0
	v_mfma_f32_16x16x32_bf16 v[24:27], v[172:175], v[180:183], 0
	v_mfma_f32_16x16x32_bf16 v[20:23], v[158:161], v[188:191], 0
	v_mfma_f32_16x16x32_bf16 v[16:19], v[172:175], v[188:191], 0
	v_mfma_f32_16x16x32_bf16 v[12:15], v[158:161], v[196:199], 0
	v_mfma_f32_16x16x32_bf16 v[8:11], v[172:175], v[196:199], 0
	v_mfma_f32_16x16x32_bf16 v[4:7], v[158:161], v[204:207], 0
	v_mfma_f32_16x16x32_bf16 v[0:3], v[172:175], v[204:207], 0
	v_mfma_f32_16x16x32_bf16 v[28:31], v[162:165], v[184:187], v[28:31]
	v_mfma_f32_16x16x32_bf16 v[24:27], v[176:179], v[184:187], v[24:27]
	v_mfma_f32_16x16x32_bf16 v[20:23], v[162:165], v[192:195], v[20:23]
	v_mfma_f32_16x16x32_bf16 v[16:19], v[176:179], v[192:195], v[16:19]
	v_mfma_f32_16x16x32_bf16 v[12:15], v[162:165], v[200:203], v[12:15]
	v_mfma_f32_16x16x32_bf16 v[8:11], v[176:179], v[200:203], v[8:11]
	v_mfma_f32_16x16x32_bf16 v[4:7], v[162:165], v[208:211], v[4:7]
	v_mfma_f32_16x16x32_bf16 v[0:3], v[176:179], v[208:211], v[0:3]
	s_setprio 0
	s_barrier
	s_add_i32 s72, 0, 0x18000
	s_add_i32 s73, 0, 0x1c000
	v_add_u32_e32 v140, s72, v168
	v_add_u32_e32 v176, s73, v168
	ds_read_b128 v[128:131], v140
	ds_read_b128 v[132:135], v140 offset:1024
	ds_read_b128 v[136:139], v140 offset:2048
	ds_read_b128 v[140:143], v140 offset:3072
	ds_read_b128 v[158:161], v176
	ds_read_b128 v[162:165], v176 offset:1024
	ds_read_b128 v[172:175], v176 offset:2048
	ds_read_b128 v[176:179], v176 offset:3072
	s_add_u32 s46, s46, 0x40000
	s_addc_u32 s47, s47, 0
	s_mov_b32 m0, s50
	v_lshl_add_u64 v[216:217], s[46:47], 0, v[146:147]
	ds_read_b128 v[180:183], v171 offset:32768
	ds_read_b128 v[184:187], v171 offset:33792
	ds_read_b128 v[188:191], v171 offset:34816
	ds_read_b128 v[192:195], v171 offset:35840
	ds_read_b128 v[196:199], v171 offset:36864
	ds_read_b128 v[200:203], v171 offset:37888
	ds_read_b128 v[204:207], v171 offset:38912
	ds_read_b128 v[208:211], v171 offset:39936
	global_load_lds_dwordx4 v[216:217], off
	v_lshl_add_u64 v[216:217], s[46:47], 0, v[150:151]
	s_mov_b32 m0, s51
	s_nop 0
	global_load_lds_dwordx4 v[216:217], off
	s_waitcnt vmcnt(8)
	s_waitcnt lgkmcnt(0)
	s_barrier
	s_setprio 1
	v_mfma_f32_16x16x32_bf16 v[124:127], v[128:131], v[180:183], v[124:127]
	v_mfma_f32_16x16x32_bf16 v[120:123], v[136:139], v[180:183], v[120:123]
	v_mfma_f32_16x16x32_bf16 v[116:119], v[128:131], v[188:191], v[116:119]
	v_mfma_f32_16x16x32_bf16 v[112:115], v[136:139], v[188:191], v[112:115]
	v_mfma_f32_16x16x32_bf16 v[108:111], v[128:131], v[196:199], v[108:111]
	v_mfma_f32_16x16x32_bf16 v[104:107], v[136:139], v[196:199], v[104:107]
	v_mfma_f32_16x16x32_bf16 v[100:103], v[128:131], v[204:207], v[100:103]
	v_mfma_f32_16x16x32_bf16 v[96:99], v[136:139], v[204:207], v[96:99]
	v_mfma_f32_16x16x32_bf16 v[124:127], v[132:135], v[184:187], v[124:127]
	v_mfma_f32_16x16x32_bf16 v[120:123], v[140:143], v[184:187], v[120:123]
	v_mfma_f32_16x16x32_bf16 v[116:119], v[132:135], v[192:195], v[116:119]
	v_mfma_f32_16x16x32_bf16 v[112:115], v[140:143], v[192:195], v[112:115]
	v_mfma_f32_16x16x32_bf16 v[108:111], v[132:135], v[200:203], v[108:111]
	v_mfma_f32_16x16x32_bf16 v[104:107], v[140:143], v[200:203], v[104:107]
	v_mfma_f32_16x16x32_bf16 v[100:103], v[132:135], v[208:211], v[100:103]
	v_mfma_f32_16x16x32_bf16 v[96:99], v[140:143], v[208:211], v[96:99]
	s_setprio 0
	s_setprio 1
	v_mfma_f32_16x16x32_bf16 v[60:63], v[158:161], v[180:183], v[60:63]
	v_mfma_f32_16x16x32_bf16 v[56:59], v[172:175], v[180:183], v[56:59]
	v_mfma_f32_16x16x32_bf16 v[52:55], v[158:161], v[188:191], v[52:55]
	v_mfma_f32_16x16x32_bf16 v[48:51], v[172:175], v[188:191], v[48:51]
	v_mfma_f32_16x16x32_bf16 v[44:47], v[158:161], v[196:199], v[44:47]
	v_mfma_f32_16x16x32_bf16 v[40:43], v[172:175], v[196:199], v[40:43]
	v_mfma_f32_16x16x32_bf16 v[36:39], v[158:161], v[204:207], v[36:39]
	v_mfma_f32_16x16x32_bf16 v[32:35], v[172:175], v[204:207], v[32:35]
	v_mfma_f32_16x16x32_bf16 v[60:63], v[162:165], v[184:187], v[60:63]
	v_mfma_f32_16x16x32_bf16 v[56:59], v[176:179], v[184:187], v[56:59]
	v_mfma_f32_16x16x32_bf16 v[52:55], v[162:165], v[192:195], v[52:55]
	v_mfma_f32_16x16x32_bf16 v[48:51], v[176:179], v[192:195], v[48:51]
	v_mfma_f32_16x16x32_bf16 v[44:47], v[162:165], v[200:203], v[44:47]
	v_mfma_f32_16x16x32_bf16 v[40:43], v[176:179], v[200:203], v[40:43]
	v_mfma_f32_16x16x32_bf16 v[36:39], v[162:165], v[208:211], v[36:39]
	v_mfma_f32_16x16x32_bf16 v[32:35], v[176:179], v[208:211], v[32:35]
	s_setprio 0
	s_barrier
; #define G_STAGE(bufoff, gbase, voff) do { _Pragma("unroll") for (int _i = 0; _i < 2; ++_i) \
;         __builtin_amdgcn_global_load_lds((const unsigned*)((const char*)(gbase) + voff[_i]), (LAS unsigned*)(lds + (bufoff) + ldsw + _i * 8192), 16, 0, 0); } while (0)
; #define G_LDA(dst, b, h) do { _Pragma("unroll") for (int m = 0; m < 4; ++m) _Pragma("unroll") for (int k = 0; k < 2; ++k) dst[m][k] = *(const LAS bf16x8*)(lds + G_SA(b, h) + aoff + m * 2048 + k * 1024); } while (0)
; #define G_LDB(dst, b, h) do { _Pragma("unroll") for (int n = 0; n < 2; ++n) _Pragma("unroll") for (int k = 0; k < 2; ++k) dst[n][k] = *(const LAS bf16x8*)(lds + G_SB(b, h) + boff + n * 2048 + k * 1024); } while (0)
; #define G_MMA(ai, bj, At_, Bt_) do { __builtin_amdgcn_s_setprio(1); _Pragma("unroll") for (int m = 0; m < 4; ++m) _Pragma("unroll") for (int n = 0; n < 2; ++n) _Pragma("unroll") for (int k = 0; k < 2; ++k) \
;         acc[ai][bj][m][n] = __builtin_amdgcn_mfma_f32_16x16x32_bf16(Bt_[n][k], At_[m][k], acc[ai][bj][m][n], 0, 0, 0); __builtin_amdgcn_s_setprio(0); } while (0)
; #define WAIT_V(n) asm volatile("s_waitcnt vmcnt(" #n ")" ::: "memory")
; #define WAIT_L(n) asm volatile("s_waitcnt lgkmcnt(" #n ")" ::: "memory")
; #define BAR __builtin_amdgcn_s_barrier()
; #define SCHED __builtin_amdgcn_sched_barrier(0)
; template <class Get, class Epi>
; DI void gemm_loop(int ntiles, int ld, char* shm, const Get& get, const Epi& epi) {
;     ...
;         for (int t = 0; t < nt; t += 2) {
;             const bool last = (t == nt - 2);
;             const char* a1 = cA + (size_t)(t + 1) * kstep;
;             const char* a2 = last ? nA : cA + (size_t)(t + 2) * kstep; const char* b2 = last ? nB : cB + (size_t)(t + 2) * kstep;
;             const char* a3 = a2 + kstep; const char* b3 = b2 + kstep;
;             G_LDB(B0, 0, 0); G_LDB(B1, 0, 1); SCHED; G_LDA(At, 0, 0); G_STAGE(G_SA(1, 1), a1 + hstep, voffA);
;     ...
;             G_LDA(At, 1, 1); G_STAGE(G_SB(1, 0), b3, voffB); G_STAGE(G_SB(1, 1), b3 + hstep, voffB); G_STAGE(G_SA(1, 0), a3, voffA);
;             WAIT_V(8); WAIT_L(0); BAR; G_MMA(1, 0, At, B0); G_MMA(1, 1, At, B1); BAR; SCHED;
	s_add_i32 s46, s72, s48
	v_lshl_add_u64 v[144:145], v[144:145], 0, s[4:5]
	s_mov_b32 m0, s46
	ds_read_b128 v[180:183], v171 offset:49152
	ds_read_b128 v[184:187], v171 offset:50176
	ds_read_b128 v[188:191], v171 offset:51200
	ds_read_b128 v[192:195], v171 offset:52224
	ds_read_b128 v[196:199], v171 offset:53248
	ds_read_b128 v[200:203], v171 offset:54272
	ds_read_b128 v[204:207], v171 offset:55296
	ds_read_b128 v[208:211], v171 offset:56320
	global_load_lds_dwordx4 v[144:145], off
	s_add_i32 m0, s46, 0x2000
	s_add_u32 s14, s14, 0x40080
	v_lshl_add_u64 v[144:145], v[166:167], 0, s[4:5]
	s_addc_u32 s15, s15, 0
	s_add_i32 s46, s73, s48
	global_load_lds_dwordx4 v[144:145], off
	v_lshl_add_u64 v[144:145], s[14:15], 0, v[148:149]
	s_mov_b32 m0, s46
	s_nop 0
	global_load_lds_dwordx4 v[144:145], off
	v_lshl_add_u64 v[144:145], s[14:15], 0, v[152:153]
	s_add_i32 m0, s46, 0x2000
	s_nop 0
	global_load_lds_dwordx4 v[144:145], off
	v_lshl_add_u64 v[144:145], v[212:213], 0, s[4:5]
	s_mov_b32 m0, s54
	s_nop 0
	global_load_lds_dwordx4 v[144:145], off
	v_lshl_add_u64 v[144:145], v[214:215], 0, s[4:5]
	s_mov_b32 m0, s55
	s_nop 0
	global_load_lds_dwordx4 v[144:145], off
	s_waitcnt vmcnt(8)
	s_waitcnt lgkmcnt(0)
	s_barrier
	s_setprio 1
	v_mfma_f32_16x16x32_bf16 v[92:95], v[128:131], v[180:183], v[92:95]
	v_mfma_f32_16x16x32_bf16 v[88:91], v[136:139], v[180:183], v[88:91]
	v_mfma_f32_16x16x32_bf16 v[84:87], v[128:131], v[188:191], v[84:87]
	v_mfma_f32_16x16x32_bf16 v[80:83], v[136:139], v[188:191], v[80:83]
	v_mfma_f32_16x16x32_bf16 v[76:79], v[128:131], v[196:199], v[76:79]
	v_mfma_f32_16x16x32_bf16 v[72:75], v[136:139], v[196:199], v[72:75]
	v_mfma_f32_16x16x32_bf16 v[68:71], v[128:131], v[204:207], v[68:71]
	v_mfma_f32_16x16x32_bf16 v[64:67], v[136:139], v[204:207], v[64:67]
	v_mfma_f32_16x16x32_bf16 v[92:95], v[132:135], v[184:187], v[92:95]
	v_mfma_f32_16x16x32_bf16 v[88:91], v[140:143], v[184:187], v[88:91]
	v_mfma_f32_16x16x32_bf16 v[84:87], v[132:135], v[192:195], v[84:87]
	v_mfma_f32_16x16x32_bf16 v[80:83], v[140:143], v[192:195], v[80:83]
	v_mfma_f32_16x16x32_bf16 v[76:79], v[132:135], v[200:203], v[76:79]
	v_mfma_f32_16x16x32_bf16 v[72:75], v[140:143], v[200:203], v[72:75]
	v_mfma_f32_16x16x32_bf16 v[68:71], v[132:135], v[208:211], v[68:71]
	v_mfma_f32_16x16x32_bf16 v[64:67], v[140:143], v[208:211], v[64:67]
	s_setprio 0
	s_setprio 1
	v_mfma_f32_16x16x32_bf16 v[28:31], v[158:161], v[180:183], v[28:31]
	v_mfma_f32_16x16x32_bf16 v[24:27], v[172:175], v[180:183], v[24:27]
	v_mfma_f32_16x16x32_bf16 v[20:23], v[158:161], v[188:191], v[20:23]
	v_mfma_f32_16x16x32_bf16 v[16:19], v[172:175], v[188:191], v[16:19]
	v_mfma_f32_16x16x32_bf16 v[12:15], v[158:161], v[196:199], v[12:15]
	v_mfma_f32_16x16x32_bf16 v[8:11], v[172:175], v[196:199], v[8:11]
	v_mfma_f32_16x16x32_bf16 v[4:7], v[158:161], v[204:207], v[4:7]
	v_mfma_f32_16x16x32_bf16 v[0:3], v[172:175], v[204:207], v[0:3]
	v_mfma_f32_16x16x32_bf16 v[28:31], v[162:165], v[184:187], v[28:31]
	v_mfma_f32_16x16x32_bf16 v[24:27], v[176:179], v[184:187], v[24:27]
	v_mfma_f32_16x16x32_bf16 v[20:23], v[162:165], v[192:195], v[20:23]
	v_mfma_f32_16x16x32_bf16 v[16:19], v[176:179], v[192:195], v[16:19]
	v_mfma_f32_16x16x32_bf16 v[12:15], v[162:165], v[200:203], v[12:15]
	v_mfma_f32_16x16x32_bf16 v[8:11], v[176:179], v[200:203], v[8:11]
	v_mfma_f32_16x16x32_bf16 v[4:7], v[162:165], v[208:211], v[4:7]
	v_mfma_f32_16x16x32_bf16 v[0:3], v[176:179], v[208:211], v[0:3]
	s_setprio 0
	s_barrier
	s_add_i32 s71, s71, 2
	s_add_u32 s44, s44, 0x100
	s_addc_u32 s45, s45, 0
	s_add_u32 s65, s65, 0x100
	s_addc_u32 s70, s70, 0
	s_cmp_gt_u32 s71, 13
	s_cbranch_scc0 .LBB0_3466
	s_branch .Lpost_3466
.LBB0_3466:
	ds_read_b128 v[128:131], v169
	ds_read_b128 v[132:135], v169 offset:1024
	ds_read_b128 v[136:139], v169 offset:2048
	ds_read_b128 v[140:143], v169 offset:3072
	ds_read_b128 v[158:161], v170
	ds_read_b128 v[162:165], v170 offset:1024
	ds_read_b128 v[172:175], v170 offset:2048
	ds_read_b128 v[176:179], v170 offset:3072
	s_add_u32 s14, s44, 0xfffc0080
	s_addc_u32 s15, s45, -1
	s_cmp_eq_u32 s71, 12
	s_cselect_b32 s47, s3, s15
	s_cselect_b32 s46, s35, s14
	s_cselect_b32 s15, s37, s70
	s_cselect_b32 s14, s64, s65
	v_lshl_add_u64 v[144:145], s[44:45], 0, v[154:155]
	s_add_i32 m0, s43, 0xc000
	ds_read_b128 v[180:183], v171
	ds_read_b128 v[184:187], v171 offset:1024
	ds_read_b128 v[188:191], v171 offset:2048
	ds_read_b128 v[192:195], v171 offset:3072
	ds_read_b128 v[196:199], v171 offset:4096
	ds_read_b128 v[200:203], v171 offset:5120
	ds_read_b128 v[204:207], v171 offset:6144
	ds_read_b128 v[208:211], v171 offset:7168
	global_load_lds_dwordx4 v[144:145], off
	v_lshl_add_u64 v[144:145], s[44:45], 0, v[156:157]
	s_add_i32 m0, s43, 0xe000
	s_nop 0
	global_load_lds_dwordx4 v[144:145], off
	s_waitcnt vmcnt(8)
	s_waitcnt lgkmcnt(0)
	s_barrier
; #define G_STAGE(bufoff, gbase, voff) do { _Pragma("unroll") for (int _i = 0; _i < 2; ++_i) \
;         __builtin_amdgcn_global_load_lds((const unsigned*)((const char*)(gbase) + voff[_i]), (LAS unsigned*)(lds + (bufoff) + ldsw + _i * 8192), 16, 0, 0); } while (0)
; #define G_LDA(dst, b, h) do { _Pragma("unroll") for (int m = 0; m < 4; ++m) _Pragma("unroll") for (int k = 0; k < 2; ++k) dst[m][k] = *(const LAS bf16x8*)(lds + G_SA(b, h) + aoff + m * 2048 + k * 1024); } while (0)
; #define G_MMA(ai, bj, At_, Bt_) do { __builtin_amdgcn_s_setprio(1); _Pragma("unroll") for (int m = 0; m < 4; ++m) _Pragma("unroll") for (int n = 0; n < 2; ++n) _Pragma("unroll") for (int k = 0; k < 2; ++k) \
;         acc[ai][bj][m][n] = __builtin_amdgcn_mfma_f32_16x16x32_bf16(Bt_[n][k], At_[m][k], acc[ai][bj][m][n], 0, 0, 0); __builtin_amdgcn_s_setprio(0); } while (0)
; #define WAIT_V(n) asm volatile("s_waitcnt vmcnt(" #n ")" ::: "memory")
; #define WAIT_L(n) asm volatile("s_waitcnt lgkmcnt(" #n ")" ::: "memory")
; #define BAR __builtin_amdgcn_s_barrier()
; #define SCHED __builtin_amdgcn_sched_barrier(0)
; template <class Get, class Epi>
; DI void gemm_loop(int ntiles, int ld, char* shm, const Get& get, const Epi& epi) {
;     ...
;             WAIT_V(8); WAIT_L(0); BAR; G_MMA(0, 0, At, B0); G_MMA(0, 1, At, B1); BAR; SCHED;
;             G_LDA(At, 0, 1); G_STAGE(G_SB(0, 0), b2, voffB); G_STAGE(G_SB(0, 1), b2 + hstep, voffB); G_STAGE(G_SA(0, 0), a2, voffA);
;             WAIT_V(8); WAIT_L(0); BAR; G_MMA(1, 0, At, B0); G_MMA(1, 1, At, B1); BAR; SCHED;
	s_setprio 1
	v_mfma_f32_16x16x32_bf16 v[124:127], v[128:131], v[180:183], v[124:127]
	v_mfma_f32_16x16x32_bf16 v[120:123], v[136:139], v[180:183], v[120:123]
	v_mfma_f32_16x16x32_bf16 v[116:119], v[128:131], v[188:191], v[116:119]
	v_mfma_f32_16x16x32_bf16 v[112:115], v[136:139], v[188:191], v[112:115]
	v_mfma_f32_16x16x32_bf16 v[108:111], v[128:131], v[196:199], v[108:111]
	v_mfma_f32_16x16x32_bf16 v[104:107], v[136:139], v[196:199], v[104:107]
	v_mfma_f32_16x16x32_bf16 v[100:103], v[128:131], v[204:207], v[100:103]
	v_mfma_f32_16x16x32_bf16 v[96:99], v[136:139], v[204:207], v[96:99]
	v_mfma_f32_16x16x32_bf16 v[124:127], v[132:135], v[184:187], v[124:127]
	v_mfma_f32_16x16x32_bf16 v[120:123], v[140:143], v[184:187], v[120:123]
	v_mfma_f32_16x16x32_bf16 v[116:119], v[132:135], v[192:195], v[116:119]
	v_mfma_f32_16x16x32_bf16 v[112:115], v[140:143], v[192:195], v[112:115]
	v_mfma_f32_16x16x32_bf16 v[108:111], v[132:135], v[200:203], v[108:111]
	v_mfma_f32_16x16x32_bf16 v[104:107], v[140:143], v[200:203], v[104:107]
	v_mfma_f32_16x16x32_bf16 v[100:103], v[132:135], v[208:211], v[100:103]
	v_mfma_f32_16x16x32_bf16 v[96:99], v[140:143], v[208:211], v[96:99]
	s_setprio 0
	s_setprio 1
	v_mfma_f32_16x16x32_bf16 v[60:63], v[158:161], v[180:183], v[60:63]
	v_mfma_f32_16x16x32_bf16 v[56:59], v[172:175], v[180:183], v[56:59]
	v_mfma_f32_16x16x32_bf16 v[52:55], v[158:161], v[188:191], v[52:55]
	v_mfma_f32_16x16x32_bf16 v[48:51], v[172:175], v[188:191], v[48:51]
	v_mfma_f32_16x16x32_bf16 v[44:47], v[158:161], v[196:199], v[44:47]
	v_mfma_f32_16x16x32_bf16 v[40:43], v[172:175], v[196:199], v[40:43]
	v_mfma_f32_16x16x32_bf16 v[36:39], v[158:161], v[204:207], v[36:39]
	v_mfma_f32_16x16x32_bf16 v[32:35], v[172:175], v[204:207], v[32:35]
	v_mfma_f32_16x16x32_bf16 v[60:63], v[162:165], v[184:187], v[60:63]
	v_mfma_f32_16x16x32_bf16 v[56:59], v[176:179], v[184:187], v[56:59]
	v_mfma_f32_16x16x32_bf16 v[52:55], v[162:165], v[192:195], v[52:55]
	v_mfma_f32_16x16x32_bf16 v[48:51], v[176:179], v[192:195], v[48:51]
	v_mfma_f32_16x16x32_bf16 v[44:47], v[162:165], v[200:203], v[44:47]
	v_mfma_f32_16x16x32_bf16 v[40:43], v[176:179], v[200:203], v[40:43]
	v_mfma_f32_16x16x32_bf16 v[36:39], v[162:165], v[208:211], v[36:39]
	v_mfma_f32_16x16x32_bf16 v[32:35], v[176:179], v[208:211], v[32:35]
	s_setprio 0
	s_barrier
	s_add_i32 s72, s56, s48
	v_lshl_add_u64 v[144:145], s[14:15], 0, v[148:149]
	s_mov_b32 m0, s72
	ds_read_b128 v[180:183], v171 offset:16384
	ds_read_b128 v[184:187], v171 offset:17408
	ds_read_b128 v[188:191], v171 offset:18432
	ds_read_b128 v[192:195], v171 offset:19456
	ds_read_b128 v[196:199], v171 offset:20480
	ds_read_b128 v[200:203], v171 offset:21504
	ds_read_b128 v[204:207], v171 offset:22528
	ds_read_b128 v[208:211], v171 offset:23552
	global_load_lds_dwordx4 v[144:145], off
	s_add_i32 m0, s72, 0x2000
	s_add_u32 s72, s14, 0x40000
	v_lshl_add_u64 v[166:167], s[14:15], 0, v[152:153]
	s_addc_u32 s73, s15, 0
	s_add_i32 s74, s57, s48
	global_load_lds_dwordx4 v[166:167], off
	v_lshl_add_u64 v[212:213], s[72:73], 0, v[148:149]
	s_mov_b32 m0, s74
	v_lshl_add_u64 v[214:215], s[46:47], 0, v[150:151]
	global_load_lds_dwordx4 v[212:213], off
	v_lshl_add_u64 v[212:213], s[72:73], 0, v[152:153]
	s_add_i32 m0, s74, 0x2000
	s_nop 0
	global_load_lds_dwordx4 v[212:213], off
	v_lshl_add_u64 v[212:213], s[46:47], 0, v[146:147]
	s_mov_b32 m0, s43
	s_nop 0
	global_load_lds_dwordx4 v[212:213], off
	s_mov_b32 m0, s49
	s_nop 0
	global_load_lds_dwordx4 v[214:215], off
	s_waitcnt vmcnt(8)
	s_waitcnt lgkmcnt(0)
	s_barrier
	s_setprio 1
	v_mfma_f32_16x16x32_bf16 v[92:95], v[128:131], v[180:183], v[92:95]
	v_mfma_f32_16x16x32_bf16 v[88:91], v[136:139], v[180:183], v[88:91]
	v_mfma_f32_16x16x32_bf16 v[84:87], v[128:131], v[188:191], v[84:87]
	v_mfma_f32_16x16x32_bf16 v[80:83], v[136:139], v[188:191], v[80:83]
	v_mfma_f32_16x16x32_bf16 v[76:79], v[128:131], v[196:199], v[76:79]
	v_mfma_f32_16x16x32_bf16 v[72:75], v[136:139], v[196:199], v[72:75]
	v_mfma_f32_16x16x32_bf16 v[68:71], v[128:131], v[204:207], v[68:71]
	v_mfma_f32_16x16x32_bf16 v[64:67], v[136:139], v[204:207], v[64:67]
	v_mfma_f32_16x16x32_bf16 v[92:95], v[132:135], v[184:187], v[92:95]
	v_mfma_f32_16x16x32_bf16 v[88:91], v[140:143], v[184:187], v[88:91]
	v_mfma_f32_16x16x32_bf16 v[84:87], v[132:135], v[192:195], v[84:87]
	v_mfma_f32_16x16x32_bf16 v[80:83], v[140:143], v[192:195], v[80:83]
	v_mfma_f32_16x16x32_bf16 v[76:79], v[132:135], v[200:203], v[76:79]
	v_mfma_f32_16x16x32_bf16 v[72:75], v[140:143], v[200:203], v[72:75]
	v_mfma_f32_16x16x32_bf16 v[68:71], v[132:135], v[208:211], v[68:71]
	v_mfma_f32_16x16x32_bf16 v[64:67], v[140:143], v[208:211], v[64:67]
	s_setprio 0
	s_setprio 1
	v_mfma_f32_16x16x32_bf16 v[28:31], v[158:161], v[180:183], v[28:31]
	v_mfma_f32_16x16x32_bf16 v[24:27], v[172:175], v[180:183], v[24:27]
	v_mfma_f32_16x16x32_bf16 v[20:23], v[158:161], v[188:191], v[20:23]
	v_mfma_f32_16x16x32_bf16 v[16:19], v[172:175], v[188:191], v[16:19]
	v_mfma_f32_16x16x32_bf16 v[12:15], v[158:161], v[196:199], v[12:15]
	v_mfma_f32_16x16x32_bf16 v[8:11], v[172:175], v[196:199], v[8:11]
	v_mfma_f32_16x16x32_bf16 v[4:7], v[158:161], v[204:207], v[4:7]
	v_mfma_f32_16x16x32_bf16 v[0:3], v[172:175], v[204:207], v[0:3]
	v_mfma_f32_16x16x32_bf16 v[28:31], v[162:165], v[184:187], v[28:31]
	v_mfma_f32_16x16x32_bf16 v[24:27], v[176:179], v[184:187], v[24:27]
	v_mfma_f32_16x16x32_bf16 v[20:23], v[162:165], v[192:195], v[20:23]
	v_mfma_f32_16x16x32_bf16 v[16:19], v[176:179], v[192:195], v[16:19]
	v_mfma_f32_16x16x32_bf16 v[12:15], v[162:165], v[200:203], v[12:15]
	v_mfma_f32_16x16x32_bf16 v[8:11], v[176:179], v[200:203], v[8:11]
	v_mfma_f32_16x16x32_bf16 v[4:7], v[162:165], v[208:211], v[4:7]
	v_mfma_f32_16x16x32_bf16 v[0:3], v[176:179], v[208:211], v[0:3]
	s_setprio 0
	s_barrier
; #define G_STAGE(bufoff, gbase, voff) do { _Pragma("unroll") for (int _i = 0; _i < 2; ++_i) \
;         __builtin_amdgcn_global_load_lds((const unsigned*)((const char*)(gbase) + voff[_i]), (LAS unsigned*)(lds + (bufoff) + ldsw + _i * 8192), 16, 0, 0); } while (0)
; #define G_LDA(dst, b, h) do { _Pragma("unroll") for (int m = 0; m < 4; ++m) _Pragma("unroll") for (int k = 0; k < 2; ++k) dst[m][k] = *(const LAS bf16x8*)(lds + G_SA(b, h) + aoff + m * 2048 + k * 1024); } while (0)
; #define G_LDB(dst, b, h) do { _Pragma("unroll") for (int n = 0; n < 2; ++n) _Pragma("unroll") for (int k = 0; k < 2; ++k) dst[n][k] = *(const LAS bf16x8*)(lds + G_SB(b, h) + boff + n * 2048 + k * 1024); } while (0)
; #define G_MMA(ai, bj, At_, Bt_) do { __builtin_amdgcn_s_setprio(1); _Pragma("unroll") for (int m = 0; m < 4; ++m) _Pragma("unroll") for (int n = 0; n < 2; ++n) _Pragma("unroll") for (int k = 0; k < 2; ++k) \
;         acc[ai][bj][m][n] = __builtin_amdgcn_mfma_f32_16x16x32_bf16(Bt_[n][k], At_[m][k], acc[ai][bj][m][n], 0, 0, 0); __builtin_amdgcn_s_setprio(0); } while (0)
; #define WAIT_V(n) asm volatile("s_waitcnt vmcnt(" #n ")" ::: "memory")
; #define WAIT_L(n) asm volatile("s_waitcnt lgkmcnt(" #n ")" ::: "memory")
; #define BAR __builtin_amdgcn_s_barrier()
; #define SCHED __builtin_amdgcn_sched_barrier(0)
; template <class Get, class Epi>
; DI void gemm_loop(int ntiles, int ld, char* shm, const Get& get, const Epi& epi) {
;     ...
;             G_LDB(B0, 1, 0); G_LDB(B1, 1, 1); SCHED; G_LDA(At, 1, 0); G_STAGE(G_SA(0, 1), a2 + hstep, voffA);
;             WAIT_V(8); WAIT_L(0); BAR; G_MMA(0, 0, At, B0); G_MMA(0, 1, At, B1); BAR; SCHED;
	s_add_i32 s72, 0, 0x18000
	s_add_i32 s73, 0, 0x1c000
	v_add_u32_e32 v140, s72, v168
	v_add_u32_e32 v176, s73, v168
	ds_read_b128 v[128:131], v140
	ds_read_b128 v[132:135], v140 offset:1024
	ds_read_b128 v[136:139], v140 offset:2048
	ds_read_b128 v[140:143], v140 offset:3072
	ds_read_b128 v[158:161], v176
	ds_read_b128 v[162:165], v176 offset:1024
	ds_read_b128 v[172:175], v176 offset:2048
	ds_read_b128 v[176:179], v176 offset:3072
	s_add_u32 s46, s46, 0x40000
	s_addc_u32 s47, s47, 0
	s_mov_b32 m0, s50
	v_lshl_add_u64 v[216:217], s[46:47], 0, v[146:147]
	ds_read_b128 v[180:183], v171 offset:32768
	ds_read_b128 v[184:187], v171 offset:33792
	ds_read_b128 v[188:191], v171 offset:34816
	ds_read_b128 v[192:195], v171 offset:35840
	ds_read_b128 v[196:199], v171 offset:36864
	ds_read_b128 v[200:203], v171 offset:37888
	ds_read_b128 v[204:207], v171 offset:38912
	ds_read_b128 v[208:211], v171 offset:39936
	global_load_lds_dwordx4 v[216:217], off
	v_lshl_add_u64 v[216:217], s[46:47], 0, v[150:151]
	s_mov_b32 m0, s51
	s_nop 0
	global_load_lds_dwordx4 v[216:217], off
	s_waitcnt vmcnt(8)
	s_waitcnt lgkmcnt(0)
	s_barrier
	s_setprio 1
	v_mfma_f32_16x16x32_bf16 v[124:127], v[128:131], v[180:183], v[124:127]
	v_mfma_f32_16x16x32_bf16 v[120:123], v[136:139], v[180:183], v[120:123]
	v_mfma_f32_16x16x32_bf16 v[116:119], v[128:131], v[188:191], v[116:119]
	v_mfma_f32_16x16x32_bf16 v[112:115], v[136:139], v[188:191], v[112:115]
	v_mfma_f32_16x16x32_bf16 v[108:111], v[128:131], v[196:199], v[108:111]
	v_mfma_f32_16x16x32_bf16 v[104:107], v[136:139], v[196:199], v[104:107]
	v_mfma_f32_16x16x32_bf16 v[100:103], v[128:131], v[204:207], v[100:103]
	v_mfma_f32_16x16x32_bf16 v[96:99], v[136:139], v[204:207], v[96:99]
	v_mfma_f32_16x16x32_bf16 v[124:127], v[132:135], v[184:187], v[124:127]
	v_mfma_f32_16x16x32_bf16 v[120:123], v[140:143], v[184:187], v[120:123]
	v_mfma_f32_16x16x32_bf16 v[116:119], v[132:135], v[192:195], v[116:119]
	v_mfma_f32_16x16x32_bf16 v[112:115], v[140:143], v[192:195], v[112:115]
	v_mfma_f32_16x16x32_bf16 v[108:111], v[132:135], v[200:203], v[108:111]
	v_mfma_f32_16x16x32_bf16 v[104:107], v[140:143], v[200:203], v[104:107]
	v_mfma_f32_16x16x32_bf16 v[100:103], v[132:135], v[208:211], v[100:103]
	v_mfma_f32_16x16x32_bf16 v[96:99], v[140:143], v[208:211], v[96:99]
	s_setprio 0
	s_setprio 1
	v_mfma_f32_16x16x32_bf16 v[60:63], v[158:161], v[180:183], v[60:63]
	v_mfma_f32_16x16x32_bf16 v[56:59], v[172:175], v[180:183], v[56:59]
	v_mfma_f32_16x16x32_bf16 v[52:55], v[158:161], v[188:191], v[52:55]
	v_mfma_f32_16x16x32_bf16 v[48:51], v[172:175], v[188:191], v[48:51]
	v_mfma_f32_16x16x32_bf16 v[44:47], v[158:161], v[196:199], v[44:47]
	v_mfma_f32_16x16x32_bf16 v[40:43], v[172:175], v[196:199], v[40:43]
	v_mfma_f32_16x16x32_bf16 v[36:39], v[158:161], v[204:207], v[36:39]
	v_mfma_f32_16x16x32_bf16 v[32:35], v[172:175], v[204:207], v[32:35]
	v_mfma_f32_16x16x32_bf16 v[60:63], v[162:165], v[184:187], v[60:63]
	v_mfma_f32_16x16x32_bf16 v[56:59], v[176:179], v[184:187], v[56:59]
	v_mfma_f32_16x16x32_bf16 v[52:55], v[162:165], v[192:195], v[52:55]
	v_mfma_f32_16x16x32_bf16 v[48:51], v[176:179], v[192:195], v[48:51]
	v_mfma_f32_16x16x32_bf16 v[44:47], v[162:165], v[200:203], v[44:47]
	v_mfma_f32_16x16x32_bf16 v[40:43], v[176:179], v[200:203], v[40:43]
	v_mfma_f32_16x16x32_bf16 v[36:39], v[162:165], v[208:211], v[36:39]
	v_mfma_f32_16x16x32_bf16 v[32:35], v[176:179], v[208:211], v[32:35]
	s_setprio 0
	s_barrier
; #define G_STAGE(bufoff, gbase, voff) do { _Pragma("unroll") for (int _i = 0; _i < 2; ++_i) \
;         __builtin_amdgcn_global_load_lds((const unsigned*)((const char*)(gbase) + voff[_i]), (LAS unsigned*)(lds + (bufoff) + ldsw + _i * 8192), 16, 0, 0); } while (0)
; #define G_LDA(dst, b, h) do { _Pragma("unroll") for (int m = 0; m < 4; ++m) _Pragma("unroll") for (int k = 0; k < 2; ++k) dst[m][k] = *(const LAS bf16x8*)(lds + G_SA(b, h) + aoff + m * 2048 + k * 1024); } while (0)
; #define G_MMA(ai, bj, At_, Bt_) do { __builtin_amdgcn_s_setprio(1); _Pragma("unroll") for (int m = 0; m < 4; ++m) _Pragma("unroll") for (int n = 0; n < 2; ++n) _Pragma("unroll") for (int k = 0; k < 2; ++k) \
;         acc[ai][bj][m][n] = __builtin_amdgcn_mfma_f32_16x16x32_bf16(Bt_[n][k], At_[m][k], acc[ai][bj][m][n], 0, 0, 0); __builtin_amdgcn_s_setprio(0); } while (0)
; #define WAIT_V(n) asm volatile("s_waitcnt vmcnt(" #n ")" ::: "memory")
; #define WAIT_L(n) asm volatile("s_waitcnt lgkmcnt(" #n ")" ::: "memory")
; #define BAR __builtin_amdgcn_s_barrier()
; #define SCHED __builtin_amdgcn_sched_barrier(0)
; template <class Get, class Epi>
; DI void gemm_loop(int ntiles, int ld, char* shm, const Get& get, const Epi& epi) {
;     ...
;             G_LDA(At, 1, 1); G_STAGE(G_SB(1, 0), b3, voffB); G_STAGE(G_SB(1, 1), b3 + hstep, voffB); G_STAGE(G_SA(1, 0), a3, voffA);
;             WAIT_V(8); WAIT_L(0); BAR; G_MMA(1, 0, At, B0); G_MMA(1, 1, At, B1); BAR; SCHED;
;         }
	s_add_i32 s46, s72, s48
	v_lshl_add_u64 v[144:145], v[144:145], 0, s[4:5]
	s_mov_b32 m0, s46
	ds_read_b128 v[180:183], v171 offset:49152
	ds_read_b128 v[184:187], v171 offset:50176
	ds_read_b128 v[188:191], v171 offset:51200
	ds_read_b128 v[192:195], v171 offset:52224
	ds_read_b128 v[196:199], v171 offset:53248
	ds_read_b128 v[200:203], v171 offset:54272
	ds_read_b128 v[204:207], v171 offset:55296
	ds_read_b128 v[208:211], v171 offset:56320
	global_load_lds_dwordx4 v[144:145], off
	s_add_i32 m0, s46, 0x2000
	s_add_u32 s14, s14, 0x40080
	v_lshl_add_u64 v[144:145], v[166:167], 0, s[4:5]
	s_addc_u32 s15, s15, 0
	s_add_i32 s46, s73, s48
	global_load_lds_dwordx4 v[144:145], off
	v_lshl_add_u64 v[144:145], s[14:15], 0, v[148:149]
	s_mov_b32 m0, s46
	s_nop 0
	global_load_lds_dwordx4 v[144:145], off
	v_lshl_add_u64 v[144:145], s[14:15], 0, v[152:153]
	s_add_i32 m0, s46, 0x2000
	s_nop 0
	global_load_lds_dwordx4 v[144:145], off
	v_lshl_add_u64 v[144:145], v[212:213], 0, s[4:5]
	s_mov_b32 m0, s54
	s_nop 0
	global_load_lds_dwordx4 v[144:145], off
	v_lshl_add_u64 v[144:145], v[214:215], 0, s[4:5]
	s_mov_b32 m0, s55
	s_nop 0
	global_load_lds_dwordx4 v[144:145], off
	s_waitcnt vmcnt(8)
	s_waitcnt lgkmcnt(0)
	s_barrier
	s_setprio 1
	v_mfma_f32_16x16x32_bf16 v[92:95], v[128:131], v[180:183], v[92:95]
	v_mfma_f32_16x16x32_bf16 v[88:91], v[136:139], v[180:183], v[88:91]
	v_mfma_f32_16x16x32_bf16 v[84:87], v[128:131], v[188:191], v[84:87]
	v_mfma_f32_16x16x32_bf16 v[80:83], v[136:139], v[188:191], v[80:83]
	v_mfma_f32_16x16x32_bf16 v[76:79], v[128:131], v[196:199], v[76:79]
	v_mfma_f32_16x16x32_bf16 v[72:75], v[136:139], v[196:199], v[72:75]
	v_mfma_f32_16x16x32_bf16 v[68:71], v[128:131], v[204:207], v[68:71]
	v_mfma_f32_16x16x32_bf16 v[64:67], v[136:139], v[204:207], v[64:67]
	v_mfma_f32_16x16x32_bf16 v[92:95], v[132:135], v[184:187], v[92:95]
	v_mfma_f32_16x16x32_bf16 v[88:91], v[140:143], v[184:187], v[88:91]
	v_mfma_f32_16x16x32_bf16 v[84:87], v[132:135], v[192:195], v[84:87]
	v_mfma_f32_16x16x32_bf16 v[80:83], v[140:143], v[192:195], v[80:83]
	v_mfma_f32_16x16x32_bf16 v[76:79], v[132:135], v[200:203], v[76:79]
	v_mfma_f32_16x16x32_bf16 v[72:75], v[140:143], v[200:203], v[72:75]
	v_mfma_f32_16x16x32_bf16 v[68:71], v[132:135], v[208:211], v[68:71]
	v_mfma_f32_16x16x32_bf16 v[64:67], v[140:143], v[208:211], v[64:67]
	s_setprio 0
	s_setprio 1
	v_mfma_f32_16x16x32_bf16 v[28:31], v[158:161], v[180:183], v[28:31]
	v_mfma_f32_16x16x32_bf16 v[24:27], v[172:175], v[180:183], v[24:27]
	v_mfma_f32_16x16x32_bf16 v[20:23], v[158:161], v[188:191], v[20:23]
	v_mfma_f32_16x16x32_bf16 v[16:19], v[172:175], v[188:191], v[16:19]
	v_mfma_f32_16x16x32_bf16 v[12:15], v[158:161], v[196:199], v[12:15]
	v_mfma_f32_16x16x32_bf16 v[8:11], v[172:175], v[196:199], v[8:11]
	v_mfma_f32_16x16x32_bf16 v[4:7], v[158:161], v[204:207], v[4:7]
	v_mfma_f32_16x16x32_bf16 v[0:3], v[172:175], v[204:207], v[0:3]
	v_mfma_f32_16x16x32_bf16 v[28:31], v[162:165], v[184:187], v[28:31]
	v_mfma_f32_16x16x32_bf16 v[24:27], v[176:179], v[184:187], v[24:27]
	v_mfma_f32_16x16x32_bf16 v[20:23], v[162:165], v[192:195], v[20:23]
	v_mfma_f32_16x16x32_bf16 v[16:19], v[176:179], v[192:195], v[16:19]
	v_mfma_f32_16x16x32_bf16 v[12:15], v[162:165], v[200:203], v[12:15]
	v_mfma_f32_16x16x32_bf16 v[8:11], v[176:179], v[200:203], v[8:11]
	v_mfma_f32_16x16x32_bf16 v[4:7], v[162:165], v[208:211], v[4:7]
	v_mfma_f32_16x16x32_bf16 v[0:3], v[176:179], v[208:211], v[0:3]
	s_setprio 0
	s_barrier
	s_add_i32 s71, s71, 2
	s_add_u32 s44, s44, 0x100
	s_addc_u32 s45, s45, 0
	s_add_u32 s65, s65, 0x100
	s_addc_u32 s70, s70, 0
	s_cmp_gt_u32 s71, 13
	s_cbranch_scc0 .LBB0_3466

; #define G_STAGE(bufoff, gbase, voff) do { _Pragma("unroll") for (int _i = 0; _i < 2; ++_i) \
;         __builtin_amdgcn_global_load_lds((const unsigned*)((const char*)(gbase) + voff[_i]), (LAS unsigned*)(lds + (bufoff) + ldsw + _i * 8192), 16, 0, 0); } while (0)
; #define G_LDA(dst, b, h) do { _Pragma("unroll") for (int m = 0; m < 4; ++m) _Pragma("unroll") for (int k = 0; k < 2; ++k) dst[m][k] = *(const LAS bf16x8*)(lds + G_SA(b, h) + aoff + m * 2048 + k * 1024); } while (0)
; #define G_MMA(ai, bj, At_, Bt_) do { __builtin_amdgcn_s_setprio(1); _Pragma("unroll") for (int m = 0; m < 4; ++m) _Pragma("unroll") for (int n = 0; n < 2; ++n) _Pragma("unroll") for (int k = 0; k < 2; ++k) \
;         acc[ai][bj][m][n] = __builtin_amdgcn_mfma_f32_16x16x32_bf16(Bt_[n][k], At_[m][k], acc[ai][bj][m][n], 0, 0, 0); __builtin_amdgcn_s_setprio(0); } while (0)
; #define WAIT_V(n) asm volatile("s_waitcnt vmcnt(" #n ")" ::: "memory")
; #define WAIT_L(n) asm volatile("s_waitcnt lgkmcnt(" #n ")" ::: "memory")
; #define BAR __builtin_amdgcn_s_barrier()
; #define SCHED __builtin_amdgcn_sched_barrier(0)
; template <class Get, class Epi>
; DI void gemm_loop(int ntiles, int ld, char* shm, const Get& get, const Epi& epi) {
;     ...
;             WAIT_V(8); WAIT_L(0); BAR; G_MMA(0, 0, At, B0); G_MMA(0, 1, At, B1); BAR; SCHED;
;             G_LDA(At, 0, 1); G_STAGE(G_SB(0, 0), b2, voffB); G_STAGE(G_SB(0, 1), b2 + hstep, voffB); G_STAGE(G_SA(0, 0), a2, voffA);
.Lrj_3679_0:
	s_waitcnt lgkmcnt(0)
	s_barrier
	s_setprio 1
	v_mfma_f32_16x16x32_bf16 v[124:127], v[144:147], v[176:179], 0
	v_mfma_f32_16x16x32_bf16 v[120:123], v[152:155], v[176:179], 0
	v_mfma_f32_16x16x32_bf16 v[108:111], v[144:147], v[184:187], 0
	v_mfma_f32_16x16x32_bf16 v[104:107], v[152:155], v[184:187], 0
	v_mfma_f32_16x16x32_bf16 v[92:95], v[144:147], v[192:195], 0
	v_mfma_f32_16x16x32_bf16 v[88:91], v[152:155], v[192:195], 0
	v_mfma_f32_16x16x32_bf16 v[76:79], v[144:147], v[200:203], 0
	v_mfma_f32_16x16x32_bf16 v[72:75], v[152:155], v[200:203], 0
	v_mfma_f32_16x16x32_bf16 v[124:127], v[148:151], v[180:183], v[124:127]
	v_mfma_f32_16x16x32_bf16 v[120:123], v[156:159], v[180:183], v[120:123]
	v_mfma_f32_16x16x32_bf16 v[108:111], v[148:151], v[188:191], v[108:111]
	v_mfma_f32_16x16x32_bf16 v[104:107], v[156:159], v[188:191], v[104:107]
	v_mfma_f32_16x16x32_bf16 v[92:95], v[148:151], v[196:199], v[92:95]
	v_mfma_f32_16x16x32_bf16 v[88:91], v[156:159], v[196:199], v[88:91]
	v_mfma_f32_16x16x32_bf16 v[76:79], v[148:151], v[204:207], v[76:79]
	v_mfma_f32_16x16x32_bf16 v[72:75], v[156:159], v[204:207], v[72:75]
	s_setprio 0
	s_setprio 1
	v_mfma_f32_16x16x32_bf16 v[116:119], v[160:163], v[176:179], 0
	v_mfma_f32_16x16x32_bf16 v[112:115], v[168:171], v[176:179], 0
	v_mfma_f32_16x16x32_bf16 v[100:103], v[160:163], v[184:187], 0
	v_mfma_f32_16x16x32_bf16 v[96:99], v[168:171], v[184:187], 0
	v_mfma_f32_16x16x32_bf16 v[84:87], v[160:163], v[192:195], 0
	v_mfma_f32_16x16x32_bf16 v[80:83], v[168:171], v[192:195], 0
	v_mfma_f32_16x16x32_bf16 v[68:71], v[160:163], v[200:203], 0
	v_mfma_f32_16x16x32_bf16 v[64:67], v[168:171], v[200:203], 0
	v_mfma_f32_16x16x32_bf16 v[116:119], v[164:167], v[180:183], v[116:119]
	v_mfma_f32_16x16x32_bf16 v[112:115], v[172:175], v[180:183], v[112:115]
	v_mfma_f32_16x16x32_bf16 v[100:103], v[164:167], v[188:191], v[100:103]
	v_mfma_f32_16x16x32_bf16 v[96:99], v[172:175], v[188:191], v[96:99]
	v_mfma_f32_16x16x32_bf16 v[84:87], v[164:167], v[196:199], v[84:87]
	v_mfma_f32_16x16x32_bf16 v[80:83], v[172:175], v[196:199], v[80:83]
	v_mfma_f32_16x16x32_bf16 v[68:71], v[164:167], v[204:207], v[68:71]
	v_mfma_f32_16x16x32_bf16 v[64:67], v[172:175], v[204:207], v[64:67]
	s_setprio 0
	s_barrier
	s_add_i32 s54, s44, s38
	v_lshl_add_u64 v[208:209], s[14:15], 0, v[132:133]
	s_mov_b32 m0, s54
	ds_read_b128 v[176:179], v143 offset:16384
	ds_read_b128 v[180:183], v143 offset:17408
	ds_read_b128 v[184:187], v143 offset:18432
	ds_read_b128 v[188:191], v143 offset:19456
	ds_read_b128 v[192:195], v143 offset:20480
	ds_read_b128 v[196:199], v143 offset:21504
	ds_read_b128 v[200:203], v143 offset:22528
	ds_read_b128 v[204:207], v143 offset:23552
	global_load_lds_dwordx4 v[208:209], off
	s_add_i32 m0, s54, 0x2000
	s_add_u32 s54, s14, 0x40000
	v_lshl_add_u64 v[210:211], s[14:15], 0, v[128:129]
	s_addc_u32 s55, s15, 0
	s_add_i32 s56, s45, s38
	global_load_lds_dwordx4 v[210:211], off
	v_lshl_add_u64 v[212:213], s[54:55], 0, v[132:133]
	s_mov_b32 m0, s56
	v_lshl_add_u64 v[214:215], s[36:37], 0, v[130:131]
	global_load_lds_dwordx4 v[212:213], off
	v_lshl_add_u64 v[212:213], s[54:55], 0, v[128:129]
	s_add_i32 m0, s56, 0x2000
	s_nop 0
	global_load_lds_dwordx4 v[212:213], off
	v_lshl_add_u64 v[212:213], s[36:37], 0, v[134:135]
	s_mov_b32 m0, s25
	s_nop 0
	global_load_lds_dwordx4 v[212:213], off
	s_mov_b32 m0, s31
	s_nop 0
	global_load_lds_dwordx4 v[214:215], off
	s_cmp_lg_u32 s100, 0
	s_cbranch_scc0 .Lrf_3679_1
	s_waitcnt vmcnt(16)
	s_branch .Lrj_3679_1

; #define G_STAGE(bufoff, gbase, voff) do { _Pragma("unroll") for (int _i = 0; _i < 2; ++_i) \
;         __builtin_amdgcn_global_load_lds((const unsigned*)((const char*)(gbase) + voff[_i]), (LAS unsigned*)(lds + (bufoff) + ldsw + _i * 8192), 16, 0, 0); } while (0)
; #define G_LDA(dst, b, h) do { _Pragma("unroll") for (int m = 0; m < 4; ++m) _Pragma("unroll") for (int k = 0; k < 2; ++k) dst[m][k] = *(const LAS bf16x8*)(lds + G_SA(b, h) + aoff + m * 2048 + k * 1024); } while (0)
; #define G_LDB(dst, b, h) do { _Pragma("unroll") for (int n = 0; n < 2; ++n) _Pragma("unroll") for (int k = 0; k < 2; ++k) dst[n][k] = *(const LAS bf16x8*)(lds + G_SB(b, h) + boff + n * 2048 + k * 1024); } while (0)
; #define G_MMA(ai, bj, At_, Bt_) do { __builtin_amdgcn_s_setprio(1); _Pragma("unroll") for (int m = 0; m < 4; ++m) _Pragma("unroll") for (int n = 0; n < 2; ++n) _Pragma("unroll") for (int k = 0; k < 2; ++k) \
;         acc[ai][bj][m][n] = __builtin_amdgcn_mfma_f32_16x16x32_bf16(Bt_[n][k], At_[m][k], acc[ai][bj][m][n], 0, 0, 0); __builtin_amdgcn_s_setprio(0); } while (0)
; #define WAIT_V(n) asm volatile("s_waitcnt vmcnt(" #n ")" ::: "memory")
; #define WAIT_L(n) asm volatile("s_waitcnt lgkmcnt(" #n ")" ::: "memory")
; #define BAR __builtin_amdgcn_s_barrier()
; #define SCHED __builtin_amdgcn_sched_barrier(0)
; template <class Get, class Epi>
; DI void gemm_loop(int ntiles, int ld, char* shm, const Get& get, const Epi& epi) {
;     ...
;             WAIT_V(8); WAIT_L(0); BAR; G_MMA(1, 0, At, B0); G_MMA(1, 1, At, B1); BAR; SCHED;
;             G_LDB(B0, 1, 0); G_LDB(B1, 1, 1); SCHED; G_LDA(At, 1, 0); G_STAGE(G_SA(0, 1), a2 + hstep, voffA);
;             WAIT_V(8); WAIT_L(0); BAR; G_MMA(0, 0, At, B0); G_MMA(0, 1, At, B1); BAR; SCHED;
.Lrj_3679_1:
	s_waitcnt lgkmcnt(0)
	s_barrier
	s_setprio 1
	v_mfma_f32_16x16x32_bf16 v[60:63], v[144:147], v[176:179], 0
	v_mfma_f32_16x16x32_bf16 v[56:59], v[152:155], v[176:179], 0
	v_mfma_f32_16x16x32_bf16 v[44:47], v[144:147], v[184:187], 0
	v_mfma_f32_16x16x32_bf16 v[40:43], v[152:155], v[184:187], 0
	v_mfma_f32_16x16x32_bf16 v[28:31], v[144:147], v[192:195], 0
	v_mfma_f32_16x16x32_bf16 v[24:27], v[152:155], v[192:195], 0
	v_mfma_f32_16x16x32_bf16 v[12:15], v[144:147], v[200:203], 0
	v_mfma_f32_16x16x32_bf16 v[8:11], v[152:155], v[200:203], 0
	v_mfma_f32_16x16x32_bf16 v[60:63], v[148:151], v[180:183], v[60:63]
	v_mfma_f32_16x16x32_bf16 v[56:59], v[156:159], v[180:183], v[56:59]
	v_mfma_f32_16x16x32_bf16 v[44:47], v[148:151], v[188:191], v[44:47]
	v_mfma_f32_16x16x32_bf16 v[40:43], v[156:159], v[188:191], v[40:43]
	v_mfma_f32_16x16x32_bf16 v[28:31], v[148:151], v[196:199], v[28:31]
	v_mfma_f32_16x16x32_bf16 v[24:27], v[156:159], v[196:199], v[24:27]
	v_mfma_f32_16x16x32_bf16 v[12:15], v[148:151], v[204:207], v[12:15]
	v_mfma_f32_16x16x32_bf16 v[8:11], v[156:159], v[204:207], v[8:11]
	s_setprio 0
	s_setprio 1
	v_mfma_f32_16x16x32_bf16 v[52:55], v[160:163], v[176:179], 0
	v_mfma_f32_16x16x32_bf16 v[48:51], v[168:171], v[176:179], 0
	v_mfma_f32_16x16x32_bf16 v[36:39], v[160:163], v[184:187], 0
	v_mfma_f32_16x16x32_bf16 v[32:35], v[168:171], v[184:187], 0
	v_mfma_f32_16x16x32_bf16 v[20:23], v[160:163], v[192:195], 0
	v_mfma_f32_16x16x32_bf16 v[16:19], v[168:171], v[192:195], 0
	v_mfma_f32_16x16x32_bf16 v[4:7], v[160:163], v[200:203], 0
	v_mfma_f32_16x16x32_bf16 v[0:3], v[168:171], v[200:203], 0
	v_mfma_f32_16x16x32_bf16 v[52:55], v[164:167], v[180:183], v[52:55]
	v_mfma_f32_16x16x32_bf16 v[48:51], v[172:175], v[180:183], v[48:51]
	v_mfma_f32_16x16x32_bf16 v[36:39], v[164:167], v[188:191], v[36:39]
	v_mfma_f32_16x16x32_bf16 v[32:35], v[172:175], v[188:191], v[32:35]
	v_mfma_f32_16x16x32_bf16 v[20:23], v[164:167], v[196:199], v[20:23]
	v_mfma_f32_16x16x32_bf16 v[16:19], v[172:175], v[196:199], v[16:19]
	v_mfma_f32_16x16x32_bf16 v[4:7], v[164:167], v[204:207], v[4:7]
	v_mfma_f32_16x16x32_bf16 v[0:3], v[172:175], v[204:207], v[0:3]
	s_setprio 0
	s_barrier
	s_add_i32 s54, 0, 0x18000
	s_add_i32 s55, 0, 0x1c000
	v_add_u32_e32 v156, s54, v140
	v_add_u32_e32 v172, s55, v140
	ds_read_b128 v[144:147], v156
	ds_read_b128 v[148:151], v156 offset:1024
	ds_read_b128 v[152:155], v156 offset:2048
	ds_read_b128 v[156:159], v156 offset:3072
	ds_read_b128 v[160:163], v172
	ds_read_b128 v[164:167], v172 offset:1024
	ds_read_b128 v[168:171], v172 offset:2048
	ds_read_b128 v[172:175], v172 offset:3072
	s_add_u32 s36, s36, 0x40000
	s_addc_u32 s37, s37, 0
	s_mov_b32 m0, s40
	v_lshl_add_u64 v[216:217], s[36:37], 0, v[134:135]
	ds_read_b128 v[176:179], v143 offset:32768
	ds_read_b128 v[180:183], v143 offset:33792
	ds_read_b128 v[184:187], v143 offset:34816
	ds_read_b128 v[188:191], v143 offset:35840
	ds_read_b128 v[192:195], v143 offset:36864
	ds_read_b128 v[196:199], v143 offset:37888
	ds_read_b128 v[200:203], v143 offset:38912
	ds_read_b128 v[204:207], v143 offset:39936
	global_load_lds_dwordx4 v[216:217], off
	v_lshl_add_u64 v[216:217], s[36:37], 0, v[130:131]
	s_mov_b32 m0, s41
	s_nop 0
	global_load_lds_dwordx4 v[216:217], off
	s_waitcnt vmcnt(8)
	s_waitcnt lgkmcnt(0)
	s_barrier
	s_setprio 1
	v_mfma_f32_16x16x32_bf16 v[124:127], v[144:147], v[176:179], v[124:127]
	v_mfma_f32_16x16x32_bf16 v[120:123], v[152:155], v[176:179], v[120:123]
	v_mfma_f32_16x16x32_bf16 v[108:111], v[144:147], v[184:187], v[108:111]
	v_mfma_f32_16x16x32_bf16 v[104:107], v[152:155], v[184:187], v[104:107]
	v_mfma_f32_16x16x32_bf16 v[92:95], v[144:147], v[192:195], v[92:95]
	v_mfma_f32_16x16x32_bf16 v[88:91], v[152:155], v[192:195], v[88:91]
	v_mfma_f32_16x16x32_bf16 v[76:79], v[144:147], v[200:203], v[76:79]
	v_mfma_f32_16x16x32_bf16 v[72:75], v[152:155], v[200:203], v[72:75]
	v_mfma_f32_16x16x32_bf16 v[124:127], v[148:151], v[180:183], v[124:127]
	v_mfma_f32_16x16x32_bf16 v[120:123], v[156:159], v[180:183], v[120:123]
	v_mfma_f32_16x16x32_bf16 v[108:111], v[148:151], v[188:191], v[108:111]
	v_mfma_f32_16x16x32_bf16 v[104:107], v[156:159], v[188:191], v[104:107]
	v_mfma_f32_16x16x32_bf16 v[92:95], v[148:151], v[196:199], v[92:95]
	v_mfma_f32_16x16x32_bf16 v[88:91], v[156:159], v[196:199], v[88:91]
	v_mfma_f32_16x16x32_bf16 v[76:79], v[148:151], v[204:207], v[76:79]
	v_mfma_f32_16x16x32_bf16 v[72:75], v[156:159], v[204:207], v[72:75]
	s_setprio 0
	s_setprio 1
	v_mfma_f32_16x16x32_bf16 v[116:119], v[160:163], v[176:179], v[116:119]
	v_mfma_f32_16x16x32_bf16 v[112:115], v[168:171], v[176:179], v[112:115]
	v_mfma_f32_16x16x32_bf16 v[100:103], v[160:163], v[184:187], v[100:103]
	v_mfma_f32_16x16x32_bf16 v[96:99], v[168:171], v[184:187], v[96:99]
	v_mfma_f32_16x16x32_bf16 v[84:87], v[160:163], v[192:195], v[84:87]
	v_mfma_f32_16x16x32_bf16 v[80:83], v[168:171], v[192:195], v[80:83]
	v_mfma_f32_16x16x32_bf16 v[68:71], v[160:163], v[200:203], v[68:71]
	v_mfma_f32_16x16x32_bf16 v[64:67], v[168:171], v[200:203], v[64:67]
	v_mfma_f32_16x16x32_bf16 v[116:119], v[164:167], v[180:183], v[116:119]
	v_mfma_f32_16x16x32_bf16 v[112:115], v[172:175], v[180:183], v[112:115]
	v_mfma_f32_16x16x32_bf16 v[100:103], v[164:167], v[188:191], v[100:103]
	v_mfma_f32_16x16x32_bf16 v[96:99], v[172:175], v[188:191], v[96:99]
	v_mfma_f32_16x16x32_bf16 v[84:87], v[164:167], v[196:199], v[84:87]
	v_mfma_f32_16x16x32_bf16 v[80:83], v[172:175], v[196:199], v[80:83]
	v_mfma_f32_16x16x32_bf16 v[68:71], v[164:167], v[204:207], v[68:71]
	v_mfma_f32_16x16x32_bf16 v[64:67], v[172:175], v[204:207], v[64:67]
	s_setprio 0
	s_barrier
; #define G_STAGE(bufoff, gbase, voff) do { _Pragma("unroll") for (int _i = 0; _i < 2; ++_i) \
;         __builtin_amdgcn_global_load_lds((const unsigned*)((const char*)(gbase) + voff[_i]), (LAS unsigned*)(lds + (bufoff) + ldsw + _i * 8192), 16, 0, 0); } while (0)
; #define G_LDA(dst, b, h) do { _Pragma("unroll") for (int m = 0; m < 4; ++m) _Pragma("unroll") for (int k = 0; k < 2; ++k) dst[m][k] = *(const LAS bf16x8*)(lds + G_SA(b, h) + aoff + m * 2048 + k * 1024); } while (0)
; #define G_LDB(dst, b, h) do { _Pragma("unroll") for (int n = 0; n < 2; ++n) _Pragma("unroll") for (int k = 0; k < 2; ++k) dst[n][k] = *(const LAS bf16x8*)(lds + G_SB(b, h) + boff + n * 2048 + k * 1024); } while (0)
; #define G_MMA(ai, bj, At_, Bt_) do { __builtin_amdgcn_s_setprio(1); _Pragma("unroll") for (int m = 0; m < 4; ++m) _Pragma("unroll") for (int n = 0; n < 2; ++n) _Pragma("unroll") for (int k = 0; k < 2; ++k) \
;         acc[ai][bj][m][n] = __builtin_amdgcn_mfma_f32_16x16x32_bf16(Bt_[n][k], At_[m][k], acc[ai][bj][m][n], 0, 0, 0); __builtin_amdgcn_s_setprio(0); } while (0)
; #define WAIT_V(n) asm volatile("s_waitcnt vmcnt(" #n ")" ::: "memory")
; #define WAIT_L(n) asm volatile("s_waitcnt lgkmcnt(" #n ")" ::: "memory")
; #define BAR __builtin_amdgcn_s_barrier()
; #define SCHED __builtin_amdgcn_sched_barrier(0)
; template <class Get, class Epi>
; DI void gemm_loop(int ntiles, int ld, char* shm, const Get& get, const Epi& epi) {
;     ...
;             G_LDB(B0, 0, 0); G_LDB(B1, 0, 1); SCHED; G_LDA(At, 0, 0); G_STAGE(G_SA(1, 1), a1 + hstep, voffA);
;             WAIT_V(8); WAIT_L(0); BAR; G_MMA(0, 0, At, B0); G_MMA(0, 1, At, B1); BAR; SCHED;
;             G_LDA(At, 0, 1); G_STAGE(G_SB(0, 0), b2, voffB); G_STAGE(G_SB(0, 1), b2 + hstep, voffB); G_STAGE(G_SA(0, 0), a2, voffA);
;             WAIT_V(8); WAIT_L(0); BAR; G_MMA(1, 0, At, B0); G_MMA(1, 1, At, B1); BAR; SCHED;
;             G_LDB(B0, 1, 0); G_LDB(B1, 1, 1); SCHED; G_LDA(At, 1, 0); G_STAGE(G_SA(0, 1), a2 + hstep, voffA);
;             WAIT_V(8); WAIT_L(0); BAR; G_MMA(0, 0, At, B0); G_MMA(0, 1, At, B1); BAR; SCHED;
;             G_LDA(At, 1, 1); G_STAGE(G_SB(1, 0), b3, voffB); G_STAGE(G_SB(1, 1), b3 + hstep, voffB); G_STAGE(G_SA(1, 0), a3, voffA);
;             WAIT_V(8); WAIT_L(0); BAR; G_MMA(1, 0, At, B0); G_MMA(1, 1, At, B1); BAR; SCHED;
;         }
	s_add_i32 s36, s54, s38
	v_lshl_add_u64 v[208:209], v[208:209], 0, s[2:3]
	s_mov_b32 m0, s36
	ds_read_b128 v[176:179], v143 offset:49152
	ds_read_b128 v[180:183], v143 offset:50176
	ds_read_b128 v[184:187], v143 offset:51200
	ds_read_b128 v[188:191], v143 offset:52224
	ds_read_b128 v[192:195], v143 offset:53248
	ds_read_b128 v[196:199], v143 offset:54272
	ds_read_b128 v[200:203], v143 offset:55296
	ds_read_b128 v[204:207], v143 offset:56320
	global_load_lds_dwordx4 v[208:209], off
	s_add_i32 m0, s36, 0x2000
	s_add_u32 s14, s14, 0x40080
	v_lshl_add_u64 v[208:209], v[210:211], 0, s[2:3]
	s_addc_u32 s15, s15, 0
	s_add_i32 s36, s55, s38
	global_load_lds_dwordx4 v[208:209], off
	v_lshl_add_u64 v[208:209], s[14:15], 0, v[132:133]
	s_mov_b32 m0, s36
	s_nop 0
	global_load_lds_dwordx4 v[208:209], off
	v_lshl_add_u64 v[208:209], s[14:15], 0, v[128:129]
	s_add_i32 m0, s36, 0x2000
	s_nop 0
	global_load_lds_dwordx4 v[208:209], off
	v_lshl_add_u64 v[208:209], v[212:213], 0, s[2:3]
	s_mov_b32 m0, s42
	s_nop 0
	global_load_lds_dwordx4 v[208:209], off
	v_lshl_add_u64 v[208:209], v[214:215], 0, s[2:3]
	s_mov_b32 m0, s43
	s_nop 0
	global_load_lds_dwordx4 v[208:209], off
	s_waitcnt vmcnt(8)
	s_waitcnt lgkmcnt(0)
	s_barrier
	s_setprio 1
	v_mfma_f32_16x16x32_bf16 v[60:63], v[144:147], v[176:179], v[60:63]
	v_mfma_f32_16x16x32_bf16 v[56:59], v[152:155], v[176:179], v[56:59]
	v_mfma_f32_16x16x32_bf16 v[44:47], v[144:147], v[184:187], v[44:47]
	v_mfma_f32_16x16x32_bf16 v[40:43], v[152:155], v[184:187], v[40:43]
	v_mfma_f32_16x16x32_bf16 v[28:31], v[144:147], v[192:195], v[28:31]
	v_mfma_f32_16x16x32_bf16 v[24:27], v[152:155], v[192:195], v[24:27]
	v_mfma_f32_16x16x32_bf16 v[12:15], v[144:147], v[200:203], v[12:15]
	v_mfma_f32_16x16x32_bf16 v[8:11], v[152:155], v[200:203], v[8:11]
	v_mfma_f32_16x16x32_bf16 v[60:63], v[148:151], v[180:183], v[60:63]
	v_mfma_f32_16x16x32_bf16 v[56:59], v[156:159], v[180:183], v[56:59]
	v_mfma_f32_16x16x32_bf16 v[44:47], v[148:151], v[188:191], v[44:47]
	v_mfma_f32_16x16x32_bf16 v[40:43], v[156:159], v[188:191], v[40:43]
	v_mfma_f32_16x16x32_bf16 v[28:31], v[148:151], v[196:199], v[28:31]
	v_mfma_f32_16x16x32_bf16 v[24:27], v[156:159], v[196:199], v[24:27]
	v_mfma_f32_16x16x32_bf16 v[12:15], v[148:151], v[204:207], v[12:15]
	v_mfma_f32_16x16x32_bf16 v[8:11], v[156:159], v[204:207], v[8:11]
	s_setprio 0
	s_setprio 1
	v_mfma_f32_16x16x32_bf16 v[52:55], v[160:163], v[176:179], v[52:55]
	v_mfma_f32_16x16x32_bf16 v[48:51], v[168:171], v[176:179], v[48:51]
	v_mfma_f32_16x16x32_bf16 v[36:39], v[160:163], v[184:187], v[36:39]
	v_mfma_f32_16x16x32_bf16 v[32:35], v[168:171], v[184:187], v[32:35]
	v_mfma_f32_16x16x32_bf16 v[20:23], v[160:163], v[192:195], v[20:23]
	v_mfma_f32_16x16x32_bf16 v[16:19], v[168:171], v[192:195], v[16:19]
	v_mfma_f32_16x16x32_bf16 v[4:7], v[160:163], v[200:203], v[4:7]
	v_mfma_f32_16x16x32_bf16 v[0:3], v[168:171], v[200:203], v[0:3]
	v_mfma_f32_16x16x32_bf16 v[52:55], v[164:167], v[180:183], v[52:55]
	v_mfma_f32_16x16x32_bf16 v[48:51], v[172:175], v[180:183], v[48:51]
	v_mfma_f32_16x16x32_bf16 v[36:39], v[164:167], v[188:191], v[36:39]
	v_mfma_f32_16x16x32_bf16 v[32:35], v[172:175], v[188:191], v[32:35]
	v_mfma_f32_16x16x32_bf16 v[20:23], v[164:167], v[196:199], v[20:23]
	v_mfma_f32_16x16x32_bf16 v[16:19], v[172:175], v[196:199], v[16:19]
	v_mfma_f32_16x16x32_bf16 v[4:7], v[164:167], v[204:207], v[4:7]
	v_mfma_f32_16x16x32_bf16 v[0:3], v[172:175], v[204:207], v[0:3]
	s_setprio 0
	s_barrier
	s_add_i32 s53, s53, 2
	s_add_u32 s34, s34, 0x100
	s_addc_u32 s35, s35, 0
	s_add_u32 s51, s51, 0x100
	s_addc_u32 s52, s52, 0
	s_cmp_gt_u32 s53, 13
	s_cbranch_scc0 .LBB0_3679
	s_branch .Lpost_3679
.LBB0_3679:
	ds_read_b128 v[144:147], v141
	ds_read_b128 v[148:151], v141 offset:1024
	ds_read_b128 v[152:155], v141 offset:2048
	ds_read_b128 v[156:159], v141 offset:3072
	ds_read_b128 v[160:163], v142
	ds_read_b128 v[164:167], v142 offset:1024
	ds_read_b128 v[168:171], v142 offset:2048
	ds_read_b128 v[172:175], v142 offset:3072
	s_add_u32 s14, s34, 0xfffc0080
	s_addc_u32 s15, s35, -1
	s_cmp_eq_u32 s53, 12
	s_cselect_b32 s37, s9, s15
	s_cselect_b32 s36, s49, s14
	s_cselect_b32 s15, s11, s52
	s_cselect_b32 s14, s50, s51
	v_lshl_add_u64 v[208:209], s[34:35], 0, v[136:137]
	s_add_i32 m0, s25, 0xc000
	ds_read_b128 v[176:179], v143
	ds_read_b128 v[180:183], v143 offset:1024
	ds_read_b128 v[184:187], v143 offset:2048
	ds_read_b128 v[188:191], v143 offset:3072
	ds_read_b128 v[192:195], v143 offset:4096
	ds_read_b128 v[196:199], v143 offset:5120
	ds_read_b128 v[200:203], v143 offset:6144
	ds_read_b128 v[204:207], v143 offset:7168
	global_load_lds_dwordx4 v[208:209], off
	v_lshl_add_u64 v[208:209], s[34:35], 0, v[138:139]
	s_add_i32 m0, s25, 0xe000
	s_nop 0
	global_load_lds_dwordx4 v[208:209], off
	s_waitcnt vmcnt(8)
	s_waitcnt lgkmcnt(0)
	s_barrier
; #define G_STAGE(bufoff, gbase, voff) do { _Pragma("unroll") for (int _i = 0; _i < 2; ++_i) \
;         __builtin_amdgcn_global_load_lds((const unsigned*)((const char*)(gbase) + voff[_i]), (LAS unsigned*)(lds + (bufoff) + ldsw + _i * 8192), 16, 0, 0); } while (0)
; #define G_LDA(dst, b, h) do { _Pragma("unroll") for (int m = 0; m < 4; ++m) _Pragma("unroll") for (int k = 0; k < 2; ++k) dst[m][k] = *(const LAS bf16x8*)(lds + G_SA(b, h) + aoff + m * 2048 + k * 1024); } while (0)
; #define G_MMA(ai, bj, At_, Bt_) do { __builtin_amdgcn_s_setprio(1); _Pragma("unroll") for (int m = 0; m < 4; ++m) _Pragma("unroll") for (int n = 0; n < 2; ++n) _Pragma("unroll") for (int k = 0; k < 2; ++k) \
;         acc[ai][bj][m][n] = __builtin_amdgcn_mfma_f32_16x16x32_bf16(Bt_[n][k], At_[m][k], acc[ai][bj][m][n], 0, 0, 0); __builtin_amdgcn_s_setprio(0); } while (0)
; #define WAIT_V(n) asm volatile("s_waitcnt vmcnt(" #n ")" ::: "memory")
; #define WAIT_L(n) asm volatile("s_waitcnt lgkmcnt(" #n ")" ::: "memory")
; #define BAR __builtin_amdgcn_s_barrier()
; #define SCHED __builtin_amdgcn_sched_barrier(0)
; template <class Get, class Epi>
; DI void gemm_loop(int ntiles, int ld, char* shm, const Get& get, const Epi& epi) {
;     ...
;             WAIT_V(8); WAIT_L(0); BAR; G_MMA(0, 0, At, B0); G_MMA(0, 1, At, B1); BAR; SCHED;
;             G_LDA(At, 0, 1); G_STAGE(G_SB(0, 0), b2, voffB); G_STAGE(G_SB(0, 1), b2 + hstep, voffB); G_STAGE(G_SA(0, 0), a2, voffA);
;             WAIT_V(8); WAIT_L(0); BAR; G_MMA(1, 0, At, B0); G_MMA(1, 1, At, B1); BAR; SCHED;
	s_setprio 1
	v_mfma_f32_16x16x32_bf16 v[124:127], v[144:147], v[176:179], v[124:127]
	v_mfma_f32_16x16x32_bf16 v[120:123], v[152:155], v[176:179], v[120:123]
	v_mfma_f32_16x16x32_bf16 v[108:111], v[144:147], v[184:187], v[108:111]
	v_mfma_f32_16x16x32_bf16 v[104:107], v[152:155], v[184:187], v[104:107]
	v_mfma_f32_16x16x32_bf16 v[92:95], v[144:147], v[192:195], v[92:95]
	v_mfma_f32_16x16x32_bf16 v[88:91], v[152:155], v[192:195], v[88:91]
	v_mfma_f32_16x16x32_bf16 v[76:79], v[144:147], v[200:203], v[76:79]
	v_mfma_f32_16x16x32_bf16 v[72:75], v[152:155], v[200:203], v[72:75]
	v_mfma_f32_16x16x32_bf16 v[124:127], v[148:151], v[180:183], v[124:127]
	v_mfma_f32_16x16x32_bf16 v[120:123], v[156:159], v[180:183], v[120:123]
	v_mfma_f32_16x16x32_bf16 v[108:111], v[148:151], v[188:191], v[108:111]
	v_mfma_f32_16x16x32_bf16 v[104:107], v[156:159], v[188:191], v[104:107]
	v_mfma_f32_16x16x32_bf16 v[92:95], v[148:151], v[196:199], v[92:95]
	v_mfma_f32_16x16x32_bf16 v[88:91], v[156:159], v[196:199], v[88:91]
	v_mfma_f32_16x16x32_bf16 v[76:79], v[148:151], v[204:207], v[76:79]
	v_mfma_f32_16x16x32_bf16 v[72:75], v[156:159], v[204:207], v[72:75]
	s_setprio 0
	s_setprio 1
	v_mfma_f32_16x16x32_bf16 v[116:119], v[160:163], v[176:179], v[116:119]
	v_mfma_f32_16x16x32_bf16 v[112:115], v[168:171], v[176:179], v[112:115]
	v_mfma_f32_16x16x32_bf16 v[100:103], v[160:163], v[184:187], v[100:103]
	v_mfma_f32_16x16x32_bf16 v[96:99], v[168:171], v[184:187], v[96:99]
	v_mfma_f32_16x16x32_bf16 v[84:87], v[160:163], v[192:195], v[84:87]
	v_mfma_f32_16x16x32_bf16 v[80:83], v[168:171], v[192:195], v[80:83]
	v_mfma_f32_16x16x32_bf16 v[68:71], v[160:163], v[200:203], v[68:71]
	v_mfma_f32_16x16x32_bf16 v[64:67], v[168:171], v[200:203], v[64:67]
	v_mfma_f32_16x16x32_bf16 v[116:119], v[164:167], v[180:183], v[116:119]
	v_mfma_f32_16x16x32_bf16 v[112:115], v[172:175], v[180:183], v[112:115]
	v_mfma_f32_16x16x32_bf16 v[100:103], v[164:167], v[188:191], v[100:103]
	v_mfma_f32_16x16x32_bf16 v[96:99], v[172:175], v[188:191], v[96:99]
	v_mfma_f32_16x16x32_bf16 v[84:87], v[164:167], v[196:199], v[84:87]
	v_mfma_f32_16x16x32_bf16 v[80:83], v[172:175], v[196:199], v[80:83]
	v_mfma_f32_16x16x32_bf16 v[68:71], v[164:167], v[204:207], v[68:71]
	v_mfma_f32_16x16x32_bf16 v[64:67], v[172:175], v[204:207], v[64:67]
	s_setprio 0
	s_barrier
	s_add_i32 s54, s44, s38
	v_lshl_add_u64 v[208:209], s[14:15], 0, v[132:133]
	s_mov_b32 m0, s54
	ds_read_b128 v[176:179], v143 offset:16384
	ds_read_b128 v[180:183], v143 offset:17408
	ds_read_b128 v[184:187], v143 offset:18432
	ds_read_b128 v[188:191], v143 offset:19456
	ds_read_b128 v[192:195], v143 offset:20480
	ds_read_b128 v[196:199], v143 offset:21504
	ds_read_b128 v[200:203], v143 offset:22528
	ds_read_b128 v[204:207], v143 offset:23552
	global_load_lds_dwordx4 v[208:209], off
	s_add_i32 m0, s54, 0x2000
	s_add_u32 s54, s14, 0x40000
	v_lshl_add_u64 v[210:211], s[14:15], 0, v[128:129]
	s_addc_u32 s55, s15, 0
	s_add_i32 s56, s45, s38
	global_load_lds_dwordx4 v[210:211], off
	v_lshl_add_u64 v[212:213], s[54:55], 0, v[132:133]
	s_mov_b32 m0, s56
	v_lshl_add_u64 v[214:215], s[36:37], 0, v[130:131]
	global_load_lds_dwordx4 v[212:213], off
	v_lshl_add_u64 v[212:213], s[54:55], 0, v[128:129]
	s_add_i32 m0, s56, 0x2000
	s_nop 0
	global_load_lds_dwordx4 v[212:213], off
	v_lshl_add_u64 v[212:213], s[36:37], 0, v[134:135]
	s_mov_b32 m0, s25
	s_nop 0
	global_load_lds_dwordx4 v[212:213], off
	s_mov_b32 m0, s31
	s_nop 0
	global_load_lds_dwordx4 v[214:215], off
	s_waitcnt vmcnt(8)
	s_waitcnt lgkmcnt(0)
	s_barrier
	s_setprio 1
	v_mfma_f32_16x16x32_bf16 v[60:63], v[144:147], v[176:179], v[60:63]
	v_mfma_f32_16x16x32_bf16 v[56:59], v[152:155], v[176:179], v[56:59]
	v_mfma_f32_16x16x32_bf16 v[44:47], v[144:147], v[184:187], v[44:47]
	v_mfma_f32_16x16x32_bf16 v[40:43], v[152:155], v[184:187], v[40:43]
	v_mfma_f32_16x16x32_bf16 v[28:31], v[144:147], v[192:195], v[28:31]
	v_mfma_f32_16x16x32_bf16 v[24:27], v[152:155], v[192:195], v[24:27]
	v_mfma_f32_16x16x32_bf16 v[12:15], v[144:147], v[200:203], v[12:15]
	v_mfma_f32_16x16x32_bf16 v[8:11], v[152:155], v[200:203], v[8:11]
	v_mfma_f32_16x16x32_bf16 v[60:63], v[148:151], v[180:183], v[60:63]
	v_mfma_f32_16x16x32_bf16 v[56:59], v[156:159], v[180:183], v[56:59]
	v_mfma_f32_16x16x32_bf16 v[44:47], v[148:151], v[188:191], v[44:47]
	v_mfma_f32_16x16x32_bf16 v[40:43], v[156:159], v[188:191], v[40:43]
	v_mfma_f32_16x16x32_bf16 v[28:31], v[148:151], v[196:199], v[28:31]
	v_mfma_f32_16x16x32_bf16 v[24:27], v[156:159], v[196:199], v[24:27]
	v_mfma_f32_16x16x32_bf16 v[12:15], v[148:151], v[204:207], v[12:15]
	v_mfma_f32_16x16x32_bf16 v[8:11], v[156:159], v[204:207], v[8:11]
	s_setprio 0
	s_setprio 1
	v_mfma_f32_16x16x32_bf16 v[52:55], v[160:163], v[176:179], v[52:55]
	v_mfma_f32_16x16x32_bf16 v[48:51], v[168:171], v[176:179], v[48:51]
	v_mfma_f32_16x16x32_bf16 v[36:39], v[160:163], v[184:187], v[36:39]
	v_mfma_f32_16x16x32_bf16 v[32:35], v[168:171], v[184:187], v[32:35]
	v_mfma_f32_16x16x32_bf16 v[20:23], v[160:163], v[192:195], v[20:23]
	v_mfma_f32_16x16x32_bf16 v[16:19], v[168:171], v[192:195], v[16:19]
	v_mfma_f32_16x16x32_bf16 v[4:7], v[160:163], v[200:203], v[4:7]
	v_mfma_f32_16x16x32_bf16 v[0:3], v[168:171], v[200:203], v[0:3]
	v_mfma_f32_16x16x32_bf16 v[52:55], v[164:167], v[180:183], v[52:55]
	v_mfma_f32_16x16x32_bf16 v[48:51], v[172:175], v[180:183], v[48:51]
	v_mfma_f32_16x16x32_bf16 v[36:39], v[164:167], v[188:191], v[36:39]
	v_mfma_f32_16x16x32_bf16 v[32:35], v[172:175], v[188:191], v[32:35]
	v_mfma_f32_16x16x32_bf16 v[20:23], v[164:167], v[196:199], v[20:23]
	v_mfma_f32_16x16x32_bf16 v[16:19], v[172:175], v[196:199], v[16:19]
	v_mfma_f32_16x16x32_bf16 v[4:7], v[164:167], v[204:207], v[4:7]
	v_mfma_f32_16x16x32_bf16 v[0:3], v[172:175], v[204:207], v[0:3]
	s_setprio 0
	s_barrier
; #define G_STAGE(bufoff, gbase, voff) do { _Pragma("unroll") for (int _i = 0; _i < 2; ++_i) \
;         __builtin_amdgcn_global_load_lds((const unsigned*)((const char*)(gbase) + voff[_i]), (LAS unsigned*)(lds + (bufoff) + ldsw + _i * 8192), 16, 0, 0); } while (0)
; #define G_LDA(dst, b, h) do { _Pragma("unroll") for (int m = 0; m < 4; ++m) _Pragma("unroll") for (int k = 0; k < 2; ++k) dst[m][k] = *(const LAS bf16x8*)(lds + G_SA(b, h) + aoff + m * 2048 + k * 1024); } while (0)
; #define G_LDB(dst, b, h) do { _Pragma("unroll") for (int n = 0; n < 2; ++n) _Pragma("unroll") for (int k = 0; k < 2; ++k) dst[n][k] = *(const LAS bf16x8*)(lds + G_SB(b, h) + boff + n * 2048 + k * 1024); } while (0)
; #define G_MMA(ai, bj, At_, Bt_) do { __builtin_amdgcn_s_setprio(1); _Pragma("unroll") for (int m = 0; m < 4; ++m) _Pragma("unroll") for (int n = 0; n < 2; ++n) _Pragma("unroll") for (int k = 0; k < 2; ++k) \
;         acc[ai][bj][m][n] = __builtin_amdgcn_mfma_f32_16x16x32_bf16(Bt_[n][k], At_[m][k], acc[ai][bj][m][n], 0, 0, 0); __builtin_amdgcn_s_setprio(0); } while (0)
; #define WAIT_V(n) asm volatile("s_waitcnt vmcnt(" #n ")" ::: "memory")
; #define WAIT_L(n) asm volatile("s_waitcnt lgkmcnt(" #n ")" ::: "memory")
; #define BAR __builtin_amdgcn_s_barrier()
; #define SCHED __builtin_amdgcn_sched_barrier(0)
; template <class Get, class Epi>
; DI void gemm_loop(int ntiles, int ld, char* shm, const Get& get, const Epi& epi) {
;     ...
;             G_LDB(B0, 1, 0); G_LDB(B1, 1, 1); SCHED; G_LDA(At, 1, 0); G_STAGE(G_SA(0, 1), a2 + hstep, voffA);
;             WAIT_V(8); WAIT_L(0); BAR; G_MMA(0, 0, At, B0); G_MMA(0, 1, At, B1); BAR; SCHED;
	s_add_i32 s54, 0, 0x18000
	s_add_i32 s55, 0, 0x1c000
	v_add_u32_e32 v156, s54, v140
	v_add_u32_e32 v172, s55, v140
	ds_read_b128 v[144:147], v156
	ds_read_b128 v[148:151], v156 offset:1024
	ds_read_b128 v[152:155], v156 offset:2048
	ds_read_b128 v[156:159], v156 offset:3072
	ds_read_b128 v[160:163], v172
	ds_read_b128 v[164:167], v172 offset:1024
	ds_read_b128 v[168:171], v172 offset:2048
	ds_read_b128 v[172:175], v172 offset:3072
	s_add_u32 s36, s36, 0x40000
	s_addc_u32 s37, s37, 0
	s_mov_b32 m0, s40
	v_lshl_add_u64 v[216:217], s[36:37], 0, v[134:135]
	ds_read_b128 v[176:179], v143 offset:32768
	ds_read_b128 v[180:183], v143 offset:33792
	ds_read_b128 v[184:187], v143 offset:34816
	ds_read_b128 v[188:191], v143 offset:35840
	ds_read_b128 v[192:195], v143 offset:36864
	ds_read_b128 v[196:199], v143 offset:37888
	ds_read_b128 v[200:203], v143 offset:38912
	ds_read_b128 v[204:207], v143 offset:39936
	global_load_lds_dwordx4 v[216:217], off
	v_lshl_add_u64 v[216:217], s[36:37], 0, v[130:131]
	s_mov_b32 m0, s41
	s_nop 0
	global_load_lds_dwordx4 v[216:217], off
	s_waitcnt vmcnt(8)
	s_waitcnt lgkmcnt(0)
	s_barrier
	s_setprio 1
	v_mfma_f32_16x16x32_bf16 v[124:127], v[144:147], v[176:179], v[124:127]
	v_mfma_f32_16x16x32_bf16 v[120:123], v[152:155], v[176:179], v[120:123]
	v_mfma_f32_16x16x32_bf16 v[108:111], v[144:147], v[184:187], v[108:111]
	v_mfma_f32_16x16x32_bf16 v[104:107], v[152:155], v[184:187], v[104:107]
	v_mfma_f32_16x16x32_bf16 v[92:95], v[144:147], v[192:195], v[92:95]
	v_mfma_f32_16x16x32_bf16 v[88:91], v[152:155], v[192:195], v[88:91]
	v_mfma_f32_16x16x32_bf16 v[76:79], v[144:147], v[200:203], v[76:79]
	v_mfma_f32_16x16x32_bf16 v[72:75], v[152:155], v[200:203], v[72:75]
	v_mfma_f32_16x16x32_bf16 v[124:127], v[148:151], v[180:183], v[124:127]
	v_mfma_f32_16x16x32_bf16 v[120:123], v[156:159], v[180:183], v[120:123]
	v_mfma_f32_16x16x32_bf16 v[108:111], v[148:151], v[188:191], v[108:111]
	v_mfma_f32_16x16x32_bf16 v[104:107], v[156:159], v[188:191], v[104:107]
	v_mfma_f32_16x16x32_bf16 v[92:95], v[148:151], v[196:199], v[92:95]
	v_mfma_f32_16x16x32_bf16 v[88:91], v[156:159], v[196:199], v[88:91]
	v_mfma_f32_16x16x32_bf16 v[76:79], v[148:151], v[204:207], v[76:79]
	v_mfma_f32_16x16x32_bf16 v[72:75], v[156:159], v[204:207], v[72:75]
	s_setprio 0
	s_setprio 1
	v_mfma_f32_16x16x32_bf16 v[116:119], v[160:163], v[176:179], v[116:119]
	v_mfma_f32_16x16x32_bf16 v[112:115], v[168:171], v[176:179], v[112:115]
	v_mfma_f32_16x16x32_bf16 v[100:103], v[160:163], v[184:187], v[100:103]
	v_mfma_f32_16x16x32_bf16 v[96:99], v[168:171], v[184:187], v[96:99]
	v_mfma_f32_16x16x32_bf16 v[84:87], v[160:163], v[192:195], v[84:87]
	v_mfma_f32_16x16x32_bf16 v[80:83], v[168:171], v[192:195], v[80:83]
	v_mfma_f32_16x16x32_bf16 v[68:71], v[160:163], v[200:203], v[68:71]
	v_mfma_f32_16x16x32_bf16 v[64:67], v[168:171], v[200:203], v[64:67]
	v_mfma_f32_16x16x32_bf16 v[116:119], v[164:167], v[180:183], v[116:119]
	v_mfma_f32_16x16x32_bf16 v[112:115], v[172:175], v[180:183], v[112:115]
	v_mfma_f32_16x16x32_bf16 v[100:103], v[164:167], v[188:191], v[100:103]
	v_mfma_f32_16x16x32_bf16 v[96:99], v[172:175], v[188:191], v[96:99]
	v_mfma_f32_16x16x32_bf16 v[84:87], v[164:167], v[196:199], v[84:87]
	v_mfma_f32_16x16x32_bf16 v[80:83], v[172:175], v[196:199], v[80:83]
	v_mfma_f32_16x16x32_bf16 v[68:71], v[164:167], v[204:207], v[68:71]
	v_mfma_f32_16x16x32_bf16 v[64:67], v[172:175], v[204:207], v[64:67]
	s_setprio 0
	s_barrier
; #define G_STAGE(bufoff, gbase, voff) do { _Pragma("unroll") for (int _i = 0; _i < 2; ++_i) \
;         __builtin_amdgcn_global_load_lds((const unsigned*)((const char*)(gbase) + voff[_i]), (LAS unsigned*)(lds + (bufoff) + ldsw + _i * 8192), 16, 0, 0); } while (0)
; #define G_LDA(dst, b, h) do { _Pragma("unroll") for (int m = 0; m < 4; ++m) _Pragma("unroll") for (int k = 0; k < 2; ++k) dst[m][k] = *(const LAS bf16x8*)(lds + G_SA(b, h) + aoff + m * 2048 + k * 1024); } while (0)
; #define G_MMA(ai, bj, At_, Bt_) do { __builtin_amdgcn_s_setprio(1); _Pragma("unroll") for (int m = 0; m < 4; ++m) _Pragma("unroll") for (int n = 0; n < 2; ++n) _Pragma("unroll") for (int k = 0; k < 2; ++k) \
;         acc[ai][bj][m][n] = __builtin_amdgcn_mfma_f32_16x16x32_bf16(Bt_[n][k], At_[m][k], acc[ai][bj][m][n], 0, 0, 0); __builtin_amdgcn_s_setprio(0); } while (0)
; #define WAIT_V(n) asm volatile("s_waitcnt vmcnt(" #n ")" ::: "memory")
; #define WAIT_L(n) asm volatile("s_waitcnt lgkmcnt(" #n ")" ::: "memory")
; #define BAR __builtin_amdgcn_s_barrier()
; #define SCHED __builtin_amdgcn_sched_barrier(0)
; template <class Get, class Epi>
; DI void gemm_loop(int ntiles, int ld, char* shm, const Get& get, const Epi& epi) {
;     ...
;             G_LDA(At, 1, 1); G_STAGE(G_SB(1, 0), b3, voffB); G_STAGE(G_SB(1, 1), b3 + hstep, voffB); G_STAGE(G_SA(1, 0), a3, voffA);
;             WAIT_V(8); WAIT_L(0); BAR; G_MMA(1, 0, At, B0); G_MMA(1, 1, At, B1); BAR; SCHED;
;         }
	s_add_i32 s36, s54, s38
	v_lshl_add_u64 v[208:209], v[208:209], 0, s[2:3]
	s_mov_b32 m0, s36
	ds_read_b128 v[176:179], v143 offset:49152
	ds_read_b128 v[180:183], v143 offset:50176
	ds_read_b128 v[184:187], v143 offset:51200
	ds_read_b128 v[188:191], v143 offset:52224
	ds_read_b128 v[192:195], v143 offset:53248
	ds_read_b128 v[196:199], v143 offset:54272
	ds_read_b128 v[200:203], v143 offset:55296
	ds_read_b128 v[204:207], v143 offset:56320
	global_load_lds_dwordx4 v[208:209], off
	s_add_i32 m0, s36, 0x2000
	s_add_u32 s14, s14, 0x40080
	v_lshl_add_u64 v[208:209], v[210:211], 0, s[2:3]
	s_addc_u32 s15, s15, 0
	s_add_i32 s36, s55, s38
	global_load_lds_dwordx4 v[208:209], off
	v_lshl_add_u64 v[208:209], s[14:15], 0, v[132:133]
	s_mov_b32 m0, s36
	s_nop 0
	global_load_lds_dwordx4 v[208:209], off
	v_lshl_add_u64 v[208:209], s[14:15], 0, v[128:129]
	s_add_i32 m0, s36, 0x2000
	s_nop 0
	global_load_lds_dwordx4 v[208:209], off
	v_lshl_add_u64 v[208:209], v[212:213], 0, s[2:3]
	s_mov_b32 m0, s42
	s_nop 0
	global_load_lds_dwordx4 v[208:209], off
	v_lshl_add_u64 v[208:209], v[214:215], 0, s[2:3]
	s_mov_b32 m0, s43
	s_nop 0
	global_load_lds_dwordx4 v[208:209], off
	s_waitcnt vmcnt(8)
	s_waitcnt lgkmcnt(0)
	s_barrier
	s_setprio 1
	v_mfma_f32_16x16x32_bf16 v[60:63], v[144:147], v[176:179], v[60:63]
	v_mfma_f32_16x16x32_bf16 v[56:59], v[152:155], v[176:179], v[56:59]
	v_mfma_f32_16x16x32_bf16 v[44:47], v[144:147], v[184:187], v[44:47]
	v_mfma_f32_16x16x32_bf16 v[40:43], v[152:155], v[184:187], v[40:43]
	v_mfma_f32_16x16x32_bf16 v[28:31], v[144:147], v[192:195], v[28:31]
	v_mfma_f32_16x16x32_bf16 v[24:27], v[152:155], v[192:195], v[24:27]
	v_mfma_f32_16x16x32_bf16 v[12:15], v[144:147], v[200:203], v[12:15]
	v_mfma_f32_16x16x32_bf16 v[8:11], v[152:155], v[200:203], v[8:11]
	v_mfma_f32_16x16x32_bf16 v[60:63], v[148:151], v[180:183], v[60:63]
	v_mfma_f32_16x16x32_bf16 v[56:59], v[156:159], v[180:183], v[56:59]
	v_mfma_f32_16x16x32_bf16 v[44:47], v[148:151], v[188:191], v[44:47]
	v_mfma_f32_16x16x32_bf16 v[40:43], v[156:159], v[188:191], v[40:43]
	v_mfma_f32_16x16x32_bf16 v[28:31], v[148:151], v[196:199], v[28:31]
	v_mfma_f32_16x16x32_bf16 v[24:27], v[156:159], v[196:199], v[24:27]
	v_mfma_f32_16x16x32_bf16 v[12:15], v[148:151], v[204:207], v[12:15]
	v_mfma_f32_16x16x32_bf16 v[8:11], v[156:159], v[204:207], v[8:11]
	s_setprio 0
	s_setprio 1
	v_mfma_f32_16x16x32_bf16 v[52:55], v[160:163], v[176:179], v[52:55]
	v_mfma_f32_16x16x32_bf16 v[48:51], v[168:171], v[176:179], v[48:51]
	v_mfma_f32_16x16x32_bf16 v[36:39], v[160:163], v[184:187], v[36:39]
	v_mfma_f32_16x16x32_bf16 v[32:35], v[168:171], v[184:187], v[32:35]
	v_mfma_f32_16x16x32_bf16 v[20:23], v[160:163], v[192:195], v[20:23]
	v_mfma_f32_16x16x32_bf16 v[16:19], v[168:171], v[192:195], v[16:19]
	v_mfma_f32_16x16x32_bf16 v[4:7], v[160:163], v[200:203], v[4:7]
	v_mfma_f32_16x16x32_bf16 v[0:3], v[168:171], v[200:203], v[0:3]
	v_mfma_f32_16x16x32_bf16 v[52:55], v[164:167], v[180:183], v[52:55]
	v_mfma_f32_16x16x32_bf16 v[48:51], v[172:175], v[180:183], v[48:51]
	v_mfma_f32_16x16x32_bf16 v[36:39], v[164:167], v[188:191], v[36:39]
	v_mfma_f32_16x16x32_bf16 v[32:35], v[172:175], v[188:191], v[32:35]
	v_mfma_f32_16x16x32_bf16 v[20:23], v[164:167], v[196:199], v[20:23]
	v_mfma_f32_16x16x32_bf16 v[16:19], v[172:175], v[196:199], v[16:19]
	v_mfma_f32_16x16x32_bf16 v[4:7], v[164:167], v[204:207], v[4:7]
	v_mfma_f32_16x16x32_bf16 v[0:3], v[172:175], v[204:207], v[0:3]
	s_setprio 0
	s_barrier
	s_add_i32 s53, s53, 2
	s_add_u32 s34, s34, 0x100
	s_addc_u32 s35, s35, 0
	s_add_u32 s51, s51, 0x100
	s_addc_u32 s52, s52, 0
	s_cmp_gt_u32 s53, 13
	s_cbranch_scc0 .LBB0_3679

; #define G_STAGE(bufoff, gbase, voff) do { _Pragma("unroll") for (int _i = 0; _i < 2; ++_i) \
;         __builtin_amdgcn_global_load_lds((const unsigned*)((const char*)(gbase) + voff[_i]), (LAS unsigned*)(lds + (bufoff) + ldsw + _i * 8192), 16, 0, 0); } while (0)
; #define G_LDA(dst, b, h) do { _Pragma("unroll") for (int m = 0; m < 4; ++m) _Pragma("unroll") for (int k = 0; k < 2; ++k) dst[m][k] = *(const LAS bf16x8*)(lds + G_SA(b, h) + aoff + m * 2048 + k * 1024); } while (0)
; #define G_MMA(ai, bj, At_, Bt_) do { __builtin_amdgcn_s_setprio(1); _Pragma("unroll") for (int m = 0; m < 4; ++m) _Pragma("unroll") for (int n = 0; n < 2; ++n) _Pragma("unroll") for (int k = 0; k < 2; ++k) \
;         acc[ai][bj][m][n] = __builtin_amdgcn_mfma_f32_16x16x32_bf16(Bt_[n][k], At_[m][k], acc[ai][bj][m][n], 0, 0, 0); __builtin_amdgcn_s_setprio(0); } while (0)
; #define WAIT_V(n) asm volatile("s_waitcnt vmcnt(" #n ")" ::: "memory")
; #define WAIT_L(n) asm volatile("s_waitcnt lgkmcnt(" #n ")" ::: "memory")
; #define BAR __builtin_amdgcn_s_barrier()
; #define SCHED __builtin_amdgcn_sched_barrier(0)
; template <class Get, class Epi>
; DI void gemm_loop(int ntiles, int ld, char* shm, const Get& get, const Epi& epi) {
;     ...
;             WAIT_V(8); WAIT_L(0); BAR; G_MMA(0, 0, At, B0); G_MMA(0, 1, At, B1); BAR; SCHED;
;             G_LDA(At, 0, 1); G_STAGE(G_SB(0, 0), b2, voffB); G_STAGE(G_SB(0, 1), b2 + hstep, voffB); G_STAGE(G_SA(0, 0), a2, voffA);
.Lrj_3759_0:
	s_waitcnt lgkmcnt(0)
	s_barrier
	s_setprio 1
	v_mfma_f32_16x16x32_bf16 v[124:127], v[128:131], v[180:183], 0
	v_mfma_f32_16x16x32_bf16 v[120:123], v[136:139], v[180:183], 0
	v_mfma_f32_16x16x32_bf16 v[116:119], v[128:131], v[188:191], 0
	v_mfma_f32_16x16x32_bf16 v[112:115], v[136:139], v[188:191], 0
	v_mfma_f32_16x16x32_bf16 v[108:111], v[128:131], v[196:199], 0
	v_mfma_f32_16x16x32_bf16 v[104:107], v[136:139], v[196:199], 0
	v_mfma_f32_16x16x32_bf16 v[100:103], v[128:131], v[204:207], 0
	v_mfma_f32_16x16x32_bf16 v[96:99], v[136:139], v[204:207], 0
	v_mfma_f32_16x16x32_bf16 v[124:127], v[132:135], v[184:187], v[124:127]
	v_mfma_f32_16x16x32_bf16 v[120:123], v[140:143], v[184:187], v[120:123]
	v_mfma_f32_16x16x32_bf16 v[116:119], v[132:135], v[192:195], v[116:119]
	v_mfma_f32_16x16x32_bf16 v[112:115], v[140:143], v[192:195], v[112:115]
	v_mfma_f32_16x16x32_bf16 v[108:111], v[132:135], v[200:203], v[108:111]
	v_mfma_f32_16x16x32_bf16 v[104:107], v[140:143], v[200:203], v[104:107]
	v_mfma_f32_16x16x32_bf16 v[100:103], v[132:135], v[208:211], v[100:103]
	v_mfma_f32_16x16x32_bf16 v[96:99], v[140:143], v[208:211], v[96:99]
	s_setprio 0
	s_setprio 1
	v_mfma_f32_16x16x32_bf16 v[60:63], v[158:161], v[180:183], 0
	v_mfma_f32_16x16x32_bf16 v[56:59], v[172:175], v[180:183], 0
	v_mfma_f32_16x16x32_bf16 v[52:55], v[158:161], v[188:191], 0
	v_mfma_f32_16x16x32_bf16 v[48:51], v[172:175], v[188:191], 0
	v_mfma_f32_16x16x32_bf16 v[44:47], v[158:161], v[196:199], 0
	v_mfma_f32_16x16x32_bf16 v[40:43], v[172:175], v[196:199], 0
	v_mfma_f32_16x16x32_bf16 v[36:39], v[158:161], v[204:207], 0
	v_mfma_f32_16x16x32_bf16 v[32:35], v[172:175], v[204:207], 0
	v_mfma_f32_16x16x32_bf16 v[60:63], v[162:165], v[184:187], v[60:63]
	v_mfma_f32_16x16x32_bf16 v[56:59], v[176:179], v[184:187], v[56:59]
	v_mfma_f32_16x16x32_bf16 v[52:55], v[162:165], v[192:195], v[52:55]
	v_mfma_f32_16x16x32_bf16 v[48:51], v[176:179], v[192:195], v[48:51]
	v_mfma_f32_16x16x32_bf16 v[44:47], v[162:165], v[200:203], v[44:47]
	v_mfma_f32_16x16x32_bf16 v[40:43], v[176:179], v[200:203], v[40:43]
	v_mfma_f32_16x16x32_bf16 v[36:39], v[162:165], v[208:211], v[36:39]
	v_mfma_f32_16x16x32_bf16 v[32:35], v[176:179], v[208:211], v[32:35]
	s_setprio 0
	s_barrier
	s_add_i32 s2, s44, s33
	v_lshl_add_u64 v[144:145], s[30:31], 0, v[148:149]
	s_mov_b32 m0, s2
	ds_read_b128 v[180:183], v171 offset:16384
	ds_read_b128 v[184:187], v171 offset:17408
	ds_read_b128 v[188:191], v171 offset:18432
	ds_read_b128 v[192:195], v171 offset:19456
	ds_read_b128 v[196:199], v171 offset:20480
	ds_read_b128 v[200:203], v171 offset:21504
	ds_read_b128 v[204:207], v171 offset:22528
	ds_read_b128 v[208:211], v171 offset:23552
	global_load_lds_dwordx4 v[144:145], off
	s_add_i32 m0, s2, 0x2000
	s_add_u32 s2, s30, 0xb0000
	v_lshl_add_u64 v[166:167], s[30:31], 0, v[152:153]
	s_addc_u32 s3, s31, 0
	s_add_i32 s55, s45, s33
	global_load_lds_dwordx4 v[166:167], off
	v_lshl_add_u64 v[212:213], s[2:3], 0, v[148:149]
	s_mov_b32 m0, s55
	v_lshl_add_u64 v[214:215], s[34:35], 0, v[150:151]
	global_load_lds_dwordx4 v[212:213], off
	v_lshl_add_u64 v[212:213], s[2:3], 0, v[152:153]
	s_add_i32 m0, s55, 0x2000
	s_nop 0
	global_load_lds_dwordx4 v[212:213], off
	v_lshl_add_u64 v[212:213], s[34:35], 0, v[146:147]
	s_mov_b32 m0, s36
	s_nop 0
	global_load_lds_dwordx4 v[212:213], off
	s_mov_b32 m0, s37
	s_nop 0
	global_load_lds_dwordx4 v[214:215], off
	s_cmp_lg_u32 s100, 0
	s_cbranch_scc0 .Lrf_3759_1
	s_waitcnt vmcnt(16)
	s_branch .Lrj_3759_1

; #define G_STAGE(bufoff, gbase, voff) do { _Pragma("unroll") for (int _i = 0; _i < 2; ++_i) \
;         __builtin_amdgcn_global_load_lds((const unsigned*)((const char*)(gbase) + voff[_i]), (LAS unsigned*)(lds + (bufoff) + ldsw + _i * 8192), 16, 0, 0); } while (0)
; #define G_LDA(dst, b, h) do { _Pragma("unroll") for (int m = 0; m < 4; ++m) _Pragma("unroll") for (int k = 0; k < 2; ++k) dst[m][k] = *(const LAS bf16x8*)(lds + G_SA(b, h) + aoff + m * 2048 + k * 1024); } while (0)
; #define G_LDB(dst, b, h) do { _Pragma("unroll") for (int n = 0; n < 2; ++n) _Pragma("unroll") for (int k = 0; k < 2; ++k) dst[n][k] = *(const LAS bf16x8*)(lds + G_SB(b, h) + boff + n * 2048 + k * 1024); } while (0)
; #define G_MMA(ai, bj, At_, Bt_) do { __builtin_amdgcn_s_setprio(1); _Pragma("unroll") for (int m = 0; m < 4; ++m) _Pragma("unroll") for (int n = 0; n < 2; ++n) _Pragma("unroll") for (int k = 0; k < 2; ++k) \
;         acc[ai][bj][m][n] = __builtin_amdgcn_mfma_f32_16x16x32_bf16(Bt_[n][k], At_[m][k], acc[ai][bj][m][n], 0, 0, 0); __builtin_amdgcn_s_setprio(0); } while (0)
; #define WAIT_V(n) asm volatile("s_waitcnt vmcnt(" #n ")" ::: "memory")
; #define WAIT_L(n) asm volatile("s_waitcnt lgkmcnt(" #n ")" ::: "memory")
; #define BAR __builtin_amdgcn_s_barrier()
; #define SCHED __builtin_amdgcn_sched_barrier(0)
; template <class Get, class Epi>
; DI void gemm_loop(int ntiles, int ld, char* shm, const Get& get, const Epi& epi) {
;     ...
;             WAIT_V(8); WAIT_L(0); BAR; G_MMA(1, 0, At, B0); G_MMA(1, 1, At, B1); BAR; SCHED;
;             G_LDB(B0, 1, 0); G_LDB(B1, 1, 1); SCHED; G_LDA(At, 1, 0); G_STAGE(G_SA(0, 1), a2 + hstep, voffA);
;             WAIT_V(8); WAIT_L(0); BAR; G_MMA(0, 0, At, B0); G_MMA(0, 1, At, B1); BAR; SCHED;
.Lrj_3759_1:
	s_waitcnt lgkmcnt(0)
	s_barrier
	s_setprio 1
	v_mfma_f32_16x16x32_bf16 v[92:95], v[128:131], v[180:183], 0
	v_mfma_f32_16x16x32_bf16 v[88:91], v[136:139], v[180:183], 0
	v_mfma_f32_16x16x32_bf16 v[84:87], v[128:131], v[188:191], 0
	v_mfma_f32_16x16x32_bf16 v[80:83], v[136:139], v[188:191], 0
	v_mfma_f32_16x16x32_bf16 v[76:79], v[128:131], v[196:199], 0
	v_mfma_f32_16x16x32_bf16 v[72:75], v[136:139], v[196:199], 0
	v_mfma_f32_16x16x32_bf16 v[68:71], v[128:131], v[204:207], 0
	v_mfma_f32_16x16x32_bf16 v[64:67], v[136:139], v[204:207], 0
	v_mfma_f32_16x16x32_bf16 v[92:95], v[132:135], v[184:187], v[92:95]
	v_mfma_f32_16x16x32_bf16 v[88:91], v[140:143], v[184:187], v[88:91]
	v_mfma_f32_16x16x32_bf16 v[84:87], v[132:135], v[192:195], v[84:87]
	v_mfma_f32_16x16x32_bf16 v[80:83], v[140:143], v[192:195], v[80:83]
	v_mfma_f32_16x16x32_bf16 v[76:79], v[132:135], v[200:203], v[76:79]
	v_mfma_f32_16x16x32_bf16 v[72:75], v[140:143], v[200:203], v[72:75]
	v_mfma_f32_16x16x32_bf16 v[68:71], v[132:135], v[208:211], v[68:71]
	v_mfma_f32_16x16x32_bf16 v[64:67], v[140:143], v[208:211], v[64:67]
	s_setprio 0
	s_setprio 1
	v_mfma_f32_16x16x32_bf16 v[28:31], v[158:161], v[180:183], 0
	v_mfma_f32_16x16x32_bf16 v[24:27], v[172:175], v[180:183], 0
	v_mfma_f32_16x16x32_bf16 v[20:23], v[158:161], v[188:191], 0
	v_mfma_f32_16x16x32_bf16 v[16:19], v[172:175], v[188:191], 0
	v_mfma_f32_16x16x32_bf16 v[12:15], v[158:161], v[196:199], 0
	v_mfma_f32_16x16x32_bf16 v[8:11], v[172:175], v[196:199], 0
	v_mfma_f32_16x16x32_bf16 v[4:7], v[158:161], v[204:207], 0
	v_mfma_f32_16x16x32_bf16 v[0:3], v[172:175], v[204:207], 0
	v_mfma_f32_16x16x32_bf16 v[28:31], v[162:165], v[184:187], v[28:31]
	v_mfma_f32_16x16x32_bf16 v[24:27], v[176:179], v[184:187], v[24:27]
	v_mfma_f32_16x16x32_bf16 v[20:23], v[162:165], v[192:195], v[20:23]
	v_mfma_f32_16x16x32_bf16 v[16:19], v[176:179], v[192:195], v[16:19]
	v_mfma_f32_16x16x32_bf16 v[12:15], v[162:165], v[200:203], v[12:15]
	v_mfma_f32_16x16x32_bf16 v[8:11], v[176:179], v[200:203], v[8:11]
	v_mfma_f32_16x16x32_bf16 v[4:7], v[162:165], v[208:211], v[4:7]
	v_mfma_f32_16x16x32_bf16 v[0:3], v[176:179], v[208:211], v[0:3]
	s_setprio 0
	s_barrier
	s_add_i32 s55, 0, 0x18000
	s_add_i32 s56, 0, 0x1c000
	v_add_u32_e32 v140, s55, v168
	v_add_u32_e32 v176, s56, v168
	ds_read_b128 v[128:131], v140
	ds_read_b128 v[132:135], v140 offset:1024
	ds_read_b128 v[136:139], v140 offset:2048
	ds_read_b128 v[140:143], v140 offset:3072
	ds_read_b128 v[158:161], v176
	ds_read_b128 v[162:165], v176 offset:1024
	ds_read_b128 v[172:175], v176 offset:2048
	ds_read_b128 v[176:179], v176 offset:3072
	s_add_u32 s2, s34, 0xb0000
	s_addc_u32 s3, s35, 0
	s_mov_b32 m0, s38
	v_lshl_add_u64 v[216:217], s[2:3], 0, v[146:147]
	ds_read_b128 v[180:183], v171 offset:32768
	ds_read_b128 v[184:187], v171 offset:33792
	ds_read_b128 v[188:191], v171 offset:34816
	ds_read_b128 v[192:195], v171 offset:35840
	ds_read_b128 v[196:199], v171 offset:36864
	ds_read_b128 v[200:203], v171 offset:37888
	ds_read_b128 v[204:207], v171 offset:38912
	ds_read_b128 v[208:211], v171 offset:39936
	global_load_lds_dwordx4 v[216:217], off
	v_lshl_add_u64 v[216:217], s[2:3], 0, v[150:151]
	s_mov_b32 m0, s39
	s_nop 0
	global_load_lds_dwordx4 v[216:217], off
	s_waitcnt vmcnt(8)
	s_waitcnt lgkmcnt(0)
	s_barrier
	s_setprio 1
	v_mfma_f32_16x16x32_bf16 v[124:127], v[128:131], v[180:183], v[124:127]
	v_mfma_f32_16x16x32_bf16 v[120:123], v[136:139], v[180:183], v[120:123]
	v_mfma_f32_16x16x32_bf16 v[116:119], v[128:131], v[188:191], v[116:119]
	v_mfma_f32_16x16x32_bf16 v[112:115], v[136:139], v[188:191], v[112:115]
	v_mfma_f32_16x16x32_bf16 v[108:111], v[128:131], v[196:199], v[108:111]
	v_mfma_f32_16x16x32_bf16 v[104:107], v[136:139], v[196:199], v[104:107]
	v_mfma_f32_16x16x32_bf16 v[100:103], v[128:131], v[204:207], v[100:103]
	v_mfma_f32_16x16x32_bf16 v[96:99], v[136:139], v[204:207], v[96:99]
	v_mfma_f32_16x16x32_bf16 v[124:127], v[132:135], v[184:187], v[124:127]
	v_mfma_f32_16x16x32_bf16 v[120:123], v[140:143], v[184:187], v[120:123]
	v_mfma_f32_16x16x32_bf16 v[116:119], v[132:135], v[192:195], v[116:119]
	v_mfma_f32_16x16x32_bf16 v[112:115], v[140:143], v[192:195], v[112:115]
	v_mfma_f32_16x16x32_bf16 v[108:111], v[132:135], v[200:203], v[108:111]
	v_mfma_f32_16x16x32_bf16 v[104:107], v[140:143], v[200:203], v[104:107]
	v_mfma_f32_16x16x32_bf16 v[100:103], v[132:135], v[208:211], v[100:103]
	v_mfma_f32_16x16x32_bf16 v[96:99], v[140:143], v[208:211], v[96:99]
	s_setprio 0
	s_setprio 1
	v_mfma_f32_16x16x32_bf16 v[60:63], v[158:161], v[180:183], v[60:63]
	v_mfma_f32_16x16x32_bf16 v[56:59], v[172:175], v[180:183], v[56:59]
	v_mfma_f32_16x16x32_bf16 v[52:55], v[158:161], v[188:191], v[52:55]
	v_mfma_f32_16x16x32_bf16 v[48:51], v[172:175], v[188:191], v[48:51]
	v_mfma_f32_16x16x32_bf16 v[44:47], v[158:161], v[196:199], v[44:47]
	v_mfma_f32_16x16x32_bf16 v[40:43], v[172:175], v[196:199], v[40:43]
	v_mfma_f32_16x16x32_bf16 v[36:39], v[158:161], v[204:207], v[36:39]
	v_mfma_f32_16x16x32_bf16 v[32:35], v[172:175], v[204:207], v[32:35]
	v_mfma_f32_16x16x32_bf16 v[60:63], v[162:165], v[184:187], v[60:63]
	v_mfma_f32_16x16x32_bf16 v[56:59], v[176:179], v[184:187], v[56:59]
	v_mfma_f32_16x16x32_bf16 v[52:55], v[162:165], v[192:195], v[52:55]
	v_mfma_f32_16x16x32_bf16 v[48:51], v[176:179], v[192:195], v[48:51]
	v_mfma_f32_16x16x32_bf16 v[44:47], v[162:165], v[200:203], v[44:47]
	v_mfma_f32_16x16x32_bf16 v[40:43], v[176:179], v[200:203], v[40:43]
	v_mfma_f32_16x16x32_bf16 v[36:39], v[162:165], v[208:211], v[36:39]
	v_mfma_f32_16x16x32_bf16 v[32:35], v[176:179], v[208:211], v[32:35]
	s_setprio 0
	s_barrier
; #define G_STAGE(bufoff, gbase, voff) do { _Pragma("unroll") for (int _i = 0; _i < 2; ++_i) \
;         __builtin_amdgcn_global_load_lds((const unsigned*)((const char*)(gbase) + voff[_i]), (LAS unsigned*)(lds + (bufoff) + ldsw + _i * 8192), 16, 0, 0); } while (0)
; #define G_LDA(dst, b, h) do { _Pragma("unroll") for (int m = 0; m < 4; ++m) _Pragma("unroll") for (int k = 0; k < 2; ++k) dst[m][k] = *(const LAS bf16x8*)(lds + G_SA(b, h) + aoff + m * 2048 + k * 1024); } while (0)
; #define G_LDB(dst, b, h) do { _Pragma("unroll") for (int n = 0; n < 2; ++n) _Pragma("unroll") for (int k = 0; k < 2; ++k) dst[n][k] = *(const LAS bf16x8*)(lds + G_SB(b, h) + boff + n * 2048 + k * 1024); } while (0)
; #define G_MMA(ai, bj, At_, Bt_) do { __builtin_amdgcn_s_setprio(1); _Pragma("unroll") for (int m = 0; m < 4; ++m) _Pragma("unroll") for (int n = 0; n < 2; ++n) _Pragma("unroll") for (int k = 0; k < 2; ++k) \
;         acc[ai][bj][m][n] = __builtin_amdgcn_mfma_f32_16x16x32_bf16(Bt_[n][k], At_[m][k], acc[ai][bj][m][n], 0, 0, 0); __builtin_amdgcn_s_setprio(0); } while (0)
; #define WAIT_V(n) asm volatile("s_waitcnt vmcnt(" #n ")" ::: "memory")
; #define WAIT_L(n) asm volatile("s_waitcnt lgkmcnt(" #n ")" ::: "memory")
; #define BAR __builtin_amdgcn_s_barrier()
; #define SCHED __builtin_amdgcn_sched_barrier(0)
; template <class Get, class Epi>
; DI void gemm_loop(int ntiles, int ld, char* shm, const Get& get, const Epi& epi) {
;     ...
;             G_LDB(B0, 0, 0); G_LDB(B1, 0, 1); SCHED; G_LDA(At, 0, 0); G_STAGE(G_SA(1, 1), a1 + hstep, voffA);
;             WAIT_V(8); WAIT_L(0); BAR; G_MMA(0, 0, At, B0); G_MMA(0, 1, At, B1); BAR; SCHED;
;             G_LDA(At, 0, 1); G_STAGE(G_SB(0, 0), b2, voffB); G_STAGE(G_SB(0, 1), b2 + hstep, voffB); G_STAGE(G_SA(0, 0), a2, voffA);
;             WAIT_V(8); WAIT_L(0); BAR; G_MMA(1, 0, At, B0); G_MMA(1, 1, At, B1); BAR; SCHED;
;             G_LDB(B0, 1, 0); G_LDB(B1, 1, 1); SCHED; G_LDA(At, 1, 0); G_STAGE(G_SA(0, 1), a2 + hstep, voffA);
;             WAIT_V(8); WAIT_L(0); BAR; G_MMA(0, 0, At, B0); G_MMA(0, 1, At, B1); BAR; SCHED;
;             G_LDA(At, 1, 1); G_STAGE(G_SB(1, 0), b3, voffB); G_STAGE(G_SB(1, 1), b3 + hstep, voffB); G_STAGE(G_SA(1, 0), a3, voffA);
;             WAIT_V(8); WAIT_L(0); BAR; G_MMA(1, 0, At, B0); G_MMA(1, 1, At, B1); BAR; SCHED;
;         }
	s_add_i32 s2, s55, s33
	v_lshl_add_u64 v[144:145], v[144:145], 0, s[6:7]
	s_mov_b32 m0, s2
	ds_read_b128 v[180:183], v171 offset:49152
	ds_read_b128 v[184:187], v171 offset:50176
	ds_read_b128 v[188:191], v171 offset:51200
	ds_read_b128 v[192:195], v171 offset:52224
	ds_read_b128 v[196:199], v171 offset:53248
	ds_read_b128 v[200:203], v171 offset:54272
	ds_read_b128 v[204:207], v171 offset:55296
	ds_read_b128 v[208:211], v171 offset:56320
	global_load_lds_dwordx4 v[144:145], off
	s_add_i32 m0, s2, 0x2000
	s_add_u32 s2, s30, 0xb0080
	v_lshl_add_u64 v[144:145], v[166:167], 0, s[6:7]
	s_addc_u32 s3, s31, 0
	s_add_i32 s30, s56, s33
	global_load_lds_dwordx4 v[144:145], off
	v_lshl_add_u64 v[144:145], s[2:3], 0, v[148:149]
	s_mov_b32 m0, s30
	s_nop 0
	global_load_lds_dwordx4 v[144:145], off
	v_lshl_add_u64 v[144:145], s[2:3], 0, v[152:153]
	s_add_i32 m0, s30, 0x2000
	s_nop 0
	global_load_lds_dwordx4 v[144:145], off
	v_lshl_add_u64 v[144:145], v[212:213], 0, s[6:7]
	s_mov_b32 m0, s42
	s_nop 0
	global_load_lds_dwordx4 v[144:145], off
	v_lshl_add_u64 v[144:145], v[214:215], 0, s[6:7]
	s_mov_b32 m0, s43
	s_nop 0
	global_load_lds_dwordx4 v[144:145], off
	s_waitcnt vmcnt(8)
	s_waitcnt lgkmcnt(0)
	s_barrier
	s_setprio 1
	v_mfma_f32_16x16x32_bf16 v[92:95], v[128:131], v[180:183], v[92:95]
	v_mfma_f32_16x16x32_bf16 v[88:91], v[136:139], v[180:183], v[88:91]
	v_mfma_f32_16x16x32_bf16 v[84:87], v[128:131], v[188:191], v[84:87]
	v_mfma_f32_16x16x32_bf16 v[80:83], v[136:139], v[188:191], v[80:83]
	v_mfma_f32_16x16x32_bf16 v[76:79], v[128:131], v[196:199], v[76:79]
	v_mfma_f32_16x16x32_bf16 v[72:75], v[136:139], v[196:199], v[72:75]
	v_mfma_f32_16x16x32_bf16 v[68:71], v[128:131], v[204:207], v[68:71]
	v_mfma_f32_16x16x32_bf16 v[64:67], v[136:139], v[204:207], v[64:67]
	v_mfma_f32_16x16x32_bf16 v[92:95], v[132:135], v[184:187], v[92:95]
	v_mfma_f32_16x16x32_bf16 v[88:91], v[140:143], v[184:187], v[88:91]
	v_mfma_f32_16x16x32_bf16 v[84:87], v[132:135], v[192:195], v[84:87]
	v_mfma_f32_16x16x32_bf16 v[80:83], v[140:143], v[192:195], v[80:83]
	v_mfma_f32_16x16x32_bf16 v[76:79], v[132:135], v[200:203], v[76:79]
	v_mfma_f32_16x16x32_bf16 v[72:75], v[140:143], v[200:203], v[72:75]
	v_mfma_f32_16x16x32_bf16 v[68:71], v[132:135], v[208:211], v[68:71]
	v_mfma_f32_16x16x32_bf16 v[64:67], v[140:143], v[208:211], v[64:67]
	s_setprio 0
	s_setprio 1
	v_mfma_f32_16x16x32_bf16 v[28:31], v[158:161], v[180:183], v[28:31]
	v_mfma_f32_16x16x32_bf16 v[24:27], v[172:175], v[180:183], v[24:27]
	v_mfma_f32_16x16x32_bf16 v[20:23], v[158:161], v[188:191], v[20:23]
	v_mfma_f32_16x16x32_bf16 v[16:19], v[172:175], v[188:191], v[16:19]
	v_mfma_f32_16x16x32_bf16 v[12:15], v[158:161], v[196:199], v[12:15]
	v_mfma_f32_16x16x32_bf16 v[8:11], v[172:175], v[196:199], v[8:11]
	v_mfma_f32_16x16x32_bf16 v[4:7], v[158:161], v[204:207], v[4:7]
	v_mfma_f32_16x16x32_bf16 v[0:3], v[172:175], v[204:207], v[0:3]
	v_mfma_f32_16x16x32_bf16 v[28:31], v[162:165], v[184:187], v[28:31]
	v_mfma_f32_16x16x32_bf16 v[24:27], v[176:179], v[184:187], v[24:27]
	v_mfma_f32_16x16x32_bf16 v[20:23], v[162:165], v[192:195], v[20:23]
	v_mfma_f32_16x16x32_bf16 v[16:19], v[176:179], v[192:195], v[16:19]
	v_mfma_f32_16x16x32_bf16 v[12:15], v[162:165], v[200:203], v[12:15]
	v_mfma_f32_16x16x32_bf16 v[8:11], v[176:179], v[200:203], v[8:11]
	v_mfma_f32_16x16x32_bf16 v[4:7], v[162:165], v[208:211], v[4:7]
	v_mfma_f32_16x16x32_bf16 v[0:3], v[176:179], v[208:211], v[0:3]
	s_setprio 0
	s_barrier
	s_add_i32 s54, s54, 2
	s_add_u32 s52, s52, 0x100
	s_addc_u32 s53, s53, 0
	s_cmp_gt_u32 s54, 41
	s_mov_b64 s[2:3], s[24:25]
	s_cbranch_scc0 .LBB0_3759
	s_branch .Lpost_3759
.LBB0_3759:
	ds_read_b128 v[128:131], v169
	ds_read_b128 v[132:135], v169 offset:1024
	ds_read_b128 v[136:139], v169 offset:2048
	ds_read_b128 v[140:143], v169 offset:3072
	ds_read_b128 v[158:161], v170
	ds_read_b128 v[162:165], v170 offset:1024
	ds_read_b128 v[172:175], v170 offset:2048
	ds_read_b128 v[176:179], v170 offset:3072
	s_add_u32 s24, s2, 0x100
	s_addc_u32 s25, s3, 0
	s_cmp_eq_u32 s54, 40
	s_cselect_b32 s35, s21, s25
	s_cselect_b32 s34, s20, s24
	s_cselect_b32 s31, s23, s53
	s_cselect_b32 s30, s22, s52
	v_lshl_add_u64 v[144:145], s[2:3], 0, v[154:155]
	s_add_i32 m0, s36, 0xc000
	ds_read_b128 v[180:183], v171
	ds_read_b128 v[184:187], v171 offset:1024
	ds_read_b128 v[188:191], v171 offset:2048
	ds_read_b128 v[192:195], v171 offset:3072
	ds_read_b128 v[196:199], v171 offset:4096
	ds_read_b128 v[200:203], v171 offset:5120
	ds_read_b128 v[204:207], v171 offset:6144
	ds_read_b128 v[208:211], v171 offset:7168
	global_load_lds_dwordx4 v[144:145], off
	v_lshl_add_u64 v[144:145], s[2:3], 0, v[156:157]
	s_add_i32 m0, s36, 0xe000
	s_nop 0
	global_load_lds_dwordx4 v[144:145], off
	s_waitcnt vmcnt(8)
	s_waitcnt lgkmcnt(0)
	s_barrier
; #define G_STAGE(bufoff, gbase, voff) do { _Pragma("unroll") for (int _i = 0; _i < 2; ++_i) \
;         __builtin_amdgcn_global_load_lds((const unsigned*)((const char*)(gbase) + voff[_i]), (LAS unsigned*)(lds + (bufoff) + ldsw + _i * 8192), 16, 0, 0); } while (0)
; #define G_LDA(dst, b, h) do { _Pragma("unroll") for (int m = 0; m < 4; ++m) _Pragma("unroll") for (int k = 0; k < 2; ++k) dst[m][k] = *(const LAS bf16x8*)(lds + G_SA(b, h) + aoff + m * 2048 + k * 1024); } while (0)
; #define G_MMA(ai, bj, At_, Bt_) do { __builtin_amdgcn_s_setprio(1); _Pragma("unroll") for (int m = 0; m < 4; ++m) _Pragma("unroll") for (int n = 0; n < 2; ++n) _Pragma("unroll") for (int k = 0; k < 2; ++k) \
;         acc[ai][bj][m][n] = __builtin_amdgcn_mfma_f32_16x16x32_bf16(Bt_[n][k], At_[m][k], acc[ai][bj][m][n], 0, 0, 0); __builtin_amdgcn_s_setprio(0); } while (0)
; #define WAIT_V(n) asm volatile("s_waitcnt vmcnt(" #n ")" ::: "memory")
; #define WAIT_L(n) asm volatile("s_waitcnt lgkmcnt(" #n ")" ::: "memory")
; #define BAR __builtin_amdgcn_s_barrier()
; #define SCHED __builtin_amdgcn_sched_barrier(0)
; template <class Get, class Epi>
; DI void gemm_loop(int ntiles, int ld, char* shm, const Get& get, const Epi& epi) {
;     ...
;             WAIT_V(8); WAIT_L(0); BAR; G_MMA(0, 0, At, B0); G_MMA(0, 1, At, B1); BAR; SCHED;
;             G_LDA(At, 0, 1); G_STAGE(G_SB(0, 0), b2, voffB); G_STAGE(G_SB(0, 1), b2 + hstep, voffB); G_STAGE(G_SA(0, 0), a2, voffA);
;             WAIT_V(8); WAIT_L(0); BAR; G_MMA(1, 0, At, B0); G_MMA(1, 1, At, B1); BAR; SCHED;
	s_setprio 1
	v_mfma_f32_16x16x32_bf16 v[124:127], v[128:131], v[180:183], v[124:127]
	v_mfma_f32_16x16x32_bf16 v[120:123], v[136:139], v[180:183], v[120:123]
	v_mfma_f32_16x16x32_bf16 v[116:119], v[128:131], v[188:191], v[116:119]
	v_mfma_f32_16x16x32_bf16 v[112:115], v[136:139], v[188:191], v[112:115]
	v_mfma_f32_16x16x32_bf16 v[108:111], v[128:131], v[196:199], v[108:111]
	v_mfma_f32_16x16x32_bf16 v[104:107], v[136:139], v[196:199], v[104:107]
	v_mfma_f32_16x16x32_bf16 v[100:103], v[128:131], v[204:207], v[100:103]
	v_mfma_f32_16x16x32_bf16 v[96:99], v[136:139], v[204:207], v[96:99]
	v_mfma_f32_16x16x32_bf16 v[124:127], v[132:135], v[184:187], v[124:127]
	v_mfma_f32_16x16x32_bf16 v[120:123], v[140:143], v[184:187], v[120:123]
	v_mfma_f32_16x16x32_bf16 v[116:119], v[132:135], v[192:195], v[116:119]
	v_mfma_f32_16x16x32_bf16 v[112:115], v[140:143], v[192:195], v[112:115]
	v_mfma_f32_16x16x32_bf16 v[108:111], v[132:135], v[200:203], v[108:111]
	v_mfma_f32_16x16x32_bf16 v[104:107], v[140:143], v[200:203], v[104:107]
	v_mfma_f32_16x16x32_bf16 v[100:103], v[132:135], v[208:211], v[100:103]
	v_mfma_f32_16x16x32_bf16 v[96:99], v[140:143], v[208:211], v[96:99]
	s_setprio 0
	s_setprio 1
	v_mfma_f32_16x16x32_bf16 v[60:63], v[158:161], v[180:183], v[60:63]
	v_mfma_f32_16x16x32_bf16 v[56:59], v[172:175], v[180:183], v[56:59]
	v_mfma_f32_16x16x32_bf16 v[52:55], v[158:161], v[188:191], v[52:55]
	v_mfma_f32_16x16x32_bf16 v[48:51], v[172:175], v[188:191], v[48:51]
	v_mfma_f32_16x16x32_bf16 v[44:47], v[158:161], v[196:199], v[44:47]
	v_mfma_f32_16x16x32_bf16 v[40:43], v[172:175], v[196:199], v[40:43]
	v_mfma_f32_16x16x32_bf16 v[36:39], v[158:161], v[204:207], v[36:39]
	v_mfma_f32_16x16x32_bf16 v[32:35], v[172:175], v[204:207], v[32:35]
	v_mfma_f32_16x16x32_bf16 v[60:63], v[162:165], v[184:187], v[60:63]
	v_mfma_f32_16x16x32_bf16 v[56:59], v[176:179], v[184:187], v[56:59]
	v_mfma_f32_16x16x32_bf16 v[52:55], v[162:165], v[192:195], v[52:55]
	v_mfma_f32_16x16x32_bf16 v[48:51], v[176:179], v[192:195], v[48:51]
	v_mfma_f32_16x16x32_bf16 v[44:47], v[162:165], v[200:203], v[44:47]
	v_mfma_f32_16x16x32_bf16 v[40:43], v[176:179], v[200:203], v[40:43]
	v_mfma_f32_16x16x32_bf16 v[36:39], v[162:165], v[208:211], v[36:39]
	v_mfma_f32_16x16x32_bf16 v[32:35], v[176:179], v[208:211], v[32:35]
	s_setprio 0
	s_barrier
	s_add_i32 s2, s44, s33
	v_lshl_add_u64 v[144:145], s[30:31], 0, v[148:149]
	s_mov_b32 m0, s2
	ds_read_b128 v[180:183], v171 offset:16384
	ds_read_b128 v[184:187], v171 offset:17408
	ds_read_b128 v[188:191], v171 offset:18432
	ds_read_b128 v[192:195], v171 offset:19456
	ds_read_b128 v[196:199], v171 offset:20480
	ds_read_b128 v[200:203], v171 offset:21504
	ds_read_b128 v[204:207], v171 offset:22528
	ds_read_b128 v[208:211], v171 offset:23552
	global_load_lds_dwordx4 v[144:145], off
	s_add_i32 m0, s2, 0x2000
	s_add_u32 s2, s30, 0xb0000
	v_lshl_add_u64 v[166:167], s[30:31], 0, v[152:153]
	s_addc_u32 s3, s31, 0
	s_add_i32 s55, s45, s33
	global_load_lds_dwordx4 v[166:167], off
	v_lshl_add_u64 v[212:213], s[2:3], 0, v[148:149]
	s_mov_b32 m0, s55
	v_lshl_add_u64 v[214:215], s[34:35], 0, v[150:151]
	global_load_lds_dwordx4 v[212:213], off
	v_lshl_add_u64 v[212:213], s[2:3], 0, v[152:153]
	s_add_i32 m0, s55, 0x2000
	s_nop 0
	global_load_lds_dwordx4 v[212:213], off
	v_lshl_add_u64 v[212:213], s[34:35], 0, v[146:147]
	s_mov_b32 m0, s36
	s_nop 0
	global_load_lds_dwordx4 v[212:213], off
	s_mov_b32 m0, s37
	s_nop 0
	global_load_lds_dwordx4 v[214:215], off
	s_waitcnt vmcnt(8)
	s_waitcnt lgkmcnt(0)
	s_barrier
	s_setprio 1
	v_mfma_f32_16x16x32_bf16 v[92:95], v[128:131], v[180:183], v[92:95]
	v_mfma_f32_16x16x32_bf16 v[88:91], v[136:139], v[180:183], v[88:91]
	v_mfma_f32_16x16x32_bf16 v[84:87], v[128:131], v[188:191], v[84:87]
	v_mfma_f32_16x16x32_bf16 v[80:83], v[136:139], v[188:191], v[80:83]
	v_mfma_f32_16x16x32_bf16 v[76:79], v[128:131], v[196:199], v[76:79]
	v_mfma_f32_16x16x32_bf16 v[72:75], v[136:139], v[196:199], v[72:75]
	v_mfma_f32_16x16x32_bf16 v[68:71], v[128:131], v[204:207], v[68:71]
	v_mfma_f32_16x16x32_bf16 v[64:67], v[136:139], v[204:207], v[64:67]
	v_mfma_f32_16x16x32_bf16 v[92:95], v[132:135], v[184:187], v[92:95]
	v_mfma_f32_16x16x32_bf16 v[88:91], v[140:143], v[184:187], v[88:91]
	v_mfma_f32_16x16x32_bf16 v[84:87], v[132:135], v[192:195], v[84:87]
	v_mfma_f32_16x16x32_bf16 v[80:83], v[140:143], v[192:195], v[80:83]
	v_mfma_f32_16x16x32_bf16 v[76:79], v[132:135], v[200:203], v[76:79]
	v_mfma_f32_16x16x32_bf16 v[72:75], v[140:143], v[200:203], v[72:75]
	v_mfma_f32_16x16x32_bf16 v[68:71], v[132:135], v[208:211], v[68:71]
	v_mfma_f32_16x16x32_bf16 v[64:67], v[140:143], v[208:211], v[64:67]
	s_setprio 0
	s_setprio 1
	v_mfma_f32_16x16x32_bf16 v[28:31], v[158:161], v[180:183], v[28:31]
	v_mfma_f32_16x16x32_bf16 v[24:27], v[172:175], v[180:183], v[24:27]
	v_mfma_f32_16x16x32_bf16 v[20:23], v[158:161], v[188:191], v[20:23]
	v_mfma_f32_16x16x32_bf16 v[16:19], v[172:175], v[188:191], v[16:19]
	v_mfma_f32_16x16x32_bf16 v[12:15], v[158:161], v[196:199], v[12:15]
	v_mfma_f32_16x16x32_bf16 v[8:11], v[172:175], v[196:199], v[8:11]
	v_mfma_f32_16x16x32_bf16 v[4:7], v[158:161], v[204:207], v[4:7]
	v_mfma_f32_16x16x32_bf16 v[0:3], v[172:175], v[204:207], v[0:3]
	v_mfma_f32_16x16x32_bf16 v[28:31], v[162:165], v[184:187], v[28:31]
	v_mfma_f32_16x16x32_bf16 v[24:27], v[176:179], v[184:187], v[24:27]
	v_mfma_f32_16x16x32_bf16 v[20:23], v[162:165], v[192:195], v[20:23]
	v_mfma_f32_16x16x32_bf16 v[16:19], v[176:179], v[192:195], v[16:19]
	v_mfma_f32_16x16x32_bf16 v[12:15], v[162:165], v[200:203], v[12:15]
	v_mfma_f32_16x16x32_bf16 v[8:11], v[176:179], v[200:203], v[8:11]
	v_mfma_f32_16x16x32_bf16 v[4:7], v[162:165], v[208:211], v[4:7]
	v_mfma_f32_16x16x32_bf16 v[0:3], v[176:179], v[208:211], v[0:3]
	s_setprio 0
	s_barrier
; #define G_STAGE(bufoff, gbase, voff) do { _Pragma("unroll") for (int _i = 0; _i < 2; ++_i) \
;         __builtin_amdgcn_global_load_lds((const unsigned*)((const char*)(gbase) + voff[_i]), (LAS unsigned*)(lds + (bufoff) + ldsw + _i * 8192), 16, 0, 0); } while (0)
; #define G_LDA(dst, b, h) do { _Pragma("unroll") for (int m = 0; m < 4; ++m) _Pragma("unroll") for (int k = 0; k < 2; ++k) dst[m][k] = *(const LAS bf16x8*)(lds + G_SA(b, h) + aoff + m * 2048 + k * 1024); } while (0)
; #define G_LDB(dst, b, h) do { _Pragma("unroll") for (int n = 0; n < 2; ++n) _Pragma("unroll") for (int k = 0; k < 2; ++k) dst[n][k] = *(const LAS bf16x8*)(lds + G_SB(b, h) + boff + n * 2048 + k * 1024); } while (0)
; #define G_MMA(ai, bj, At_, Bt_) do { __builtin_amdgcn_s_setprio(1); _Pragma("unroll") for (int m = 0; m < 4; ++m) _Pragma("unroll") for (int n = 0; n < 2; ++n) _Pragma("unroll") for (int k = 0; k < 2; ++k) \
;         acc[ai][bj][m][n] = __builtin_amdgcn_mfma_f32_16x16x32_bf16(Bt_[n][k], At_[m][k], acc[ai][bj][m][n], 0, 0, 0); __builtin_amdgcn_s_setprio(0); } while (0)
; #define WAIT_V(n) asm volatile("s_waitcnt vmcnt(" #n ")" ::: "memory")
; #define WAIT_L(n) asm volatile("s_waitcnt lgkmcnt(" #n ")" ::: "memory")
; #define BAR __builtin_amdgcn_s_barrier()
; #define SCHED __builtin_amdgcn_sched_barrier(0)
; template <class Get, class Epi>
; DI void gemm_loop(int ntiles, int ld, char* shm, const Get& get, const Epi& epi) {
;     ...
;             G_LDB(B0, 1, 0); G_LDB(B1, 1, 1); SCHED; G_LDA(At, 1, 0); G_STAGE(G_SA(0, 1), a2 + hstep, voffA);
;             WAIT_V(8); WAIT_L(0); BAR; G_MMA(0, 0, At, B0); G_MMA(0, 1, At, B1); BAR; SCHED;
	s_add_i32 s55, 0, 0x18000
	s_add_i32 s56, 0, 0x1c000
	v_add_u32_e32 v140, s55, v168
	v_add_u32_e32 v176, s56, v168
	ds_read_b128 v[128:131], v140
	ds_read_b128 v[132:135], v140 offset:1024
	ds_read_b128 v[136:139], v140 offset:2048
	ds_read_b128 v[140:143], v140 offset:3072
	ds_read_b128 v[158:161], v176
	ds_read_b128 v[162:165], v176 offset:1024
	ds_read_b128 v[172:175], v176 offset:2048
	ds_read_b128 v[176:179], v176 offset:3072
	s_add_u32 s2, s34, 0xb0000
	s_addc_u32 s3, s35, 0
	s_mov_b32 m0, s38
	v_lshl_add_u64 v[216:217], s[2:3], 0, v[146:147]
	ds_read_b128 v[180:183], v171 offset:32768
	ds_read_b128 v[184:187], v171 offset:33792
	ds_read_b128 v[188:191], v171 offset:34816
	ds_read_b128 v[192:195], v171 offset:35840
	ds_read_b128 v[196:199], v171 offset:36864
	ds_read_b128 v[200:203], v171 offset:37888
	ds_read_b128 v[204:207], v171 offset:38912
	ds_read_b128 v[208:211], v171 offset:39936
	global_load_lds_dwordx4 v[216:217], off
	v_lshl_add_u64 v[216:217], s[2:3], 0, v[150:151]
	s_mov_b32 m0, s39
	s_nop 0
	global_load_lds_dwordx4 v[216:217], off
	s_waitcnt vmcnt(8)
	s_waitcnt lgkmcnt(0)
	s_barrier
	s_setprio 1
	v_mfma_f32_16x16x32_bf16 v[124:127], v[128:131], v[180:183], v[124:127]
	v_mfma_f32_16x16x32_bf16 v[120:123], v[136:139], v[180:183], v[120:123]
	v_mfma_f32_16x16x32_bf16 v[116:119], v[128:131], v[188:191], v[116:119]
	v_mfma_f32_16x16x32_bf16 v[112:115], v[136:139], v[188:191], v[112:115]
	v_mfma_f32_16x16x32_bf16 v[108:111], v[128:131], v[196:199], v[108:111]
	v_mfma_f32_16x16x32_bf16 v[104:107], v[136:139], v[196:199], v[104:107]
	v_mfma_f32_16x16x32_bf16 v[100:103], v[128:131], v[204:207], v[100:103]
	v_mfma_f32_16x16x32_bf16 v[96:99], v[136:139], v[204:207], v[96:99]
	v_mfma_f32_16x16x32_bf16 v[124:127], v[132:135], v[184:187], v[124:127]
	v_mfma_f32_16x16x32_bf16 v[120:123], v[140:143], v[184:187], v[120:123]
	v_mfma_f32_16x16x32_bf16 v[116:119], v[132:135], v[192:195], v[116:119]
	v_mfma_f32_16x16x32_bf16 v[112:115], v[140:143], v[192:195], v[112:115]
	v_mfma_f32_16x16x32_bf16 v[108:111], v[132:135], v[200:203], v[108:111]
	v_mfma_f32_16x16x32_bf16 v[104:107], v[140:143], v[200:203], v[104:107]
	v_mfma_f32_16x16x32_bf16 v[100:103], v[132:135], v[208:211], v[100:103]
	v_mfma_f32_16x16x32_bf16 v[96:99], v[140:143], v[208:211], v[96:99]
	s_setprio 0
	s_setprio 1
	v_mfma_f32_16x16x32_bf16 v[60:63], v[158:161], v[180:183], v[60:63]
	v_mfma_f32_16x16x32_bf16 v[56:59], v[172:175], v[180:183], v[56:59]
	v_mfma_f32_16x16x32_bf16 v[52:55], v[158:161], v[188:191], v[52:55]
	v_mfma_f32_16x16x32_bf16 v[48:51], v[172:175], v[188:191], v[48:51]
	v_mfma_f32_16x16x32_bf16 v[44:47], v[158:161], v[196:199], v[44:47]
	v_mfma_f32_16x16x32_bf16 v[40:43], v[172:175], v[196:199], v[40:43]
	v_mfma_f32_16x16x32_bf16 v[36:39], v[158:161], v[204:207], v[36:39]
	v_mfma_f32_16x16x32_bf16 v[32:35], v[172:175], v[204:207], v[32:35]
	v_mfma_f32_16x16x32_bf16 v[60:63], v[162:165], v[184:187], v[60:63]
	v_mfma_f32_16x16x32_bf16 v[56:59], v[176:179], v[184:187], v[56:59]
	v_mfma_f32_16x16x32_bf16 v[52:55], v[162:165], v[192:195], v[52:55]
	v_mfma_f32_16x16x32_bf16 v[48:51], v[176:179], v[192:195], v[48:51]
	v_mfma_f32_16x16x32_bf16 v[44:47], v[162:165], v[200:203], v[44:47]
	v_mfma_f32_16x16x32_bf16 v[40:43], v[176:179], v[200:203], v[40:43]
	v_mfma_f32_16x16x32_bf16 v[36:39], v[162:165], v[208:211], v[36:39]
	v_mfma_f32_16x16x32_bf16 v[32:35], v[176:179], v[208:211], v[32:35]
	s_setprio 0
	s_barrier
; #define G_STAGE(bufoff, gbase, voff) do { _Pragma("unroll") for (int _i = 0; _i < 2; ++_i) \
;         __builtin_amdgcn_global_load_lds((const unsigned*)((const char*)(gbase) + voff[_i]), (LAS unsigned*)(lds + (bufoff) + ldsw + _i * 8192), 16, 0, 0); } while (0)
; #define G_LDA(dst, b, h) do { _Pragma("unroll") for (int m = 0; m < 4; ++m) _Pragma("unroll") for (int k = 0; k < 2; ++k) dst[m][k] = *(const LAS bf16x8*)(lds + G_SA(b, h) + aoff + m * 2048 + k * 1024); } while (0)
; #define G_MMA(ai, bj, At_, Bt_) do { __builtin_amdgcn_s_setprio(1); _Pragma("unroll") for (int m = 0; m < 4; ++m) _Pragma("unroll") for (int n = 0; n < 2; ++n) _Pragma("unroll") for (int k = 0; k < 2; ++k) \
;         acc[ai][bj][m][n] = __builtin_amdgcn_mfma_f32_16x16x32_bf16(Bt_[n][k], At_[m][k], acc[ai][bj][m][n], 0, 0, 0); __builtin_amdgcn_s_setprio(0); } while (0)
; #define WAIT_V(n) asm volatile("s_waitcnt vmcnt(" #n ")" ::: "memory")
; #define WAIT_L(n) asm volatile("s_waitcnt lgkmcnt(" #n ")" ::: "memory")
; #define BAR __builtin_amdgcn_s_barrier()
; #define SCHED __builtin_amdgcn_sched_barrier(0)
; template <class Get, class Epi>
; DI void gemm_loop(int ntiles, int ld, char* shm, const Get& get, const Epi& epi) {
;     ...
;             G_LDA(At, 1, 1); G_STAGE(G_SB(1, 0), b3, voffB); G_STAGE(G_SB(1, 1), b3 + hstep, voffB); G_STAGE(G_SA(1, 0), a3, voffA);
;             WAIT_V(8); WAIT_L(0); BAR; G_MMA(1, 0, At, B0); G_MMA(1, 1, At, B1); BAR; SCHED;
;         }
	s_add_i32 s2, s55, s33
	v_lshl_add_u64 v[144:145], v[144:145], 0, s[6:7]
	s_mov_b32 m0, s2
	ds_read_b128 v[180:183], v171 offset:49152
	ds_read_b128 v[184:187], v171 offset:50176
	ds_read_b128 v[188:191], v171 offset:51200
	ds_read_b128 v[192:195], v171 offset:52224
	ds_read_b128 v[196:199], v171 offset:53248
	ds_read_b128 v[200:203], v171 offset:54272
	ds_read_b128 v[204:207], v171 offset:55296
	ds_read_b128 v[208:211], v171 offset:56320
	global_load_lds_dwordx4 v[144:145], off
	s_add_i32 m0, s2, 0x2000
	s_add_u32 s2, s30, 0xb0080
	v_lshl_add_u64 v[144:145], v[166:167], 0, s[6:7]
	s_addc_u32 s3, s31, 0
	s_add_i32 s30, s56, s33
	global_load_lds_dwordx4 v[144:145], off
	v_lshl_add_u64 v[144:145], s[2:3], 0, v[148:149]
	s_mov_b32 m0, s30
	s_nop 0
	global_load_lds_dwordx4 v[144:145], off
	v_lshl_add_u64 v[144:145], s[2:3], 0, v[152:153]
	s_add_i32 m0, s30, 0x2000
	s_nop 0
	global_load_lds_dwordx4 v[144:145], off
	v_lshl_add_u64 v[144:145], v[212:213], 0, s[6:7]
	s_mov_b32 m0, s42
	s_nop 0
	global_load_lds_dwordx4 v[144:145], off
	v_lshl_add_u64 v[144:145], v[214:215], 0, s[6:7]
	s_mov_b32 m0, s43
	s_nop 0
	global_load_lds_dwordx4 v[144:145], off
	s_waitcnt vmcnt(8)
	s_waitcnt lgkmcnt(0)
	s_barrier
	s_setprio 1
	v_mfma_f32_16x16x32_bf16 v[92:95], v[128:131], v[180:183], v[92:95]
	v_mfma_f32_16x16x32_bf16 v[88:91], v[136:139], v[180:183], v[88:91]
	v_mfma_f32_16x16x32_bf16 v[84:87], v[128:131], v[188:191], v[84:87]
	v_mfma_f32_16x16x32_bf16 v[80:83], v[136:139], v[188:191], v[80:83]
	v_mfma_f32_16x16x32_bf16 v[76:79], v[128:131], v[196:199], v[76:79]
	v_mfma_f32_16x16x32_bf16 v[72:75], v[136:139], v[196:199], v[72:75]
	v_mfma_f32_16x16x32_bf16 v[68:71], v[128:131], v[204:207], v[68:71]
	v_mfma_f32_16x16x32_bf16 v[64:67], v[136:139], v[204:207], v[64:67]
	v_mfma_f32_16x16x32_bf16 v[92:95], v[132:135], v[184:187], v[92:95]
	v_mfma_f32_16x16x32_bf16 v[88:91], v[140:143], v[184:187], v[88:91]
	v_mfma_f32_16x16x32_bf16 v[84:87], v[132:135], v[192:195], v[84:87]
	v_mfma_f32_16x16x32_bf16 v[80:83], v[140:143], v[192:195], v[80:83]
	v_mfma_f32_16x16x32_bf16 v[76:79], v[132:135], v[200:203], v[76:79]
	v_mfma_f32_16x16x32_bf16 v[72:75], v[140:143], v[200:203], v[72:75]
	v_mfma_f32_16x16x32_bf16 v[68:71], v[132:135], v[208:211], v[68:71]
	v_mfma_f32_16x16x32_bf16 v[64:67], v[140:143], v[208:211], v[64:67]
	s_setprio 0
	s_setprio 1
	v_mfma_f32_16x16x32_bf16 v[28:31], v[158:161], v[180:183], v[28:31]
	v_mfma_f32_16x16x32_bf16 v[24:27], v[172:175], v[180:183], v[24:27]
	v_mfma_f32_16x16x32_bf16 v[20:23], v[158:161], v[188:191], v[20:23]
	v_mfma_f32_16x16x32_bf16 v[16:19], v[172:175], v[188:191], v[16:19]
	v_mfma_f32_16x16x32_bf16 v[12:15], v[158:161], v[196:199], v[12:15]
	v_mfma_f32_16x16x32_bf16 v[8:11], v[172:175], v[196:199], v[8:11]
	v_mfma_f32_16x16x32_bf16 v[4:7], v[158:161], v[204:207], v[4:7]
	v_mfma_f32_16x16x32_bf16 v[0:3], v[172:175], v[204:207], v[0:3]
	v_mfma_f32_16x16x32_bf16 v[28:31], v[162:165], v[184:187], v[28:31]
	v_mfma_f32_16x16x32_bf16 v[24:27], v[176:179], v[184:187], v[24:27]
	v_mfma_f32_16x16x32_bf16 v[20:23], v[162:165], v[192:195], v[20:23]
	v_mfma_f32_16x16x32_bf16 v[16:19], v[176:179], v[192:195], v[16:19]
	v_mfma_f32_16x16x32_bf16 v[12:15], v[162:165], v[200:203], v[12:15]
	v_mfma_f32_16x16x32_bf16 v[8:11], v[176:179], v[200:203], v[8:11]
	v_mfma_f32_16x16x32_bf16 v[4:7], v[162:165], v[208:211], v[4:7]
	v_mfma_f32_16x16x32_bf16 v[0:3], v[176:179], v[208:211], v[0:3]
	s_setprio 0
	s_barrier
	s_add_i32 s54, s54, 2
	s_add_u32 s52, s52, 0x100
	s_addc_u32 s53, s53, 0
	s_cmp_gt_u32 s54, 41
	s_mov_b64 s[2:3], s[24:25]
	s_cbranch_scc0 .LBB0_3759
